# o4+o8 plus f32 division expansions (silu/sigmoid) in gdn prep / sample / pool / o_a phases replaced by v_rcp_f32+v_mul_f32 (f32 throughout, ~1 ulp)
# speedup vs baseline: 1.0538x; 1.0143x over previous
; DEV float bflo(unsigned u) { return __uint_as_float(u << 16); }
; DEV float bfhi(unsigned u) { return __uint_as_float(u & 0xffff0000u); }
; DEV float silu_f(float x) { return x / (1.f + __expf(-x)); }
; DEV void gdn_prep_chunk(const Params& p, int item, unsigned char* lds) {
;     ...
;         for (int r = 0; r < 16; ++r) {
;             float y[8]; float ss = 0.f;
; #pragma unroll
;             for (int e = 0; e < 8; ++e) {
;                 float a = 0.f;
; #pragma unroll
;                 for (int j = 0; j < 4; ++j) {
;                     const uint4 u = raw[r + j];
;                     const unsigned wd = (e < 2 ? u.x : (e < 4 ? u.y : (e < 6 ? u.z : u.w)));
;                     const float xv = (e & 1) ? bfhi(wd) : bflo(wd);
;                     a += w[j][e] * xv;
;                 }
;                 y[e] = silu_f(a); ss += y[e] * y[e];
;             }
.LBB0_472:
	s_or_b64 exec, exec, s[4:5]
	v_or_b32_e32 v38, s31, v133
	v_mad_i64_i32 v[36:37], s[4:5], v38, s55, v[34:35]
	global_load_dwordx4 v[106:109], v[36:37], off
	s_waitcnt vmcnt(1)
	v_lshlrev_b32_e32 v36, 16, v98
	v_and_b32_e32 v37, 0xffff0000, v98
	v_lshlrev_b32_e32 v116, 16, v94
	v_and_b32_e32 v117, 0xffff0000, v94
	v_or_b32_e32 v39, 1, v38
	v_or_b32_e32 v50, 7, v38
	v_or_b32_e32 v52, 8, v38
	v_or_b32_e32 v54, 9, v38
	v_or_b32_e32 v56, 10, v38
	v_or_b32_e32 v58, 11, v38
	v_pk_fma_f32 v[36:37], v[18:19], v[36:37], 0 op_sel_hi:[1,1,0]
	v_lshlrev_b32_e32 v112, 16, v102
	v_and_b32_e32 v113, 0xffff0000, v102
	v_or_b32_e32 v40, 2, v38
	v_or_b32_e32 v42, 3, v38
	v_or_b32_e32 v44, 4, v38
	v_or_b32_e32 v46, 5, v38
	v_or_b32_e32 v48, 6, v38
	v_or_b32_e32 v59, 12, v38
	v_or_b32_e32 v60, 13, v38
	v_or_b32_e32 v61, 14, v38
	v_or_b32_e32 v62, 15, v38
	v_mad_i64_i32 v[38:39], s[36:37], v39, s55, v[34:35]
	v_mad_i64_i32 v[50:51], s[36:37], v50, s55, v[34:35]
	v_mad_i64_i32 v[52:53], s[36:37], v52, s55, v[34:35]
	v_mad_i64_i32 v[54:55], s[36:37], v54, s55, v[34:35]
	v_mad_i64_i32 v[56:57], s[36:37], v56, s55, v[34:35]
	v_mad_i64_i32 v[110:111], s[36:37], v58, s55, v[34:35]
	v_pk_fma_f32 v[36:37], v[22:23], v[116:117], v[36:37]
	v_mad_i64_i32 v[40:41], s[36:37], v40, s55, v[34:35]
	v_mad_i64_i32 v[42:43], s[36:37], v42, s55, v[34:35]
	v_mad_i64_i32 v[44:45], s[36:37], v44, s55, v[34:35]
	v_mad_i64_i32 v[46:47], s[36:37], v46, s55, v[34:35]
	v_mad_i64_i32 v[48:49], s[36:37], v48, s55, v[34:35]
	v_mad_i64_i32 v[114:115], s[36:37], v59, s55, v[34:35]
	v_mad_i64_i32 v[118:119], s[36:37], v60, s55, v[34:35]
	v_mad_i64_i32 v[120:121], s[36:37], v61, s55, v[34:35]
	v_mad_i64_i32 v[34:35], s[36:37], v62, s55, v[34:35]
	global_load_dwordx4 v[90:93], v[38:39], off
	global_load_dwordx4 v[86:89], v[40:41], off
	global_load_dwordx4 v[82:85], v[42:43], off
	global_load_dwordx4 v[78:81], v[44:45], off
	global_load_dwordx4 v[74:77], v[46:47], off
	global_load_dwordx4 v[70:73], v[48:49], off
	global_load_dwordx4 v[66:69], v[50:51], off
	global_load_dwordx4 v[62:65], v[52:53], off
	global_load_dwordx4 v[58:61], v[54:55], off
	s_nop 0
	global_load_dwordx4 v[54:57], v[56:57], off
	s_nop 0
	global_load_dwordx4 v[50:53], v[110:111], off
	v_pk_fma_f32 v[36:37], v[26:27], v[112:113], v[36:37]
	v_cmp_gt_u32_e64 s[4:5], 64, v130
	v_cmp_gt_i32_e64 s[6:7], 2, v131
	s_waitcnt vmcnt(11)
	v_lshlrev_b32_e32 v110, 16, v106
	v_and_b32_e32 v111, 0xffff0000, v106
	v_pk_fma_f32 v[122:123], v[30:31], v[110:111], v[36:37]
	s_nop 0
	v_mul_f32_e32 v36, 0xbfb8aa3b, v122
	v_mul_f32_e32 v37, 0xbfb8aa3b, v123
	v_exp_f32_e32 v124, v36
	v_exp_f32_e32 v125, v37
	global_load_dwordx4 v[46:49], v[114:115], off
	global_load_dwordx4 v[42:45], v[118:119], off
	global_load_dwordx4 v[38:41], v[120:121], off
	s_nop 0
	global_load_dwordx4 v[34:37], v[34:35], off
	v_lshlrev_b32_e32 v118, 16, v95
	v_and_b32_e32 v119, 0xffff0000, v95
	v_pk_add_f32 v[120:121], v[124:125], 1.0 op_sel_hi:[1,0]
	v_and_b32_e32 v95, 0xffff0000, v107


; DEV float bflo(unsigned u) { return __uint_as_float(u << 16); }
; DEV float bfhi(unsigned u) { return __uint_as_float(u & 0xffff0000u); }
; DEV float silu_f(float x) { return x / (1.f + __expf(-x)); }
; DEV void gdn_prep_chunk(const Params& p, int item, unsigned char* lds) {
;     ...
;         for (int r = 0; r < 16; ++r) {
;             float y[8]; float ss = 0.f;
; #pragma unroll
;             for (int e = 0; e < 8; ++e) {
;                 float a = 0.f;
; #pragma unroll
;                 for (int j = 0; j < 4; ++j) {
;                     const uint4 u = raw[r + j];
;                     const unsigned wd = (e < 2 ? u.x : (e < 4 ? u.y : (e < 6 ? u.z : u.w)));
;                     const float xv = (e & 1) ? bfhi(wd) : bflo(wd);
;                     a += w[j][e] * xv;
;                 }
;                 y[e] = silu_f(a); ss += y[e] * y[e];
;             }
	v_lshlrev_b32_e32 v98, 16, v99
	v_and_b32_e32 v99, 0xffff0000, v99
	v_pk_fma_f32 v[98:99], v[20:21], v[98:99], 0 op_sel_hi:[1,1,0]
	v_lshlrev_b32_e32 v114, 16, v103
	v_and_b32_e32 v115, 0xffff0000, v103
	v_pk_fma_f32 v[98:99], v[24:25], v[118:119], v[98:99]
	v_rcp_f32_e32 v94, v121
	s_nop 0
	v_mul_f32_e32 v125, v123, v94
	v_lshlrev_b32_e32 v94, 16, v107
	v_pk_fma_f32 v[98:99], v[28:29], v[114:115], v[98:99]

; DEV float bflo(unsigned u) { return __uint_as_float(u << 16); }
; DEV float bfhi(unsigned u) { return __uint_as_float(u & 0xffff0000u); }
; DEV float silu_f(float x) { return x / (1.f + __expf(-x)); }
; DEV void gdn_prep_chunk(const Params& p, int item, unsigned char* lds) {
;     ...
;         for (int r = 0; r < 16; ++r) {
;             float y[8]; float ss = 0.f;
; #pragma unroll
;             for (int e = 0; e < 8; ++e) {
;                 float a = 0.f;
; #pragma unroll
;                 for (int j = 0; j < 4; ++j) {
;                     const uint4 u = raw[r + j];
;                     const unsigned wd = (e < 2 ? u.x : (e < 4 ? u.y : (e < 6 ? u.z : u.w)));
;                     const float xv = (e & 1) ? bfhi(wd) : bflo(wd);
;                     a += w[j][e] * xv;
;                 }
;                 y[e] = silu_f(a); ss += y[e] * y[e];
;             }
	v_pk_fma_f32 v[102:103], v[32:33], v[94:95], v[98:99]

; DEV float bflo(unsigned u) { return __uint_as_float(u << 16); }
; DEV float bfhi(unsigned u) { return __uint_as_float(u & 0xffff0000u); }
; DEV float silu_f(float x) { return x / (1.f + __expf(-x)); }
; DEV void gdn_prep_chunk(const Params& p, int item, unsigned char* lds) {
;     ...
;         for (int r = 0; r < 16; ++r) {
;             float y[8]; float ss = 0.f;
; #pragma unroll
;             for (int e = 0; e < 8; ++e) {
;                 float a = 0.f;
; #pragma unroll
;                 for (int j = 0; j < 4; ++j) {
;                     const uint4 u = raw[r + j];
;                     const unsigned wd = (e < 2 ? u.x : (e < 4 ? u.y : (e < 6 ? u.z : u.w)));
;                     const float xv = (e & 1) ? bfhi(wd) : bflo(wd);
;                     a += w[j][e] * xv;
;                 }
;                 y[e] = silu_f(a); ss += y[e] * y[e];
;             }
	v_mul_f32_e32 v98, 0xbfb8aa3b, v102
	v_mul_f32_e32 v99, 0xbfb8aa3b, v103
	v_exp_f32_e32 v98, v98
	v_exp_f32_e32 v99, v99


; DEV float bflo(unsigned u) { return __uint_as_float(u << 16); }
; DEV float bfhi(unsigned u) { return __uint_as_float(u & 0xffff0000u); }
; DEV float silu_f(float x) { return x / (1.f + __expf(-x)); }
; DEV void gdn_prep_chunk(const Params& p, int item, unsigned char* lds) {
;     ...
;         for (int r = 0; r < 16; ++r) {
;             float y[8]; float ss = 0.f;
; #pragma unroll
;             for (int e = 0; e < 8; ++e) {
;                 float a = 0.f;
; #pragma unroll
;                 for (int j = 0; j < 4; ++j) {
;                     const uint4 u = raw[r + j];
;                     const unsigned wd = (e < 2 ? u.x : (e < 4 ? u.y : (e < 6 ? u.z : u.w)));
;                     const float xv = (e & 1) ? bfhi(wd) : bflo(wd);
;                     a += w[j][e] * xv;
;                 }
;                 y[e] = silu_f(a); ss += y[e] * y[e];
;             }
	s_nop 0
	v_pk_add_f32 v[126:127], v[98:99], 1.0 op_sel_hi:[1,0]


; DEV float bflo(unsigned u) { return __uint_as_float(u << 16); }
; DEV float bfhi(unsigned u) { return __uint_as_float(u & 0xffff0000u); }
; DEV float silu_f(float x) { return x / (1.f + __expf(-x)); }
; DEV void gdn_prep_chunk(const Params& p, int item, unsigned char* lds) {
;     ...
;         for (int r = 0; r < 16; ++r) {
;             float y[8]; float ss = 0.f;
; #pragma unroll
;             for (int e = 0; e < 8; ++e) {
;                 float a = 0.f;
; #pragma unroll
;                 for (int j = 0; j < 4; ++j) {
;                     const uint4 u = raw[r + j];
;                     const unsigned wd = (e < 2 ? u.x : (e < 4 ? u.y : (e < 6 ? u.z : u.w)));
;                     const float xv = (e & 1) ? bfhi(wd) : bflo(wd);
;                     a += w[j][e] * xv;
;                 }
;                 y[e] = silu_f(a); ss += y[e] * y[e];
;             }
	v_rcp_f32_e32 v106, v120
	s_nop 0
	v_mul_f32_e32 v124, v122, v106


; DEV float bflo(unsigned u) { return __uint_as_float(u << 16); }
; DEV float bfhi(unsigned u) { return __uint_as_float(u & 0xffff0000u); }
; DEV float silu_f(float x) { return x / (1.f + __expf(-x)); }
; DEV void gdn_prep_chunk(const Params& p, int item, unsigned char* lds) {
;     ...
;         for (int r = 0; r < 16; ++r) {
;             float y[8]; float ss = 0.f;
; #pragma unroll
;             for (int e = 0; e < 8; ++e) {
;                 float a = 0.f;
; #pragma unroll
;                 for (int j = 0; j < 4; ++j) {
;                     const uint4 u = raw[r + j];
;                     const unsigned wd = (e < 2 ? u.x : (e < 4 ? u.y : (e < 6 ? u.z : u.w)));
;                     const float xv = (e & 1) ? bfhi(wd) : bflo(wd);
;                     a += w[j][e] * xv;
;                 }
;                 y[e] = silu_f(a); ss += y[e] * y[e];
;             }
	v_lshlrev_b32_e32 v120, 16, v100
	v_and_b32_e32 v121, 0xffff0000, v100

; DEV float bflo(unsigned u) { return __uint_as_float(u << 16); }
; DEV float bfhi(unsigned u) { return __uint_as_float(u & 0xffff0000u); }
; DEV float silu_f(float x) { return x / (1.f + __expf(-x)); }
; DEV void gdn_prep_chunk(const Params& p, int item, unsigned char* lds) {
;     ...
;         for (int r = 0; r < 16; ++r) {
;             float y[8]; float ss = 0.f;
; #pragma unroll
;             for (int e = 0; e < 8; ++e) {
;                 float a = 0.f;
; #pragma unroll
;                 for (int j = 0; j < 4; ++j) {
;                     const uint4 u = raw[r + j];
;                     const unsigned wd = (e < 2 ? u.x : (e < 4 ? u.y : (e < 6 ? u.z : u.w)));
;                     const float xv = (e & 1) ? bfhi(wd) : bflo(wd);
;                     a += w[j][e] * xv;
;                 }
;                 y[e] = silu_f(a); ss += y[e] * y[e];
;             }
	v_lshlrev_b32_e32 v122, 16, v96
	v_and_b32_e32 v123, 0xffff0000, v96
	v_pk_fma_f32 v[120:121], v[2:3], v[120:121], 0 op_sel_hi:[1,1,0]
	v_rcp_f32_e32 v98, v127
	s_nop 0
	v_mul_f32_e32 v103, v103, v98

; DEV float bflo(unsigned u) { return __uint_as_float(u << 16); }
; DEV float bfhi(unsigned u) { return __uint_as_float(u & 0xffff0000u); }
; DEV float silu_f(float x) { return x / (1.f + __expf(-x)); }
; DEV void gdn_prep_chunk(const Params& p, int item, unsigned char* lds) {
;     ...
;         for (int r = 0; r < 16; ++r) {
;             float y[8]; float ss = 0.f;
; #pragma unroll
;             for (int e = 0; e < 8; ++e) {
;                 float a = 0.f;
; #pragma unroll
;                 for (int j = 0; j < 4; ++j) {
;                     const uint4 u = raw[r + j];
;                     const unsigned wd = (e < 2 ? u.x : (e < 4 ? u.y : (e < 6 ? u.z : u.w)));
;                     const float xv = (e & 1) ? bfhi(wd) : bflo(wd);
;                     a += w[j][e] * xv;
;                 }
;                 y[e] = silu_f(a); ss += y[e] * y[e];
;             }
	v_lshlrev_b32_e32 v106, 16, v104
	v_and_b32_e32 v107, 0xffff0000, v104
	v_pk_fma_f32 v[120:121], v[6:7], v[122:123], v[120:121]

; DEV float bflo(unsigned u) { return __uint_as_float(u << 16); }
; DEV float bfhi(unsigned u) { return __uint_as_float(u & 0xffff0000u); }
; DEV float silu_f(float x) { return x / (1.f + __expf(-x)); }
; DEV void gdn_prep_chunk(const Params& p, int item, unsigned char* lds) {
;     ...
;         for (int r = 0; r < 16; ++r) {
;             float y[8]; float ss = 0.f;
; #pragma unroll
;             for (int e = 0; e < 8; ++e) {
;                 float a = 0.f;
; #pragma unroll
;                 for (int j = 0; j < 4; ++j) {
;                     const uint4 u = raw[r + j];
;                     const unsigned wd = (e < 2 ? u.x : (e < 4 ? u.y : (e < 6 ? u.z : u.w)));
;                     const float xv = (e & 1) ? bfhi(wd) : bflo(wd);
;                     a += w[j][e] * xv;
;                 }
;                 y[e] = silu_f(a); ss += y[e] * y[e];
;             }
	v_lshlrev_b32_e32 v98, 16, v108
	v_and_b32_e32 v99, 0xffff0000, v108
	v_pk_fma_f32 v[120:121], v[10:11], v[106:107], v[120:121]

; DEV float bflo(unsigned u) { return __uint_as_float(u << 16); }
; DEV float bfhi(unsigned u) { return __uint_as_float(u & 0xffff0000u); }
; DEV float silu_f(float x) { return x / (1.f + __expf(-x)); }
; DEV void gdn_prep_chunk(const Params& p, int item, unsigned char* lds) {
;     ...
;         for (int r = 0; r < 16; ++r) {
;             float y[8]; float ss = 0.f;
; #pragma unroll
;             for (int e = 0; e < 8; ++e) {
;                 float a = 0.f;
; #pragma unroll
;                 for (int j = 0; j < 4; ++j) {
;                     const uint4 u = raw[r + j];
;                     const unsigned wd = (e < 2 ? u.x : (e < 4 ? u.y : (e < 6 ? u.z : u.w)));
;                     const float xv = (e & 1) ? bfhi(wd) : bflo(wd);
;                     a += w[j][e] * xv;
;                 }
;                 y[e] = silu_f(a); ss += y[e] * y[e];
;             }
	v_pk_fma_f32 v[128:129], v[14:15], v[98:99], v[120:121]

; DEV float bflo(unsigned u) { return __uint_as_float(u << 16); }
; DEV float bfhi(unsigned u) { return __uint_as_float(u & 0xffff0000u); }
; DEV float silu_f(float x) { return x / (1.f + __expf(-x)); }
; DEV void gdn_prep_chunk(const Params& p, int item, unsigned char* lds) {
;     ...
;         for (int r = 0; r < 16; ++r) {
;             float y[8]; float ss = 0.f;
; #pragma unroll
;             for (int e = 0; e < 8; ++e) {
;                 float a = 0.f;
; #pragma unroll
;                 for (int j = 0; j < 4; ++j) {
;                     const uint4 u = raw[r + j];
;                     const unsigned wd = (e < 2 ? u.x : (e < 4 ? u.y : (e < 6 ? u.z : u.w)));
;                     const float xv = (e & 1) ? bfhi(wd) : bflo(wd);
;                     a += w[j][e] * xv;
;                 }
;                 y[e] = silu_f(a); ss += y[e] * y[e];
;             }
	v_mul_f32_e32 v96, 0xbfb8aa3b, v128
	v_exp_f32_e32 v120, v96
	v_mul_f32_e32 v96, 0xbfb8aa3b, v129
	v_exp_f32_e32 v121, v96


; DEV float bflo(unsigned u) { return __uint_as_float(u << 16); }
; DEV float bfhi(unsigned u) { return __uint_as_float(u & 0xffff0000u); }
; DEV float silu_f(float x) { return x / (1.f + __expf(-x)); }
; DEV void gdn_prep_chunk(const Params& p, int item, unsigned char* lds) {
;     ...
;         for (int r = 0; r < 16; ++r) {
;             float y[8]; float ss = 0.f;
; #pragma unroll
;             for (int e = 0; e < 8; ++e) {
;                 float a = 0.f;
; #pragma unroll
;                 for (int j = 0; j < 4; ++j) {
;                     const uint4 u = raw[r + j];
;                     const unsigned wd = (e < 2 ? u.x : (e < 4 ? u.y : (e < 6 ? u.z : u.w)));
;                     const float xv = (e & 1) ? bfhi(wd) : bflo(wd);
;                     a += w[j][e] * xv;
;                 }
;                 y[e] = silu_f(a); ss += y[e] * y[e];
;             }
	s_nop 0
	v_pk_add_f32 v[134:135], v[120:121], 1.0 op_sel_hi:[1,0]


; DEV float bflo(unsigned u) { return __uint_as_float(u << 16); }
; DEV float bfhi(unsigned u) { return __uint_as_float(u & 0xffff0000u); }
; DEV float silu_f(float x) { return x / (1.f + __expf(-x)); }
; DEV void gdn_prep_chunk(const Params& p, int item, unsigned char* lds) {
;     ...
;         for (int r = 0; r < 16; ++r) {
;             float y[8]; float ss = 0.f;
; #pragma unroll
;             for (int e = 0; e < 8; ++e) {
;                 float a = 0.f;
; #pragma unroll
;                 for (int j = 0; j < 4; ++j) {
;                     const uint4 u = raw[r + j];
;                     const unsigned wd = (e < 2 ? u.x : (e < 4 ? u.y : (e < 6 ? u.z : u.w)));
;                     const float xv = (e & 1) ? bfhi(wd) : bflo(wd);
;                     a += w[j][e] * xv;
;                 }
;                 y[e] = silu_f(a); ss += y[e] * y[e];
;             }
	v_rcp_f32_e32 v96, v126
	s_nop 0
	v_mul_f32_e32 v102, v102, v96


; DEV float bflo(unsigned u) { return __uint_as_float(u << 16); }
; DEV float bfhi(unsigned u) { return __uint_as_float(u & 0xffff0000u); }
; DEV float silu_f(float x) { return x / (1.f + __expf(-x)); }
; DEV void gdn_prep_chunk(const Params& p, int item, unsigned char* lds) {
;     ...
;         for (int r = 0; r < 16; ++r) {
;             float y[8]; float ss = 0.f;
; #pragma unroll
;             for (int e = 0; e < 8; ++e) {
;                 float a = 0.f;
; #pragma unroll
;                 for (int j = 0; j < 4; ++j) {
;                     const uint4 u = raw[r + j];
;                     const unsigned wd = (e < 2 ? u.x : (e < 4 ? u.y : (e < 6 ? u.z : u.w)));
;                     const float xv = (e & 1) ? bfhi(wd) : bflo(wd);
;                     a += w[j][e] * xv;
;                 }
;                 y[e] = silu_f(a); ss += y[e] * y[e];
;             }
	v_lshlrev_b32_e32 v100, 16, v101
	v_and_b32_e32 v101, 0xffff0000, v101

; DEV float bflo(unsigned u) { return __uint_as_float(u << 16); }
; DEV float bfhi(unsigned u) { return __uint_as_float(u & 0xffff0000u); }
; DEV float silu_f(float x) { return x / (1.f + __expf(-x)); }
; DEV void gdn_prep_chunk(const Params& p, int item, unsigned char* lds) {
;     ...
;         for (int r = 0; r < 16; ++r) {
;             float y[8]; float ss = 0.f;
; #pragma unroll
;             for (int e = 0; e < 8; ++e) {
;                 float a = 0.f;
; #pragma unroll
;                 for (int j = 0; j < 4; ++j) {
;                     const uint4 u = raw[r + j];
;                     const unsigned wd = (e < 2 ? u.x : (e < 4 ? u.y : (e < 6 ? u.z : u.w)));
;                     const float xv = (e & 1) ? bfhi(wd) : bflo(wd);
;                     a += w[j][e] * xv;
;                 }
;                 y[e] = silu_f(a); ss += y[e] * y[e];
;             }
	v_lshlrev_b32_e32 v126, 16, v97
	v_and_b32_e32 v127, 0xffff0000, v97
	v_pk_fma_f32 v[100:101], v[4:5], v[100:101], 0 op_sel_hi:[1,1,0]
	v_rcp_f32_e32 v96, v135
	s_nop 0
	v_mul_f32_e32 v129, v129, v96

; DEV float bflo(unsigned u) { return __uint_as_float(u << 16); }
; DEV float bfhi(unsigned u) { return __uint_as_float(u & 0xffff0000u); }
; DEV float silu_f(float x) { return x / (1.f + __expf(-x)); }
; DEV void gdn_prep_chunk(const Params& p, int item, unsigned char* lds) {
;     ...
;         for (int r = 0; r < 16; ++r) {
;             float y[8]; float ss = 0.f;
; #pragma unroll
;             for (int e = 0; e < 8; ++e) {
;                 float a = 0.f;
; #pragma unroll
;                 for (int j = 0; j < 4; ++j) {
;                     const uint4 u = raw[r + j];
;                     const unsigned wd = (e < 2 ? u.x : (e < 4 ? u.y : (e < 6 ? u.z : u.w)));
;                     const float xv = (e & 1) ? bfhi(wd) : bflo(wd);
;                     a += w[j][e] * xv;
;                 }
;                 y[e] = silu_f(a); ss += y[e] * y[e];
;             }
	v_lshlrev_b32_e32 v120, 16, v105
	v_and_b32_e32 v121, 0xffff0000, v105
	v_pk_fma_f32 v[100:101], v[8:9], v[126:127], v[100:101]

; DEV float bflo(unsigned u) { return __uint_as_float(u << 16); }
; DEV float bfhi(unsigned u) { return __uint_as_float(u & 0xffff0000u); }
; DEV float silu_f(float x) { return x / (1.f + __expf(-x)); }
; DEV void gdn_prep_chunk(const Params& p, int item, unsigned char* lds) {
;     ...
;         for (int r = 0; r < 16; ++r) {
;             float y[8]; float ss = 0.f;
; #pragma unroll
;             for (int e = 0; e < 8; ++e) {
;                 float a = 0.f;
; #pragma unroll
;                 for (int j = 0; j < 4; ++j) {
;                     const uint4 u = raw[r + j];
;                     const unsigned wd = (e < 2 ? u.x : (e < 4 ? u.y : (e < 6 ? u.z : u.w)));
;                     const float xv = (e & 1) ? bfhi(wd) : bflo(wd);
;                     a += w[j][e] * xv;
;                 }
;                 y[e] = silu_f(a); ss += y[e] * y[e];
;             }
	v_lshlrev_b32_e32 v96, 16, v109
	v_and_b32_e32 v97, 0xffff0000, v109
	v_pk_fma_f32 v[100:101], v[12:13], v[120:121], v[100:101]

; DEV float bflo(unsigned u) { return __uint_as_float(u << 16); }
; DEV float bfhi(unsigned u) { return __uint_as_float(u & 0xffff0000u); }
; DEV float silu_f(float x) { return x / (1.f + __expf(-x)); }
; DEV void gdn_prep_chunk(const Params& p, int item, unsigned char* lds) {
;     ...
;         for (int r = 0; r < 16; ++r) {
;             float y[8]; float ss = 0.f;
; #pragma unroll
;             for (int e = 0; e < 8; ++e) {
;                 float a = 0.f;
; #pragma unroll
;                 for (int j = 0; j < 4; ++j) {
;                     const uint4 u = raw[r + j];
;                     const unsigned wd = (e < 2 ? u.x : (e < 4 ? u.y : (e < 6 ? u.z : u.w)));
;                     const float xv = (e & 1) ? bfhi(wd) : bflo(wd);
;                     a += w[j][e] * xv;
;                 }
;                 y[e] = silu_f(a); ss += y[e] * y[e];
;             }
	v_pk_fma_f32 v[100:101], v[16:17], v[96:97], v[100:101]

; DEV float bflo(unsigned u) { return __uint_as_float(u << 16); }
; DEV float bfhi(unsigned u) { return __uint_as_float(u & 0xffff0000u); }
; DEV float silu_f(float x) { return x / (1.f + __expf(-x)); }
; DEV void gdn_prep_chunk(const Params& p, int item, unsigned char* lds) {
;     ...
;         for (int r = 0; r < 16; ++r) {
;             float y[8]; float ss = 0.f;
; #pragma unroll
;             for (int e = 0; e < 8; ++e) {
;                 float a = 0.f;
; #pragma unroll
;                 for (int j = 0; j < 4; ++j) {
;                     const uint4 u = raw[r + j];
;                     const unsigned wd = (e < 2 ? u.x : (e < 4 ? u.y : (e < 6 ? u.z : u.w)));
;                     const float xv = (e & 1) ? bfhi(wd) : bflo(wd);
;                     a += w[j][e] * xv;
;                 }
;                 y[e] = silu_f(a); ss += y[e] * y[e];
;             }
	v_mul_f32_e32 v104, 0xbfb8aa3b, v100
	v_mul_f32_e32 v105, 0xbfb8aa3b, v101
	v_exp_f32_e32 v104, v104
	v_exp_f32_e32 v105, v105


; DEV float silu_f(float x) { return x / (1.f + __expf(-x)); }
; DEV void gdn_prep_chunk(const Params& p, int item, unsigned char* lds) {
;     ...
;                 y[e] = silu_f(a); ss += y[e] * y[e];
	s_nop 0
	v_pk_add_f32 v[104:105], v[104:105], 1.0 op_sel_hi:[1,0]


; DEV float silu_f(float x) { return x / (1.f + __expf(-x)); }
; DEV void gdn_prep_chunk(const Params& p, int item, unsigned char* lds) {
;     ...
;                 y[e] = silu_f(a); ss += y[e] * y[e];
	v_rcp_f32_e32 v108, v134
	s_nop 0
	v_mul_f32_e32 v128, v128, v108


; DEV float silu_f(float x) { return x / (1.f + __expf(-x)); }
; DEV void gdn_prep_chunk(const Params& p, int item, unsigned char* lds) {
;     ...
;                 y[e] = silu_f(a); ss += y[e] * y[e];
	v_rcp_f32_e32 v108, v105
	s_nop 0
	v_mul_f32_e32 v101, v101, v108


; DEV unsigned cvt_pk_bf16(float lo, float hi) { const f32x2_t v = {lo, hi}; const bf16x2_t b = __builtin_convertvector(v, bf16x2_t); return __builtin_bit_cast(unsigned, b); }
; DEV float bflo(unsigned u) { return __uint_as_float(u << 16); }
; DEV float bfhi(unsigned u) { return __uint_as_float(u & 0xffff0000u); }
; DEV float silu_f(float x) { return x / (1.f + __expf(-x)); }
; DEV void gdn_prep_chunk(const Params& p, int item, unsigned char* lds) {
;     ...
;             for (int e = 0; e < 8; ++e) {
;                 float a = 0.f;
; #pragma unroll
;                 for (int j = 0; j < 4; ++j) {
;                     const uint4 u = raw[r + j];
;                     const unsigned wd = (e < 2 ? u.x : (e < 4 ? u.y : (e < 6 ? u.z : u.w)));
;                     const float xv = (e & 1) ? bfhi(wd) : bflo(wd);
;                     a += w[j][e] * xv;
;                 }
;                 y[e] = silu_f(a); ss += y[e] * y[e];
;     ...
;             if (mat < 2) {
;                 ss += __shfl_xor(ss, 1); ss += __shfl_xor(ss, 2); ss += __shfl_xor(ss, 4); ss += __shfl_xor(ss, 8);
;                 float inv = rsqrtf(ss + EPS); if (mat == 0) inv *= 0.08838834764831845f;
; #pragma unroll
;                 for (int e = 0; e < 8; ++e) y[e] *= inv;
;             }
;             uint4 o; o.x = cvt_pk_bf16(y[0], y[1]); o.y = cvt_pk_bf16(y[2], y[3]); o.z = cvt_pk_bf16(y[4], y[5]); o.w = cvt_pk_bf16(y[6], y[7]);
;             *(uint4*)(dst + (tl0 + r) * QS + cv * 8) = o;
	v_rcp_f32_e32 v105, v104
	s_nop 0
	v_mul_f32_e32 v100, v100, v105
	s_and_saveexec_b64 s[36:37], s[6:7]
	s_cbranch_execz .LBB0_474
	v_pk_mul_f32 v[104:105], v[124:125], v[124:125]
	v_pk_mul_f32 v[108:109], v[102:103], v[102:103]
	v_add_f32_e32 v104, v104, v105
	v_add_f32_e32 v104, v104, v108
	v_pk_mul_f32 v[134:135], v[128:129], v[128:129]
	v_add_f32_e32 v104, v109, v104
	v_and_b32_e32 v108, 64, v182
	v_add_f32_e32 v104, v134, v104
	v_xor_b32_e32 v105, 1, v182
	v_add_u32_e32 v108, 64, v108
	v_pk_mul_f32 v[136:137], v[100:101], v[100:101]
	v_add_f32_e32 v104, v135, v104
	v_cmp_lt_i32_e32 vcc, v105, v108
	v_add_f32_e32 v104, v136, v104
	v_add_f32_e32 v104, v137, v104
	v_cndmask_b32_e32 v105, v182, v105, vcc
	v_lshlrev_b32_e32 v105, 2, v105
	ds_bpermute_b32 v105, v105, v104
	s_waitcnt lgkmcnt(0)
	v_add_f32_e32 v104, v104, v105
	v_xor_b32_e32 v105, 2, v182
	v_cmp_lt_i32_e32 vcc, v105, v108
	s_nop 1
	v_cndmask_b32_e32 v105, v182, v105, vcc
	v_lshlrev_b32_e32 v105, 2, v105
	ds_bpermute_b32 v105, v105, v104
	s_waitcnt lgkmcnt(0)
	v_add_f32_e32 v104, v104, v105
	v_xor_b32_e32 v105, 4, v182
	v_cmp_lt_i32_e32 vcc, v105, v108
	s_nop 1
	v_cndmask_b32_e32 v105, v182, v105, vcc
	v_lshlrev_b32_e32 v105, 2, v105
	ds_bpermute_b32 v105, v105, v104
	s_waitcnt lgkmcnt(0)
	v_add_f32_e32 v104, v104, v105
	v_xor_b32_e32 v105, 8, v182
	v_cmp_lt_i32_e32 vcc, v105, v108
	s_nop 1
	v_cndmask_b32_e32 v105, v182, v105, vcc
	v_lshlrev_b32_e32 v105, 2, v105
	ds_bpermute_b32 v105, v105, v104
	s_waitcnt lgkmcnt(0)
	v_add_f32_e32 v104, v104, v105
	v_add_f32_e32 v104, 0x358637bd, v104
	v_mul_f32_e32 v105, 0x4b800000, v104
	v_cmp_gt_f32_e32 vcc, s56, v104
	s_nop 1
	v_cndmask_b32_e32 v104, v104, v105, vcc
	v_rsq_f32_e32 v104, v104
	s_nop 0
	v_mul_f32_e32 v105, 0x45800000, v104
	v_cndmask_b32_e32 v104, v104, v105, vcc
	v_mul_f32_e32 v105, 0x3db504f3, v104
	v_cndmask_b32_e64 v104, v104, v105, s[4:5]
	v_pk_mul_f32 v[124:125], v[124:125], v[104:105] op_sel_hi:[1,0]
	v_pk_mul_f32 v[102:103], v[102:103], v[104:105] op_sel_hi:[1,0]
	v_pk_mul_f32 v[128:129], v[128:129], v[104:105] op_sel_hi:[1,0]
	v_pk_mul_f32 v[100:101], v[100:101], v[104:105] op_sel_hi:[1,0]
.LBB0_474:
	s_or_b64 exec, exec, s[36:37]
	v_mov_b32_e32 v104, s42
	v_mov_b32_e32 v105, s41
	v_cmp_eq_u32_e32 vcc, 1, v131
	v_pk_fma_f32 v[108:109], v[18:19], v[116:117], 0 op_sel_hi:[1,1,0]
	v_cvt_pk_bf16_f32 v135, v102, v103
	v_cndmask_b32_e32 v104, v104, v105, vcc
	v_mov_b32_e32 v105, s39
	v_cndmask_b32_e64 v104, v104, v105, s[4:5]
	v_pk_fma_f32 v[108:109], v[22:23], v[112:113], v[108:109]
	v_lshl_add_u32 v132, v132, 1, v104
	s_waitcnt vmcnt(14)
	v_lshlrev_b32_e32 v104, 16, v90
	v_and_b32_e32 v105, 0xffff0000, v90
	v_pk_fma_f32 v[108:109], v[26:27], v[110:111], v[108:109]
	v_cvt_pk_bf16_f32 v134, v124, v125
	v_pk_fma_f32 v[108:109], v[30:31], v[104:105], v[108:109]
	v_cvt_pk_bf16_f32 v136, v128, v129
	v_mul_f32_e32 v90, 0xbfb8aa3b, v108
	v_exp_f32_e32 v116, v90
	v_mul_f32_e32 v90, 0xbfb8aa3b, v109
	v_exp_f32_e32 v117, v90
	v_cvt_pk_bf16_f32 v137, v100, v101
	v_mad_u32_u24 v100, v133, s57, v132
	ds_write_b128 v100, v[134:137]
	v_pk_add_f32 v[116:117], v[116:117], 1.0 op_sel_hi:[1,0]
	v_pk_fma_f32 v[122:123], v[2:3], v[122:123], 0 op_sel_hi:[1,1,0]


; DEV float silu_f(float x) { return x / (1.f + __expf(-x)); }
; DEV void gdn_prep_chunk(const Params& p, int item, unsigned char* lds) {
;     ...
;                 y[e] = silu_f(a); ss += y[e] * y[e];
	v_rcp_f32_e32 v90, v117
	s_nop 0
	v_mul_f32_e32 v109, v109, v90


; DEV float bflo(unsigned u) { return __uint_as_float(u << 16); }
; DEV float bfhi(unsigned u) { return __uint_as_float(u & 0xffff0000u); }
; DEV void gdn_prep_chunk(const Params& p, int item, unsigned char* lds) {
;     ...
;                 for (int j = 0; j < 4; ++j) {
;                     const uint4 u = raw[r + j];
;                     const unsigned wd = (e < 2 ? u.x : (e < 4 ? u.y : (e < 6 ? u.z : u.w)));
;                     const float xv = (e & 1) ? bfhi(wd) : bflo(wd);
;                     a += w[j][e] * xv;
	v_lshlrev_b32_e32 v102, 16, v91
	v_and_b32_e32 v103, 0xffff0000, v91
	v_pk_fma_f32 v[90:91], v[20:21], v[118:119], 0 op_sel_hi:[1,1,0]

; DEV float bflo(unsigned u) { return __uint_as_float(u << 16); }
; DEV float bfhi(unsigned u) { return __uint_as_float(u & 0xffff0000u); }
; DEV void gdn_prep_chunk(const Params& p, int item, unsigned char* lds) {
;     ...
;                 for (int j = 0; j < 4; ++j) {
;                     const uint4 u = raw[r + j];
;                     const unsigned wd = (e < 2 ? u.x : (e < 4 ? u.y : (e < 6 ? u.z : u.w)));
;                     const float xv = (e & 1) ? bfhi(wd) : bflo(wd);
;                     a += w[j][e] * xv;
	v_pk_fma_f32 v[90:91], v[24:25], v[114:115], v[90:91]

; DEV float bflo(unsigned u) { return __uint_as_float(u << 16); }
; DEV float bfhi(unsigned u) { return __uint_as_float(u & 0xffff0000u); }
; DEV void gdn_prep_chunk(const Params& p, int item, unsigned char* lds) {
;     ...
;                 for (int j = 0; j < 4; ++j) {
;                     const uint4 u = raw[r + j];
;                     const unsigned wd = (e < 2 ? u.x : (e < 4 ? u.y : (e < 6 ? u.z : u.w)));
;                     const float xv = (e & 1) ? bfhi(wd) : bflo(wd);
;                     a += w[j][e] * xv;
	v_pk_fma_f32 v[90:91], v[28:29], v[94:95], v[90:91]

; DEV float bflo(unsigned u) { return __uint_as_float(u << 16); }
; DEV float bfhi(unsigned u) { return __uint_as_float(u & 0xffff0000u); }
; DEV void gdn_prep_chunk(const Params& p, int item, unsigned char* lds) {
;     ...
;                 for (int j = 0; j < 4; ++j) {
;                     const uint4 u = raw[r + j];
;                     const unsigned wd = (e < 2 ? u.x : (e < 4 ? u.y : (e < 6 ? u.z : u.w)));
;                     const float xv = (e & 1) ? bfhi(wd) : bflo(wd);
;                     a += w[j][e] * xv;
	v_pk_fma_f32 v[90:91], v[32:33], v[102:103], v[90:91]

; DEV float silu_f(float x) { return x / (1.f + __expf(-x)); }
; DEV void gdn_prep_chunk(const Params& p, int item, unsigned char* lds) {
;     ...
;                 y[e] = silu_f(a); ss += y[e] * y[e];
	v_mul_f32_e32 v100, 0xbfb8aa3b, v90
	v_mul_f32_e32 v101, 0xbfb8aa3b, v91
	v_exp_f32_e32 v100, v100
	v_exp_f32_e32 v101, v101


; DEV float bflo(unsigned u) { return __uint_as_float(u << 16); }
; DEV float bfhi(unsigned u) { return __uint_as_float(u & 0xffff0000u); }
; DEV float silu_f(float x) { return x / (1.f + __expf(-x)); }
; DEV void gdn_prep_chunk(const Params& p, int item, unsigned char* lds) {
;     ...
;                 for (int j = 0; j < 4; ++j) {
;                     const uint4 u = raw[r + j];
;                     const unsigned wd = (e < 2 ? u.x : (e < 4 ? u.y : (e < 6 ? u.z : u.w)));
;                     const float xv = (e & 1) ? bfhi(wd) : bflo(wd);
;                     a += w[j][e] * xv;
;     ...
;                 y[e] = silu_f(a); ss += y[e] * y[e];
	v_rcp_f32_e32 v117, v116
	s_nop 0
	v_mul_f32_e32 v108, v108, v117
	v_pk_add_f32 v[118:119], v[100:101], 1.0 op_sel_hi:[1,0]
	v_pk_fma_f32 v[122:123], v[6:7], v[106:107], v[122:123]


; DEV float bflo(unsigned u) { return __uint_as_float(u << 16); }
; DEV float bfhi(unsigned u) { return __uint_as_float(u & 0xffff0000u); }
; DEV void gdn_prep_chunk(const Params& p, int item, unsigned char* lds) {
;     ...
;                 for (int j = 0; j < 4; ++j) {
;                     const uint4 u = raw[r + j];
;                     const unsigned wd = (e < 2 ? u.x : (e < 4 ? u.y : (e < 6 ? u.z : u.w)));
;                     const float xv = (e & 1) ? bfhi(wd) : bflo(wd);
;                     a += w[j][e] * xv;
	v_pk_fma_f32 v[122:123], v[10:11], v[98:99], v[122:123]


; DEV float bflo(unsigned u) { return __uint_as_float(u << 16); }
; DEV float bfhi(unsigned u) { return __uint_as_float(u & 0xffff0000u); }
; DEV float silu_f(float x) { return x / (1.f + __expf(-x)); }
; DEV void gdn_prep_chunk(const Params& p, int item, unsigned char* lds) {
;     ...
;                 for (int j = 0; j < 4; ++j) {
;                     const uint4 u = raw[r + j];
;                     const unsigned wd = (e < 2 ? u.x : (e < 4 ? u.y : (e < 6 ? u.z : u.w)));
;                     const float xv = (e & 1) ? bfhi(wd) : bflo(wd);
;                     a += w[j][e] * xv;
;     ...
;                 y[e] = silu_f(a); ss += y[e] * y[e];
	v_rcp_f32_e32 v100, v119
	s_nop 0
	v_mul_f32_e32 v117, v91, v100
	v_lshlrev_b32_e32 v100, 16, v92
	v_and_b32_e32 v101, 0xffff0000, v92

; DEV float bflo(unsigned u) { return __uint_as_float(u << 16); }
; DEV float bfhi(unsigned u) { return __uint_as_float(u & 0xffff0000u); }
; DEV void gdn_prep_chunk(const Params& p, int item, unsigned char* lds) {
;     ...
;                 for (int j = 0; j < 4; ++j) {
;                     const uint4 u = raw[r + j];
;                     const unsigned wd = (e < 2 ? u.x : (e < 4 ? u.y : (e < 6 ? u.z : u.w)));
;                     const float xv = (e & 1) ? bfhi(wd) : bflo(wd);
;                     a += w[j][e] * xv;
	v_pk_fma_f32 v[122:123], v[14:15], v[100:101], v[122:123]

; DEV float silu_f(float x) { return x / (1.f + __expf(-x)); }
; DEV void gdn_prep_chunk(const Params& p, int item, unsigned char* lds) {
;     ...
;                 y[e] = silu_f(a); ss += y[e] * y[e];
	v_mul_f32_e32 v92, 0xbfb8aa3b, v122
	v_exp_f32_e32 v124, v92
	v_mul_f32_e32 v92, 0xbfb8aa3b, v123
	v_exp_f32_e32 v125, v92


; DEV float silu_f(float x) { return x / (1.f + __expf(-x)); }
; DEV void gdn_prep_chunk(const Params& p, int item, unsigned char* lds) {
;     ...
;                 y[e] = silu_f(a); ss += y[e] * y[e];
	s_nop 0
	v_pk_add_f32 v[124:125], v[124:125], 1.0 op_sel_hi:[1,0]


; DEV float silu_f(float x) { return x / (1.f + __expf(-x)); }
; DEV void gdn_prep_chunk(const Params& p, int item, unsigned char* lds) {
;     ...
;                 y[e] = silu_f(a); ss += y[e] * y[e];
	v_rcp_f32_e32 v91, v118
	s_nop 0
	v_mul_f32_e32 v116, v90, v91


; DEV float silu_f(float x) { return x / (1.f + __expf(-x)); }
; DEV void gdn_prep_chunk(const Params& p, int item, unsigned char* lds) {
;     ...
;                 y[e] = silu_f(a); ss += y[e] * y[e];
	v_rcp_f32_e32 v90, v125
	s_nop 0
	v_mul_f32_e32 v123, v123, v90


; DEV float bflo(unsigned u) { return __uint_as_float(u << 16); }
; DEV float bfhi(unsigned u) { return __uint_as_float(u & 0xffff0000u); }
; DEV void gdn_prep_chunk(const Params& p, int item, unsigned char* lds) {
;     ...
;                 for (int j = 0; j < 4; ++j) {
;                     const uint4 u = raw[r + j];
;                     const unsigned wd = (e < 2 ? u.x : (e < 4 ? u.y : (e < 6 ? u.z : u.w)));
;                     const float xv = (e & 1) ? bfhi(wd) : bflo(wd);
;                     a += w[j][e] * xv;
	v_lshlrev_b32_e32 v90, 16, v93
	v_and_b32_e32 v91, 0xffff0000, v93
	v_pk_fma_f32 v[92:93], v[4:5], v[126:127], 0 op_sel_hi:[1,1,0]

; DEV float bflo(unsigned u) { return __uint_as_float(u << 16); }
; DEV float bfhi(unsigned u) { return __uint_as_float(u & 0xffff0000u); }
; DEV void gdn_prep_chunk(const Params& p, int item, unsigned char* lds) {
;     ...
;                 for (int j = 0; j < 4; ++j) {
;                     const uint4 u = raw[r + j];
;                     const unsigned wd = (e < 2 ? u.x : (e < 4 ? u.y : (e < 6 ? u.z : u.w)));
;                     const float xv = (e & 1) ? bfhi(wd) : bflo(wd);
;                     a += w[j][e] * xv;
	v_pk_fma_f32 v[92:93], v[8:9], v[120:121], v[92:93]

; DEV float bflo(unsigned u) { return __uint_as_float(u << 16); }
; DEV float bfhi(unsigned u) { return __uint_as_float(u & 0xffff0000u); }
; DEV void gdn_prep_chunk(const Params& p, int item, unsigned char* lds) {
;     ...
;                 for (int j = 0; j < 4; ++j) {
;                     const uint4 u = raw[r + j];
;                     const unsigned wd = (e < 2 ? u.x : (e < 4 ? u.y : (e < 6 ? u.z : u.w)));
;                     const float xv = (e & 1) ? bfhi(wd) : bflo(wd);
;                     a += w[j][e] * xv;
	v_pk_fma_f32 v[92:93], v[12:13], v[96:97], v[92:93]

; DEV float bflo(unsigned u) { return __uint_as_float(u << 16); }
; DEV float bfhi(unsigned u) { return __uint_as_float(u & 0xffff0000u); }
; DEV void gdn_prep_chunk(const Params& p, int item, unsigned char* lds) {
;     ...
;                 for (int j = 0; j < 4; ++j) {
;                     const uint4 u = raw[r + j];
;                     const unsigned wd = (e < 2 ? u.x : (e < 4 ? u.y : (e < 6 ? u.z : u.w)));
;                     const float xv = (e & 1) ? bfhi(wd) : bflo(wd);
;                     a += w[j][e] * xv;
	v_pk_fma_f32 v[92:93], v[16:17], v[90:91], v[92:93]

; DEV float silu_f(float x) { return x / (1.f + __expf(-x)); }
; DEV void gdn_prep_chunk(const Params& p, int item, unsigned char* lds) {
;     ...
;                 y[e] = silu_f(a); ss += y[e] * y[e];
	v_mul_f32_e32 v118, 0xbfb8aa3b, v92
	v_mul_f32_e32 v119, 0xbfb8aa3b, v93
	v_exp_f32_e32 v118, v118
	v_exp_f32_e32 v119, v119


; DEV float silu_f(float x) { return x / (1.f + __expf(-x)); }
; DEV void gdn_prep_chunk(const Params& p, int item, unsigned char* lds) {
;     ...
;                 y[e] = silu_f(a); ss += y[e] * y[e];
	v_rcp_f32_e32 v125, v124
	s_nop 0
	v_mul_f32_e32 v122, v122, v125
	v_pk_add_f32 v[118:119], v[118:119], 1.0 op_sel_hi:[1,0]
	s_nop 0


; DEV float silu_f(float x) { return x / (1.f + __expf(-x)); }
; DEV void gdn_prep_chunk(const Params& p, int item, unsigned char* lds) {
;     ...
;                 y[e] = silu_f(a); ss += y[e] * y[e];
	s_nop 0


; DEV float silu_f(float x) { return x / (1.f + __expf(-x)); }
; DEV void gdn_prep_chunk(const Params& p, int item, unsigned char* lds) {
;     ...
;                 y[e] = silu_f(a); ss += y[e] * y[e];
	v_rcp_f32_e32 v124, v119
	s_nop 0
	v_mul_f32_e32 v93, v93, v124


; DEV unsigned cvt_pk_bf16(float lo, float hi) { const f32x2_t v = {lo, hi}; const bf16x2_t b = __builtin_convertvector(v, bf16x2_t); return __builtin_bit_cast(unsigned, b); }
; DEV float bflo(unsigned u) { return __uint_as_float(u << 16); }
; DEV float bfhi(unsigned u) { return __uint_as_float(u & 0xffff0000u); }
; DEV float silu_f(float x) { return x / (1.f + __expf(-x)); }
; DEV void gdn_prep_chunk(const Params& p, int item, unsigned char* lds) {
;     ...
;             for (int e = 0; e < 8; ++e) {
;                 float a = 0.f;
; #pragma unroll
;                 for (int j = 0; j < 4; ++j) {
;                     const uint4 u = raw[r + j];
;                     const unsigned wd = (e < 2 ? u.x : (e < 4 ? u.y : (e < 6 ? u.z : u.w)));
;                     const float xv = (e & 1) ? bfhi(wd) : bflo(wd);
;                     a += w[j][e] * xv;
;                 }
;                 y[e] = silu_f(a); ss += y[e] * y[e];
;     ...
;             if (mat < 2) {
;                 ss += __shfl_xor(ss, 1); ss += __shfl_xor(ss, 2); ss += __shfl_xor(ss, 4); ss += __shfl_xor(ss, 8);
;                 float inv = rsqrtf(ss + EPS); if (mat == 0) inv *= 0.08838834764831845f;
; #pragma unroll
;                 for (int e = 0; e < 8; ++e) y[e] *= inv;
;             }
;             uint4 o; o.x = cvt_pk_bf16(y[0], y[1]); o.y = cvt_pk_bf16(y[2], y[3]); o.z = cvt_pk_bf16(y[4], y[5]); o.w = cvt_pk_bf16(y[6], y[7]);
;             *(uint4*)(dst + (tl0 + r) * QS + cv * 8) = o;
	v_rcp_f32_e32 v119, v118
	s_nop 0
	v_mul_f32_e32 v92, v92, v119
	s_and_saveexec_b64 s[36:37], s[6:7]
	s_cbranch_execz .LBB0_476
	v_pk_mul_f32 v[118:119], v[108:109], v[108:109]
	v_pk_mul_f32 v[124:125], v[116:117], v[116:117]
	v_add_f32_e32 v118, v118, v119
	v_add_f32_e32 v118, v118, v124
	v_pk_mul_f32 v[126:127], v[122:123], v[122:123]
	v_add_f32_e32 v118, v125, v118
	v_and_b32_e32 v124, 64, v182
	v_add_f32_e32 v118, v126, v118
	v_xor_b32_e32 v119, 1, v182
	v_add_u32_e32 v124, 64, v124
	v_pk_mul_f32 v[128:129], v[92:93], v[92:93]
	v_add_f32_e32 v118, v127, v118
	v_cmp_lt_i32_e32 vcc, v119, v124
	v_add_f32_e32 v118, v128, v118
	v_add_f32_e32 v118, v129, v118
	v_cndmask_b32_e32 v119, v182, v119, vcc
	v_lshlrev_b32_e32 v119, 2, v119
	ds_bpermute_b32 v119, v119, v118
	s_waitcnt lgkmcnt(0)
	v_add_f32_e32 v118, v118, v119
	v_xor_b32_e32 v119, 2, v182
	v_cmp_lt_i32_e32 vcc, v119, v124
	s_nop 1
	v_cndmask_b32_e32 v119, v182, v119, vcc
	v_lshlrev_b32_e32 v119, 2, v119
	ds_bpermute_b32 v119, v119, v118
	s_waitcnt lgkmcnt(0)
	v_add_f32_e32 v118, v118, v119
	v_xor_b32_e32 v119, 4, v182
	v_cmp_lt_i32_e32 vcc, v119, v124
	s_nop 1
	v_cndmask_b32_e32 v119, v182, v119, vcc
	v_lshlrev_b32_e32 v119, 2, v119
	ds_bpermute_b32 v119, v119, v118
	s_waitcnt lgkmcnt(0)
	v_add_f32_e32 v118, v118, v119
	v_xor_b32_e32 v119, 8, v182
	v_cmp_lt_i32_e32 vcc, v119, v124
	s_nop 1
	v_cndmask_b32_e32 v119, v182, v119, vcc
	v_lshlrev_b32_e32 v119, 2, v119
	ds_bpermute_b32 v119, v119, v118
	s_waitcnt lgkmcnt(0)
	v_add_f32_e32 v118, v118, v119
	v_add_f32_e32 v118, 0x358637bd, v118
	v_mul_f32_e32 v119, 0x4b800000, v118
	v_cmp_gt_f32_e32 vcc, s56, v118
	s_nop 1
	v_cndmask_b32_e32 v118, v118, v119, vcc
	v_rsq_f32_e32 v118, v118
	s_nop 0
	v_mul_f32_e32 v119, 0x45800000, v118
	v_cndmask_b32_e32 v118, v118, v119, vcc
	v_mul_f32_e32 v119, 0x3db504f3, v118
	v_cndmask_b32_e64 v118, v118, v119, s[4:5]
	v_pk_mul_f32 v[108:109], v[108:109], v[118:119] op_sel_hi:[1,0]
	v_pk_mul_f32 v[116:117], v[116:117], v[118:119] op_sel_hi:[1,0]
	v_pk_mul_f32 v[122:123], v[122:123], v[118:119] op_sel_hi:[1,0]
	v_pk_mul_f32 v[92:93], v[92:93], v[118:119] op_sel_hi:[1,0]
.LBB0_476:
	s_or_b64 exec, exec, s[36:37]
	v_cvt_pk_bf16_f32 v124, v108, v109
	v_pk_fma_f32 v[108:109], v[18:19], v[112:113], 0 op_sel_hi:[1,1,0]
	s_waitcnt vmcnt(13)
	v_lshlrev_b32_e32 v118, 16, v86
	v_pk_fma_f32 v[108:109], v[22:23], v[110:111], v[108:109]
	v_and_b32_e32 v119, 0xffff0000, v86
	v_pk_fma_f32 v[108:109], v[26:27], v[104:105], v[108:109]
	v_cvt_pk_bf16_f32 v127, v92, v93
	v_pk_fma_f32 v[108:109], v[30:31], v[118:119], v[108:109]
	v_mul_u32_u24_e32 v128, 0x110, v133
	v_mul_f32_e32 v86, 0xbfb8aa3b, v108
	v_exp_f32_e32 v112, v86
	v_mul_f32_e32 v86, 0xbfb8aa3b, v109
	v_exp_f32_e32 v113, v86
	v_cvt_pk_bf16_f32 v126, v122, v123
	v_add_u32_e32 v122, 0x110, v128
	v_cvt_pk_bf16_f32 v125, v116, v117
	v_pk_add_f32 v[92:93], v[112:113], 1.0 op_sel_hi:[1,0]
	v_add_u32_e32 v113, v132, v122


; DEV float silu_f(float x) { return x / (1.f + __expf(-x)); }
; DEV void gdn_prep_chunk(const Params& p, int item, unsigned char* lds) {
;     ...
;                 y[e] = silu_f(a); ss += y[e] * y[e];
	ds_write_b128 v113, v[124:127]


; DEV float silu_f(float x) { return x / (1.f + __expf(-x)); }
; DEV void gdn_prep_chunk(const Params& p, int item, unsigned char* lds) {
;     ...
;                 y[e] = silu_f(a); ss += y[e] * y[e];
	v_rcp_f32_e32 v86, v93
	s_nop 0
	v_mul_f32_e32 v93, v109, v86


; DEV float bflo(unsigned u) { return __uint_as_float(u << 16); }
; DEV float bfhi(unsigned u) { return __uint_as_float(u & 0xffff0000u); }
; DEV void gdn_prep_chunk(const Params& p, int item, unsigned char* lds) {
;     ...
;                 for (int j = 0; j < 4; ++j) {
;                     const uint4 u = raw[r + j];
;                     const unsigned wd = (e < 2 ? u.x : (e < 4 ? u.y : (e < 6 ? u.z : u.w)));
;                     const float xv = (e & 1) ? bfhi(wd) : bflo(wd);
;                     a += w[j][e] * xv;
	v_lshlrev_b32_e32 v116, 16, v87
	v_and_b32_e32 v117, 0xffff0000, v87
	v_pk_fma_f32 v[86:87], v[20:21], v[114:115], 0 op_sel_hi:[1,1,0]

; DEV float bflo(unsigned u) { return __uint_as_float(u << 16); }
; DEV float bfhi(unsigned u) { return __uint_as_float(u & 0xffff0000u); }
; DEV void gdn_prep_chunk(const Params& p, int item, unsigned char* lds) {
;     ...
;                 for (int j = 0; j < 4; ++j) {
;                     const uint4 u = raw[r + j];
;                     const unsigned wd = (e < 2 ? u.x : (e < 4 ? u.y : (e < 6 ? u.z : u.w)));
;                     const float xv = (e & 1) ? bfhi(wd) : bflo(wd);
;                     a += w[j][e] * xv;
	v_pk_fma_f32 v[86:87], v[24:25], v[94:95], v[86:87]

; DEV float bflo(unsigned u) { return __uint_as_float(u << 16); }
; DEV float bfhi(unsigned u) { return __uint_as_float(u & 0xffff0000u); }
; DEV void gdn_prep_chunk(const Params& p, int item, unsigned char* lds) {
;     ...
;                 for (int j = 0; j < 4; ++j) {
;                     const uint4 u = raw[r + j];
;                     const unsigned wd = (e < 2 ? u.x : (e < 4 ? u.y : (e < 6 ? u.z : u.w)));
;                     const float xv = (e & 1) ? bfhi(wd) : bflo(wd);
;                     a += w[j][e] * xv;
	v_pk_fma_f32 v[86:87], v[28:29], v[102:103], v[86:87]

; DEV float bflo(unsigned u) { return __uint_as_float(u << 16); }
; DEV float bfhi(unsigned u) { return __uint_as_float(u & 0xffff0000u); }
; DEV void gdn_prep_chunk(const Params& p, int item, unsigned char* lds) {
;     ...
;                 for (int j = 0; j < 4; ++j) {
;                     const uint4 u = raw[r + j];
;                     const unsigned wd = (e < 2 ? u.x : (e < 4 ? u.y : (e < 6 ? u.z : u.w)));
;                     const float xv = (e & 1) ? bfhi(wd) : bflo(wd);
;                     a += w[j][e] * xv;
	v_pk_fma_f32 v[86:87], v[32:33], v[116:117], v[86:87]

; DEV float silu_f(float x) { return x / (1.f + __expf(-x)); }
; DEV void gdn_prep_chunk(const Params& p, int item, unsigned char* lds) {
;     ...
;                 y[e] = silu_f(a); ss += y[e] * y[e];
	v_mul_f32_e32 v112, 0xbfb8aa3b, v86
	v_mul_f32_e32 v113, 0xbfb8aa3b, v87
	v_exp_f32_e32 v112, v112
	v_exp_f32_e32 v113, v113


; DEV float bflo(unsigned u) { return __uint_as_float(u << 16); }
; DEV float bfhi(unsigned u) { return __uint_as_float(u & 0xffff0000u); }
; DEV float silu_f(float x) { return x / (1.f + __expf(-x)); }
; DEV void gdn_prep_chunk(const Params& p, int item, unsigned char* lds) {
;     ...
;                 for (int j = 0; j < 4; ++j) {
;                     const uint4 u = raw[r + j];
;                     const unsigned wd = (e < 2 ? u.x : (e < 4 ? u.y : (e < 6 ? u.z : u.w)));
;                     const float xv = (e & 1) ? bfhi(wd) : bflo(wd);
;                     a += w[j][e] * xv;
;     ...
;                 y[e] = silu_f(a); ss += y[e] * y[e];
	v_rcp_f32_e32 v109, v92
	s_nop 0
	v_mul_f32_e32 v92, v108, v109
	v_pk_add_f32 v[112:113], v[112:113], 1.0 op_sel_hi:[1,0]
	v_pk_fma_f32 v[106:107], v[2:3], v[106:107], 0 op_sel_hi:[1,1,0]


; DEV float bflo(unsigned u) { return __uint_as_float(u << 16); }
; DEV float bfhi(unsigned u) { return __uint_as_float(u & 0xffff0000u); }
; DEV void gdn_prep_chunk(const Params& p, int item, unsigned char* lds) {
;     ...
;                 for (int j = 0; j < 4; ++j) {
;                     const uint4 u = raw[r + j];
;                     const unsigned wd = (e < 2 ? u.x : (e < 4 ? u.y : (e < 6 ? u.z : u.w)));
;                     const float xv = (e & 1) ? bfhi(wd) : bflo(wd);
;                     a += w[j][e] * xv;
	v_pk_fma_f32 v[106:107], v[6:7], v[98:99], v[106:107]


; DEV float bflo(unsigned u) { return __uint_as_float(u << 16); }
; DEV float bfhi(unsigned u) { return __uint_as_float(u & 0xffff0000u); }
; DEV float silu_f(float x) { return x / (1.f + __expf(-x)); }
; DEV void gdn_prep_chunk(const Params& p, int item, unsigned char* lds) {
;     ...
;                 for (int j = 0; j < 4; ++j) {
;                     const uint4 u = raw[r + j];
;                     const unsigned wd = (e < 2 ? u.x : (e < 4 ? u.y : (e < 6 ? u.z : u.w)));
;                     const float xv = (e & 1) ? bfhi(wd) : bflo(wd);
;                     a += w[j][e] * xv;
;     ...
;                 y[e] = silu_f(a); ss += y[e] * y[e];
	v_lshlrev_b32_e32 v114, 16, v88
	v_and_b32_e32 v115, 0xffff0000, v88
	v_pk_fma_f32 v[106:107], v[10:11], v[100:101], v[106:107]
	v_rcp_f32_e32 v108, v113
	s_nop 0
	v_mul_f32_e32 v87, v87, v108
	v_pk_fma_f32 v[106:107], v[14:15], v[114:115], v[106:107]

; DEV float silu_f(float x) { return x / (1.f + __expf(-x)); }
; DEV void gdn_prep_chunk(const Params& p, int item, unsigned char* lds) {
;     ...
;                 y[e] = silu_f(a); ss += y[e] * y[e];
	v_mul_f32_e32 v88, 0xbfb8aa3b, v106

; DEV float silu_f(float x) { return x / (1.f + __expf(-x)); }
; DEV void gdn_prep_chunk(const Params& p, int item, unsigned char* lds) {
;     ...
;                 y[e] = silu_f(a); ss += y[e] * y[e];
	v_exp_f32_e32 v108, v88
	v_mul_f32_e32 v88, 0xbfb8aa3b, v107
	v_exp_f32_e32 v109, v88


; DEV float silu_f(float x) { return x / (1.f + __expf(-x)); }
; DEV void gdn_prep_chunk(const Params& p, int item, unsigned char* lds) {
;     ...
;                 y[e] = silu_f(a); ss += y[e] * y[e];
	s_nop 0
	v_pk_add_f32 v[108:109], v[108:109], 1.0 op_sel_hi:[1,0]


; DEV float silu_f(float x) { return x / (1.f + __expf(-x)); }
; DEV void gdn_prep_chunk(const Params& p, int item, unsigned char* lds) {
;     ...
;                 y[e] = silu_f(a); ss += y[e] * y[e];
	v_rcp_f32_e32 v88, v112
	s_nop 0
	v_mul_f32_e32 v86, v86, v88


; DEV float silu_f(float x) { return x / (1.f + __expf(-x)); }
; DEV void gdn_prep_chunk(const Params& p, int item, unsigned char* lds) {
;     ...
;                 y[e] = silu_f(a); ss += y[e] * y[e];
	v_rcp_f32_e32 v88, v109
	s_nop 0
	v_mul_f32_e32 v107, v107, v88


; DEV float bflo(unsigned u) { return __uint_as_float(u << 16); }
; DEV float bfhi(unsigned u) { return __uint_as_float(u & 0xffff0000u); }
; DEV void gdn_prep_chunk(const Params& p, int item, unsigned char* lds) {
;     ...
;                 for (int j = 0; j < 4; ++j) {
;                     const uint4 u = raw[r + j];
;                     const unsigned wd = (e < 2 ? u.x : (e < 4 ? u.y : (e < 6 ? u.z : u.w)));
;                     const float xv = (e & 1) ? bfhi(wd) : bflo(wd);
;                     a += w[j][e] * xv;
	v_lshlrev_b32_e32 v112, 16, v89
	v_and_b32_e32 v113, 0xffff0000, v89
	v_pk_fma_f32 v[88:89], v[4:5], v[120:121], 0 op_sel_hi:[1,1,0]

; DEV float bflo(unsigned u) { return __uint_as_float(u << 16); }
; DEV float bfhi(unsigned u) { return __uint_as_float(u & 0xffff0000u); }
; DEV void gdn_prep_chunk(const Params& p, int item, unsigned char* lds) {
;     ...
;                 for (int j = 0; j < 4; ++j) {
;                     const uint4 u = raw[r + j];
;                     const unsigned wd = (e < 2 ? u.x : (e < 4 ? u.y : (e < 6 ? u.z : u.w)));
;                     const float xv = (e & 1) ? bfhi(wd) : bflo(wd);
;                     a += w[j][e] * xv;
	v_pk_fma_f32 v[88:89], v[8:9], v[96:97], v[88:89]

; DEV float bflo(unsigned u) { return __uint_as_float(u << 16); }
; DEV float bfhi(unsigned u) { return __uint_as_float(u & 0xffff0000u); }
; DEV void gdn_prep_chunk(const Params& p, int item, unsigned char* lds) {
;     ...
;                 for (int j = 0; j < 4; ++j) {
;                     const uint4 u = raw[r + j];
;                     const unsigned wd = (e < 2 ? u.x : (e < 4 ? u.y : (e < 6 ? u.z : u.w)));
;                     const float xv = (e & 1) ? bfhi(wd) : bflo(wd);
;                     a += w[j][e] * xv;
	v_pk_fma_f32 v[88:89], v[12:13], v[90:91], v[88:89]

; DEV float bflo(unsigned u) { return __uint_as_float(u << 16); }
; DEV float bfhi(unsigned u) { return __uint_as_float(u & 0xffff0000u); }
; DEV void gdn_prep_chunk(const Params& p, int item, unsigned char* lds) {
;     ...
;                 for (int j = 0; j < 4; ++j) {
;                     const uint4 u = raw[r + j];
;                     const unsigned wd = (e < 2 ? u.x : (e < 4 ? u.y : (e < 6 ? u.z : u.w)));
;                     const float xv = (e & 1) ? bfhi(wd) : bflo(wd);
;                     a += w[j][e] * xv;
	v_pk_fma_f32 v[88:89], v[16:17], v[112:113], v[88:89]

; DEV float silu_f(float x) { return x / (1.f + __expf(-x)); }
; DEV void gdn_prep_chunk(const Params& p, int item, unsigned char* lds) {
;     ...
;                 y[e] = silu_f(a); ss += y[e] * y[e];
	v_mul_f32_e32 v120, 0xbfb8aa3b, v88
	v_mul_f32_e32 v121, 0xbfb8aa3b, v89
	v_exp_f32_e32 v120, v120
	v_exp_f32_e32 v121, v121


; DEV float silu_f(float x) { return x / (1.f + __expf(-x)); }
; DEV void gdn_prep_chunk(const Params& p, int item, unsigned char* lds) {
;     ...
;                 y[e] = silu_f(a); ss += y[e] * y[e];
	v_rcp_f32_e32 v109, v108
	s_nop 0
	v_mul_f32_e32 v106, v106, v109
	v_pk_add_f32 v[120:121], v[120:121], 1.0 op_sel_hi:[1,0]
	s_nop 0


; DEV float silu_f(float x) { return x / (1.f + __expf(-x)); }
; DEV void gdn_prep_chunk(const Params& p, int item, unsigned char* lds) {
;     ...
;                 y[e] = silu_f(a); ss += y[e] * y[e];
	s_nop 0


; DEV float silu_f(float x) { return x / (1.f + __expf(-x)); }
; DEV void gdn_prep_chunk(const Params& p, int item, unsigned char* lds) {
;     ...
;                 y[e] = silu_f(a); ss += y[e] * y[e];
	v_rcp_f32_e32 v108, v121
	s_nop 0
	v_mul_f32_e32 v89, v89, v108


; DEV unsigned cvt_pk_bf16(float lo, float hi) { const f32x2_t v = {lo, hi}; const bf16x2_t b = __builtin_convertvector(v, bf16x2_t); return __builtin_bit_cast(unsigned, b); }
; DEV float bflo(unsigned u) { return __uint_as_float(u << 16); }
; DEV float bfhi(unsigned u) { return __uint_as_float(u & 0xffff0000u); }
; DEV float silu_f(float x) { return x / (1.f + __expf(-x)); }
; DEV void gdn_prep_chunk(const Params& p, int item, unsigned char* lds) {
;     ...
;             for (int e = 0; e < 8; ++e) {
;                 float a = 0.f;
; #pragma unroll
;                 for (int j = 0; j < 4; ++j) {
;                     const uint4 u = raw[r + j];
;                     const unsigned wd = (e < 2 ? u.x : (e < 4 ? u.y : (e < 6 ? u.z : u.w)));
;                     const float xv = (e & 1) ? bfhi(wd) : bflo(wd);
;                     a += w[j][e] * xv;
;                 }
;                 y[e] = silu_f(a); ss += y[e] * y[e];
;     ...
;             if (mat < 2) {
;                 ss += __shfl_xor(ss, 1); ss += __shfl_xor(ss, 2); ss += __shfl_xor(ss, 4); ss += __shfl_xor(ss, 8);
;                 float inv = rsqrtf(ss + EPS); if (mat == 0) inv *= 0.08838834764831845f;
; #pragma unroll
;                 for (int e = 0; e < 8; ++e) y[e] *= inv;
;             }
;             uint4 o; o.x = cvt_pk_bf16(y[0], y[1]); o.y = cvt_pk_bf16(y[2], y[3]); o.z = cvt_pk_bf16(y[4], y[5]); o.w = cvt_pk_bf16(y[6], y[7]);
;             *(uint4*)(dst + (tl0 + r) * QS + cv * 8) = o;
	v_rcp_f32_e32 v108, v120
	s_nop 0
	v_mul_f32_e32 v88, v88, v108
	s_and_saveexec_b64 s[36:37], s[6:7]
	s_cbranch_execz .LBB0_478
	v_pk_mul_f32 v[108:109], v[92:93], v[92:93]
	v_pk_mul_f32 v[120:121], v[86:87], v[86:87]
	v_add_f32_e32 v108, v108, v109
	v_add_f32_e32 v108, v108, v120
	v_pk_mul_f32 v[124:125], v[106:107], v[106:107]
	v_add_f32_e32 v108, v121, v108
	v_and_b32_e32 v120, 64, v182
	v_add_f32_e32 v108, v124, v108
	v_xor_b32_e32 v109, 1, v182
	v_add_u32_e32 v120, 64, v120
	v_pk_mul_f32 v[126:127], v[88:89], v[88:89]
	v_add_f32_e32 v108, v125, v108
	v_cmp_lt_i32_e32 vcc, v109, v120
	v_add_f32_e32 v108, v126, v108
	v_add_f32_e32 v108, v127, v108
	v_cndmask_b32_e32 v109, v182, v109, vcc
	v_lshlrev_b32_e32 v109, 2, v109
	ds_bpermute_b32 v109, v109, v108
	s_waitcnt lgkmcnt(0)
	v_add_f32_e32 v108, v108, v109
	v_xor_b32_e32 v109, 2, v182
	v_cmp_lt_i32_e32 vcc, v109, v120
	s_nop 1
	v_cndmask_b32_e32 v109, v182, v109, vcc
	v_lshlrev_b32_e32 v109, 2, v109
	ds_bpermute_b32 v109, v109, v108
	s_waitcnt lgkmcnt(0)
	v_add_f32_e32 v108, v108, v109
	v_xor_b32_e32 v109, 4, v182
	v_cmp_lt_i32_e32 vcc, v109, v120
	s_nop 1
	v_cndmask_b32_e32 v109, v182, v109, vcc
	v_lshlrev_b32_e32 v109, 2, v109
	ds_bpermute_b32 v109, v109, v108
	s_waitcnt lgkmcnt(0)
	v_add_f32_e32 v108, v108, v109
	v_xor_b32_e32 v109, 8, v182
	v_cmp_lt_i32_e32 vcc, v109, v120
	s_nop 1
	v_cndmask_b32_e32 v109, v182, v109, vcc
	v_lshlrev_b32_e32 v109, 2, v109
	ds_bpermute_b32 v109, v109, v108
	s_waitcnt lgkmcnt(0)
	v_add_f32_e32 v108, v108, v109
	v_add_f32_e32 v108, 0x358637bd, v108
	v_mul_f32_e32 v109, 0x4b800000, v108
	v_cmp_gt_f32_e32 vcc, s56, v108
	s_nop 1
	v_cndmask_b32_e32 v108, v108, v109, vcc
	v_rsq_f32_e32 v108, v108
	s_nop 0
	v_mul_f32_e32 v109, 0x45800000, v108
	v_cndmask_b32_e32 v108, v108, v109, vcc
	v_mul_f32_e32 v109, 0x3db504f3, v108
	v_cndmask_b32_e64 v108, v108, v109, s[4:5]
	v_pk_mul_f32 v[92:93], v[92:93], v[108:109] op_sel_hi:[1,0]
	v_pk_mul_f32 v[86:87], v[86:87], v[108:109] op_sel_hi:[1,0]
	v_pk_mul_f32 v[106:107], v[106:107], v[108:109] op_sel_hi:[1,0]
	v_pk_mul_f32 v[88:89], v[88:89], v[108:109] op_sel_hi:[1,0]
.LBB0_478:
	s_or_b64 exec, exec, s[36:37]
	v_cvt_pk_bf16_f32 v124, v92, v93
	v_pk_fma_f32 v[92:93], v[18:19], v[110:111], 0 op_sel_hi:[1,1,0]
	s_waitcnt vmcnt(12)
	v_lshlrev_b32_e32 v108, 16, v82
	v_pk_fma_f32 v[92:93], v[22:23], v[104:105], v[92:93]
	v_and_b32_e32 v109, 0xffff0000, v82
	v_pk_fma_f32 v[92:93], v[26:27], v[118:119], v[92:93]
	v_cvt_pk_bf16_f32 v125, v86, v87
	v_pk_fma_f32 v[92:93], v[30:31], v[108:109], v[92:93]
	v_cvt_pk_bf16_f32 v127, v88, v89
	v_mul_f32_e32 v82, 0xbfb8aa3b, v92
	v_exp_f32_e32 v110, v82
	v_mul_f32_e32 v82, 0xbfb8aa3b, v93
	v_exp_f32_e32 v111, v82
	v_cvt_pk_bf16_f32 v126, v106, v107
	v_pk_add_f32 v[86:87], v[110:111], 1.0 op_sel_hi:[1,0]
	s_nop 0


; DEV float silu_f(float x) { return x / (1.f + __expf(-x)); }
; DEV void gdn_prep_chunk(const Params& p, int item, unsigned char* lds) {
;     ...
;                 y[e] = silu_f(a); ss += y[e] * y[e];
;     ...
;             *(uint4*)(dst + (tl0 + r) * QS + cv * 8) = o;
	v_add_u32_e32 v110, 0x110, v122
	v_add_u32_e32 v89, v132, v110
	ds_write_b128 v89, v[124:127]


; DEV float silu_f(float x) { return x / (1.f + __expf(-x)); }
; DEV void gdn_prep_chunk(const Params& p, int item, unsigned char* lds) {
;     ...
;                 y[e] = silu_f(a); ss += y[e] * y[e];
	v_rcp_f32_e32 v82, v87
	s_nop 0
	v_mul_f32_e32 v87, v93, v82


; DEV float bflo(unsigned u) { return __uint_as_float(u << 16); }
; DEV float bfhi(unsigned u) { return __uint_as_float(u & 0xffff0000u); }
; DEV void gdn_prep_chunk(const Params& p, int item, unsigned char* lds) {
;     ...
;                 for (int j = 0; j < 4; ++j) {
;                     const uint4 u = raw[r + j];
;                     const unsigned wd = (e < 2 ? u.x : (e < 4 ? u.y : (e < 6 ? u.z : u.w)));
;                     const float xv = (e & 1) ? bfhi(wd) : bflo(wd);
;                     a += w[j][e] * xv;
	v_lshlrev_b32_e32 v106, 16, v83
	v_and_b32_e32 v107, 0xffff0000, v83
	v_pk_fma_f32 v[82:83], v[20:21], v[94:95], 0 op_sel_hi:[1,1,0]

; DEV float bflo(unsigned u) { return __uint_as_float(u << 16); }
; DEV float bfhi(unsigned u) { return __uint_as_float(u & 0xffff0000u); }
; DEV void gdn_prep_chunk(const Params& p, int item, unsigned char* lds) {
;     ...
;                 for (int j = 0; j < 4; ++j) {
;                     const uint4 u = raw[r + j];
;                     const unsigned wd = (e < 2 ? u.x : (e < 4 ? u.y : (e < 6 ? u.z : u.w)));
;                     const float xv = (e & 1) ? bfhi(wd) : bflo(wd);
;                     a += w[j][e] * xv;
	v_pk_fma_f32 v[82:83], v[24:25], v[102:103], v[82:83]

; DEV float bflo(unsigned u) { return __uint_as_float(u << 16); }
; DEV float bfhi(unsigned u) { return __uint_as_float(u & 0xffff0000u); }
; DEV void gdn_prep_chunk(const Params& p, int item, unsigned char* lds) {
;     ...
;                 for (int j = 0; j < 4; ++j) {
;                     const uint4 u = raw[r + j];
;                     const unsigned wd = (e < 2 ? u.x : (e < 4 ? u.y : (e < 6 ? u.z : u.w)));
;                     const float xv = (e & 1) ? bfhi(wd) : bflo(wd);
;                     a += w[j][e] * xv;
	v_pk_fma_f32 v[82:83], v[28:29], v[116:117], v[82:83]

; DEV float bflo(unsigned u) { return __uint_as_float(u << 16); }
; DEV float bfhi(unsigned u) { return __uint_as_float(u & 0xffff0000u); }
; DEV void gdn_prep_chunk(const Params& p, int item, unsigned char* lds) {
;     ...
;                 for (int j = 0; j < 4; ++j) {
;                     const uint4 u = raw[r + j];
;                     const unsigned wd = (e < 2 ? u.x : (e < 4 ? u.y : (e < 6 ? u.z : u.w)));
;                     const float xv = (e & 1) ? bfhi(wd) : bflo(wd);
;                     a += w[j][e] * xv;
	v_pk_fma_f32 v[82:83], v[32:33], v[106:107], v[82:83]

; DEV float silu_f(float x) { return x / (1.f + __expf(-x)); }
; DEV void gdn_prep_chunk(const Params& p, int item, unsigned char* lds) {
;     ...
;                 y[e] = silu_f(a); ss += y[e] * y[e];
	v_mul_f32_e32 v88, 0xbfb8aa3b, v82
	v_mul_f32_e32 v89, 0xbfb8aa3b, v83
	v_exp_f32_e32 v88, v88
	v_exp_f32_e32 v89, v89


; DEV float silu_f(float x) { return x / (1.f + __expf(-x)); }
; DEV void gdn_prep_chunk(const Params& p, int item, unsigned char* lds) {
;     ...
;                 y[e] = silu_f(a); ss += y[e] * y[e];
	v_rcp_f32_e32 v93, v86
	s_nop 0
	v_mul_f32_e32 v86, v92, v93
	v_pk_add_f32 v[88:89], v[88:89], 1.0 op_sel_hi:[1,0]
	s_nop 0


; DEV float silu_f(float x) { return x / (1.f + __expf(-x)); }
; DEV void gdn_prep_chunk(const Params& p, int item, unsigned char* lds) {
;     ...
;                 y[e] = silu_f(a); ss += y[e] * y[e];
	s_nop 0


; DEV float bflo(unsigned u) { return __uint_as_float(u << 16); }
; DEV float bfhi(unsigned u) { return __uint_as_float(u & 0xffff0000u); }
; DEV float silu_f(float x) { return x / (1.f + __expf(-x)); }
; DEV void gdn_prep_chunk(const Params& p, int item, unsigned char* lds) {
;     ...
;             for (int e = 0; e < 8; ++e) {
;                 float a = 0.f;
; #pragma unroll
;                 for (int j = 0; j < 4; ++j) {
;                     const uint4 u = raw[r + j];
;                     const unsigned wd = (e < 2 ? u.x : (e < 4 ? u.y : (e < 6 ? u.z : u.w)));
;                     const float xv = (e & 1) ? bfhi(wd) : bflo(wd);
;                     a += w[j][e] * xv;
;                 }
;                 y[e] = silu_f(a); ss += y[e] * y[e];
	v_pk_fma_f32 v[94:95], v[2:3], v[98:99], 0 op_sel_hi:[1,1,0]

; DEV float bflo(unsigned u) { return __uint_as_float(u << 16); }
; DEV float bfhi(unsigned u) { return __uint_as_float(u & 0xffff0000u); }
; DEV float silu_f(float x) { return x / (1.f + __expf(-x)); }
; DEV void gdn_prep_chunk(const Params& p, int item, unsigned char* lds) {
;     ...
;                 for (int j = 0; j < 4; ++j) {
;                     const uint4 u = raw[r + j];
;                     const unsigned wd = (e < 2 ? u.x : (e < 4 ? u.y : (e < 6 ? u.z : u.w)));
;                     const float xv = (e & 1) ? bfhi(wd) : bflo(wd);
;                     a += w[j][e] * xv;
	v_pk_fma_f32 v[94:95], v[6:7], v[100:101], v[94:95]

; DEV float bflo(unsigned u) { return __uint_as_float(u << 16); }
; DEV float bfhi(unsigned u) { return __uint_as_float(u & 0xffff0000u); }
; DEV float silu_f(float x) { return x / (1.f + __expf(-x)); }
; DEV void gdn_prep_chunk(const Params& p, int item, unsigned char* lds) {
;     ...
;             for (int e = 0; e < 8; ++e) {
;                 float a = 0.f;
; #pragma unroll
;                 for (int j = 0; j < 4; ++j) {
;                     const uint4 u = raw[r + j];
;                     const unsigned wd = (e < 2 ? u.x : (e < 4 ? u.y : (e < 6 ? u.z : u.w)));
;                     const float xv = (e & 1) ? bfhi(wd) : bflo(wd);
;                     a += w[j][e] * xv;
;                 }
;                 y[e] = silu_f(a); ss += y[e] * y[e];
	v_rcp_f32_e32 v92, v89
	s_nop 0
	v_mul_f32_e32 v83, v83, v92
	v_lshlrev_b32_e32 v92, 16, v84
	v_and_b32_e32 v93, 0xffff0000, v84
	v_pk_fma_f32 v[94:95], v[10:11], v[114:115], v[94:95]

; DEV float bflo(unsigned u) { return __uint_as_float(u << 16); }
; DEV float bfhi(unsigned u) { return __uint_as_float(u & 0xffff0000u); }
; DEV void gdn_prep_chunk(const Params& p, int item, unsigned char* lds) {
;     ...
;                 for (int j = 0; j < 4; ++j) {
;                     const uint4 u = raw[r + j];
;                     const unsigned wd = (e < 2 ? u.x : (e < 4 ? u.y : (e < 6 ? u.z : u.w)));
;                     const float xv = (e & 1) ? bfhi(wd) : bflo(wd);
;                     a += w[j][e] * xv;
	v_pk_fma_f32 v[94:95], v[14:15], v[92:93], v[94:95]

; DEV float silu_f(float x) { return x / (1.f + __expf(-x)); }
; DEV void gdn_prep_chunk(const Params& p, int item, unsigned char* lds) {
;     ...
;                 y[e] = silu_f(a); ss += y[e] * y[e];
	v_mul_f32_e32 v84, 0xbfb8aa3b, v94
	v_exp_f32_e32 v98, v84
	v_mul_f32_e32 v84, 0xbfb8aa3b, v95
	v_exp_f32_e32 v99, v84


; DEV float silu_f(float x) { return x / (1.f + __expf(-x)); }
; DEV void gdn_prep_chunk(const Params& p, int item, unsigned char* lds) {
;     ...
;                 y[e] = silu_f(a); ss += y[e] * y[e];
	s_nop 0
	v_pk_add_f32 v[98:99], v[98:99], 1.0 op_sel_hi:[1,0]


; DEV float silu_f(float x) { return x / (1.f + __expf(-x)); }
; DEV void gdn_prep_chunk(const Params& p, int item, unsigned char* lds) {
;     ...
;                 y[e] = silu_f(a); ss += y[e] * y[e];
	v_rcp_f32_e32 v84, v88
	s_nop 0
	v_mul_f32_e32 v82, v82, v84


; DEV float silu_f(float x) { return x / (1.f + __expf(-x)); }
; DEV void gdn_prep_chunk(const Params& p, int item, unsigned char* lds) {
;     ...
;                 y[e] = silu_f(a); ss += y[e] * y[e];
	v_rcp_f32_e32 v84, v99
	s_nop 0
	v_mul_f32_e32 v95, v95, v84


; DEV float bflo(unsigned u) { return __uint_as_float(u << 16); }
; DEV float bfhi(unsigned u) { return __uint_as_float(u & 0xffff0000u); }
; DEV void gdn_prep_chunk(const Params& p, int item, unsigned char* lds) {
;     ...
;                 for (int j = 0; j < 4; ++j) {
;                     const uint4 u = raw[r + j];
;                     const unsigned wd = (e < 2 ? u.x : (e < 4 ? u.y : (e < 6 ? u.z : u.w)));
;                     const float xv = (e & 1) ? bfhi(wd) : bflo(wd);
;                     a += w[j][e] * xv;
	v_lshlrev_b32_e32 v88, 16, v85
	v_and_b32_e32 v89, 0xffff0000, v85
	v_pk_fma_f32 v[84:85], v[4:5], v[96:97], 0 op_sel_hi:[1,1,0]

; DEV float bflo(unsigned u) { return __uint_as_float(u << 16); }
; DEV float bfhi(unsigned u) { return __uint_as_float(u & 0xffff0000u); }
; DEV void gdn_prep_chunk(const Params& p, int item, unsigned char* lds) {
;     ...
;                 for (int j = 0; j < 4; ++j) {
;                     const uint4 u = raw[r + j];
;                     const unsigned wd = (e < 2 ? u.x : (e < 4 ? u.y : (e < 6 ? u.z : u.w)));
;                     const float xv = (e & 1) ? bfhi(wd) : bflo(wd);
;                     a += w[j][e] * xv;
	v_pk_fma_f32 v[84:85], v[8:9], v[90:91], v[84:85]

; DEV float bflo(unsigned u) { return __uint_as_float(u << 16); }
; DEV float bfhi(unsigned u) { return __uint_as_float(u & 0xffff0000u); }
; DEV void gdn_prep_chunk(const Params& p, int item, unsigned char* lds) {
;     ...
;                 for (int j = 0; j < 4; ++j) {
;                     const uint4 u = raw[r + j];
;                     const unsigned wd = (e < 2 ? u.x : (e < 4 ? u.y : (e < 6 ? u.z : u.w)));
;                     const float xv = (e & 1) ? bfhi(wd) : bflo(wd);
;                     a += w[j][e] * xv;
	v_pk_fma_f32 v[84:85], v[12:13], v[112:113], v[84:85]

; DEV float bflo(unsigned u) { return __uint_as_float(u << 16); }
; DEV float bfhi(unsigned u) { return __uint_as_float(u & 0xffff0000u); }
; DEV void gdn_prep_chunk(const Params& p, int item, unsigned char* lds) {
;     ...
;                 for (int j = 0; j < 4; ++j) {
;                     const uint4 u = raw[r + j];
;                     const unsigned wd = (e < 2 ? u.x : (e < 4 ? u.y : (e < 6 ? u.z : u.w)));
;                     const float xv = (e & 1) ? bfhi(wd) : bflo(wd);
;                     a += w[j][e] * xv;
	v_pk_fma_f32 v[84:85], v[16:17], v[88:89], v[84:85]

; DEV float silu_f(float x) { return x / (1.f + __expf(-x)); }
; DEV void gdn_prep_chunk(const Params& p, int item, unsigned char* lds) {
;     ...
;                 y[e] = silu_f(a); ss += y[e] * y[e];
	v_mul_f32_e32 v96, 0xbfb8aa3b, v84
	v_mul_f32_e32 v97, 0xbfb8aa3b, v85
	v_exp_f32_e32 v96, v96
	v_exp_f32_e32 v97, v97


; DEV float silu_f(float x) { return x / (1.f + __expf(-x)); }
; DEV void gdn_prep_chunk(const Params& p, int item, unsigned char* lds) {
;     ...
;                 y[e] = silu_f(a); ss += y[e] * y[e];
	v_rcp_f32_e32 v99, v98
	s_nop 0
	v_mul_f32_e32 v94, v94, v99
	v_pk_add_f32 v[96:97], v[96:97], 1.0 op_sel_hi:[1,0]
	s_nop 0


; DEV float silu_f(float x) { return x / (1.f + __expf(-x)); }
; DEV void gdn_prep_chunk(const Params& p, int item, unsigned char* lds) {
;     ...
;                 y[e] = silu_f(a); ss += y[e] * y[e];
	s_nop 0


; DEV float silu_f(float x) { return x / (1.f + __expf(-x)); }
; DEV void gdn_prep_chunk(const Params& p, int item, unsigned char* lds) {
;     ...
;                 y[e] = silu_f(a); ss += y[e] * y[e];
	v_rcp_f32_e32 v98, v97
	s_nop 0
	v_mul_f32_e32 v85, v85, v98


; DEV unsigned cvt_pk_bf16(float lo, float hi) { const f32x2_t v = {lo, hi}; const bf16x2_t b = __builtin_convertvector(v, bf16x2_t); return __builtin_bit_cast(unsigned, b); }
; DEV float silu_f(float x) { return x / (1.f + __expf(-x)); }
; DEV void gdn_prep_chunk(const Params& p, int item, unsigned char* lds) {
;     ...
;                 y[e] = silu_f(a); ss += y[e] * y[e];
;             }
;             if (mat < 2) {
;                 ss += __shfl_xor(ss, 1); ss += __shfl_xor(ss, 2); ss += __shfl_xor(ss, 4); ss += __shfl_xor(ss, 8);
;                 float inv = rsqrtf(ss + EPS); if (mat == 0) inv *= 0.08838834764831845f;
; #pragma unroll
;                 for (int e = 0; e < 8; ++e) y[e] *= inv;
;             }
;             uint4 o; o.x = cvt_pk_bf16(y[0], y[1]); o.y = cvt_pk_bf16(y[2], y[3]); o.z = cvt_pk_bf16(y[4], y[5]); o.w = cvt_pk_bf16(y[6], y[7]);
;             *(uint4*)(dst + (tl0 + r) * QS + cv * 8) = o;
	v_rcp_f32_e32 v97, v96
	s_nop 0
	v_mul_f32_e32 v84, v84, v97
	s_and_saveexec_b64 s[36:37], s[6:7]
	s_cbranch_execz .LBB0_480
	v_pk_mul_f32 v[96:97], v[86:87], v[86:87]
	v_pk_mul_f32 v[98:99], v[82:83], v[82:83]
	v_add_f32_e32 v96, v96, v97
	v_add_f32_e32 v96, v96, v98
	v_pk_mul_f32 v[120:121], v[94:95], v[94:95]
	v_add_f32_e32 v96, v99, v96
	v_and_b32_e32 v98, 64, v182
	v_add_f32_e32 v96, v120, v96
	v_xor_b32_e32 v97, 1, v182
	v_add_u32_e32 v98, 64, v98
	v_pk_mul_f32 v[122:123], v[84:85], v[84:85]
	v_add_f32_e32 v96, v121, v96
	v_cmp_lt_i32_e32 vcc, v97, v98
	v_add_f32_e32 v96, v122, v96
	v_add_f32_e32 v96, v123, v96
	v_cndmask_b32_e32 v97, v182, v97, vcc
	v_lshlrev_b32_e32 v97, 2, v97
	ds_bpermute_b32 v97, v97, v96
	s_waitcnt lgkmcnt(0)
	v_add_f32_e32 v96, v96, v97
	v_xor_b32_e32 v97, 2, v182
	v_cmp_lt_i32_e32 vcc, v97, v98
	s_nop 1
	v_cndmask_b32_e32 v97, v182, v97, vcc
	v_lshlrev_b32_e32 v97, 2, v97
	ds_bpermute_b32 v97, v97, v96
	s_waitcnt lgkmcnt(0)
	v_add_f32_e32 v96, v96, v97
	v_xor_b32_e32 v97, 4, v182
	v_cmp_lt_i32_e32 vcc, v97, v98
	s_nop 1
	v_cndmask_b32_e32 v97, v182, v97, vcc
	v_lshlrev_b32_e32 v97, 2, v97
	ds_bpermute_b32 v97, v97, v96
	s_waitcnt lgkmcnt(0)
	v_add_f32_e32 v96, v96, v97
	v_xor_b32_e32 v97, 8, v182
	v_cmp_lt_i32_e32 vcc, v97, v98
	s_nop 1
	v_cndmask_b32_e32 v97, v182, v97, vcc
	v_lshlrev_b32_e32 v97, 2, v97
	ds_bpermute_b32 v97, v97, v96
	s_waitcnt lgkmcnt(0)
	v_add_f32_e32 v96, v96, v97
	v_add_f32_e32 v96, 0x358637bd, v96
	v_mul_f32_e32 v97, 0x4b800000, v96
	v_cmp_gt_f32_e32 vcc, s56, v96
	s_nop 1
	v_cndmask_b32_e32 v96, v96, v97, vcc
	v_rsq_f32_e32 v96, v96
	s_nop 0
	v_mul_f32_e32 v97, 0x45800000, v96
	v_cndmask_b32_e32 v96, v96, v97, vcc
	v_mul_f32_e32 v97, 0x3db504f3, v96
	v_cndmask_b32_e64 v96, v96, v97, s[4:5]
	v_pk_mul_f32 v[86:87], v[86:87], v[96:97] op_sel_hi:[1,0]
	v_pk_mul_f32 v[82:83], v[82:83], v[96:97] op_sel_hi:[1,0]
	v_pk_mul_f32 v[94:95], v[94:95], v[96:97] op_sel_hi:[1,0]
	v_pk_mul_f32 v[84:85], v[84:85], v[96:97] op_sel_hi:[1,0]
.LBB0_480:
	s_or_b64 exec, exec, s[36:37]
	v_pk_fma_f32 v[98:99], v[18:19], v[104:105], 0 op_sel_hi:[1,1,0]
	v_cvt_pk_bf16_f32 v96, v86, v87
	v_pk_fma_f32 v[98:99], v[22:23], v[118:119], v[98:99]
	s_waitcnt vmcnt(11)
	v_lshlrev_b32_e32 v86, 16, v78
	v_and_b32_e32 v87, 0xffff0000, v78
	v_pk_fma_f32 v[98:99], v[26:27], v[108:109], v[98:99]
	v_cvt_pk_bf16_f32 v97, v82, v83
	v_pk_fma_f32 v[120:121], v[30:31], v[86:87], v[98:99]
	v_cvt_pk_bf16_f32 v99, v84, v85
	v_mul_f32_e32 v78, 0xbfb8aa3b, v120
	v_exp_f32_e32 v104, v78
	v_mul_f32_e32 v78, 0xbfb8aa3b, v121
	v_exp_f32_e32 v105, v78
	v_cvt_pk_bf16_f32 v98, v94, v95
	v_pk_add_f32 v[82:83], v[104:105], 1.0 op_sel_hi:[1,0]
	s_nop 0


; DEV float silu_f(float x) { return x / (1.f + __expf(-x)); }
; DEV void gdn_prep_chunk(const Params& p, int item, unsigned char* lds) {
;     ...
;                 y[e] = silu_f(a); ss += y[e] * y[e];
;     ...
;             *(uint4*)(dst + (tl0 + r) * QS + cv * 8) = o;
	v_add_u32_e32 v104, 0x110, v110
	v_add_u32_e32 v85, v132, v104
	ds_write_b128 v85, v[96:99]


; DEV float silu_f(float x) { return x / (1.f + __expf(-x)); }
; DEV void gdn_prep_chunk(const Params& p, int item, unsigned char* lds) {
;     ...
;                 y[e] = silu_f(a); ss += y[e] * y[e];
	v_rcp_f32_e32 v78, v83
	s_nop 0
	v_mul_f32_e32 v95, v121, v78


; DEV float bflo(unsigned u) { return __uint_as_float(u << 16); }
; DEV float bfhi(unsigned u) { return __uint_as_float(u & 0xffff0000u); }
; DEV void gdn_prep_chunk(const Params& p, int item, unsigned char* lds) {
;     ...
;                 for (int j = 0; j < 4; ++j) {
;                     const uint4 u = raw[r + j];
;                     const unsigned wd = (e < 2 ? u.x : (e < 4 ? u.y : (e < 6 ? u.z : u.w)));
;                     const float xv = (e & 1) ? bfhi(wd) : bflo(wd);
;                     a += w[j][e] * xv;
	v_lshlrev_b32_e32 v84, 16, v79
	v_and_b32_e32 v85, 0xffff0000, v79
	v_pk_fma_f32 v[78:79], v[20:21], v[102:103], 0 op_sel_hi:[1,1,0]

; DEV float bflo(unsigned u) { return __uint_as_float(u << 16); }
; DEV float bfhi(unsigned u) { return __uint_as_float(u & 0xffff0000u); }
; DEV void gdn_prep_chunk(const Params& p, int item, unsigned char* lds) {
;     ...
;                 for (int j = 0; j < 4; ++j) {
;                     const uint4 u = raw[r + j];
;                     const unsigned wd = (e < 2 ? u.x : (e < 4 ? u.y : (e < 6 ? u.z : u.w)));
;                     const float xv = (e & 1) ? bfhi(wd) : bflo(wd);
;                     a += w[j][e] * xv;
	v_pk_fma_f32 v[78:79], v[24:25], v[116:117], v[78:79]

; DEV float bflo(unsigned u) { return __uint_as_float(u << 16); }
; DEV float bfhi(unsigned u) { return __uint_as_float(u & 0xffff0000u); }
; DEV void gdn_prep_chunk(const Params& p, int item, unsigned char* lds) {
;     ...
;                 for (int j = 0; j < 4; ++j) {
;                     const uint4 u = raw[r + j];
;                     const unsigned wd = (e < 2 ? u.x : (e < 4 ? u.y : (e < 6 ? u.z : u.w)));
;                     const float xv = (e & 1) ? bfhi(wd) : bflo(wd);
;                     a += w[j][e] * xv;
	v_pk_fma_f32 v[78:79], v[28:29], v[106:107], v[78:79]

; DEV float bflo(unsigned u) { return __uint_as_float(u << 16); }
; DEV float bfhi(unsigned u) { return __uint_as_float(u & 0xffff0000u); }
; DEV void gdn_prep_chunk(const Params& p, int item, unsigned char* lds) {
;     ...
;                 for (int j = 0; j < 4; ++j) {
;                     const uint4 u = raw[r + j];
;                     const unsigned wd = (e < 2 ? u.x : (e < 4 ? u.y : (e < 6 ? u.z : u.w)));
;                     const float xv = (e & 1) ? bfhi(wd) : bflo(wd);
;                     a += w[j][e] * xv;
	v_pk_fma_f32 v[78:79], v[32:33], v[84:85], v[78:79]

; DEV float silu_f(float x) { return x / (1.f + __expf(-x)); }
; DEV void gdn_prep_chunk(const Params& p, int item, unsigned char* lds) {
;     ...
;                 y[e] = silu_f(a); ss += y[e] * y[e];
	v_mul_f32_e32 v96, 0xbfb8aa3b, v78
	v_mul_f32_e32 v97, 0xbfb8aa3b, v79
	v_exp_f32_e32 v96, v96
	v_exp_f32_e32 v97, v97


; DEV float silu_f(float x) { return x / (1.f + __expf(-x)); }
; DEV void gdn_prep_chunk(const Params& p, int item, unsigned char* lds) {
;     ...
;                 y[e] = silu_f(a); ss += y[e] * y[e];
	v_rcp_f32_e32 v83, v82
	s_nop 0
	v_mul_f32_e32 v94, v120, v83
	v_pk_add_f32 v[96:97], v[96:97], 1.0 op_sel_hi:[1,0]
	s_nop 0


; DEV float bflo(unsigned u) { return __uint_as_float(u << 16); }
; DEV float bfhi(unsigned u) { return __uint_as_float(u & 0xffff0000u); }
; DEV void gdn_prep_chunk(const Params& p, int item, unsigned char* lds) {
;     ...
;                 for (int j = 0; j < 4; ++j) {
;                     const uint4 u = raw[r + j];
;                     const unsigned wd = (e < 2 ? u.x : (e < 4 ? u.y : (e < 6 ? u.z : u.w)));
;                     const float xv = (e & 1) ? bfhi(wd) : bflo(wd);
;                     a += w[j][e] * xv;
	v_pk_fma_f32 v[98:99], v[2:3], v[100:101], 0 op_sel_hi:[1,1,0]

; DEV float bflo(unsigned u) { return __uint_as_float(u << 16); }
; DEV float bfhi(unsigned u) { return __uint_as_float(u & 0xffff0000u); }
; DEV float silu_f(float x) { return x / (1.f + __expf(-x)); }
; DEV void gdn_prep_chunk(const Params& p, int item, unsigned char* lds) {
;     ...
;                 for (int j = 0; j < 4; ++j) {
;                     const uint4 u = raw[r + j];
;                     const unsigned wd = (e < 2 ? u.x : (e < 4 ? u.y : (e < 6 ? u.z : u.w)));
;                     const float xv = (e & 1) ? bfhi(wd) : bflo(wd);
;                     a += w[j][e] * xv;
;                 }
;                 y[e] = silu_f(a); ss += y[e] * y[e];
	v_pk_fma_f32 v[98:99], v[6:7], v[114:115], v[98:99]
	v_rcp_f32_e32 v82, v97
	s_nop 0
	v_mul_f32_e32 v97, v79, v82
	v_lshlrev_b32_e32 v82, 16, v80
	v_and_b32_e32 v83, 0xffff0000, v80
	v_pk_fma_f32 v[98:99], v[10:11], v[92:93], v[98:99]

; DEV float bflo(unsigned u) { return __uint_as_float(u << 16); }
; DEV float bfhi(unsigned u) { return __uint_as_float(u & 0xffff0000u); }
; DEV void gdn_prep_chunk(const Params& p, int item, unsigned char* lds) {
;     ...
;                 for (int j = 0; j < 4; ++j) {
;                     const uint4 u = raw[r + j];
;                     const unsigned wd = (e < 2 ? u.x : (e < 4 ? u.y : (e < 6 ? u.z : u.w)));
;                     const float xv = (e & 1) ? bfhi(wd) : bflo(wd);
;                     a += w[j][e] * xv;
	v_pk_fma_f32 v[98:99], v[14:15], v[82:83], v[98:99]

; DEV float silu_f(float x) { return x / (1.f + __expf(-x)); }
; DEV void gdn_prep_chunk(const Params& p, int item, unsigned char* lds) {
;     ...
;                 y[e] = silu_f(a); ss += y[e] * y[e];
	v_mul_f32_e32 v80, 0xbfb8aa3b, v98
	v_exp_f32_e32 v100, v80
	v_mul_f32_e32 v80, 0xbfb8aa3b, v99
	v_exp_f32_e32 v101, v80


; DEV float silu_f(float x) { return x / (1.f + __expf(-x)); }
; DEV void gdn_prep_chunk(const Params& p, int item, unsigned char* lds) {
;     ...
;                 y[e] = silu_f(a); ss += y[e] * y[e];
	s_nop 0
	v_pk_add_f32 v[100:101], v[100:101], 1.0 op_sel_hi:[1,0]


; DEV float silu_f(float x) { return x / (1.f + __expf(-x)); }
; DEV void gdn_prep_chunk(const Params& p, int item, unsigned char* lds) {
;     ...
;                 y[e] = silu_f(a); ss += y[e] * y[e];
	v_rcp_f32_e32 v79, v96
	s_nop 0
	v_mul_f32_e32 v96, v78, v79


; DEV float silu_f(float x) { return x / (1.f + __expf(-x)); }
; DEV void gdn_prep_chunk(const Params& p, int item, unsigned char* lds) {
;     ...
;                 y[e] = silu_f(a); ss += y[e] * y[e];
	v_rcp_f32_e32 v78, v101
	s_nop 0
	v_mul_f32_e32 v99, v99, v78


; DEV float bflo(unsigned u) { return __uint_as_float(u << 16); }
; DEV float bfhi(unsigned u) { return __uint_as_float(u & 0xffff0000u); }
; DEV void gdn_prep_chunk(const Params& p, int item, unsigned char* lds) {
;     ...
;                 for (int j = 0; j < 4; ++j) {
;                     const uint4 u = raw[r + j];
;                     const unsigned wd = (e < 2 ? u.x : (e < 4 ? u.y : (e < 6 ? u.z : u.w)));
;                     const float xv = (e & 1) ? bfhi(wd) : bflo(wd);
;                     a += w[j][e] * xv;
	v_lshlrev_b32_e32 v78, 16, v81
	v_and_b32_e32 v79, 0xffff0000, v81
	v_pk_fma_f32 v[80:81], v[4:5], v[90:91], 0 op_sel_hi:[1,1,0]

; DEV float bflo(unsigned u) { return __uint_as_float(u << 16); }
; DEV float bfhi(unsigned u) { return __uint_as_float(u & 0xffff0000u); }
; DEV void gdn_prep_chunk(const Params& p, int item, unsigned char* lds) {
;     ...
;                 for (int j = 0; j < 4; ++j) {
;                     const uint4 u = raw[r + j];
;                     const unsigned wd = (e < 2 ? u.x : (e < 4 ? u.y : (e < 6 ? u.z : u.w)));
;                     const float xv = (e & 1) ? bfhi(wd) : bflo(wd);
;                     a += w[j][e] * xv;
	v_pk_fma_f32 v[80:81], v[8:9], v[112:113], v[80:81]

; DEV float bflo(unsigned u) { return __uint_as_float(u << 16); }
; DEV float bfhi(unsigned u) { return __uint_as_float(u & 0xffff0000u); }
; DEV void gdn_prep_chunk(const Params& p, int item, unsigned char* lds) {
;     ...
;                 for (int j = 0; j < 4; ++j) {
;                     const uint4 u = raw[r + j];
;                     const unsigned wd = (e < 2 ? u.x : (e < 4 ? u.y : (e < 6 ? u.z : u.w)));
;                     const float xv = (e & 1) ? bfhi(wd) : bflo(wd);
;                     a += w[j][e] * xv;
	v_pk_fma_f32 v[80:81], v[12:13], v[88:89], v[80:81]

; DEV float bflo(unsigned u) { return __uint_as_float(u << 16); }
; DEV float bfhi(unsigned u) { return __uint_as_float(u & 0xffff0000u); }
; DEV void gdn_prep_chunk(const Params& p, int item, unsigned char* lds) {
;     ...
;                 for (int j = 0; j < 4; ++j) {
;                     const uint4 u = raw[r + j];
;                     const unsigned wd = (e < 2 ? u.x : (e < 4 ? u.y : (e < 6 ? u.z : u.w)));
;                     const float xv = (e & 1) ? bfhi(wd) : bflo(wd);
;                     a += w[j][e] * xv;
	v_pk_fma_f32 v[80:81], v[16:17], v[78:79], v[80:81]

; DEV float silu_f(float x) { return x / (1.f + __expf(-x)); }
; DEV void gdn_prep_chunk(const Params& p, int item, unsigned char* lds) {
;     ...
;                 y[e] = silu_f(a); ss += y[e] * y[e];
	v_mul_f32_e32 v90, 0xbfb8aa3b, v80
	v_mul_f32_e32 v91, 0xbfb8aa3b, v81
	v_exp_f32_e32 v90, v90
	v_exp_f32_e32 v91, v91


; DEV float silu_f(float x) { return x / (1.f + __expf(-x)); }
; DEV void gdn_prep_chunk(const Params& p, int item, unsigned char* lds) {
;     ...
;                 y[e] = silu_f(a); ss += y[e] * y[e];
	v_rcp_f32_e32 v101, v100
	s_nop 0
	v_mul_f32_e32 v98, v98, v101
	v_pk_add_f32 v[90:91], v[90:91], 1.0 op_sel_hi:[1,0]
	s_nop 0


; DEV float silu_f(float x) { return x / (1.f + __expf(-x)); }
; DEV void gdn_prep_chunk(const Params& p, int item, unsigned char* lds) {
;     ...
;                 y[e] = silu_f(a); ss += y[e] * y[e];
	s_nop 0


; DEV float silu_f(float x) { return x / (1.f + __expf(-x)); }
; DEV void gdn_prep_chunk(const Params& p, int item, unsigned char* lds) {
;     ...
;                 y[e] = silu_f(a); ss += y[e] * y[e];
	v_rcp_f32_e32 v100, v91
	s_nop 0
	v_mul_f32_e32 v91, v81, v100


; DEV unsigned cvt_pk_bf16(float lo, float hi) { const f32x2_t v = {lo, hi}; const bf16x2_t b = __builtin_convertvector(v, bf16x2_t); return __builtin_bit_cast(unsigned, b); }
; DEV float silu_f(float x) { return x / (1.f + __expf(-x)); }
; DEV void gdn_prep_chunk(const Params& p, int item, unsigned char* lds) {
;     ...
;                 y[e] = silu_f(a); ss += y[e] * y[e];
;             }
;             if (mat < 2) {
;                 ss += __shfl_xor(ss, 1); ss += __shfl_xor(ss, 2); ss += __shfl_xor(ss, 4); ss += __shfl_xor(ss, 8);
;                 float inv = rsqrtf(ss + EPS); if (mat == 0) inv *= 0.08838834764831845f;
; #pragma unroll
;                 for (int e = 0; e < 8; ++e) y[e] *= inv;
;             }
;             uint4 o; o.x = cvt_pk_bf16(y[0], y[1]); o.y = cvt_pk_bf16(y[2], y[3]); o.z = cvt_pk_bf16(y[4], y[5]); o.w = cvt_pk_bf16(y[6], y[7]);
;             *(uint4*)(dst + (tl0 + r) * QS + cv * 8) = o;
	v_rcp_f32_e32 v81, v90
	s_nop 0
	v_mul_f32_e32 v90, v80, v81
	s_and_saveexec_b64 s[36:37], s[6:7]
	s_cbranch_execz .LBB0_482
	v_pk_mul_f32 v[80:81], v[94:95], v[94:95]
	v_pk_mul_f32 v[100:101], v[96:97], v[96:97]
	v_add_f32_e32 v80, v80, v81
	v_add_f32_e32 v80, v80, v100
	v_pk_mul_f32 v[102:103], v[98:99], v[98:99]
	v_add_f32_e32 v80, v101, v80
	v_and_b32_e32 v100, 64, v182
	v_add_f32_e32 v80, v102, v80
	v_xor_b32_e32 v81, 1, v182
	v_add_u32_e32 v100, 64, v100
	v_pk_mul_f32 v[110:111], v[90:91], v[90:91]
	v_add_f32_e32 v80, v103, v80
	v_cmp_lt_i32_e32 vcc, v81, v100
	v_add_f32_e32 v80, v110, v80
	v_add_f32_e32 v80, v111, v80
	v_cndmask_b32_e32 v81, v182, v81, vcc
	v_lshlrev_b32_e32 v81, 2, v81
	ds_bpermute_b32 v81, v81, v80
	s_waitcnt lgkmcnt(0)
	v_add_f32_e32 v80, v80, v81
	v_xor_b32_e32 v81, 2, v182
	v_cmp_lt_i32_e32 vcc, v81, v100
	s_nop 1
	v_cndmask_b32_e32 v81, v182, v81, vcc
	v_lshlrev_b32_e32 v81, 2, v81
	ds_bpermute_b32 v81, v81, v80
	s_waitcnt lgkmcnt(0)
	v_add_f32_e32 v80, v80, v81
	v_xor_b32_e32 v81, 4, v182
	v_cmp_lt_i32_e32 vcc, v81, v100
	s_nop 1
	v_cndmask_b32_e32 v81, v182, v81, vcc
	v_lshlrev_b32_e32 v81, 2, v81
	ds_bpermute_b32 v81, v81, v80
	s_waitcnt lgkmcnt(0)
	v_add_f32_e32 v80, v80, v81
	v_xor_b32_e32 v81, 8, v182
	v_cmp_lt_i32_e32 vcc, v81, v100
	s_nop 1
	v_cndmask_b32_e32 v81, v182, v81, vcc
	v_lshlrev_b32_e32 v81, 2, v81
	ds_bpermute_b32 v81, v81, v80
	s_waitcnt lgkmcnt(0)
	v_add_f32_e32 v80, v80, v81
	v_add_f32_e32 v80, 0x358637bd, v80
	v_mul_f32_e32 v81, 0x4b800000, v80
	v_cmp_gt_f32_e32 vcc, s56, v80
	s_nop 1
	v_cndmask_b32_e32 v80, v80, v81, vcc
	v_rsq_f32_e32 v80, v80
	s_nop 0
	v_mul_f32_e32 v81, 0x45800000, v80
	v_cndmask_b32_e32 v80, v80, v81, vcc
	v_mul_f32_e32 v81, 0x3db504f3, v80
	v_cndmask_b32_e64 v80, v80, v81, s[4:5]
	v_pk_mul_f32 v[94:95], v[94:95], v[80:81] op_sel_hi:[1,0]
	v_pk_mul_f32 v[96:97], v[96:97], v[80:81] op_sel_hi:[1,0]
	v_pk_mul_f32 v[98:99], v[98:99], v[80:81] op_sel_hi:[1,0]
	v_pk_mul_f32 v[90:91], v[90:91], v[80:81] op_sel_hi:[1,0]
.LBB0_482:
	s_or_b64 exec, exec, s[36:37]
	v_pk_fma_f32 v[100:101], v[18:19], v[118:119], 0 op_sel_hi:[1,1,0]
	s_waitcnt vmcnt(10)
	v_lshlrev_b32_e32 v80, 16, v74
	v_pk_fma_f32 v[100:101], v[22:23], v[108:109], v[100:101]
	v_and_b32_e32 v81, 0xffff0000, v74
	v_pk_fma_f32 v[100:101], v[26:27], v[86:87], v[100:101]
	v_cvt_pk_bf16_f32 v94, v94, v95
	v_pk_fma_f32 v[100:101], v[30:31], v[80:81], v[100:101]
	v_cvt_pk_bf16_f32 v95, v96, v97
	v_mul_f32_e32 v74, 0xbfb8aa3b, v100
	v_exp_f32_e32 v102, v74
	v_mul_f32_e32 v74, 0xbfb8aa3b, v101
	v_exp_f32_e32 v103, v74
	v_cvt_pk_bf16_f32 v97, v90, v91
	v_cvt_pk_bf16_f32 v96, v98, v99
	v_add_u32_e32 v104, 0x110, v104
	v_pk_add_f32 v[90:91], v[102:103], 1.0 op_sel_hi:[1,0]
	v_add_u32_e32 v99, v132, v104


; DEV float silu_f(float x) { return x / (1.f + __expf(-x)); }
; DEV void gdn_prep_chunk(const Params& p, int item, unsigned char* lds) {
;     ...
;                 y[e] = silu_f(a); ss += y[e] * y[e];
;     ...
;             *(uint4*)(dst + (tl0 + r) * QS + cv * 8) = o;
	ds_write_b128 v99, v[94:97]


; DEV float silu_f(float x) { return x / (1.f + __expf(-x)); }
; DEV void gdn_prep_chunk(const Params& p, int item, unsigned char* lds) {
;     ...
;                 y[e] = silu_f(a); ss += y[e] * y[e];
	v_rcp_f32_e32 v74, v91
	s_nop 0
	v_mul_f32_e32 v97, v101, v74


; DEV float bflo(unsigned u) { return __uint_as_float(u << 16); }
; DEV float bfhi(unsigned u) { return __uint_as_float(u & 0xffff0000u); }
; DEV void gdn_prep_chunk(const Params& p, int item, unsigned char* lds) {
;     ...
;                 for (int j = 0; j < 4; ++j) {
;                     const uint4 u = raw[r + j];
;                     const unsigned wd = (e < 2 ? u.x : (e < 4 ? u.y : (e < 6 ? u.z : u.w)));
;                     const float xv = (e & 1) ? bfhi(wd) : bflo(wd);
;                     a += w[j][e] * xv;
	v_lshlrev_b32_e32 v94, 16, v75
	v_and_b32_e32 v95, 0xffff0000, v75
	v_pk_fma_f32 v[74:75], v[20:21], v[116:117], 0 op_sel_hi:[1,1,0]

; DEV float bflo(unsigned u) { return __uint_as_float(u << 16); }
; DEV float bfhi(unsigned u) { return __uint_as_float(u & 0xffff0000u); }
; DEV void gdn_prep_chunk(const Params& p, int item, unsigned char* lds) {
;     ...
;                 for (int j = 0; j < 4; ++j) {
;                     const uint4 u = raw[r + j];
;                     const unsigned wd = (e < 2 ? u.x : (e < 4 ? u.y : (e < 6 ? u.z : u.w)));
;                     const float xv = (e & 1) ? bfhi(wd) : bflo(wd);
;                     a += w[j][e] * xv;
	v_pk_fma_f32 v[74:75], v[24:25], v[106:107], v[74:75]

; DEV float bflo(unsigned u) { return __uint_as_float(u << 16); }
; DEV float bfhi(unsigned u) { return __uint_as_float(u & 0xffff0000u); }
; DEV void gdn_prep_chunk(const Params& p, int item, unsigned char* lds) {
;     ...
;                 for (int j = 0; j < 4; ++j) {
;                     const uint4 u = raw[r + j];
;                     const unsigned wd = (e < 2 ? u.x : (e < 4 ? u.y : (e < 6 ? u.z : u.w)));
;                     const float xv = (e & 1) ? bfhi(wd) : bflo(wd);
;                     a += w[j][e] * xv;
	v_pk_fma_f32 v[74:75], v[28:29], v[84:85], v[74:75]

; DEV float bflo(unsigned u) { return __uint_as_float(u << 16); }
; DEV float bfhi(unsigned u) { return __uint_as_float(u & 0xffff0000u); }
; DEV void gdn_prep_chunk(const Params& p, int item, unsigned char* lds) {
;     ...
;                 for (int j = 0; j < 4; ++j) {
;                     const uint4 u = raw[r + j];
;                     const unsigned wd = (e < 2 ? u.x : (e < 4 ? u.y : (e < 6 ? u.z : u.w)));
;                     const float xv = (e & 1) ? bfhi(wd) : bflo(wd);
;                     a += w[j][e] * xv;
	v_pk_fma_f32 v[74:75], v[32:33], v[94:95], v[74:75]

; DEV float silu_f(float x) { return x / (1.f + __expf(-x)); }
; DEV void gdn_prep_chunk(const Params& p, int item, unsigned char* lds) {
;     ...
;                 y[e] = silu_f(a); ss += y[e] * y[e];
	v_mul_f32_e32 v98, 0xbfb8aa3b, v74
	v_mul_f32_e32 v99, 0xbfb8aa3b, v75
	v_exp_f32_e32 v98, v98
	v_exp_f32_e32 v99, v99


; DEV float silu_f(float x) { return x / (1.f + __expf(-x)); }
; DEV void gdn_prep_chunk(const Params& p, int item, unsigned char* lds) {
;     ...
;                 y[e] = silu_f(a); ss += y[e] * y[e];
	v_rcp_f32_e32 v91, v90
	s_nop 0
	v_mul_f32_e32 v96, v100, v91
	v_pk_add_f32 v[98:99], v[98:99], 1.0 op_sel_hi:[1,0]
	s_nop 0


; DEV float bflo(unsigned u) { return __uint_as_float(u << 16); }
; DEV float bfhi(unsigned u) { return __uint_as_float(u & 0xffff0000u); }
; DEV void gdn_prep_chunk(const Params& p, int item, unsigned char* lds) {
;     ...
;                 for (int j = 0; j < 4; ++j) {
;                     const uint4 u = raw[r + j];
;                     const unsigned wd = (e < 2 ? u.x : (e < 4 ? u.y : (e < 6 ? u.z : u.w)));
;                     const float xv = (e & 1) ? bfhi(wd) : bflo(wd);
;                     a += w[j][e] * xv;
	v_pk_fma_f32 v[100:101], v[2:3], v[114:115], 0 op_sel_hi:[1,1,0]

; DEV float bflo(unsigned u) { return __uint_as_float(u << 16); }
; DEV float bfhi(unsigned u) { return __uint_as_float(u & 0xffff0000u); }
; DEV float silu_f(float x) { return x / (1.f + __expf(-x)); }
; DEV void gdn_prep_chunk(const Params& p, int item, unsigned char* lds) {
;     ...
;                 for (int j = 0; j < 4; ++j) {
;                     const uint4 u = raw[r + j];
;                     const unsigned wd = (e < 2 ? u.x : (e < 4 ? u.y : (e < 6 ? u.z : u.w)));
;                     const float xv = (e & 1) ? bfhi(wd) : bflo(wd);
;                     a += w[j][e] * xv;
;                 }
;                 y[e] = silu_f(a); ss += y[e] * y[e];
	v_pk_fma_f32 v[100:101], v[6:7], v[92:93], v[100:101]
	v_rcp_f32_e32 v90, v99
	s_nop 0
	v_mul_f32_e32 v99, v75, v90
	v_lshlrev_b32_e32 v90, 16, v76
	v_and_b32_e32 v91, 0xffff0000, v76
	v_pk_fma_f32 v[100:101], v[10:11], v[82:83], v[100:101]

; DEV float bflo(unsigned u) { return __uint_as_float(u << 16); }
; DEV float bfhi(unsigned u) { return __uint_as_float(u & 0xffff0000u); }
; DEV void gdn_prep_chunk(const Params& p, int item, unsigned char* lds) {
;     ...
;                 for (int j = 0; j < 4; ++j) {
;                     const uint4 u = raw[r + j];
;                     const unsigned wd = (e < 2 ? u.x : (e < 4 ? u.y : (e < 6 ? u.z : u.w)));
;                     const float xv = (e & 1) ? bfhi(wd) : bflo(wd);
;                     a += w[j][e] * xv;
	v_pk_fma_f32 v[100:101], v[14:15], v[90:91], v[100:101]

; DEV float silu_f(float x) { return x / (1.f + __expf(-x)); }
; DEV void gdn_prep_chunk(const Params& p, int item, unsigned char* lds) {
;     ...
;                 y[e] = silu_f(a); ss += y[e] * y[e];
	v_mul_f32_e32 v76, 0xbfb8aa3b, v100
	v_exp_f32_e32 v102, v76
	v_mul_f32_e32 v76, 0xbfb8aa3b, v101
	v_exp_f32_e32 v103, v76


; DEV float silu_f(float x) { return x / (1.f + __expf(-x)); }
; DEV void gdn_prep_chunk(const Params& p, int item, unsigned char* lds) {
;     ...
;                 y[e] = silu_f(a); ss += y[e] * y[e];
	s_nop 0
	v_pk_add_f32 v[102:103], v[102:103], 1.0 op_sel_hi:[1,0]


; DEV float silu_f(float x) { return x / (1.f + __expf(-x)); }
; DEV void gdn_prep_chunk(const Params& p, int item, unsigned char* lds) {
;     ...
;                 y[e] = silu_f(a); ss += y[e] * y[e];
	v_rcp_f32_e32 v75, v98
	s_nop 0
	v_mul_f32_e32 v98, v74, v75


; DEV float silu_f(float x) { return x / (1.f + __expf(-x)); }
; DEV void gdn_prep_chunk(const Params& p, int item, unsigned char* lds) {
;     ...
;                 y[e] = silu_f(a); ss += y[e] * y[e];
	v_rcp_f32_e32 v74, v103
	s_nop 0
	v_mul_f32_e32 v101, v101, v74


; DEV float bflo(unsigned u) { return __uint_as_float(u << 16); }
; DEV float bfhi(unsigned u) { return __uint_as_float(u & 0xffff0000u); }
; DEV void gdn_prep_chunk(const Params& p, int item, unsigned char* lds) {
;     ...
;                 for (int j = 0; j < 4; ++j) {
;                     const uint4 u = raw[r + j];
;                     const unsigned wd = (e < 2 ? u.x : (e < 4 ? u.y : (e < 6 ? u.z : u.w)));
;                     const float xv = (e & 1) ? bfhi(wd) : bflo(wd);
;                     a += w[j][e] * xv;
	v_lshlrev_b32_e32 v74, 16, v77
	v_and_b32_e32 v75, 0xffff0000, v77
	v_pk_fma_f32 v[76:77], v[4:5], v[112:113], 0 op_sel_hi:[1,1,0]

; DEV float bflo(unsigned u) { return __uint_as_float(u << 16); }
; DEV float bfhi(unsigned u) { return __uint_as_float(u & 0xffff0000u); }
; DEV void gdn_prep_chunk(const Params& p, int item, unsigned char* lds) {
;     ...
;                 for (int j = 0; j < 4; ++j) {
;                     const uint4 u = raw[r + j];
;                     const unsigned wd = (e < 2 ? u.x : (e < 4 ? u.y : (e < 6 ? u.z : u.w)));
;                     const float xv = (e & 1) ? bfhi(wd) : bflo(wd);
;                     a += w[j][e] * xv;
	v_pk_fma_f32 v[76:77], v[8:9], v[88:89], v[76:77]

; DEV float bflo(unsigned u) { return __uint_as_float(u << 16); }
; DEV float bfhi(unsigned u) { return __uint_as_float(u & 0xffff0000u); }
; DEV void gdn_prep_chunk(const Params& p, int item, unsigned char* lds) {
;     ...
;                 for (int j = 0; j < 4; ++j) {
;                     const uint4 u = raw[r + j];
;                     const unsigned wd = (e < 2 ? u.x : (e < 4 ? u.y : (e < 6 ? u.z : u.w)));
;                     const float xv = (e & 1) ? bfhi(wd) : bflo(wd);
;                     a += w[j][e] * xv;
	v_pk_fma_f32 v[76:77], v[12:13], v[78:79], v[76:77]

; DEV float bflo(unsigned u) { return __uint_as_float(u << 16); }
; DEV float bfhi(unsigned u) { return __uint_as_float(u & 0xffff0000u); }
; DEV void gdn_prep_chunk(const Params& p, int item, unsigned char* lds) {
;     ...
;                 for (int j = 0; j < 4; ++j) {
;                     const uint4 u = raw[r + j];
;                     const unsigned wd = (e < 2 ? u.x : (e < 4 ? u.y : (e < 6 ? u.z : u.w)));
;                     const float xv = (e & 1) ? bfhi(wd) : bflo(wd);
;                     a += w[j][e] * xv;
	v_pk_fma_f32 v[76:77], v[16:17], v[74:75], v[76:77]

; DEV float bflo(unsigned u) { return __uint_as_float(u << 16); }
; DEV float bfhi(unsigned u) { return __uint_as_float(u & 0xffff0000u); }
; DEV float silu_f(float x) { return x / (1.f + __expf(-x)); }
; DEV void gdn_prep_chunk(const Params& p, int item, unsigned char* lds) {
;     ...
;             for (int e = 0; e < 8; ++e) {
;                 float a = 0.f;
; #pragma unroll
;                 for (int j = 0; j < 4; ++j) {
;                     const uint4 u = raw[r + j];
;                     const unsigned wd = (e < 2 ? u.x : (e < 4 ? u.y : (e < 6 ? u.z : u.w)));
;                     const float xv = (e & 1) ? bfhi(wd) : bflo(wd);
;                     a += w[j][e] * xv;
;                 }
;                 y[e] = silu_f(a); ss += y[e] * y[e];
	v_mul_f32_e32 v110, 0xbfb8aa3b, v76
	v_mul_f32_e32 v111, 0xbfb8aa3b, v77
	v_exp_f32_e32 v110, v110
	v_exp_f32_e32 v111, v111


; DEV float silu_f(float x) { return x / (1.f + __expf(-x)); }
; DEV void gdn_prep_chunk(const Params& p, int item, unsigned char* lds) {
;     ...
;                 y[e] = silu_f(a); ss += y[e] * y[e];
	v_rcp_f32_e32 v103, v102
	s_nop 0
	v_mul_f32_e32 v100, v100, v103
	v_pk_add_f32 v[110:111], v[110:111], 1.0 op_sel_hi:[1,0]
	s_nop 0


; DEV float silu_f(float x) { return x / (1.f + __expf(-x)); }
; DEV void gdn_prep_chunk(const Params& p, int item, unsigned char* lds) {
;     ...
;                 y[e] = silu_f(a); ss += y[e] * y[e];
	s_nop 0


; DEV float silu_f(float x) { return x / (1.f + __expf(-x)); }
; DEV void gdn_prep_chunk(const Params& p, int item, unsigned char* lds) {
;     ...
;                 y[e] = silu_f(a); ss += y[e] * y[e];
	v_rcp_f32_e32 v102, v111
	s_nop 0
	v_mul_f32_e32 v103, v77, v102


; DEV unsigned cvt_pk_bf16(float lo, float hi) { const f32x2_t v = {lo, hi}; const bf16x2_t b = __builtin_convertvector(v, bf16x2_t); return __builtin_bit_cast(unsigned, b); }
; DEV float silu_f(float x) { return x / (1.f + __expf(-x)); }
; DEV void gdn_prep_chunk(const Params& p, int item, unsigned char* lds) {
;     ...
;                 y[e] = silu_f(a); ss += y[e] * y[e];
;             }
;             if (mat < 2) {
;                 ss += __shfl_xor(ss, 1); ss += __shfl_xor(ss, 2); ss += __shfl_xor(ss, 4); ss += __shfl_xor(ss, 8);
;                 float inv = rsqrtf(ss + EPS); if (mat == 0) inv *= 0.08838834764831845f;
; #pragma unroll
;                 for (int e = 0; e < 8; ++e) y[e] *= inv;
;             }
;             uint4 o; o.x = cvt_pk_bf16(y[0], y[1]); o.y = cvt_pk_bf16(y[2], y[3]); o.z = cvt_pk_bf16(y[4], y[5]); o.w = cvt_pk_bf16(y[6], y[7]);
;             *(uint4*)(dst + (tl0 + r) * QS + cv * 8) = o;
;         }
	v_rcp_f32_e32 v77, v110
	s_nop 0
	v_mul_f32_e32 v102, v76, v77
	s_and_saveexec_b64 s[36:37], s[6:7]
	s_cbranch_execz .LBB0_484
	v_pk_mul_f32 v[76:77], v[96:97], v[96:97]
	v_pk_mul_f32 v[110:111], v[98:99], v[98:99]
	v_add_f32_e32 v76, v76, v77
	v_add_f32_e32 v76, v76, v110
	v_pk_mul_f32 v[112:113], v[100:101], v[100:101]
	v_add_f32_e32 v76, v111, v76
	v_and_b32_e32 v105, 64, v182
	v_add_f32_e32 v76, v112, v76
	v_xor_b32_e32 v77, 1, v182
	v_add_u32_e32 v105, 64, v105
	v_pk_mul_f32 v[114:115], v[102:103], v[102:103]
	v_add_f32_e32 v76, v113, v76
	v_cmp_lt_i32_e32 vcc, v77, v105
	v_add_f32_e32 v76, v114, v76
	v_add_f32_e32 v76, v115, v76
	v_cndmask_b32_e32 v77, v182, v77, vcc
	v_lshlrev_b32_e32 v77, 2, v77
	ds_bpermute_b32 v77, v77, v76
	s_waitcnt lgkmcnt(0)
	v_add_f32_e32 v76, v76, v77
	v_xor_b32_e32 v77, 2, v182
	v_cmp_lt_i32_e32 vcc, v77, v105
	s_nop 1
	v_cndmask_b32_e32 v77, v182, v77, vcc
	v_lshlrev_b32_e32 v77, 2, v77
	ds_bpermute_b32 v77, v77, v76
	s_waitcnt lgkmcnt(0)
	v_add_f32_e32 v76, v76, v77
	v_xor_b32_e32 v77, 4, v182
	v_cmp_lt_i32_e32 vcc, v77, v105
	s_nop 1
	v_cndmask_b32_e32 v77, v182, v77, vcc
	v_lshlrev_b32_e32 v77, 2, v77
	ds_bpermute_b32 v77, v77, v76
	s_waitcnt lgkmcnt(0)
	v_add_f32_e32 v76, v76, v77
	v_xor_b32_e32 v77, 8, v182
	v_cmp_lt_i32_e32 vcc, v77, v105
	s_nop 1
	v_cndmask_b32_e32 v77, v182, v77, vcc
	v_lshlrev_b32_e32 v77, 2, v77
	ds_bpermute_b32 v77, v77, v76
	s_waitcnt lgkmcnt(0)
	v_add_f32_e32 v76, v76, v77
	v_add_f32_e32 v76, 0x358637bd, v76
	v_mul_f32_e32 v77, 0x4b800000, v76
	v_cmp_gt_f32_e32 vcc, s56, v76
	s_nop 1
	v_cndmask_b32_e32 v76, v76, v77, vcc
	v_rsq_f32_e32 v76, v76
	s_nop 0
	v_mul_f32_e32 v77, 0x45800000, v76
	v_cndmask_b32_e32 v76, v76, v77, vcc
	v_mul_f32_e32 v77, 0x3db504f3, v76
	v_cndmask_b32_e64 v76, v76, v77, s[4:5]
	v_pk_mul_f32 v[96:97], v[96:97], v[76:77] op_sel_hi:[1,0]
	v_pk_mul_f32 v[98:99], v[98:99], v[76:77] op_sel_hi:[1,0]
	v_pk_mul_f32 v[100:101], v[100:101], v[76:77] op_sel_hi:[1,0]
	v_pk_mul_f32 v[102:103], v[102:103], v[76:77] op_sel_hi:[1,0]
.LBB0_484:
	s_or_b64 exec, exec, s[36:37]
	v_pk_fma_f32 v[108:109], v[18:19], v[108:109], 0 op_sel_hi:[1,1,0]
	s_waitcnt vmcnt(9)
	v_lshlrev_b32_e32 v76, 16, v70
	v_pk_fma_f32 v[108:109], v[22:23], v[86:87], v[108:109]
	v_and_b32_e32 v77, 0xffff0000, v70
	v_pk_fma_f32 v[108:109], v[26:27], v[80:81], v[108:109]
	v_cvt_pk_bf16_f32 v96, v96, v97
	v_pk_fma_f32 v[108:109], v[30:31], v[76:77], v[108:109]
	v_cvt_pk_bf16_f32 v97, v98, v99
	v_mul_f32_e32 v70, 0xbfb8aa3b, v108
	v_exp_f32_e32 v110, v70
	v_mul_f32_e32 v70, 0xbfb8aa3b, v109
	v_exp_f32_e32 v111, v70
	v_cvt_pk_bf16_f32 v98, v100, v101
	v_cvt_pk_bf16_f32 v99, v102, v103
	v_add_u32_e32 v104, 0x110, v104
	v_pk_add_f32 v[100:101], v[110:111], 1.0 op_sel_hi:[1,0]
	v_add_u32_e32 v103, v132, v104


; DEV float silu_f(float x) { return x / (1.f + __expf(-x)); }
; DEV void gdn_prep_chunk(const Params& p, int item, unsigned char* lds) {
;     ...
;                 y[e] = silu_f(a); ss += y[e] * y[e];
;     ...
;             *(uint4*)(dst + (tl0 + r) * QS + cv * 8) = o;
	ds_write_b128 v103, v[96:99]


; DEV float silu_f(float x) { return x / (1.f + __expf(-x)); }
; DEV void gdn_prep_chunk(const Params& p, int item, unsigned char* lds) {
;     ...
;                 y[e] = silu_f(a); ss += y[e] * y[e];
	v_rcp_f32_e32 v70, v101
	s_nop 0
	v_mul_f32_e32 v101, v109, v70


; DEV float bflo(unsigned u) { return __uint_as_float(u << 16); }
; DEV float bfhi(unsigned u) { return __uint_as_float(u & 0xffff0000u); }
; DEV void gdn_prep_chunk(const Params& p, int item, unsigned char* lds) {
;     ...
;                 float a = 0.f;
; #pragma unroll
;                 for (int j = 0; j < 4; ++j) {
;                     const uint4 u = raw[r + j];
;                     const unsigned wd = (e < 2 ? u.x : (e < 4 ? u.y : (e < 6 ? u.z : u.w)));
;                     const float xv = (e & 1) ? bfhi(wd) : bflo(wd);
;                     a += w[j][e] * xv;
;                 }
	v_lshlrev_b32_e32 v98, 16, v71
	v_and_b32_e32 v99, 0xffff0000, v71
	v_pk_fma_f32 v[70:71], v[20:21], v[106:107], 0 op_sel_hi:[1,1,0]

; DEV float bflo(unsigned u) { return __uint_as_float(u << 16); }
; DEV float bfhi(unsigned u) { return __uint_as_float(u & 0xffff0000u); }
; DEV void gdn_prep_chunk(const Params& p, int item, unsigned char* lds) {
;     ...
;                 float a = 0.f;
; #pragma unroll
;                 for (int j = 0; j < 4; ++j) {
;                     const uint4 u = raw[r + j];
;                     const unsigned wd = (e < 2 ? u.x : (e < 4 ? u.y : (e < 6 ? u.z : u.w)));
;                     const float xv = (e & 1) ? bfhi(wd) : bflo(wd);
;                     a += w[j][e] * xv;
;                 }
	v_pk_fma_f32 v[70:71], v[24:25], v[84:85], v[70:71]

; DEV float bflo(unsigned u) { return __uint_as_float(u << 16); }
; DEV float bfhi(unsigned u) { return __uint_as_float(u & 0xffff0000u); }
; DEV void gdn_prep_chunk(const Params& p, int item, unsigned char* lds) {
;     ...
;                 float a = 0.f;
; #pragma unroll
;                 for (int j = 0; j < 4; ++j) {
;                     const uint4 u = raw[r + j];
;                     const unsigned wd = (e < 2 ? u.x : (e < 4 ? u.y : (e < 6 ? u.z : u.w)));
;                     const float xv = (e & 1) ? bfhi(wd) : bflo(wd);
;                     a += w[j][e] * xv;
;                 }
	v_pk_fma_f32 v[70:71], v[28:29], v[94:95], v[70:71]

; DEV float bflo(unsigned u) { return __uint_as_float(u << 16); }
; DEV float bfhi(unsigned u) { return __uint_as_float(u & 0xffff0000u); }
; DEV void gdn_prep_chunk(const Params& p, int item, unsigned char* lds) {
;     ...
;                 float a = 0.f;
; #pragma unroll
;                 for (int j = 0; j < 4; ++j) {
;                     const uint4 u = raw[r + j];
;                     const unsigned wd = (e < 2 ? u.x : (e < 4 ? u.y : (e < 6 ? u.z : u.w)));
;                     const float xv = (e & 1) ? bfhi(wd) : bflo(wd);
;                     a += w[j][e] * xv;
;                 }
	v_pk_fma_f32 v[70:71], v[32:33], v[98:99], v[70:71]

; DEV float silu_f(float x) { return x / (1.f + __expf(-x)); }
; DEV void gdn_prep_chunk(const Params& p, int item, unsigned char* lds) {
;     ...
;                 y[e] = silu_f(a); ss += y[e] * y[e];
	v_mul_f32_e32 v96, 0xbfb8aa3b, v70
	v_mul_f32_e32 v97, 0xbfb8aa3b, v71
	v_exp_f32_e32 v96, v96
	v_exp_f32_e32 v97, v97


; DEV float silu_f(float x) { return x / (1.f + __expf(-x)); }
; DEV void gdn_prep_chunk(const Params& p, int item, unsigned char* lds) {
;     ...
;                 y[e] = silu_f(a); ss += y[e] * y[e];
	v_rcp_f32_e32 v105, v100
	s_nop 0
	v_mul_f32_e32 v100, v108, v105
	v_pk_add_f32 v[102:103], v[96:97], 1.0 op_sel_hi:[1,0]
	v_pk_fma_f32 v[92:93], v[2:3], v[92:93], 0 op_sel_hi:[1,1,0]


; DEV float bflo(unsigned u) { return __uint_as_float(u << 16); }
; DEV float bfhi(unsigned u) { return __uint_as_float(u & 0xffff0000u); }
; DEV float silu_f(float x) { return x / (1.f + __expf(-x)); }
; DEV void gdn_prep_chunk(const Params& p, int item, unsigned char* lds) {
;     ...
;                 float a = 0.f;
; #pragma unroll
;                 for (int j = 0; j < 4; ++j) {
;                     const uint4 u = raw[r + j];
;                     const unsigned wd = (e < 2 ? u.x : (e < 4 ? u.y : (e < 6 ? u.z : u.w)));
;                     const float xv = (e & 1) ? bfhi(wd) : bflo(wd);
;                     a += w[j][e] * xv;
;                 }
;                 y[e] = silu_f(a); ss += y[e] * y[e];
	v_pk_fma_f32 v[92:93], v[6:7], v[82:83], v[92:93]


; DEV float bflo(unsigned u) { return __uint_as_float(u << 16); }
; DEV float bfhi(unsigned u) { return __uint_as_float(u & 0xffff0000u); }
; DEV float silu_f(float x) { return x / (1.f + __expf(-x)); }
; DEV void gdn_prep_chunk(const Params& p, int item, unsigned char* lds) {
;     ...
;                     const float xv = (e & 1) ? bfhi(wd) : bflo(wd);
;                     a += w[j][e] * xv;
;                 }
;                 y[e] = silu_f(a); ss += y[e] * y[e];
	v_rcp_f32_e32 v96, v103
	s_nop 0
	v_mul_f32_e32 v103, v71, v96
	v_lshlrev_b32_e32 v96, 16, v72
	v_and_b32_e32 v97, 0xffff0000, v72
	v_pk_fma_f32 v[92:93], v[10:11], v[90:91], v[92:93]

; DEV float bflo(unsigned u) { return __uint_as_float(u << 16); }
; DEV float bfhi(unsigned u) { return __uint_as_float(u & 0xffff0000u); }
; DEV void gdn_prep_chunk(const Params& p, int item, unsigned char* lds) {
;     ...
;                 float a = 0.f;
; #pragma unroll
;                 for (int j = 0; j < 4; ++j) {
;                     const uint4 u = raw[r + j];
;                     const unsigned wd = (e < 2 ? u.x : (e < 4 ? u.y : (e < 6 ? u.z : u.w)));
;                     const float xv = (e & 1) ? bfhi(wd) : bflo(wd);
;                     a += w[j][e] * xv;
;                 }
	v_pk_fma_f32 v[92:93], v[14:15], v[96:97], v[92:93]

; DEV float silu_f(float x) { return x / (1.f + __expf(-x)); }
; DEV void gdn_prep_chunk(const Params& p, int item, unsigned char* lds) {
;     ...
;                 y[e] = silu_f(a); ss += y[e] * y[e];
	v_mul_f32_e32 v72, 0xbfb8aa3b, v92
	v_exp_f32_e32 v106, v72
	v_mul_f32_e32 v72, 0xbfb8aa3b, v93
	v_exp_f32_e32 v107, v72


; DEV float silu_f(float x) { return x / (1.f + __expf(-x)); }
; DEV void gdn_prep_chunk(const Params& p, int item, unsigned char* lds) {
;     ...
;                 y[e] = silu_f(a); ss += y[e] * y[e];
	s_nop 0
	v_pk_add_f32 v[106:107], v[106:107], 1.0 op_sel_hi:[1,0]


; DEV float silu_f(float x) { return x / (1.f + __expf(-x)); }
; DEV void gdn_prep_chunk(const Params& p, int item, unsigned char* lds) {
;     ...
;                 y[e] = silu_f(a); ss += y[e] * y[e];
	v_rcp_f32_e32 v71, v102
	s_nop 0
	v_mul_f32_e32 v102, v70, v71


; DEV float silu_f(float x) { return x / (1.f + __expf(-x)); }
; DEV void gdn_prep_chunk(const Params& p, int item, unsigned char* lds) {
;     ...
;                 y[e] = silu_f(a); ss += y[e] * y[e];
	v_rcp_f32_e32 v70, v107
	s_nop 0
	v_mul_f32_e32 v93, v93, v70


; DEV float bflo(unsigned u) { return __uint_as_float(u << 16); }
; DEV float bfhi(unsigned u) { return __uint_as_float(u & 0xffff0000u); }
; DEV void gdn_prep_chunk(const Params& p, int item, unsigned char* lds) {
;     ...
;                 float a = 0.f;
; #pragma unroll
;                 for (int j = 0; j < 4; ++j) {
;                     const uint4 u = raw[r + j];
;                     const unsigned wd = (e < 2 ? u.x : (e < 4 ? u.y : (e < 6 ? u.z : u.w)));
;                     const float xv = (e & 1) ? bfhi(wd) : bflo(wd);
;                     a += w[j][e] * xv;
;                 }
	v_lshlrev_b32_e32 v70, 16, v73
	v_and_b32_e32 v71, 0xffff0000, v73
	v_pk_fma_f32 v[72:73], v[4:5], v[88:89], 0 op_sel_hi:[1,1,0]

; DEV float bflo(unsigned u) { return __uint_as_float(u << 16); }
; DEV float bfhi(unsigned u) { return __uint_as_float(u & 0xffff0000u); }
; DEV void gdn_prep_chunk(const Params& p, int item, unsigned char* lds) {
;     ...
;                 float a = 0.f;
; #pragma unroll
;                 for (int j = 0; j < 4; ++j) {
;                     const uint4 u = raw[r + j];
;                     const unsigned wd = (e < 2 ? u.x : (e < 4 ? u.y : (e < 6 ? u.z : u.w)));
;                     const float xv = (e & 1) ? bfhi(wd) : bflo(wd);
;                     a += w[j][e] * xv;
;                 }
	v_pk_fma_f32 v[72:73], v[8:9], v[78:79], v[72:73]

; DEV float bflo(unsigned u) { return __uint_as_float(u << 16); }
; DEV float bfhi(unsigned u) { return __uint_as_float(u & 0xffff0000u); }
; DEV void gdn_prep_chunk(const Params& p, int item, unsigned char* lds) {
;     ...
;                 float a = 0.f;
; #pragma unroll
;                 for (int j = 0; j < 4; ++j) {
;                     const uint4 u = raw[r + j];
;                     const unsigned wd = (e < 2 ? u.x : (e < 4 ? u.y : (e < 6 ? u.z : u.w)));
;                     const float xv = (e & 1) ? bfhi(wd) : bflo(wd);
;                     a += w[j][e] * xv;
;                 }
	v_pk_fma_f32 v[72:73], v[12:13], v[74:75], v[72:73]

; DEV float bflo(unsigned u) { return __uint_as_float(u << 16); }
; DEV float bfhi(unsigned u) { return __uint_as_float(u & 0xffff0000u); }
; DEV void gdn_prep_chunk(const Params& p, int item, unsigned char* lds) {
;     ...
;                 float a = 0.f;
; #pragma unroll
;                 for (int j = 0; j < 4; ++j) {
;                     const uint4 u = raw[r + j];
;                     const unsigned wd = (e < 2 ? u.x : (e < 4 ? u.y : (e < 6 ? u.z : u.w)));
;                     const float xv = (e & 1) ? bfhi(wd) : bflo(wd);
;                     a += w[j][e] * xv;
;                 }
	v_pk_fma_f32 v[72:73], v[16:17], v[70:71], v[72:73]

; DEV float silu_f(float x) { return x / (1.f + __expf(-x)); }
; DEV void gdn_prep_chunk(const Params& p, int item, unsigned char* lds) {
;     ...
;                 y[e] = silu_f(a); ss += y[e] * y[e];
	v_mul_f32_e32 v88, 0xbfb8aa3b, v72
	v_mul_f32_e32 v89, 0xbfb8aa3b, v73
	v_exp_f32_e32 v88, v88
	v_exp_f32_e32 v89, v89


; DEV float silu_f(float x) { return x / (1.f + __expf(-x)); }
; DEV void gdn_prep_chunk(const Params& p, int item, unsigned char* lds) {
;     ...
;                 y[e] = silu_f(a); ss += y[e] * y[e];
	v_rcp_f32_e32 v105, v106
	s_nop 0
	v_mul_f32_e32 v92, v92, v105
	v_pk_add_f32 v[88:89], v[88:89], 1.0 op_sel_hi:[1,0]
	s_nop 0


; DEV float silu_f(float x) { return x / (1.f + __expf(-x)); }
; DEV void gdn_prep_chunk(const Params& p, int item, unsigned char* lds) {
;     ...
;                 y[e] = silu_f(a); ss += y[e] * y[e];
	s_nop 0


; DEV float silu_f(float x) { return x / (1.f + __expf(-x)); }
; DEV void gdn_prep_chunk(const Params& p, int item, unsigned char* lds) {
;     ...
;                 y[e] = silu_f(a); ss += y[e] * y[e];
	v_rcp_f32_e32 v105, v89
	s_nop 0
	v_mul_f32_e32 v89, v73, v105


; DEV unsigned cvt_pk_bf16(float lo, float hi) { const f32x2_t v = {lo, hi}; const bf16x2_t b = __builtin_convertvector(v, bf16x2_t); return __builtin_bit_cast(unsigned, b); }
; DEV float silu_f(float x) { return x / (1.f + __expf(-x)); }
; DEV void gdn_prep_chunk(const Params& p, int item, unsigned char* lds) {
;     ...
;                 y[e] = silu_f(a); ss += y[e] * y[e];
;             }
;             if (mat < 2) {
;                 ss += __shfl_xor(ss, 1); ss += __shfl_xor(ss, 2); ss += __shfl_xor(ss, 4); ss += __shfl_xor(ss, 8);
;                 float inv = rsqrtf(ss + EPS); if (mat == 0) inv *= 0.08838834764831845f;
; #pragma unroll
;                 for (int e = 0; e < 8; ++e) y[e] *= inv;
;             }
;             uint4 o; o.x = cvt_pk_bf16(y[0], y[1]); o.y = cvt_pk_bf16(y[2], y[3]); o.z = cvt_pk_bf16(y[4], y[5]); o.w = cvt_pk_bf16(y[6], y[7]);
;             *(uint4*)(dst + (tl0 + r) * QS + cv * 8) = o;
;         }
	v_rcp_f32_e32 v73, v88
	s_nop 0
	v_mul_f32_e32 v88, v72, v73
	s_and_saveexec_b64 s[36:37], s[6:7]
	s_cbranch_execz .LBB0_486
	v_pk_mul_f32 v[72:73], v[100:101], v[100:101]
	v_pk_mul_f32 v[106:107], v[102:103], v[102:103]
	v_add_f32_e32 v72, v72, v73
	v_add_f32_e32 v72, v72, v106
	v_pk_mul_f32 v[108:109], v[92:93], v[92:93]
	v_add_f32_e32 v72, v107, v72
	v_and_b32_e32 v105, 64, v182
	v_add_f32_e32 v72, v108, v72
	v_xor_b32_e32 v73, 1, v182
	v_add_u32_e32 v105, 64, v105
	v_pk_mul_f32 v[110:111], v[88:89], v[88:89]
	v_add_f32_e32 v72, v109, v72
	v_cmp_lt_i32_e32 vcc, v73, v105
	v_add_f32_e32 v72, v110, v72
	v_add_f32_e32 v72, v111, v72
	v_cndmask_b32_e32 v73, v182, v73, vcc
	v_lshlrev_b32_e32 v73, 2, v73
	ds_bpermute_b32 v73, v73, v72
	s_waitcnt lgkmcnt(0)
	v_add_f32_e32 v72, v72, v73
	v_xor_b32_e32 v73, 2, v182
	v_cmp_lt_i32_e32 vcc, v73, v105
	s_nop 1
	v_cndmask_b32_e32 v73, v182, v73, vcc
	v_lshlrev_b32_e32 v73, 2, v73
	ds_bpermute_b32 v73, v73, v72
	s_waitcnt lgkmcnt(0)
	v_add_f32_e32 v72, v72, v73
	v_xor_b32_e32 v73, 4, v182
	v_cmp_lt_i32_e32 vcc, v73, v105
	s_nop 1
	v_cndmask_b32_e32 v73, v182, v73, vcc
	v_lshlrev_b32_e32 v73, 2, v73
	ds_bpermute_b32 v73, v73, v72
	s_waitcnt lgkmcnt(0)
	v_add_f32_e32 v72, v72, v73
	v_xor_b32_e32 v73, 8, v182
	v_cmp_lt_i32_e32 vcc, v73, v105
	s_nop 1
	v_cndmask_b32_e32 v73, v182, v73, vcc
	v_lshlrev_b32_e32 v73, 2, v73
	ds_bpermute_b32 v73, v73, v72
	s_waitcnt lgkmcnt(0)
	v_add_f32_e32 v72, v72, v73
	v_add_f32_e32 v72, 0x358637bd, v72
	v_mul_f32_e32 v73, 0x4b800000, v72
	v_cmp_gt_f32_e32 vcc, s56, v72
	s_nop 1
	v_cndmask_b32_e32 v72, v72, v73, vcc
	v_rsq_f32_e32 v72, v72
	s_nop 0
	v_mul_f32_e32 v73, 0x45800000, v72
	v_cndmask_b32_e32 v72, v72, v73, vcc
	v_mul_f32_e32 v73, 0x3db504f3, v72
	v_cndmask_b32_e64 v72, v72, v73, s[4:5]
	v_pk_mul_f32 v[100:101], v[100:101], v[72:73] op_sel_hi:[1,0]
	v_pk_mul_f32 v[102:103], v[102:103], v[72:73] op_sel_hi:[1,0]
	v_pk_mul_f32 v[92:93], v[92:93], v[72:73] op_sel_hi:[1,0]
	v_pk_mul_f32 v[88:89], v[88:89], v[72:73] op_sel_hi:[1,0]
.LBB0_486:
	s_or_b64 exec, exec, s[36:37]
	v_pk_fma_f32 v[86:87], v[18:19], v[86:87], 0 op_sel_hi:[1,1,0]
	s_waitcnt vmcnt(8)
	v_lshlrev_b32_e32 v72, 16, v66
	v_pk_fma_f32 v[86:87], v[22:23], v[80:81], v[86:87]
	v_and_b32_e32 v73, 0xffff0000, v66
	v_pk_fma_f32 v[86:87], v[26:27], v[76:77], v[86:87]
	v_cvt_pk_bf16_f32 v100, v100, v101
	v_pk_fma_f32 v[86:87], v[30:31], v[72:73], v[86:87]
	v_cvt_pk_bf16_f32 v101, v102, v103
	v_mul_f32_e32 v66, 0xbfb8aa3b, v86
	v_exp_f32_e32 v106, v66
	v_mul_f32_e32 v66, 0xbfb8aa3b, v87
	v_exp_f32_e32 v107, v66
	v_cvt_pk_bf16_f32 v103, v88, v89
	v_cvt_pk_bf16_f32 v102, v92, v93
	v_add_u32_e32 v93, 0x110, v104
	v_pk_add_f32 v[88:89], v[106:107], 1.0 op_sel_hi:[1,0]
	v_add_u32_e32 v104, v132, v93


; DEV float silu_f(float x) { return x / (1.f + __expf(-x)); }
; DEV void gdn_prep_chunk(const Params& p, int item, unsigned char* lds) {
;     ...
;                 y[e] = silu_f(a); ss += y[e] * y[e];
;     ...
;             *(uint4*)(dst + (tl0 + r) * QS + cv * 8) = o;
	ds_write_b128 v104, v[100:103]
	v_pk_fma_f32 v[82:83], v[2:3], v[82:83], 0 op_sel_hi:[1,1,0]


; DEV float bflo(unsigned u) { return __uint_as_float(u << 16); }
; DEV float bfhi(unsigned u) { return __uint_as_float(u & 0xffff0000u); }
; DEV float silu_f(float x) { return x / (1.f + __expf(-x)); }
; DEV void gdn_prep_chunk(const Params& p, int item, unsigned char* lds) {
;     ...
;                     const float xv = (e & 1) ? bfhi(wd) : bflo(wd);
;                     a += w[j][e] * xv;
;                 }
;                 y[e] = silu_f(a); ss += y[e] * y[e];
	v_rcp_f32_e32 v66, v89
	s_nop 0
	v_mul_f32_e32 v103, v87, v66
	v_lshlrev_b32_e32 v100, 16, v67


; DEV float bflo(unsigned u) { return __uint_as_float(u << 16); }
; DEV float bfhi(unsigned u) { return __uint_as_float(u & 0xffff0000u); }
; DEV void gdn_prep_chunk(const Params& p, int item, unsigned char* lds) {
;     ...
;                 float a = 0.f;
; #pragma unroll
;                 for (int j = 0; j < 4; ++j) {
;                     const uint4 u = raw[r + j];
;                     const unsigned wd = (e < 2 ? u.x : (e < 4 ? u.y : (e < 6 ? u.z : u.w)));
;                     const float xv = (e & 1) ? bfhi(wd) : bflo(wd);
;                     a += w[j][e] * xv;
;                 }
	v_and_b32_e32 v101, 0xffff0000, v67
	v_pk_fma_f32 v[66:67], v[20:21], v[84:85], 0 op_sel_hi:[1,1,0]

; DEV float bflo(unsigned u) { return __uint_as_float(u << 16); }
; DEV float bfhi(unsigned u) { return __uint_as_float(u & 0xffff0000u); }
; DEV void gdn_prep_chunk(const Params& p, int item, unsigned char* lds) {
;     ...
;                 float a = 0.f;
; #pragma unroll
;                 for (int j = 0; j < 4; ++j) {
;                     const uint4 u = raw[r + j];
;                     const unsigned wd = (e < 2 ? u.x : (e < 4 ? u.y : (e < 6 ? u.z : u.w)));
;                     const float xv = (e & 1) ? bfhi(wd) : bflo(wd);
;                     a += w[j][e] * xv;
;                 }
	v_pk_fma_f32 v[66:67], v[24:25], v[94:95], v[66:67]

; DEV float bflo(unsigned u) { return __uint_as_float(u << 16); }
; DEV float bfhi(unsigned u) { return __uint_as_float(u & 0xffff0000u); }
; DEV void gdn_prep_chunk(const Params& p, int item, unsigned char* lds) {
;     ...
;                 float a = 0.f;
; #pragma unroll
;                 for (int j = 0; j < 4; ++j) {
;                     const uint4 u = raw[r + j];
;                     const unsigned wd = (e < 2 ? u.x : (e < 4 ? u.y : (e < 6 ? u.z : u.w)));
;                     const float xv = (e & 1) ? bfhi(wd) : bflo(wd);
;                     a += w[j][e] * xv;
;                 }
	v_pk_fma_f32 v[66:67], v[28:29], v[98:99], v[66:67]

; DEV float bflo(unsigned u) { return __uint_as_float(u << 16); }
; DEV float bfhi(unsigned u) { return __uint_as_float(u & 0xffff0000u); }
; DEV void gdn_prep_chunk(const Params& p, int item, unsigned char* lds) {
;     ...
;                 float a = 0.f;
; #pragma unroll
;                 for (int j = 0; j < 4; ++j) {
;                     const uint4 u = raw[r + j];
;                     const unsigned wd = (e < 2 ? u.x : (e < 4 ? u.y : (e < 6 ? u.z : u.w)));
;                     const float xv = (e & 1) ? bfhi(wd) : bflo(wd);
;                     a += w[j][e] * xv;
;                 }
	v_pk_fma_f32 v[66:67], v[32:33], v[100:101], v[66:67]

; DEV float silu_f(float x) { return x / (1.f + __expf(-x)); }
; DEV void gdn_prep_chunk(const Params& p, int item, unsigned char* lds) {
;     ...
;                 y[e] = silu_f(a); ss += y[e] * y[e];
	v_mul_f32_e32 v84, 0xbfb8aa3b, v66
	v_mul_f32_e32 v85, 0xbfb8aa3b, v67
	v_exp_f32_e32 v84, v84
	v_exp_f32_e32 v85, v85


; DEV float silu_f(float x) { return x / (1.f + __expf(-x)); }
; DEV void gdn_prep_chunk(const Params& p, int item, unsigned char* lds) {
;     ...
;                 y[e] = silu_f(a); ss += y[e] * y[e];
	v_rcp_f32_e32 v87, v88
	s_nop 0
	v_mul_f32_e32 v102, v86, v87
	v_pk_add_f32 v[84:85], v[84:85], 1.0 op_sel_hi:[1,0]
	v_pk_fma_f32 v[82:83], v[6:7], v[90:91], v[82:83]


; DEV float bflo(unsigned u) { return __uint_as_float(u << 16); }
; DEV float bfhi(unsigned u) { return __uint_as_float(u & 0xffff0000u); }
; DEV float silu_f(float x) { return x / (1.f + __expf(-x)); }
; DEV void gdn_prep_chunk(const Params& p, int item, unsigned char* lds) {
;     ...
;                 float a = 0.f;
; #pragma unroll
;                 for (int j = 0; j < 4; ++j) {
;                     const uint4 u = raw[r + j];
;                     const unsigned wd = (e < 2 ? u.x : (e < 4 ? u.y : (e < 6 ? u.z : u.w)));
;                     const float xv = (e & 1) ? bfhi(wd) : bflo(wd);
;                     a += w[j][e] * xv;
;                 }
;                 y[e] = silu_f(a); ss += y[e] * y[e];
	v_pk_fma_f32 v[82:83], v[10:11], v[96:97], v[82:83]


; DEV float bflo(unsigned u) { return __uint_as_float(u << 16); }
; DEV float bfhi(unsigned u) { return __uint_as_float(u & 0xffff0000u); }
; DEV float silu_f(float x) { return x / (1.f + __expf(-x)); }
; DEV void gdn_prep_chunk(const Params& p, int item, unsigned char* lds) {
;     ...
;                 float a = 0.f;
; #pragma unroll
;                 for (int j = 0; j < 4; ++j) {
;                     const uint4 u = raw[r + j];
;                     const unsigned wd = (e < 2 ? u.x : (e < 4 ? u.y : (e < 6 ? u.z : u.w)));
;                     const float xv = (e & 1) ? bfhi(wd) : bflo(wd);
;                     a += w[j][e] * xv;
;                 }
;                 y[e] = silu_f(a); ss += y[e] * y[e];
	v_lshlrev_b32_e32 v92, 16, v68
	v_and_b32_e32 v93, 0xffff0000, v68
	v_pk_fma_f32 v[82:83], v[14:15], v[92:93], v[82:83]
	v_rcp_f32_e32 v86, v85
	s_nop 0
	v_mul_f32_e32 v67, v67, v86
	v_mul_f32_e32 v68, 0xbfb8aa3b, v82
	v_exp_f32_e32 v86, v68
	v_mul_f32_e32 v68, 0xbfb8aa3b, v83

; DEV float silu_f(float x) { return x / (1.f + __expf(-x)); }
; DEV void gdn_prep_chunk(const Params& p, int item, unsigned char* lds) {
;     ...
;                 y[e] = silu_f(a); ss += y[e] * y[e];
	v_exp_f32_e32 v87, v68


; DEV float silu_f(float x) { return x / (1.f + __expf(-x)); }
; DEV void gdn_prep_chunk(const Params& p, int item, unsigned char* lds) {
;     ...
;                 y[e] = silu_f(a); ss += y[e] * y[e];
	s_nop 0
	v_pk_add_f32 v[86:87], v[86:87], 1.0 op_sel_hi:[1,0]


; DEV float silu_f(float x) { return x / (1.f + __expf(-x)); }
; DEV void gdn_prep_chunk(const Params& p, int item, unsigned char* lds) {
;     ...
;                 y[e] = silu_f(a); ss += y[e] * y[e];
	v_rcp_f32_e32 v68, v84
	s_nop 0
	v_mul_f32_e32 v66, v66, v68


; DEV float bflo(unsigned u) { return __uint_as_float(u << 16); }
; DEV float bfhi(unsigned u) { return __uint_as_float(u & 0xffff0000u); }
; DEV float silu_f(float x) { return x / (1.f + __expf(-x)); }
; DEV void gdn_prep_chunk(const Params& p, int item, unsigned char* lds) {
;     ...
;                     const float xv = (e & 1) ? bfhi(wd) : bflo(wd);
;                     a += w[j][e] * xv;
;                 }
;                 y[e] = silu_f(a); ss += y[e] * y[e];
	v_rcp_f32_e32 v68, v87
	s_nop 0
	v_mul_f32_e32 v83, v83, v68
	v_lshlrev_b32_e32 v88, 16, v69


; DEV float bflo(unsigned u) { return __uint_as_float(u << 16); }
; DEV float bfhi(unsigned u) { return __uint_as_float(u & 0xffff0000u); }
; DEV void gdn_prep_chunk(const Params& p, int item, unsigned char* lds) {
;     ...
;                 float a = 0.f;
; #pragma unroll
;                 for (int j = 0; j < 4; ++j) {
;                     const uint4 u = raw[r + j];
;                     const unsigned wd = (e < 2 ? u.x : (e < 4 ? u.y : (e < 6 ? u.z : u.w)));
;                     const float xv = (e & 1) ? bfhi(wd) : bflo(wd);
;                     a += w[j][e] * xv;
;                 }
	v_and_b32_e32 v89, 0xffff0000, v69
	v_pk_fma_f32 v[68:69], v[4:5], v[78:79], 0 op_sel_hi:[1,1,0]

; DEV float bflo(unsigned u) { return __uint_as_float(u << 16); }
; DEV float bfhi(unsigned u) { return __uint_as_float(u & 0xffff0000u); }
; DEV void gdn_prep_chunk(const Params& p, int item, unsigned char* lds) {
;     ...
;                 float a = 0.f;
; #pragma unroll
;                 for (int j = 0; j < 4; ++j) {
;                     const uint4 u = raw[r + j];
;                     const unsigned wd = (e < 2 ? u.x : (e < 4 ? u.y : (e < 6 ? u.z : u.w)));
;                     const float xv = (e & 1) ? bfhi(wd) : bflo(wd);
;                     a += w[j][e] * xv;
;                 }
	v_pk_fma_f32 v[68:69], v[8:9], v[74:75], v[68:69]

; DEV float bflo(unsigned u) { return __uint_as_float(u << 16); }
; DEV float bfhi(unsigned u) { return __uint_as_float(u & 0xffff0000u); }
; DEV void gdn_prep_chunk(const Params& p, int item, unsigned char* lds) {
;     ...
;                 float a = 0.f;
; #pragma unroll
;                 for (int j = 0; j < 4; ++j) {
;                     const uint4 u = raw[r + j];
;                     const unsigned wd = (e < 2 ? u.x : (e < 4 ? u.y : (e < 6 ? u.z : u.w)));
;                     const float xv = (e & 1) ? bfhi(wd) : bflo(wd);
;                     a += w[j][e] * xv;
;                 }
	v_pk_fma_f32 v[68:69], v[12:13], v[70:71], v[68:69]

; DEV float bflo(unsigned u) { return __uint_as_float(u << 16); }
; DEV float bfhi(unsigned u) { return __uint_as_float(u & 0xffff0000u); }
; DEV void gdn_prep_chunk(const Params& p, int item, unsigned char* lds) {
;     ...
;                 float a = 0.f;
; #pragma unroll
;                 for (int j = 0; j < 4; ++j) {
;                     const uint4 u = raw[r + j];
;                     const unsigned wd = (e < 2 ? u.x : (e < 4 ? u.y : (e < 6 ? u.z : u.w)));
;                     const float xv = (e & 1) ? bfhi(wd) : bflo(wd);
;                     a += w[j][e] * xv;
;                 }
	v_pk_fma_f32 v[68:69], v[16:17], v[88:89], v[68:69]

; DEV float silu_f(float x) { return x / (1.f + __expf(-x)); }
; DEV void gdn_prep_chunk(const Params& p, int item, unsigned char* lds) {
;     ...
;                 y[e] = silu_f(a); ss += y[e] * y[e];
	v_mul_f32_e32 v78, 0xbfb8aa3b, v68
	v_mul_f32_e32 v79, 0xbfb8aa3b, v69
	v_exp_f32_e32 v78, v78
	v_exp_f32_e32 v79, v79


; DEV float silu_f(float x) { return x / (1.f + __expf(-x)); }
; DEV void gdn_prep_chunk(const Params& p, int item, unsigned char* lds) {
;     ...
;                 y[e] = silu_f(a); ss += y[e] * y[e];
	v_rcp_f32_e32 v84, v86
	s_nop 0
	v_mul_f32_e32 v82, v82, v84
	v_pk_add_f32 v[78:79], v[78:79], 1.0 op_sel_hi:[1,0]
	s_nop 0


; DEV float silu_f(float x) { return x / (1.f + __expf(-x)); }
; DEV void gdn_prep_chunk(const Params& p, int item, unsigned char* lds) {
;     ...
;                 y[e] = silu_f(a); ss += y[e] * y[e];
	s_nop 0


; DEV float silu_f(float x) { return x / (1.f + __expf(-x)); }
; DEV void gdn_prep_chunk(const Params& p, int item, unsigned char* lds) {
;     ...
;                 y[e] = silu_f(a); ss += y[e] * y[e];
	v_rcp_f32_e32 v84, v79
	s_nop 0
	v_mul_f32_e32 v69, v69, v84


; DEV unsigned cvt_pk_bf16(float lo, float hi) { const f32x2_t v = {lo, hi}; const bf16x2_t b = __builtin_convertvector(v, bf16x2_t); return __builtin_bit_cast(unsigned, b); }
; DEV float silu_f(float x) { return x / (1.f + __expf(-x)); }
; DEV void gdn_prep_chunk(const Params& p, int item, unsigned char* lds) {
;     ...
;                 y[e] = silu_f(a); ss += y[e] * y[e];
;             }
;             if (mat < 2) {
;                 ss += __shfl_xor(ss, 1); ss += __shfl_xor(ss, 2); ss += __shfl_xor(ss, 4); ss += __shfl_xor(ss, 8);
;                 float inv = rsqrtf(ss + EPS); if (mat == 0) inv *= 0.08838834764831845f;
; #pragma unroll
;                 for (int e = 0; e < 8; ++e) y[e] *= inv;
;             }
;             uint4 o; o.x = cvt_pk_bf16(y[0], y[1]); o.y = cvt_pk_bf16(y[2], y[3]); o.z = cvt_pk_bf16(y[4], y[5]); o.w = cvt_pk_bf16(y[6], y[7]);
;             *(uint4*)(dst + (tl0 + r) * QS + cv * 8) = o;
;         }
	v_rcp_f32_e32 v79, v78
	s_nop 0
	v_mul_f32_e32 v68, v68, v79
	s_and_saveexec_b64 s[36:37], s[6:7]
	s_cbranch_execz .LBB0_488
	v_pk_mul_f32 v[78:79], v[102:103], v[102:103]
	v_pk_mul_f32 v[84:85], v[66:67], v[66:67]
	v_add_f32_e32 v78, v78, v79
	v_add_f32_e32 v78, v78, v84
	v_pk_mul_f32 v[86:87], v[82:83], v[82:83]
	v_add_f32_e32 v78, v85, v78
	v_and_b32_e32 v84, 64, v182
	v_add_f32_e32 v78, v86, v78
	v_xor_b32_e32 v79, 1, v182
	v_add_u32_e32 v84, 64, v84
	v_pk_mul_f32 v[106:107], v[68:69], v[68:69]
	v_add_f32_e32 v78, v87, v78
	v_cmp_lt_i32_e32 vcc, v79, v84
	v_add_f32_e32 v78, v106, v78
	v_add_f32_e32 v78, v107, v78
	v_cndmask_b32_e32 v79, v182, v79, vcc
	v_lshlrev_b32_e32 v79, 2, v79
	ds_bpermute_b32 v79, v79, v78
	s_waitcnt lgkmcnt(0)
	v_add_f32_e32 v78, v78, v79
	v_xor_b32_e32 v79, 2, v182
	v_cmp_lt_i32_e32 vcc, v79, v84
	s_nop 1
	v_cndmask_b32_e32 v79, v182, v79, vcc
	v_lshlrev_b32_e32 v79, 2, v79
	ds_bpermute_b32 v79, v79, v78
	s_waitcnt lgkmcnt(0)
	v_add_f32_e32 v78, v78, v79
	v_xor_b32_e32 v79, 4, v182
	v_cmp_lt_i32_e32 vcc, v79, v84
	s_nop 1
	v_cndmask_b32_e32 v79, v182, v79, vcc
	v_lshlrev_b32_e32 v79, 2, v79
	ds_bpermute_b32 v79, v79, v78
	s_waitcnt lgkmcnt(0)
	v_add_f32_e32 v78, v78, v79
	v_xor_b32_e32 v79, 8, v182
	v_cmp_lt_i32_e32 vcc, v79, v84
	s_nop 1
	v_cndmask_b32_e32 v79, v182, v79, vcc
	v_lshlrev_b32_e32 v79, 2, v79
	ds_bpermute_b32 v79, v79, v78
	s_waitcnt lgkmcnt(0)
	v_add_f32_e32 v78, v78, v79
	v_add_f32_e32 v78, 0x358637bd, v78
	v_mul_f32_e32 v79, 0x4b800000, v78
	v_cmp_gt_f32_e32 vcc, s56, v78
	s_nop 1
	v_cndmask_b32_e32 v78, v78, v79, vcc
	v_rsq_f32_e32 v78, v78
	s_nop 0
	v_mul_f32_e32 v79, 0x45800000, v78
	v_cndmask_b32_e32 v78, v78, v79, vcc
	v_mul_f32_e32 v79, 0x3db504f3, v78
	v_cndmask_b32_e64 v78, v78, v79, s[4:5]
	v_pk_mul_f32 v[102:103], v[102:103], v[78:79] op_sel_hi:[1,0]
	v_pk_mul_f32 v[66:67], v[66:67], v[78:79] op_sel_hi:[1,0]
	v_pk_mul_f32 v[82:83], v[82:83], v[78:79] op_sel_hi:[1,0]
	v_pk_mul_f32 v[68:69], v[68:69], v[78:79] op_sel_hi:[1,0]
.LBB0_488:
	s_or_b64 exec, exec, s[36:37]
	v_pk_fma_f32 v[78:79], v[18:19], v[80:81], 0 op_sel_hi:[1,1,0]
	s_waitcnt vmcnt(7)
	v_lshlrev_b32_e32 v86, 16, v62
	v_pk_fma_f32 v[78:79], v[22:23], v[76:77], v[78:79]
	v_and_b32_e32 v87, 0xffff0000, v62
	v_pk_fma_f32 v[78:79], v[26:27], v[72:73], v[78:79]
	v_and_b32_e32 v85, 0xffff0000, v63
	v_pk_fma_f32 v[106:107], v[30:31], v[86:87], v[78:79]
	v_cvt_pk_bf16_f32 v79, v66, v67
	v_mul_f32_e32 v62, 0xbfb8aa3b, v106
	v_exp_f32_e32 v80, v62
	v_mul_f32_e32 v62, 0xbfb8aa3b, v107
	v_exp_f32_e32 v81, v62
	v_cvt_pk_bf16_f32 v78, v102, v103
	v_pk_add_f32 v[66:67], v[80:81], 1.0 op_sel_hi:[1,0]
	s_nop 0


; DEV float silu_f(float x) { return x / (1.f + __expf(-x)); }
; DEV void gdn_prep_chunk(const Params& p, int item, unsigned char* lds) {
;     ...
;                 y[e] = silu_f(a); ss += y[e] * y[e];
;     ...
;             *(uint4*)(dst + (tl0 + r) * QS + cv * 8) = o;
	v_cvt_pk_bf16_f32 v81, v68, v69
	v_cvt_pk_bf16_f32 v80, v82, v83
	ds_write_b128 v104, v[78:81] offset:272


; DEV float silu_f(float x) { return x / (1.f + __expf(-x)); }
; DEV void gdn_prep_chunk(const Params& p, int item, unsigned char* lds) {
;     ...
;                 y[e] = silu_f(a); ss += y[e] * y[e];
	v_rcp_f32_e32 v62, v67
	s_nop 0
	v_mul_f32_e32 v67, v107, v62


; DEV float bflo(unsigned u) { return __uint_as_float(u << 16); }
; DEV float bfhi(unsigned u) { return __uint_as_float(u & 0xffff0000u); }
; DEV void gdn_prep_chunk(const Params& p, int item, unsigned char* lds) {
;     ...
;                 float a = 0.f;
; #pragma unroll
;                 for (int j = 0; j < 4; ++j) {
;                     const uint4 u = raw[r + j];
;                     const unsigned wd = (e < 2 ? u.x : (e < 4 ? u.y : (e < 6 ? u.z : u.w)));
;                     const float xv = (e & 1) ? bfhi(wd) : bflo(wd);
;                     a += w[j][e] * xv;
;                 }
	v_lshlrev_b32_e32 v84, 16, v63
	v_pk_fma_f32 v[62:63], v[20:21], v[94:95], 0 op_sel_hi:[1,1,0]

; DEV float bflo(unsigned u) { return __uint_as_float(u << 16); }
; DEV float bfhi(unsigned u) { return __uint_as_float(u & 0xffff0000u); }
; DEV void gdn_prep_chunk(const Params& p, int item, unsigned char* lds) {
;     ...
;                 float a = 0.f;
; #pragma unroll
;                 for (int j = 0; j < 4; ++j) {
;                     const uint4 u = raw[r + j];
;                     const unsigned wd = (e < 2 ? u.x : (e < 4 ? u.y : (e < 6 ? u.z : u.w)));
;                     const float xv = (e & 1) ? bfhi(wd) : bflo(wd);
;                     a += w[j][e] * xv;
;                 }
	v_pk_fma_f32 v[62:63], v[24:25], v[98:99], v[62:63]

; DEV float bflo(unsigned u) { return __uint_as_float(u << 16); }
; DEV float bfhi(unsigned u) { return __uint_as_float(u & 0xffff0000u); }
; DEV void gdn_prep_chunk(const Params& p, int item, unsigned char* lds) {
;     ...
;                 float a = 0.f;
; #pragma unroll
;                 for (int j = 0; j < 4; ++j) {
;                     const uint4 u = raw[r + j];
;                     const unsigned wd = (e < 2 ? u.x : (e < 4 ? u.y : (e < 6 ? u.z : u.w)));
;                     const float xv = (e & 1) ? bfhi(wd) : bflo(wd);
;                     a += w[j][e] * xv;
;                 }
	v_pk_fma_f32 v[62:63], v[28:29], v[100:101], v[62:63]

; DEV float bflo(unsigned u) { return __uint_as_float(u << 16); }
; DEV float bfhi(unsigned u) { return __uint_as_float(u & 0xffff0000u); }
; DEV void gdn_prep_chunk(const Params& p, int item, unsigned char* lds) {
;     ...
;                 float a = 0.f;
; #pragma unroll
;                 for (int j = 0; j < 4; ++j) {
;                     const uint4 u = raw[r + j];
;                     const unsigned wd = (e < 2 ? u.x : (e < 4 ? u.y : (e < 6 ? u.z : u.w)));
;                     const float xv = (e & 1) ? bfhi(wd) : bflo(wd);
;                     a += w[j][e] * xv;
;                 }
	v_pk_fma_f32 v[62:63], v[32:33], v[84:85], v[62:63]

; DEV float silu_f(float x) { return x / (1.f + __expf(-x)); }
; DEV void gdn_prep_chunk(const Params& p, int item, unsigned char* lds) {
;     ...
;                 y[e] = silu_f(a); ss += y[e] * y[e];
	v_mul_f32_e32 v68, 0xbfb8aa3b, v62
	v_mul_f32_e32 v69, 0xbfb8aa3b, v63
	v_exp_f32_e32 v68, v68
	v_exp_f32_e32 v69, v69


; DEV float silu_f(float x) { return x / (1.f + __expf(-x)); }
; DEV void gdn_prep_chunk(const Params& p, int item, unsigned char* lds) {
;     ...
;                 y[e] = silu_f(a); ss += y[e] * y[e];
	v_rcp_f32_e32 v78, v66
	s_nop 0
	v_mul_f32_e32 v66, v106, v78
	v_pk_add_f32 v[68:69], v[68:69], 1.0 op_sel_hi:[1,0]
	v_and_b32_e32 v83, 0xffff0000, v64


; DEV float bflo(unsigned u) { return __uint_as_float(u << 16); }
; DEV float bfhi(unsigned u) { return __uint_as_float(u & 0xffff0000u); }
; DEV float silu_f(float x) { return x / (1.f + __expf(-x)); }
; DEV void gdn_prep_chunk(const Params& p, int item, unsigned char* lds) {
;     ...
;                 for (int j = 0; j < 4; ++j) {
;                     const uint4 u = raw[r + j];
;                     const unsigned wd = (e < 2 ? u.x : (e < 4 ? u.y : (e < 6 ? u.z : u.w)));
;                     const float xv = (e & 1) ? bfhi(wd) : bflo(wd);
;                     a += w[j][e] * xv;
;     ...
;                 y[e] = silu_f(a); ss += y[e] * y[e];
	v_rcp_f32_e32 v78, v69
	s_nop 0
	v_mul_f32_e32 v63, v63, v78
	v_pk_fma_f32 v[78:79], v[2:3], v[90:91], 0 op_sel_hi:[1,1,0]
	v_lshlrev_b32_e32 v82, 16, v64
	v_pk_fma_f32 v[78:79], v[6:7], v[96:97], v[78:79]

; DEV float bflo(unsigned u) { return __uint_as_float(u << 16); }
; DEV float bfhi(unsigned u) { return __uint_as_float(u & 0xffff0000u); }
; DEV void gdn_prep_chunk(const Params& p, int item, unsigned char* lds) {
;     ...
;                 for (int j = 0; j < 4; ++j) {
;                     const uint4 u = raw[r + j];
;                     const unsigned wd = (e < 2 ? u.x : (e < 4 ? u.y : (e < 6 ? u.z : u.w)));
;                     const float xv = (e & 1) ? bfhi(wd) : bflo(wd);
;                     a += w[j][e] * xv;
	v_pk_fma_f32 v[78:79], v[10:11], v[92:93], v[78:79]

; DEV float bflo(unsigned u) { return __uint_as_float(u << 16); }
; DEV float bfhi(unsigned u) { return __uint_as_float(u & 0xffff0000u); }
; DEV void gdn_prep_chunk(const Params& p, int item, unsigned char* lds) {
;     ...
;                 for (int j = 0; j < 4; ++j) {
;                     const uint4 u = raw[r + j];
;                     const unsigned wd = (e < 2 ? u.x : (e < 4 ? u.y : (e < 6 ? u.z : u.w)));
;                     const float xv = (e & 1) ? bfhi(wd) : bflo(wd);
;                     a += w[j][e] * xv;
	v_pk_fma_f32 v[78:79], v[14:15], v[82:83], v[78:79]

; DEV float silu_f(float x) { return x / (1.f + __expf(-x)); }
; DEV void gdn_prep_chunk(const Params& p, int item, unsigned char* lds) {
;     ...
;                 y[e] = silu_f(a); ss += y[e] * y[e];
	v_mul_f32_e32 v64, 0xbfb8aa3b, v78
	v_exp_f32_e32 v80, v64
	v_mul_f32_e32 v64, 0xbfb8aa3b, v79
	v_exp_f32_e32 v81, v64


; DEV float silu_f(float x) { return x / (1.f + __expf(-x)); }
; DEV void gdn_prep_chunk(const Params& p, int item, unsigned char* lds) {
;     ...
;                 y[e] = silu_f(a); ss += y[e] * y[e];
	s_nop 0
	v_pk_add_f32 v[90:91], v[80:81], 1.0 op_sel_hi:[1,0]


; DEV float silu_f(float x) { return x / (1.f + __expf(-x)); }
; DEV void gdn_prep_chunk(const Params& p, int item, unsigned char* lds) {
;     ...
;                 y[e] = silu_f(a); ss += y[e] * y[e];
	v_rcp_f32_e32 v64, v68
	s_nop 0
	v_mul_f32_e32 v62, v62, v64


; DEV float silu_f(float x) { return x / (1.f + __expf(-x)); }
; DEV void gdn_prep_chunk(const Params& p, int item, unsigned char* lds) {
;     ...
;                 y[e] = silu_f(a); ss += y[e] * y[e];
	v_rcp_f32_e32 v64, v91
	s_nop 0
	v_mul_f32_e32 v69, v79, v64


; DEV float bflo(unsigned u) { return __uint_as_float(u << 16); }
; DEV float bfhi(unsigned u) { return __uint_as_float(u & 0xffff0000u); }
; DEV void gdn_prep_chunk(const Params& p, int item, unsigned char* lds) {
;     ...
;                 for (int j = 0; j < 4; ++j) {
;                     const uint4 u = raw[r + j];
;                     const unsigned wd = (e < 2 ? u.x : (e < 4 ? u.y : (e < 6 ? u.z : u.w)));
;                     const float xv = (e & 1) ? bfhi(wd) : bflo(wd);
;                     a += w[j][e] * xv;
	v_lshlrev_b32_e32 v80, 16, v65
	v_and_b32_e32 v81, 0xffff0000, v65
	v_pk_fma_f32 v[64:65], v[4:5], v[74:75], 0 op_sel_hi:[1,1,0]

; DEV float bflo(unsigned u) { return __uint_as_float(u << 16); }
; DEV float bfhi(unsigned u) { return __uint_as_float(u & 0xffff0000u); }
; DEV void gdn_prep_chunk(const Params& p, int item, unsigned char* lds) {
;     ...
;                 for (int j = 0; j < 4; ++j) {
;                     const uint4 u = raw[r + j];
;                     const unsigned wd = (e < 2 ? u.x : (e < 4 ? u.y : (e < 6 ? u.z : u.w)));
;                     const float xv = (e & 1) ? bfhi(wd) : bflo(wd);
;                     a += w[j][e] * xv;
	v_pk_fma_f32 v[64:65], v[8:9], v[70:71], v[64:65]

; DEV float bflo(unsigned u) { return __uint_as_float(u << 16); }
; DEV float bfhi(unsigned u) { return __uint_as_float(u & 0xffff0000u); }
; DEV void gdn_prep_chunk(const Params& p, int item, unsigned char* lds) {
;     ...
;                 for (int j = 0; j < 4; ++j) {
;                     const uint4 u = raw[r + j];
;                     const unsigned wd = (e < 2 ? u.x : (e < 4 ? u.y : (e < 6 ? u.z : u.w)));
;                     const float xv = (e & 1) ? bfhi(wd) : bflo(wd);
;                     a += w[j][e] * xv;
	v_pk_fma_f32 v[64:65], v[12:13], v[88:89], v[64:65]

; DEV float bflo(unsigned u) { return __uint_as_float(u << 16); }
; DEV float bfhi(unsigned u) { return __uint_as_float(u & 0xffff0000u); }
; DEV void gdn_prep_chunk(const Params& p, int item, unsigned char* lds) {
;     ...
;                 for (int j = 0; j < 4; ++j) {
;                     const uint4 u = raw[r + j];
;                     const unsigned wd = (e < 2 ? u.x : (e < 4 ? u.y : (e < 6 ? u.z : u.w)));
;                     const float xv = (e & 1) ? bfhi(wd) : bflo(wd);
;                     a += w[j][e] * xv;
	v_pk_fma_f32 v[64:65], v[16:17], v[80:81], v[64:65]

; DEV float silu_f(float x) { return x / (1.f + __expf(-x)); }
; DEV void gdn_prep_chunk(const Params& p, int item, unsigned char* lds) {
;     ...
;                 y[e] = silu_f(a); ss += y[e] * y[e];
	v_mul_f32_e32 v74, 0xbfb8aa3b, v64
	v_mul_f32_e32 v75, 0xbfb8aa3b, v65
	v_exp_f32_e32 v74, v74
	v_exp_f32_e32 v75, v75


; DEV float silu_f(float x) { return x / (1.f + __expf(-x)); }
; DEV void gdn_prep_chunk(const Params& p, int item, unsigned char* lds) {
;     ...
;                 y[e] = silu_f(a); ss += y[e] * y[e];
	v_rcp_f32_e32 v68, v90
	s_nop 0
	v_mul_f32_e32 v68, v78, v68
	v_pk_add_f32 v[74:75], v[74:75], 1.0 op_sel_hi:[1,0]
	s_nop 0


; DEV float silu_f(float x) { return x / (1.f + __expf(-x)); }
; DEV void gdn_prep_chunk(const Params& p, int item, unsigned char* lds) {
;     ...
;                 y[e] = silu_f(a); ss += y[e] * y[e];
	s_nop 0


; DEV float silu_f(float x) { return x / (1.f + __expf(-x)); }
; DEV void gdn_prep_chunk(const Params& p, int item, unsigned char* lds) {
;     ...
;                 y[e] = silu_f(a); ss += y[e] * y[e];
	v_rcp_f32_e32 v78, v75
	s_nop 0
	v_mul_f32_e32 v65, v65, v78


; DEV unsigned cvt_pk_bf16(float lo, float hi) { const f32x2_t v = {lo, hi}; const bf16x2_t b = __builtin_convertvector(v, bf16x2_t); return __builtin_bit_cast(unsigned, b); }
; DEV float bflo(unsigned u) { return __uint_as_float(u << 16); }
; DEV float bfhi(unsigned u) { return __uint_as_float(u & 0xffff0000u); }
; DEV float silu_f(float x) { return x / (1.f + __expf(-x)); }
; DEV void gdn_prep_chunk(const Params& p, int item, unsigned char* lds) {
;     ...
;             for (int e = 0; e < 8; ++e) {
;                 float a = 0.f;
; #pragma unroll
;                 for (int j = 0; j < 4; ++j) {
;                     const uint4 u = raw[r + j];
;                     const unsigned wd = (e < 2 ? u.x : (e < 4 ? u.y : (e < 6 ? u.z : u.w)));
;                     const float xv = (e & 1) ? bfhi(wd) : bflo(wd);
;                     a += w[j][e] * xv;
;     ...
;                 y[e] = silu_f(a); ss += y[e] * y[e];
;             }
;             if (mat < 2) {
;                 ss += __shfl_xor(ss, 1); ss += __shfl_xor(ss, 2); ss += __shfl_xor(ss, 4); ss += __shfl_xor(ss, 8);
;                 float inv = rsqrtf(ss + EPS); if (mat == 0) inv *= 0.08838834764831845f;
; #pragma unroll
;                 for (int e = 0; e < 8; ++e) y[e] *= inv;
;             }
;             uint4 o; o.x = cvt_pk_bf16(y[0], y[1]); o.y = cvt_pk_bf16(y[2], y[3]); o.z = cvt_pk_bf16(y[4], y[5]); o.w = cvt_pk_bf16(y[6], y[7]);
;             *(uint4*)(dst + (tl0 + r) * QS + cv * 8) = o;
	v_rcp_f32_e32 v75, v74
	s_nop 0
	v_mul_f32_e32 v64, v64, v75
	s_and_saveexec_b64 s[36:37], s[6:7]
	s_cbranch_execz .LBB0_490
	v_pk_mul_f32 v[74:75], v[66:67], v[66:67]
	v_pk_mul_f32 v[78:79], v[62:63], v[62:63]
	v_add_f32_e32 v74, v74, v75
	v_add_f32_e32 v74, v74, v78
	v_pk_mul_f32 v[90:91], v[68:69], v[68:69]
	v_add_f32_e32 v74, v79, v74
	v_and_b32_e32 v78, 64, v182
	v_add_f32_e32 v74, v90, v74
	v_xor_b32_e32 v75, 1, v182
	v_add_u32_e32 v78, 64, v78
	v_pk_mul_f32 v[94:95], v[64:65], v[64:65]
	v_add_f32_e32 v74, v91, v74
	v_cmp_lt_i32_e32 vcc, v75, v78
	v_add_f32_e32 v74, v94, v74
	v_add_f32_e32 v74, v95, v74
	v_cndmask_b32_e32 v75, v182, v75, vcc
	v_lshlrev_b32_e32 v75, 2, v75
	ds_bpermute_b32 v75, v75, v74
	s_waitcnt lgkmcnt(0)
	v_add_f32_e32 v74, v74, v75
	v_xor_b32_e32 v75, 2, v182
	v_cmp_lt_i32_e32 vcc, v75, v78
	s_nop 1
	v_cndmask_b32_e32 v75, v182, v75, vcc
	v_lshlrev_b32_e32 v75, 2, v75
	ds_bpermute_b32 v75, v75, v74
	s_waitcnt lgkmcnt(0)
	v_add_f32_e32 v74, v74, v75
	v_xor_b32_e32 v75, 4, v182
	v_cmp_lt_i32_e32 vcc, v75, v78
	s_nop 1
	v_cndmask_b32_e32 v75, v182, v75, vcc
	v_lshlrev_b32_e32 v75, 2, v75
	ds_bpermute_b32 v75, v75, v74
	s_waitcnt lgkmcnt(0)
	v_add_f32_e32 v74, v74, v75
	v_xor_b32_e32 v75, 8, v182
	v_cmp_lt_i32_e32 vcc, v75, v78
	s_nop 1
	v_cndmask_b32_e32 v75, v182, v75, vcc
	v_lshlrev_b32_e32 v75, 2, v75
	ds_bpermute_b32 v75, v75, v74
	s_waitcnt lgkmcnt(0)
	v_add_f32_e32 v74, v74, v75
	v_add_f32_e32 v74, 0x358637bd, v74
	v_mul_f32_e32 v75, 0x4b800000, v74
	v_cmp_gt_f32_e32 vcc, s56, v74
	s_nop 1
	v_cndmask_b32_e32 v74, v74, v75, vcc
	v_rsq_f32_e32 v74, v74
	s_nop 0
	v_mul_f32_e32 v75, 0x45800000, v74
	v_cndmask_b32_e32 v74, v74, v75, vcc
	v_mul_f32_e32 v75, 0x3db504f3, v74
	v_cndmask_b32_e64 v74, v74, v75, s[4:5]
	v_pk_mul_f32 v[66:67], v[66:67], v[74:75] op_sel_hi:[1,0]
	v_pk_mul_f32 v[62:63], v[62:63], v[74:75] op_sel_hi:[1,0]
	v_pk_mul_f32 v[68:69], v[68:69], v[74:75] op_sel_hi:[1,0]
	v_pk_mul_f32 v[64:65], v[64:65], v[74:75] op_sel_hi:[1,0]
.LBB0_490:
	s_or_b64 exec, exec, s[36:37]
	v_pk_fma_f32 v[74:75], v[18:19], v[76:77], 0 op_sel_hi:[1,1,0]
	s_waitcnt vmcnt(6)
	v_lshlrev_b32_e32 v78, 16, v58
	v_pk_fma_f32 v[74:75], v[22:23], v[72:73], v[74:75]
	v_and_b32_e32 v79, 0xffff0000, v58
	v_pk_fma_f32 v[74:75], v[26:27], v[86:87], v[74:75]
	v_cvt_pk_bf16_f32 v66, v66, v67
	v_pk_fma_f32 v[74:75], v[30:31], v[78:79], v[74:75]
	v_cvt_pk_bf16_f32 v67, v62, v63
	v_mul_f32_e32 v58, 0xbfb8aa3b, v74
	v_exp_f32_e32 v76, v58
	v_mul_f32_e32 v58, 0xbfb8aa3b, v75
	v_exp_f32_e32 v77, v58
	v_cvt_pk_bf16_f32 v68, v68, v69
	v_cvt_pk_bf16_f32 v69, v64, v65
	ds_write_b128 v104, v[66:69] offset:544
	v_pk_add_f32 v[62:63], v[76:77], 1.0 op_sel_hi:[1,0]
	v_and_b32_e32 v77, 0xffff0000, v59


; DEV float silu_f(float x) { return x / (1.f + __expf(-x)); }
; DEV void gdn_prep_chunk(const Params& p, int item, unsigned char* lds) {
;     ...
;                 y[e] = silu_f(a); ss += y[e] * y[e];
	s_nop 0


; DEV float silu_f(float x) { return x / (1.f + __expf(-x)); }
; DEV void gdn_prep_chunk(const Params& p, int item, unsigned char* lds) {
;     ...
;                 y[e] = silu_f(a); ss += y[e] * y[e];
	v_rcp_f32_e32 v58, v63
	s_nop 0
	v_mul_f32_e32 v63, v75, v58


; DEV float bflo(unsigned u) { return __uint_as_float(u << 16); }
; DEV float bfhi(unsigned u) { return __uint_as_float(u & 0xffff0000u); }
; DEV void gdn_prep_chunk(const Params& p, int item, unsigned char* lds) {
;     ...
;                 for (int j = 0; j < 4; ++j) {
;                     const uint4 u = raw[r + j];
;                     const unsigned wd = (e < 2 ? u.x : (e < 4 ? u.y : (e < 6 ? u.z : u.w)));
;                     const float xv = (e & 1) ? bfhi(wd) : bflo(wd);
;                     a += w[j][e] * xv;
	v_lshlrev_b32_e32 v76, 16, v59
	v_pk_fma_f32 v[58:59], v[20:21], v[98:99], 0 op_sel_hi:[1,1,0]

; DEV float bflo(unsigned u) { return __uint_as_float(u << 16); }
; DEV float bfhi(unsigned u) { return __uint_as_float(u & 0xffff0000u); }
; DEV void gdn_prep_chunk(const Params& p, int item, unsigned char* lds) {
;     ...
;                 for (int j = 0; j < 4; ++j) {
;                     const uint4 u = raw[r + j];
;                     const unsigned wd = (e < 2 ? u.x : (e < 4 ? u.y : (e < 6 ? u.z : u.w)));
;                     const float xv = (e & 1) ? bfhi(wd) : bflo(wd);
;                     a += w[j][e] * xv;
	v_pk_fma_f32 v[58:59], v[24:25], v[100:101], v[58:59]

; DEV float bflo(unsigned u) { return __uint_as_float(u << 16); }
; DEV float bfhi(unsigned u) { return __uint_as_float(u & 0xffff0000u); }
; DEV void gdn_prep_chunk(const Params& p, int item, unsigned char* lds) {
;     ...
;                 for (int j = 0; j < 4; ++j) {
;                     const uint4 u = raw[r + j];
;                     const unsigned wd = (e < 2 ? u.x : (e < 4 ? u.y : (e < 6 ? u.z : u.w)));
;                     const float xv = (e & 1) ? bfhi(wd) : bflo(wd);
;                     a += w[j][e] * xv;
	v_pk_fma_f32 v[58:59], v[28:29], v[84:85], v[58:59]

; DEV float bflo(unsigned u) { return __uint_as_float(u << 16); }
; DEV float bfhi(unsigned u) { return __uint_as_float(u & 0xffff0000u); }
; DEV void gdn_prep_chunk(const Params& p, int item, unsigned char* lds) {
;     ...
;                 for (int j = 0; j < 4; ++j) {
;                     const uint4 u = raw[r + j];
;                     const unsigned wd = (e < 2 ? u.x : (e < 4 ? u.y : (e < 6 ? u.z : u.w)));
;                     const float xv = (e & 1) ? bfhi(wd) : bflo(wd);
;                     a += w[j][e] * xv;
	v_pk_fma_f32 v[58:59], v[32:33], v[76:77], v[58:59]

; DEV float silu_f(float x) { return x / (1.f + __expf(-x)); }
; DEV void gdn_prep_chunk(const Params& p, int item, unsigned char* lds) {
;     ...
;                 y[e] = silu_f(a); ss += y[e] * y[e];
	v_mul_f32_e32 v64, 0xbfb8aa3b, v58
	v_mul_f32_e32 v65, 0xbfb8aa3b, v59
	v_exp_f32_e32 v64, v64
	v_exp_f32_e32 v65, v65


; DEV float silu_f(float x) { return x / (1.f + __expf(-x)); }
; DEV void gdn_prep_chunk(const Params& p, int item, unsigned char* lds) {
;     ...
;                 y[e] = silu_f(a); ss += y[e] * y[e];
	v_rcp_f32_e32 v66, v62
	s_nop 0
	v_mul_f32_e32 v62, v74, v66
	v_pk_add_f32 v[64:65], v[64:65], 1.0 op_sel_hi:[1,0]
	v_lshlrev_b32_e32 v74, 16, v60


; DEV float bflo(unsigned u) { return __uint_as_float(u << 16); }
; DEV float bfhi(unsigned u) { return __uint_as_float(u & 0xffff0000u); }
; DEV float silu_f(float x) { return x / (1.f + __expf(-x)); }
; DEV void gdn_prep_chunk(const Params& p, int item, unsigned char* lds) {
;     ...
;                 for (int j = 0; j < 4; ++j) {
;                     const uint4 u = raw[r + j];
;                     const unsigned wd = (e < 2 ? u.x : (e < 4 ? u.y : (e < 6 ? u.z : u.w)));
;                     const float xv = (e & 1) ? bfhi(wd) : bflo(wd);
;                     a += w[j][e] * xv;
;     ...
;                 y[e] = silu_f(a); ss += y[e] * y[e];
	v_rcp_f32_e32 v66, v65
	s_nop 0
	v_mul_f32_e32 v59, v59, v66
	v_pk_fma_f32 v[66:67], v[2:3], v[96:97], 0 op_sel_hi:[1,1,0]
	v_and_b32_e32 v75, 0xffff0000, v60
	v_pk_fma_f32 v[66:67], v[6:7], v[92:93], v[66:67]

; DEV float bflo(unsigned u) { return __uint_as_float(u << 16); }
; DEV float bfhi(unsigned u) { return __uint_as_float(u & 0xffff0000u); }
; DEV void gdn_prep_chunk(const Params& p, int item, unsigned char* lds) {
;     ...
;                 for (int j = 0; j < 4; ++j) {
;                     const uint4 u = raw[r + j];
;                     const unsigned wd = (e < 2 ? u.x : (e < 4 ? u.y : (e < 6 ? u.z : u.w)));
;                     const float xv = (e & 1) ? bfhi(wd) : bflo(wd);
;                     a += w[j][e] * xv;
	v_pk_fma_f32 v[66:67], v[10:11], v[82:83], v[66:67]

; DEV float bflo(unsigned u) { return __uint_as_float(u << 16); }
; DEV float bfhi(unsigned u) { return __uint_as_float(u & 0xffff0000u); }
; DEV void gdn_prep_chunk(const Params& p, int item, unsigned char* lds) {
;     ...
;                 for (int j = 0; j < 4; ++j) {
;                     const uint4 u = raw[r + j];
;                     const unsigned wd = (e < 2 ? u.x : (e < 4 ? u.y : (e < 6 ? u.z : u.w)));
;                     const float xv = (e & 1) ? bfhi(wd) : bflo(wd);
;                     a += w[j][e] * xv;
	v_pk_fma_f32 v[66:67], v[14:15], v[74:75], v[66:67]

; DEV float silu_f(float x) { return x / (1.f + __expf(-x)); }
; DEV void gdn_prep_chunk(const Params& p, int item, unsigned char* lds) {
;     ...
;                 y[e] = silu_f(a); ss += y[e] * y[e];
	v_mul_f32_e32 v60, 0xbfb8aa3b, v66
	v_exp_f32_e32 v68, v60
	v_mul_f32_e32 v60, 0xbfb8aa3b, v67
	v_exp_f32_e32 v69, v60


; DEV float silu_f(float x) { return x / (1.f + __expf(-x)); }
; DEV void gdn_prep_chunk(const Params& p, int item, unsigned char* lds) {
;     ...
;                 y[e] = silu_f(a); ss += y[e] * y[e];
	s_nop 0
	v_pk_add_f32 v[90:91], v[68:69], 1.0 op_sel_hi:[1,0]


; DEV float silu_f(float x) { return x / (1.f + __expf(-x)); }
; DEV void gdn_prep_chunk(const Params& p, int item, unsigned char* lds) {
;     ...
;                 y[e] = silu_f(a); ss += y[e] * y[e];
	v_rcp_f32_e32 v60, v64
	s_nop 0
	v_mul_f32_e32 v58, v58, v60


; DEV float silu_f(float x) { return x / (1.f + __expf(-x)); }
; DEV void gdn_prep_chunk(const Params& p, int item, unsigned char* lds) {
;     ...
;                 y[e] = silu_f(a); ss += y[e] * y[e];
	v_rcp_f32_e32 v60, v91
	s_nop 0
	v_mul_f32_e32 v65, v67, v60


; DEV float bflo(unsigned u) { return __uint_as_float(u << 16); }
; DEV float bfhi(unsigned u) { return __uint_as_float(u & 0xffff0000u); }
; DEV void gdn_prep_chunk(const Params& p, int item, unsigned char* lds) {
;     ...
;                 for (int j = 0; j < 4; ++j) {
;                     const uint4 u = raw[r + j];
;                     const unsigned wd = (e < 2 ? u.x : (e < 4 ? u.y : (e < 6 ? u.z : u.w)));
;                     const float xv = (e & 1) ? bfhi(wd) : bflo(wd);
;                     a += w[j][e] * xv;
	v_lshlrev_b32_e32 v68, 16, v61
	v_and_b32_e32 v69, 0xffff0000, v61
	v_pk_fma_f32 v[60:61], v[4:5], v[70:71], 0 op_sel_hi:[1,1,0]

; DEV float bflo(unsigned u) { return __uint_as_float(u << 16); }
; DEV float bfhi(unsigned u) { return __uint_as_float(u & 0xffff0000u); }
; DEV void gdn_prep_chunk(const Params& p, int item, unsigned char* lds) {
;     ...
;                 for (int j = 0; j < 4; ++j) {
;                     const uint4 u = raw[r + j];
;                     const unsigned wd = (e < 2 ? u.x : (e < 4 ? u.y : (e < 6 ? u.z : u.w)));
;                     const float xv = (e & 1) ? bfhi(wd) : bflo(wd);
;                     a += w[j][e] * xv;
	v_pk_fma_f32 v[60:61], v[8:9], v[88:89], v[60:61]

; DEV float bflo(unsigned u) { return __uint_as_float(u << 16); }
; DEV float bfhi(unsigned u) { return __uint_as_float(u & 0xffff0000u); }
; DEV void gdn_prep_chunk(const Params& p, int item, unsigned char* lds) {
;     ...
;                 for (int j = 0; j < 4; ++j) {
;                     const uint4 u = raw[r + j];
;                     const unsigned wd = (e < 2 ? u.x : (e < 4 ? u.y : (e < 6 ? u.z : u.w)));
;                     const float xv = (e & 1) ? bfhi(wd) : bflo(wd);
;                     a += w[j][e] * xv;
	v_pk_fma_f32 v[60:61], v[12:13], v[80:81], v[60:61]

; DEV float bflo(unsigned u) { return __uint_as_float(u << 16); }
; DEV float bfhi(unsigned u) { return __uint_as_float(u & 0xffff0000u); }
; DEV void gdn_prep_chunk(const Params& p, int item, unsigned char* lds) {
;     ...
;                 for (int j = 0; j < 4; ++j) {
;                     const uint4 u = raw[r + j];
;                     const unsigned wd = (e < 2 ? u.x : (e < 4 ? u.y : (e < 6 ? u.z : u.w)));
;                     const float xv = (e & 1) ? bfhi(wd) : bflo(wd);
;                     a += w[j][e] * xv;
	v_pk_fma_f32 v[60:61], v[16:17], v[68:69], v[60:61]

; DEV float silu_f(float x) { return x / (1.f + __expf(-x)); }
; DEV void gdn_prep_chunk(const Params& p, int item, unsigned char* lds) {
;     ...
;                 y[e] = silu_f(a); ss += y[e] * y[e];
	v_mul_f32_e32 v70, 0xbfb8aa3b, v60
	v_mul_f32_e32 v71, 0xbfb8aa3b, v61
	v_exp_f32_e32 v70, v70
	v_exp_f32_e32 v71, v71


; DEV float silu_f(float x) { return x / (1.f + __expf(-x)); }
; DEV void gdn_prep_chunk(const Params& p, int item, unsigned char* lds) {
;     ...
;                 y[e] = silu_f(a); ss += y[e] * y[e];
	v_rcp_f32_e32 v64, v90
	s_nop 0
	v_mul_f32_e32 v64, v66, v64
	v_pk_add_f32 v[70:71], v[70:71], 1.0 op_sel_hi:[1,0]
	s_nop 0


; DEV float silu_f(float x) { return x / (1.f + __expf(-x)); }
; DEV void gdn_prep_chunk(const Params& p, int item, unsigned char* lds) {
;     ...
;                 y[e] = silu_f(a); ss += y[e] * y[e];
	s_nop 0


; DEV float silu_f(float x) { return x / (1.f + __expf(-x)); }
; DEV void gdn_prep_chunk(const Params& p, int item, unsigned char* lds) {
;     ...
;                 y[e] = silu_f(a); ss += y[e] * y[e];
	v_rcp_f32_e32 v66, v71
	s_nop 0
	v_mul_f32_e32 v61, v61, v66


; DEV unsigned cvt_pk_bf16(float lo, float hi) { const f32x2_t v = {lo, hi}; const bf16x2_t b = __builtin_convertvector(v, bf16x2_t); return __builtin_bit_cast(unsigned, b); }
; DEV float bflo(unsigned u) { return __uint_as_float(u << 16); }
; DEV float bfhi(unsigned u) { return __uint_as_float(u & 0xffff0000u); }
; DEV float silu_f(float x) { return x / (1.f + __expf(-x)); }
; DEV void gdn_prep_chunk(const Params& p, int item, unsigned char* lds) {
;     ...
;             for (int e = 0; e < 8; ++e) {
;                 float a = 0.f;
; #pragma unroll
;                 for (int j = 0; j < 4; ++j) {
;                     const uint4 u = raw[r + j];
;                     const unsigned wd = (e < 2 ? u.x : (e < 4 ? u.y : (e < 6 ? u.z : u.w)));
;                     const float xv = (e & 1) ? bfhi(wd) : bflo(wd);
;                     a += w[j][e] * xv;
;     ...
;                 y[e] = silu_f(a); ss += y[e] * y[e];
;             }
;             if (mat < 2) {
;                 ss += __shfl_xor(ss, 1); ss += __shfl_xor(ss, 2); ss += __shfl_xor(ss, 4); ss += __shfl_xor(ss, 8);
;                 float inv = rsqrtf(ss + EPS); if (mat == 0) inv *= 0.08838834764831845f;
; #pragma unroll
;                 for (int e = 0; e < 8; ++e) y[e] *= inv;
;             }
;             uint4 o; o.x = cvt_pk_bf16(y[0], y[1]); o.y = cvt_pk_bf16(y[2], y[3]); o.z = cvt_pk_bf16(y[4], y[5]); o.w = cvt_pk_bf16(y[6], y[7]);
;             *(uint4*)(dst + (tl0 + r) * QS + cv * 8) = o;
	v_rcp_f32_e32 v66, v70
	s_nop 0
	v_mul_f32_e32 v60, v60, v66
	s_and_saveexec_b64 s[36:37], s[6:7]
	s_cbranch_execz .LBB0_492
	v_pk_mul_f32 v[66:67], v[62:63], v[62:63]
	v_pk_mul_f32 v[70:71], v[58:59], v[58:59]
	v_add_f32_e32 v66, v66, v67
	v_add_f32_e32 v66, v66, v70
	v_pk_mul_f32 v[90:91], v[64:65], v[64:65]
	v_add_f32_e32 v66, v71, v66
	v_and_b32_e32 v70, 64, v182
	v_add_f32_e32 v66, v90, v66
	v_xor_b32_e32 v67, 1, v182
	v_add_u32_e32 v70, 64, v70
	v_pk_mul_f32 v[94:95], v[60:61], v[60:61]
	v_add_f32_e32 v66, v91, v66
	v_cmp_lt_i32_e32 vcc, v67, v70
	v_add_f32_e32 v66, v94, v66
	v_add_f32_e32 v66, v95, v66
	v_cndmask_b32_e32 v67, v182, v67, vcc
	v_lshlrev_b32_e32 v67, 2, v67
	ds_bpermute_b32 v67, v67, v66
	s_waitcnt lgkmcnt(0)
	v_add_f32_e32 v66, v66, v67
	v_xor_b32_e32 v67, 2, v182
	v_cmp_lt_i32_e32 vcc, v67, v70
	s_nop 1
	v_cndmask_b32_e32 v67, v182, v67, vcc
	v_lshlrev_b32_e32 v67, 2, v67
	ds_bpermute_b32 v67, v67, v66
	s_waitcnt lgkmcnt(0)
	v_add_f32_e32 v66, v66, v67
	v_xor_b32_e32 v67, 4, v182
	v_cmp_lt_i32_e32 vcc, v67, v70
	s_nop 1
	v_cndmask_b32_e32 v67, v182, v67, vcc
	v_lshlrev_b32_e32 v67, 2, v67
	ds_bpermute_b32 v67, v67, v66
	s_waitcnt lgkmcnt(0)
	v_add_f32_e32 v66, v66, v67
	v_xor_b32_e32 v67, 8, v182
	v_cmp_lt_i32_e32 vcc, v67, v70
	s_nop 1
	v_cndmask_b32_e32 v67, v182, v67, vcc
	v_lshlrev_b32_e32 v67, 2, v67
	ds_bpermute_b32 v67, v67, v66
	s_waitcnt lgkmcnt(0)
	v_add_f32_e32 v66, v66, v67
	v_add_f32_e32 v66, 0x358637bd, v66
	v_mul_f32_e32 v67, 0x4b800000, v66
	v_cmp_gt_f32_e32 vcc, s56, v66
	s_nop 1
	v_cndmask_b32_e32 v66, v66, v67, vcc
	v_rsq_f32_e32 v66, v66
	s_nop 0
	v_mul_f32_e32 v67, 0x45800000, v66
	v_cndmask_b32_e32 v66, v66, v67, vcc
	v_mul_f32_e32 v67, 0x3db504f3, v66
	v_cndmask_b32_e64 v66, v66, v67, s[4:5]
	v_pk_mul_f32 v[62:63], v[62:63], v[66:67] op_sel_hi:[1,0]
	v_pk_mul_f32 v[58:59], v[58:59], v[66:67] op_sel_hi:[1,0]
	v_pk_mul_f32 v[64:65], v[64:65], v[66:67] op_sel_hi:[1,0]
	v_pk_mul_f32 v[60:61], v[60:61], v[66:67] op_sel_hi:[1,0]
.LBB0_492:
	s_or_b64 exec, exec, s[36:37]
	v_pk_fma_f32 v[70:71], v[18:19], v[72:73], 0 op_sel_hi:[1,1,0]
	s_waitcnt vmcnt(5)
	v_lshlrev_b32_e32 v66, 16, v54
	v_pk_fma_f32 v[70:71], v[22:23], v[86:87], v[70:71]
	v_and_b32_e32 v67, 0xffff0000, v54
	v_pk_fma_f32 v[70:71], v[26:27], v[78:79], v[70:71]
	v_cvt_pk_bf16_f32 v62, v62, v63
	v_pk_fma_f32 v[70:71], v[30:31], v[66:67], v[70:71]
	v_cvt_pk_bf16_f32 v63, v58, v59
	v_mul_f32_e32 v54, 0xbfb8aa3b, v70
	v_exp_f32_e32 v72, v54
	v_mul_f32_e32 v54, 0xbfb8aa3b, v71
	v_exp_f32_e32 v73, v54
	v_cvt_pk_bf16_f32 v64, v64, v65
	v_cvt_pk_bf16_f32 v65, v60, v61
	ds_write_b128 v104, v[62:65] offset:816
	v_pk_add_f32 v[58:59], v[72:73], 1.0 op_sel_hi:[1,0]
	v_lshlrev_b32_e32 v64, 16, v55


; DEV float bflo(unsigned u) { return __uint_as_float(u << 16); }
; DEV float bfhi(unsigned u) { return __uint_as_float(u & 0xffff0000u); }
; DEV float silu_f(float x) { return x / (1.f + __expf(-x)); }
; DEV void gdn_prep_chunk(const Params& p, int item, unsigned char* lds) {
;     ...
;                     const float xv = (e & 1) ? bfhi(wd) : bflo(wd);
;     ...
;                 y[e] = silu_f(a); ss += y[e] * y[e];
	v_and_b32_e32 v65, 0xffff0000, v55


; DEV float silu_f(float x) { return x / (1.f + __expf(-x)); }
; DEV void gdn_prep_chunk(const Params& p, int item, unsigned char* lds) {
;     ...
;                 y[e] = silu_f(a); ss += y[e] * y[e];
	v_rcp_f32_e32 v54, v59
	s_nop 0
	v_mul_f32_e32 v71, v71, v54


; DEV float bflo(unsigned u) { return __uint_as_float(u << 16); }
; DEV float bfhi(unsigned u) { return __uint_as_float(u & 0xffff0000u); }
; DEV void gdn_prep_chunk(const Params& p, int item, unsigned char* lds) {
;     ...
;                 for (int j = 0; j < 4; ++j) {
;                     const uint4 u = raw[r + j];
;                     const unsigned wd = (e < 2 ? u.x : (e < 4 ? u.y : (e < 6 ? u.z : u.w)));
;                     const float xv = (e & 1) ? bfhi(wd) : bflo(wd);
;                     a += w[j][e] * xv;
	v_pk_fma_f32 v[54:55], v[20:21], v[100:101], 0 op_sel_hi:[1,1,0]

; DEV float bflo(unsigned u) { return __uint_as_float(u << 16); }
; DEV float bfhi(unsigned u) { return __uint_as_float(u & 0xffff0000u); }
; DEV void gdn_prep_chunk(const Params& p, int item, unsigned char* lds) {
;     ...
;                 for (int j = 0; j < 4; ++j) {
;                     const uint4 u = raw[r + j];
;                     const unsigned wd = (e < 2 ? u.x : (e < 4 ? u.y : (e < 6 ? u.z : u.w)));
;                     const float xv = (e & 1) ? bfhi(wd) : bflo(wd);
;                     a += w[j][e] * xv;
	v_pk_fma_f32 v[54:55], v[24:25], v[84:85], v[54:55]

; DEV float bflo(unsigned u) { return __uint_as_float(u << 16); }
; DEV float bfhi(unsigned u) { return __uint_as_float(u & 0xffff0000u); }
; DEV void gdn_prep_chunk(const Params& p, int item, unsigned char* lds) {
;     ...
;                 for (int j = 0; j < 4; ++j) {
;                     const uint4 u = raw[r + j];
;                     const unsigned wd = (e < 2 ? u.x : (e < 4 ? u.y : (e < 6 ? u.z : u.w)));
;                     const float xv = (e & 1) ? bfhi(wd) : bflo(wd);
;                     a += w[j][e] * xv;
	v_pk_fma_f32 v[54:55], v[28:29], v[76:77], v[54:55]

; DEV float bflo(unsigned u) { return __uint_as_float(u << 16); }
; DEV float bfhi(unsigned u) { return __uint_as_float(u & 0xffff0000u); }
; DEV void gdn_prep_chunk(const Params& p, int item, unsigned char* lds) {
;     ...
;                 for (int j = 0; j < 4; ++j) {
;                     const uint4 u = raw[r + j];
;                     const unsigned wd = (e < 2 ? u.x : (e < 4 ? u.y : (e < 6 ? u.z : u.w)));
;                     const float xv = (e & 1) ? bfhi(wd) : bflo(wd);
;                     a += w[j][e] * xv;
	v_pk_fma_f32 v[54:55], v[32:33], v[64:65], v[54:55]

; DEV float silu_f(float x) { return x / (1.f + __expf(-x)); }
; DEV void gdn_prep_chunk(const Params& p, int item, unsigned char* lds) {
;     ...
;                 y[e] = silu_f(a); ss += y[e] * y[e];
	v_mul_f32_e32 v60, 0xbfb8aa3b, v54
	v_mul_f32_e32 v61, 0xbfb8aa3b, v55
	v_exp_f32_e32 v60, v60
	v_exp_f32_e32 v61, v61


; DEV float silu_f(float x) { return x / (1.f + __expf(-x)); }
; DEV void gdn_prep_chunk(const Params& p, int item, unsigned char* lds) {
;     ...
;                 y[e] = silu_f(a); ss += y[e] * y[e];
	v_rcp_f32_e32 v59, v58
	s_nop 0
	v_mul_f32_e32 v70, v70, v59
	v_pk_add_f32 v[60:61], v[60:61], 1.0 op_sel_hi:[1,0]
	s_nop 0


; DEV float silu_f(float x) { return x / (1.f + __expf(-x)); }
; DEV void gdn_prep_chunk(const Params& p, int item, unsigned char* lds) {
;     ...
;                 y[e] = silu_f(a); ss += y[e] * y[e];
	v_rcp_f32_e32 v58, v61
	s_nop 0
	v_mul_f32_e32 v55, v55, v58


; DEV float bflo(unsigned u) { return __uint_as_float(u << 16); }
; DEV float bfhi(unsigned u) { return __uint_as_float(u & 0xffff0000u); }
; DEV void gdn_prep_chunk(const Params& p, int item, unsigned char* lds) {
;     ...
;                 for (int j = 0; j < 4; ++j) {
;                     const uint4 u = raw[r + j];
;                     const unsigned wd = (e < 2 ? u.x : (e < 4 ? u.y : (e < 6 ? u.z : u.w)));
;                     const float xv = (e & 1) ? bfhi(wd) : bflo(wd);
;                     a += w[j][e] * xv;
	v_pk_fma_f32 v[58:59], v[2:3], v[92:93], 0 op_sel_hi:[1,1,0]
	v_lshlrev_b32_e32 v62, 16, v56
	v_pk_fma_f32 v[58:59], v[6:7], v[82:83], v[58:59]
	v_and_b32_e32 v63, 0xffff0000, v56
	v_pk_fma_f32 v[58:59], v[10:11], v[74:75], v[58:59]

; DEV float bflo(unsigned u) { return __uint_as_float(u << 16); }
; DEV float bfhi(unsigned u) { return __uint_as_float(u & 0xffff0000u); }
; DEV void gdn_prep_chunk(const Params& p, int item, unsigned char* lds) {
;     ...
;                 for (int j = 0; j < 4; ++j) {
;                     const uint4 u = raw[r + j];
;                     const unsigned wd = (e < 2 ? u.x : (e < 4 ? u.y : (e < 6 ? u.z : u.w)));
;                     const float xv = (e & 1) ? bfhi(wd) : bflo(wd);
;                     a += w[j][e] * xv;
	v_pk_fma_f32 v[58:59], v[14:15], v[62:63], v[58:59]

; DEV float silu_f(float x) { return x / (1.f + __expf(-x)); }
; DEV void gdn_prep_chunk(const Params& p, int item, unsigned char* lds) {
;     ...
;                 y[e] = silu_f(a); ss += y[e] * y[e];
	v_mul_f32_e32 v56, 0xbfb8aa3b, v58
	v_exp_f32_e32 v72, v56
	v_mul_f32_e32 v56, 0xbfb8aa3b, v59
	v_exp_f32_e32 v73, v56


; DEV float silu_f(float x) { return x / (1.f + __expf(-x)); }
; DEV void gdn_prep_chunk(const Params& p, int item, unsigned char* lds) {
;     ...
;                 y[e] = silu_f(a); ss += y[e] * y[e];
	s_nop 0
	v_pk_add_f32 v[72:73], v[72:73], 1.0 op_sel_hi:[1,0]


; DEV float silu_f(float x) { return x / (1.f + __expf(-x)); }
; DEV void gdn_prep_chunk(const Params& p, int item, unsigned char* lds) {
;     ...
;                 y[e] = silu_f(a); ss += y[e] * y[e];
	v_rcp_f32_e32 v56, v60
	s_nop 0
	v_mul_f32_e32 v54, v54, v56


; DEV float silu_f(float x) { return x / (1.f + __expf(-x)); }
; DEV void gdn_prep_chunk(const Params& p, int item, unsigned char* lds) {
;     ...
;                 y[e] = silu_f(a); ss += y[e] * y[e];
	v_rcp_f32_e32 v56, v73
	s_nop 0
	v_mul_f32_e32 v73, v59, v56


; DEV float bflo(unsigned u) { return __uint_as_float(u << 16); }
; DEV float bfhi(unsigned u) { return __uint_as_float(u & 0xffff0000u); }
; DEV void gdn_prep_chunk(const Params& p, int item, unsigned char* lds) {
;     ...
;                 for (int j = 0; j < 4; ++j) {
;                     const uint4 u = raw[r + j];
;                     const unsigned wd = (e < 2 ? u.x : (e < 4 ? u.y : (e < 6 ? u.z : u.w)));
;                     const float xv = (e & 1) ? bfhi(wd) : bflo(wd);
;                     a += w[j][e] * xv;
	v_lshlrev_b32_e32 v60, 16, v57
	v_and_b32_e32 v61, 0xffff0000, v57
	v_pk_fma_f32 v[56:57], v[4:5], v[88:89], 0 op_sel_hi:[1,1,0]

; DEV float bflo(unsigned u) { return __uint_as_float(u << 16); }
; DEV float bfhi(unsigned u) { return __uint_as_float(u & 0xffff0000u); }
; DEV void gdn_prep_chunk(const Params& p, int item, unsigned char* lds) {
;     ...
;                 for (int j = 0; j < 4; ++j) {
;                     const uint4 u = raw[r + j];
;                     const unsigned wd = (e < 2 ? u.x : (e < 4 ? u.y : (e < 6 ? u.z : u.w)));
;                     const float xv = (e & 1) ? bfhi(wd) : bflo(wd);
;                     a += w[j][e] * xv;
	v_pk_fma_f32 v[56:57], v[8:9], v[80:81], v[56:57]

; DEV float bflo(unsigned u) { return __uint_as_float(u << 16); }
; DEV float bfhi(unsigned u) { return __uint_as_float(u & 0xffff0000u); }
; DEV void gdn_prep_chunk(const Params& p, int item, unsigned char* lds) {
;     ...
;                 for (int j = 0; j < 4; ++j) {
;                     const uint4 u = raw[r + j];
;                     const unsigned wd = (e < 2 ? u.x : (e < 4 ? u.y : (e < 6 ? u.z : u.w)));
;                     const float xv = (e & 1) ? bfhi(wd) : bflo(wd);
;                     a += w[j][e] * xv;
	v_pk_fma_f32 v[56:57], v[12:13], v[68:69], v[56:57]

; DEV float bflo(unsigned u) { return __uint_as_float(u << 16); }
; DEV float bfhi(unsigned u) { return __uint_as_float(u & 0xffff0000u); }
; DEV void gdn_prep_chunk(const Params& p, int item, unsigned char* lds) {
;     ...
;                 for (int j = 0; j < 4; ++j) {
;                     const uint4 u = raw[r + j];
;                     const unsigned wd = (e < 2 ? u.x : (e < 4 ? u.y : (e < 6 ? u.z : u.w)));
;                     const float xv = (e & 1) ? bfhi(wd) : bflo(wd);
;                     a += w[j][e] * xv;
	v_pk_fma_f32 v[56:57], v[16:17], v[60:61], v[56:57]

; DEV float silu_f(float x) { return x / (1.f + __expf(-x)); }
; DEV void gdn_prep_chunk(const Params& p, int item, unsigned char* lds) {
;     ...
;                 y[e] = silu_f(a); ss += y[e] * y[e];
	v_mul_f32_e32 v88, 0xbfb8aa3b, v56
	v_mul_f32_e32 v89, 0xbfb8aa3b, v57
	v_exp_f32_e32 v88, v88
	v_exp_f32_e32 v89, v89


; DEV float silu_f(float x) { return x / (1.f + __expf(-x)); }
	v_rcp_f32_e32 v59, v72
	s_nop 0
	v_mul_f32_e32 v72, v58, v59
	v_pk_add_f32 v[88:89], v[88:89], 1.0 op_sel_hi:[1,0]
	s_nop 0


; DEV float silu_f(float x) { return x / (1.f + __expf(-x)); }
	s_nop 0


; DEV float silu_f(float x) { return x / (1.f + __expf(-x)); }
	v_rcp_f32_e32 v58, v89
	s_nop 0
	v_mul_f32_e32 v57, v57, v58


; DEV unsigned cvt_pk_bf16(float lo, float hi) { const f32x2_t v = {lo, hi}; const bf16x2_t b = __builtin_convertvector(v, bf16x2_t); return __builtin_bit_cast(unsigned, b); }
; DEV float bflo(unsigned u) { return __uint_as_float(u << 16); }
; DEV float bfhi(unsigned u) { return __uint_as_float(u & 0xffff0000u); }
; DEV float silu_f(float x) { return x / (1.f + __expf(-x)); }
; DEV void gdn_prep_chunk(const Params& p, int item, unsigned char* lds) {
;     ...
;         for (int r = 0; r < 16; ++r) {
;             float y[8]; float ss = 0.f;
; #pragma unroll
;             for (int e = 0; e < 8; ++e) {
;                 float a = 0.f;
; #pragma unroll
;                 for (int j = 0; j < 4; ++j) {
;                     const uint4 u = raw[r + j];
;                     const unsigned wd = (e < 2 ? u.x : (e < 4 ? u.y : (e < 6 ? u.z : u.w)));
;                     const float xv = (e & 1) ? bfhi(wd) : bflo(wd);
;                     a += w[j][e] * xv;
;                 }
;                 y[e] = silu_f(a); ss += y[e] * y[e];
;             }
;             if (mat < 2) {
;                 ss += __shfl_xor(ss, 1); ss += __shfl_xor(ss, 2); ss += __shfl_xor(ss, 4); ss += __shfl_xor(ss, 8);
;                 float inv = rsqrtf(ss + EPS); if (mat == 0) inv *= 0.08838834764831845f;
; #pragma unroll
;                 for (int e = 0; e < 8; ++e) y[e] *= inv;
;             }
;             uint4 o; o.x = cvt_pk_bf16(y[0], y[1]); o.y = cvt_pk_bf16(y[2], y[3]); o.z = cvt_pk_bf16(y[4], y[5]); o.w = cvt_pk_bf16(y[6], y[7]);
;             *(uint4*)(dst + (tl0 + r) * QS + cv * 8) = o;
	v_rcp_f32_e32 v58, v88
	s_nop 0
	v_mul_f32_e32 v56, v56, v58
	s_and_saveexec_b64 s[36:37], s[6:7]
	s_cbranch_execz .LBB0_494
	v_pk_mul_f32 v[58:59], v[70:71], v[70:71]
	v_pk_mul_f32 v[88:89], v[54:55], v[54:55]
	v_add_f32_e32 v58, v58, v59
	v_add_f32_e32 v58, v58, v88
	v_pk_mul_f32 v[90:91], v[72:73], v[72:73]
	v_add_f32_e32 v58, v89, v58
	v_and_b32_e32 v88, 64, v182
	v_add_f32_e32 v58, v90, v58
	v_xor_b32_e32 v59, 1, v182
	v_add_u32_e32 v88, 64, v88
	v_pk_mul_f32 v[92:93], v[56:57], v[56:57]
	v_add_f32_e32 v58, v91, v58
	v_cmp_lt_i32_e32 vcc, v59, v88
	v_add_f32_e32 v58, v92, v58
	v_add_f32_e32 v58, v93, v58
	v_cndmask_b32_e32 v59, v182, v59, vcc
	v_lshlrev_b32_e32 v59, 2, v59
	ds_bpermute_b32 v59, v59, v58
	s_waitcnt lgkmcnt(0)
	v_add_f32_e32 v58, v58, v59
	v_xor_b32_e32 v59, 2, v182
	v_cmp_lt_i32_e32 vcc, v59, v88
	s_nop 1
	v_cndmask_b32_e32 v59, v182, v59, vcc
	v_lshlrev_b32_e32 v59, 2, v59
	ds_bpermute_b32 v59, v59, v58
	s_waitcnt lgkmcnt(0)
	v_add_f32_e32 v58, v58, v59
	v_xor_b32_e32 v59, 4, v182
	v_cmp_lt_i32_e32 vcc, v59, v88
	s_nop 1
	v_cndmask_b32_e32 v59, v182, v59, vcc
	v_lshlrev_b32_e32 v59, 2, v59
	ds_bpermute_b32 v59, v59, v58
	s_waitcnt lgkmcnt(0)
	v_add_f32_e32 v58, v58, v59
	v_xor_b32_e32 v59, 8, v182
	v_cmp_lt_i32_e32 vcc, v59, v88
	s_nop 1
	v_cndmask_b32_e32 v59, v182, v59, vcc
	v_lshlrev_b32_e32 v59, 2, v59
	ds_bpermute_b32 v59, v59, v58
	s_waitcnt lgkmcnt(0)
	v_add_f32_e32 v58, v58, v59
	v_add_f32_e32 v58, 0x358637bd, v58
	v_mul_f32_e32 v59, 0x4b800000, v58
	v_cmp_gt_f32_e32 vcc, s56, v58
	s_nop 1
	v_cndmask_b32_e32 v58, v58, v59, vcc
	v_rsq_f32_e32 v58, v58
	s_nop 0
	v_mul_f32_e32 v59, 0x45800000, v58
	v_cndmask_b32_e32 v58, v58, v59, vcc
	v_mul_f32_e32 v59, 0x3db504f3, v58
	v_cndmask_b32_e64 v58, v58, v59, s[4:5]
	v_pk_mul_f32 v[70:71], v[70:71], v[58:59] op_sel_hi:[1,0]
	v_pk_mul_f32 v[54:55], v[54:55], v[58:59] op_sel_hi:[1,0]
	v_pk_mul_f32 v[72:73], v[72:73], v[58:59] op_sel_hi:[1,0]
	v_pk_mul_f32 v[56:57], v[56:57], v[58:59] op_sel_hi:[1,0]
.LBB0_494:
	s_or_b64 exec, exec, s[36:37]
	v_pk_fma_f32 v[86:87], v[18:19], v[86:87], 0 op_sel_hi:[1,1,0]
	s_waitcnt vmcnt(4)
	v_lshlrev_b32_e32 v58, 16, v50
	v_pk_fma_f32 v[86:87], v[22:23], v[78:79], v[86:87]
	v_and_b32_e32 v59, 0xffff0000, v50
	v_pk_fma_f32 v[86:87], v[26:27], v[66:67], v[86:87]
	v_cvt_pk_bf16_f32 v70, v70, v71
	v_pk_fma_f32 v[86:87], v[30:31], v[58:59], v[86:87]
	v_cvt_pk_bf16_f32 v71, v54, v55
	v_mul_f32_e32 v50, 0xbfb8aa3b, v86
	v_exp_f32_e32 v88, v50
	v_mul_f32_e32 v50, 0xbfb8aa3b, v87
	v_exp_f32_e32 v89, v50
	v_cvt_pk_bf16_f32 v72, v72, v73
	v_cvt_pk_bf16_f32 v73, v56, v57
	ds_write_b128 v104, v[70:73] offset:1088
	v_pk_add_f32 v[54:55], v[88:89], 1.0 op_sel_hi:[1,0]
	v_pk_fma_f32 v[82:83], v[2:3], v[82:83], 0 op_sel_hi:[1,1,0]


; DEV float silu_f(float x) { return x / (1.f + __expf(-x)); }
	v_pk_fma_f32 v[82:83], v[6:7], v[74:75], v[82:83]


; DEV float silu_f(float x) { return x / (1.f + __expf(-x)); }
	v_rcp_f32_e32 v50, v55
	s_nop 0
	v_mul_f32_e32 v71, v87, v50


; DEV float bflo(unsigned u) { return __uint_as_float(u << 16); }
; DEV float bfhi(unsigned u) { return __uint_as_float(u & 0xffff0000u); }
; DEV void gdn_prep_chunk(const Params& p, int item, unsigned char* lds) {
;     ...
;         for (int r = 0; r < 16; ++r) {
;             float y[8]; float ss = 0.f;
; #pragma unroll
;             for (int e = 0; e < 8; ++e) {
;                 float a = 0.f;
; #pragma unroll
;                 for (int j = 0; j < 4; ++j) {
;                     const uint4 u = raw[r + j];
;                     const unsigned wd = (e < 2 ? u.x : (e < 4 ? u.y : (e < 6 ? u.z : u.w)));
;                     const float xv = (e & 1) ? bfhi(wd) : bflo(wd);
;                     a += w[j][e] * xv;
;                 }
	v_lshlrev_b32_e32 v56, 16, v51
	v_and_b32_e32 v57, 0xffff0000, v51
	v_pk_fma_f32 v[50:51], v[20:21], v[84:85], 0 op_sel_hi:[1,1,0]

; DEV float bflo(unsigned u) { return __uint_as_float(u << 16); }
; DEV float bfhi(unsigned u) { return __uint_as_float(u & 0xffff0000u); }
; DEV void gdn_prep_chunk(const Params& p, int item, unsigned char* lds) {
;     ...
;                 for (int j = 0; j < 4; ++j) {
;                     const uint4 u = raw[r + j];
;                     const unsigned wd = (e < 2 ? u.x : (e < 4 ? u.y : (e < 6 ? u.z : u.w)));
;                     const float xv = (e & 1) ? bfhi(wd) : bflo(wd);
;                     a += w[j][e] * xv;
;                 }
	v_pk_fma_f32 v[50:51], v[24:25], v[76:77], v[50:51]

; DEV float bflo(unsigned u) { return __uint_as_float(u << 16); }
; DEV float bfhi(unsigned u) { return __uint_as_float(u & 0xffff0000u); }
; DEV void gdn_prep_chunk(const Params& p, int item, unsigned char* lds) {
;     ...
;                 for (int j = 0; j < 4; ++j) {
;                     const uint4 u = raw[r + j];
;                     const unsigned wd = (e < 2 ? u.x : (e < 4 ? u.y : (e < 6 ? u.z : u.w)));
;                     const float xv = (e & 1) ? bfhi(wd) : bflo(wd);
;                     a += w[j][e] * xv;
;                 }
	v_pk_fma_f32 v[50:51], v[28:29], v[64:65], v[50:51]

; DEV float bflo(unsigned u) { return __uint_as_float(u << 16); }
; DEV float bfhi(unsigned u) { return __uint_as_float(u & 0xffff0000u); }
; DEV void gdn_prep_chunk(const Params& p, int item, unsigned char* lds) {
;     ...
;                 for (int j = 0; j < 4; ++j) {
;                     const uint4 u = raw[r + j];
;                     const unsigned wd = (e < 2 ? u.x : (e < 4 ? u.y : (e < 6 ? u.z : u.w)));
;                     const float xv = (e & 1) ? bfhi(wd) : bflo(wd);
;                     a += w[j][e] * xv;
;                 }
	v_pk_fma_f32 v[50:51], v[32:33], v[56:57], v[50:51]

; DEV float silu_f(float x) { return x / (1.f + __expf(-x)); }
	v_mul_f32_e32 v72, 0xbfb8aa3b, v50
	v_mul_f32_e32 v73, 0xbfb8aa3b, v51
	v_exp_f32_e32 v72, v72
	v_exp_f32_e32 v73, v73


; DEV float silu_f(float x) { return x / (1.f + __expf(-x)); }
	v_rcp_f32_e32 v55, v54
	s_nop 0
	v_mul_f32_e32 v70, v86, v55
	v_pk_add_f32 v[72:73], v[72:73], 1.0 op_sel_hi:[1,0]
	v_pk_fma_f32 v[82:83], v[10:11], v[62:63], v[82:83]


; DEV float silu_f(float x) { return x / (1.f + __expf(-x)); }
	s_nop 0


; DEV float bflo(unsigned u) { return __uint_as_float(u << 16); }
; DEV float bfhi(unsigned u) { return __uint_as_float(u & 0xffff0000u); }
; DEV float silu_f(float x) { return x / (1.f + __expf(-x)); }
; DEV void gdn_prep_chunk(const Params& p, int item, unsigned char* lds) {
;     ...
;                     const float xv = (e & 1) ? bfhi(wd) : bflo(wd);
	v_rcp_f32_e32 v54, v73
	s_nop 0
	v_mul_f32_e32 v85, v51, v54
	v_lshlrev_b32_e32 v54, 16, v52
	v_and_b32_e32 v55, 0xffff0000, v52

; DEV float bflo(unsigned u) { return __uint_as_float(u << 16); }
; DEV float bfhi(unsigned u) { return __uint_as_float(u & 0xffff0000u); }
; DEV void gdn_prep_chunk(const Params& p, int item, unsigned char* lds) {
;     ...
;                 for (int j = 0; j < 4; ++j) {
;                     const uint4 u = raw[r + j];
;                     const unsigned wd = (e < 2 ? u.x : (e < 4 ? u.y : (e < 6 ? u.z : u.w)));
;                     const float xv = (e & 1) ? bfhi(wd) : bflo(wd);
;                     a += w[j][e] * xv;
;                 }
	v_pk_fma_f32 v[82:83], v[14:15], v[54:55], v[82:83]

; DEV float silu_f(float x) { return x / (1.f + __expf(-x)); }
	v_mul_f32_e32 v52, 0xbfb8aa3b, v82
	v_exp_f32_e32 v86, v52
	v_mul_f32_e32 v52, 0xbfb8aa3b, v83
	v_exp_f32_e32 v87, v52


; DEV float silu_f(float x) { return x / (1.f + __expf(-x)); }
	s_nop 0
	v_pk_add_f32 v[86:87], v[86:87], 1.0 op_sel_hi:[1,0]


; DEV float silu_f(float x) { return x / (1.f + __expf(-x)); }
	v_rcp_f32_e32 v51, v72
	s_nop 0
	v_mul_f32_e32 v84, v50, v51


; DEV float silu_f(float x) { return x / (1.f + __expf(-x)); }
	v_rcp_f32_e32 v50, v87
	s_nop 0
	v_mul_f32_e32 v83, v83, v50


; DEV float bflo(unsigned u) { return __uint_as_float(u << 16); }
; DEV float bfhi(unsigned u) { return __uint_as_float(u & 0xffff0000u); }
; DEV void gdn_prep_chunk(const Params& p, int item, unsigned char* lds) {
;     ...
;         for (int r = 0; r < 16; ++r) {
;             float y[8]; float ss = 0.f;
; #pragma unroll
;             for (int e = 0; e < 8; ++e) {
;                 float a = 0.f;
; #pragma unroll
;                 for (int j = 0; j < 4; ++j) {
;                     const uint4 u = raw[r + j];
;                     const unsigned wd = (e < 2 ? u.x : (e < 4 ? u.y : (e < 6 ? u.z : u.w)));
;                     const float xv = (e & 1) ? bfhi(wd) : bflo(wd);
;                     a += w[j][e] * xv;
;                 }
	v_lshlrev_b32_e32 v50, 16, v53
	v_and_b32_e32 v51, 0xffff0000, v53
	v_pk_fma_f32 v[52:53], v[4:5], v[80:81], 0 op_sel_hi:[1,1,0]

; DEV float bflo(unsigned u) { return __uint_as_float(u << 16); }
; DEV float bfhi(unsigned u) { return __uint_as_float(u & 0xffff0000u); }
; DEV void gdn_prep_chunk(const Params& p, int item, unsigned char* lds) {
;     ...
;                 for (int j = 0; j < 4; ++j) {
;                     const uint4 u = raw[r + j];
;                     const unsigned wd = (e < 2 ? u.x : (e < 4 ? u.y : (e < 6 ? u.z : u.w)));
;                     const float xv = (e & 1) ? bfhi(wd) : bflo(wd);
;                     a += w[j][e] * xv;
;                 }
	v_pk_fma_f32 v[52:53], v[8:9], v[68:69], v[52:53]

; DEV float bflo(unsigned u) { return __uint_as_float(u << 16); }
; DEV float bfhi(unsigned u) { return __uint_as_float(u & 0xffff0000u); }
; DEV void gdn_prep_chunk(const Params& p, int item, unsigned char* lds) {
;     ...
;                 for (int j = 0; j < 4; ++j) {
;                     const uint4 u = raw[r + j];
;                     const unsigned wd = (e < 2 ? u.x : (e < 4 ? u.y : (e < 6 ? u.z : u.w)));
;                     const float xv = (e & 1) ? bfhi(wd) : bflo(wd);
;                     a += w[j][e] * xv;
;                 }
	v_pk_fma_f32 v[52:53], v[12:13], v[60:61], v[52:53]

; DEV float bflo(unsigned u) { return __uint_as_float(u << 16); }
; DEV float bfhi(unsigned u) { return __uint_as_float(u & 0xffff0000u); }
; DEV void gdn_prep_chunk(const Params& p, int item, unsigned char* lds) {
;     ...
;                 for (int j = 0; j < 4; ++j) {
;                     const uint4 u = raw[r + j];
;                     const unsigned wd = (e < 2 ? u.x : (e < 4 ? u.y : (e < 6 ? u.z : u.w)));
;                     const float xv = (e & 1) ? bfhi(wd) : bflo(wd);
;                     a += w[j][e] * xv;
;                 }
	v_pk_fma_f32 v[52:53], v[16:17], v[50:51], v[52:53]

; DEV float silu_f(float x) { return x / (1.f + __expf(-x)); }
	v_mul_f32_e32 v72, 0xbfb8aa3b, v52
	v_mul_f32_e32 v73, 0xbfb8aa3b, v53
	v_exp_f32_e32 v72, v72
	v_exp_f32_e32 v73, v73


; DEV float silu_f(float x) { return x / (1.f + __expf(-x)); }
	v_rcp_f32_e32 v80, v86
	s_nop 0
	v_mul_f32_e32 v82, v82, v80
	v_pk_add_f32 v[72:73], v[72:73], 1.0 op_sel_hi:[1,0]
	s_nop 0


; DEV float silu_f(float x) { return x / (1.f + __expf(-x)); }
	s_nop 0


; DEV float silu_f(float x) { return x / (1.f + __expf(-x)); }
	v_rcp_f32_e32 v80, v73
	s_nop 0
	v_mul_f32_e32 v53, v53, v80


; DEV unsigned cvt_pk_bf16(float lo, float hi) { const f32x2_t v = {lo, hi}; const bf16x2_t b = __builtin_convertvector(v, bf16x2_t); return __builtin_bit_cast(unsigned, b); }
; DEV float bflo(unsigned u) { return __uint_as_float(u << 16); }
; DEV float bfhi(unsigned u) { return __uint_as_float(u & 0xffff0000u); }
; DEV float silu_f(float x) { return x / (1.f + __expf(-x)); }
; DEV void gdn_prep_chunk(const Params& p, int item, unsigned char* lds) {
;     ...
;         for (int r = 0; r < 16; ++r) {
;             float y[8]; float ss = 0.f;
; #pragma unroll
;             for (int e = 0; e < 8; ++e) {
;                 float a = 0.f;
; #pragma unroll
;                 for (int j = 0; j < 4; ++j) {
;                     const uint4 u = raw[r + j];
;                     const unsigned wd = (e < 2 ? u.x : (e < 4 ? u.y : (e < 6 ? u.z : u.w)));
;                     const float xv = (e & 1) ? bfhi(wd) : bflo(wd);
;                     a += w[j][e] * xv;
;                 }
;                 y[e] = silu_f(a); ss += y[e] * y[e];
;             }
;             if (mat < 2) {
;                 ss += __shfl_xor(ss, 1); ss += __shfl_xor(ss, 2); ss += __shfl_xor(ss, 4); ss += __shfl_xor(ss, 8);
;                 float inv = rsqrtf(ss + EPS); if (mat == 0) inv *= 0.08838834764831845f;
; #pragma unroll
;                 for (int e = 0; e < 8; ++e) y[e] *= inv;
;             }
;             uint4 o; o.x = cvt_pk_bf16(y[0], y[1]); o.y = cvt_pk_bf16(y[2], y[3]); o.z = cvt_pk_bf16(y[4], y[5]); o.w = cvt_pk_bf16(y[6], y[7]);
;             *(uint4*)(dst + (tl0 + r) * QS + cv * 8) = o;
	v_rcp_f32_e32 v73, v72
	s_nop 0
	v_mul_f32_e32 v52, v52, v73
	s_and_saveexec_b64 s[36:37], s[6:7]
	s_cbranch_execz .LBB0_496
	v_pk_mul_f32 v[72:73], v[70:71], v[70:71]
	v_pk_mul_f32 v[80:81], v[84:85], v[84:85]
	v_add_f32_e32 v72, v72, v73
	v_add_f32_e32 v72, v72, v80
	v_pk_mul_f32 v[86:87], v[82:83], v[82:83]
	v_add_f32_e32 v72, v81, v72
	v_and_b32_e32 v80, 64, v182
	v_add_f32_e32 v72, v86, v72
	v_xor_b32_e32 v73, 1, v182
	v_add_u32_e32 v80, 64, v80
	v_pk_mul_f32 v[88:89], v[52:53], v[52:53]
	v_add_f32_e32 v72, v87, v72
	v_cmp_lt_i32_e32 vcc, v73, v80
	v_add_f32_e32 v72, v88, v72
	v_add_f32_e32 v72, v89, v72
	v_cndmask_b32_e32 v73, v182, v73, vcc
	v_lshlrev_b32_e32 v73, 2, v73
	ds_bpermute_b32 v73, v73, v72
	s_waitcnt lgkmcnt(0)
	v_add_f32_e32 v72, v72, v73
	v_xor_b32_e32 v73, 2, v182
	v_cmp_lt_i32_e32 vcc, v73, v80
	s_nop 1
	v_cndmask_b32_e32 v73, v182, v73, vcc
	v_lshlrev_b32_e32 v73, 2, v73
	ds_bpermute_b32 v73, v73, v72
	s_waitcnt lgkmcnt(0)
	v_add_f32_e32 v72, v72, v73
	v_xor_b32_e32 v73, 4, v182
	v_cmp_lt_i32_e32 vcc, v73, v80
	s_nop 1
	v_cndmask_b32_e32 v73, v182, v73, vcc
	v_lshlrev_b32_e32 v73, 2, v73
	ds_bpermute_b32 v73, v73, v72
	s_waitcnt lgkmcnt(0)
	v_add_f32_e32 v72, v72, v73
	v_xor_b32_e32 v73, 8, v182
	v_cmp_lt_i32_e32 vcc, v73, v80
	s_nop 1
	v_cndmask_b32_e32 v73, v182, v73, vcc
	v_lshlrev_b32_e32 v73, 2, v73
	ds_bpermute_b32 v73, v73, v72
	s_waitcnt lgkmcnt(0)
	v_add_f32_e32 v72, v72, v73
	v_add_f32_e32 v72, 0x358637bd, v72
	v_mul_f32_e32 v73, 0x4b800000, v72
	v_cmp_gt_f32_e32 vcc, s56, v72
	s_nop 1
	v_cndmask_b32_e32 v72, v72, v73, vcc
	v_rsq_f32_e32 v72, v72
	s_nop 0
	v_mul_f32_e32 v73, 0x45800000, v72
	v_cndmask_b32_e32 v72, v72, v73, vcc
	v_mul_f32_e32 v73, 0x3db504f3, v72
	v_cndmask_b32_e64 v72, v72, v73, s[4:5]
	v_pk_mul_f32 v[70:71], v[70:71], v[72:73] op_sel_hi:[1,0]
	v_pk_mul_f32 v[84:85], v[84:85], v[72:73] op_sel_hi:[1,0]
	v_pk_mul_f32 v[82:83], v[82:83], v[72:73] op_sel_hi:[1,0]
	v_pk_mul_f32 v[52:53], v[52:53], v[72:73] op_sel_hi:[1,0]
.LBB0_496:
	s_or_b64 exec, exec, s[36:37]
	v_pk_fma_f32 v[78:79], v[18:19], v[78:79], 0 op_sel_hi:[1,1,0]
	s_waitcnt vmcnt(3)
	v_lshlrev_b32_e32 v72, 16, v46
	v_pk_fma_f32 v[78:79], v[22:23], v[66:67], v[78:79]
	v_and_b32_e32 v73, 0xffff0000, v46
	v_pk_fma_f32 v[78:79], v[26:27], v[58:59], v[78:79]
	v_pk_fma_f32 v[74:75], v[2:3], v[74:75], 0 op_sel_hi:[1,1,0]
	v_pk_fma_f32 v[86:87], v[30:31], v[72:73], v[78:79]
	v_cvt_pk_bf16_f32 v79, v84, v85
	v_mul_f32_e32 v46, 0xbfb8aa3b, v86
	v_exp_f32_e32 v80, v46
	v_mul_f32_e32 v46, 0xbfb8aa3b, v87
	v_exp_f32_e32 v81, v46
	v_cvt_pk_bf16_f32 v78, v70, v71
	v_pk_fma_f32 v[74:75], v[6:7], v[62:63], v[74:75]
	v_pk_add_f32 v[84:85], v[80:81], 1.0 op_sel_hi:[1,0]
	s_nop 0


; DEV unsigned cvt_pk_bf16(float lo, float hi) { const f32x2_t v = {lo, hi}; const bf16x2_t b = __builtin_convertvector(v, bf16x2_t); return __builtin_bit_cast(unsigned, b); }
; DEV float silu_f(float x) { return x / (1.f + __expf(-x)); }
; DEV void gdn_prep_chunk(const Params& p, int item, unsigned char* lds) {
;     ...
;             uint4 o; o.x = cvt_pk_bf16(y[0], y[1]); o.y = cvt_pk_bf16(y[2], y[3]); o.z = cvt_pk_bf16(y[4], y[5]); o.w = cvt_pk_bf16(y[6], y[7]);
;             *(uint4*)(dst + (tl0 + r) * QS + cv * 8) = o;
	v_cvt_pk_bf16_f32 v81, v52, v53
	v_cvt_pk_bf16_f32 v80, v82, v83
	ds_write_b128 v104, v[78:81] offset:1360


; DEV float silu_f(float x) { return x / (1.f + __expf(-x)); }
	v_rcp_f32_e32 v46, v85
	s_nop 0
	v_mul_f32_e32 v79, v87, v46


; DEV float bflo(unsigned u) { return __uint_as_float(u << 16); }
; DEV float bfhi(unsigned u) { return __uint_as_float(u & 0xffff0000u); }
; DEV void gdn_prep_chunk(const Params& p, int item, unsigned char* lds) {
;     ...
;         for (int r = 0; r < 16; ++r) {
;             float y[8]; float ss = 0.f;
; #pragma unroll
;             for (int e = 0; e < 8; ++e) {
;                 float a = 0.f;
; #pragma unroll
;                 for (int j = 0; j < 4; ++j) {
;                     const uint4 u = raw[r + j];
;                     const unsigned wd = (e < 2 ? u.x : (e < 4 ? u.y : (e < 6 ? u.z : u.w)));
;                     const float xv = (e & 1) ? bfhi(wd) : bflo(wd);
;                     a += w[j][e] * xv;
;                 }
	v_lshlrev_b32_e32 v70, 16, v47
	v_and_b32_e32 v71, 0xffff0000, v47
	v_pk_fma_f32 v[46:47], v[20:21], v[76:77], 0 op_sel_hi:[1,1,0]

; DEV float bflo(unsigned u) { return __uint_as_float(u << 16); }
; DEV float bfhi(unsigned u) { return __uint_as_float(u & 0xffff0000u); }
; DEV void gdn_prep_chunk(const Params& p, int item, unsigned char* lds) {
;     ...
;                 for (int j = 0; j < 4; ++j) {
;                     const uint4 u = raw[r + j];
;                     const unsigned wd = (e < 2 ? u.x : (e < 4 ? u.y : (e < 6 ? u.z : u.w)));
;                     const float xv = (e & 1) ? bfhi(wd) : bflo(wd);
;                     a += w[j][e] * xv;
;                 }
	v_pk_fma_f32 v[46:47], v[24:25], v[64:65], v[46:47]

; DEV float bflo(unsigned u) { return __uint_as_float(u << 16); }
; DEV float bfhi(unsigned u) { return __uint_as_float(u & 0xffff0000u); }
; DEV void gdn_prep_chunk(const Params& p, int item, unsigned char* lds) {
;     ...
;                 for (int j = 0; j < 4; ++j) {
;                     const uint4 u = raw[r + j];
;                     const unsigned wd = (e < 2 ? u.x : (e < 4 ? u.y : (e < 6 ? u.z : u.w)));
;                     const float xv = (e & 1) ? bfhi(wd) : bflo(wd);
;                     a += w[j][e] * xv;
;                 }
	v_pk_fma_f32 v[46:47], v[28:29], v[56:57], v[46:47]

; DEV float bflo(unsigned u) { return __uint_as_float(u << 16); }
; DEV float bfhi(unsigned u) { return __uint_as_float(u & 0xffff0000u); }
; DEV void gdn_prep_chunk(const Params& p, int item, unsigned char* lds) {
;     ...
;                 for (int j = 0; j < 4; ++j) {
;                     const uint4 u = raw[r + j];
;                     const unsigned wd = (e < 2 ? u.x : (e < 4 ? u.y : (e < 6 ? u.z : u.w)));
;                     const float xv = (e & 1) ? bfhi(wd) : bflo(wd);
;                     a += w[j][e] * xv;
;                 }
	v_pk_fma_f32 v[46:47], v[32:33], v[70:71], v[46:47]

; DEV float silu_f(float x) { return x / (1.f + __expf(-x)); }
	v_mul_f32_e32 v52, 0xbfb8aa3b, v46
	v_mul_f32_e32 v53, 0xbfb8aa3b, v47
	v_exp_f32_e32 v52, v52
	v_exp_f32_e32 v53, v53


; DEV float silu_f(float x) { return x / (1.f + __expf(-x)); }
	v_pk_fma_f32 v[74:75], v[10:11], v[54:55], v[74:75]
	v_pk_add_f32 v[76:77], v[52:53], 1.0 op_sel_hi:[1,0]
	v_rcp_f32_e32 v78, v84
	s_nop 0
	v_mul_f32_e32 v78, v86, v78


; DEV float silu_f(float x) { return x / (1.f + __expf(-x)); }
	s_nop 0


; DEV float bflo(unsigned u) { return __uint_as_float(u << 16); }
; DEV float bfhi(unsigned u) { return __uint_as_float(u & 0xffff0000u); }
; DEV float silu_f(float x) { return x / (1.f + __expf(-x)); }
; DEV void gdn_prep_chunk(const Params& p, int item, unsigned char* lds) {
;     ...
;                     const float xv = (e & 1) ? bfhi(wd) : bflo(wd);
	v_rcp_f32_e32 v52, v77
	s_nop 0
	v_mul_f32_e32 v77, v47, v52
	v_lshlrev_b32_e32 v52, 16, v48
	v_and_b32_e32 v53, 0xffff0000, v48

; DEV float bflo(unsigned u) { return __uint_as_float(u << 16); }
; DEV float bfhi(unsigned u) { return __uint_as_float(u & 0xffff0000u); }
; DEV void gdn_prep_chunk(const Params& p, int item, unsigned char* lds) {
;     ...
;                 for (int j = 0; j < 4; ++j) {
;                     const uint4 u = raw[r + j];
;                     const unsigned wd = (e < 2 ? u.x : (e < 4 ? u.y : (e < 6 ? u.z : u.w)));
;                     const float xv = (e & 1) ? bfhi(wd) : bflo(wd);
;                     a += w[j][e] * xv;
;                 }
	v_pk_fma_f32 v[74:75], v[14:15], v[52:53], v[74:75]

; DEV float silu_f(float x) { return x / (1.f + __expf(-x)); }
	v_mul_f32_e32 v48, 0xbfb8aa3b, v74
	v_exp_f32_e32 v80, v48
	v_mul_f32_e32 v48, 0xbfb8aa3b, v75
	v_exp_f32_e32 v81, v48


; DEV float silu_f(float x) { return x / (1.f + __expf(-x)); }
	s_nop 0
	v_pk_add_f32 v[80:81], v[80:81], 1.0 op_sel_hi:[1,0]


; DEV float silu_f(float x) { return x / (1.f + __expf(-x)); }
	v_rcp_f32_e32 v47, v76
	s_nop 0
	v_mul_f32_e32 v76, v46, v47


; DEV float silu_f(float x) { return x / (1.f + __expf(-x)); }
	v_rcp_f32_e32 v46, v81
	s_nop 0
	v_mul_f32_e32 v75, v75, v46


; DEV float bflo(unsigned u) { return __uint_as_float(u << 16); }
; DEV float bfhi(unsigned u) { return __uint_as_float(u & 0xffff0000u); }
; DEV void gdn_prep_chunk(const Params& p, int item, unsigned char* lds) {
;     ...
;         for (int r = 0; r < 16; ++r) {
;             float y[8]; float ss = 0.f;
; #pragma unroll
;             for (int e = 0; e < 8; ++e) {
;                 float a = 0.f;
; #pragma unroll
;                 for (int j = 0; j < 4; ++j) {
;                     const uint4 u = raw[r + j];
;                     const unsigned wd = (e < 2 ? u.x : (e < 4 ? u.y : (e < 6 ? u.z : u.w)));
;                     const float xv = (e & 1) ? bfhi(wd) : bflo(wd);
;                     a += w[j][e] * xv;
;                 }
	v_lshlrev_b32_e32 v46, 16, v49
	v_and_b32_e32 v47, 0xffff0000, v49
	v_pk_fma_f32 v[48:49], v[4:5], v[68:69], 0 op_sel_hi:[1,1,0]

; DEV float bflo(unsigned u) { return __uint_as_float(u << 16); }
; DEV float bfhi(unsigned u) { return __uint_as_float(u & 0xffff0000u); }
; DEV void gdn_prep_chunk(const Params& p, int item, unsigned char* lds) {
;     ...
;                 for (int j = 0; j < 4; ++j) {
;                     const uint4 u = raw[r + j];
;                     const unsigned wd = (e < 2 ? u.x : (e < 4 ? u.y : (e < 6 ? u.z : u.w)));
;                     const float xv = (e & 1) ? bfhi(wd) : bflo(wd);
;                     a += w[j][e] * xv;
;                 }
	v_pk_fma_f32 v[48:49], v[8:9], v[60:61], v[48:49]

; DEV float bflo(unsigned u) { return __uint_as_float(u << 16); }
; DEV float bfhi(unsigned u) { return __uint_as_float(u & 0xffff0000u); }
; DEV void gdn_prep_chunk(const Params& p, int item, unsigned char* lds) {
;     ...
;                 for (int j = 0; j < 4; ++j) {
;                     const uint4 u = raw[r + j];
;                     const unsigned wd = (e < 2 ? u.x : (e < 4 ? u.y : (e < 6 ? u.z : u.w)));
;                     const float xv = (e & 1) ? bfhi(wd) : bflo(wd);
;                     a += w[j][e] * xv;
;                 }
	v_pk_fma_f32 v[48:49], v[12:13], v[50:51], v[48:49]

; DEV float bflo(unsigned u) { return __uint_as_float(u << 16); }
; DEV float bfhi(unsigned u) { return __uint_as_float(u & 0xffff0000u); }
; DEV void gdn_prep_chunk(const Params& p, int item, unsigned char* lds) {
;     ...
;                 for (int j = 0; j < 4; ++j) {
;                     const uint4 u = raw[r + j];
;                     const unsigned wd = (e < 2 ? u.x : (e < 4 ? u.y : (e < 6 ? u.z : u.w)));
;                     const float xv = (e & 1) ? bfhi(wd) : bflo(wd);
;                     a += w[j][e] * xv;
;                 }
	v_pk_fma_f32 v[48:49], v[16:17], v[46:47], v[48:49]

; DEV float silu_f(float x) { return x / (1.f + __expf(-x)); }
	v_mul_f32_e32 v68, 0xbfb8aa3b, v48
	v_mul_f32_e32 v69, 0xbfb8aa3b, v49
	v_exp_f32_e32 v68, v68
	v_exp_f32_e32 v69, v69


; DEV float silu_f(float x) { return x / (1.f + __expf(-x)); }
	v_rcp_f32_e32 v81, v80
	s_nop 0
	v_mul_f32_e32 v74, v74, v81
	v_pk_add_f32 v[68:69], v[68:69], 1.0 op_sel_hi:[1,0]
	s_nop 0


; DEV float silu_f(float x) { return x / (1.f + __expf(-x)); }
	s_nop 0


; DEV float silu_f(float x) { return x / (1.f + __expf(-x)); }
	v_rcp_f32_e32 v80, v69
	s_nop 0
	v_mul_f32_e32 v49, v49, v80


; DEV unsigned cvt_pk_bf16(float lo, float hi) { const f32x2_t v = {lo, hi}; const bf16x2_t b = __builtin_convertvector(v, bf16x2_t); return __builtin_bit_cast(unsigned, b); }
; DEV float bflo(unsigned u) { return __uint_as_float(u << 16); }
; DEV float bfhi(unsigned u) { return __uint_as_float(u & 0xffff0000u); }
; DEV float silu_f(float x) { return x / (1.f + __expf(-x)); }
; DEV void gdn_prep_chunk(const Params& p, int item, unsigned char* lds) {
;     ...
;         for (int r = 0; r < 16; ++r) {
;             float y[8]; float ss = 0.f;
; #pragma unroll
;             for (int e = 0; e < 8; ++e) {
;                 float a = 0.f;
; #pragma unroll
;                 for (int j = 0; j < 4; ++j) {
;                     const uint4 u = raw[r + j];
;                     const unsigned wd = (e < 2 ? u.x : (e < 4 ? u.y : (e < 6 ? u.z : u.w)));
;                     const float xv = (e & 1) ? bfhi(wd) : bflo(wd);
;                     a += w[j][e] * xv;
;                 }
;                 y[e] = silu_f(a); ss += y[e] * y[e];
;             }
;             if (mat < 2) {
;                 ss += __shfl_xor(ss, 1); ss += __shfl_xor(ss, 2); ss += __shfl_xor(ss, 4); ss += __shfl_xor(ss, 8);
;                 float inv = rsqrtf(ss + EPS); if (mat == 0) inv *= 0.08838834764831845f;
; #pragma unroll
;                 for (int e = 0; e < 8; ++e) y[e] *= inv;
;             }
;             uint4 o; o.x = cvt_pk_bf16(y[0], y[1]); o.y = cvt_pk_bf16(y[2], y[3]); o.z = cvt_pk_bf16(y[4], y[5]); o.w = cvt_pk_bf16(y[6], y[7]);
;             *(uint4*)(dst + (tl0 + r) * QS + cv * 8) = o;
	v_rcp_f32_e32 v69, v68
	s_nop 0
	v_mul_f32_e32 v48, v48, v69
	s_and_saveexec_b64 s[36:37], s[6:7]
	s_cbranch_execz .LBB0_498
	v_pk_mul_f32 v[68:69], v[78:79], v[78:79]
	v_pk_mul_f32 v[80:81], v[76:77], v[76:77]
	v_add_f32_e32 v68, v68, v69
	v_add_f32_e32 v68, v68, v80
	v_pk_mul_f32 v[82:83], v[74:75], v[74:75]
	v_add_f32_e32 v68, v81, v68
	v_and_b32_e32 v80, 64, v182
	v_add_f32_e32 v68, v82, v68
	v_xor_b32_e32 v69, 1, v182
	v_add_u32_e32 v80, 64, v80
	v_pk_mul_f32 v[84:85], v[48:49], v[48:49]
	v_add_f32_e32 v68, v83, v68
	v_cmp_lt_i32_e32 vcc, v69, v80
	v_add_f32_e32 v68, v84, v68
	v_add_f32_e32 v68, v85, v68
	v_cndmask_b32_e32 v69, v182, v69, vcc
	v_lshlrev_b32_e32 v69, 2, v69
	ds_bpermute_b32 v69, v69, v68
	s_waitcnt lgkmcnt(0)
	v_add_f32_e32 v68, v68, v69
	v_xor_b32_e32 v69, 2, v182
	v_cmp_lt_i32_e32 vcc, v69, v80
	s_nop 1
	v_cndmask_b32_e32 v69, v182, v69, vcc
	v_lshlrev_b32_e32 v69, 2, v69
	ds_bpermute_b32 v69, v69, v68
	s_waitcnt lgkmcnt(0)
	v_add_f32_e32 v68, v68, v69
	v_xor_b32_e32 v69, 4, v182
	v_cmp_lt_i32_e32 vcc, v69, v80
	s_nop 1
	v_cndmask_b32_e32 v69, v182, v69, vcc
	v_lshlrev_b32_e32 v69, 2, v69
	ds_bpermute_b32 v69, v69, v68
	s_waitcnt lgkmcnt(0)
	v_add_f32_e32 v68, v68, v69
	v_xor_b32_e32 v69, 8, v182
	v_cmp_lt_i32_e32 vcc, v69, v80
	s_nop 1
	v_cndmask_b32_e32 v69, v182, v69, vcc
	v_lshlrev_b32_e32 v69, 2, v69
	ds_bpermute_b32 v69, v69, v68
	s_waitcnt lgkmcnt(0)
	v_add_f32_e32 v68, v68, v69
	v_add_f32_e32 v68, 0x358637bd, v68
	v_mul_f32_e32 v69, 0x4b800000, v68
	v_cmp_gt_f32_e32 vcc, s56, v68
	s_nop 1
	v_cndmask_b32_e32 v68, v68, v69, vcc
	v_rsq_f32_e32 v68, v68
	s_nop 0
	v_mul_f32_e32 v69, 0x45800000, v68
	v_cndmask_b32_e32 v68, v68, v69, vcc
	v_mul_f32_e32 v69, 0x3db504f3, v68
	v_cndmask_b32_e64 v68, v68, v69, s[4:5]
	v_pk_mul_f32 v[78:79], v[78:79], v[68:69] op_sel_hi:[1,0]
	v_pk_mul_f32 v[76:77], v[76:77], v[68:69] op_sel_hi:[1,0]
	v_pk_mul_f32 v[74:75], v[74:75], v[68:69] op_sel_hi:[1,0]
	v_pk_mul_f32 v[48:49], v[48:49], v[68:69] op_sel_hi:[1,0]
.LBB0_498:
	s_or_b64 exec, exec, s[36:37]
	v_pk_fma_f32 v[66:67], v[18:19], v[66:67], 0 op_sel_hi:[1,1,0]
	s_waitcnt vmcnt(2)
	v_lshlrev_b32_e32 v68, 16, v42
	v_pk_fma_f32 v[66:67], v[22:23], v[58:59], v[66:67]
	v_and_b32_e32 v69, 0xffff0000, v42
	v_pk_fma_f32 v[66:67], v[26:27], v[72:73], v[66:67]
	v_cvt_pk_bf16_f32 v78, v78, v79
	v_pk_fma_f32 v[82:83], v[30:31], v[68:69], v[66:67]
	v_cvt_pk_bf16_f32 v79, v76, v77
	v_mul_f32_e32 v42, 0xbfb8aa3b, v82
	v_exp_f32_e32 v66, v42
	v_mul_f32_e32 v42, 0xbfb8aa3b, v83
	v_exp_f32_e32 v67, v42
	v_cvt_pk_bf16_f32 v81, v48, v49
	v_cvt_pk_bf16_f32 v80, v74, v75
	ds_write_b128 v104, v[78:81] offset:1632
	v_pk_add_f32 v[76:77], v[66:67], 1.0 op_sel_hi:[1,0]
	v_pk_fma_f32 v[62:63], v[2:3], v[62:63], 0 op_sel_hi:[1,1,0]


; DEV float silu_f(float x) { return x / (1.f + __expf(-x)); }
	v_rcp_f32_e32 v42, v77
	s_nop 0
	v_mul_f32_e32 v75, v83, v42


; DEV float bflo(unsigned u) { return __uint_as_float(u << 16); }
; DEV float bfhi(unsigned u) { return __uint_as_float(u & 0xffff0000u); }
; DEV void gdn_prep_chunk(const Params& p, int item, unsigned char* lds) {
;     ...
;         for (int r = 0; r < 16; ++r) {
;             float y[8]; float ss = 0.f;
; #pragma unroll
;             for (int e = 0; e < 8; ++e) {
;                 float a = 0.f;
; #pragma unroll
;                 for (int j = 0; j < 4; ++j) {
;                     const uint4 u = raw[r + j];
;                     const unsigned wd = (e < 2 ? u.x : (e < 4 ? u.y : (e < 6 ? u.z : u.w)));
;                     const float xv = (e & 1) ? bfhi(wd) : bflo(wd);
;                     a += w[j][e] * xv;
;                 }
	v_lshlrev_b32_e32 v66, 16, v43
	v_and_b32_e32 v67, 0xffff0000, v43
	v_pk_fma_f32 v[42:43], v[20:21], v[64:65], 0 op_sel_hi:[1,1,0]

; DEV float bflo(unsigned u) { return __uint_as_float(u << 16); }
; DEV float bfhi(unsigned u) { return __uint_as_float(u & 0xffff0000u); }
; DEV void gdn_prep_chunk(const Params& p, int item, unsigned char* lds) {
;     ...
;                 for (int j = 0; j < 4; ++j) {
;                     const uint4 u = raw[r + j];
;                     const unsigned wd = (e < 2 ? u.x : (e < 4 ? u.y : (e < 6 ? u.z : u.w)));
;                     const float xv = (e & 1) ? bfhi(wd) : bflo(wd);
;                     a += w[j][e] * xv;
;                 }
	v_pk_fma_f32 v[42:43], v[24:25], v[56:57], v[42:43]

; DEV float bflo(unsigned u) { return __uint_as_float(u << 16); }
; DEV float bfhi(unsigned u) { return __uint_as_float(u & 0xffff0000u); }
; DEV void gdn_prep_chunk(const Params& p, int item, unsigned char* lds) {
;     ...
;                 for (int j = 0; j < 4; ++j) {
;                     const uint4 u = raw[r + j];
;                     const unsigned wd = (e < 2 ? u.x : (e < 4 ? u.y : (e < 6 ? u.z : u.w)));
;                     const float xv = (e & 1) ? bfhi(wd) : bflo(wd);
;                     a += w[j][e] * xv;
;                 }
	v_pk_fma_f32 v[42:43], v[28:29], v[70:71], v[42:43]

; DEV float bflo(unsigned u) { return __uint_as_float(u << 16); }
; DEV float bfhi(unsigned u) { return __uint_as_float(u & 0xffff0000u); }
; DEV void gdn_prep_chunk(const Params& p, int item, unsigned char* lds) {
;     ...
;                 for (int j = 0; j < 4; ++j) {
;                     const uint4 u = raw[r + j];
;                     const unsigned wd = (e < 2 ? u.x : (e < 4 ? u.y : (e < 6 ? u.z : u.w)));
;                     const float xv = (e & 1) ? bfhi(wd) : bflo(wd);
;                     a += w[j][e] * xv;
;                 }
	v_pk_fma_f32 v[42:43], v[32:33], v[66:67], v[42:43]

; DEV float silu_f(float x) { return x / (1.f + __expf(-x)); }
	v_mul_f32_e32 v48, 0xbfb8aa3b, v42
	v_mul_f32_e32 v49, 0xbfb8aa3b, v43
	v_exp_f32_e32 v48, v48
	v_exp_f32_e32 v49, v49


; DEV float silu_f(float x) { return x / (1.f + __expf(-x)); }
	v_rcp_f32_e32 v74, v76
	s_nop 0
	v_mul_f32_e32 v74, v82, v74
	v_pk_add_f32 v[64:65], v[48:49], 1.0 op_sel_hi:[1,0]
	v_pk_fma_f32 v[62:63], v[6:7], v[54:55], v[62:63]


; DEV float silu_f(float x) { return x / (1.f + __expf(-x)); }
	v_pk_fma_f32 v[62:63], v[10:11], v[52:53], v[62:63]


; DEV float bflo(unsigned u) { return __uint_as_float(u << 16); }
; DEV float bfhi(unsigned u) { return __uint_as_float(u & 0xffff0000u); }
; DEV float silu_f(float x) { return x / (1.f + __expf(-x)); }
; DEV void gdn_prep_chunk(const Params& p, int item, unsigned char* lds) {
;     ...
;             for (int e = 0; e < 8; ++e) {
;                 float a = 0.f;
; #pragma unroll
;                 for (int j = 0; j < 4; ++j) {
;                     const uint4 u = raw[r + j];
;                     const unsigned wd = (e < 2 ? u.x : (e < 4 ? u.y : (e < 6 ? u.z : u.w)));
;                     const float xv = (e & 1) ? bfhi(wd) : bflo(wd);
;                     a += w[j][e] * xv;
;                 }
;                 y[e] = silu_f(a); ss += y[e] * y[e];
;             }
	v_rcp_f32_e32 v48, v65
	s_nop 0
	v_mul_f32_e32 v65, v43, v48
	v_lshlrev_b32_e32 v48, 16, v44
	v_and_b32_e32 v49, 0xffff0000, v44

; DEV float bflo(unsigned u) { return __uint_as_float(u << 16); }
; DEV float bfhi(unsigned u) { return __uint_as_float(u & 0xffff0000u); }
; DEV void gdn_prep_chunk(const Params& p, int item, unsigned char* lds) {
;     ...
;                 for (int j = 0; j < 4; ++j) {
;                     const uint4 u = raw[r + j];
;                     const unsigned wd = (e < 2 ? u.x : (e < 4 ? u.y : (e < 6 ? u.z : u.w)));
;                     const float xv = (e & 1) ? bfhi(wd) : bflo(wd);
;                     a += w[j][e] * xv;
	v_pk_fma_f32 v[62:63], v[14:15], v[48:49], v[62:63]

; DEV float silu_f(float x) { return x / (1.f + __expf(-x)); }
; DEV void gdn_prep_chunk(const Params& p, int item, unsigned char* lds) {
;     ...
;                 y[e] = silu_f(a); ss += y[e] * y[e];
	v_mul_f32_e32 v44, 0xbfb8aa3b, v62
	v_exp_f32_e32 v76, v44
	v_mul_f32_e32 v44, 0xbfb8aa3b, v63
	v_exp_f32_e32 v77, v44


; DEV float silu_f(float x) { return x / (1.f + __expf(-x)); }
; DEV void gdn_prep_chunk(const Params& p, int item, unsigned char* lds) {
;     ...
;                 y[e] = silu_f(a); ss += y[e] * y[e];
	s_nop 0
	v_pk_add_f32 v[76:77], v[76:77], 1.0 op_sel_hi:[1,0]


; DEV float silu_f(float x) { return x / (1.f + __expf(-x)); }
; DEV void gdn_prep_chunk(const Params& p, int item, unsigned char* lds) {
;     ...
;                 y[e] = silu_f(a); ss += y[e] * y[e];
	v_rcp_f32_e32 v43, v64
	s_nop 0
	v_mul_f32_e32 v64, v42, v43


; DEV float silu_f(float x) { return x / (1.f + __expf(-x)); }
; DEV void gdn_prep_chunk(const Params& p, int item, unsigned char* lds) {
;     ...
;                 y[e] = silu_f(a); ss += y[e] * y[e];
	v_rcp_f32_e32 v42, v77
	s_nop 0
	v_mul_f32_e32 v63, v63, v42


; DEV float bflo(unsigned u) { return __uint_as_float(u << 16); }
; DEV float bfhi(unsigned u) { return __uint_as_float(u & 0xffff0000u); }
; DEV void gdn_prep_chunk(const Params& p, int item, unsigned char* lds) {
;     ...
;                     const uint4 u = raw[r + j];
;                     const unsigned wd = (e < 2 ? u.x : (e < 4 ? u.y : (e < 6 ? u.z : u.w)));
;                     const float xv = (e & 1) ? bfhi(wd) : bflo(wd);
;                     a += w[j][e] * xv;
	v_lshlrev_b32_e32 v42, 16, v45
	v_and_b32_e32 v43, 0xffff0000, v45
	v_pk_fma_f32 v[44:45], v[4:5], v[60:61], 0 op_sel_hi:[1,1,0]

; DEV void gdn_prep_chunk(const Params& p, int item, unsigned char* lds) {
;     ...
;                     a += w[j][e] * xv;
	v_pk_fma_f32 v[44:45], v[8:9], v[50:51], v[44:45]

; DEV void gdn_prep_chunk(const Params& p, int item, unsigned char* lds) {
;     ...
;                     a += w[j][e] * xv;
	v_pk_fma_f32 v[44:45], v[12:13], v[46:47], v[44:45]

; DEV void gdn_prep_chunk(const Params& p, int item, unsigned char* lds) {
;     ...
;                     a += w[j][e] * xv;
	v_pk_fma_f32 v[44:45], v[16:17], v[42:43], v[44:45]

; DEV float silu_f(float x) { return x / (1.f + __expf(-x)); }
; DEV void gdn_prep_chunk(const Params& p, int item, unsigned char* lds) {
;     ...
;                 y[e] = silu_f(a); ss += y[e] * y[e];
	v_mul_f32_e32 v60, 0xbfb8aa3b, v44
	v_mul_f32_e32 v61, 0xbfb8aa3b, v45
	v_exp_f32_e32 v60, v60
	v_exp_f32_e32 v61, v61


; DEV float silu_f(float x) { return x / (1.f + __expf(-x)); }
; DEV void gdn_prep_chunk(const Params& p, int item, unsigned char* lds) {
;     ...
;                 y[e] = silu_f(a); ss += y[e] * y[e];
	v_rcp_f32_e32 v77, v76
	s_nop 0
	v_mul_f32_e32 v62, v62, v77
	v_pk_add_f32 v[60:61], v[60:61], 1.0 op_sel_hi:[1,0]
	s_nop 0


; DEV float silu_f(float x) { return x / (1.f + __expf(-x)); }
; DEV void gdn_prep_chunk(const Params& p, int item, unsigned char* lds) {
;     ...
;                 y[e] = silu_f(a); ss += y[e] * y[e];
	s_nop 0


; DEV float silu_f(float x) { return x / (1.f + __expf(-x)); }
; DEV void gdn_prep_chunk(const Params& p, int item, unsigned char* lds) {
;     ...
;                 y[e] = silu_f(a); ss += y[e] * y[e];
	v_rcp_f32_e32 v76, v61
	s_nop 0
	v_mul_f32_e32 v45, v45, v76


; DEV unsigned cvt_pk_bf16(float lo, float hi) { const f32x2_t v = {lo, hi}; const bf16x2_t b = __builtin_convertvector(v, bf16x2_t); return __builtin_bit_cast(unsigned, b); }
; DEV float silu_f(float x) { return x / (1.f + __expf(-x)); }
; DEV void gdn_prep_chunk(const Params& p, int item, unsigned char* lds) {
;     ...
;                 y[e] = silu_f(a); ss += y[e] * y[e];
;             }
;             if (mat < 2) {
;                 ss += __shfl_xor(ss, 1); ss += __shfl_xor(ss, 2); ss += __shfl_xor(ss, 4); ss += __shfl_xor(ss, 8);
;                 float inv = rsqrtf(ss + EPS); if (mat == 0) inv *= 0.08838834764831845f;
; #pragma unroll
;                 for (int e = 0; e < 8; ++e) y[e] *= inv;
;             }
;             uint4 o; o.x = cvt_pk_bf16(y[0], y[1]); o.y = cvt_pk_bf16(y[2], y[3]); o.z = cvt_pk_bf16(y[4], y[5]); o.w = cvt_pk_bf16(y[6], y[7]);
;             *(uint4*)(dst + (tl0 + r) * QS + cv * 8) = o;
	v_rcp_f32_e32 v61, v60
	s_nop 0
	v_mul_f32_e32 v44, v44, v61
	s_and_saveexec_b64 s[36:37], s[6:7]
	s_cbranch_execz .LBB0_500
	v_pk_mul_f32 v[60:61], v[74:75], v[74:75]
	v_pk_mul_f32 v[76:77], v[64:65], v[64:65]
	v_add_f32_e32 v60, v60, v61
	v_add_f32_e32 v60, v60, v76
	v_pk_mul_f32 v[78:79], v[62:63], v[62:63]
	v_add_f32_e32 v60, v77, v60
	v_and_b32_e32 v76, 64, v182
	v_add_f32_e32 v60, v78, v60
	v_xor_b32_e32 v61, 1, v182
	v_add_u32_e32 v76, 64, v76
	v_pk_mul_f32 v[80:81], v[44:45], v[44:45]
	v_add_f32_e32 v60, v79, v60
	v_cmp_lt_i32_e32 vcc, v61, v76
	v_add_f32_e32 v60, v80, v60
	v_add_f32_e32 v60, v81, v60
	v_cndmask_b32_e32 v61, v182, v61, vcc
	v_lshlrev_b32_e32 v61, 2, v61
	ds_bpermute_b32 v61, v61, v60
	s_waitcnt lgkmcnt(0)
	v_add_f32_e32 v60, v60, v61
	v_xor_b32_e32 v61, 2, v182
	v_cmp_lt_i32_e32 vcc, v61, v76
	s_nop 1
	v_cndmask_b32_e32 v61, v182, v61, vcc
	v_lshlrev_b32_e32 v61, 2, v61
	ds_bpermute_b32 v61, v61, v60
	s_waitcnt lgkmcnt(0)
	v_add_f32_e32 v60, v60, v61
	v_xor_b32_e32 v61, 4, v182
	v_cmp_lt_i32_e32 vcc, v61, v76
	s_nop 1
	v_cndmask_b32_e32 v61, v182, v61, vcc
	v_lshlrev_b32_e32 v61, 2, v61
	ds_bpermute_b32 v61, v61, v60
	s_waitcnt lgkmcnt(0)
	v_add_f32_e32 v60, v60, v61
	v_xor_b32_e32 v61, 8, v182
	v_cmp_lt_i32_e32 vcc, v61, v76
	s_nop 1
	v_cndmask_b32_e32 v61, v182, v61, vcc
	v_lshlrev_b32_e32 v61, 2, v61
	ds_bpermute_b32 v61, v61, v60
	s_waitcnt lgkmcnt(0)
	v_add_f32_e32 v60, v60, v61
	v_add_f32_e32 v60, 0x358637bd, v60
	v_mul_f32_e32 v61, 0x4b800000, v60
	v_cmp_gt_f32_e32 vcc, s56, v60
	s_nop 1
	v_cndmask_b32_e32 v60, v60, v61, vcc
	v_rsq_f32_e32 v60, v60
	s_nop 0
	v_mul_f32_e32 v61, 0x45800000, v60
	v_cndmask_b32_e32 v60, v60, v61, vcc
	v_mul_f32_e32 v61, 0x3db504f3, v60
	v_cndmask_b32_e64 v60, v60, v61, s[4:5]
	v_pk_mul_f32 v[74:75], v[74:75], v[60:61] op_sel_hi:[1,0]
	v_pk_mul_f32 v[64:65], v[64:65], v[60:61] op_sel_hi:[1,0]
	v_pk_mul_f32 v[62:63], v[62:63], v[60:61] op_sel_hi:[1,0]
	v_pk_mul_f32 v[44:45], v[44:45], v[60:61] op_sel_hi:[1,0]
.LBB0_500:
	s_or_b64 exec, exec, s[36:37]
	v_pk_fma_f32 v[58:59], v[18:19], v[58:59], 0 op_sel_hi:[1,1,0]
	s_waitcnt vmcnt(1)
	v_lshlrev_b32_e32 v60, 16, v38
	v_pk_fma_f32 v[58:59], v[22:23], v[72:73], v[58:59]
	v_and_b32_e32 v61, 0xffff0000, v38
	v_pk_fma_f32 v[58:59], v[26:27], v[68:69], v[58:59]
	v_cvt_pk_bf16_f32 v74, v74, v75
	v_pk_fma_f32 v[78:79], v[30:31], v[60:61], v[58:59]
	v_cvt_pk_bf16_f32 v75, v64, v65
	v_mul_f32_e32 v38, 0xbfb8aa3b, v78
	v_exp_f32_e32 v58, v38
	v_mul_f32_e32 v38, 0xbfb8aa3b, v79
	v_exp_f32_e32 v59, v38
	v_cvt_pk_bf16_f32 v77, v44, v45
	v_cvt_pk_bf16_f32 v76, v62, v63
	ds_write_b128 v104, v[74:77] offset:1904
	v_pk_add_f32 v[64:65], v[58:59], 1.0 op_sel_hi:[1,0]
	v_pk_fma_f32 v[54:55], v[2:3], v[54:55], 0 op_sel_hi:[1,1,0]


; DEV float silu_f(float x) { return x / (1.f + __expf(-x)); }
; DEV void gdn_prep_chunk(const Params& p, int item, unsigned char* lds) {
;     ...
;                 y[e] = silu_f(a); ss += y[e] * y[e];
	v_rcp_f32_e32 v38, v65
	s_nop 0
	v_mul_f32_e32 v63, v79, v38


; DEV float bflo(unsigned u) { return __uint_as_float(u << 16); }
; DEV float bfhi(unsigned u) { return __uint_as_float(u & 0xffff0000u); }
; DEV void gdn_prep_chunk(const Params& p, int item, unsigned char* lds) {
;     ...
;                     const uint4 u = raw[r + j];
;                     const unsigned wd = (e < 2 ? u.x : (e < 4 ? u.y : (e < 6 ? u.z : u.w)));
;                     const float xv = (e & 1) ? bfhi(wd) : bflo(wd);
;                     a += w[j][e] * xv;
	v_lshlrev_b32_e32 v58, 16, v39
	v_and_b32_e32 v59, 0xffff0000, v39
	v_pk_fma_f32 v[38:39], v[20:21], v[56:57], 0 op_sel_hi:[1,1,0]

; DEV void gdn_prep_chunk(const Params& p, int item, unsigned char* lds) {
;     ...
;                     a += w[j][e] * xv;
	v_pk_fma_f32 v[38:39], v[24:25], v[70:71], v[38:39]

; DEV void gdn_prep_chunk(const Params& p, int item, unsigned char* lds) {
;     ...
;                     a += w[j][e] * xv;
	v_pk_fma_f32 v[38:39], v[28:29], v[66:67], v[38:39]

; DEV void gdn_prep_chunk(const Params& p, int item, unsigned char* lds) {
;     ...
;                     a += w[j][e] * xv;
	v_pk_fma_f32 v[38:39], v[32:33], v[58:59], v[38:39]

; DEV float silu_f(float x) { return x / (1.f + __expf(-x)); }
; DEV void gdn_prep_chunk(const Params& p, int item, unsigned char* lds) {
;     ...
;                 y[e] = silu_f(a); ss += y[e] * y[e];
	v_mul_f32_e32 v44, 0xbfb8aa3b, v38
	v_mul_f32_e32 v45, 0xbfb8aa3b, v39
	v_exp_f32_e32 v44, v44
	v_exp_f32_e32 v45, v45


; DEV float silu_f(float x) { return x / (1.f + __expf(-x)); }
; DEV void gdn_prep_chunk(const Params& p, int item, unsigned char* lds) {
;     ...
;                 y[e] = silu_f(a); ss += y[e] * y[e];
	v_rcp_f32_e32 v62, v64
	s_nop 0
	v_mul_f32_e32 v62, v78, v62
	v_pk_add_f32 v[56:57], v[44:45], 1.0 op_sel_hi:[1,0]
	v_pk_fma_f32 v[54:55], v[6:7], v[52:53], v[54:55]


; DEV float silu_f(float x) { return x / (1.f + __expf(-x)); }
; DEV void gdn_prep_chunk(const Params& p, int item, unsigned char* lds) {
;     ...
;                     a += w[j][e] * xv;
;     ...
;                 y[e] = silu_f(a); ss += y[e] * y[e];
	v_pk_fma_f32 v[54:55], v[10:11], v[48:49], v[54:55]


; DEV float bflo(unsigned u) { return __uint_as_float(u << 16); }
; DEV float bfhi(unsigned u) { return __uint_as_float(u & 0xffff0000u); }
; DEV float silu_f(float x) { return x / (1.f + __expf(-x)); }
; DEV void gdn_prep_chunk(const Params& p, int item, unsigned char* lds) {
;     ...
;                     const uint4 u = raw[r + j];
;                     const unsigned wd = (e < 2 ? u.x : (e < 4 ? u.y : (e < 6 ? u.z : u.w)));
;                     const float xv = (e & 1) ? bfhi(wd) : bflo(wd);
;     ...
;                 y[e] = silu_f(a); ss += y[e] * y[e];
	v_rcp_f32_e32 v44, v57
	s_nop 0
	v_mul_f32_e32 v57, v39, v44
	v_lshlrev_b32_e32 v44, 16, v40
	v_and_b32_e32 v45, 0xffff0000, v40

; DEV void gdn_prep_chunk(const Params& p, int item, unsigned char* lds) {
;     ...
;                     a += w[j][e] * xv;
	v_pk_fma_f32 v[54:55], v[14:15], v[44:45], v[54:55]

; DEV float silu_f(float x) { return x / (1.f + __expf(-x)); }
; DEV void gdn_prep_chunk(const Params& p, int item, unsigned char* lds) {
;     ...
;                 y[e] = silu_f(a); ss += y[e] * y[e];
	v_mul_f32_e32 v40, 0xbfb8aa3b, v54
	v_exp_f32_e32 v64, v40
	v_mul_f32_e32 v40, 0xbfb8aa3b, v55
	v_exp_f32_e32 v65, v40


; DEV float silu_f(float x) { return x / (1.f + __expf(-x)); }
; DEV void gdn_prep_chunk(const Params& p, int item, unsigned char* lds) {
;     ...
;                 y[e] = silu_f(a); ss += y[e] * y[e];
	s_nop 0
	v_pk_add_f32 v[64:65], v[64:65], 1.0 op_sel_hi:[1,0]


; DEV float silu_f(float x) { return x / (1.f + __expf(-x)); }
; DEV void gdn_prep_chunk(const Params& p, int item, unsigned char* lds) {
;     ...
;                 y[e] = silu_f(a); ss += y[e] * y[e];
	v_rcp_f32_e32 v39, v56
	s_nop 0
	v_mul_f32_e32 v56, v38, v39


; DEV float silu_f(float x) { return x / (1.f + __expf(-x)); }
; DEV void gdn_prep_chunk(const Params& p, int item, unsigned char* lds) {
;     ...
;                 y[e] = silu_f(a); ss += y[e] * y[e];
	v_rcp_f32_e32 v38, v65
	s_nop 0
	v_mul_f32_e32 v55, v55, v38


; DEV float bflo(unsigned u) { return __uint_as_float(u << 16); }
; DEV float bfhi(unsigned u) { return __uint_as_float(u & 0xffff0000u); }
; DEV void gdn_prep_chunk(const Params& p, int item, unsigned char* lds) {
;     ...
;                     const uint4 u = raw[r + j];
;                     const unsigned wd = (e < 2 ? u.x : (e < 4 ? u.y : (e < 6 ? u.z : u.w)));
;                     const float xv = (e & 1) ? bfhi(wd) : bflo(wd);
;                     a += w[j][e] * xv;
	v_lshlrev_b32_e32 v38, 16, v41
	v_and_b32_e32 v39, 0xffff0000, v41
	v_pk_fma_f32 v[40:41], v[4:5], v[50:51], 0 op_sel_hi:[1,1,0]

; DEV void gdn_prep_chunk(const Params& p, int item, unsigned char* lds) {
;     ...
;                     a += w[j][e] * xv;
	v_pk_fma_f32 v[40:41], v[8:9], v[46:47], v[40:41]

; DEV void gdn_prep_chunk(const Params& p, int item, unsigned char* lds) {
;     ...
;                     a += w[j][e] * xv;
	v_pk_fma_f32 v[40:41], v[12:13], v[42:43], v[40:41]

; DEV void gdn_prep_chunk(const Params& p, int item, unsigned char* lds) {
;     ...
;                     a += w[j][e] * xv;
	v_pk_fma_f32 v[40:41], v[16:17], v[38:39], v[40:41]

; DEV float silu_f(float x) { return x / (1.f + __expf(-x)); }
; DEV void gdn_prep_chunk(const Params& p, int item, unsigned char* lds) {
;     ...
;                 y[e] = silu_f(a); ss += y[e] * y[e];
	v_mul_f32_e32 v50, 0xbfb8aa3b, v40
	v_mul_f32_e32 v51, 0xbfb8aa3b, v41
	v_exp_f32_e32 v50, v50
	v_exp_f32_e32 v51, v51


; DEV float silu_f(float x) { return x / (1.f + __expf(-x)); }
; DEV void gdn_prep_chunk(const Params& p, int item, unsigned char* lds) {
;     ...
;                 y[e] = silu_f(a); ss += y[e] * y[e];
	v_rcp_f32_e32 v65, v64
	s_nop 0
	v_mul_f32_e32 v54, v54, v65
	v_pk_add_f32 v[50:51], v[50:51], 1.0 op_sel_hi:[1,0]
	s_nop 0


; DEV float silu_f(float x) { return x / (1.f + __expf(-x)); }
; DEV void gdn_prep_chunk(const Params& p, int item, unsigned char* lds) {
;     ...
;                 y[e] = silu_f(a); ss += y[e] * y[e];
	s_nop 0


; DEV float silu_f(float x) { return x / (1.f + __expf(-x)); }
; DEV void gdn_prep_chunk(const Params& p, int item, unsigned char* lds) {
;     ...
;                 y[e] = silu_f(a); ss += y[e] * y[e];
	v_rcp_f32_e32 v64, v51
	s_nop 0
	v_mul_f32_e32 v41, v41, v64


; DEV unsigned cvt_pk_bf16(float lo, float hi) { const f32x2_t v = {lo, hi}; const bf16x2_t b = __builtin_convertvector(v, bf16x2_t); return __builtin_bit_cast(unsigned, b); }
; DEV float bflo(unsigned u) { return __uint_as_float(u << 16); }
; DEV float bfhi(unsigned u) { return __uint_as_float(u & 0xffff0000u); }
; DEV float silu_f(float x) { return x / (1.f + __expf(-x)); }
; DEV void gdn_prep_chunk(const Params& p, int item, unsigned char* lds) {
;     ...
;                 float a = 0.f;
; #pragma unroll
;                 for (int j = 0; j < 4; ++j) {
;                     const uint4 u = raw[r + j];
;                     const unsigned wd = (e < 2 ? u.x : (e < 4 ? u.y : (e < 6 ? u.z : u.w)));
;                     const float xv = (e & 1) ? bfhi(wd) : bflo(wd);
;                     a += w[j][e] * xv;
;                 }
;                 y[e] = silu_f(a); ss += y[e] * y[e];
;             }
;             if (mat < 2) {
;                 ss += __shfl_xor(ss, 1); ss += __shfl_xor(ss, 2); ss += __shfl_xor(ss, 4); ss += __shfl_xor(ss, 8);
;                 float inv = rsqrtf(ss + EPS); if (mat == 0) inv *= 0.08838834764831845f;
; #pragma unroll
;                 for (int e = 0; e < 8; ++e) y[e] *= inv;
;             }
;             uint4 o; o.x = cvt_pk_bf16(y[0], y[1]); o.y = cvt_pk_bf16(y[2], y[3]); o.z = cvt_pk_bf16(y[4], y[5]); o.w = cvt_pk_bf16(y[6], y[7]);
;             *(uint4*)(dst + (tl0 + r) * QS + cv * 8) = o;
	v_rcp_f32_e32 v51, v50
	s_nop 0
	v_mul_f32_e32 v40, v40, v51
	s_and_saveexec_b64 s[36:37], s[6:7]
	s_cbranch_execz .LBB0_502
	v_pk_mul_f32 v[50:51], v[62:63], v[62:63]
	v_pk_mul_f32 v[64:65], v[56:57], v[56:57]
	v_add_f32_e32 v50, v50, v51
	v_add_f32_e32 v50, v50, v64
	v_pk_mul_f32 v[74:75], v[54:55], v[54:55]
	v_add_f32_e32 v50, v65, v50
	v_and_b32_e32 v64, 64, v182
	v_add_f32_e32 v50, v74, v50
	v_xor_b32_e32 v51, 1, v182
	v_add_u32_e32 v64, 64, v64
	v_pk_mul_f32 v[76:77], v[40:41], v[40:41]
	v_add_f32_e32 v50, v75, v50
	v_cmp_lt_i32_e32 vcc, v51, v64
	v_add_f32_e32 v50, v76, v50
	v_add_f32_e32 v50, v77, v50
	v_cndmask_b32_e32 v51, v182, v51, vcc
	v_lshlrev_b32_e32 v51, 2, v51
	ds_bpermute_b32 v51, v51, v50
	s_waitcnt lgkmcnt(0)
	v_add_f32_e32 v50, v50, v51
	v_xor_b32_e32 v51, 2, v182
	v_cmp_lt_i32_e32 vcc, v51, v64
	s_nop 1
	v_cndmask_b32_e32 v51, v182, v51, vcc
	v_lshlrev_b32_e32 v51, 2, v51
	ds_bpermute_b32 v51, v51, v50
	s_waitcnt lgkmcnt(0)
	v_add_f32_e32 v50, v50, v51
	v_xor_b32_e32 v51, 4, v182
	v_cmp_lt_i32_e32 vcc, v51, v64
	s_nop 1
	v_cndmask_b32_e32 v51, v182, v51, vcc
	v_lshlrev_b32_e32 v51, 2, v51
	ds_bpermute_b32 v51, v51, v50
	s_waitcnt lgkmcnt(0)
	v_add_f32_e32 v50, v50, v51
	v_xor_b32_e32 v51, 8, v182
	v_cmp_lt_i32_e32 vcc, v51, v64
	s_nop 1
	v_cndmask_b32_e32 v51, v182, v51, vcc
	v_lshlrev_b32_e32 v51, 2, v51
	ds_bpermute_b32 v51, v51, v50
	s_waitcnt lgkmcnt(0)
	v_add_f32_e32 v50, v50, v51
	v_add_f32_e32 v50, 0x358637bd, v50
	v_mul_f32_e32 v51, 0x4b800000, v50
	v_cmp_gt_f32_e32 vcc, s56, v50
	s_nop 1
	v_cndmask_b32_e32 v50, v50, v51, vcc
	v_rsq_f32_e32 v50, v50
	s_nop 0
	v_mul_f32_e32 v51, 0x45800000, v50
	v_cndmask_b32_e32 v50, v50, v51, vcc
	v_mul_f32_e32 v51, 0x3db504f3, v50
	v_cndmask_b32_e64 v50, v50, v51, s[4:5]
	v_pk_mul_f32 v[62:63], v[62:63], v[50:51] op_sel_hi:[1,0]
	v_pk_mul_f32 v[56:57], v[56:57], v[50:51] op_sel_hi:[1,0]
	v_pk_mul_f32 v[54:55], v[54:55], v[50:51] op_sel_hi:[1,0]
	v_pk_mul_f32 v[40:41], v[40:41], v[50:51] op_sel_hi:[1,0]
.LBB0_502:
	s_or_b64 exec, exec, s[36:37]
	v_pk_fma_f32 v[18:19], v[18:19], v[72:73], 0 op_sel_hi:[1,1,0]
	s_waitcnt vmcnt(0)
	v_lshlrev_b32_e32 v50, 16, v34
	v_pk_fma_f32 v[18:19], v[22:23], v[68:69], v[18:19]
	v_and_b32_e32 v51, 0xffff0000, v34
	v_pk_fma_f32 v[18:19], v[26:27], v[60:61], v[18:19]
	v_pk_fma_f32 v[20:21], v[20:21], v[70:71], 0 op_sel_hi:[1,1,0]
	v_pk_fma_f32 v[18:19], v[30:31], v[50:51], v[18:19]
	v_pk_fma_f32 v[20:21], v[24:25], v[66:67], v[20:21]
	v_mul_f32_e32 v22, 0xbfb8aa3b, v18
	v_mul_f32_e32 v23, 0xbfb8aa3b, v19
	v_exp_f32_e32 v22, v22
	v_exp_f32_e32 v23, v23
	v_pk_fma_f32 v[20:21], v[28:29], v[58:59], v[20:21]
	v_pk_fma_f32 v[2:3], v[2:3], v[52:53], 0 op_sel_hi:[1,1,0]
	v_pk_fma_f32 v[4:5], v[4:5], v[46:47], 0 op_sel_hi:[1,1,0]
	v_pk_add_f32 v[22:23], v[22:23], 1.0 op_sel_hi:[1,0]
	v_pk_fma_f32 v[2:3], v[6:7], v[48:49], v[2:3]


; DEV unsigned cvt_pk_bf16(float lo, float hi) { const f32x2_t v = {lo, hi}; const bf16x2_t b = __builtin_convertvector(v, bf16x2_t); return __builtin_bit_cast(unsigned, b); }
; DEV void gdn_prep_chunk(const Params& p, int item, unsigned char* lds) {
;     ...
;                     a += w[j][e] * xv;
;     ...
;             uint4 o; o.x = cvt_pk_bf16(y[0], y[1]); o.y = cvt_pk_bf16(y[2], y[3]); o.z = cvt_pk_bf16(y[4], y[5]); o.w = cvt_pk_bf16(y[6], y[7]);
	v_pk_fma_f32 v[2:3], v[10:11], v[44:45], v[2:3]
	v_pk_fma_f32 v[4:5], v[8:9], v[42:43], v[4:5]
	v_cvt_pk_bf16_f32 v60, v62, v63


; DEV float bflo(unsigned u) { return __uint_as_float(u << 16); }
; DEV float bfhi(unsigned u) { return __uint_as_float(u & 0xffff0000u); }
; DEV float silu_f(float x) { return x / (1.f + __expf(-x)); }
; DEV void gdn_prep_chunk(const Params& p, int item, unsigned char* lds) {
;     ...
;                     const uint4 u = raw[r + j];
;                     const unsigned wd = (e < 2 ? u.x : (e < 4 ? u.y : (e < 6 ? u.z : u.w)));
;                     const float xv = (e & 1) ? bfhi(wd) : bflo(wd);
;                     a += w[j][e] * xv;
;     ...
;                 y[e] = silu_f(a); ss += y[e] * y[e];
	v_rcp_f32_e32 v26, v23
	s_nop 0
	v_mul_f32_e32 v19, v19, v26
	v_lshlrev_b32_e32 v26, 16, v35
	v_and_b32_e32 v27, 0xffff0000, v35
	v_pk_fma_f32 v[20:21], v[32:33], v[26:27], v[20:21]

; DEV float silu_f(float x) { return x / (1.f + __expf(-x)); }
; DEV void gdn_prep_chunk(const Params& p, int item, unsigned char* lds) {
;     ...
;                 y[e] = silu_f(a); ss += y[e] * y[e];
	v_mul_f32_e32 v24, 0xbfb8aa3b, v20
	v_mul_f32_e32 v25, 0xbfb8aa3b, v21
	v_exp_f32_e32 v24, v24
	v_exp_f32_e32 v25, v25


; DEV float silu_f(float x) { return x / (1.f + __expf(-x)); }
; DEV void gdn_prep_chunk(const Params& p, int item, unsigned char* lds) {
;     ...
;                 y[e] = silu_f(a); ss += y[e] * y[e];
	s_nop 0
	v_pk_add_f32 v[24:25], v[24:25], 1.0 op_sel_hi:[1,0]


; DEV float silu_f(float x) { return x / (1.f + __expf(-x)); }
; DEV void gdn_prep_chunk(const Params& p, int item, unsigned char* lds) {
;     ...
;                 y[e] = silu_f(a); ss += y[e] * y[e];
	v_rcp_f32_e32 v23, v22
	s_nop 0
	v_mul_f32_e32 v18, v18, v23


; DEV float bflo(unsigned u) { return __uint_as_float(u << 16); }
; DEV float bfhi(unsigned u) { return __uint_as_float(u & 0xffff0000u); }
; DEV float silu_f(float x) { return x / (1.f + __expf(-x)); }
; DEV void gdn_prep_chunk(const Params& p, int item, unsigned char* lds) {
;     ...
;                     const uint4 u = raw[r + j];
;                     const unsigned wd = (e < 2 ? u.x : (e < 4 ? u.y : (e < 6 ? u.z : u.w)));
;                     const float xv = (e & 1) ? bfhi(wd) : bflo(wd);
;     ...
;                 y[e] = silu_f(a); ss += y[e] * y[e];
	v_rcp_f32_e32 v22, v25
	s_nop 0
	v_mul_f32_e32 v21, v21, v22
	v_and_b32_e32 v23, 0xffff0000, v36


; DEV float bflo(unsigned u) { return __uint_as_float(u << 16); }
; DEV float bfhi(unsigned u) { return __uint_as_float(u & 0xffff0000u); }
; DEV void gdn_prep_chunk(const Params& p, int item, unsigned char* lds) {
;     ...
;                     const uint4 u = raw[r + j];
;                     const unsigned wd = (e < 2 ? u.x : (e < 4 ? u.y : (e < 6 ? u.z : u.w)));
;                     const float xv = (e & 1) ? bfhi(wd) : bflo(wd);
;                     a += w[j][e] * xv;
	v_lshlrev_b32_e32 v22, 16, v36
	v_pk_fma_f32 v[2:3], v[14:15], v[22:23], v[2:3]

; DEV float silu_f(float x) { return x / (1.f + __expf(-x)); }
; DEV void gdn_prep_chunk(const Params& p, int item, unsigned char* lds) {
;     ...
;                 y[e] = silu_f(a); ss += y[e] * y[e];
	v_mul_f32_e32 v6, 0xbfb8aa3b, v2
	v_mul_f32_e32 v7, 0xbfb8aa3b, v3
	v_exp_f32_e32 v6, v6
	v_exp_f32_e32 v7, v7


; DEV float silu_f(float x) { return x / (1.f + __expf(-x)); }
; DEV void gdn_prep_chunk(const Params& p, int item, unsigned char* lds) {
;     ...
;                 y[e] = silu_f(a); ss += y[e] * y[e];
	s_nop 0
	v_pk_add_f32 v[6:7], v[6:7], 1.0 op_sel_hi:[1,0]


; DEV float silu_f(float x) { return x / (1.f + __expf(-x)); }
; DEV void gdn_prep_chunk(const Params& p, int item, unsigned char* lds) {
;     ...
;                     a += w[j][e] * xv;
;     ...
;                 y[e] = silu_f(a); ss += y[e] * y[e];
	v_rcp_f32_e32 v10, v24
	s_nop 0
	v_mul_f32_e32 v20, v20, v10
	v_pk_fma_f32 v[4:5], v[12:13], v[38:39], v[4:5]


; DEV float bflo(unsigned u) { return __uint_as_float(u << 16); }
; DEV float bfhi(unsigned u) { return __uint_as_float(u & 0xffff0000u); }
; DEV float silu_f(float x) { return x / (1.f + __expf(-x)); }
; DEV void gdn_prep_chunk(const Params& p, int item, unsigned char* lds) {
;     ...
;                     const uint4 u = raw[r + j];
;                     const unsigned wd = (e < 2 ? u.x : (e < 4 ? u.y : (e < 6 ? u.z : u.w)));
;                     const float xv = (e & 1) ? bfhi(wd) : bflo(wd);
;                     a += w[j][e] * xv;
;     ...
;                 y[e] = silu_f(a); ss += y[e] * y[e];
	v_rcp_f32_e32 v10, v7
	s_nop 0
	v_mul_f32_e32 v3, v3, v10
	v_lshlrev_b32_e32 v10, 16, v37
	v_and_b32_e32 v11, 0xffff0000, v37
	v_pk_fma_f32 v[4:5], v[16:17], v[10:11], v[4:5]

; DEV float silu_f(float x) { return x / (1.f + __expf(-x)); }
; DEV void gdn_prep_chunk(const Params& p, int item, unsigned char* lds) {
;     ...
;                 y[e] = silu_f(a); ss += y[e] * y[e];
	v_mul_f32_e32 v8, 0xbfb8aa3b, v4
	v_mul_f32_e32 v9, 0xbfb8aa3b, v5
	v_exp_f32_e32 v8, v8
	v_exp_f32_e32 v9, v9


; DEV float silu_f(float x) { return x / (1.f + __expf(-x)); }
; DEV void gdn_prep_chunk(const Params& p, int item, unsigned char* lds) {
;     ...
;                 y[e] = silu_f(a); ss += y[e] * y[e];
	s_nop 0
	v_pk_add_f32 v[8:9], v[8:9], 1.0 op_sel_hi:[1,0]


; DEV float silu_f(float x) { return x / (1.f + __expf(-x)); }
; DEV void gdn_prep_chunk(const Params& p, int item, unsigned char* lds) {
;     ...
;                 y[e] = silu_f(a); ss += y[e] * y[e];
	v_rcp_f32_e32 v7, v6
	s_nop 0
	v_mul_f32_e32 v2, v2, v7


; DEV unsigned cvt_pk_bf16(float lo, float hi) { const f32x2_t v = {lo, hi}; const bf16x2_t b = __builtin_convertvector(v, bf16x2_t); return __builtin_bit_cast(unsigned, b); }
; DEV float silu_f(float x) { return x / (1.f + __expf(-x)); }
; DEV void gdn_prep_chunk(const Params& p, int item, unsigned char* lds) {
;     ...
;                 y[e] = silu_f(a); ss += y[e] * y[e];
;     ...
;             uint4 o; o.x = cvt_pk_bf16(y[0], y[1]); o.y = cvt_pk_bf16(y[2], y[3]); o.z = cvt_pk_bf16(y[4], y[5]); o.w = cvt_pk_bf16(y[6], y[7]);
	v_rcp_f32_e32 v6, v9
	s_nop 0
	v_mul_f32_e32 v5, v5, v6
	v_cvt_pk_bf16_f32 v61, v56, v57


; DEV unsigned cvt_pk_bf16(float lo, float hi) { const f32x2_t v = {lo, hi}; const bf16x2_t b = __builtin_convertvector(v, bf16x2_t); return __builtin_bit_cast(unsigned, b); }
; DEV float silu_f(float x) { return x / (1.f + __expf(-x)); }
; DEV void gdn_prep_chunk(const Params& p, int item, unsigned char* lds) {
;     ...
;                 y[e] = silu_f(a); ss += y[e] * y[e];
;             }
;             if (mat < 2) {
;                 ss += __shfl_xor(ss, 1); ss += __shfl_xor(ss, 2); ss += __shfl_xor(ss, 4); ss += __shfl_xor(ss, 8);
;                 float inv = rsqrtf(ss + EPS); if (mat == 0) inv *= 0.08838834764831845f;
; #pragma unroll
;                 for (int e = 0; e < 8; ++e) y[e] *= inv;
;             }
;             uint4 o; o.x = cvt_pk_bf16(y[0], y[1]); o.y = cvt_pk_bf16(y[2], y[3]); o.z = cvt_pk_bf16(y[4], y[5]); o.w = cvt_pk_bf16(y[6], y[7]);
;             *(uint4*)(dst + (tl0 + r) * QS + cv * 8) = o;
	v_cvt_pk_bf16_f32 v62, v54, v55
	v_cvt_pk_bf16_f32 v63, v40, v41
	v_rcp_f32_e32 v6, v8
	s_nop 0
	v_mul_f32_e32 v4, v4, v6
	ds_write_b128 v104, v[60:63] offset:2176
	s_and_saveexec_b64 s[36:37], s[6:7]
	s_cbranch_execz .LBB0_504
	v_pk_mul_f32 v[6:7], v[18:19], v[18:19]
	v_pk_mul_f32 v[8:9], v[20:21], v[20:21]
	v_add_f32_e32 v6, v6, v7
	v_add_f32_e32 v6, v6, v8
	v_pk_mul_f32 v[10:11], v[2:3], v[2:3]
	v_add_f32_e32 v6, v9, v6
	v_and_b32_e32 v8, 64, v182
	v_add_f32_e32 v6, v10, v6
	v_xor_b32_e32 v7, 1, v182
	v_add_u32_e32 v8, 64, v8
	v_pk_mul_f32 v[12:13], v[4:5], v[4:5]
	v_add_f32_e32 v6, v11, v6
	v_cmp_lt_i32_e32 vcc, v7, v8
	v_add_f32_e32 v6, v12, v6
	v_add_f32_e32 v6, v13, v6
	v_cndmask_b32_e32 v7, v182, v7, vcc
	v_lshlrev_b32_e32 v7, 2, v7
	ds_bpermute_b32 v7, v7, v6
	s_waitcnt lgkmcnt(0)
	v_add_f32_e32 v6, v6, v7
	v_xor_b32_e32 v7, 2, v182
	v_cmp_lt_i32_e32 vcc, v7, v8
	s_nop 1
	v_cndmask_b32_e32 v7, v182, v7, vcc
	v_lshlrev_b32_e32 v7, 2, v7
	ds_bpermute_b32 v7, v7, v6
	s_waitcnt lgkmcnt(0)
	v_add_f32_e32 v6, v6, v7
	v_xor_b32_e32 v7, 4, v182
	v_cmp_lt_i32_e32 vcc, v7, v8
	s_nop 1
	v_cndmask_b32_e32 v7, v182, v7, vcc
	v_lshlrev_b32_e32 v7, 2, v7
	ds_bpermute_b32 v7, v7, v6
	s_waitcnt lgkmcnt(0)
	v_add_f32_e32 v6, v6, v7
	v_xor_b32_e32 v7, 8, v182
	v_cmp_lt_i32_e32 vcc, v7, v8
	s_nop 1
	v_cndmask_b32_e32 v7, v182, v7, vcc
	v_lshlrev_b32_e32 v7, 2, v7
	ds_bpermute_b32 v7, v7, v6
	s_waitcnt lgkmcnt(0)
	v_add_f32_e32 v6, v6, v7
	v_add_f32_e32 v6, 0x358637bd, v6
	v_mul_f32_e32 v7, 0x4b800000, v6
	v_cmp_gt_f32_e32 vcc, s56, v6
	s_nop 1
	v_cndmask_b32_e32 v6, v6, v7, vcc
	v_rsq_f32_e32 v6, v6
	s_nop 0
	v_mul_f32_e32 v7, 0x45800000, v6
	v_cndmask_b32_e32 v6, v6, v7, vcc
	v_mul_f32_e32 v7, 0x3db504f3, v6
	v_cndmask_b32_e64 v6, v6, v7, s[4:5]
	v_pk_mul_f32 v[18:19], v[18:19], v[6:7] op_sel_hi:[1,0]
	v_pk_mul_f32 v[20:21], v[20:21], v[6:7] op_sel_hi:[1,0]
	v_pk_mul_f32 v[2:3], v[2:3], v[6:7] op_sel_hi:[1,0]
	v_pk_mul_f32 v[4:5], v[4:5], v[6:7] op_sel_hi:[1,0]

; DEV void gdn_prep_chunk(const Params& p, int item, unsigned char* lds) {
;     ...
;         float a = 0.f, bb = 0.f;
; #pragma unroll
;         for (int kq = 0; kq < 4; ++kq) { a += ab[(size_t)kq * TT * 16 + (size_t)(row0 + lane) * 16 + h]; bb += ab[(size_t)kq * TT * 16 + (size_t)(row0 + lane) * 16 + 8 + h]; }
;         const float xx = a + p.in[12][h];
;         const float sp = xx > 20.f ? xx : log1pf(__expf(xx));
;         float s = -__expf(p.in[11][h]) * sp;
; #pragma unroll
;         for (int d = 1; d < 64; d <<= 1) { const float t = __shfl_up(s, d); if (lane >= d) s += t; }
;         gcs[lane] = s; bts[lane] = 1.f / (1.f + __expf(-bb));
.LBB0_508:
	s_or_b64 exec, exec, s[4:5]
	v_mov_b32_e32 v7, s22
	global_load_dword v7, v7, s[10:11]
	v_and_b32_e32 v8, 64, v182
	v_add_u32_e32 v9, -1, v182
	v_add_f32_e32 v5, 0, v5
	v_add_u32_e32 v10, -2, v182
	v_cmp_lt_i32_e32 vcc, v9, v8
	v_add_u32_e32 v11, -4, v182
	s_waitcnt vmcnt(3)
	v_add_f32_e32 v4, v5, v4
	v_cndmask_b32_e32 v5, v9, v182, vcc
	v_cmp_lt_i32_e32 vcc, v10, v8
	v_add_u32_e32 v12, -8, v182
	v_add_u32_e32 v13, -16, v182
	v_cndmask_b32_e32 v9, v10, v182, vcc
	v_cmp_lt_i32_e32 vcc, v11, v8
	v_lshlrev_b32_e32 v5, 2, v5
	v_subrev_u32_e32 v14, 32, v182
	v_cndmask_b32_e32 v10, v11, v182, vcc
	v_cmp_lt_i32_e32 vcc, v12, v8
	s_waitcnt vmcnt(2)
	v_add_f32_e32 v3, v4, v3
	v_lshlrev_b32_e32 v4, 2, v9
	v_cndmask_b32_e32 v11, v12, v182, vcc
	v_cmp_lt_i32_e32 vcc, v13, v8
	s_waitcnt vmcnt(1)
	v_add_f32_e32 v2, v3, v2
	v_mul_f32_e32 v2, 0xbfb8aa3b, v2
	v_cndmask_b32_e32 v12, v13, v182, vcc
	v_cmp_lt_i32_e32 vcc, v14, v8
	v_exp_f32_e32 v2, v2
	v_lshl_add_u32 v15, v34, 2, s39
	v_cndmask_b32_e32 v8, v14, v182, vcc
	v_cmp_eq_u32_e32 vcc, 0, v34
	v_add_f32_e32 v2, 1.0, v2
	s_waitcnt vmcnt(0)
	v_mul_f32_e32 v7, 0x3fb8aa3b, v7
	v_exp_f32_e32 v7, v7
	s_nop 0
	v_mul_f32_e64 v13, v6, -v7
	ds_bpermute_b32 v5, v5, v13
	s_waitcnt lgkmcnt(0)
	v_fma_f32 v5, v6, -v7, v5
	v_cndmask_b32_e32 v5, v5, v13, vcc
	ds_bpermute_b32 v4, v4, v5
	v_cmp_gt_u32_e32 vcc, 2, v34
	v_lshlrev_b32_e32 v6, 2, v10
	v_lshlrev_b32_e32 v7, 2, v8
	s_waitcnt lgkmcnt(0)
	v_add_f32_e32 v3, v5, v4
	v_cndmask_b32_e32 v3, v3, v5, vcc
	ds_bpermute_b32 v4, v6, v3
	v_cmp_gt_u32_e32 vcc, 4, v34
	v_lshlrev_b32_e32 v5, 2, v11
	v_lshlrev_b32_e32 v6, 2, v12
	s_waitcnt lgkmcnt(0)
	v_add_f32_e32 v4, v3, v4
	v_cndmask_b32_e32 v3, v4, v3, vcc
	ds_bpermute_b32 v4, v5, v3

; DEV void gdn_prep_chunk(const Params& p, int item, unsigned char* lds) {
;     ...
;         for (int d = 1; d < 64; d <<= 1) { const float t = __shfl_up(s, d); if (lane >= d) s += t; }
	v_cmp_gt_u32_e64 s[4:5], 8, v34

; DEV void gdn_prep_chunk(const Params& p, int item, unsigned char* lds) {
;     ...
;         for (int d = 1; d < 64; d <<= 1) { const float t = __shfl_up(s, d); if (lane >= d) s += t; }
	s_waitcnt lgkmcnt(0)
	v_add_f32_e32 v4, v3, v4
	v_cndmask_b32_e64 v3, v4, v3, s[4:5]
	ds_bpermute_b32 v4, v6, v3
	v_cmp_gt_u32_e64 s[4:5], 16, v34


; DEV void gdn_prep_chunk(const Params& p, int item, unsigned char* lds) {
;     ...
;         for (int d = 1; d < 64; d <<= 1) { const float t = __shfl_up(s, d); if (lane >= d) s += t; }
	s_waitcnt lgkmcnt(0)
	v_add_f32_e32 v4, v3, v4
	v_cndmask_b32_e64 v3, v4, v3, s[4:5]

; DEV void gdn_prep_chunk(const Params& p, int item, unsigned char* lds) {
;     ...
;         for (int d = 1; d < 64; d <<= 1) { const float t = __shfl_up(s, d); if (lane >= d) s += t; }
	ds_bpermute_b32 v4, v7, v3


; DEV void gdn_prep_chunk(const Params& p, int item, unsigned char* lds) {
;     ...
;         for (int d = 1; d < 64; d <<= 1) { const float t = __shfl_up(s, d); if (lane >= d) s += t; }
;         gcs[lane] = s; bts[lane] = 1.f / (1.f + __expf(-bb));
	s_waitcnt lgkmcnt(0)
	v_add_f32_e32 v4, v3, v4
	v_cmp_gt_u32_e32 vcc, 32, v34
	v_rcp_f32_e32 v5, v2
	s_nop 0
	v_mul_f32_e32 v2, 1.0, v5
	s_nop 0
	v_cndmask_b32_e32 v3, v4, v3, vcc
	ds_write2st64_b32 v15, v3, v2 offset0:204 offset1:205

; DEV float bflo(unsigned u) { return __uint_as_float(u << 16); }
; DEV float bfhi(unsigned u) { return __uint_as_float(u & 0xffff0000u); }
; template <int WIN>
; DEV void pool_d_prompt8(const bf16_t* __restrict__ proj, bf16_t* __restrict__ dpl, int row0, int c8) {
;     ...
;     for (int i = 0; i < WIN + 7; ++i) { const int tt = t0 - (WIN - 1) + i; u[i] = (tt >= 0) ? *(const uint4*)(proj + (size_t)(row0 - (WIN - 1) + i) * NPJ + C_U + c8) : make_uint4(0u, 0u, 0u, 0u); }
;     float acc[8] = {0.f, 0.f, 0.f, 0.f, 0.f, 0.f, 0.f, 0.f};
; #pragma unroll
;     for (int i = 0; i < WIN - 1; ++i) { acc[0] += bflo(u[i].x); acc[1] += bfhi(u[i].x); acc[2] += bflo(u[i].y); acc[3] += bfhi(u[i].y); acc[4] += bflo(u[i].z); acc[5] += bfhi(u[i].z); acc[6] += bflo(u[i].w); acc[7] += bfhi(u[i].w); }
; #pragma unroll
;     for (int j = 0; j < 8; ++j) {
;         const uint4 x = u[j + WIN - 1];
;         const float xs[8] = {bflo(x.x), bfhi(x.x), bflo(x.y), bfhi(x.y), bflo(x.z), bfhi(x.z), bflo(x.w), bfhi(x.w)};
; #pragma unroll
;         for (int e_ = 0; e_ < 8; ++e_) acc[e_] += xs[e_];
;         const float ic = 1.f / (float)min(WIN, t0 + j + 1);
.LBB0_681:
	s_or_b64 exec, exec, s[16:17]
	v_mad_i64_i32 v[2:3], s[16:17], v145, s25, v[172:173]
	v_lshlrev_b32_e32 v94, 1, v143
	v_lshl_add_u64 v[2:3], v[2:3], 0, v[94:95]
	v_add_co_u32_e32 v2, vcc, 0x2000, v2
	v_or_b32_e32 v66, 1, v145
	s_nop 0
	v_addc_co_u32_e32 v3, vcc, 0, v3, vcc
	global_load_dwordx4 v[16:19], v[2:3], off
	v_mad_i64_i32 v[2:3], s[16:17], v66, s25, v[172:173]
	v_lshl_add_u64 v[2:3], v[2:3], 0, v[94:95]
	v_or_b32_e32 v69, 4, v145
	v_or_b32_e32 v70, 5, v145
	v_add_co_u32_e32 v2, vcc, 0x2000, v2
	v_mad_i64_i32 v[20:21], s[16:17], v69, s25, v[172:173]
	v_mad_i64_i32 v[22:23], s[16:17], v70, s25, v[172:173]
	v_addc_co_u32_e32 v3, vcc, 0, v3, vcc
	v_lshl_add_u64 v[32:33], v[20:21], 0, v[94:95]
	v_lshl_add_u64 v[34:35], v[22:23], 0, v[94:95]
	global_load_dwordx4 v[20:23], v[2:3], off
	v_or_b32_e32 v67, 2, v145
	v_mad_i64_i32 v[4:5], s[16:17], v67, s25, v[172:173]
	v_or_b32_e32 v68, 3, v145
	v_lshl_add_u64 v[4:5], v[4:5], 0, v[94:95]
	v_mad_i64_i32 v[12:13], s[16:17], v68, s25, v[172:173]
	v_add_co_u32_e32 v4, vcc, 0x2000, v4
	v_or_b32_e32 v72, 6, v145
	v_or_b32_e32 v96, 7, v98
	v_lshl_add_u64 v[12:13], v[12:13], 0, v[94:95]
	v_addc_co_u32_e32 v5, vcc, 0, v5, vcc
	v_mad_i64_i32 v[24:25], s[16:17], v72, s25, v[172:173]
	v_mad_i64_i32 v[26:27], s[16:17], v96, s25, v[172:173]
	v_add_co_u32_e32 v2, vcc, 0x2000, v12
	v_lshl_add_u64 v[40:41], v[24:25], 0, v[94:95]
	v_lshl_add_u64 v[42:43], v[26:27], 0, v[94:95]
	v_addc_co_u32_e32 v3, vcc, 0, v13, vcc
	global_load_dwordx4 v[24:27], v[4:5], off
	global_load_dwordx4 v[28:31], v[2:3], off
	v_add_co_u32_e32 v12, vcc, 0x2000, v32

; DEV float bflo(unsigned u) { return __uint_as_float(u << 16); }
; DEV float bfhi(unsigned u) { return __uint_as_float(u & 0xffff0000u); }
; template <int WIN>
; DEV void pool_d_prompt8(const bf16_t* __restrict__ proj, bf16_t* __restrict__ dpl, int row0, int c8) {
;     ...
;     for (int i = 0; i < WIN + 7; ++i) { const int tt = t0 - (WIN - 1) + i; u[i] = (tt >= 0) ? *(const uint4*)(proj + (size_t)(row0 - (WIN - 1) + i) * NPJ + C_U + c8) : make_uint4(0u, 0u, 0u, 0u); }
;     float acc[8] = {0.f, 0.f, 0.f, 0.f, 0.f, 0.f, 0.f, 0.f};
; #pragma unroll
;     for (int i = 0; i < WIN - 1; ++i) { acc[0] += bflo(u[i].x); acc[1] += bfhi(u[i].x); acc[2] += bflo(u[i].y); acc[3] += bfhi(u[i].y); acc[4] += bflo(u[i].z); acc[5] += bfhi(u[i].z); acc[6] += bflo(u[i].w); acc[7] += bfhi(u[i].w); }
; #pragma unroll
;     for (int j = 0; j < 8; ++j) {
;         const uint4 x = u[j + WIN - 1];
;         const float xs[8] = {bflo(x.x), bfhi(x.x), bflo(x.y), bfhi(x.y), bflo(x.z), bfhi(x.z), bflo(x.w), bfhi(x.w)};
; #pragma unroll
;         for (int e_ = 0; e_ < 8; ++e_) acc[e_] += xs[e_];
;         const float ic = 1.f / (float)min(WIN, t0 + j + 1);
	s_nop 0
	s_nop 0
	v_addc_co_u32_e32 v13, vcc, 0, v33, vcc
	v_add_co_u32_e32 v2, vcc, 0x2000, v34

; DEV float bflo(unsigned u) { return __uint_as_float(u << 16); }
; DEV float bfhi(unsigned u) { return __uint_as_float(u & 0xffff0000u); }
; template <int WIN>
; DEV void pool_d_prompt8(const bf16_t* __restrict__ proj, bf16_t* __restrict__ dpl, int row0, int c8) {
;     ...
;     for (int i = 0; i < WIN + 7; ++i) { const int tt = t0 - (WIN - 1) + i; u[i] = (tt >= 0) ? *(const uint4*)(proj + (size_t)(row0 - (WIN - 1) + i) * NPJ + C_U + c8) : make_uint4(0u, 0u, 0u, 0u); }
;     float acc[8] = {0.f, 0.f, 0.f, 0.f, 0.f, 0.f, 0.f, 0.f};
; #pragma unroll
;     for (int i = 0; i < WIN - 1; ++i) { acc[0] += bflo(u[i].x); acc[1] += bfhi(u[i].x); acc[2] += bflo(u[i].y); acc[3] += bfhi(u[i].y); acc[4] += bflo(u[i].z); acc[5] += bfhi(u[i].z); acc[6] += bflo(u[i].w); acc[7] += bfhi(u[i].w); }
; #pragma unroll
;     for (int j = 0; j < 8; ++j) {
;         const uint4 x = u[j + WIN - 1];
;         const float xs[8] = {bflo(x.x), bfhi(x.x), bflo(x.y), bfhi(x.y), bflo(x.z), bfhi(x.z), bflo(x.w), bfhi(x.w)};
; #pragma unroll
;         for (int e_ = 0; e_ < 8; ++e_) acc[e_] += xs[e_];
;         const float ic = 1.f / (float)min(WIN, t0 + j + 1);
	s_nop 0
	s_nop 0
	v_addc_co_u32_e32 v3, vcc, 0, v35, vcc
	global_load_dwordx4 v[32:35], v[12:13], off
	global_load_dwordx4 v[36:39], v[2:3], off
	v_add_co_u32_e32 v44, vcc, 0x2000, v40
	v_lshl_add_u64 v[10:11], v[140:141], 0, v[94:95]
	s_nop 0
	v_addc_co_u32_e32 v45, vcc, 0, v41, vcc
	v_add_co_u32_e32 v12, vcc, s26, v42
	v_ashrrev_i32_e32 v97, 31, v96
	s_nop 0
	v_addc_co_u32_e32 v13, vcc, 0, v43, vcc
	global_load_dwordx4 v[40:43], v[44:45], off
	global_load_dwordx4 v[2:5], v[12:13], off
	s_waitcnt vmcnt(7)
	v_lshlrev_b32_e32 v46, 16, v18
	v_and_b32_e32 v47, 0xffff0000, v18


; DEV float bflo(unsigned u) { return __uint_as_float(u << 16); }
; DEV float bfhi(unsigned u) { return __uint_as_float(u & 0xffff0000u); }
; template <int WIN>
; DEV void pool_d_prompt8(const bf16_t* __restrict__ proj, bf16_t* __restrict__ dpl, int row0, int c8) {
;     ...
;         const uint4 x = u[j + WIN - 1];
;         const float xs[8] = {bflo(x.x), bfhi(x.x), bflo(x.y), bfhi(x.y), bflo(x.z), bfhi(x.z), bflo(x.w), bfhi(x.w)};
; #pragma unroll
;         for (int e_ = 0; e_ < 8; ++e_) acc[e_] += xs[e_];
;         const float ic = 1.f / (float)min(WIN, t0 + j + 1);
	v_lshlrev_b32_e32 v12, 16, v19
	v_and_b32_e32 v13, 0xffff0000, v19


; DEV unsigned cvt_pk_bf16(float lo, float hi) { const f32x2_t v = {lo, hi}; const bf16x2_t b = __builtin_convertvector(v, bf16x2_t); return __builtin_bit_cast(unsigned, b); }
; DEV float bflo(unsigned u) { return __uint_as_float(u << 16); }
; DEV float bfhi(unsigned u) { return __uint_as_float(u & 0xffff0000u); }
; template <int WIN>
; DEV void pool_d_prompt8(const bf16_t* __restrict__ proj, bf16_t* __restrict__ dpl, int row0, int c8) {
;     ...
;     for (int j = 0; j < 8; ++j) {
;         const uint4 x = u[j + WIN - 1];
;         const float xs[8] = {bflo(x.x), bfhi(x.x), bflo(x.y), bfhi(x.y), bflo(x.z), bfhi(x.z), bflo(x.w), bfhi(x.w)};
; #pragma unroll
;         for (int e_ = 0; e_ < 8; ++e_) acc[e_] += xs[e_];
;         const float ic = 1.f / (float)min(WIN, t0 + j + 1);
;         uint4 o;
;         o.x = cvt_pk_bf16(acc[0] * ic - xs[0], acc[1] * ic - xs[1]); o.y = cvt_pk_bf16(acc[2] * ic - xs[2], acc[3] * ic - xs[3]);
;         o.z = cvt_pk_bf16(acc[4] * ic - xs[4], acc[5] * ic - xs[5]); o.w = cvt_pk_bf16(acc[6] * ic - xs[6], acc[7] * ic - xs[7]);
;         *(uint4*)(dpl + (size_t)(row0 + j) * LDP + c8) = o;
;         const uint4 y = u[j];
;         acc[0] -= bflo(y.x); acc[1] -= bfhi(y.x); acc[2] -= bflo(y.y); acc[3] -= bfhi(y.y); acc[4] -= bflo(y.z); acc[5] -= bfhi(y.z); acc[6] -= bflo(y.w); acc[7] -= bfhi(y.w);
	v_lshlrev_b32_e32 v18, 16, v6
	v_and_b32_e32 v19, 0xffff0000, v6
	v_lshlrev_b32_e32 v44, 16, v16
	v_and_b32_e32 v45, 0xffff0000, v16
	v_pk_add_f32 v[48:49], v[18:19], 0 op_sel_hi:[1,0]
	v_rcp_f32_e32 v15, v14
	s_nop 0
	v_mul_f32_e32 v14, 1.0, v15
	v_pk_add_f32 v[48:49], v[48:49], v[44:45]
	v_lshlrev_b32_e32 v16, 16, v17
	v_pk_fma_f32 v[50:51], v[14:15], v[48:49], v[44:45] op_sel_hi:[0,1,1] neg_lo:[0,0,1] neg_hi:[0,0,1]
	v_cvt_pk_bf16_f32 v6, v50, v51
	v_lshlrev_b32_e32 v50, 16, v7
	v_and_b32_e32 v51, 0xffff0000, v7
	v_and_b32_e32 v17, 0xffff0000, v17
	v_pk_add_f32 v[52:53], v[50:51], 0 op_sel_hi:[1,0]
	s_waitcnt vmcnt(6)
	v_lshlrev_b32_e32 v62, 16, v22
	v_pk_add_f32 v[52:53], v[52:53], v[16:17]
	v_and_b32_e32 v63, 0xffff0000, v22
	v_pk_fma_f32 v[54:55], v[14:15], v[52:53], v[16:17] op_sel_hi:[0,1,1] neg_lo:[0,0,1] neg_hi:[0,0,1]
	v_cvt_pk_bf16_f32 v7, v54, v55
	v_lshlrev_b32_e32 v54, 16, v8
	v_and_b32_e32 v55, 0xffff0000, v8
	v_pk_add_f32 v[56:57], v[54:55], 0 op_sel_hi:[1,0]
	v_lshlrev_b32_e32 v64, 16, v23
	v_pk_add_f32 v[56:57], v[56:57], v[46:47]
	v_and_b32_e32 v65, 0xffff0000, v23
	v_pk_fma_f32 v[58:59], v[14:15], v[56:57], v[46:47] op_sel_hi:[0,1,1] neg_lo:[0,0,1] neg_hi:[0,0,1]
	v_cvt_pk_bf16_f32 v8, v58, v59
	v_lshlrev_b32_e32 v58, 16, v9
	v_and_b32_e32 v59, 0xffff0000, v9
	v_pk_add_f32 v[60:61], v[58:59], 0 op_sel_hi:[1,0]
	s_waitcnt vmcnt(1)
	v_and_b32_e32 v71, 0xffff0000, v42
	v_pk_add_f32 v[60:61], v[60:61], v[12:13]
	s_nop 0
	v_pk_fma_f32 v[14:15], v[14:15], v[60:61], v[12:13] op_sel_hi:[0,1,1] neg_lo:[0,0,1] neg_hi:[0,0,1]
	v_cvt_pk_bf16_f32 v9, v14, v15
	v_mad_i64_i32 v[14:15], s[16:17], v145, s27, v[10:11]
	global_store_dwordx4 v[14:15], v[6:9], off
	v_lshlrev_b32_e32 v14, 16, v20
	v_and_b32_e32 v15, 0xffff0000, v20
	v_lshlrev_b32_e32 v20, 16, v21
	v_and_b32_e32 v21, 0xffff0000, v21
	v_pk_add_f32 v[6:7], v[48:49], v[18:19] neg_lo:[0,1] neg_hi:[0,1]
	v_pk_add_f32 v[8:9], v[52:53], v[50:51] neg_lo:[0,1] neg_hi:[0,1]
	v_pk_add_f32 v[18:19], v[6:7], v[14:15]
	v_pk_add_f32 v[22:23], v[8:9], v[20:21]
	v_pk_fma_f32 v[6:7], v[18:19], 0.5, v[14:15] op_sel_hi:[1,0,1] neg_lo:[0,0,1] neg_hi:[0,0,1]
	v_pk_fma_f32 v[8:9], v[22:23], 0.5, v[20:21] op_sel_hi:[1,0,1] neg_lo:[0,0,1] neg_hi:[0,0,1]
	v_cvt_pk_bf16_f32 v6, v6, v7
	v_cvt_pk_bf16_f32 v7, v8, v9
	v_pk_add_f32 v[8:9], v[56:57], v[54:55] neg_lo:[0,1] neg_hi:[0,1]
	v_pk_add_f32 v[50:51], v[60:61], v[58:59] neg_lo:[0,1] neg_hi:[0,1]
	v_pk_add_f32 v[48:49], v[8:9], v[62:63]
	v_pk_add_f32 v[50:51], v[50:51], v[64:65]
	v_pk_fma_f32 v[8:9], v[48:49], 0.5, v[62:63] op_sel_hi:[1,0,1] neg_lo:[0,0,1] neg_hi:[0,0,1]
	v_pk_fma_f32 v[52:53], v[50:51], 0.5, v[64:65] op_sel_hi:[1,0,1] neg_lo:[0,0,1] neg_hi:[0,0,1]
	v_cvt_pk_bf16_f32 v8, v8, v9
	v_cvt_pk_bf16_f32 v9, v52, v53
	v_mad_i64_i32 v[52:53], s[16:17], v66, s27, v[10:11]
	global_store_dwordx4 v[52:53], v[6:9], off
	v_lshlrev_b32_e32 v52, 16, v24
	v_and_b32_e32 v53, 0xffff0000, v24
	v_lshlrev_b32_e32 v24, 16, v25
	v_and_b32_e32 v25, 0xffff0000, v25
	v_pk_add_f32 v[6:7], v[18:19], v[44:45] neg_lo:[0,1] neg_hi:[0,1]
	v_pk_add_f32 v[8:9], v[22:23], v[16:17] neg_lo:[0,1] neg_hi:[0,1]
	v_pk_add_f32 v[18:19], v[6:7], v[52:53]
	v_pk_add_f32 v[16:17], v[8:9], v[24:25]
	v_lshlrev_b32_e32 v54, 16, v26
	v_and_b32_e32 v55, 0xffff0000, v26
	v_lshlrev_b32_e32 v56, 16, v27
	v_and_b32_e32 v57, 0xffff0000, v27
	v_pk_fma_f32 v[6:7], v[18:19], 0.5, v[52:53] op_sel_hi:[1,0,1] neg_lo:[0,0,1] neg_hi:[0,0,1]
	v_pk_fma_f32 v[8:9], v[16:17], 0.5, v[24:25] op_sel_hi:[1,0,1] neg_lo:[0,0,1] neg_hi:[0,0,1]
	v_lshlrev_b32_e32 v26, 16, v28
	v_and_b32_e32 v27, 0xffff0000, v28
	v_lshlrev_b32_e32 v28, 16, v29
	v_and_b32_e32 v29, 0xffff0000, v29
	v_pk_add_f32 v[14:15], v[18:19], v[14:15] neg_lo:[0,1] neg_hi:[0,1]
	v_pk_add_f32 v[16:17], v[16:17], v[20:21] neg_lo:[0,1] neg_hi:[0,1]
	v_cvt_pk_bf16_f32 v6, v6, v7
	v_cvt_pk_bf16_f32 v7, v8, v9
	v_pk_add_f32 v[8:9], v[48:49], v[46:47] neg_lo:[0,1] neg_hi:[0,1]
	v_pk_add_f32 v[18:19], v[14:15], v[26:27]
	v_pk_add_f32 v[20:21], v[16:17], v[28:29]
	v_pk_add_f32 v[22:23], v[8:9], v[54:55]
	v_lshlrev_b32_e32 v46, 16, v30
	v_and_b32_e32 v47, 0xffff0000, v30
	v_lshlrev_b32_e32 v48, 16, v31
	v_and_b32_e32 v49, 0xffff0000, v31
	v_pk_fma_f32 v[14:15], v[18:19], 0.5, v[26:27] op_sel_hi:[1,0,1] neg_lo:[0,0,1] neg_hi:[0,0,1]
	v_pk_fma_f32 v[16:17], v[20:21], 0.5, v[28:29] op_sel_hi:[1,0,1] neg_lo:[0,0,1] neg_hi:[0,0,1]
	v_lshlrev_b32_e32 v30, 16, v32
	v_and_b32_e32 v31, 0xffff0000, v32
	v_lshlrev_b32_e32 v32, 16, v33
	v_and_b32_e32 v33, 0xffff0000, v33
	v_pk_add_f32 v[18:19], v[18:19], v[52:53] neg_lo:[0,1] neg_hi:[0,1]
	v_pk_add_f32 v[20:21], v[20:21], v[24:25] neg_lo:[0,1] neg_hi:[0,1]
	v_cvt_pk_bf16_f32 v14, v14, v15
	v_cvt_pk_bf16_f32 v15, v16, v17
	v_pk_add_f32 v[16:17], v[22:23], v[62:63] neg_lo:[0,1] neg_hi:[0,1]
	v_lshlrev_b32_e32 v60, 16, v34
	v_and_b32_e32 v61, 0xffff0000, v34
	v_lshlrev_b32_e32 v62, 16, v35
	v_and_b32_e32 v63, 0xffff0000, v35
	v_pk_add_f32 v[34:35], v[18:19], v[30:31]
	v_pk_add_f32 v[24:25], v[20:21], v[32:33]
	v_pk_fma_f32 v[8:9], v[22:23], 0.5, v[54:55] op_sel_hi:[1,0,1] neg_lo:[0,0,1] neg_hi:[0,0,1]
	v_pk_add_f32 v[22:23], v[16:17], v[46:47]
	v_pk_fma_f32 v[18:19], v[34:35], 0.5, v[30:31] op_sel_hi:[1,0,1] neg_lo:[0,0,1] neg_hi:[0,0,1]
; DEV unsigned cvt_pk_bf16(float lo, float hi) { const f32x2_t v = {lo, hi}; const bf16x2_t b = __builtin_convertvector(v, bf16x2_t); return __builtin_bit_cast(unsigned, b); }
; DEV float bflo(unsigned u) { return __uint_as_float(u << 16); }
; DEV float bfhi(unsigned u) { return __uint_as_float(u & 0xffff0000u); }
; template <int WIN>
; DEV void pool_d_prompt8(const bf16_t* __restrict__ proj, bf16_t* __restrict__ dpl, int row0, int c8) {
;     ...
;     for (int j = 0; j < 8; ++j) {
;         const uint4 x = u[j + WIN - 1];
;         const float xs[8] = {bflo(x.x), bfhi(x.x), bflo(x.y), bfhi(x.y), bflo(x.z), bfhi(x.z), bflo(x.w), bfhi(x.w)};
; #pragma unroll
;         for (int e_ = 0; e_ < 8; ++e_) acc[e_] += xs[e_];
;         const float ic = 1.f / (float)min(WIN, t0 + j + 1);
;         uint4 o;
;         o.x = cvt_pk_bf16(acc[0] * ic - xs[0], acc[1] * ic - xs[1]); o.y = cvt_pk_bf16(acc[2] * ic - xs[2], acc[3] * ic - xs[3]);
;         o.z = cvt_pk_bf16(acc[4] * ic - xs[4], acc[5] * ic - xs[5]); o.w = cvt_pk_bf16(acc[6] * ic - xs[6], acc[7] * ic - xs[7]);
;         *(uint4*)(dpl + (size_t)(row0 + j) * LDP + c8) = o;
;         const uint4 y = u[j];
;         acc[0] -= bflo(y.x); acc[1] -= bfhi(y.x); acc[2] -= bflo(y.y); acc[3] -= bfhi(y.y); acc[4] -= bflo(y.z); acc[5] -= bfhi(y.z); acc[6] -= bflo(y.w); acc[7] -= bfhi(y.w);
	v_pk_fma_f32 v[20:21], v[24:25], 0.5, v[32:33] op_sel_hi:[1,0,1] neg_lo:[0,0,1] neg_hi:[0,0,1]
	v_mad_i64_i32 v[44:45], s[16:17], v67, s27, v[10:11]
	v_pk_fma_f32 v[16:17], v[22:23], 0.5, v[46:47] op_sel_hi:[1,0,1] neg_lo:[0,0,1] neg_hi:[0,0,1]
	v_cvt_pk_bf16_f32 v18, v18, v19
	v_cvt_pk_bf16_f32 v19, v20, v21
	v_pk_add_f32 v[20:21], v[22:23], v[54:55] neg_lo:[0,1] neg_hi:[0,1]
	v_lshlrev_b32_e32 v66, 16, v36
	v_and_b32_e32 v67, 0xffff0000, v36
	v_lshlrev_b32_e32 v36, 16, v37
	v_and_b32_e32 v37, 0xffff0000, v37
	v_pk_add_f32 v[22:23], v[34:35], v[26:27] neg_lo:[0,1] neg_hi:[0,1]
	v_pk_add_f32 v[24:25], v[24:25], v[28:29] neg_lo:[0,1] neg_hi:[0,1]
	v_pk_add_f32 v[26:27], v[22:23], v[66:67]
	v_pk_add_f32 v[28:29], v[24:25], v[36:37]
	v_pk_add_f32 v[52:53], v[20:21], v[60:61]
	v_pk_fma_f32 v[22:23], v[26:27], 0.5, v[66:67] op_sel_hi:[1,0,1] neg_lo:[0,0,1] neg_hi:[0,0,1]
	v_pk_fma_f32 v[24:25], v[28:29], 0.5, v[36:37] op_sel_hi:[1,0,1] neg_lo:[0,0,1] neg_hi:[0,0,1]
	v_pk_fma_f32 v[20:21], v[52:53], 0.5, v[60:61] op_sel_hi:[1,0,1] neg_lo:[0,0,1] neg_hi:[0,0,1]
	v_cvt_pk_bf16_f32 v22, v22, v23
	v_cvt_pk_bf16_f32 v23, v24, v25
	v_pk_add_f32 v[24:25], v[52:53], v[46:47] neg_lo:[0,1] neg_hi:[0,1]
	v_lshlrev_b32_e32 v52, 16, v40
	v_and_b32_e32 v53, 0xffff0000, v40
	v_lshlrev_b32_e32 v40, 16, v41
	v_and_b32_e32 v41, 0xffff0000, v41
	v_pk_add_f32 v[26:27], v[26:27], v[30:31] neg_lo:[0,1] neg_hi:[0,1]
	v_pk_add_f32 v[28:29], v[28:29], v[32:33] neg_lo:[0,1] neg_hi:[0,1]
	v_mad_i64_i32 v[58:59], s[16:17], v68, s27, v[10:11]
	v_mad_i64_i32 v[54:55], s[16:17], v69, s27, v[10:11]
	v_lshlrev_b32_e32 v68, 16, v38
	v_and_b32_e32 v69, 0xffff0000, v38
	v_pk_add_f32 v[26:27], v[26:27], v[52:53]
	v_pk_add_f32 v[28:29], v[28:29], v[40:41]
	v_pk_add_f32 v[34:35], v[24:25], v[68:69]
	v_pk_fma_f32 v[30:31], v[26:27], 0.5, v[52:53] op_sel_hi:[1,0,1] neg_lo:[0,0,1] neg_hi:[0,0,1]
	v_pk_fma_f32 v[32:33], v[28:29], 0.5, v[40:41] op_sel_hi:[1,0,1] neg_lo:[0,0,1] neg_hi:[0,0,1]
	v_mad_i64_i32 v[46:47], s[16:17], v70, s27, v[10:11]
	v_lshlrev_b32_e32 v70, 16, v42
	v_cvt_pk_bf16_f32 v30, v30, v31
	v_cvt_pk_bf16_f32 v31, v32, v33
	v_pk_add_f32 v[32:33], v[34:35], v[60:61] neg_lo:[0,1] neg_hi:[0,1]
	s_waitcnt vmcnt(2)
	v_lshlrev_b32_e32 v40, 16, v2
	v_and_b32_e32 v41, 0xffff0000, v2
	v_lshlrev_b32_e32 v2, 16, v3
	v_and_b32_e32 v3, 0xffff0000, v3
	v_pk_add_f32 v[28:29], v[28:29], v[36:37] neg_lo:[0,1] neg_hi:[0,1]
	v_pk_fma_f32 v[24:25], v[34:35], 0.5, v[68:69] op_sel_hi:[1,0,1] neg_lo:[0,0,1] neg_hi:[0,0,1]
	v_pk_add_f32 v[34:35], v[32:33], v[70:71]
	v_pk_add_f32 v[28:29], v[28:29], v[2:3]
	v_lshlrev_b32_e32 v52, 16, v4
	v_and_b32_e32 v53, 0xffff0000, v4
	v_pk_fma_f32 v[28:29], v[28:29], 0.5, v[2:3] op_sel_hi:[1,0,1] neg_lo:[0,0,1] neg_hi:[0,0,1]
	v_pk_add_f32 v[2:3], v[34:35], v[68:69] neg_lo:[0,1] neg_hi:[0,1]
	v_pk_fma_f32 v[32:33], v[34:35], 0.5, v[70:71] op_sel_hi:[1,0,1] neg_lo:[0,0,1] neg_hi:[0,0,1]
	v_pk_add_f32 v[2:3], v[2:3], v[52:53]
	v_cvt_pk_bf16_f32 v8, v8, v9
	v_pk_fma_f32 v[34:35], v[2:3], 0.5, v[52:53] op_sel_hi:[1,0,1] neg_lo:[0,0,1] neg_hi:[0,0,1]
	v_pk_add_f32 v[2:3], v[50:51], v[12:13] neg_lo:[0,1] neg_hi:[0,1]
	v_cvt_pk_bf16_f32 v16, v16, v17
	v_pk_add_f32 v[2:3], v[2:3], v[56:57]
	v_lshlrev_b32_e32 v38, 16, v39
	v_pk_fma_f32 v[12:13], v[2:3], 0.5, v[56:57] op_sel_hi:[1,0,1] neg_lo:[0,0,1] neg_hi:[0,0,1]
	v_pk_add_f32 v[2:3], v[2:3], v[64:65] neg_lo:[0,1] neg_hi:[0,1]
	v_cvt_pk_bf16_f32 v9, v12, v13
	v_pk_add_f32 v[2:3], v[2:3], v[48:49]
	global_store_dwordx4 v[44:45], v[6:9], off
	v_and_b32_e32 v39, 0xffff0000, v39
	v_cvt_pk_bf16_f32 v20, v20, v21
	v_pk_fma_f32 v[6:7], v[2:3], 0.5, v[48:49] op_sel_hi:[1,0,1] neg_lo:[0,0,1] neg_hi:[0,0,1]
	v_pk_add_f32 v[2:3], v[2:3], v[56:57] neg_lo:[0,1] neg_hi:[0,1]
	v_cvt_pk_bf16_f32 v17, v6, v7
	v_pk_add_f32 v[2:3], v[2:3], v[62:63]
	v_lshlrev_b32_e32 v42, 16, v43
	v_pk_fma_f32 v[6:7], v[2:3], 0.5, v[62:63] op_sel_hi:[1,0,1] neg_lo:[0,0,1] neg_hi:[0,0,1]
	v_pk_add_f32 v[2:3], v[2:3], v[48:49] neg_lo:[0,1] neg_hi:[0,1]
	v_and_b32_e32 v43, 0xffff0000, v43
	v_pk_add_f32 v[2:3], v[2:3], v[38:39]
	v_cvt_pk_bf16_f32 v21, v6, v7
	v_pk_fma_f32 v[6:7], v[2:3], 0.5, v[38:39] op_sel_hi:[1,0,1] neg_lo:[0,0,1] neg_hi:[0,0,1]
	v_pk_add_f32 v[2:3], v[2:3], v[62:63] neg_lo:[0,1] neg_hi:[0,1]
	v_cvt_pk_bf16_f32 v24, v24, v25
	v_pk_add_f32 v[2:3], v[2:3], v[42:43]
	v_lshlrev_b32_e32 v4, 16, v5
	v_and_b32_e32 v5, 0xffff0000, v5
	v_pk_add_f32 v[26:27], v[26:27], v[66:67] neg_lo:[0,1] neg_hi:[0,1]
	v_cvt_pk_bf16_f32 v25, v6, v7
	v_pk_fma_f32 v[6:7], v[2:3], 0.5, v[42:43] op_sel_hi:[1,0,1] neg_lo:[0,0,1] neg_hi:[0,0,1]
	v_pk_add_f32 v[2:3], v[2:3], v[38:39] neg_lo:[0,1] neg_hi:[0,1]
	v_pk_add_f32 v[26:27], v[26:27], v[40:41]
	v_pk_add_f32 v[2:3], v[2:3], v[4:5]
	v_cvt_pk_bf16_f32 v32, v32, v33
	v_mad_i64_i32 v[10:11], s[16:17], v72, s27, v[10:11]
	v_pk_fma_f32 v[26:27], v[26:27], 0.5, v[40:41] op_sel_hi:[1,0,1] neg_lo:[0,0,1] neg_hi:[0,0,1]
	v_cvt_pk_bf16_f32 v33, v6, v7
	v_pk_fma_f32 v[2:3], v[2:3], 0.5, v[4:5] op_sel_hi:[1,0,1] neg_lo:[0,0,1] neg_hi:[0,0,1]
	global_store_dwordx4 v[58:59], v[14:17], off
	global_store_dwordx4 v[54:55], v[18:21], off
	global_store_dwordx4 v[46:47], v[22:25], off
	global_store_dwordx4 v[10:11], v[30:33], off

; DEV float bflo(unsigned u) { return __uint_as_float(u << 16); }
; DEV float bfhi(unsigned u) { return __uint_as_float(u & 0xffff0000u); }
; template <int WIN>
; DEV void pool_d_prompt8(const bf16_t* __restrict__ proj, bf16_t* __restrict__ dpl, int row0, int c8) {
;     ...
;     for (int i = 0; i < WIN + 7; ++i) { const int tt = t0 - (WIN - 1) + i; u[i] = (tt >= 0) ? *(const uint4*)(proj + (size_t)(row0 - (WIN - 1) + i) * NPJ + C_U + c8) : make_uint4(0u, 0u, 0u, 0u); }
;     float acc[8] = {0.f, 0.f, 0.f, 0.f, 0.f, 0.f, 0.f, 0.f};
; #pragma unroll
;     for (int i = 0; i < WIN - 1; ++i) { acc[0] += bflo(u[i].x); acc[1] += bfhi(u[i].x); acc[2] += bflo(u[i].y); acc[3] += bfhi(u[i].y); acc[4] += bflo(u[i].z); acc[5] += bfhi(u[i].z); acc[6] += bflo(u[i].w); acc[7] += bfhi(u[i].w); }
; #pragma unroll
;     for (int j = 0; j < 8; ++j) {
;         const uint4 x = u[j + WIN - 1];
;         const float xs[8] = {bflo(x.x), bfhi(x.x), bflo(x.y), bfhi(x.y), bflo(x.z), bfhi(x.z), bflo(x.w), bfhi(x.w)};
; #pragma unroll
;         for (int e_ = 0; e_ < 8; ++e_) acc[e_] += xs[e_];
;         const float ic = 1.f / (float)min(WIN, t0 + j + 1);
.LBB0_716:
	s_or_b64 exec, exec, s[22:23]
	v_mad_i64_i32 v[14:15], s[4:5], v145, s25, v[172:173]
	v_lshlrev_b32_e32 v94, 1, v143
	v_lshl_add_u64 v[14:15], v[14:15], 0, v[94:95]
	v_or_b32_e32 v149, 1, v145
	v_add_co_u32_e32 v14, vcc, 0x2000, v14
	v_mad_i64_i32 v[16:17], s[4:5], v149, s25, v[172:173]
	s_nop 0
	v_addc_co_u32_e32 v15, vcc, 0, v15, vcc
	v_lshl_add_u64 v[16:17], v[16:17], 0, v[94:95]
	v_add_co_u32_e32 v16, vcc, 0x2000, v16
	v_or_b32_e32 v200, 2, v145
	s_nop 0
	v_addc_co_u32_e32 v17, vcc, 0, v17, vcc
	global_load_dwordx4 v[90:93], v[14:15], off
	global_load_dwordx4 v[78:81], v[16:17], off
	v_mad_i64_i32 v[14:15], s[4:5], v200, s25, v[172:173]
	v_lshl_add_u64 v[14:15], v[14:15], 0, v[94:95]
	v_or_b32_e32 v201, 3, v145
	v_add_co_u32_e32 v14, vcc, 0x2000, v14
	v_mad_i64_i32 v[16:17], s[4:5], v201, s25, v[172:173]
	s_nop 0
	v_addc_co_u32_e32 v15, vcc, 0, v15, vcc
	v_lshl_add_u64 v[16:17], v[16:17], 0, v[94:95]
	v_add_co_u32_e32 v16, vcc, 0x2000, v16
	v_or_b32_e32 v148, 4, v145
	s_nop 0
	v_addc_co_u32_e32 v17, vcc, 0, v17, vcc
	global_load_dwordx4 v[74:77], v[14:15], off
	global_load_dwordx4 v[62:65], v[16:17], off
	v_mad_i64_i32 v[14:15], s[4:5], v148, s25, v[172:173]
	v_lshl_add_u64 v[14:15], v[14:15], 0, v[94:95]
	v_or_b32_e32 v147, 5, v145
	v_add_co_u32_e32 v14, vcc, 0x2000, v14
	v_mad_i64_i32 v[16:17], s[4:5], v147, s25, v[172:173]
	s_waitcnt vmcnt(4)
	v_lshlrev_b32_e32 v134, 16, v10
	v_and_b32_e32 v135, 0xffff0000, v10
	v_addc_co_u32_e32 v15, vcc, 0, v15, vcc
	v_lshl_add_u64 v[16:17], v[16:17], 0, v[94:95]
	v_lshlrev_b32_e32 v132, 16, v11
	v_and_b32_e32 v133, 0xffff0000, v11
	v_lshlrev_b32_e32 v10, 16, v6
	v_and_b32_e32 v11, 0xffff0000, v6
	v_lshlrev_b32_e32 v128, 16, v7
	v_and_b32_e32 v129, 0xffff0000, v7
	v_pk_add_f32 v[6:7], v[134:135], 0 op_sel_hi:[1,0]
	v_lshlrev_b32_e32 v176, 16, v54
	v_and_b32_e32 v177, 0xffff0000, v54
	v_lshlrev_b32_e32 v178, 16, v55
	v_and_b32_e32 v179, 0xffff0000, v55
	v_lshlrev_b32_e32 v186, 16, v72
	v_and_b32_e32 v187, 0xffff0000, v72
	v_lshlrev_b32_e32 v54, 16, v73
	v_and_b32_e32 v55, 0xffff0000, v73
	v_lshlrev_b32_e32 v72, 16, v66
	v_and_b32_e32 v73, 0xffff0000, v66
	v_min_u32_e32 v66, 15, v144
	v_add_co_u32_e32 v16, vcc, 0x2000, v16
	v_lshlrev_b32_e32 v126, 16, v22
	v_and_b32_e32 v127, 0xffff0000, v22
	v_pk_add_f32 v[6:7], v[6:7], v[10:11]
	v_add_u32_e32 v66, 1, v66
	v_addc_co_u32_e32 v17, vcc, 0, v17, vcc
	v_or_b32_e32 v146, 6, v145
	v_or_b32_e32 v96, 7, v98
	v_lshlrev_b32_e32 v120, 16, v18
	v_and_b32_e32 v121, 0xffff0000, v18
	v_pk_add_f32 v[6:7], v[6:7], v[126:127]
	v_lshlrev_b32_e32 v190, 16, v68
	v_and_b32_e32 v191, 0xffff0000, v68
	v_cvt_f32_ubyte0_e32 v68, v66
	global_load_dwordx4 v[50:53], v[14:15], off
	global_load_dwordx4 v[34:37], v[16:17], off
	v_mad_i64_i32 v[14:15], s[4:5], v146, s25, v[172:173]
	v_mad_i64_i32 v[16:17], s[4:5], v96, s25, v[172:173]
	v_lshlrev_b32_e32 v122, 16, v24
	v_and_b32_e32 v123, 0xffff0000, v24
	v_lshlrev_b32_e32 v100, 16, v25
	v_and_b32_e32 v101, 0xffff0000, v25
	v_lshlrev_b32_e32 v114, 16, v46
	v_and_b32_e32 v115, 0xffff0000, v46
	v_lshlrev_b32_e32 v110, 16, v48
	v_and_b32_e32 v111, 0xffff0000, v48
	v_lshlrev_b32_e32 v24, 16, v49
	v_and_b32_e32 v25, 0xffff0000, v49
	v_lshlrev_b32_e32 v108, 16, v38
	v_and_b32_e32 v109, 0xffff0000, v38
	v_lshlrev_b32_e32 v106, 16, v39
	v_and_b32_e32 v107, 0xffff0000, v39
	v_pk_add_f32 v[6:7], v[6:7], v[120:121]
	v_lshlrev_b32_e32 v48, 16, v44
	v_and_b32_e32 v49, 0xffff0000, v44
	v_lshlrev_b32_e32 v38, 16, v45
	v_and_b32_e32 v39, 0xffff0000, v45
	v_lshlrev_b32_e32 v180, 16, v56
	v_and_b32_e32 v181, 0xffff0000, v56
	v_lshlrev_b32_e32 v44, 16, v57
	v_and_b32_e32 v45, 0xffff0000, v57
	v_lshlrev_b32_e32 v56, 16, v69
	v_and_b32_e32 v57, 0xffff0000, v69

; DEV float bflo(unsigned u) { return __uint_as_float(u << 16); }
; DEV float bfhi(unsigned u) { return __uint_as_float(u & 0xffff0000u); }
; template <int WIN>
; DEV void pool_d_prompt8(const bf16_t* __restrict__ proj, bf16_t* __restrict__ dpl, int row0, int c8) {
;     ...
;     for (int i = 0; i < WIN + 7; ++i) { const int tt = t0 - (WIN - 1) + i; u[i] = (tt >= 0) ? *(const uint4*)(proj + (size_t)(row0 - (WIN - 1) + i) * NPJ + C_U + c8) : make_uint4(0u, 0u, 0u, 0u); }
;     float acc[8] = {0.f, 0.f, 0.f, 0.f, 0.f, 0.f, 0.f, 0.f};
; #pragma unroll
;     for (int i = 0; i < WIN - 1; ++i) { acc[0] += bflo(u[i].x); acc[1] += bfhi(u[i].x); acc[2] += bflo(u[i].y); acc[3] += bfhi(u[i].y); acc[4] += bflo(u[i].z); acc[5] += bfhi(u[i].z); acc[6] += bflo(u[i].w); acc[7] += bfhi(u[i].w); }
; #pragma unroll
;     for (int j = 0; j < 8; ++j) {
;         const uint4 x = u[j + WIN - 1];
;         const float xs[8] = {bflo(x.x), bfhi(x.x), bflo(x.y), bfhi(x.y), bflo(x.z), bfhi(x.z), bflo(x.w), bfhi(x.w)};
; #pragma unroll
;         for (int e_ = 0; e_ < 8; ++e_) acc[e_] += xs[e_];
;         const float ic = 1.f / (float)min(WIN, t0 + j + 1);
	v_lshl_add_u64 v[14:15], v[14:15], 0, v[94:95]
	v_lshl_add_u64 v[16:17], v[16:17], 0, v[94:95]
	v_lshlrev_b32_e32 v130, 16, v12
	v_and_b32_e32 v131, 0xffff0000, v12
	v_lshlrev_b32_e32 v104, 16, v13
	v_and_b32_e32 v105, 0xffff0000, v13
	v_lshlrev_b32_e32 v12, 16, v8
	v_and_b32_e32 v13, 0xffff0000, v8
	v_lshlrev_b32_e32 v102, 16, v9
	v_and_b32_e32 v103, 0xffff0000, v9
	v_pk_add_f32 v[6:7], v[6:7], v[114:115]
	v_pk_add_f32 v[8:9], v[132:133], 0 op_sel_hi:[1,0]
	v_lshlrev_b32_e32 v182, 16, v70
	v_and_b32_e32 v183, 0xffff0000, v70
	v_lshlrev_b32_e32 v184, 16, v71
	v_and_b32_e32 v185, 0xffff0000, v71
	v_lshl_add_u64 v[70:71], v[140:141], 0, v[94:95]

; DEV float bflo(unsigned u) { return __uint_as_float(u << 16); }
; DEV float bfhi(unsigned u) { return __uint_as_float(u & 0xffff0000u); }
; template <int WIN>
; DEV void pool_d_prompt8(const bf16_t* __restrict__ proj, bf16_t* __restrict__ dpl, int row0, int c8) {
;     ...
;     for (int i = 0; i < WIN + 7; ++i) { const int tt = t0 - (WIN - 1) + i; u[i] = (tt >= 0) ? *(const uint4*)(proj + (size_t)(row0 - (WIN - 1) + i) * NPJ + C_U + c8) : make_uint4(0u, 0u, 0u, 0u); }
;     float acc[8] = {0.f, 0.f, 0.f, 0.f, 0.f, 0.f, 0.f, 0.f};
; #pragma unroll
;     for (int i = 0; i < WIN - 1; ++i) { acc[0] += bflo(u[i].x); acc[1] += bfhi(u[i].x); acc[2] += bflo(u[i].y); acc[3] += bfhi(u[i].y); acc[4] += bflo(u[i].z); acc[5] += bfhi(u[i].z); acc[6] += bflo(u[i].w); acc[7] += bfhi(u[i].w); }
; #pragma unroll
;     for (int j = 0; j < 8; ++j) {
;         const uint4 x = u[j + WIN - 1];
;         const float xs[8] = {bflo(x.x), bfhi(x.x), bflo(x.y), bfhi(x.y), bflo(x.z), bfhi(x.z), bflo(x.w), bfhi(x.w)};
; #pragma unroll
;         for (int e_ = 0; e_ < 8; ++e_) acc[e_] += xs[e_];
;         const float ic = 1.f / (float)min(WIN, t0 + j + 1);
	v_add_co_u32_e32 v14, vcc, 0x2000, v14
	v_lshlrev_b32_e32 v124, 16, v23
	v_and_b32_e32 v125, 0xffff0000, v23
	v_lshlrev_b32_e32 v112, 16, v47
	v_and_b32_e32 v113, 0xffff0000, v47
	v_lshlrev_b32_e32 v46, 16, v40
	v_and_b32_e32 v47, 0xffff0000, v40
	v_lshlrev_b32_e32 v22, 16, v41
	v_and_b32_e32 v23, 0xffff0000, v41
	v_lshlrev_b32_e32 v40, 16, v42
	v_and_b32_e32 v41, 0xffff0000, v42
	v_pk_add_f32 v[6:7], v[6:7], v[108:109]
	v_pk_add_f32 v[8:9], v[8:9], v[128:129]
	v_addc_co_u32_e32 v15, vcc, 0, v15, vcc
	v_lshlrev_b32_e32 v118, 16, v19
	v_and_b32_e32 v119, 0xffff0000, v19
	v_lshlrev_b32_e32 v116, 16, v20
	v_and_b32_e32 v117, 0xffff0000, v20
	v_lshlrev_b32_e32 v98, 16, v21
	v_and_b32_e32 v99, 0xffff0000, v21
	v_pk_add_f32 v[6:7], v[6:7], v[40:41]
	v_pk_add_f32 v[8:9], v[8:9], v[124:125]
	v_lshlrev_b32_e32 v20, 16, v30
	v_and_b32_e32 v21, 0xffff0000, v30
	v_add_co_u32_e32 v16, vcc, s26, v16
	v_pk_add_f32 v[8:9], v[8:9], v[118:119]
	v_lshlrev_b32_e32 v154, 16, v58
	v_and_b32_e32 v155, 0xffff0000, v58
	v_pk_add_f32 v[6:7], v[6:7], v[20:21]
	v_addc_co_u32_e32 v17, vcc, 0, v17, vcc
	v_pk_add_f32 v[8:9], v[8:9], v[112:113]
	v_pk_add_f32 v[18:19], v[130:131], 0 op_sel_hi:[1,0]
	s_waitcnt vmcnt(5)
	v_lshlrev_b32_e32 v198, 16, v92
	v_and_b32_e32 v199, 0xffff0000, v92

; DEV float bflo(unsigned u) { return __uint_as_float(u << 16); }
; DEV float bfhi(unsigned u) { return __uint_as_float(u & 0xffff0000u); }
; template <int WIN>
; DEV void pool_d_prompt8(const bf16_t* __restrict__ proj, bf16_t* __restrict__ dpl, int row0, int c8) {
;     ...
;     for (int i = 0; i < WIN + 7; ++i) { const int tt = t0 - (WIN - 1) + i; u[i] = (tt >= 0) ? *(const uint4*)(proj + (size_t)(row0 - (WIN - 1) + i) * NPJ + C_U + c8) : make_uint4(0u, 0u, 0u, 0u); }
;     float acc[8] = {0.f, 0.f, 0.f, 0.f, 0.f, 0.f, 0.f, 0.f};
; #pragma unroll
;     for (int i = 0; i < WIN - 1; ++i) { acc[0] += bflo(u[i].x); acc[1] += bfhi(u[i].x); acc[2] += bflo(u[i].y); acc[3] += bfhi(u[i].y); acc[4] += bflo(u[i].z); acc[5] += bfhi(u[i].z); acc[6] += bflo(u[i].w); acc[7] += bfhi(u[i].w); }
; #pragma unroll
;     for (int j = 0; j < 8; ++j) {
;         const uint4 x = u[j + WIN - 1];
;         const float xs[8] = {bflo(x.x), bfhi(x.x), bflo(x.y), bfhi(x.y), bflo(x.z), bfhi(x.z), bflo(x.w), bfhi(x.w)};
; #pragma unroll
;         for (int e_ = 0; e_ < 8; ++e_) acc[e_] += xs[e_];
;         const float ic = 1.f / (float)min(WIN, t0 + j + 1);
	v_pk_add_f32 v[6:7], v[6:7], v[154:155]
	v_lshlrev_b32_e32 v42, 16, v43
	v_and_b32_e32 v43, 0xffff0000, v43
	v_pk_add_f32 v[8:9], v[8:9], v[106:107]
	v_pk_add_f32 v[18:19], v[18:19], v[12:13]


; DEV float bflo(unsigned u) { return __uint_as_float(u << 16); }
; DEV float bfhi(unsigned u) { return __uint_as_float(u & 0xffff0000u); }
; template <int WIN>
; DEV void pool_d_prompt8(const bf16_t* __restrict__ proj, bf16_t* __restrict__ dpl, int row0, int c8) {
;     ...
;     for (int i = 0; i < WIN + 7; ++i) { const int tt = t0 - (WIN - 1) + i; u[i] = (tt >= 0) ? *(const uint4*)(proj + (size_t)(row0 - (WIN - 1) + i) * NPJ + C_U + c8) : make_uint4(0u, 0u, 0u, 0u); }
;     float acc[8] = {0.f, 0.f, 0.f, 0.f, 0.f, 0.f, 0.f, 0.f};
; #pragma unroll
;     for (int i = 0; i < WIN - 1; ++i) { acc[0] += bflo(u[i].x); acc[1] += bfhi(u[i].x); acc[2] += bflo(u[i].y); acc[3] += bfhi(u[i].y); acc[4] += bflo(u[i].z); acc[5] += bfhi(u[i].z); acc[6] += bflo(u[i].w); acc[7] += bfhi(u[i].w); }
; #pragma unroll
;     for (int j = 0; j < 8; ++j) {
;         const uint4 x = u[j + WIN - 1];
;         const float xs[8] = {bflo(x.x), bfhi(x.x), bflo(x.y), bfhi(x.y), bflo(x.z), bfhi(x.z), bflo(x.w), bfhi(x.w)};
; #pragma unroll
;         for (int e_ = 0; e_ < 8; ++e_) acc[e_] += xs[e_];
;         const float ic = 1.f / (float)min(WIN, t0 + j + 1);
	v_pk_add_f32 v[6:7], v[6:7], v[176:177]
	v_pk_add_f32 v[8:9], v[8:9], v[42:43]
	v_pk_add_f32 v[18:19], v[18:19], v[122:123]
	v_lshlrev_b32_e32 v150, 16, v31
	v_and_b32_e32 v151, 0xffff0000, v31
	v_lshlrev_b32_e32 v188, 16, v67
	v_and_b32_e32 v189, 0xffff0000, v67
	v_lshlrev_b32_e32 v66, 16, v93
	v_and_b32_e32 v67, 0xffff0000, v93

; DEV float bflo(unsigned u) { return __uint_as_float(u << 16); }
; DEV float bfhi(unsigned u) { return __uint_as_float(u & 0xffff0000u); }
; template <int WIN>
; DEV void pool_d_prompt8(const bf16_t* __restrict__ proj, bf16_t* __restrict__ dpl, int row0, int c8) {
;     ...
;     for (int i = 0; i < WIN + 7; ++i) { const int tt = t0 - (WIN - 1) + i; u[i] = (tt >= 0) ? *(const uint4*)(proj + (size_t)(row0 - (WIN - 1) + i) * NPJ + C_U + c8) : make_uint4(0u, 0u, 0u, 0u); }
;     float acc[8] = {0.f, 0.f, 0.f, 0.f, 0.f, 0.f, 0.f, 0.f};
; #pragma unroll
;     for (int i = 0; i < WIN - 1; ++i) { acc[0] += bflo(u[i].x); acc[1] += bfhi(u[i].x); acc[2] += bflo(u[i].y); acc[3] += bfhi(u[i].y); acc[4] += bflo(u[i].z); acc[5] += bfhi(u[i].z); acc[6] += bflo(u[i].w); acc[7] += bfhi(u[i].w); }
; #pragma unroll
;     for (int j = 0; j < 8; ++j) {
;         const uint4 x = u[j + WIN - 1];
;         const float xs[8] = {bflo(x.x), bfhi(x.x), bflo(x.y), bfhi(x.y), bflo(x.z), bfhi(x.z), bflo(x.w), bfhi(x.w)};
; #pragma unroll
;         for (int e_ = 0; e_ < 8; ++e_) acc[e_] += xs[e_];
;         const float ic = 1.f / (float)min(WIN, t0 + j + 1);
	v_pk_add_f32 v[6:7], v[6:7], v[182:183]
	v_pk_add_f32 v[18:19], v[18:19], v[116:117]
	v_lshlrev_b32_e32 v156, 16, v59
	v_and_b32_e32 v157, 0xffff0000, v59
	v_lshlrev_b32_e32 v192, 16, v86
	v_and_b32_e32 v193, 0xffff0000, v86

; DEV float bflo(unsigned u) { return __uint_as_float(u << 16); }
; DEV float bfhi(unsigned u) { return __uint_as_float(u & 0xffff0000u); }
; template <int WIN>
; DEV void pool_d_prompt8(const bf16_t* __restrict__ proj, bf16_t* __restrict__ dpl, int row0, int c8) {
;     ...
;     for (int i = 0; i < WIN + 7; ++i) { const int tt = t0 - (WIN - 1) + i; u[i] = (tt >= 0) ? *(const uint4*)(proj + (size_t)(row0 - (WIN - 1) + i) * NPJ + C_U + c8) : make_uint4(0u, 0u, 0u, 0u); }
;     float acc[8] = {0.f, 0.f, 0.f, 0.f, 0.f, 0.f, 0.f, 0.f};
; #pragma unroll
;     for (int i = 0; i < WIN - 1; ++i) { acc[0] += bflo(u[i].x); acc[1] += bfhi(u[i].x); acc[2] += bflo(u[i].y); acc[3] += bfhi(u[i].y); acc[4] += bflo(u[i].z); acc[5] += bfhi(u[i].z); acc[6] += bflo(u[i].w); acc[7] += bfhi(u[i].w); }
; #pragma unroll
;     for (int j = 0; j < 8; ++j) {
;         const uint4 x = u[j + WIN - 1];
;         const float xs[8] = {bflo(x.x), bfhi(x.x), bflo(x.y), bfhi(x.y), bflo(x.z), bfhi(x.z), bflo(x.w), bfhi(x.w)};
; #pragma unroll
;         for (int e_ = 0; e_ < 8; ++e_) acc[e_] += xs[e_];
;         const float ic = 1.f / (float)min(WIN, t0 + j + 1);
	v_pk_add_f32 v[6:7], v[6:7], v[72:73]
	v_pk_add_f32 v[8:9], v[8:9], v[150:151]
	v_pk_add_f32 v[18:19], v[18:19], v[110:111]
	v_lshlrev_b32_e32 v194, 16, v88
	v_and_b32_e32 v195, 0xffff0000, v88
	v_lshlrev_b32_e32 v58, 16, v89
	v_and_b32_e32 v59, 0xffff0000, v89
	v_lshlrev_b32_e32 v88, 16, v82
	v_and_b32_e32 v89, 0xffff0000, v82

; DEV float bflo(unsigned u) { return __uint_as_float(u << 16); }
; DEV float bfhi(unsigned u) { return __uint_as_float(u & 0xffff0000u); }
; template <int WIN>
; DEV void pool_d_prompt8(const bf16_t* __restrict__ proj, bf16_t* __restrict__ dpl, int row0, int c8) {
;     ...
;     for (int i = 0; i < WIN + 7; ++i) { const int tt = t0 - (WIN - 1) + i; u[i] = (tt >= 0) ? *(const uint4*)(proj + (size_t)(row0 - (WIN - 1) + i) * NPJ + C_U + c8) : make_uint4(0u, 0u, 0u, 0u); }
;     float acc[8] = {0.f, 0.f, 0.f, 0.f, 0.f, 0.f, 0.f, 0.f};
; #pragma unroll
;     for (int i = 0; i < WIN - 1; ++i) { acc[0] += bflo(u[i].x); acc[1] += bfhi(u[i].x); acc[2] += bflo(u[i].y); acc[3] += bfhi(u[i].y); acc[4] += bflo(u[i].z); acc[5] += bfhi(u[i].z); acc[6] += bflo(u[i].w); acc[7] += bfhi(u[i].w); }
; #pragma unroll
;     for (int j = 0; j < 8; ++j) {
;         const uint4 x = u[j + WIN - 1];
;         const float xs[8] = {bflo(x.x), bfhi(x.x), bflo(x.y), bfhi(x.y), bflo(x.z), bfhi(x.z), bflo(x.w), bfhi(x.w)};
; #pragma unroll
;         for (int e_ = 0; e_ < 8; ++e_) acc[e_] += xs[e_];
;         const float ic = 1.f / (float)min(WIN, t0 + j + 1);
	v_pk_add_f32 v[6:7], v[6:7], v[192:193]
	v_pk_add_f32 v[8:9], v[8:9], v[156:157]
	v_pk_add_f32 v[18:19], v[18:19], v[46:47]

; DEV float bflo(unsigned u) { return __uint_as_float(u << 16); }
; DEV float bfhi(unsigned u) { return __uint_as_float(u & 0xffff0000u); }
; template <int WIN>
; DEV void pool_d_prompt8(const bf16_t* __restrict__ proj, bf16_t* __restrict__ dpl, int row0, int c8) {
;     ...
;     for (int i = 0; i < WIN + 7; ++i) { const int tt = t0 - (WIN - 1) + i; u[i] = (tt >= 0) ? *(const uint4*)(proj + (size_t)(row0 - (WIN - 1) + i) * NPJ + C_U + c8) : make_uint4(0u, 0u, 0u, 0u); }
;     float acc[8] = {0.f, 0.f, 0.f, 0.f, 0.f, 0.f, 0.f, 0.f};
; #pragma unroll
;     for (int i = 0; i < WIN - 1; ++i) { acc[0] += bflo(u[i].x); acc[1] += bfhi(u[i].x); acc[2] += bflo(u[i].y); acc[3] += bfhi(u[i].y); acc[4] += bflo(u[i].z); acc[5] += bfhi(u[i].z); acc[6] += bflo(u[i].w); acc[7] += bfhi(u[i].w); }
; #pragma unroll
;     for (int j = 0; j < 8; ++j) {
;         const uint4 x = u[j + WIN - 1];
;         const float xs[8] = {bflo(x.x), bfhi(x.x), bflo(x.y), bfhi(x.y), bflo(x.z), bfhi(x.z), bflo(x.w), bfhi(x.w)};
; #pragma unroll
;         for (int e_ = 0; e_ < 8; ++e_) acc[e_] += xs[e_];
;         const float ic = 1.f / (float)min(WIN, t0 + j + 1);
	v_pk_add_f32 v[6:7], v[6:7], v[88:89]
	v_lshlrev_b32_e32 v20, 16, v2
	v_and_b32_e32 v21, 0xffff0000, v2
	v_pk_add_f32 v[8:9], v[8:9], v[178:179]
	v_pk_add_f32 v[18:19], v[18:19], v[48:49]
	v_lshlrev_b32_e32 v152, 16, v32
	v_and_b32_e32 v153, 0xffff0000, v32
	v_lshlrev_b32_e32 v30, 16, v33
	v_and_b32_e32 v31, 0xffff0000, v33
	v_lshlrev_b32_e32 v174, 16, v60
	v_and_b32_e32 v175, 0xffff0000, v60
	v_lshlrev_b32_e32 v32, 16, v61
	v_and_b32_e32 v33, 0xffff0000, v61
	v_lshlrev_b32_e32 v196, 16, v84
	v_and_b32_e32 v197, 0xffff0000, v84
	v_lshlrev_b32_e32 v60, 16, v85
	v_and_b32_e32 v61, 0xffff0000, v85
	v_lshlrev_b32_e32 v84, 16, v90
	v_and_b32_e32 v85, 0xffff0000, v90

; DEV unsigned cvt_pk_bf16(float lo, float hi) { const f32x2_t v = {lo, hi}; const bf16x2_t b = __builtin_convertvector(v, bf16x2_t); return __builtin_bit_cast(unsigned, b); }
; DEV float bflo(unsigned u) { return __uint_as_float(u << 16); }
; DEV float bfhi(unsigned u) { return __uint_as_float(u & 0xffff0000u); }
; template <int WIN>
; DEV void pool_d_prompt8(const bf16_t* __restrict__ proj, bf16_t* __restrict__ dpl, int row0, int c8) {
;     ...
;     for (int i = 0; i < WIN - 1; ++i) { acc[0] += bflo(u[i].x); acc[1] += bfhi(u[i].x); acc[2] += bflo(u[i].y); acc[3] += bfhi(u[i].y); acc[4] += bflo(u[i].z); acc[5] += bfhi(u[i].z); acc[6] += bflo(u[i].w); acc[7] += bfhi(u[i].w); }
; #pragma unroll
;     for (int j = 0; j < 8; ++j) {
;         const uint4 x = u[j + WIN - 1];
;         const float xs[8] = {bflo(x.x), bfhi(x.x), bflo(x.y), bfhi(x.y), bflo(x.z), bfhi(x.z), bflo(x.w), bfhi(x.w)};
; #pragma unroll
;         for (int e_ = 0; e_ < 8; ++e_) acc[e_] += xs[e_];
;         const float ic = 1.f / (float)min(WIN, t0 + j + 1);
;         uint4 o;
;         o.x = cvt_pk_bf16(acc[0] * ic - xs[0], acc[1] * ic - xs[1]); o.y = cvt_pk_bf16(acc[2] * ic - xs[2], acc[3] * ic - xs[3]);
;         o.z = cvt_pk_bf16(acc[4] * ic - xs[4], acc[5] * ic - xs[5]); o.w = cvt_pk_bf16(acc[6] * ic - xs[6], acc[7] * ic - xs[7]);
;         *(uint4*)(dpl + (size_t)(row0 + j) * LDP + c8) = o;
;         const uint4 y = u[j];
;         acc[0] -= bflo(y.x); acc[1] -= bfhi(y.x); acc[2] -= bflo(y.y); acc[3] -= bfhi(y.y); acc[4] -= bflo(y.z); acc[5] -= bfhi(y.z); acc[6] -= bflo(y.w); acc[7] -= bfhi(y.w);
	v_pk_add_f32 v[6:7], v[6:7], v[20:21]
	v_pk_add_f32 v[8:9], v[8:9], v[184:185]
	v_lshlrev_b32_e32 v86, 16, v87
	v_and_b32_e32 v87, 0xffff0000, v87
	v_rcp_f32_e32 v69, v68
	s_nop 0
	v_mul_f32_e32 v68, 1.0, v69
	v_pk_add_f32 v[6:7], v[6:7], v[84:85]
	v_pk_add_f32 v[8:9], v[8:9], v[188:189]
	v_pk_add_f32 v[18:19], v[18:19], v[152:153]
	v_lshlrev_b32_e32 v82, 16, v83
	v_and_b32_e32 v83, 0xffff0000, v83
	v_pk_fma_f32 v[20:21], v[68:69], v[6:7], v[84:85] op_sel_hi:[0,1,1] neg_lo:[0,0,1] neg_hi:[0,0,1]
	v_pk_add_f32 v[8:9], v[8:9], v[86:87]
	v_pk_add_f32 v[18:19], v[18:19], v[174:175]
	v_cvt_pk_bf16_f32 v2, v20, v21
	v_pk_add_f32 v[8:9], v[8:9], v[82:83]
	v_lshlrev_b32_e32 v20, 16, v3
	v_and_b32_e32 v21, 0xffff0000, v3
	v_pk_add_f32 v[18:19], v[18:19], v[180:181]
	v_lshlrev_b32_e32 v90, 16, v91
	v_and_b32_e32 v91, 0xffff0000, v91
	v_pk_add_f32 v[8:9], v[8:9], v[20:21]
	v_pk_add_f32 v[18:19], v[18:19], v[186:187]
	v_pk_add_f32 v[8:9], v[8:9], v[90:91]
	v_pk_add_f32 v[18:19], v[18:19], v[190:191]
	v_pk_fma_f32 v[20:21], v[68:69], v[8:9], v[90:91] op_sel_hi:[0,1,1] neg_lo:[0,0,1] neg_hi:[0,0,1]
	v_pk_add_f32 v[18:19], v[18:19], v[194:195]
	v_cvt_pk_bf16_f32 v3, v20, v21
	v_pk_add_f32 v[18:19], v[18:19], v[196:197]
	v_lshlrev_b32_e32 v20, 16, v4
	v_and_b32_e32 v21, 0xffff0000, v4
	v_pk_add_f32 v[18:19], v[18:19], v[20:21]
	s_waitcnt vmcnt(4)
	v_lshlrev_b32_e32 v84, 16, v80
	v_pk_add_f32 v[18:19], v[18:19], v[198:199]
	v_and_b32_e32 v85, 0xffff0000, v80
	v_pk_fma_f32 v[20:21], v[68:69], v[18:19], v[198:199] op_sel_hi:[0,1,1] neg_lo:[0,0,1] neg_hi:[0,0,1]
	v_min_u32_e32 v69, 14, v144
	v_add_u32_e32 v69, 2, v69
	v_cvt_f32_ubyte0_e32 v69, v69


; DEV float bflo(unsigned u) { return __uint_as_float(u << 16); }
; DEV float bfhi(unsigned u) { return __uint_as_float(u & 0xffff0000u); }
; template <int WIN>
; DEV void pool_d_prompt8(const bf16_t* __restrict__ proj, bf16_t* __restrict__ dpl, int row0, int c8) {
;     ...
;         const float xs[8] = {bflo(x.x), bfhi(x.x), bflo(x.y), bfhi(x.y), bflo(x.z), bfhi(x.z), bflo(x.w), bfhi(x.w)};
; #pragma unroll
;         for (int e_ = 0; e_ < 8; ++e_) acc[e_] += xs[e_];
;         const float ic = 1.f / (float)min(WIN, t0 + j + 1);
	v_cvt_pk_bf16_f32 v4, v20, v21
	v_lshlrev_b32_e32 v20, 16, v78
	v_and_b32_e32 v21, 0xffff0000, v78


; DEV float bflo(unsigned u) { return __uint_as_float(u << 16); }
; DEV float bfhi(unsigned u) { return __uint_as_float(u & 0xffff0000u); }
; template <int WIN>
; DEV void pool_d_prompt8(const bf16_t* __restrict__ proj, bf16_t* __restrict__ dpl, int row0, int c8) {
;     ...
;         const float xs[8] = {bflo(x.x), bfhi(x.x), bflo(x.y), bfhi(x.y), bflo(x.z), bfhi(x.z), bflo(x.w), bfhi(x.w)};
; #pragma unroll
;         for (int e_ = 0; e_ < 8; ++e_) acc[e_] += xs[e_];
;         const float ic = 1.f / (float)min(WIN, t0 + j + 1);
	v_lshlrev_b32_e32 v82, 16, v79
	v_and_b32_e32 v83, 0xffff0000, v79
	v_lshlrev_b32_e32 v78, 16, v81
	v_and_b32_e32 v79, 0xffff0000, v81

; DEV float bflo(unsigned u) { return __uint_as_float(u << 16); }
; DEV float bfhi(unsigned u) { return __uint_as_float(u & 0xffff0000u); }
; template <int WIN>
; DEV void pool_d_prompt8(const bf16_t* __restrict__ proj, bf16_t* __restrict__ dpl, int row0, int c8) {
;     ...
;         const float xs[8] = {bflo(x.x), bfhi(x.x), bflo(x.y), bfhi(x.y), bflo(x.z), bfhi(x.z), bflo(x.w), bfhi(x.w)};
; #pragma unroll
;         for (int e_ = 0; e_ < 8; ++e_) acc[e_] += xs[e_];
;         const float ic = 1.f / (float)min(WIN, t0 + j + 1);
	global_load_dwordx4 v[26:29], v[14:15], off
	s_nop 0
	global_load_dwordx4 v[14:17], v[16:17], off


; DEV unsigned cvt_pk_bf16(float lo, float hi) { const f32x2_t v = {lo, hi}; const bf16x2_t b = __builtin_convertvector(v, bf16x2_t); return __builtin_bit_cast(unsigned, b); }
; DEV float bflo(unsigned u) { return __uint_as_float(u << 16); }
; DEV float bfhi(unsigned u) { return __uint_as_float(u & 0xffff0000u); }
; template <int WIN>
; DEV void pool_d_prompt8(const bf16_t* __restrict__ proj, bf16_t* __restrict__ dpl, int row0, int c8) {
;     ...
;     for (int j = 0; j < 8; ++j) {
;         const uint4 x = u[j + WIN - 1];
;         const float xs[8] = {bflo(x.x), bfhi(x.x), bflo(x.y), bfhi(x.y), bflo(x.z), bfhi(x.z), bflo(x.w), bfhi(x.w)};
; #pragma unroll
;         for (int e_ = 0; e_ < 8; ++e_) acc[e_] += xs[e_];
;         const float ic = 1.f / (float)min(WIN, t0 + j + 1);
;         uint4 o;
;         o.x = cvt_pk_bf16(acc[0] * ic - xs[0], acc[1] * ic - xs[1]); o.y = cvt_pk_bf16(acc[2] * ic - xs[2], acc[3] * ic - xs[3]);
;         o.z = cvt_pk_bf16(acc[4] * ic - xs[4], acc[5] * ic - xs[5]); o.w = cvt_pk_bf16(acc[6] * ic - xs[6], acc[7] * ic - xs[7]);
;         *(uint4*)(dpl + (size_t)(row0 + j) * LDP + c8) = o;
;         const uint4 y = u[j];
;         acc[0] -= bflo(y.x); acc[1] -= bfhi(y.x); acc[2] -= bflo(y.y); acc[3] -= bfhi(y.y); acc[4] -= bflo(y.z); acc[5] -= bfhi(y.z); acc[6] -= bflo(y.w); acc[7] -= bfhi(y.w);
	v_pk_add_f32 v[6:7], v[6:7], v[134:135] neg_lo:[0,1] neg_hi:[0,1]
	v_rcp_f32_e32 v80, v69
	s_nop 0
	v_mul_f32_e32 v80, 1.0, v80
	v_pk_add_f32 v[86:87], v[6:7], v[20:21]
	v_pk_add_f32 v[8:9], v[8:9], v[132:133] neg_lo:[0,1] neg_hi:[0,1]
	v_pk_fma_f32 v[6:7], v[80:81], v[86:87], v[20:21] op_sel_hi:[0,1,1] neg_lo:[0,0,1] neg_hi:[0,0,1]
	v_pk_add_f32 v[20:21], v[8:9], v[82:83]
	v_cvt_pk_bf16_f32 v6, v6, v7
	v_pk_fma_f32 v[8:9], v[80:81], v[20:21], v[82:83] op_sel_hi:[0,1,1] neg_lo:[0,0,1] neg_hi:[0,0,1]
	v_cvt_pk_bf16_f32 v7, v8, v9
	v_pk_add_f32 v[8:9], v[18:19], v[130:131] neg_lo:[0,1] neg_hi:[0,1]
	s_waitcnt vmcnt(5)
	v_lshlrev_b32_e32 v90, 16, v76
	v_pk_add_f32 v[18:19], v[8:9], v[84:85]
	v_and_b32_e32 v91, 0xffff0000, v76
	v_pk_fma_f32 v[8:9], v[80:81], v[18:19], v[84:85] op_sel_hi:[0,1,1] neg_lo:[0,0,1] neg_hi:[0,0,1]
	v_cvt_pk_bf16_f32 v8, v8, v9
	v_min_u32_e32 v9, 13, v144
	v_add_u32_e32 v9, 3, v9
	v_cvt_f32_ubyte0_e32 v9, v9


; DEV float bflo(unsigned u) { return __uint_as_float(u << 16); }
; DEV float bfhi(unsigned u) { return __uint_as_float(u & 0xffff0000u); }
; template <int WIN>
; DEV void pool_d_prompt8(const bf16_t* __restrict__ proj, bf16_t* __restrict__ dpl, int row0, int c8) {
;     ...
;         const float xs[8] = {bflo(x.x), bfhi(x.x), bflo(x.y), bfhi(x.y), bflo(x.z), bfhi(x.z), bflo(x.w), bfhi(x.w)};
; #pragma unroll
;         for (int e_ = 0; e_ < 8; ++e_) acc[e_] += xs[e_];
;         const float ic = 1.f / (float)min(WIN, t0 + j + 1);
	v_lshlrev_b32_e32 v84, 16, v74
	v_and_b32_e32 v85, 0xffff0000, v74
	v_lshlrev_b32_e32 v88, 16, v75


; DEV float bflo(unsigned u) { return __uint_as_float(u << 16); }
; DEV float bfhi(unsigned u) { return __uint_as_float(u & 0xffff0000u); }
; template <int WIN>
; DEV void pool_d_prompt8(const bf16_t* __restrict__ proj, bf16_t* __restrict__ dpl, int row0, int c8) {
;     ...
;         const float xs[8] = {bflo(x.x), bfhi(x.x), bflo(x.y), bfhi(x.y), bflo(x.z), bfhi(x.z), bflo(x.w), bfhi(x.w)};
; #pragma unroll
;         for (int e_ = 0; e_ < 8; ++e_) acc[e_] += xs[e_];
;         const float ic = 1.f / (float)min(WIN, t0 + j + 1);
	v_and_b32_e32 v89, 0xffff0000, v75
	v_lshlrev_b32_e32 v74, 16, v77
	v_and_b32_e32 v75, 0xffff0000, v77


; DEV unsigned cvt_pk_bf16(float lo, float hi) { const f32x2_t v = {lo, hi}; const bf16x2_t b = __builtin_convertvector(v, bf16x2_t); return __builtin_bit_cast(unsigned, b); }
; DEV float bflo(unsigned u) { return __uint_as_float(u << 16); }
; DEV float bfhi(unsigned u) { return __uint_as_float(u & 0xffff0000u); }
; template <int WIN>
; DEV void pool_d_prompt8(const bf16_t* __restrict__ proj, bf16_t* __restrict__ dpl, int row0, int c8) {
;     ...
;     for (int j = 0; j < 8; ++j) {
;         const uint4 x = u[j + WIN - 1];
;         const float xs[8] = {bflo(x.x), bfhi(x.x), bflo(x.y), bfhi(x.y), bflo(x.z), bfhi(x.z), bflo(x.w), bfhi(x.w)};
; #pragma unroll
;         for (int e_ = 0; e_ < 8; ++e_) acc[e_] += xs[e_];
;         const float ic = 1.f / (float)min(WIN, t0 + j + 1);
;         uint4 o;
;         o.x = cvt_pk_bf16(acc[0] * ic - xs[0], acc[1] * ic - xs[1]); o.y = cvt_pk_bf16(acc[2] * ic - xs[2], acc[3] * ic - xs[3]);
;         o.z = cvt_pk_bf16(acc[4] * ic - xs[4], acc[5] * ic - xs[5]); o.w = cvt_pk_bf16(acc[6] * ic - xs[6], acc[7] * ic - xs[7]);
;         *(uint4*)(dpl + (size_t)(row0 + j) * LDP + c8) = o;
;         const uint4 y = u[j];
;         acc[0] -= bflo(y.x); acc[1] -= bfhi(y.x); acc[2] -= bflo(y.y); acc[3] -= bfhi(y.y); acc[4] -= bflo(y.z); acc[5] -= bfhi(y.z); acc[6] -= bflo(y.w); acc[7] -= bfhi(y.w);
	v_pk_add_f32 v[10:11], v[86:87], v[10:11] neg_lo:[0,1] neg_hi:[0,1]
	v_pk_add_f32 v[20:21], v[20:21], v[128:129] neg_lo:[0,1] neg_hi:[0,1]
	v_rcp_f32_e32 v69, v9
	s_nop 0
	v_mul_f32_e32 v76, 1.0, v69
	v_pk_add_f32 v[86:87], v[10:11], v[84:85]
	v_pk_add_f32 v[20:21], v[20:21], v[88:89]
	v_pk_add_f32 v[12:13], v[18:19], v[12:13] neg_lo:[0,1] neg_hi:[0,1]
	v_min_u32_e32 v9, 12, v144
	v_pk_fma_f32 v[10:11], v[76:77], v[86:87], v[84:85] op_sel_hi:[0,1,1] neg_lo:[0,0,1] neg_hi:[0,0,1]
	v_pk_fma_f32 v[84:85], v[76:77], v[20:21], v[88:89] op_sel_hi:[0,1,1] neg_lo:[0,0,1] neg_hi:[0,0,1]
	v_pk_add_f32 v[88:89], v[12:13], v[90:91]
	v_add_u32_e32 v9, 4, v9
	v_pk_fma_f32 v[12:13], v[76:77], v[88:89], v[90:91] op_sel_hi:[0,1,1] neg_lo:[0,0,1] neg_hi:[0,0,1]
	v_cvt_f32_ubyte0_e32 v9, v9
	v_cvt_pk_bf16_f32 v12, v12, v13


; DEV float bflo(unsigned u) { return __uint_as_float(u << 16); }
; DEV float bfhi(unsigned u) { return __uint_as_float(u & 0xffff0000u); }
; template <int WIN>
; DEV void pool_d_prompt8(const bf16_t* __restrict__ proj, bf16_t* __restrict__ dpl, int row0, int c8) {
;     ...
;         const float xs[8] = {bflo(x.x), bfhi(x.x), bflo(x.y), bfhi(x.y), bflo(x.z), bfhi(x.z), bflo(x.w), bfhi(x.w)};
; #pragma unroll
;         for (int e_ = 0; e_ < 8; ++e_) acc[e_] += xs[e_];
;         const float ic = 1.f / (float)min(WIN, t0 + j + 1);
	s_waitcnt vmcnt(4)
	v_lshlrev_b32_e32 v92, 16, v64
	v_and_b32_e32 v93, 0xffff0000, v64
	v_lshlrev_b32_e32 v18, 16, v62


; DEV float bflo(unsigned u) { return __uint_as_float(u << 16); }
; DEV float bfhi(unsigned u) { return __uint_as_float(u & 0xffff0000u); }
; template <int WIN>
; DEV void pool_d_prompt8(const bf16_t* __restrict__ proj, bf16_t* __restrict__ dpl, int row0, int c8) {
;     ...
;         const float xs[8] = {bflo(x.x), bfhi(x.x), bflo(x.y), bfhi(x.y), bflo(x.z), bfhi(x.z), bflo(x.w), bfhi(x.w)};
; #pragma unroll
;         for (int e_ = 0; e_ < 8; ++e_) acc[e_] += xs[e_];
;         const float ic = 1.f / (float)min(WIN, t0 + j + 1);
	v_and_b32_e32 v19, 0xffff0000, v62
	v_lshlrev_b32_e32 v90, 16, v63
	v_and_b32_e32 v91, 0xffff0000, v63
	v_lshlrev_b32_e32 v62, 16, v65
	v_and_b32_e32 v63, 0xffff0000, v65


; DEV unsigned cvt_pk_bf16(float lo, float hi) { const f32x2_t v = {lo, hi}; const bf16x2_t b = __builtin_convertvector(v, bf16x2_t); return __builtin_bit_cast(unsigned, b); }
; DEV float bflo(unsigned u) { return __uint_as_float(u << 16); }
; DEV float bfhi(unsigned u) { return __uint_as_float(u & 0xffff0000u); }
; template <int WIN>
; DEV void pool_d_prompt8(const bf16_t* __restrict__ proj, bf16_t* __restrict__ dpl, int row0, int c8) {
;     ...
;     for (int j = 0; j < 8; ++j) {
;         const uint4 x = u[j + WIN - 1];
;         const float xs[8] = {bflo(x.x), bfhi(x.x), bflo(x.y), bfhi(x.y), bflo(x.z), bfhi(x.z), bflo(x.w), bfhi(x.w)};
; #pragma unroll
;         for (int e_ = 0; e_ < 8; ++e_) acc[e_] += xs[e_];
;         const float ic = 1.f / (float)min(WIN, t0 + j + 1);
;         uint4 o;
;         o.x = cvt_pk_bf16(acc[0] * ic - xs[0], acc[1] * ic - xs[1]); o.y = cvt_pk_bf16(acc[2] * ic - xs[2], acc[3] * ic - xs[3]);
;         o.z = cvt_pk_bf16(acc[4] * ic - xs[4], acc[5] * ic - xs[5]); o.w = cvt_pk_bf16(acc[6] * ic - xs[6], acc[7] * ic - xs[7]);
;         *(uint4*)(dpl + (size_t)(row0 + j) * LDP + c8) = o;
;         const uint4 y = u[j];
;         acc[0] -= bflo(y.x); acc[1] -= bfhi(y.x); acc[2] -= bflo(y.y); acc[3] -= bfhi(y.y); acc[4] -= bflo(y.z); acc[5] -= bfhi(y.z); acc[6] -= bflo(y.w); acc[7] -= bfhi(y.w);
	v_pk_add_f32 v[86:87], v[86:87], v[126:127] neg_lo:[0,1] neg_hi:[0,1]
	v_pk_add_f32 v[20:21], v[20:21], v[124:125] neg_lo:[0,1] neg_hi:[0,1]
	v_rcp_f32_e32 v13, v9
	s_nop 0
	v_mul_f32_e32 v64, 1.0, v13
	v_pk_add_f32 v[126:127], v[86:87], v[18:19]
	v_pk_add_f32 v[124:125], v[20:21], v[90:91]
	v_pk_fma_f32 v[18:19], v[64:65], v[126:127], v[18:19] op_sel_hi:[0,1,1] neg_lo:[0,0,1] neg_hi:[0,0,1]
	v_pk_fma_f32 v[20:21], v[64:65], v[124:125], v[90:91] op_sel_hi:[0,1,1] neg_lo:[0,0,1] neg_hi:[0,0,1]
	v_min_u32_e32 v9, 11, v144
	v_cvt_pk_bf16_f32 v18, v18, v19
	v_cvt_pk_bf16_f32 v19, v20, v21
	v_pk_add_f32 v[20:21], v[88:89], v[122:123] neg_lo:[0,1] neg_hi:[0,1]
	v_add_u32_e32 v9, 5, v9
	v_pk_add_f32 v[90:91], v[20:21], v[92:93]
	v_cvt_f32_ubyte0_e32 v9, v9
	v_pk_fma_f32 v[20:21], v[64:65], v[90:91], v[92:93] op_sel_hi:[0,1,1] neg_lo:[0,0,1] neg_hi:[0,0,1]

; DEV unsigned cvt_pk_bf16(float lo, float hi) { const f32x2_t v = {lo, hi}; const bf16x2_t b = __builtin_convertvector(v, bf16x2_t); return __builtin_bit_cast(unsigned, b); }
; DEV float bflo(unsigned u) { return __uint_as_float(u << 16); }
; DEV float bfhi(unsigned u) { return __uint_as_float(u & 0xffff0000u); }
; template <int WIN>
; DEV void pool_d_prompt8(const bf16_t* __restrict__ proj, bf16_t* __restrict__ dpl, int row0, int c8) {
;     ...
;         const float xs[8] = {bflo(x.x), bfhi(x.x), bflo(x.y), bfhi(x.y), bflo(x.z), bfhi(x.z), bflo(x.w), bfhi(x.w)};
; #pragma unroll
;         for (int e_ = 0; e_ < 8; ++e_) acc[e_] += xs[e_];
;         const float ic = 1.f / (float)min(WIN, t0 + j + 1);
;         uint4 o;
;         o.x = cvt_pk_bf16(acc[0] * ic - xs[0], acc[1] * ic - xs[1]); o.y = cvt_pk_bf16(acc[2] * ic - xs[2], acc[3] * ic - xs[3]);
;         o.z = cvt_pk_bf16(acc[4] * ic - xs[4], acc[5] * ic - xs[5]); o.w = cvt_pk_bf16(acc[6] * ic - xs[6], acc[7] * ic - xs[7]);
	v_cvt_pk_bf16_f32 v20, v20, v21

; DEV float bflo(unsigned u) { return __uint_as_float(u << 16); }
; DEV float bfhi(unsigned u) { return __uint_as_float(u & 0xffff0000u); }
; template <int WIN>
; DEV void pool_d_prompt8(const bf16_t* __restrict__ proj, bf16_t* __restrict__ dpl, int row0, int c8) {
;     ...
;         const float xs[8] = {bflo(x.x), bfhi(x.x), bflo(x.y), bfhi(x.y), bflo(x.z), bfhi(x.z), bflo(x.w), bfhi(x.w)};
; #pragma unroll
;         for (int e_ = 0; e_ < 8; ++e_) acc[e_] += xs[e_];
;         const float ic = 1.f / (float)min(WIN, t0 + j + 1);
	s_waitcnt vmcnt(3)
	v_lshlrev_b32_e32 v122, 16, v52
	v_and_b32_e32 v123, 0xffff0000, v52
	v_lshlrev_b32_e32 v88, 16, v50


; DEV float bflo(unsigned u) { return __uint_as_float(u << 16); }
; DEV float bfhi(unsigned u) { return __uint_as_float(u & 0xffff0000u); }
; template <int WIN>
; DEV void pool_d_prompt8(const bf16_t* __restrict__ proj, bf16_t* __restrict__ dpl, int row0, int c8) {
;     ...
;         const float xs[8] = {bflo(x.x), bfhi(x.x), bflo(x.y), bfhi(x.y), bflo(x.z), bfhi(x.z), bflo(x.w), bfhi(x.w)};
; #pragma unroll
;         for (int e_ = 0; e_ < 8; ++e_) acc[e_] += xs[e_];
;         const float ic = 1.f / (float)min(WIN, t0 + j + 1);
	v_and_b32_e32 v89, 0xffff0000, v50
	v_lshlrev_b32_e32 v92, 16, v51
	v_and_b32_e32 v93, 0xffff0000, v51
	v_lshlrev_b32_e32 v50, 16, v53
	v_and_b32_e32 v51, 0xffff0000, v53


; DEV unsigned cvt_pk_bf16(float lo, float hi) { const f32x2_t v = {lo, hi}; const bf16x2_t b = __builtin_convertvector(v, bf16x2_t); return __builtin_bit_cast(unsigned, b); }
; template <int WIN>
; DEV void pool_d_prompt8(const bf16_t* __restrict__ proj, bf16_t* __restrict__ dpl, int row0, int c8) {
;     ...
;         const float ic = 1.f / (float)min(WIN, t0 + j + 1);
;         uint4 o;
;         o.x = cvt_pk_bf16(acc[0] * ic - xs[0], acc[1] * ic - xs[1]); o.y = cvt_pk_bf16(acc[2] * ic - xs[2], acc[3] * ic - xs[3]);
	v_rcp_f32_e32 v13, v9
	s_nop 0
	v_mul_f32_e32 v52, 1.0, v13
	v_min_u32_e32 v9, 10, v144
	v_add_u32_e32 v9, 6, v9
	v_cvt_f32_ubyte0_e32 v9, v9

; DEV unsigned cvt_pk_bf16(float lo, float hi) { const f32x2_t v = {lo, hi}; const bf16x2_t b = __builtin_convertvector(v, bf16x2_t); return __builtin_bit_cast(unsigned, b); }
; DEV float bflo(unsigned u) { return __uint_as_float(u << 16); }
; DEV float bfhi(unsigned u) { return __uint_as_float(u & 0xffff0000u); }
; template <int WIN>
; DEV void pool_d_prompt8(const bf16_t* __restrict__ proj, bf16_t* __restrict__ dpl, int row0, int c8) {
;     ...
;         const float ic = 1.f / (float)min(WIN, t0 + j + 1);
;         uint4 o;
;         o.x = cvt_pk_bf16(acc[0] * ic - xs[0], acc[1] * ic - xs[1]); o.y = cvt_pk_bf16(acc[2] * ic - xs[2], acc[3] * ic - xs[3]);
;         o.z = cvt_pk_bf16(acc[4] * ic - xs[4], acc[5] * ic - xs[5]); o.w = cvt_pk_bf16(acc[6] * ic - xs[6], acc[7] * ic - xs[7]);
;         *(uint4*)(dpl + (size_t)(row0 + j) * LDP + c8) = o;
;         const uint4 y = u[j];
;         acc[0] -= bflo(y.x); acc[1] -= bfhi(y.x); acc[2] -= bflo(y.y); acc[3] -= bfhi(y.y); acc[4] -= bflo(y.z); acc[5] -= bfhi(y.z); acc[6] -= bflo(y.w); acc[7] -= bfhi(y.w);
	v_pk_add_f32 v[120:121], v[126:127], v[120:121] neg_lo:[0,1] neg_hi:[0,1]
	v_pk_add_f32 v[118:119], v[124:125], v[118:119] neg_lo:[0,1] neg_hi:[0,1]

; DEV unsigned cvt_pk_bf16(float lo, float hi) { const f32x2_t v = {lo, hi}; const bf16x2_t b = __builtin_convertvector(v, bf16x2_t); return __builtin_bit_cast(unsigned, b); }
; DEV float bflo(unsigned u) { return __uint_as_float(u << 16); }
; DEV float bfhi(unsigned u) { return __uint_as_float(u & 0xffff0000u); }
; template <int WIN>
; DEV void pool_d_prompt8(const bf16_t* __restrict__ proj, bf16_t* __restrict__ dpl, int row0, int c8) {
;     ...
;     for (int j = 0; j < 8; ++j) {
;         const uint4 x = u[j + WIN - 1];
;         const float xs[8] = {bflo(x.x), bfhi(x.x), bflo(x.y), bfhi(x.y), bflo(x.z), bfhi(x.z), bflo(x.w), bfhi(x.w)};
; #pragma unroll
;         for (int e_ = 0; e_ < 8; ++e_) acc[e_] += xs[e_];
;         const float ic = 1.f / (float)min(WIN, t0 + j + 1);
;         uint4 o;
;         o.x = cvt_pk_bf16(acc[0] * ic - xs[0], acc[1] * ic - xs[1]); o.y = cvt_pk_bf16(acc[2] * ic - xs[2], acc[3] * ic - xs[3]);
;         o.z = cvt_pk_bf16(acc[4] * ic - xs[4], acc[5] * ic - xs[5]); o.w = cvt_pk_bf16(acc[6] * ic - xs[6], acc[7] * ic - xs[7]);
;         *(uint4*)(dpl + (size_t)(row0 + j) * LDP + c8) = o;
;         const uint4 y = u[j];
;         acc[0] -= bflo(y.x); acc[1] -= bfhi(y.x); acc[2] -= bflo(y.y); acc[3] -= bfhi(y.y); acc[4] -= bflo(y.z); acc[5] -= bfhi(y.z); acc[6] -= bflo(y.w); acc[7] -= bfhi(y.w);
	v_pk_add_f32 v[120:121], v[120:121], v[88:89]
	v_pk_add_f32 v[118:119], v[118:119], v[92:93]
	v_pk_fma_f32 v[88:89], v[52:53], v[120:121], v[88:89] op_sel_hi:[0,1,1] neg_lo:[0,0,1] neg_hi:[0,0,1]
	v_pk_fma_f32 v[92:93], v[52:53], v[118:119], v[92:93] op_sel_hi:[0,1,1] neg_lo:[0,0,1] neg_hi:[0,0,1]
	v_pk_add_f32 v[90:91], v[90:91], v[116:117] neg_lo:[0,1] neg_hi:[0,1]
	v_cvt_pk_bf16_f32 v88, v88, v89
	v_cvt_pk_bf16_f32 v89, v92, v93
	v_pk_add_f32 v[92:93], v[90:91], v[122:123]
	s_waitcnt vmcnt(2)
	v_lshlrev_b32_e32 v116, 16, v34
	v_pk_fma_f32 v[90:91], v[52:53], v[92:93], v[122:123] op_sel_hi:[0,1,1] neg_lo:[0,0,1] neg_hi:[0,0,1]


; DEV unsigned cvt_pk_bf16(float lo, float hi) { const f32x2_t v = {lo, hi}; const bf16x2_t b = __builtin_convertvector(v, bf16x2_t); return __builtin_bit_cast(unsigned, b); }
; DEV float bflo(unsigned u) { return __uint_as_float(u << 16); }
; DEV float bfhi(unsigned u) { return __uint_as_float(u & 0xffff0000u); }
; template <int WIN>
; DEV void pool_d_prompt8(const bf16_t* __restrict__ proj, bf16_t* __restrict__ dpl, int row0, int c8) {
;     ...
;         const float ic = 1.f / (float)min(WIN, t0 + j + 1);
;         uint4 o;
;         o.x = cvt_pk_bf16(acc[0] * ic - xs[0], acc[1] * ic - xs[1]); o.y = cvt_pk_bf16(acc[2] * ic - xs[2], acc[3] * ic - xs[3]);
;         o.z = cvt_pk_bf16(acc[4] * ic - xs[4], acc[5] * ic - xs[5]); o.w = cvt_pk_bf16(acc[6] * ic - xs[6], acc[7] * ic - xs[7]);
;         *(uint4*)(dpl + (size_t)(row0 + j) * LDP + c8) = o;
;         const uint4 y = u[j];
;         acc[0] -= bflo(y.x); acc[1] -= bfhi(y.x); acc[2] -= bflo(y.y); acc[3] -= bfhi(y.y); acc[4] -= bflo(y.z); acc[5] -= bfhi(y.z); acc[6] -= bflo(y.w); acc[7] -= bfhi(y.w);
	v_rcp_f32_e32 v13, v9
	s_nop 0
	v_mul_f32_e32 v94, 1.0, v13
	v_min_u32_e32 v9, 9, v144
	v_add_u32_e32 v9, 7, v9
	v_cvt_f32_ubyte0_e32 v9, v9


; DEV unsigned cvt_pk_bf16(float lo, float hi) { const f32x2_t v = {lo, hi}; const bf16x2_t b = __builtin_convertvector(v, bf16x2_t); return __builtin_bit_cast(unsigned, b); }
; DEV float bflo(unsigned u) { return __uint_as_float(u << 16); }
; DEV float bfhi(unsigned u) { return __uint_as_float(u & 0xffff0000u); }
; template <int WIN>
; DEV void pool_d_prompt8(const bf16_t* __restrict__ proj, bf16_t* __restrict__ dpl, int row0, int c8) {
;     ...
;     for (int j = 0; j < 8; ++j) {
;         const uint4 x = u[j + WIN - 1];
;         const float xs[8] = {bflo(x.x), bfhi(x.x), bflo(x.y), bfhi(x.y), bflo(x.z), bfhi(x.z), bflo(x.w), bfhi(x.w)};
; #pragma unroll
;         for (int e_ = 0; e_ < 8; ++e_) acc[e_] += xs[e_];
;         const float ic = 1.f / (float)min(WIN, t0 + j + 1);
;         uint4 o;
;         o.x = cvt_pk_bf16(acc[0] * ic - xs[0], acc[1] * ic - xs[1]); o.y = cvt_pk_bf16(acc[2] * ic - xs[2], acc[3] * ic - xs[3]);
;         o.z = cvt_pk_bf16(acc[4] * ic - xs[4], acc[5] * ic - xs[5]); o.w = cvt_pk_bf16(acc[6] * ic - xs[6], acc[7] * ic - xs[7]);
;         *(uint4*)(dpl + (size_t)(row0 + j) * LDP + c8) = o;
;         const uint4 y = u[j];
;         acc[0] -= bflo(y.x); acc[1] -= bfhi(y.x); acc[2] -= bflo(y.y); acc[3] -= bfhi(y.y); acc[4] -= bflo(y.z); acc[5] -= bfhi(y.z); acc[6] -= bflo(y.w); acc[7] -= bfhi(y.w);
	v_and_b32_e32 v117, 0xffff0000, v34
	v_lshlrev_b32_e32 v34, 16, v35
	v_and_b32_e32 v35, 0xffff0000, v35
	v_pk_add_f32 v[114:115], v[120:121], v[114:115] neg_lo:[0,1] neg_hi:[0,1]
	v_pk_add_f32 v[112:113], v[118:119], v[112:113] neg_lo:[0,1] neg_hi:[0,1]
	v_pk_add_f32 v[120:121], v[114:115], v[116:117]
	v_pk_add_f32 v[112:113], v[112:113], v[34:35]
	v_pk_fma_f32 v[114:115], v[94:95], v[120:121], v[116:117] op_sel_hi:[0,1,1] neg_lo:[0,0,1] neg_hi:[0,0,1]
	v_pk_fma_f32 v[34:35], v[94:95], v[112:113], v[34:35] op_sel_hi:[0,1,1] neg_lo:[0,0,1] neg_hi:[0,0,1]
	v_lshlrev_b32_e32 v124, 16, v36
	v_and_b32_e32 v125, 0xffff0000, v36
	v_cvt_pk_bf16_f32 v114, v114, v115
	v_cvt_pk_bf16_f32 v115, v34, v35
	v_pk_add_f32 v[34:35], v[92:93], v[110:111] neg_lo:[0,1] neg_hi:[0,1]
	s_waitcnt vmcnt(1)
	v_lshlrev_b32_e32 v118, 16, v28
	v_and_b32_e32 v119, 0xffff0000, v28

; DEV unsigned cvt_pk_bf16(float lo, float hi) { const f32x2_t v = {lo, hi}; const bf16x2_t b = __builtin_convertvector(v, bf16x2_t); return __builtin_bit_cast(unsigned, b); }
; DEV float bflo(unsigned u) { return __uint_as_float(u << 16); }
; DEV float bfhi(unsigned u) { return __uint_as_float(u & 0xffff0000u); }
; template <int WIN>
; DEV void pool_d_prompt8(const bf16_t* __restrict__ proj, bf16_t* __restrict__ dpl, int row0, int c8) {
;     ...
;     for (int j = 0; j < 8; ++j) {
;         const uint4 x = u[j + WIN - 1];
;         const float xs[8] = {bflo(x.x), bfhi(x.x), bflo(x.y), bfhi(x.y), bflo(x.z), bfhi(x.z), bflo(x.w), bfhi(x.w)};
; #pragma unroll
;         for (int e_ = 0; e_ < 8; ++e_) acc[e_] += xs[e_];
;         const float ic = 1.f / (float)min(WIN, t0 + j + 1);
;         uint4 o;
;         o.x = cvt_pk_bf16(acc[0] * ic - xs[0], acc[1] * ic - xs[1]); o.y = cvt_pk_bf16(acc[2] * ic - xs[2], acc[3] * ic - xs[3]);
;         o.z = cvt_pk_bf16(acc[4] * ic - xs[4], acc[5] * ic - xs[5]); o.w = cvt_pk_bf16(acc[6] * ic - xs[6], acc[7] * ic - xs[7]);
;         *(uint4*)(dpl + (size_t)(row0 + j) * LDP + c8) = o;
;         const uint4 y = u[j];
;         acc[0] -= bflo(y.x); acc[1] -= bfhi(y.x); acc[2] -= bflo(y.y); acc[3] -= bfhi(y.y); acc[4] -= bflo(y.z); acc[5] -= bfhi(y.z); acc[6] -= bflo(y.w); acc[7] -= bfhi(y.w);
	v_pk_add_f32 v[34:35], v[34:35], v[124:125]


; DEV unsigned cvt_pk_bf16(float lo, float hi) { const f32x2_t v = {lo, hi}; const bf16x2_t b = __builtin_convertvector(v, bf16x2_t); return __builtin_bit_cast(unsigned, b); }
; DEV float bflo(unsigned u) { return __uint_as_float(u << 16); }
; DEV float bfhi(unsigned u) { return __uint_as_float(u & 0xffff0000u); }
; template <int WIN>
; DEV void pool_d_prompt8(const bf16_t* __restrict__ proj, bf16_t* __restrict__ dpl, int row0, int c8) {
;     ...
;     for (int j = 0; j < 8; ++j) {
;         const uint4 x = u[j + WIN - 1];
;         const float xs[8] = {bflo(x.x), bfhi(x.x), bflo(x.y), bfhi(x.y), bflo(x.z), bfhi(x.z), bflo(x.w), bfhi(x.w)};
; #pragma unroll
;         for (int e_ = 0; e_ < 8; ++e_) acc[e_] += xs[e_];
;         const float ic = 1.f / (float)min(WIN, t0 + j + 1);
;         uint4 o;
;         o.x = cvt_pk_bf16(acc[0] * ic - xs[0], acc[1] * ic - xs[1]); o.y = cvt_pk_bf16(acc[2] * ic - xs[2], acc[3] * ic - xs[3]);
;         o.z = cvt_pk_bf16(acc[4] * ic - xs[4], acc[5] * ic - xs[5]); o.w = cvt_pk_bf16(acc[6] * ic - xs[6], acc[7] * ic - xs[7]);
;         *(uint4*)(dpl + (size_t)(row0 + j) * LDP + c8) = o;
;         const uint4 y = u[j];
;         acc[0] -= bflo(y.x); acc[1] -= bfhi(y.x); acc[2] -= bflo(y.y); acc[3] -= bfhi(y.y); acc[4] -= bflo(y.z); acc[5] -= bfhi(y.z); acc[6] -= bflo(y.w); acc[7] -= bfhi(y.w);
	v_pk_fma_f32 v[92:93], v[94:95], v[34:35], v[124:125] op_sel_hi:[0,1,1] neg_lo:[0,0,1] neg_hi:[0,0,1]
	v_lshlrev_b32_e32 v124, 16, v29
	v_and_b32_e32 v125, 0xffff0000, v29


; DEV unsigned cvt_pk_bf16(float lo, float hi) { const f32x2_t v = {lo, hi}; const bf16x2_t b = __builtin_convertvector(v, bf16x2_t); return __builtin_bit_cast(unsigned, b); }
; DEV float bflo(unsigned u) { return __uint_as_float(u << 16); }
; DEV float bfhi(unsigned u) { return __uint_as_float(u & 0xffff0000u); }
; template <int WIN>
; DEV void pool_d_prompt8(const bf16_t* __restrict__ proj, bf16_t* __restrict__ dpl, int row0, int c8) {
;     ...
;         const float ic = 1.f / (float)min(WIN, t0 + j + 1);
;         uint4 o;
;         o.x = cvt_pk_bf16(acc[0] * ic - xs[0], acc[1] * ic - xs[1]); o.y = cvt_pk_bf16(acc[2] * ic - xs[2], acc[3] * ic - xs[3]);
;         o.z = cvt_pk_bf16(acc[4] * ic - xs[4], acc[5] * ic - xs[5]); o.w = cvt_pk_bf16(acc[6] * ic - xs[6], acc[7] * ic - xs[7]);
;         *(uint4*)(dpl + (size_t)(row0 + j) * LDP + c8) = o;
;         const uint4 y = u[j];
;         acc[0] -= bflo(y.x); acc[1] -= bfhi(y.x); acc[2] -= bflo(y.y); acc[3] -= bfhi(y.y); acc[4] -= bflo(y.z); acc[5] -= bfhi(y.z); acc[6] -= bflo(y.w); acc[7] -= bfhi(y.w);
	v_rcp_f32_e32 v13, v9
	s_nop 0
	v_mul_f32_e32 v126, 1.0, v13
	v_min_u32_e32 v9, 8, v144
	v_add_u32_e32 v9, 8, v9
	v_cvt_f32_ubyte0_e32 v9, v9


; DEV unsigned cvt_pk_bf16(float lo, float hi) { const f32x2_t v = {lo, hi}; const bf16x2_t b = __builtin_convertvector(v, bf16x2_t); return __builtin_bit_cast(unsigned, b); }
; DEV float bflo(unsigned u) { return __uint_as_float(u << 16); }
; DEV float bfhi(unsigned u) { return __uint_as_float(u & 0xffff0000u); }
; template <int WIN>
; DEV void pool_d_prompt8(const bf16_t* __restrict__ proj, bf16_t* __restrict__ dpl, int row0, int c8) {
;     ...
;     for (int j = 0; j < 8; ++j) {
;         const uint4 x = u[j + WIN - 1];
;         const float xs[8] = {bflo(x.x), bfhi(x.x), bflo(x.y), bfhi(x.y), bflo(x.z), bfhi(x.z), bflo(x.w), bfhi(x.w)};
; #pragma unroll
;         for (int e_ = 0; e_ < 8; ++e_) acc[e_] += xs[e_];
;         const float ic = 1.f / (float)min(WIN, t0 + j + 1);
;         uint4 o;
;         o.x = cvt_pk_bf16(acc[0] * ic - xs[0], acc[1] * ic - xs[1]); o.y = cvt_pk_bf16(acc[2] * ic - xs[2], acc[3] * ic - xs[3]);
;         o.z = cvt_pk_bf16(acc[4] * ic - xs[4], acc[5] * ic - xs[5]); o.w = cvt_pk_bf16(acc[6] * ic - xs[6], acc[7] * ic - xs[7]);
;         *(uint4*)(dpl + (size_t)(row0 + j) * LDP + c8) = o;
;         const uint4 y = u[j];
;         acc[0] -= bflo(y.x); acc[1] -= bfhi(y.x); acc[2] -= bflo(y.y); acc[3] -= bfhi(y.y); acc[4] -= bflo(y.z); acc[5] -= bfhi(y.z); acc[6] -= bflo(y.w); acc[7] -= bfhi(y.w);
	v_lshlrev_b32_e32 v110, 16, v26
	v_and_b32_e32 v111, 0xffff0000, v26
	v_lshlrev_b32_e32 v26, 16, v27
	v_and_b32_e32 v27, 0xffff0000, v27
	v_pk_add_f32 v[28:29], v[120:121], v[108:109] neg_lo:[0,1] neg_hi:[0,1]
	v_pk_add_f32 v[106:107], v[112:113], v[106:107] neg_lo:[0,1] neg_hi:[0,1]

; DEV unsigned cvt_pk_bf16(float lo, float hi) { const f32x2_t v = {lo, hi}; const bf16x2_t b = __builtin_convertvector(v, bf16x2_t); return __builtin_bit_cast(unsigned, b); }
; DEV float bflo(unsigned u) { return __uint_as_float(u << 16); }
; DEV float bfhi(unsigned u) { return __uint_as_float(u & 0xffff0000u); }
; template <int WIN>
; DEV void pool_d_prompt8(const bf16_t* __restrict__ proj, bf16_t* __restrict__ dpl, int row0, int c8) {
;     ...
;     for (int j = 0; j < 8; ++j) {
;         const uint4 x = u[j + WIN - 1];
;         const float xs[8] = {bflo(x.x), bfhi(x.x), bflo(x.y), bfhi(x.y), bflo(x.z), bfhi(x.z), bflo(x.w), bfhi(x.w)};
; #pragma unroll
;         for (int e_ = 0; e_ < 8; ++e_) acc[e_] += xs[e_];
;         const float ic = 1.f / (float)min(WIN, t0 + j + 1);
;         uint4 o;
;         o.x = cvt_pk_bf16(acc[0] * ic - xs[0], acc[1] * ic - xs[1]); o.y = cvt_pk_bf16(acc[2] * ic - xs[2], acc[3] * ic - xs[3]);
;         o.z = cvt_pk_bf16(acc[4] * ic - xs[4], acc[5] * ic - xs[5]); o.w = cvt_pk_bf16(acc[6] * ic - xs[6], acc[7] * ic - xs[7]);
;         *(uint4*)(dpl + (size_t)(row0 + j) * LDP + c8) = o;
;         const uint4 y = u[j];
;         acc[0] -= bflo(y.x); acc[1] -= bfhi(y.x); acc[2] -= bflo(y.y); acc[3] -= bfhi(y.y); acc[4] -= bflo(y.z); acc[5] -= bfhi(y.z); acc[6] -= bflo(y.w); acc[7] -= bfhi(y.w);
	v_pk_add_f32 v[28:29], v[28:29], v[110:111]
	v_pk_add_f32 v[106:107], v[106:107], v[26:27]


; DEV unsigned cvt_pk_bf16(float lo, float hi) { const f32x2_t v = {lo, hi}; const bf16x2_t b = __builtin_convertvector(v, bf16x2_t); return __builtin_bit_cast(unsigned, b); }
; DEV float bflo(unsigned u) { return __uint_as_float(u << 16); }
; DEV float bfhi(unsigned u) { return __uint_as_float(u & 0xffff0000u); }
; template <int WIN>
; DEV void pool_d_prompt8(const bf16_t* __restrict__ proj, bf16_t* __restrict__ dpl, int row0, int c8) {
;     ...
;     for (int j = 0; j < 8; ++j) {
;         const uint4 x = u[j + WIN - 1];
;         const float xs[8] = {bflo(x.x), bfhi(x.x), bflo(x.y), bfhi(x.y), bflo(x.z), bfhi(x.z), bflo(x.w), bfhi(x.w)};
; #pragma unroll
;         for (int e_ = 0; e_ < 8; ++e_) acc[e_] += xs[e_];
;         const float ic = 1.f / (float)min(WIN, t0 + j + 1);
;         uint4 o;
;         o.x = cvt_pk_bf16(acc[0] * ic - xs[0], acc[1] * ic - xs[1]); o.y = cvt_pk_bf16(acc[2] * ic - xs[2], acc[3] * ic - xs[3]);
;         o.z = cvt_pk_bf16(acc[4] * ic - xs[4], acc[5] * ic - xs[5]); o.w = cvt_pk_bf16(acc[6] * ic - xs[6], acc[7] * ic - xs[7]);
;         *(uint4*)(dpl + (size_t)(row0 + j) * LDP + c8) = o;
;         const uint4 y = u[j];
;         acc[0] -= bflo(y.x); acc[1] -= bfhi(y.x); acc[2] -= bflo(y.y); acc[3] -= bfhi(y.y); acc[4] -= bflo(y.z); acc[5] -= bfhi(y.z); acc[6] -= bflo(y.w); acc[7] -= bfhi(y.w);
	v_pk_fma_f32 v[108:109], v[126:127], v[28:29], v[110:111] op_sel_hi:[0,1,1] neg_lo:[0,0,1] neg_hi:[0,0,1]
	v_pk_fma_f32 v[26:27], v[126:127], v[106:107], v[26:27] op_sel_hi:[0,1,1] neg_lo:[0,0,1] neg_hi:[0,0,1]

; DEV unsigned cvt_pk_bf16(float lo, float hi) { const f32x2_t v = {lo, hi}; const bf16x2_t b = __builtin_convertvector(v, bf16x2_t); return __builtin_bit_cast(unsigned, b); }
; DEV float bflo(unsigned u) { return __uint_as_float(u << 16); }
; DEV float bfhi(unsigned u) { return __uint_as_float(u & 0xffff0000u); }
; template <int WIN>
; DEV void pool_d_prompt8(const bf16_t* __restrict__ proj, bf16_t* __restrict__ dpl, int row0, int c8) {
;     ...
;     for (int j = 0; j < 8; ++j) {
;         const uint4 x = u[j + WIN - 1];
;         const float xs[8] = {bflo(x.x), bfhi(x.x), bflo(x.y), bfhi(x.y), bflo(x.z), bfhi(x.z), bflo(x.w), bfhi(x.w)};
; #pragma unroll
;         for (int e_ = 0; e_ < 8; ++e_) acc[e_] += xs[e_];
;         const float ic = 1.f / (float)min(WIN, t0 + j + 1);
;         uint4 o;
;         o.x = cvt_pk_bf16(acc[0] * ic - xs[0], acc[1] * ic - xs[1]); o.y = cvt_pk_bf16(acc[2] * ic - xs[2], acc[3] * ic - xs[3]);
;         o.z = cvt_pk_bf16(acc[4] * ic - xs[4], acc[5] * ic - xs[5]); o.w = cvt_pk_bf16(acc[6] * ic - xs[6], acc[7] * ic - xs[7]);
;         *(uint4*)(dpl + (size_t)(row0 + j) * LDP + c8) = o;
;         const uint4 y = u[j];
;         acc[0] -= bflo(y.x); acc[1] -= bfhi(y.x); acc[2] -= bflo(y.y); acc[3] -= bfhi(y.y); acc[4] -= bflo(y.z); acc[5] -= bfhi(y.z); acc[6] -= bflo(y.w); acc[7] -= bfhi(y.w);
	v_cvt_pk_bf16_f32 v108, v108, v109
	v_cvt_pk_bf16_f32 v109, v26, v27
	v_pk_add_f32 v[26:27], v[34:35], v[46:47] neg_lo:[0,1] neg_hi:[0,1]

; DEV unsigned cvt_pk_bf16(float lo, float hi) { const f32x2_t v = {lo, hi}; const bf16x2_t b = __builtin_convertvector(v, bf16x2_t); return __builtin_bit_cast(unsigned, b); }
; DEV float bflo(unsigned u) { return __uint_as_float(u << 16); }
; DEV float bfhi(unsigned u) { return __uint_as_float(u & 0xffff0000u); }
; template <int WIN>
; DEV void pool_d_prompt8(const bf16_t* __restrict__ proj, bf16_t* __restrict__ dpl, int row0, int c8) {
;     ...
;     for (int j = 0; j < 8; ++j) {
;         const uint4 x = u[j + WIN - 1];
;         const float xs[8] = {bflo(x.x), bfhi(x.x), bflo(x.y), bfhi(x.y), bflo(x.z), bfhi(x.z), bflo(x.w), bfhi(x.w)};
; #pragma unroll
;         for (int e_ = 0; e_ < 8; ++e_) acc[e_] += xs[e_];
;         const float ic = 1.f / (float)min(WIN, t0 + j + 1);
;         uint4 o;
;         o.x = cvt_pk_bf16(acc[0] * ic - xs[0], acc[1] * ic - xs[1]); o.y = cvt_pk_bf16(acc[2] * ic - xs[2], acc[3] * ic - xs[3]);
;         o.z = cvt_pk_bf16(acc[4] * ic - xs[4], acc[5] * ic - xs[5]); o.w = cvt_pk_bf16(acc[6] * ic - xs[6], acc[7] * ic - xs[7]);
;         *(uint4*)(dpl + (size_t)(row0 + j) * LDP + c8) = o;
;         const uint4 y = u[j];
;         acc[0] -= bflo(y.x); acc[1] -= bfhi(y.x); acc[2] -= bflo(y.y); acc[3] -= bfhi(y.y); acc[4] -= bflo(y.z); acc[5] -= bfhi(y.z); acc[6] -= bflo(y.w); acc[7] -= bfhi(y.w);
	v_pk_add_f32 v[34:35], v[26:27], v[118:119]

; DEV unsigned cvt_pk_bf16(float lo, float hi) { const f32x2_t v = {lo, hi}; const bf16x2_t b = __builtin_convertvector(v, bf16x2_t); return __builtin_bit_cast(unsigned, b); }
; DEV float bflo(unsigned u) { return __uint_as_float(u << 16); }
; DEV float bfhi(unsigned u) { return __uint_as_float(u & 0xffff0000u); }
; template <int WIN>
; DEV void pool_d_prompt8(const bf16_t* __restrict__ proj, bf16_t* __restrict__ dpl, int row0, int c8) {
;     ...
;     for (int j = 0; j < 8; ++j) {
;         const uint4 x = u[j + WIN - 1];
;         const float xs[8] = {bflo(x.x), bfhi(x.x), bflo(x.y), bfhi(x.y), bflo(x.z), bfhi(x.z), bflo(x.w), bfhi(x.w)};
; #pragma unroll
;         for (int e_ = 0; e_ < 8; ++e_) acc[e_] += xs[e_];
;         const float ic = 1.f / (float)min(WIN, t0 + j + 1);
;         uint4 o;
;         o.x = cvt_pk_bf16(acc[0] * ic - xs[0], acc[1] * ic - xs[1]); o.y = cvt_pk_bf16(acc[2] * ic - xs[2], acc[3] * ic - xs[3]);
;         o.z = cvt_pk_bf16(acc[4] * ic - xs[4], acc[5] * ic - xs[5]); o.w = cvt_pk_bf16(acc[6] * ic - xs[6], acc[7] * ic - xs[7]);
;         *(uint4*)(dpl + (size_t)(row0 + j) * LDP + c8) = o;
;         const uint4 y = u[j];
;         acc[0] -= bflo(y.x); acc[1] -= bfhi(y.x); acc[2] -= bflo(y.y); acc[3] -= bfhi(y.y); acc[4] -= bflo(y.z); acc[5] -= bfhi(y.z); acc[6] -= bflo(y.w); acc[7] -= bfhi(y.w);
	v_pk_fma_f32 v[26:27], v[126:127], v[34:35], v[118:119] op_sel_hi:[0,1,1] neg_lo:[0,0,1] neg_hi:[0,0,1]

; DEV unsigned cvt_pk_bf16(float lo, float hi) { const f32x2_t v = {lo, hi}; const bf16x2_t b = __builtin_convertvector(v, bf16x2_t); return __builtin_bit_cast(unsigned, b); }
; DEV float bflo(unsigned u) { return __uint_as_float(u << 16); }
; DEV float bfhi(unsigned u) { return __uint_as_float(u & 0xffff0000u); }
; template <int WIN>
; DEV void pool_d_prompt8(const bf16_t* __restrict__ proj, bf16_t* __restrict__ dpl, int row0, int c8) {
;     ...
;     for (int j = 0; j < 8; ++j) {
;         const uint4 x = u[j + WIN - 1];
;         const float xs[8] = {bflo(x.x), bfhi(x.x), bflo(x.y), bfhi(x.y), bflo(x.z), bfhi(x.z), bflo(x.w), bfhi(x.w)};
; #pragma unroll
;         for (int e_ = 0; e_ < 8; ++e_) acc[e_] += xs[e_];
;         const float ic = 1.f / (float)min(WIN, t0 + j + 1);
;         uint4 o;
;         o.x = cvt_pk_bf16(acc[0] * ic - xs[0], acc[1] * ic - xs[1]); o.y = cvt_pk_bf16(acc[2] * ic - xs[2], acc[3] * ic - xs[3]);
;         o.z = cvt_pk_bf16(acc[4] * ic - xs[4], acc[5] * ic - xs[5]); o.w = cvt_pk_bf16(acc[6] * ic - xs[6], acc[7] * ic - xs[7]);
;         *(uint4*)(dpl + (size_t)(row0 + j) * LDP + c8) = o;
;         const uint4 y = u[j];
;         acc[0] -= bflo(y.x); acc[1] -= bfhi(y.x); acc[2] -= bflo(y.y); acc[3] -= bfhi(y.y); acc[4] -= bflo(y.z); acc[5] -= bfhi(y.z); acc[6] -= bflo(y.w); acc[7] -= bfhi(y.w);
	v_cvt_pk_bf16_f32 v110, v26, v27
	s_waitcnt vmcnt(0)
	v_lshlrev_b32_e32 v26, 16, v14
	v_and_b32_e32 v27, 0xffff0000, v14

; DEV unsigned cvt_pk_bf16(float lo, float hi) { const f32x2_t v = {lo, hi}; const bf16x2_t b = __builtin_convertvector(v, bf16x2_t); return __builtin_bit_cast(unsigned, b); }
; DEV float bflo(unsigned u) { return __uint_as_float(u << 16); }
; DEV float bfhi(unsigned u) { return __uint_as_float(u & 0xffff0000u); }
; template <int WIN>
; DEV void pool_d_prompt8(const bf16_t* __restrict__ proj, bf16_t* __restrict__ dpl, int row0, int c8) {
;     ...
;     for (int i = 0; i < WIN - 1; ++i) { acc[0] += bflo(u[i].x); acc[1] += bfhi(u[i].x); acc[2] += bflo(u[i].y); acc[3] += bfhi(u[i].y); acc[4] += bflo(u[i].z); acc[5] += bfhi(u[i].z); acc[6] += bflo(u[i].w); acc[7] += bfhi(u[i].w); }
; #pragma unroll
;     for (int j = 0; j < 8; ++j) {
;         const uint4 x = u[j + WIN - 1];
;         const float xs[8] = {bflo(x.x), bfhi(x.x), bflo(x.y), bfhi(x.y), bflo(x.z), bfhi(x.z), bflo(x.w), bfhi(x.w)};
; #pragma unroll
;         for (int e_ = 0; e_ < 8; ++e_) acc[e_] += xs[e_];
;         const float ic = 1.f / (float)min(WIN, t0 + j + 1);
;         uint4 o;
;         o.x = cvt_pk_bf16(acc[0] * ic - xs[0], acc[1] * ic - xs[1]); o.y = cvt_pk_bf16(acc[2] * ic - xs[2], acc[3] * ic - xs[3]);
;         o.z = cvt_pk_bf16(acc[4] * ic - xs[4], acc[5] * ic - xs[5]); o.w = cvt_pk_bf16(acc[6] * ic - xs[6], acc[7] * ic - xs[7]);
;         *(uint4*)(dpl + (size_t)(row0 + j) * LDP + c8) = o;
;         const uint4 y = u[j];
;         acc[0] -= bflo(y.x); acc[1] -= bfhi(y.x); acc[2] -= bflo(y.y); acc[3] -= bfhi(y.y); acc[4] -= bflo(y.z); acc[5] -= bfhi(y.z); acc[6] -= bflo(y.w); acc[7] -= bfhi(y.w);
	v_pk_add_f32 v[28:29], v[28:29], v[40:41] neg_lo:[0,1] neg_hi:[0,1]
	v_rcp_f32_e32 v13, v9
	s_nop 0
	v_mul_f32_e32 v112, 1.0, v13
	v_pk_add_f32 v[28:29], v[28:29], v[26:27]
	v_lshlrev_b32_e32 v14, 16, v15
	v_and_b32_e32 v15, 0xffff0000, v15
	v_pk_fma_f32 v[26:27], v[112:113], v[28:29], v[26:27] op_sel_hi:[0,1,1] neg_lo:[0,0,1] neg_hi:[0,0,1]
	v_pk_add_f32 v[28:29], v[106:107], v[42:43] neg_lo:[0,1] neg_hi:[0,1]
	v_mad_i64_i32 v[72:73], s[4:5], v145, s27, v[70:71]
	v_pk_add_f32 v[28:29], v[28:29], v[14:15]
	v_mad_i64_i32 v[82:83], s[4:5], v149, s27, v[70:71]
	v_cvt_pk_bf16_f32 v10, v10, v11
	v_cvt_pk_bf16_f32 v11, v84, v85
	v_mad_i64_i32 v[84:85], s[4:5], v200, s27, v[70:71]
	v_mad_i64_i32 v[86:87], s[4:5], v201, s27, v[70:71]
	v_mad_i64_i32 v[122:123], s[4:5], v148, s27, v[70:71]
	v_cvt_pk_bf16_f32 v116, v92, v93
	v_mad_i64_i32 v[92:93], s[4:5], v147, s27, v[70:71]
	v_mad_i64_i32 v[46:47], s[4:5], v146, s27, v[70:71]
	v_lshlrev_b32_e32 v70, 16, v16
	v_and_b32_e32 v71, 0xffff0000, v16
	v_pk_fma_f32 v[28:29], v[112:113], v[28:29], v[14:15] op_sel_hi:[0,1,1] neg_lo:[0,0,1] neg_hi:[0,0,1]
	v_pk_add_f32 v[14:15], v[34:35], v[48:49] neg_lo:[0,1] neg_hi:[0,1]
	v_lshlrev_b32_e32 v40, 16, v5
	v_pk_add_f32 v[14:15], v[14:15], v[70:71]
	v_and_b32_e32 v41, 0xffff0000, v5
	v_pk_fma_f32 v[34:35], v[112:113], v[14:15], v[70:71] op_sel_hi:[0,1,1] neg_lo:[0,0,1] neg_hi:[0,0,1]
	v_pk_add_f32 v[14:15], v[104:105], 0 op_sel_hi:[1,0]
	v_lshlrev_b32_e32 v36, 16, v37
	v_pk_add_f32 v[14:15], v[14:15], v[102:103]
	v_and_b32_e32 v37, 0xffff0000, v37
	v_pk_add_f32 v[14:15], v[14:15], v[100:101]
	v_cvt_pk_bf16_f32 v90, v90, v91
	v_pk_add_f32 v[14:15], v[14:15], v[98:99]
	v_lshlrev_b32_e32 v16, 16, v17
	v_pk_add_f32 v[14:15], v[14:15], v[24:25]
	v_and_b32_e32 v17, 0xffff0000, v17
	v_pk_add_f32 v[14:15], v[14:15], v[22:23]
	v_ashrrev_i32_e32 v97, 31, v96
	v_pk_add_f32 v[14:15], v[14:15], v[38:39]
	s_nop 0
	v_pk_add_f32 v[14:15], v[14:15], v[30:31]
	s_nop 0
	v_pk_add_f32 v[14:15], v[14:15], v[32:33]
	s_nop 0
	v_pk_add_f32 v[14:15], v[14:15], v[44:45]
	s_nop 0
	v_pk_add_f32 v[14:15], v[14:15], v[54:55]
	s_nop 0
	v_pk_add_f32 v[14:15], v[14:15], v[56:57]
	s_nop 0
	v_pk_add_f32 v[14:15], v[14:15], v[58:59]
	s_nop 0
	v_pk_add_f32 v[14:15], v[14:15], v[60:61]
	s_nop 0
	v_pk_add_f32 v[14:15], v[14:15], v[40:41]
	s_nop 0
	v_pk_add_f32 v[14:15], v[14:15], v[66:67]
	s_nop 0
	v_pk_fma_f32 v[30:31], v[68:69], v[14:15], v[66:67] op_sel_hi:[0,1,1] neg_lo:[0,0,1] neg_hi:[0,0,1]
	v_cvt_pk_bf16_f32 v5, v30, v31
	global_store_dwordx4 v[72:73], v[2:5], off
	s_nop 1
	v_pk_add_f32 v[2:3], v[14:15], v[104:105] neg_lo:[0,1] neg_hi:[0,1]
	s_nop 0
	v_pk_add_f32 v[2:3], v[2:3], v[78:79]
	s_nop 0
	v_pk_fma_f32 v[4:5], v[80:81], v[2:3], v[78:79] op_sel_hi:[0,1,1] neg_lo:[0,0,1] neg_hi:[0,0,1]
	v_pk_add_f32 v[2:3], v[2:3], v[102:103] neg_lo:[0,1] neg_hi:[0,1]
	v_cvt_pk_bf16_f32 v9, v4, v5
	v_pk_add_f32 v[2:3], v[2:3], v[74:75]
	global_store_dwordx4 v[82:83], v[6:9], off
	v_pk_fma_f32 v[4:5], v[76:77], v[2:3], v[74:75] op_sel_hi:[0,1,1] neg_lo:[0,0,1] neg_hi:[0,0,1]
	v_pk_add_f32 v[2:3], v[2:3], v[100:101] neg_lo:[0,1] neg_hi:[0,1]
	v_cvt_pk_bf16_f32 v13, v4, v5
	v_pk_add_f32 v[2:3], v[2:3], v[62:63]
	global_store_dwordx4 v[84:85], v[10:13], off
	v_pk_fma_f32 v[4:5], v[64:65], v[2:3], v[62:63] op_sel_hi:[0,1,1] neg_lo:[0,0,1] neg_hi:[0,0,1]
	v_pk_add_f32 v[2:3], v[2:3], v[98:99] neg_lo:[0,1] neg_hi:[0,1]
	v_cvt_pk_bf16_f32 v21, v4, v5
	v_pk_add_f32 v[2:3], v[2:3], v[50:51]
	global_store_dwordx4 v[86:87], v[18:21], off
	v_pk_fma_f32 v[4:5], v[52:53], v[2:3], v[50:51] op_sel_hi:[0,1,1] neg_lo:[0,0,1] neg_hi:[0,0,1]
	v_pk_add_f32 v[2:3], v[2:3], v[24:25] neg_lo:[0,1] neg_hi:[0,1]
	v_cvt_pk_bf16_f32 v91, v4, v5
	v_pk_add_f32 v[2:3], v[2:3], v[36:37]
	global_store_dwordx4 v[122:123], v[88:91], off
	v_pk_fma_f32 v[4:5], v[94:95], v[2:3], v[36:37] op_sel_hi:[0,1,1] neg_lo:[0,0,1] neg_hi:[0,0,1]
	v_pk_add_f32 v[2:3], v[2:3], v[22:23] neg_lo:[0,1] neg_hi:[0,1]
	v_cvt_pk_bf16_f32 v117, v4, v5
	v_pk_add_f32 v[2:3], v[2:3], v[124:125]
	global_store_dwordx4 v[92:93], v[114:117], off
	v_pk_fma_f32 v[4:5], v[126:127], v[2:3], v[124:125] op_sel_hi:[0,1,1] neg_lo:[0,0,1] neg_hi:[0,0,1]
	v_pk_add_f32 v[2:3], v[2:3], v[38:39] neg_lo:[0,1] neg_hi:[0,1]
	v_cvt_pk_bf16_f32 v111, v4, v5
	v_pk_add_f32 v[2:3], v[2:3], v[16:17]
	global_store_dwordx4 v[46:47], v[108:111], off
	v_pk_fma_f32 v[2:3], v[112:113], v[2:3], v[16:17] op_sel_hi:[0,1,1] neg_lo:[0,0,1] neg_hi:[0,0,1]

; DEV float bflo(unsigned u) { return __uint_as_float(u << 16); }
; DEV float bfhi(unsigned u) { return __uint_as_float(u & 0xffff0000u); }
; template <int WIN>
; DEV void pool_d_prompt8(const bf16_t* __restrict__ proj, bf16_t* __restrict__ dpl, int row0, int c8) {
;     ...
;     for (int i = 0; i < WIN + 7; ++i) { const int tt = t0 - (WIN - 1) + i; u[i] = (tt >= 0) ? *(const uint4*)(proj + (size_t)(row0 - (WIN - 1) + i) * NPJ + C_U + c8) : make_uint4(0u, 0u, 0u, 0u); }
;     float acc[8] = {0.f, 0.f, 0.f, 0.f, 0.f, 0.f, 0.f, 0.f};
; #pragma unroll
;     for (int i = 0; i < WIN - 1; ++i) { acc[0] += bflo(u[i].x); acc[1] += bfhi(u[i].x); acc[2] += bflo(u[i].y); acc[3] += bfhi(u[i].y); acc[4] += bflo(u[i].z); acc[5] += bfhi(u[i].z); acc[6] += bflo(u[i].w); acc[7] += bfhi(u[i].w); }
; #pragma unroll
;     for (int j = 0; j < 8; ++j) {
;         const uint4 x = u[j + WIN - 1];
;         const float xs[8] = {bflo(x.x), bfhi(x.x), bflo(x.y), bfhi(x.y), bflo(x.z), bfhi(x.z), bflo(x.w), bfhi(x.w)};
; #pragma unroll
;         for (int e_ = 0; e_ < 8; ++e_) acc[e_] += xs[e_];
;         const float ic = 1.f / (float)min(WIN, t0 + j + 1);
.LBB0_732:
	s_or_b64 exec, exec, s[22:23]
	v_mad_i64_i32 v[2:3], s[4:5], v145, s25, v[172:173]
	v_lshlrev_b32_e32 v94, 1, v143
	v_lshl_add_u64 v[2:3], v[2:3], 0, v[94:95]
	v_or_b32_e32 v118, 1, v145
	v_add_co_u32_e32 v2, vcc, 0x2000, v2
	v_mad_i64_i32 v[4:5], s[4:5], v118, s25, v[172:173]
	s_nop 0
	v_addc_co_u32_e32 v3, vcc, 0, v3, vcc
	v_lshl_add_u64 v[4:5], v[4:5], 0, v[94:95]
	v_add_co_u32_e32 v4, vcc, 0x2000, v4
	v_or_b32_e32 v119, 2, v145
	s_nop 0
	v_addc_co_u32_e32 v5, vcc, 0, v5, vcc
	global_load_dwordx4 v[100:103], v[2:3], off
	global_load_dwordx4 v[104:107], v[4:5], off
	v_mad_i64_i32 v[2:3], s[4:5], v119, s25, v[172:173]
	v_lshl_add_u64 v[2:3], v[2:3], 0, v[94:95]
	v_or_b32_e32 v120, 3, v145
	v_add_co_u32_e32 v2, vcc, 0x2000, v2
	v_mad_i64_i32 v[4:5], s[4:5], v120, s25, v[172:173]
	s_nop 0
	v_addc_co_u32_e32 v3, vcc, 0, v3, vcc
	v_lshl_add_u64 v[4:5], v[4:5], 0, v[94:95]
	v_add_co_u32_e32 v4, vcc, 0x2000, v4
	v_or_b32_e32 v121, 4, v145
	s_nop 0
	v_addc_co_u32_e32 v5, vcc, 0, v5, vcc
	global_load_dwordx4 v[38:41], v[2:3], off
	global_load_dwordx4 v[26:29], v[4:5], off
	v_mad_i64_i32 v[2:3], s[4:5], v121, s25, v[172:173]
	v_lshl_add_u64 v[2:3], v[2:3], 0, v[94:95]
	v_or_b32_e32 v122, 5, v145
	v_add_co_u32_e32 v2, vcc, 0x2000, v2
	v_mad_i64_i32 v[4:5], s[4:5], v122, s25, v[172:173]
	s_nop 0
	v_addc_co_u32_e32 v3, vcc, 0, v3, vcc
	v_lshl_add_u64 v[4:5], v[4:5], 0, v[94:95]
	s_waitcnt vmcnt(4)
	v_lshlrev_b32_e32 v108, 16, v23
	v_and_b32_e32 v109, 0xffff0000, v23
	v_min_u32_e32 v23, 7, v144
	v_add_co_u32_e32 v4, vcc, 0x2000, v4
	v_or_b32_e32 v123, 6, v145
	v_add_u32_e32 v23, 1, v23
	v_addc_co_u32_e32 v5, vcc, 0, v5, vcc
	global_load_dwordx4 v[18:21], v[2:3], off
	global_load_dwordx4 v[10:13], v[4:5], off
	v_mad_i64_i32 v[2:3], s[4:5], v123, s25, v[172:173]
	v_lshlrev_b32_e32 v110, 16, v24
	v_and_b32_e32 v111, 0xffff0000, v24
	v_cvt_f32_ubyte0_e32 v24, v23
	v_lshl_add_u64 v[2:3], v[2:3], 0, v[94:95]
	v_lshlrev_b32_e32 v60, 16, v25
	v_and_b32_e32 v61, 0xffff0000, v25

; DEV float bflo(unsigned u) { return __uint_as_float(u << 16); }
; DEV float bfhi(unsigned u) { return __uint_as_float(u & 0xffff0000u); }
; template <int WIN>
; DEV void pool_d_prompt8(const bf16_t* __restrict__ proj, bf16_t* __restrict__ dpl, int row0, int c8) {
;     ...
;     for (int i = 0; i < WIN + 7; ++i) { const int tt = t0 - (WIN - 1) + i; u[i] = (tt >= 0) ? *(const uint4*)(proj + (size_t)(row0 - (WIN - 1) + i) * NPJ + C_U + c8) : make_uint4(0u, 0u, 0u, 0u); }
;     float acc[8] = {0.f, 0.f, 0.f, 0.f, 0.f, 0.f, 0.f, 0.f};
; #pragma unroll
;     for (int i = 0; i < WIN - 1; ++i) { acc[0] += bflo(u[i].x); acc[1] += bfhi(u[i].x); acc[2] += bflo(u[i].y); acc[3] += bfhi(u[i].y); acc[4] += bflo(u[i].z); acc[5] += bfhi(u[i].z); acc[6] += bflo(u[i].w); acc[7] += bfhi(u[i].w); }
; #pragma unroll
;     for (int j = 0; j < 8; ++j) {
;         const uint4 x = u[j + WIN - 1];
;         const float xs[8] = {bflo(x.x), bfhi(x.x), bflo(x.y), bfhi(x.y), bflo(x.z), bfhi(x.z), bflo(x.w), bfhi(x.w)};
; #pragma unroll
;         for (int e_ = 0; e_ < 8; ++e_) acc[e_] += xs[e_];
;         const float ic = 1.f / (float)min(WIN, t0 + j + 1);
	v_add_co_u32_e32 v54, vcc, 0x2000, v2
	v_or_b32_e32 v96, 7, v98
	v_lshlrev_b32_e32 v86, 16, v30
	v_and_b32_e32 v87, 0xffff0000, v30

; DEV float bflo(unsigned u) { return __uint_as_float(u << 16); }
; DEV float bfhi(unsigned u) { return __uint_as_float(u & 0xffff0000u); }
; template <int WIN>
; DEV void pool_d_prompt8(const bf16_t* __restrict__ proj, bf16_t* __restrict__ dpl, int row0, int c8) {
;     ...
;     for (int i = 0; i < WIN + 7; ++i) { const int tt = t0 - (WIN - 1) + i; u[i] = (tt >= 0) ? *(const uint4*)(proj + (size_t)(row0 - (WIN - 1) + i) * NPJ + C_U + c8) : make_uint4(0u, 0u, 0u, 0u); }
;     float acc[8] = {0.f, 0.f, 0.f, 0.f, 0.f, 0.f, 0.f, 0.f};
; #pragma unroll
;     for (int i = 0; i < WIN - 1; ++i) { acc[0] += bflo(u[i].x); acc[1] += bfhi(u[i].x); acc[2] += bflo(u[i].y); acc[3] += bfhi(u[i].y); acc[4] += bflo(u[i].z); acc[5] += bfhi(u[i].z); acc[6] += bflo(u[i].w); acc[7] += bfhi(u[i].w); }
; #pragma unroll
;     for (int j = 0; j < 8; ++j) {
;         const uint4 x = u[j + WIN - 1];
;         const float xs[8] = {bflo(x.x), bfhi(x.x), bflo(x.y), bfhi(x.y), bflo(x.z), bfhi(x.z), bflo(x.w), bfhi(x.w)};
; #pragma unroll
;         for (int e_ = 0; e_ < 8; ++e_) acc[e_] += xs[e_];
;         const float ic = 1.f / (float)min(WIN, t0 + j + 1);
	v_addc_co_u32_e32 v55, vcc, 0, v3, vcc
	v_mad_i64_i32 v[2:3], s[4:5], v96, s25, v[172:173]
	v_lshl_add_u64 v[2:3], v[2:3], 0, v[94:95]
	v_add_co_u32_e32 v56, vcc, s26, v2
	v_lshlrev_b32_e32 v80, 16, v31
	s_nop 0
	v_addc_co_u32_e32 v57, vcc, 0, v3, vcc
	v_and_b32_e32 v81, 0xffff0000, v31


; DEV float bflo(unsigned u) { return __uint_as_float(u << 16); }
; DEV float bfhi(unsigned u) { return __uint_as_float(u & 0xffff0000u); }
; template <int WIN>
; DEV void pool_d_prompt8(const bf16_t* __restrict__ proj, bf16_t* __restrict__ dpl, int row0, int c8) {
;     ...
;     for (int i = 0; i < WIN + 7; ++i) { const int tt = t0 - (WIN - 1) + i; u[i] = (tt >= 0) ? *(const uint4*)(proj + (size_t)(row0 - (WIN - 1) + i) * NPJ + C_U + c8) : make_uint4(0u, 0u, 0u, 0u); }
;     float acc[8] = {0.f, 0.f, 0.f, 0.f, 0.f, 0.f, 0.f, 0.f};
; #pragma unroll
;     for (int i = 0; i < WIN - 1; ++i) { acc[0] += bflo(u[i].x); acc[1] += bfhi(u[i].x); acc[2] += bflo(u[i].y); acc[3] += bfhi(u[i].y); acc[4] += bflo(u[i].z); acc[5] += bfhi(u[i].z); acc[6] += bflo(u[i].w); acc[7] += bfhi(u[i].w); }
; #pragma unroll
;     for (int j = 0; j < 8; ++j) {
;         const uint4 x = u[j + WIN - 1];
;         const float xs[8] = {bflo(x.x), bfhi(x.x), bflo(x.y), bfhi(x.y), bflo(x.z), bfhi(x.z), bflo(x.w), bfhi(x.w)};
; #pragma unroll
;         for (int e_ = 0; e_ < 8; ++e_) acc[e_] += xs[e_];
;         const float ic = 1.f / (float)min(WIN, t0 + j + 1);
	v_lshlrev_b32_e32 v78, 16, v32
	v_and_b32_e32 v79, 0xffff0000, v32

; DEV float bflo(unsigned u) { return __uint_as_float(u << 16); }
; DEV float bfhi(unsigned u) { return __uint_as_float(u & 0xffff0000u); }
; template <int WIN>
; DEV void pool_d_prompt8(const bf16_t* __restrict__ proj, bf16_t* __restrict__ dpl, int row0, int c8) {
;     ...
;     for (int i = 0; i < WIN + 7; ++i) { const int tt = t0 - (WIN - 1) + i; u[i] = (tt >= 0) ? *(const uint4*)(proj + (size_t)(row0 - (WIN - 1) + i) * NPJ + C_U + c8) : make_uint4(0u, 0u, 0u, 0u); }
;     float acc[8] = {0.f, 0.f, 0.f, 0.f, 0.f, 0.f, 0.f, 0.f};
; #pragma unroll
;     for (int i = 0; i < WIN - 1; ++i) { acc[0] += bflo(u[i].x); acc[1] += bfhi(u[i].x); acc[2] += bflo(u[i].y); acc[3] += bfhi(u[i].y); acc[4] += bflo(u[i].z); acc[5] += bfhi(u[i].z); acc[6] += bflo(u[i].w); acc[7] += bfhi(u[i].w); }
; #pragma unroll
;     for (int j = 0; j < 8; ++j) {
;         const uint4 x = u[j + WIN - 1];
;         const float xs[8] = {bflo(x.x), bfhi(x.x), bflo(x.y), bfhi(x.y), bflo(x.z), bfhi(x.z), bflo(x.w), bfhi(x.w)};
; #pragma unroll
;         for (int e_ = 0; e_ < 8; ++e_) acc[e_] += xs[e_];
;         const float ic = 1.f / (float)min(WIN, t0 + j + 1);
	global_load_dwordx4 v[6:9], v[54:55], off
	global_load_dwordx4 v[2:5], v[56:57], off
	v_lshlrev_b32_e32 v54, 16, v33
	v_and_b32_e32 v55, 0xffff0000, v33


; DEV float bflo(unsigned u) { return __uint_as_float(u << 16); }
; DEV float bfhi(unsigned u) { return __uint_as_float(u & 0xffff0000u); }
; template <int WIN>
; DEV void pool_d_prompt8(const bf16_t* __restrict__ proj, bf16_t* __restrict__ dpl, int row0, int c8) {
;     ...
;     for (int i = 0; i < WIN + 7; ++i) { const int tt = t0 - (WIN - 1) + i; u[i] = (tt >= 0) ? *(const uint4*)(proj + (size_t)(row0 - (WIN - 1) + i) * NPJ + C_U + c8) : make_uint4(0u, 0u, 0u, 0u); }
;     float acc[8] = {0.f, 0.f, 0.f, 0.f, 0.f, 0.f, 0.f, 0.f};
; #pragma unroll
;     for (int i = 0; i < WIN - 1; ++i) { acc[0] += bflo(u[i].x); acc[1] += bfhi(u[i].x); acc[2] += bflo(u[i].y); acc[3] += bfhi(u[i].y); acc[4] += bflo(u[i].z); acc[5] += bfhi(u[i].z); acc[6] += bflo(u[i].w); acc[7] += bfhi(u[i].w); }
; #pragma unroll
;     for (int j = 0; j < 8; ++j) {
;         const uint4 x = u[j + WIN - 1];
;         const float xs[8] = {bflo(x.x), bfhi(x.x), bflo(x.y), bfhi(x.y), bflo(x.z), bfhi(x.z), bflo(x.w), bfhi(x.w)};
; #pragma unroll
;         for (int e_ = 0; e_ < 8; ++e_) acc[e_] += xs[e_];
;         const float ic = 1.f / (float)min(WIN, t0 + j + 1);
	v_lshlrev_b32_e32 v88, 16, v22
	v_and_b32_e32 v89, 0xffff0000, v22

; DEV unsigned cvt_pk_bf16(float lo, float hi) { const f32x2_t v = {lo, hi}; const bf16x2_t b = __builtin_convertvector(v, bf16x2_t); return __builtin_bit_cast(unsigned, b); }
; DEV float bflo(unsigned u) { return __uint_as_float(u << 16); }
; DEV float bfhi(unsigned u) { return __uint_as_float(u & 0xffff0000u); }
; template <int WIN>
; DEV void pool_d_prompt8(const bf16_t* __restrict__ proj, bf16_t* __restrict__ dpl, int row0, int c8) {
;     ...
;     for (int i = 0; i < WIN - 1; ++i) { acc[0] += bflo(u[i].x); acc[1] += bfhi(u[i].x); acc[2] += bflo(u[i].y); acc[3] += bfhi(u[i].y); acc[4] += bflo(u[i].z); acc[5] += bfhi(u[i].z); acc[6] += bflo(u[i].w); acc[7] += bfhi(u[i].w); }
; #pragma unroll
;     for (int j = 0; j < 8; ++j) {
;         const uint4 x = u[j + WIN - 1];
;         const float xs[8] = {bflo(x.x), bfhi(x.x), bflo(x.y), bfhi(x.y), bflo(x.z), bfhi(x.z), bflo(x.w), bfhi(x.w)};
; #pragma unroll
;         for (int e_ = 0; e_ < 8; ++e_) acc[e_] += xs[e_];
;         const float ic = 1.f / (float)min(WIN, t0 + j + 1);
;         uint4 o;
;         o.x = cvt_pk_bf16(acc[0] * ic - xs[0], acc[1] * ic - xs[1]); o.y = cvt_pk_bf16(acc[2] * ic - xs[2], acc[3] * ic - xs[3]);
;         o.z = cvt_pk_bf16(acc[4] * ic - xs[4], acc[5] * ic - xs[5]); o.w = cvt_pk_bf16(acc[6] * ic - xs[6], acc[7] * ic - xs[7]);
;         *(uint4*)(dpl + (size_t)(row0 + j) * LDP + c8) = o;
;         const uint4 y = u[j];
;         acc[0] -= bflo(y.x); acc[1] -= bfhi(y.x); acc[2] -= bflo(y.y); acc[3] -= bfhi(y.y); acc[4] -= bflo(y.z); acc[5] -= bfhi(y.z); acc[6] -= bflo(y.w); acc[7] -= bfhi(y.w);
	v_lshlrev_b32_e32 v112, 16, v14
	v_and_b32_e32 v113, 0xffff0000, v14
	v_lshlrev_b32_e32 v114, 16, v15
	v_and_b32_e32 v115, 0xffff0000, v15
	v_lshlrev_b32_e32 v68, 16, v52
	v_and_b32_e32 v69, 0xffff0000, v52
	v_rcp_f32_e32 v25, v24
	s_nop 0
	v_mul_f32_e32 v52, 1.0, v25
	v_pk_add_f32 v[24:25], v[88:89], 0 op_sel_hi:[1,0]
	v_pk_add_f32 v[30:31], v[108:109], 0 op_sel_hi:[1,0]
	v_lshlrev_b32_e32 v98, 16, v34
	v_and_b32_e32 v99, 0xffff0000, v34
	v_lshlrev_b32_e32 v92, 16, v35
	v_and_b32_e32 v93, 0xffff0000, v35
	v_pk_add_f32 v[24:25], v[24:25], v[112:113]
	v_pk_add_f32 v[30:31], v[30:31], v[114:115]
	v_pk_add_f32 v[24:25], v[24:25], v[98:99]
	v_pk_add_f32 v[30:31], v[30:31], v[92:93]
	v_lshlrev_b32_e32 v74, 16, v50
	v_and_b32_e32 v75, 0xffff0000, v50
	v_lshlrev_b32_e32 v72, 16, v51
	v_and_b32_e32 v73, 0xffff0000, v51
	v_pk_add_f32 v[24:25], v[24:25], v[86:87]
	v_pk_add_f32 v[30:31], v[30:31], v[80:81]
	v_lshlrev_b32_e32 v66, 16, v46
	v_and_b32_e32 v67, 0xffff0000, v46
	v_lshlrev_b32_e32 v64, 16, v47
	v_and_b32_e32 v65, 0xffff0000, v47
	v_pk_add_f32 v[24:25], v[24:25], v[74:75]
	v_pk_add_f32 v[30:31], v[30:31], v[72:73]
	v_pk_add_f32 v[24:25], v[24:25], v[66:67]
	v_lshlrev_b32_e32 v70, 16, v42
	v_and_b32_e32 v71, 0xffff0000, v42
	v_pk_add_f32 v[30:31], v[30:31], v[64:65]
	v_lshlrev_b32_e32 v76, 16, v43
	v_and_b32_e32 v77, 0xffff0000, v43
	v_lshlrev_b32_e32 v116, 16, v16
	v_and_b32_e32 v117, 0xffff0000, v16
	v_lshlrev_b32_e32 v58, 16, v17
	v_and_b32_e32 v59, 0xffff0000, v17
	s_waitcnt vmcnt(7)
	v_lshlrev_b32_e32 v14, 16, v100
	v_and_b32_e32 v15, 0xffff0000, v100
	v_lshlrev_b32_e32 v16, 16, v101
	v_and_b32_e32 v17, 0xffff0000, v101
	v_pk_add_f32 v[24:25], v[24:25], v[70:71]
	v_pk_add_f32 v[30:31], v[30:31], v[76:77]
	v_pk_add_f32 v[24:25], v[24:25], v[14:15]
	v_pk_add_f32 v[30:31], v[30:31], v[16:17]
	v_pk_fma_f32 v[14:15], v[52:53], v[24:25], v[14:15] op_sel_hi:[0,1,1] neg_lo:[0,0,1] neg_hi:[0,0,1]
	v_pk_fma_f32 v[16:17], v[52:53], v[30:31], v[16:17] op_sel_hi:[0,1,1] neg_lo:[0,0,1] neg_hi:[0,0,1]
	v_cvt_pk_bf16_f32 v14, v14, v15
	v_cvt_pk_bf16_f32 v15, v16, v17
	v_pk_add_f32 v[16:17], v[110:111], 0 op_sel_hi:[1,0]
	v_lshlrev_b32_e32 v90, 16, v36
	v_and_b32_e32 v91, 0xffff0000, v36
	v_pk_add_f32 v[16:17], v[16:17], v[116:117]
	v_lshlrev_b32_e32 v62, 16, v48
	v_pk_add_f32 v[16:17], v[16:17], v[90:91]
	v_and_b32_e32 v63, 0xffff0000, v48
	v_pk_add_f32 v[16:17], v[16:17], v[78:79]
	v_lshlrev_b32_e32 v84, 16, v44
	v_pk_add_f32 v[16:17], v[16:17], v[68:69]
	v_and_b32_e32 v85, 0xffff0000, v44
	v_pk_add_f32 v[16:17], v[16:17], v[62:63]
	v_lshlrev_b32_e32 v22, 16, v102
	v_and_b32_e32 v23, 0xffff0000, v102
	v_pk_add_f32 v[16:17], v[16:17], v[84:85]
	v_lshlrev_b32_e32 v50, 16, v53
	v_pk_add_f32 v[32:33], v[16:17], v[22:23]
	v_and_b32_e32 v51, 0xffff0000, v53
	v_pk_fma_f32 v[16:17], v[52:53], v[32:33], v[22:23] op_sel_hi:[0,1,1] neg_lo:[0,0,1] neg_hi:[0,0,1]
	v_cvt_pk_bf16_f32 v16, v16, v17
	v_min_u32_e32 v17, 6, v144
	v_add_u32_e32 v17, 2, v17
	v_cvt_f32_ubyte0_e32 v17, v17


; DEV unsigned cvt_pk_bf16(float lo, float hi) { const f32x2_t v = {lo, hi}; const bf16x2_t b = __builtin_convertvector(v, bf16x2_t); return __builtin_bit_cast(unsigned, b); }
; DEV float bflo(unsigned u) { return __uint_as_float(u << 16); }
; DEV float bfhi(unsigned u) { return __uint_as_float(u & 0xffff0000u); }
; template <int WIN>
; DEV void pool_d_prompt8(const bf16_t* __restrict__ proj, bf16_t* __restrict__ dpl, int row0, int c8) {
;     ...
;     for (int j = 0; j < 8; ++j) {
;         const uint4 x = u[j + WIN - 1];
;         const float xs[8] = {bflo(x.x), bfhi(x.x), bflo(x.y), bfhi(x.y), bflo(x.z), bfhi(x.z), bflo(x.w), bfhi(x.w)};
; #pragma unroll
;         for (int e_ = 0; e_ < 8; ++e_) acc[e_] += xs[e_];
;         const float ic = 1.f / (float)min(WIN, t0 + j + 1);
;         uint4 o;
;         o.x = cvt_pk_bf16(acc[0] * ic - xs[0], acc[1] * ic - xs[1]); o.y = cvt_pk_bf16(acc[2] * ic - xs[2], acc[3] * ic - xs[3]);
;         o.z = cvt_pk_bf16(acc[4] * ic - xs[4], acc[5] * ic - xs[5]); o.w = cvt_pk_bf16(acc[6] * ic - xs[6], acc[7] * ic - xs[7]);
;         *(uint4*)(dpl + (size_t)(row0 + j) * LDP + c8) = o;
;         const uint4 y = u[j];
;         acc[0] -= bflo(y.x); acc[1] -= bfhi(y.x); acc[2] -= bflo(y.y); acc[3] -= bfhi(y.y); acc[4] -= bflo(y.z); acc[5] -= bfhi(y.z); acc[6] -= bflo(y.w); acc[7] -= bfhi(y.w);
	v_lshl_add_u64 v[34:35], v[140:141], 0, v[94:95]
	s_waitcnt vmcnt(6)
	v_lshlrev_b32_e32 v22, 16, v104
	v_and_b32_e32 v23, 0xffff0000, v104


; DEV unsigned cvt_pk_bf16(float lo, float hi) { const f32x2_t v = {lo, hi}; const bf16x2_t b = __builtin_convertvector(v, bf16x2_t); return __builtin_bit_cast(unsigned, b); }
; DEV float bflo(unsigned u) { return __uint_as_float(u << 16); }
; DEV float bfhi(unsigned u) { return __uint_as_float(u & 0xffff0000u); }
; template <int WIN>
; DEV void pool_d_prompt8(const bf16_t* __restrict__ proj, bf16_t* __restrict__ dpl, int row0, int c8) {
;     ...
;     for (int j = 0; j < 8; ++j) {
;         const uint4 x = u[j + WIN - 1];
;         const float xs[8] = {bflo(x.x), bfhi(x.x), bflo(x.y), bfhi(x.y), bflo(x.z), bfhi(x.z), bflo(x.w), bfhi(x.w)};
; #pragma unroll
;         for (int e_ = 0; e_ < 8; ++e_) acc[e_] += xs[e_];
;         const float ic = 1.f / (float)min(WIN, t0 + j + 1);
;         uint4 o;
;         o.x = cvt_pk_bf16(acc[0] * ic - xs[0], acc[1] * ic - xs[1]); o.y = cvt_pk_bf16(acc[2] * ic - xs[2], acc[3] * ic - xs[3]);
;         o.z = cvt_pk_bf16(acc[4] * ic - xs[4], acc[5] * ic - xs[5]); o.w = cvt_pk_bf16(acc[6] * ic - xs[6], acc[7] * ic - xs[7]);
;         *(uint4*)(dpl + (size_t)(row0 + j) * LDP + c8) = o;
;         const uint4 y = u[j];
;         acc[0] -= bflo(y.x); acc[1] -= bfhi(y.x); acc[2] -= bflo(y.y); acc[3] -= bfhi(y.y); acc[4] -= bflo(y.z); acc[5] -= bfhi(y.z); acc[6] -= bflo(y.w); acc[7] -= bfhi(y.w);
	v_lshlrev_b32_e32 v100, 16, v105
	v_and_b32_e32 v101, 0xffff0000, v105


; DEV unsigned cvt_pk_bf16(float lo, float hi) { const f32x2_t v = {lo, hi}; const bf16x2_t b = __builtin_convertvector(v, bf16x2_t); return __builtin_bit_cast(unsigned, b); }
; DEV float bflo(unsigned u) { return __uint_as_float(u << 16); }
; DEV float bfhi(unsigned u) { return __uint_as_float(u & 0xffff0000u); }
; template <int WIN>
; DEV void pool_d_prompt8(const bf16_t* __restrict__ proj, bf16_t* __restrict__ dpl, int row0, int c8) {
;     ...
;     for (int j = 0; j < 8; ++j) {
;         const uint4 x = u[j + WIN - 1];
;         const float xs[8] = {bflo(x.x), bfhi(x.x), bflo(x.y), bfhi(x.y), bflo(x.z), bfhi(x.z), bflo(x.w), bfhi(x.w)};
; #pragma unroll
;         for (int e_ = 0; e_ < 8; ++e_) acc[e_] += xs[e_];
;         const float ic = 1.f / (float)min(WIN, t0 + j + 1);
;         uint4 o;
;         o.x = cvt_pk_bf16(acc[0] * ic - xs[0], acc[1] * ic - xs[1]); o.y = cvt_pk_bf16(acc[2] * ic - xs[2], acc[3] * ic - xs[3]);
;         o.z = cvt_pk_bf16(acc[4] * ic - xs[4], acc[5] * ic - xs[5]); o.w = cvt_pk_bf16(acc[6] * ic - xs[6], acc[7] * ic - xs[7]);
;         *(uint4*)(dpl + (size_t)(row0 + j) * LDP + c8) = o;
;         const uint4 y = u[j];
;         acc[0] -= bflo(y.x); acc[1] -= bfhi(y.x); acc[2] -= bflo(y.y); acc[3] -= bfhi(y.y); acc[4] -= bflo(y.z); acc[5] -= bfhi(y.z); acc[6] -= bflo(y.w); acc[7] -= bfhi(y.w);
	v_pk_add_f32 v[24:25], v[24:25], v[88:89] neg_lo:[0,1] neg_hi:[0,1]

; DEV unsigned cvt_pk_bf16(float lo, float hi) { const f32x2_t v = {lo, hi}; const bf16x2_t b = __builtin_convertvector(v, bf16x2_t); return __builtin_bit_cast(unsigned, b); }
; DEV float bflo(unsigned u) { return __uint_as_float(u << 16); }
; DEV float bfhi(unsigned u) { return __uint_as_float(u & 0xffff0000u); }
; template <int WIN>
; DEV void pool_d_prompt8(const bf16_t* __restrict__ proj, bf16_t* __restrict__ dpl, int row0, int c8) {
;     ...
;     for (int j = 0; j < 8; ++j) {
;         const uint4 x = u[j + WIN - 1];
;         const float xs[8] = {bflo(x.x), bfhi(x.x), bflo(x.y), bfhi(x.y), bflo(x.z), bfhi(x.z), bflo(x.w), bfhi(x.w)};
; #pragma unroll
;         for (int e_ = 0; e_ < 8; ++e_) acc[e_] += xs[e_];
;         const float ic = 1.f / (float)min(WIN, t0 + j + 1);
;         uint4 o;
;         o.x = cvt_pk_bf16(acc[0] * ic - xs[0], acc[1] * ic - xs[1]); o.y = cvt_pk_bf16(acc[2] * ic - xs[2], acc[3] * ic - xs[3]);
;         o.z = cvt_pk_bf16(acc[4] * ic - xs[4], acc[5] * ic - xs[5]); o.w = cvt_pk_bf16(acc[6] * ic - xs[6], acc[7] * ic - xs[7]);
;         *(uint4*)(dpl + (size_t)(row0 + j) * LDP + c8) = o;
;         const uint4 y = u[j];
;         acc[0] -= bflo(y.x); acc[1] -= bfhi(y.x); acc[2] -= bflo(y.y); acc[3] -= bfhi(y.y); acc[4] -= bflo(y.z); acc[5] -= bfhi(y.z); acc[6] -= bflo(y.w); acc[7] -= bfhi(y.w);
	v_pk_add_f32 v[104:105], v[24:25], v[22:23]
	v_pk_add_f32 v[24:25], v[30:31], v[108:109] neg_lo:[0,1] neg_hi:[0,1]
	v_lshlrev_b32_e32 v56, 16, v37
	v_and_b32_e32 v57, 0xffff0000, v37
	v_lshlrev_b32_e32 v46, 16, v49
	v_and_b32_e32 v47, 0xffff0000, v49
	v_lshlrev_b32_e32 v36, 16, v45
	v_and_b32_e32 v37, 0xffff0000, v45
	v_lshlrev_b32_e32 v48, 16, v103
	v_and_b32_e32 v49, 0xffff0000, v103
	v_lshlrev_b32_e32 v102, 16, v106
	v_and_b32_e32 v103, 0xffff0000, v106
	v_lshlrev_b32_e32 v44, 16, v107
	v_and_b32_e32 v45, 0xffff0000, v107
	v_rcp_f32_e32 v53, v17
	s_nop 0
	v_mul_f32_e32 v82, 1.0, v53
	v_pk_add_f32 v[106:107], v[24:25], v[100:101]
	v_pk_fma_f32 v[22:23], v[82:83], v[104:105], v[22:23] op_sel_hi:[0,1,1] neg_lo:[0,0,1] neg_hi:[0,0,1]
	v_pk_fma_f32 v[24:25], v[82:83], v[106:107], v[100:101] op_sel_hi:[0,1,1] neg_lo:[0,0,1] neg_hi:[0,0,1]
	v_cvt_pk_bf16_f32 v22, v22, v23
	v_cvt_pk_bf16_f32 v23, v24, v25
	v_pk_add_f32 v[24:25], v[32:33], v[110:111] neg_lo:[0,1] neg_hi:[0,1]
	v_min_u32_e32 v17, 5, v144
	v_pk_add_f32 v[32:33], v[24:25], v[102:103]
	v_add_u32_e32 v17, 3, v17
	v_pk_fma_f32 v[24:25], v[82:83], v[32:33], v[102:103] op_sel_hi:[0,1,1] neg_lo:[0,0,1] neg_hi:[0,0,1]
	v_cvt_f32_ubyte0_e32 v17, v17
	v_cvt_pk_bf16_f32 v24, v24, v25


; DEV float bflo(unsigned u) { return __uint_as_float(u << 16); }
; DEV float bfhi(unsigned u) { return __uint_as_float(u & 0xffff0000u); }
; template <int WIN>
; DEV void pool_d_prompt8(const bf16_t* __restrict__ proj, bf16_t* __restrict__ dpl, int row0, int c8) {
;     ...
;         const float xs[8] = {bflo(x.x), bfhi(x.x), bflo(x.y), bfhi(x.y), bflo(x.z), bfhi(x.z), bflo(x.w), bfhi(x.w)};
; #pragma unroll
;         for (int e_ = 0; e_ < 8; ++e_) acc[e_] += xs[e_];
;         const float ic = 1.f / (float)min(WIN, t0 + j + 1);
	s_waitcnt vmcnt(5)
	v_lshlrev_b32_e32 v102, 16, v40
	v_and_b32_e32 v103, 0xffff0000, v40
	v_lshlrev_b32_e32 v30, 16, v38


; DEV float bflo(unsigned u) { return __uint_as_float(u << 16); }
; DEV float bfhi(unsigned u) { return __uint_as_float(u & 0xffff0000u); }
; template <int WIN>
; DEV void pool_d_prompt8(const bf16_t* __restrict__ proj, bf16_t* __restrict__ dpl, int row0, int c8) {
;     ...
;         const float xs[8] = {bflo(x.x), bfhi(x.x), bflo(x.y), bfhi(x.y), bflo(x.z), bfhi(x.z), bflo(x.w), bfhi(x.w)};
; #pragma unroll
;         for (int e_ = 0; e_ < 8; ++e_) acc[e_] += xs[e_];
;         const float ic = 1.f / (float)min(WIN, t0 + j + 1);
	v_and_b32_e32 v31, 0xffff0000, v38
	v_lshlrev_b32_e32 v100, 16, v39
	v_and_b32_e32 v101, 0xffff0000, v39
	v_lshlrev_b32_e32 v38, 16, v41
	v_and_b32_e32 v39, 0xffff0000, v41


; DEV unsigned cvt_pk_bf16(float lo, float hi) { const f32x2_t v = {lo, hi}; const bf16x2_t b = __builtin_convertvector(v, bf16x2_t); return __builtin_bit_cast(unsigned, b); }
; DEV float bflo(unsigned u) { return __uint_as_float(u << 16); }
; DEV float bfhi(unsigned u) { return __uint_as_float(u & 0xffff0000u); }
; template <int WIN>
; DEV void pool_d_prompt8(const bf16_t* __restrict__ proj, bf16_t* __restrict__ dpl, int row0, int c8) {
;     ...
;     for (int j = 0; j < 8; ++j) {
;         const uint4 x = u[j + WIN - 1];
;         const float xs[8] = {bflo(x.x), bfhi(x.x), bflo(x.y), bfhi(x.y), bflo(x.z), bfhi(x.z), bflo(x.w), bfhi(x.w)};
; #pragma unroll
;         for (int e_ = 0; e_ < 8; ++e_) acc[e_] += xs[e_];
;         const float ic = 1.f / (float)min(WIN, t0 + j + 1);
;         uint4 o;
;         o.x = cvt_pk_bf16(acc[0] * ic - xs[0], acc[1] * ic - xs[1]); o.y = cvt_pk_bf16(acc[2] * ic - xs[2], acc[3] * ic - xs[3]);
;         o.z = cvt_pk_bf16(acc[4] * ic - xs[4], acc[5] * ic - xs[5]); o.w = cvt_pk_bf16(acc[6] * ic - xs[6], acc[7] * ic - xs[7]);
;         *(uint4*)(dpl + (size_t)(row0 + j) * LDP + c8) = o;
;         const uint4 y = u[j];
;         acc[0] -= bflo(y.x); acc[1] -= bfhi(y.x); acc[2] -= bflo(y.y); acc[3] -= bfhi(y.y); acc[4] -= bflo(y.z); acc[5] -= bfhi(y.z); acc[6] -= bflo(y.w); acc[7] -= bfhi(y.w);
	v_rcp_f32_e32 v25, v17
	s_nop 0
	v_mul_f32_e32 v40, 1.0, v25
	v_min_u32_e32 v17, 4, v144
	v_pk_add_f32 v[32:33], v[32:33], v[116:117] neg_lo:[0,1] neg_hi:[0,1]
	v_add_u32_e32 v17, 4, v17
	v_pk_add_f32 v[108:109], v[32:33], v[102:103]
	v_cvt_f32_ubyte0_e32 v17, v17
	v_pk_fma_f32 v[32:33], v[40:41], v[108:109], v[102:103] op_sel_hi:[0,1,1] neg_lo:[0,0,1] neg_hi:[0,0,1]

; DEV unsigned cvt_pk_bf16(float lo, float hi) { const f32x2_t v = {lo, hi}; const bf16x2_t b = __builtin_convertvector(v, bf16x2_t); return __builtin_bit_cast(unsigned, b); }
; template <int WIN>
; DEV void pool_d_prompt8(const bf16_t* __restrict__ proj, bf16_t* __restrict__ dpl, int row0, int c8) {
;     ...
;         const float ic = 1.f / (float)min(WIN, t0 + j + 1);
;         uint4 o;
;         o.x = cvt_pk_bf16(acc[0] * ic - xs[0], acc[1] * ic - xs[1]); o.y = cvt_pk_bf16(acc[2] * ic - xs[2], acc[3] * ic - xs[3]);
;         o.z = cvt_pk_bf16(acc[4] * ic - xs[4], acc[5] * ic - xs[5]); o.w = cvt_pk_bf16(acc[6] * ic - xs[6], acc[7] * ic - xs[7]);
	v_cvt_pk_bf16_f32 v32, v32, v33

; DEV unsigned cvt_pk_bf16(float lo, float hi) { const f32x2_t v = {lo, hi}; const bf16x2_t b = __builtin_convertvector(v, bf16x2_t); return __builtin_bit_cast(unsigned, b); }
; DEV float bflo(unsigned u) { return __uint_as_float(u << 16); }
; DEV float bfhi(unsigned u) { return __uint_as_float(u & 0xffff0000u); }
; template <int WIN>
; DEV void pool_d_prompt8(const bf16_t* __restrict__ proj, bf16_t* __restrict__ dpl, int row0, int c8) {
;     ...
;     for (int j = 0; j < 8; ++j) {
;         const uint4 x = u[j + WIN - 1];
;         const float xs[8] = {bflo(x.x), bfhi(x.x), bflo(x.y), bfhi(x.y), bflo(x.z), bfhi(x.z), bflo(x.w), bfhi(x.w)};
; #pragma unroll
;         for (int e_ = 0; e_ < 8; ++e_) acc[e_] += xs[e_];
;         const float ic = 1.f / (float)min(WIN, t0 + j + 1);
;         uint4 o;
;         o.x = cvt_pk_bf16(acc[0] * ic - xs[0], acc[1] * ic - xs[1]); o.y = cvt_pk_bf16(acc[2] * ic - xs[2], acc[3] * ic - xs[3]);
;         o.z = cvt_pk_bf16(acc[4] * ic - xs[4], acc[5] * ic - xs[5]); o.w = cvt_pk_bf16(acc[6] * ic - xs[6], acc[7] * ic - xs[7]);
	v_pk_add_f32 v[104:105], v[104:105], v[112:113] neg_lo:[0,1] neg_hi:[0,1]
	s_waitcnt vmcnt(4)
	v_lshlrev_b32_e32 v112, 16, v28
	v_and_b32_e32 v113, 0xffff0000, v28

; DEV unsigned cvt_pk_bf16(float lo, float hi) { const f32x2_t v = {lo, hi}; const bf16x2_t b = __builtin_convertvector(v, bf16x2_t); return __builtin_bit_cast(unsigned, b); }
; DEV float bflo(unsigned u) { return __uint_as_float(u << 16); }
; DEV float bfhi(unsigned u) { return __uint_as_float(u & 0xffff0000u); }
; template <int WIN>
; DEV void pool_d_prompt8(const bf16_t* __restrict__ proj, bf16_t* __restrict__ dpl, int row0, int c8) {
;     ...
;     for (int j = 0; j < 8; ++j) {
;         const uint4 x = u[j + WIN - 1];
;         const float xs[8] = {bflo(x.x), bfhi(x.x), bflo(x.y), bfhi(x.y), bflo(x.z), bfhi(x.z), bflo(x.w), bfhi(x.w)};
; #pragma unroll
;         for (int e_ = 0; e_ < 8; ++e_) acc[e_] += xs[e_];
;         const float ic = 1.f / (float)min(WIN, t0 + j + 1);
;         uint4 o;
;         o.x = cvt_pk_bf16(acc[0] * ic - xs[0], acc[1] * ic - xs[1]); o.y = cvt_pk_bf16(acc[2] * ic - xs[2], acc[3] * ic - xs[3]);
;         o.z = cvt_pk_bf16(acc[4] * ic - xs[4], acc[5] * ic - xs[5]); o.w = cvt_pk_bf16(acc[6] * ic - xs[6], acc[7] * ic - xs[7]);
	v_pk_add_f32 v[106:107], v[106:107], v[114:115] neg_lo:[0,1] neg_hi:[0,1]


; DEV unsigned cvt_pk_bf16(float lo, float hi) { const f32x2_t v = {lo, hi}; const bf16x2_t b = __builtin_convertvector(v, bf16x2_t); return __builtin_bit_cast(unsigned, b); }
; DEV float bflo(unsigned u) { return __uint_as_float(u << 16); }
; DEV float bfhi(unsigned u) { return __uint_as_float(u & 0xffff0000u); }
; template <int WIN>
; DEV void pool_d_prompt8(const bf16_t* __restrict__ proj, bf16_t* __restrict__ dpl, int row0, int c8) {
;     ...
;     for (int j = 0; j < 8; ++j) {
;         const uint4 x = u[j + WIN - 1];
;         const float xs[8] = {bflo(x.x), bfhi(x.x), bflo(x.y), bfhi(x.y), bflo(x.z), bfhi(x.z), bflo(x.w), bfhi(x.w)};
; #pragma unroll
;         for (int e_ = 0; e_ < 8; ++e_) acc[e_] += xs[e_];
;         const float ic = 1.f / (float)min(WIN, t0 + j + 1);
;         uint4 o;
;         o.x = cvt_pk_bf16(acc[0] * ic - xs[0], acc[1] * ic - xs[1]); o.y = cvt_pk_bf16(acc[2] * ic - xs[2], acc[3] * ic - xs[3]);
;         o.z = cvt_pk_bf16(acc[4] * ic - xs[4], acc[5] * ic - xs[5]); o.w = cvt_pk_bf16(acc[6] * ic - xs[6], acc[7] * ic - xs[7]);
	v_pk_add_f32 v[104:105], v[104:105], v[30:31]
	v_pk_add_f32 v[106:107], v[106:107], v[100:101]
	v_lshlrev_b32_e32 v102, 16, v29
	v_and_b32_e32 v103, 0xffff0000, v29

; DEV unsigned cvt_pk_bf16(float lo, float hi) { const f32x2_t v = {lo, hi}; const bf16x2_t b = __builtin_convertvector(v, bf16x2_t); return __builtin_bit_cast(unsigned, b); }
; DEV float bflo(unsigned u) { return __uint_as_float(u << 16); }
; DEV float bfhi(unsigned u) { return __uint_as_float(u & 0xffff0000u); }
; template <int WIN>
; DEV void pool_d_prompt8(const bf16_t* __restrict__ proj, bf16_t* __restrict__ dpl, int row0, int c8) {
;     ...
;     for (int j = 0; j < 8; ++j) {
;         const uint4 x = u[j + WIN - 1];
;         const float xs[8] = {bflo(x.x), bfhi(x.x), bflo(x.y), bfhi(x.y), bflo(x.z), bfhi(x.z), bflo(x.w), bfhi(x.w)};
; #pragma unroll
;         for (int e_ = 0; e_ < 8; ++e_) acc[e_] += xs[e_];
;         const float ic = 1.f / (float)min(WIN, t0 + j + 1);
;         uint4 o;
;         o.x = cvt_pk_bf16(acc[0] * ic - xs[0], acc[1] * ic - xs[1]); o.y = cvt_pk_bf16(acc[2] * ic - xs[2], acc[3] * ic - xs[3]);
;         o.z = cvt_pk_bf16(acc[4] * ic - xs[4], acc[5] * ic - xs[5]); o.w = cvt_pk_bf16(acc[6] * ic - xs[6], acc[7] * ic - xs[7]);
	v_pk_fma_f32 v[30:31], v[40:41], v[104:105], v[30:31] op_sel_hi:[0,1,1] neg_lo:[0,0,1] neg_hi:[0,0,1]
	v_pk_fma_f32 v[100:101], v[40:41], v[106:107], v[100:101] op_sel_hi:[0,1,1] neg_lo:[0,0,1] neg_hi:[0,0,1]


; DEV unsigned cvt_pk_bf16(float lo, float hi) { const f32x2_t v = {lo, hi}; const bf16x2_t b = __builtin_convertvector(v, bf16x2_t); return __builtin_bit_cast(unsigned, b); }
; DEV float bflo(unsigned u) { return __uint_as_float(u << 16); }
; DEV float bfhi(unsigned u) { return __uint_as_float(u & 0xffff0000u); }
; template <int WIN>
; DEV void pool_d_prompt8(const bf16_t* __restrict__ proj, bf16_t* __restrict__ dpl, int row0, int c8) {
;     ...
;     for (int j = 0; j < 8; ++j) {
;         const uint4 x = u[j + WIN - 1];
;         const float xs[8] = {bflo(x.x), bfhi(x.x), bflo(x.y), bfhi(x.y), bflo(x.z), bfhi(x.z), bflo(x.w), bfhi(x.w)};
; #pragma unroll
;         for (int e_ = 0; e_ < 8; ++e_) acc[e_] += xs[e_];
;         const float ic = 1.f / (float)min(WIN, t0 + j + 1);
;         uint4 o;
;         o.x = cvt_pk_bf16(acc[0] * ic - xs[0], acc[1] * ic - xs[1]); o.y = cvt_pk_bf16(acc[2] * ic - xs[2], acc[3] * ic - xs[3]);
;         o.z = cvt_pk_bf16(acc[4] * ic - xs[4], acc[5] * ic - xs[5]); o.w = cvt_pk_bf16(acc[6] * ic - xs[6], acc[7] * ic - xs[7]);
	v_lshlrev_b32_e32 v110, 16, v26
	v_and_b32_e32 v111, 0xffff0000, v26
	v_rcp_f32_e32 v25, v17
	s_nop 0
	v_mul_f32_e32 v94, 1.0, v25
	v_pk_add_f32 v[28:29], v[104:105], v[98:99] neg_lo:[0,1] neg_hi:[0,1]
	v_min_u32_e32 v17, 3, v144
	v_lshlrev_b32_e32 v26, 16, v27
	v_and_b32_e32 v27, 0xffff0000, v27
	v_pk_add_f32 v[28:29], v[28:29], v[110:111]
	v_pk_add_f32 v[92:93], v[106:107], v[92:93] neg_lo:[0,1] neg_hi:[0,1]
	v_add_u32_e32 v17, 5, v17
	v_pk_fma_f32 v[98:99], v[94:95], v[28:29], v[110:111] op_sel_hi:[0,1,1] neg_lo:[0,0,1] neg_hi:[0,0,1]
	v_pk_add_f32 v[92:93], v[92:93], v[26:27]
	v_cvt_f32_ubyte0_e32 v17, v17
	v_cvt_pk_bf16_f32 v104, v98, v99
	v_pk_fma_f32 v[26:27], v[94:95], v[92:93], v[26:27] op_sel_hi:[0,1,1] neg_lo:[0,0,1] neg_hi:[0,0,1]
	s_waitcnt vmcnt(3)
	v_lshlrev_b32_e32 v98, 16, v18
	v_and_b32_e32 v99, 0xffff0000, v18

; DEV unsigned cvt_pk_bf16(float lo, float hi) { const f32x2_t v = {lo, hi}; const bf16x2_t b = __builtin_convertvector(v, bf16x2_t); return __builtin_bit_cast(unsigned, b); }
; DEV float bflo(unsigned u) { return __uint_as_float(u << 16); }
; DEV float bfhi(unsigned u) { return __uint_as_float(u & 0xffff0000u); }
; template <int WIN>
; DEV void pool_d_prompt8(const bf16_t* __restrict__ proj, bf16_t* __restrict__ dpl, int row0, int c8) {
;     ...
;     for (int j = 0; j < 8; ++j) {
;         const uint4 x = u[j + WIN - 1];
;         const float xs[8] = {bflo(x.x), bfhi(x.x), bflo(x.y), bfhi(x.y), bflo(x.z), bfhi(x.z), bflo(x.w), bfhi(x.w)};
; #pragma unroll
;         for (int e_ = 0; e_ < 8; ++e_) acc[e_] += xs[e_];
;         const float ic = 1.f / (float)min(WIN, t0 + j + 1);
;         uint4 o;
;         o.x = cvt_pk_bf16(acc[0] * ic - xs[0], acc[1] * ic - xs[1]); o.y = cvt_pk_bf16(acc[2] * ic - xs[2], acc[3] * ic - xs[3]);
;         o.z = cvt_pk_bf16(acc[4] * ic - xs[4], acc[5] * ic - xs[5]); o.w = cvt_pk_bf16(acc[6] * ic - xs[6], acc[7] * ic - xs[7]);
	v_cvt_pk_bf16_f32 v105, v26, v27
	v_pk_add_f32 v[26:27], v[108:109], v[90:91] neg_lo:[0,1] neg_hi:[0,1]
	v_lshlrev_b32_e32 v108, 16, v19
	v_and_b32_e32 v109, 0xffff0000, v19

; DEV unsigned cvt_pk_bf16(float lo, float hi) { const f32x2_t v = {lo, hi}; const bf16x2_t b = __builtin_convertvector(v, bf16x2_t); return __builtin_bit_cast(unsigned, b); }
; DEV float bflo(unsigned u) { return __uint_as_float(u << 16); }
; DEV float bfhi(unsigned u) { return __uint_as_float(u & 0xffff0000u); }
; template <int WIN>
; DEV void pool_d_prompt8(const bf16_t* __restrict__ proj, bf16_t* __restrict__ dpl, int row0, int c8) {
;     ...
;     for (int j = 0; j < 8; ++j) {
;         const uint4 x = u[j + WIN - 1];
;         const float xs[8] = {bflo(x.x), bfhi(x.x), bflo(x.y), bfhi(x.y), bflo(x.z), bfhi(x.z), bflo(x.w), bfhi(x.w)};
; #pragma unroll
;         for (int e_ = 0; e_ < 8; ++e_) acc[e_] += xs[e_];
;         const float ic = 1.f / (float)min(WIN, t0 + j + 1);
;         uint4 o;
;         o.x = cvt_pk_bf16(acc[0] * ic - xs[0], acc[1] * ic - xs[1]); o.y = cvt_pk_bf16(acc[2] * ic - xs[2], acc[3] * ic - xs[3]);
;         o.z = cvt_pk_bf16(acc[4] * ic - xs[4], acc[5] * ic - xs[5]); o.w = cvt_pk_bf16(acc[6] * ic - xs[6], acc[7] * ic - xs[7]);
	v_lshlrev_b32_e32 v110, 16, v20
	v_and_b32_e32 v111, 0xffff0000, v20
	v_pk_add_f32 v[26:27], v[26:27], v[112:113]


; DEV unsigned cvt_pk_bf16(float lo, float hi) { const f32x2_t v = {lo, hi}; const bf16x2_t b = __builtin_convertvector(v, bf16x2_t); return __builtin_bit_cast(unsigned, b); }
; DEV float bflo(unsigned u) { return __uint_as_float(u << 16); }
; DEV float bfhi(unsigned u) { return __uint_as_float(u & 0xffff0000u); }
; template <int WIN>
; DEV void pool_d_prompt8(const bf16_t* __restrict__ proj, bf16_t* __restrict__ dpl, int row0, int c8) {
;     ...
;     for (int j = 0; j < 8; ++j) {
;         const uint4 x = u[j + WIN - 1];
;         const float xs[8] = {bflo(x.x), bfhi(x.x), bflo(x.y), bfhi(x.y), bflo(x.z), bfhi(x.z), bflo(x.w), bfhi(x.w)};
; #pragma unroll
;         for (int e_ = 0; e_ < 8; ++e_) acc[e_] += xs[e_];
;         const float ic = 1.f / (float)min(WIN, t0 + j + 1);
;         uint4 o;
;         o.x = cvt_pk_bf16(acc[0] * ic - xs[0], acc[1] * ic - xs[1]); o.y = cvt_pk_bf16(acc[2] * ic - xs[2], acc[3] * ic - xs[3]);
;         o.z = cvt_pk_bf16(acc[4] * ic - xs[4], acc[5] * ic - xs[5]); o.w = cvt_pk_bf16(acc[6] * ic - xs[6], acc[7] * ic - xs[7]);
	v_pk_fma_f32 v[90:91], v[94:95], v[26:27], v[112:113] op_sel_hi:[0,1,1] neg_lo:[0,0,1] neg_hi:[0,0,1]
	v_lshlrev_b32_e32 v112, 16, v21
	v_and_b32_e32 v113, 0xffff0000, v21


; DEV unsigned cvt_pk_bf16(float lo, float hi) { const f32x2_t v = {lo, hi}; const bf16x2_t b = __builtin_convertvector(v, bf16x2_t); return __builtin_bit_cast(unsigned, b); }
; DEV float bflo(unsigned u) { return __uint_as_float(u << 16); }
; DEV float bfhi(unsigned u) { return __uint_as_float(u & 0xffff0000u); }
; template <int WIN>
; DEV void pool_d_prompt8(const bf16_t* __restrict__ proj, bf16_t* __restrict__ dpl, int row0, int c8) {
;     ...
;     for (int j = 0; j < 8; ++j) {
;         const uint4 x = u[j + WIN - 1];
;         const float xs[8] = {bflo(x.x), bfhi(x.x), bflo(x.y), bfhi(x.y), bflo(x.z), bfhi(x.z), bflo(x.w), bfhi(x.w)};
; #pragma unroll
;         for (int e_ = 0; e_ < 8; ++e_) acc[e_] += xs[e_];
;         const float ic = 1.f / (float)min(WIN, t0 + j + 1);
;         uint4 o;
;         o.x = cvt_pk_bf16(acc[0] * ic - xs[0], acc[1] * ic - xs[1]); o.y = cvt_pk_bf16(acc[2] * ic - xs[2], acc[3] * ic - xs[3]);
;         o.z = cvt_pk_bf16(acc[4] * ic - xs[4], acc[5] * ic - xs[5]); o.w = cvt_pk_bf16(acc[6] * ic - xs[6], acc[7] * ic - xs[7]);
	v_rcp_f32_e32 v18, v17
	s_nop 0
	v_mul_f32_e32 v114, 1.0, v18
	v_pk_add_f32 v[18:19], v[28:29], v[86:87] neg_lo:[0,1] neg_hi:[0,1]
	s_waitcnt vmcnt(2)
	v_lshlrev_b32_e32 v86, 16, v10
	v_and_b32_e32 v87, 0xffff0000, v10
	v_min_u32_e32 v10, 2, v144
	v_add_u32_e32 v10, 6, v10
	v_cvt_f32_ubyte0_e32 v10, v10
	v_pk_add_f32 v[20:21], v[92:93], v[80:81] neg_lo:[0,1] neg_hi:[0,1]
	v_lshlrev_b32_e32 v92, 16, v11
	v_and_b32_e32 v93, 0xffff0000, v11


; DEV unsigned cvt_pk_bf16(float lo, float hi) { const f32x2_t v = {lo, hi}; const bf16x2_t b = __builtin_convertvector(v, bf16x2_t); return __builtin_bit_cast(unsigned, b); }
; DEV float bflo(unsigned u) { return __uint_as_float(u << 16); }
; DEV float bfhi(unsigned u) { return __uint_as_float(u & 0xffff0000u); }
; template <int WIN>
; DEV void pool_d_prompt8(const bf16_t* __restrict__ proj, bf16_t* __restrict__ dpl, int row0, int c8) {
;     ...
;     for (int j = 0; j < 8; ++j) {
;         const uint4 x = u[j + WIN - 1];
;         const float xs[8] = {bflo(x.x), bfhi(x.x), bflo(x.y), bfhi(x.y), bflo(x.z), bfhi(x.z), bflo(x.w), bfhi(x.w)};
; #pragma unroll
;         for (int e_ = 0; e_ < 8; ++e_) acc[e_] += xs[e_];
;         const float ic = 1.f / (float)min(WIN, t0 + j + 1);
;         uint4 o;
;         o.x = cvt_pk_bf16(acc[0] * ic - xs[0], acc[1] * ic - xs[1]); o.y = cvt_pk_bf16(acc[2] * ic - xs[2], acc[3] * ic - xs[3]);
;         o.z = cvt_pk_bf16(acc[4] * ic - xs[4], acc[5] * ic - xs[5]); o.w = cvt_pk_bf16(acc[6] * ic - xs[6], acc[7] * ic - xs[7]);
	v_pk_add_f32 v[28:29], v[18:19], v[98:99]
	v_pk_add_f32 v[80:81], v[20:21], v[108:109]
	v_pk_fma_f32 v[18:19], v[114:115], v[28:29], v[98:99] op_sel_hi:[0,1,1] neg_lo:[0,0,1] neg_hi:[0,0,1]
	v_pk_fma_f32 v[20:21], v[114:115], v[80:81], v[108:109] op_sel_hi:[0,1,1] neg_lo:[0,0,1] neg_hi:[0,0,1]
	v_cvt_pk_bf16_f32 v18, v18, v19
	v_cvt_pk_bf16_f32 v19, v20, v21
	v_pk_add_f32 v[20:21], v[26:27], v[78:79] neg_lo:[0,1] neg_hi:[0,1]
	v_lshlrev_b32_e32 v98, 16, v12
	v_and_b32_e32 v99, 0xffff0000, v12

; DEV unsigned cvt_pk_bf16(float lo, float hi) { const f32x2_t v = {lo, hi}; const bf16x2_t b = __builtin_convertvector(v, bf16x2_t); return __builtin_bit_cast(unsigned, b); }
; DEV float bflo(unsigned u) { return __uint_as_float(u << 16); }
; DEV float bfhi(unsigned u) { return __uint_as_float(u & 0xffff0000u); }
; template <int WIN>
; DEV void pool_d_prompt8(const bf16_t* __restrict__ proj, bf16_t* __restrict__ dpl, int row0, int c8) {
;     ...
;     for (int j = 0; j < 8; ++j) {
;         const uint4 x = u[j + WIN - 1];
;         const float xs[8] = {bflo(x.x), bfhi(x.x), bflo(x.y), bfhi(x.y), bflo(x.z), bfhi(x.z), bflo(x.w), bfhi(x.w)};
; #pragma unroll
;         for (int e_ = 0; e_ < 8; ++e_) acc[e_] += xs[e_];
;         const float ic = 1.f / (float)min(WIN, t0 + j + 1);
;         uint4 o;
;         o.x = cvt_pk_bf16(acc[0] * ic - xs[0], acc[1] * ic - xs[1]); o.y = cvt_pk_bf16(acc[2] * ic - xs[2], acc[3] * ic - xs[3]);
;         o.z = cvt_pk_bf16(acc[4] * ic - xs[4], acc[5] * ic - xs[5]); o.w = cvt_pk_bf16(acc[6] * ic - xs[6], acc[7] * ic - xs[7]);
	v_pk_add_f32 v[26:27], v[20:21], v[110:111]


; DEV unsigned cvt_pk_bf16(float lo, float hi) { const f32x2_t v = {lo, hi}; const bf16x2_t b = __builtin_convertvector(v, bf16x2_t); return __builtin_bit_cast(unsigned, b); }
; DEV float bflo(unsigned u) { return __uint_as_float(u << 16); }
; DEV float bfhi(unsigned u) { return __uint_as_float(u & 0xffff0000u); }
; template <int WIN>
; DEV void pool_d_prompt8(const bf16_t* __restrict__ proj, bf16_t* __restrict__ dpl, int row0, int c8) {
;     ...
;     for (int j = 0; j < 8; ++j) {
;         const uint4 x = u[j + WIN - 1];
;         const float xs[8] = {bflo(x.x), bfhi(x.x), bflo(x.y), bfhi(x.y), bflo(x.z), bfhi(x.z), bflo(x.w), bfhi(x.w)};
; #pragma unroll
;         for (int e_ = 0; e_ < 8; ++e_) acc[e_] += xs[e_];
;         const float ic = 1.f / (float)min(WIN, t0 + j + 1);
;         uint4 o;
;         o.x = cvt_pk_bf16(acc[0] * ic - xs[0], acc[1] * ic - xs[1]); o.y = cvt_pk_bf16(acc[2] * ic - xs[2], acc[3] * ic - xs[3]);
;         o.z = cvt_pk_bf16(acc[4] * ic - xs[4], acc[5] * ic - xs[5]); o.w = cvt_pk_bf16(acc[6] * ic - xs[6], acc[7] * ic - xs[7]);
	v_pk_fma_f32 v[20:21], v[114:115], v[26:27], v[110:111] op_sel_hi:[0,1,1] neg_lo:[0,0,1] neg_hi:[0,0,1]
	v_lshlrev_b32_e32 v108, 16, v13
	v_and_b32_e32 v109, 0xffff0000, v13

; DEV unsigned cvt_pk_bf16(float lo, float hi) { const f32x2_t v = {lo, hi}; const bf16x2_t b = __builtin_convertvector(v, bf16x2_t); return __builtin_bit_cast(unsigned, b); }
; DEV float bflo(unsigned u) { return __uint_as_float(u << 16); }
; DEV float bfhi(unsigned u) { return __uint_as_float(u & 0xffff0000u); }
; template <int WIN>
; DEV void pool_d_prompt8(const bf16_t* __restrict__ proj, bf16_t* __restrict__ dpl, int row0, int c8) {
;     ...
;     for (int j = 0; j < 8; ++j) {
;         const uint4 x = u[j + WIN - 1];
;         const float xs[8] = {bflo(x.x), bfhi(x.x), bflo(x.y), bfhi(x.y), bflo(x.z), bfhi(x.z), bflo(x.w), bfhi(x.w)};
; #pragma unroll
;         for (int e_ = 0; e_ < 8; ++e_) acc[e_] += xs[e_];
;         const float ic = 1.f / (float)min(WIN, t0 + j + 1);
;         uint4 o;
;         o.x = cvt_pk_bf16(acc[0] * ic - xs[0], acc[1] * ic - xs[1]); o.y = cvt_pk_bf16(acc[2] * ic - xs[2], acc[3] * ic - xs[3]);
;         o.z = cvt_pk_bf16(acc[4] * ic - xs[4], acc[5] * ic - xs[5]); o.w = cvt_pk_bf16(acc[6] * ic - xs[6], acc[7] * ic - xs[7]);
	v_cvt_pk_bf16_f32 v20, v20, v21


; DEV unsigned cvt_pk_bf16(float lo, float hi) { const f32x2_t v = {lo, hi}; const bf16x2_t b = __builtin_convertvector(v, bf16x2_t); return __builtin_bit_cast(unsigned, b); }
; DEV float bflo(unsigned u) { return __uint_as_float(u << 16); }
; DEV float bfhi(unsigned u) { return __uint_as_float(u & 0xffff0000u); }
; template <int WIN>
; DEV void pool_d_prompt8(const bf16_t* __restrict__ proj, bf16_t* __restrict__ dpl, int row0, int c8) {
;     ...
;     for (int j = 0; j < 8; ++j) {
;         const uint4 x = u[j + WIN - 1];
;         const float xs[8] = {bflo(x.x), bfhi(x.x), bflo(x.y), bfhi(x.y), bflo(x.z), bfhi(x.z), bflo(x.w), bfhi(x.w)};
; #pragma unroll
;         for (int e_ = 0; e_ < 8; ++e_) acc[e_] += xs[e_];
;         const float ic = 1.f / (float)min(WIN, t0 + j + 1);
;         uint4 o;
;         o.x = cvt_pk_bf16(acc[0] * ic - xs[0], acc[1] * ic - xs[1]); o.y = cvt_pk_bf16(acc[2] * ic - xs[2], acc[3] * ic - xs[3]);
;         o.z = cvt_pk_bf16(acc[4] * ic - xs[4], acc[5] * ic - xs[5]); o.w = cvt_pk_bf16(acc[6] * ic - xs[6], acc[7] * ic - xs[7]);
	v_rcp_f32_e32 v11, v10
	s_nop 0
	v_mul_f32_e32 v110, 1.0, v11
	v_pk_add_f32 v[10:11], v[28:29], v[74:75] neg_lo:[0,1] neg_hi:[0,1]
	s_waitcnt vmcnt(1)
	v_lshlrev_b32_e32 v74, 16, v6
	v_and_b32_e32 v75, 0xffff0000, v6

; DEV unsigned cvt_pk_bf16(float lo, float hi) { const f32x2_t v = {lo, hi}; const bf16x2_t b = __builtin_convertvector(v, bf16x2_t); return __builtin_bit_cast(unsigned, b); }
; DEV float bflo(unsigned u) { return __uint_as_float(u << 16); }
; DEV float bfhi(unsigned u) { return __uint_as_float(u & 0xffff0000u); }
; template <int WIN>
; DEV void pool_d_prompt8(const bf16_t* __restrict__ proj, bf16_t* __restrict__ dpl, int row0, int c8) {
;     ...
;     for (int j = 0; j < 8; ++j) {
;         const uint4 x = u[j + WIN - 1];
;         const float xs[8] = {bflo(x.x), bfhi(x.x), bflo(x.y), bfhi(x.y), bflo(x.z), bfhi(x.z), bflo(x.w), bfhi(x.w)};
; #pragma unroll
;         for (int e_ = 0; e_ < 8; ++e_) acc[e_] += xs[e_];
;         const float ic = 1.f / (float)min(WIN, t0 + j + 1);
;         uint4 o;
;         o.x = cvt_pk_bf16(acc[0] * ic - xs[0], acc[1] * ic - xs[1]); o.y = cvt_pk_bf16(acc[2] * ic - xs[2], acc[3] * ic - xs[3]);
;         o.z = cvt_pk_bf16(acc[4] * ic - xs[4], acc[5] * ic - xs[5]); o.w = cvt_pk_bf16(acc[6] * ic - xs[6], acc[7] * ic - xs[7]);
	v_pk_add_f32 v[12:13], v[80:81], v[72:73] neg_lo:[0,1] neg_hi:[0,1]
	v_lshlrev_b32_e32 v80, 16, v7
	v_and_b32_e32 v81, 0xffff0000, v7

; DEV unsigned cvt_pk_bf16(float lo, float hi) { const f32x2_t v = {lo, hi}; const bf16x2_t b = __builtin_convertvector(v, bf16x2_t); return __builtin_bit_cast(unsigned, b); }
; DEV float bflo(unsigned u) { return __uint_as_float(u << 16); }
; DEV float bfhi(unsigned u) { return __uint_as_float(u & 0xffff0000u); }
; template <int WIN>
; DEV void pool_d_prompt8(const bf16_t* __restrict__ proj, bf16_t* __restrict__ dpl, int row0, int c8) {
;     ...
;     for (int j = 0; j < 8; ++j) {
;         const uint4 x = u[j + WIN - 1];
;         const float xs[8] = {bflo(x.x), bfhi(x.x), bflo(x.y), bfhi(x.y), bflo(x.z), bfhi(x.z), bflo(x.w), bfhi(x.w)};
; #pragma unroll
;         for (int e_ = 0; e_ < 8; ++e_) acc[e_] += xs[e_];
;         const float ic = 1.f / (float)min(WIN, t0 + j + 1);
;         uint4 o;
;         o.x = cvt_pk_bf16(acc[0] * ic - xs[0], acc[1] * ic - xs[1]); o.y = cvt_pk_bf16(acc[2] * ic - xs[2], acc[3] * ic - xs[3]);
;         o.z = cvt_pk_bf16(acc[4] * ic - xs[4], acc[5] * ic - xs[5]); o.w = cvt_pk_bf16(acc[6] * ic - xs[6], acc[7] * ic - xs[7]);
	v_pk_add_f32 v[28:29], v[10:11], v[86:87]
	v_pk_add_f32 v[72:73], v[12:13], v[92:93]
	v_pk_fma_f32 v[10:11], v[110:111], v[28:29], v[86:87] op_sel_hi:[0,1,1] neg_lo:[0,0,1] neg_hi:[0,0,1]
	v_pk_fma_f32 v[12:13], v[110:111], v[72:73], v[92:93] op_sel_hi:[0,1,1] neg_lo:[0,0,1] neg_hi:[0,0,1]
	v_cvt_pk_bf16_f32 v10, v10, v11
	v_cvt_pk_bf16_f32 v11, v12, v13
	v_pk_add_f32 v[12:13], v[26:27], v[68:69] neg_lo:[0,1] neg_hi:[0,1]
	v_lshlrev_b32_e32 v86, 16, v8
	v_and_b32_e32 v87, 0xffff0000, v8

; DEV unsigned cvt_pk_bf16(float lo, float hi) { const f32x2_t v = {lo, hi}; const bf16x2_t b = __builtin_convertvector(v, bf16x2_t); return __builtin_bit_cast(unsigned, b); }
; DEV float bflo(unsigned u) { return __uint_as_float(u << 16); }
; DEV float bfhi(unsigned u) { return __uint_as_float(u & 0xffff0000u); }
; template <int WIN>
; DEV void pool_d_prompt8(const bf16_t* __restrict__ proj, bf16_t* __restrict__ dpl, int row0, int c8) {
;     ...
;     for (int j = 0; j < 8; ++j) {
;         const uint4 x = u[j + WIN - 1];
;         const float xs[8] = {bflo(x.x), bfhi(x.x), bflo(x.y), bfhi(x.y), bflo(x.z), bfhi(x.z), bflo(x.w), bfhi(x.w)};
; #pragma unroll
;         for (int e_ = 0; e_ < 8; ++e_) acc[e_] += xs[e_];
;         const float ic = 1.f / (float)min(WIN, t0 + j + 1);
;         uint4 o;
;         o.x = cvt_pk_bf16(acc[0] * ic - xs[0], acc[1] * ic - xs[1]); o.y = cvt_pk_bf16(acc[2] * ic - xs[2], acc[3] * ic - xs[3]);
;         o.z = cvt_pk_bf16(acc[4] * ic - xs[4], acc[5] * ic - xs[5]); o.w = cvt_pk_bf16(acc[6] * ic - xs[6], acc[7] * ic - xs[7]);
	v_pk_add_f32 v[26:27], v[12:13], v[98:99]


; DEV unsigned cvt_pk_bf16(float lo, float hi) { const f32x2_t v = {lo, hi}; const bf16x2_t b = __builtin_convertvector(v, bf16x2_t); return __builtin_bit_cast(unsigned, b); }
; DEV float bflo(unsigned u) { return __uint_as_float(u << 16); }
; DEV float bfhi(unsigned u) { return __uint_as_float(u & 0xffff0000u); }
; template <int WIN>
; DEV void pool_d_prompt8(const bf16_t* __restrict__ proj, bf16_t* __restrict__ dpl, int row0, int c8) {
;     ...
;     for (int j = 0; j < 8; ++j) {
;         const uint4 x = u[j + WIN - 1];
;         const float xs[8] = {bflo(x.x), bfhi(x.x), bflo(x.y), bfhi(x.y), bflo(x.z), bfhi(x.z), bflo(x.w), bfhi(x.w)};
; #pragma unroll
;         for (int e_ = 0; e_ < 8; ++e_) acc[e_] += xs[e_];
;         const float ic = 1.f / (float)min(WIN, t0 + j + 1);
;         uint4 o;
;         o.x = cvt_pk_bf16(acc[0] * ic - xs[0], acc[1] * ic - xs[1]); o.y = cvt_pk_bf16(acc[2] * ic - xs[2], acc[3] * ic - xs[3]);
;         o.z = cvt_pk_bf16(acc[4] * ic - xs[4], acc[5] * ic - xs[5]); o.w = cvt_pk_bf16(acc[6] * ic - xs[6], acc[7] * ic - xs[7]);
	v_pk_fma_f32 v[12:13], v[110:111], v[26:27], v[98:99] op_sel_hi:[0,1,1] neg_lo:[0,0,1] neg_hi:[0,0,1]
	v_lshlrev_b32_e32 v92, 16, v9
	v_and_b32_e32 v93, 0xffff0000, v9

; DEV unsigned cvt_pk_bf16(float lo, float hi) { const f32x2_t v = {lo, hi}; const bf16x2_t b = __builtin_convertvector(v, bf16x2_t); return __builtin_bit_cast(unsigned, b); }
; DEV float bflo(unsigned u) { return __uint_as_float(u << 16); }
; DEV float bfhi(unsigned u) { return __uint_as_float(u & 0xffff0000u); }
; template <int WIN>
; DEV void pool_d_prompt8(const bf16_t* __restrict__ proj, bf16_t* __restrict__ dpl, int row0, int c8) {
;     ...
;     for (int j = 0; j < 8; ++j) {
;         const uint4 x = u[j + WIN - 1];
;         const float xs[8] = {bflo(x.x), bfhi(x.x), bflo(x.y), bfhi(x.y), bflo(x.z), bfhi(x.z), bflo(x.w), bfhi(x.w)};
; #pragma unroll
;         for (int e_ = 0; e_ < 8; ++e_) acc[e_] += xs[e_];
;         const float ic = 1.f / (float)min(WIN, t0 + j + 1);
;         uint4 o;
;         o.x = cvt_pk_bf16(acc[0] * ic - xs[0], acc[1] * ic - xs[1]); o.y = cvt_pk_bf16(acc[2] * ic - xs[2], acc[3] * ic - xs[3]);
;         o.z = cvt_pk_bf16(acc[4] * ic - xs[4], acc[5] * ic - xs[5]); o.w = cvt_pk_bf16(acc[6] * ic - xs[6], acc[7] * ic - xs[7]);
	v_cvt_pk_bf16_f32 v12, v12, v13


; DEV unsigned cvt_pk_bf16(float lo, float hi) { const f32x2_t v = {lo, hi}; const bf16x2_t b = __builtin_convertvector(v, bf16x2_t); return __builtin_bit_cast(unsigned, b); }
; DEV float bflo(unsigned u) { return __uint_as_float(u << 16); }
; DEV float bfhi(unsigned u) { return __uint_as_float(u & 0xffff0000u); }
; template <int WIN>
; DEV void pool_d_prompt8(const bf16_t* __restrict__ proj, bf16_t* __restrict__ dpl, int row0, int c8) {
;     ...
;     for (int i = 0; i < WIN + 7; ++i) { const int tt = t0 - (WIN - 1) + i; u[i] = (tt >= 0) ? *(const uint4*)(proj + (size_t)(row0 - (WIN - 1) + i) * NPJ + C_U + c8) : make_uint4(0u, 0u, 0u, 0u); }
;     float acc[8] = {0.f, 0.f, 0.f, 0.f, 0.f, 0.f, 0.f, 0.f};
; #pragma unroll
;     for (int i = 0; i < WIN - 1; ++i) { acc[0] += bflo(u[i].x); acc[1] += bfhi(u[i].x); acc[2] += bflo(u[i].y); acc[3] += bfhi(u[i].y); acc[4] += bflo(u[i].z); acc[5] += bfhi(u[i].z); acc[6] += bflo(u[i].w); acc[7] += bfhi(u[i].w); }
; #pragma unroll
;     for (int j = 0; j < 8; ++j) {
;         const uint4 x = u[j + WIN - 1];
;         const float xs[8] = {bflo(x.x), bfhi(x.x), bflo(x.y), bfhi(x.y), bflo(x.z), bfhi(x.z), bflo(x.w), bfhi(x.w)};
; #pragma unroll
;         for (int e_ = 0; e_ < 8; ++e_) acc[e_] += xs[e_];
;         const float ic = 1.f / (float)min(WIN, t0 + j + 1);
;         uint4 o;
;         o.x = cvt_pk_bf16(acc[0] * ic - xs[0], acc[1] * ic - xs[1]); o.y = cvt_pk_bf16(acc[2] * ic - xs[2], acc[3] * ic - xs[3]);
;         o.z = cvt_pk_bf16(acc[4] * ic - xs[4], acc[5] * ic - xs[5]); o.w = cvt_pk_bf16(acc[6] * ic - xs[6], acc[7] * ic - xs[7]);
;         *(uint4*)(dpl + (size_t)(row0 + j) * LDP + c8) = o;
;         const uint4 y = u[j];
;         acc[0] -= bflo(y.x); acc[1] -= bfhi(y.x); acc[2] -= bflo(y.y); acc[3] -= bfhi(y.y); acc[4] -= bflo(y.z); acc[5] -= bfhi(y.z); acc[6] -= bflo(y.w); acc[7] -= bfhi(y.w);
	v_rcp_f32_e32 v6, v83
	s_nop 0
	v_mul_f32_e32 v98, 1.0, v6
	v_pk_add_f32 v[6:7], v[28:29], v[66:67] neg_lo:[0,1] neg_hi:[0,1]
	v_pk_add_f32 v[8:9], v[72:73], v[64:65] neg_lo:[0,1] neg_hi:[0,1]
	v_pk_add_f32 v[28:29], v[6:7], v[74:75]
	v_pk_add_f32 v[64:65], v[8:9], v[80:81]
	v_pk_fma_f32 v[6:7], v[98:99], v[28:29], v[74:75] op_sel_hi:[0,1,1] neg_lo:[0,0,1] neg_hi:[0,0,1]
	v_pk_fma_f32 v[8:9], v[98:99], v[64:65], v[80:81] op_sel_hi:[0,1,1] neg_lo:[0,0,1] neg_hi:[0,0,1]
	v_cvt_pk_bf16_f32 v6, v6, v7
	v_cvt_pk_bf16_f32 v7, v8, v9
	v_pk_add_f32 v[8:9], v[26:27], v[62:63] neg_lo:[0,1] neg_hi:[0,1]
	s_waitcnt vmcnt(0)
	v_lshlrev_b32_e32 v26, 16, v2
	v_and_b32_e32 v27, 0xffff0000, v2
	v_pk_add_f32 v[28:29], v[28:29], v[70:71] neg_lo:[0,1] neg_hi:[0,1]
	v_lshlrev_b32_e32 v2, 16, v3
	v_pk_add_f32 v[28:29], v[28:29], v[26:27]
	v_and_b32_e32 v3, 0xffff0000, v3
	v_pk_fma_f32 v[26:27], v[28:29], s[10:11], v[26:27] op_sel_hi:[1,0,1] neg_lo:[0,0,1] neg_hi:[0,0,1]
	v_pk_add_f32 v[28:29], v[64:65], v[76:77] neg_lo:[0,1] neg_hi:[0,1]
	v_pk_add_f32 v[62:63], v[8:9], v[86:87]
	v_pk_add_f32 v[28:29], v[28:29], v[2:3]
	v_mad_i64_i32 v[42:43], s[4:5], v145, s27, v[34:35]
	v_mad_i64_i32 v[88:89], s[4:5], v118, s27, v[34:35]
	v_cvt_pk_bf16_f32 v30, v30, v31
	v_cvt_pk_bf16_f32 v31, v100, v101
	v_mad_i64_i32 v[100:101], s[4:5], v119, s27, v[34:35]
	v_cvt_pk_bf16_f32 v106, v90, v91
	v_mad_i64_i32 v[90:91], s[4:5], v120, s27, v[34:35]
	v_mad_i64_i32 v[78:79], s[4:5], v121, s27, v[34:35]
	v_mad_i64_i32 v[68:69], s[4:5], v122, s27, v[34:35]
	v_mad_i64_i32 v[66:67], s[4:5], v123, s27, v[34:35]
	v_lshlrev_b32_e32 v34, 16, v4
	v_and_b32_e32 v35, 0xffff0000, v4
	v_pk_fma_f32 v[28:29], v[28:29], s[10:11], v[2:3] op_sel_hi:[1,0,1] neg_lo:[0,0,1] neg_hi:[0,0,1]
	v_pk_add_f32 v[2:3], v[62:63], v[84:85] neg_lo:[0,1] neg_hi:[0,1]
	v_lshlrev_b32_e32 v4, 16, v5
	v_pk_add_f32 v[2:3], v[2:3], v[34:35]
	v_and_b32_e32 v5, 0xffff0000, v5
	v_pk_fma_f32 v[34:35], v[2:3], s[10:11], v[34:35] op_sel_hi:[1,0,1] neg_lo:[0,0,1] neg_hi:[0,0,1]
	v_pk_add_f32 v[2:3], v[60:61], 0 op_sel_hi:[1,0]
	v_pk_fma_f32 v[8:9], v[98:99], v[62:63], v[86:87] op_sel_hi:[0,1,1] neg_lo:[0,0,1] neg_hi:[0,0,1]
	v_pk_add_f32 v[2:3], v[2:3], v[58:59]
	v_ashrrev_i32_e32 v97, 31, v96
	v_pk_add_f32 v[2:3], v[2:3], v[56:57]
	v_cvt_pk_bf16_f32 v8, v8, v9
	v_pk_add_f32 v[2:3], v[2:3], v[54:55]
	s_nop 0
	v_pk_add_f32 v[2:3], v[2:3], v[50:51]
	s_nop 0
	v_pk_add_f32 v[2:3], v[2:3], v[46:47]
	s_nop 0
	v_pk_add_f32 v[2:3], v[2:3], v[36:37]
	s_nop 0
	v_pk_add_f32 v[2:3], v[2:3], v[48:49]
	s_nop 0
	v_pk_fma_f32 v[48:49], v[52:53], v[2:3], v[48:49] op_sel_hi:[0,1,1] neg_lo:[0,0,1] neg_hi:[0,0,1]
	v_pk_add_f32 v[2:3], v[2:3], v[60:61] neg_lo:[0,1] neg_hi:[0,1]
	v_cvt_pk_bf16_f32 v17, v48, v49
	v_pk_add_f32 v[2:3], v[2:3], v[44:45]
	global_store_dwordx4 v[42:43], v[14:17], off
	s_nop 1
	v_pk_fma_f32 v[14:15], v[82:83], v[2:3], v[44:45] op_sel_hi:[0,1,1] neg_lo:[0,0,1] neg_hi:[0,0,1]
	v_pk_add_f32 v[2:3], v[2:3], v[58:59] neg_lo:[0,1] neg_hi:[0,1]
	v_cvt_pk_bf16_f32 v25, v14, v15
	v_pk_add_f32 v[2:3], v[2:3], v[38:39]
	global_store_dwordx4 v[88:89], v[22:25], off
	v_pk_fma_f32 v[14:15], v[40:41], v[2:3], v[38:39] op_sel_hi:[0,1,1] neg_lo:[0,0,1] neg_hi:[0,0,1]
	v_pk_add_f32 v[2:3], v[2:3], v[56:57] neg_lo:[0,1] neg_hi:[0,1]
	v_cvt_pk_bf16_f32 v33, v14, v15
	v_pk_add_f32 v[2:3], v[2:3], v[102:103]
	global_store_dwordx4 v[100:101], v[30:33], off
	v_pk_fma_f32 v[14:15], v[94:95], v[2:3], v[102:103] op_sel_hi:[0,1,1] neg_lo:[0,0,1] neg_hi:[0,0,1]
	v_pk_add_f32 v[2:3], v[2:3], v[54:55] neg_lo:[0,1] neg_hi:[0,1]
	v_cvt_pk_bf16_f32 v107, v14, v15
	v_pk_add_f32 v[2:3], v[2:3], v[112:113]
	global_store_dwordx4 v[90:91], v[104:107], off
	v_pk_fma_f32 v[14:15], v[114:115], v[2:3], v[112:113] op_sel_hi:[0,1,1] neg_lo:[0,0,1] neg_hi:[0,0,1]
	v_pk_add_f32 v[2:3], v[2:3], v[50:51] neg_lo:[0,1] neg_hi:[0,1]
	v_cvt_pk_bf16_f32 v21, v14, v15
	v_pk_add_f32 v[2:3], v[2:3], v[108:109]
	global_store_dwordx4 v[78:79], v[18:21], off
	v_pk_fma_f32 v[14:15], v[110:111], v[2:3], v[108:109] op_sel_hi:[0,1,1] neg_lo:[0,0,1] neg_hi:[0,0,1]
	v_pk_add_f32 v[2:3], v[2:3], v[46:47] neg_lo:[0,1] neg_hi:[0,1]
	v_cvt_pk_bf16_f32 v13, v14, v15
	v_pk_add_f32 v[2:3], v[2:3], v[92:93]
	global_store_dwordx4 v[68:69], v[10:13], off
	s_nop 1
	v_pk_fma_f32 v[10:11], v[98:99], v[2:3], v[92:93] op_sel_hi:[0,1,1] neg_lo:[0,0,1] neg_hi:[0,0,1]
	v_pk_add_f32 v[2:3], v[2:3], v[36:37] neg_lo:[0,1] neg_hi:[0,1]
	v_cvt_pk_bf16_f32 v9, v10, v11
	v_pk_add_f32 v[2:3], v[2:3], v[4:5]
	global_store_dwordx4 v[66:67], v[6:9], off
	v_pk_fma_f32 v[2:3], v[2:3], s[10:11], v[4:5] op_sel_hi:[1,0,1] neg_lo:[0,0,1] neg_hi:[0,0,1]

; DEV float bflo(unsigned u) { return __uint_as_float(u << 16); }
; DEV float bfhi(unsigned u) { return __uint_as_float(u & 0xffff0000u); }
; template <int WIN>
; DEV void pool_d_prompt8(const bf16_t* __restrict__ proj, bf16_t* __restrict__ dpl, int row0, int c8) {
;     const int t0 = row0 & 2047;
;     uint4 u[WIN + 7];
; #pragma unroll
;     for (int i = 0; i < WIN + 7; ++i) { const int tt = t0 - (WIN - 1) + i; u[i] = (tt >= 0) ? *(const uint4*)(proj + (size_t)(row0 - (WIN - 1) + i) * NPJ + C_U + c8) : make_uint4(0u, 0u, 0u, 0u); }
;     float acc[8] = {0.f, 0.f, 0.f, 0.f, 0.f, 0.f, 0.f, 0.f};
; #pragma unroll
;     for (int i = 0; i < WIN - 1; ++i) { acc[0] += bflo(u[i].x); acc[1] += bfhi(u[i].x); acc[2] += bflo(u[i].y); acc[3] += bfhi(u[i].y); acc[4] += bflo(u[i].z); acc[5] += bfhi(u[i].z); acc[6] += bflo(u[i].w); acc[7] += bfhi(u[i].w); }
; #pragma unroll
;     for (int j = 0; j < 8; ++j) {
;         const uint4 x = u[j + WIN - 1];
;         const float xs[8] = {bflo(x.x), bfhi(x.x), bflo(x.y), bfhi(x.y), bflo(x.z), bfhi(x.z), bflo(x.w), bfhi(x.w)};
; #pragma unroll
;         for (int e_ = 0; e_ < 8; ++e_) acc[e_] += xs[e_];
;         const float ic = 1.f / (float)min(WIN, t0 + j + 1);
.LBB0_741:
	s_or_b64 exec, exec, s[20:21]
	v_mad_i64_i32 v[6:7], s[4:5], v145, s25, v[172:173]
	v_lshlrev_b32_e32 v94, 1, v143
	v_lshl_add_u64 v[6:7], v[6:7], 0, v[94:95]
	v_or_b32_e32 v85, 1, v145
	v_add_co_u32_e32 v6, vcc, 0x2000, v6
	v_mad_i64_i32 v[8:9], s[4:5], v85, s25, v[172:173]
	s_nop 0
	v_addc_co_u32_e32 v7, vcc, 0, v7, vcc
	v_lshl_add_u64 v[8:9], v[8:9], 0, v[94:95]
	v_add_co_u32_e32 v8, vcc, 0x2000, v8
	v_or_b32_e32 v91, 2, v145
	s_nop 0
	v_addc_co_u32_e32 v9, vcc, 0, v9, vcc
	global_load_dwordx4 v[34:37], v[6:7], off
	global_load_dwordx4 v[38:41], v[8:9], off
	v_mad_i64_i32 v[6:7], s[4:5], v91, s25, v[172:173]
	v_lshl_add_u64 v[6:7], v[6:7], 0, v[94:95]
	v_or_b32_e32 v100, 3, v145
	v_add_co_u32_e32 v6, vcc, 0x2000, v6
	v_mad_i64_i32 v[8:9], s[4:5], v100, s25, v[172:173]
	s_nop 0
	v_addc_co_u32_e32 v7, vcc, 0, v7, vcc
	v_lshl_add_u64 v[8:9], v[8:9], 0, v[94:95]
	v_add_co_u32_e32 v8, vcc, 0x2000, v8
	v_or_b32_e32 v104, 4, v145
	s_nop 0
	v_addc_co_u32_e32 v9, vcc, 0, v9, vcc
	global_load_dwordx4 v[42:45], v[6:7], off
	global_load_dwordx4 v[46:49], v[8:9], off
	v_mad_i64_i32 v[6:7], s[4:5], v104, s25, v[172:173]
	v_lshl_add_u64 v[6:7], v[6:7], 0, v[94:95]
	v_or_b32_e32 v105, 5, v145
	v_add_co_u32_e32 v6, vcc, 0x2000, v6
	v_mad_i64_i32 v[8:9], s[4:5], v105, s25, v[172:173]
	s_nop 0
	v_addc_co_u32_e32 v7, vcc, 0, v7, vcc
	v_lshl_add_u64 v[8:9], v[8:9], 0, v[94:95]
	v_add_co_u32_e32 v8, vcc, 0x2000, v8
	v_or_b32_e32 v106, 6, v145
	s_nop 0
	v_addc_co_u32_e32 v9, vcc, 0, v9, vcc
	global_load_dwordx4 v[18:21], v[6:7], off
	global_load_dwordx4 v[14:17], v[8:9], off
	v_mad_i64_i32 v[6:7], s[4:5], v106, s25, v[172:173]
	v_lshl_add_u64 v[6:7], v[6:7], 0, v[94:95]
	v_add_co_u32_e32 v30, vcc, 0x2000, v6
	v_or_b32_e32 v96, 7, v98
	s_nop 0
	v_addc_co_u32_e32 v31, vcc, 0, v7, vcc
	v_mad_i64_i32 v[6:7], s[4:5], v96, s25, v[172:173]
	v_lshl_add_u64 v[6:7], v[6:7], 0, v[94:95]
	v_add_co_u32_e32 v50, vcc, s26, v6
	s_waitcnt vmcnt(6)
	v_lshlrev_b32_e32 v54, 16, v28
	v_addc_co_u32_e32 v51, vcc, 0, v7, vcc
	global_load_dwordx4 v[10:13], v[30:31], off
	global_load_dwordx4 v[6:9], v[50:51], off
	v_and_b32_e32 v55, 0xffff0000, v28
	v_lshlrev_b32_e32 v30, 16, v29
	v_and_b32_e32 v31, 0xffff0000, v29
	v_lshlrev_b32_e32 v28, 16, v22
	v_and_b32_e32 v29, 0xffff0000, v22
	v_min_u32_e32 v22, 3, v144
	v_add_u32_e32 v22, 1, v22
	v_cvt_f32_ubyte0_e32 v32, v22


; DEV unsigned cvt_pk_bf16(float lo, float hi) { const f32x2_t v = {lo, hi}; const bf16x2_t b = __builtin_convertvector(v, bf16x2_t); return __builtin_bit_cast(unsigned, b); }
; DEV float bflo(unsigned u) { return __uint_as_float(u << 16); }
; DEV float bfhi(unsigned u) { return __uint_as_float(u & 0xffff0000u); }
; template <int WIN>
; DEV void pool_d_prompt8(const bf16_t* __restrict__ proj, bf16_t* __restrict__ dpl, int row0, int c8) {
;     ...
;     for (int j = 0; j < 8; ++j) {
;         const uint4 x = u[j + WIN - 1];
;         const float xs[8] = {bflo(x.x), bfhi(x.x), bflo(x.y), bfhi(x.y), bflo(x.z), bfhi(x.z), bflo(x.w), bfhi(x.w)};
; #pragma unroll
;         for (int e_ = 0; e_ < 8; ++e_) acc[e_] += xs[e_];
;         const float ic = 1.f / (float)min(WIN, t0 + j + 1);
;         uint4 o;
;         o.x = cvt_pk_bf16(acc[0] * ic - xs[0], acc[1] * ic - xs[1]); o.y = cvt_pk_bf16(acc[2] * ic - xs[2], acc[3] * ic - xs[3]);
;         o.z = cvt_pk_bf16(acc[4] * ic - xs[4], acc[5] * ic - xs[5]); o.w = cvt_pk_bf16(acc[6] * ic - xs[6], acc[7] * ic - xs[7]);
	v_lshlrev_b32_e32 v56, 16, v23
	v_and_b32_e32 v57, 0xffff0000, v23
	v_lshlrev_b32_e32 v50, 16, v26
	v_and_b32_e32 v51, 0xffff0000, v26
	v_lshlrev_b32_e32 v52, 16, v27
	v_and_b32_e32 v53, 0xffff0000, v27
	v_lshlrev_b32_e32 v68, 16, v3
	v_and_b32_e32 v69, 0xffff0000, v3
	v_lshlrev_b32_e32 v58, 16, v24
	v_and_b32_e32 v59, 0xffff0000, v24
	v_lshlrev_b32_e32 v72, 16, v4
	v_and_b32_e32 v73, 0xffff0000, v4
	v_lshl_add_u64 v[26:27], v[140:141], 0, v[94:95]
	v_mad_i64_i32 v[76:77], s[4:5], v145, s27, v[26:27]
	v_lshlrev_b32_e32 v24, 16, v25
	s_waitcnt vmcnt(7)
	v_lshlrev_b32_e32 v62, 16, v36
	v_and_b32_e32 v63, 0xffff0000, v36


; DEV unsigned cvt_pk_bf16(float lo, float hi) { const f32x2_t v = {lo, hi}; const bf16x2_t b = __builtin_convertvector(v, bf16x2_t); return __builtin_bit_cast(unsigned, b); }
; DEV float bflo(unsigned u) { return __uint_as_float(u << 16); }
; DEV float bfhi(unsigned u) { return __uint_as_float(u & 0xffff0000u); }
; template <int WIN>
; DEV void pool_d_prompt8(const bf16_t* __restrict__ proj, bf16_t* __restrict__ dpl, int row0, int c8) {
;     ...
;     for (int j = 0; j < 8; ++j) {
;         const uint4 x = u[j + WIN - 1];
;         const float xs[8] = {bflo(x.x), bfhi(x.x), bflo(x.y), bfhi(x.y), bflo(x.z), bfhi(x.z), bflo(x.w), bfhi(x.w)};
; #pragma unroll
;         for (int e_ = 0; e_ < 8; ++e_) acc[e_] += xs[e_];
;         const float ic = 1.f / (float)min(WIN, t0 + j + 1);
;         uint4 o;
;         o.x = cvt_pk_bf16(acc[0] * ic - xs[0], acc[1] * ic - xs[1]); o.y = cvt_pk_bf16(acc[2] * ic - xs[2], acc[3] * ic - xs[3]);
;         o.z = cvt_pk_bf16(acc[4] * ic - xs[4], acc[5] * ic - xs[5]); o.w = cvt_pk_bf16(acc[6] * ic - xs[6], acc[7] * ic - xs[7]);
	v_lshlrev_b32_e32 v22, 16, v37
	v_and_b32_e32 v23, 0xffff0000, v37


; DEV unsigned cvt_pk_bf16(float lo, float hi) { const f32x2_t v = {lo, hi}; const bf16x2_t b = __builtin_convertvector(v, bf16x2_t); return __builtin_bit_cast(unsigned, b); }
; DEV float bflo(unsigned u) { return __uint_as_float(u << 16); }
; DEV float bfhi(unsigned u) { return __uint_as_float(u & 0xffff0000u); }
; template <int WIN>
; DEV void pool_d_prompt8(const bf16_t* __restrict__ proj, bf16_t* __restrict__ dpl, int row0, int c8) {
;     ...
;     for (int i = 0; i < WIN - 1; ++i) { acc[0] += bflo(u[i].x); acc[1] += bfhi(u[i].x); acc[2] += bflo(u[i].y); acc[3] += bfhi(u[i].y); acc[4] += bflo(u[i].z); acc[5] += bfhi(u[i].z); acc[6] += bflo(u[i].w); acc[7] += bfhi(u[i].w); }
; #pragma unroll
;     for (int j = 0; j < 8; ++j) {
;         const uint4 x = u[j + WIN - 1];
;         const float xs[8] = {bflo(x.x), bfhi(x.x), bflo(x.y), bfhi(x.y), bflo(x.z), bfhi(x.z), bflo(x.w), bfhi(x.w)};
; #pragma unroll
;         for (int e_ = 0; e_ < 8; ++e_) acc[e_] += xs[e_];
;         const float ic = 1.f / (float)min(WIN, t0 + j + 1);
;         uint4 o;
;         o.x = cvt_pk_bf16(acc[0] * ic - xs[0], acc[1] * ic - xs[1]); o.y = cvt_pk_bf16(acc[2] * ic - xs[2], acc[3] * ic - xs[3]);
;         o.z = cvt_pk_bf16(acc[4] * ic - xs[4], acc[5] * ic - xs[5]); o.w = cvt_pk_bf16(acc[6] * ic - xs[6], acc[7] * ic - xs[7]);
	v_rcp_f32_e32 v36, v32
	s_nop 0
	v_mul_f32_e32 v32, 1.0, v36
	v_pk_add_f32 v[36:37], v[50:51], 0 op_sel_hi:[1,0]
	v_lshlrev_b32_e32 v64, 16, v2
	v_pk_add_f32 v[36:37], v[36:37], v[28:29]
	v_and_b32_e32 v65, 0xffff0000, v2
	v_lshlrev_b32_e32 v60, 16, v34
	v_and_b32_e32 v61, 0xffff0000, v34
	v_pk_add_f32 v[36:37], v[36:37], v[64:65]
	v_lshlrev_b32_e32 v34, 16, v35
	v_pk_add_f32 v[66:67], v[36:37], v[60:61]
	v_and_b32_e32 v35, 0xffff0000, v35
	v_pk_fma_f32 v[36:37], v[32:33], v[66:67], v[60:61] op_sel_hi:[0,1,1] neg_lo:[0,0,1] neg_hi:[0,0,1]
	v_cvt_pk_bf16_f32 v2, v36, v37
	v_pk_add_f32 v[36:37], v[52:53], 0 op_sel_hi:[1,0]
	s_waitcnt vmcnt(6)
	v_lshlrev_b32_e32 v78, 16, v38
	v_pk_add_f32 v[36:37], v[36:37], v[56:57]
	v_and_b32_e32 v79, 0xffff0000, v38
	v_pk_add_f32 v[36:37], v[36:37], v[68:69]
	v_lshlrev_b32_e32 v80, 16, v39
	v_pk_add_f32 v[70:71], v[36:37], v[34:35]
	v_and_b32_e32 v81, 0xffff0000, v39
	v_pk_fma_f32 v[36:37], v[32:33], v[70:71], v[34:35] op_sel_hi:[0,1,1] neg_lo:[0,0,1] neg_hi:[0,0,1]
	v_cvt_pk_bf16_f32 v3, v36, v37
	v_pk_add_f32 v[36:37], v[54:55], 0 op_sel_hi:[1,0]
	v_lshlrev_b32_e32 v82, 16, v40
	v_pk_add_f32 v[36:37], v[36:37], v[58:59]
	v_and_b32_e32 v83, 0xffff0000, v40
	v_pk_add_f32 v[36:37], v[36:37], v[72:73]
	s_waitcnt vmcnt(5)
	v_and_b32_e32 v87, 0xffff0000, v44
	v_pk_add_f32 v[74:75], v[36:37], v[62:63]
	v_lshlrev_b32_e32 v88, 16, v45
	v_pk_fma_f32 v[36:37], v[32:33], v[74:75], v[62:63] op_sel_hi:[0,1,1] neg_lo:[0,0,1] neg_hi:[0,0,1]
	v_cvt_pk_bf16_f32 v4, v36, v37
	v_min_u32_e32 v36, 2, v144
	v_add_u32_e32 v36, 2, v36
	v_cvt_f32_ubyte0_e32 v38, v36


; DEV unsigned cvt_pk_bf16(float lo, float hi) { const f32x2_t v = {lo, hi}; const bf16x2_t b = __builtin_convertvector(v, bf16x2_t); return __builtin_bit_cast(unsigned, b); }
; DEV float bflo(unsigned u) { return __uint_as_float(u << 16); }
; DEV float bfhi(unsigned u) { return __uint_as_float(u & 0xffff0000u); }
; template <int WIN>
; DEV void pool_d_prompt8(const bf16_t* __restrict__ proj, bf16_t* __restrict__ dpl, int row0, int c8) {
;     ...
;     for (int j = 0; j < 8; ++j) {
;         const uint4 x = u[j + WIN - 1];
;         const float xs[8] = {bflo(x.x), bfhi(x.x), bflo(x.y), bfhi(x.y), bflo(x.z), bfhi(x.z), bflo(x.w), bfhi(x.w)};
; #pragma unroll
;         for (int e_ = 0; e_ < 8; ++e_) acc[e_] += xs[e_];
;         const float ic = 1.f / (float)min(WIN, t0 + j + 1);
;         uint4 o;
;         o.x = cvt_pk_bf16(acc[0] * ic - xs[0], acc[1] * ic - xs[1]); o.y = cvt_pk_bf16(acc[2] * ic - xs[2], acc[3] * ic - xs[3]);
;         o.z = cvt_pk_bf16(acc[4] * ic - xs[4], acc[5] * ic - xs[5]); o.w = cvt_pk_bf16(acc[6] * ic - xs[6], acc[7] * ic - xs[7]);
	v_lshlrev_b32_e32 v36, 16, v41
	v_and_b32_e32 v37, 0xffff0000, v41
	v_and_b32_e32 v89, 0xffff0000, v45


; DEV unsigned cvt_pk_bf16(float lo, float hi) { const f32x2_t v = {lo, hi}; const bf16x2_t b = __builtin_convertvector(v, bf16x2_t); return __builtin_bit_cast(unsigned, b); }
; DEV float bflo(unsigned u) { return __uint_as_float(u << 16); }
; DEV float bfhi(unsigned u) { return __uint_as_float(u & 0xffff0000u); }
; template <int WIN>
; DEV void pool_d_prompt8(const bf16_t* __restrict__ proj, bf16_t* __restrict__ dpl, int row0, int c8) {
;     ...
;     for (int j = 0; j < 8; ++j) {
;         const uint4 x = u[j + WIN - 1];
;         const float xs[8] = {bflo(x.x), bfhi(x.x), bflo(x.y), bfhi(x.y), bflo(x.z), bfhi(x.z), bflo(x.w), bfhi(x.w)};
; #pragma unroll
;         for (int e_ = 0; e_ < 8; ++e_) acc[e_] += xs[e_];
;         const float ic = 1.f / (float)min(WIN, t0 + j + 1);
;         uint4 o;
;         o.x = cvt_pk_bf16(acc[0] * ic - xs[0], acc[1] * ic - xs[1]); o.y = cvt_pk_bf16(acc[2] * ic - xs[2], acc[3] * ic - xs[3]);
;         o.z = cvt_pk_bf16(acc[4] * ic - xs[4], acc[5] * ic - xs[5]); o.w = cvt_pk_bf16(acc[6] * ic - xs[6], acc[7] * ic - xs[7]);
	v_rcp_f32_e32 v39, v38
	s_nop 0
	v_mul_f32_e32 v84, 1.0, v39
	v_pk_add_f32 v[38:39], v[66:67], v[50:51] neg_lo:[0,1] neg_hi:[0,1]
	v_pk_add_f32 v[40:41], v[70:71], v[52:53] neg_lo:[0,1] neg_hi:[0,1]
	v_pk_add_f32 v[50:51], v[38:39], v[78:79]
	v_pk_add_f32 v[52:53], v[40:41], v[80:81]
	v_pk_fma_f32 v[38:39], v[84:85], v[50:51], v[78:79] op_sel_hi:[0,1,1] neg_lo:[0,0,1] neg_hi:[0,0,1]
	v_pk_fma_f32 v[40:41], v[84:85], v[52:53], v[80:81] op_sel_hi:[0,1,1] neg_lo:[0,0,1] neg_hi:[0,0,1]
	v_cvt_pk_bf16_f32 v38, v38, v39
	v_cvt_pk_bf16_f32 v39, v40, v41
	v_pk_add_f32 v[40:41], v[74:75], v[54:55] neg_lo:[0,1] neg_hi:[0,1]
	v_lshlrev_b32_e32 v70, 16, v42
	v_pk_add_f32 v[54:55], v[40:41], v[82:83]
	v_and_b32_e32 v71, 0xffff0000, v42
	v_pk_fma_f32 v[40:41], v[84:85], v[54:55], v[82:83] op_sel_hi:[0,1,1] neg_lo:[0,0,1] neg_hi:[0,0,1]
	v_cvt_pk_bf16_f32 v40, v40, v41


; DEV unsigned cvt_pk_bf16(float lo, float hi) { const f32x2_t v = {lo, hi}; const bf16x2_t b = __builtin_convertvector(v, bf16x2_t); return __builtin_bit_cast(unsigned, b); }
; DEV float bflo(unsigned u) { return __uint_as_float(u << 16); }
; DEV float bfhi(unsigned u) { return __uint_as_float(u & 0xffff0000u); }
; template <int WIN>
; DEV void pool_d_prompt8(const bf16_t* __restrict__ proj, bf16_t* __restrict__ dpl, int row0, int c8) {
;     ...
;     for (int j = 0; j < 8; ++j) {
;         const uint4 x = u[j + WIN - 1];
;         const float xs[8] = {bflo(x.x), bfhi(x.x), bflo(x.y), bfhi(x.y), bflo(x.z), bfhi(x.z), bflo(x.w), bfhi(x.w)};
; #pragma unroll
;         for (int e_ = 0; e_ < 8; ++e_) acc[e_] += xs[e_];
;         const float ic = 1.f / (float)min(WIN, t0 + j + 1);
;         uint4 o;
;         o.x = cvt_pk_bf16(acc[0] * ic - xs[0], acc[1] * ic - xs[1]); o.y = cvt_pk_bf16(acc[2] * ic - xs[2], acc[3] * ic - xs[3]);
;         o.z = cvt_pk_bf16(acc[4] * ic - xs[4], acc[5] * ic - xs[5]); o.w = cvt_pk_bf16(acc[6] * ic - xs[6], acc[7] * ic - xs[7]);
	v_lshlrev_b32_e32 v74, 16, v43
	v_and_b32_e32 v75, 0xffff0000, v43
	v_lshlrev_b32_e32 v86, 16, v44


; DEV unsigned cvt_pk_bf16(float lo, float hi) { const f32x2_t v = {lo, hi}; const bf16x2_t b = __builtin_convertvector(v, bf16x2_t); return __builtin_bit_cast(unsigned, b); }
; DEV float bflo(unsigned u) { return __uint_as_float(u << 16); }
; DEV float bfhi(unsigned u) { return __uint_as_float(u & 0xffff0000u); }
; template <int WIN>
; DEV void pool_d_prompt8(const bf16_t* __restrict__ proj, bf16_t* __restrict__ dpl, int row0, int c8) {
;     ...
;     for (int j = 0; j < 8; ++j) {
;         const uint4 x = u[j + WIN - 1];
;         const float xs[8] = {bflo(x.x), bfhi(x.x), bflo(x.y), bfhi(x.y), bflo(x.z), bfhi(x.z), bflo(x.w), bfhi(x.w)};
; #pragma unroll
;         for (int e_ = 0; e_ < 8; ++e_) acc[e_] += xs[e_];
;         const float ic = 1.f / (float)min(WIN, t0 + j + 1);
;         uint4 o;
;         o.x = cvt_pk_bf16(acc[0] * ic - xs[0], acc[1] * ic - xs[1]); o.y = cvt_pk_bf16(acc[2] * ic - xs[2], acc[3] * ic - xs[3]);
;         o.z = cvt_pk_bf16(acc[4] * ic - xs[4], acc[5] * ic - xs[5]); o.w = cvt_pk_bf16(acc[6] * ic - xs[6], acc[7] * ic - xs[7]);
;         *(uint4*)(dpl + (size_t)(row0 + j) * LDP + c8) = o;
;         const uint4 y = u[j];
;         acc[0] -= bflo(y.x); acc[1] -= bfhi(y.x); acc[2] -= bflo(y.y); acc[3] -= bfhi(y.y); acc[4] -= bflo(y.z); acc[5] -= bfhi(y.z); acc[6] -= bflo(y.w); acc[7] -= bfhi(y.w);
	v_pk_add_f32 v[28:29], v[50:51], v[28:29] neg_lo:[0,1] neg_hi:[0,1]
	v_pk_add_f32 v[44:45], v[52:53], v[56:57] neg_lo:[0,1] neg_hi:[0,1]
	v_rcp_f32_e32 v41, v33
	s_nop 0
	v_mul_f32_e32 v90, 1.0, v41
	v_pk_add_f32 v[28:29], v[28:29], v[70:71]
	v_pk_add_f32 v[50:51], v[44:45], v[74:75]
	v_pk_fma_f32 v[42:43], v[90:91], v[28:29], v[70:71] op_sel_hi:[0,1,1] neg_lo:[0,0,1] neg_hi:[0,0,1]
	v_pk_fma_f32 v[44:45], v[90:91], v[50:51], v[74:75] op_sel_hi:[0,1,1] neg_lo:[0,0,1] neg_hi:[0,0,1]
	v_cvt_pk_bf16_f32 v42, v42, v43
	v_cvt_pk_bf16_f32 v43, v44, v45
	v_pk_add_f32 v[44:45], v[54:55], v[58:59] neg_lo:[0,1] neg_hi:[0,1]
	s_waitcnt vmcnt(4)
	v_lshlrev_b32_e32 v56, 16, v46
	v_and_b32_e32 v57, 0xffff0000, v46
	v_lshlrev_b32_e32 v58, 16, v47
	v_and_b32_e32 v59, 0xffff0000, v47
	v_lshlrev_b32_e32 v92, 16, v48
	v_and_b32_e32 v93, 0xffff0000, v48
	v_lshlrev_b32_e32 v98, 16, v49
	v_and_b32_e32 v99, 0xffff0000, v49
	v_pk_add_f32 v[28:29], v[28:29], v[64:65] neg_lo:[0,1] neg_hi:[0,1]
	v_pk_add_f32 v[48:49], v[50:51], v[68:69] neg_lo:[0,1] neg_hi:[0,1]
	v_pk_add_f32 v[28:29], v[28:29], v[56:57]
	v_pk_add_f32 v[50:51], v[48:49], v[58:59]
	v_pk_add_f32 v[52:53], v[44:45], v[86:87]
	v_pk_fma_f32 v[46:47], v[28:29], s[12:13], v[56:57] op_sel_hi:[1,0,1] neg_lo:[0,0,1] neg_hi:[0,0,1]
	v_pk_fma_f32 v[48:49], v[50:51], s[12:13], v[58:59] op_sel_hi:[1,0,1] neg_lo:[0,0,1] neg_hi:[0,0,1]
	v_cvt_pk_bf16_f32 v46, v46, v47
	v_cvt_pk_bf16_f32 v47, v48, v49
	v_pk_add_f32 v[48:49], v[52:53], v[72:73] neg_lo:[0,1] neg_hi:[0,1]
	v_mad_i64_i32 v[64:65], s[4:5], v100, s27, v[26:27]
	s_waitcnt vmcnt(3)
	v_lshlrev_b32_e32 v68, 16, v18
	v_and_b32_e32 v69, 0xffff0000, v18
	v_lshlrev_b32_e32 v72, 16, v19
	v_and_b32_e32 v73, 0xffff0000, v19
	v_lshlrev_b32_e32 v100, 16, v20
	v_and_b32_e32 v101, 0xffff0000, v20
	v_lshlrev_b32_e32 v102, 16, v21
	v_and_b32_e32 v103, 0xffff0000, v21
	v_pk_add_f32 v[18:19], v[28:29], v[60:61] neg_lo:[0,1] neg_hi:[0,1]
	v_pk_add_f32 v[20:21], v[50:51], v[34:35] neg_lo:[0,1] neg_hi:[0,1]
	v_pk_add_f32 v[28:29], v[18:19], v[68:69]
	v_pk_add_f32 v[34:35], v[20:21], v[72:73]
	v_pk_fma_f32 v[44:45], v[90:91], v[52:53], v[86:87] op_sel_hi:[0,1,1] neg_lo:[0,0,1] neg_hi:[0,0,1]
	v_pk_add_f32 v[52:53], v[48:49], v[92:93]
	v_pk_fma_f32 v[18:19], v[28:29], s[12:13], v[68:69] op_sel_hi:[1,0,1] neg_lo:[0,0,1] neg_hi:[0,0,1]
	v_pk_fma_f32 v[20:21], v[34:35], s[12:13], v[72:73] op_sel_hi:[1,0,1] neg_lo:[0,0,1] neg_hi:[0,0,1]
	v_cvt_pk_bf16_f32 v18, v18, v19
	v_cvt_pk_bf16_f32 v19, v20, v21
	v_pk_add_f32 v[20:21], v[52:53], v[62:63] neg_lo:[0,1] neg_hi:[0,1]
	s_waitcnt vmcnt(2)
	v_lshlrev_b32_e32 v60, 16, v14
	v_and_b32_e32 v61, 0xffff0000, v14
	v_lshlrev_b32_e32 v62, 16, v15
	v_and_b32_e32 v63, 0xffff0000, v15
	v_lshlrev_b32_e32 v68, 16, v16
	v_and_b32_e32 v69, 0xffff0000, v16
	v_lshlrev_b32_e32 v72, 16, v17
	v_and_b32_e32 v73, 0xffff0000, v17
	v_pk_add_f32 v[14:15], v[28:29], v[78:79] neg_lo:[0,1] neg_hi:[0,1]
	v_pk_add_f32 v[16:17], v[34:35], v[80:81] neg_lo:[0,1] neg_hi:[0,1]
	v_pk_add_f32 v[28:29], v[14:15], v[60:61]
	v_pk_add_f32 v[34:35], v[16:17], v[62:63]
	v_pk_add_f32 v[50:51], v[20:21], v[100:101]
	v_pk_fma_f32 v[14:15], v[28:29], s[12:13], v[60:61] op_sel_hi:[1,0,1] neg_lo:[0,0,1] neg_hi:[0,0,1]
	v_pk_fma_f32 v[16:17], v[34:35], s[12:13], v[62:63] op_sel_hi:[1,0,1] neg_lo:[0,0,1] neg_hi:[0,0,1]
	v_cvt_pk_bf16_f32 v14, v14, v15
	v_cvt_pk_bf16_f32 v15, v16, v17
	v_pk_add_f32 v[16:17], v[50:51], v[82:83] neg_lo:[0,1] neg_hi:[0,1]
	v_pk_fma_f32 v[20:21], v[50:51], s[12:13], v[100:101] op_sel_hi:[1,0,1] neg_lo:[0,0,1] neg_hi:[0,0,1]
	v_pk_add_f32 v[50:51], v[16:17], v[68:69]
	s_waitcnt vmcnt(1)
	v_lshlrev_b32_e32 v62, 16, v10
	v_pk_fma_f32 v[16:17], v[50:51], s[12:13], v[68:69] op_sel_hi:[1,0,1] neg_lo:[0,0,1] neg_hi:[0,0,1]
	v_and_b32_e32 v63, 0xffff0000, v10
	v_lshlrev_b32_e32 v68, 16, v11
	v_and_b32_e32 v69, 0xffff0000, v11
	v_pk_add_f32 v[10:11], v[28:29], v[70:71] neg_lo:[0,1] neg_hi:[0,1]
	v_lshlrev_b32_e32 v78, 16, v12
	v_and_b32_e32 v79, 0xffff0000, v12
	v_lshlrev_b32_e32 v80, 16, v13
	v_and_b32_e32 v81, 0xffff0000, v13
	v_pk_add_f32 v[28:29], v[10:11], v[62:63]
	v_pk_add_f32 v[12:13], v[34:35], v[74:75] neg_lo:[0,1] neg_hi:[0,1]
	v_mad_i64_i32 v[66:67], s[4:5], v85, s27, v[26:27]
	v_mad_i64_i32 v[54:55], s[4:5], v91, s27, v[26:27]
	v_pk_fma_f32 v[48:49], v[52:53], s[12:13], v[92:93] op_sel_hi:[1,0,1] neg_lo:[0,0,1] neg_hi:[0,0,1]
	v_mad_i64_i32 v[52:53], s[4:5], v104, s27, v[26:27]
	v_mad_i64_i32 v[60:61], s[4:5], v105, s27, v[26:27]
	v_pk_fma_f32 v[10:11], v[28:29], s[12:13], v[62:63] op_sel_hi:[1,0,1] neg_lo:[0,0,1] neg_hi:[0,0,1]
	v_pk_add_f32 v[34:35], v[12:13], v[68:69]
	v_mad_i64_i32 v[62:63], s[4:5], v106, s27, v[26:27]
	s_waitcnt vmcnt(0)
; DEV unsigned cvt_pk_bf16(float lo, float hi) { const f32x2_t v = {lo, hi}; const bf16x2_t b = __builtin_convertvector(v, bf16x2_t); return __builtin_bit_cast(unsigned, b); }
; DEV float bflo(unsigned u) { return __uint_as_float(u << 16); }
; DEV float bfhi(unsigned u) { return __uint_as_float(u & 0xffff0000u); }
; template <int WIN>
; DEV void pool_d_prompt8(const bf16_t* __restrict__ proj, bf16_t* __restrict__ dpl, int row0, int c8) {
;     ...
;     for (int j = 0; j < 8; ++j) {
;         const uint4 x = u[j + WIN - 1];
;         const float xs[8] = {bflo(x.x), bfhi(x.x), bflo(x.y), bfhi(x.y), bflo(x.z), bfhi(x.z), bflo(x.w), bfhi(x.w)};
; #pragma unroll
;         for (int e_ = 0; e_ < 8; ++e_) acc[e_] += xs[e_];
;         const float ic = 1.f / (float)min(WIN, t0 + j + 1);
;         uint4 o;
;         o.x = cvt_pk_bf16(acc[0] * ic - xs[0], acc[1] * ic - xs[1]); o.y = cvt_pk_bf16(acc[2] * ic - xs[2], acc[3] * ic - xs[3]);
;         o.z = cvt_pk_bf16(acc[4] * ic - xs[4], acc[5] * ic - xs[5]); o.w = cvt_pk_bf16(acc[6] * ic - xs[6], acc[7] * ic - xs[7]);
;         *(uint4*)(dpl + (size_t)(row0 + j) * LDP + c8) = o;
;         const uint4 y = u[j];
;         acc[0] -= bflo(y.x); acc[1] -= bfhi(y.x); acc[2] -= bflo(y.y); acc[3] -= bfhi(y.y); acc[4] -= bflo(y.z); acc[5] -= bfhi(y.z); acc[6] -= bflo(y.w); acc[7] -= bfhi(y.w);
	v_lshlrev_b32_e32 v26, 16, v6
	v_and_b32_e32 v27, 0xffff0000, v6
	v_pk_add_f32 v[28:29], v[28:29], v[56:57] neg_lo:[0,1] neg_hi:[0,1]
	v_pk_fma_f32 v[12:13], v[34:35], s[12:13], v[68:69] op_sel_hi:[1,0,1] neg_lo:[0,0,1] neg_hi:[0,0,1]
	v_pk_add_f32 v[28:29], v[28:29], v[26:27]
	v_cvt_pk_bf16_f32 v10, v10, v11
	v_cvt_pk_bf16_f32 v11, v12, v13
	v_pk_add_f32 v[12:13], v[50:51], v[86:87] neg_lo:[0,1] neg_hi:[0,1]
	v_lshlrev_b32_e32 v6, 16, v7
	v_and_b32_e32 v7, 0xffff0000, v7
	v_pk_fma_f32 v[26:27], v[28:29], s[12:13], v[26:27] op_sel_hi:[1,0,1] neg_lo:[0,0,1] neg_hi:[0,0,1]
	v_pk_add_f32 v[28:29], v[34:35], v[58:59] neg_lo:[0,1] neg_hi:[0,1]
	v_pk_add_f32 v[50:51], v[12:13], v[78:79]
	v_pk_add_f32 v[28:29], v[28:29], v[6:7]
	v_lshlrev_b32_e32 v68, 16, v8
	v_and_b32_e32 v69, 0xffff0000, v8
	v_pk_fma_f32 v[28:29], v[28:29], s[12:13], v[6:7] op_sel_hi:[1,0,1] neg_lo:[0,0,1] neg_hi:[0,0,1]
	v_pk_add_f32 v[6:7], v[50:51], v[92:93] neg_lo:[0,1] neg_hi:[0,1]
	v_and_b32_e32 v25, 0xffff0000, v25
	v_pk_add_f32 v[6:7], v[6:7], v[68:69]
	v_pk_fma_f32 v[12:13], v[50:51], s[12:13], v[78:79] op_sel_hi:[1,0,1] neg_lo:[0,0,1] neg_hi:[0,0,1]
	v_pk_fma_f32 v[34:35], v[6:7], s[12:13], v[68:69] op_sel_hi:[1,0,1] neg_lo:[0,0,1] neg_hi:[0,0,1]
	v_pk_add_f32 v[6:7], v[30:31], 0 op_sel_hi:[1,0]
	v_lshlrev_b32_e32 v50, 16, v5
	v_pk_add_f32 v[6:7], v[6:7], v[24:25]
	v_and_b32_e32 v51, 0xffff0000, v5
	v_pk_add_f32 v[6:7], v[6:7], v[50:51]
	v_cvt_pk_bf16_f32 v44, v44, v45
	v_pk_add_f32 v[6:7], v[6:7], v[22:23]
	v_cvt_pk_bf16_f32 v48, v48, v49
	v_pk_fma_f32 v[32:33], v[32:33], v[6:7], v[22:23] op_sel_hi:[0,1,1] neg_lo:[0,0,1] neg_hi:[0,0,1]
	v_cvt_pk_bf16_f32 v5, v32, v33
	global_store_dwordx4 v[76:77], v[2:5], off
	v_cvt_pk_bf16_f32 v20, v20, v21
	v_cvt_pk_bf16_f32 v16, v16, v17
	v_pk_add_f32 v[2:3], v[6:7], v[30:31] neg_lo:[0,1] neg_hi:[0,1]
	v_lshlrev_b32_e32 v8, 16, v9
	v_pk_add_f32 v[2:3], v[2:3], v[36:37]
	v_and_b32_e32 v9, 0xffff0000, v9
	v_pk_fma_f32 v[4:5], v[84:85], v[2:3], v[36:37] op_sel_hi:[0,1,1] neg_lo:[0,0,1] neg_hi:[0,0,1]
	v_pk_add_f32 v[2:3], v[2:3], v[24:25] neg_lo:[0,1] neg_hi:[0,1]
	v_cvt_pk_bf16_f32 v41, v4, v5
	v_pk_add_f32 v[2:3], v[2:3], v[88:89]
	v_ashrrev_i32_e32 v97, 31, v96
	v_pk_fma_f32 v[4:5], v[90:91], v[2:3], v[88:89] op_sel_hi:[0,1,1] neg_lo:[0,0,1] neg_hi:[0,0,1]
	v_pk_add_f32 v[2:3], v[2:3], v[50:51] neg_lo:[0,1] neg_hi:[0,1]
	v_cvt_pk_bf16_f32 v45, v4, v5
	v_pk_add_f32 v[2:3], v[2:3], v[98:99]
	v_cvt_pk_bf16_f32 v12, v12, v13
	v_pk_fma_f32 v[4:5], v[2:3], s[12:13], v[98:99] op_sel_hi:[1,0,1] neg_lo:[0,0,1] neg_hi:[0,0,1]
	v_pk_add_f32 v[2:3], v[2:3], v[22:23] neg_lo:[0,1] neg_hi:[0,1]
	v_cvt_pk_bf16_f32 v49, v4, v5
	v_pk_add_f32 v[2:3], v[2:3], v[102:103]
	global_store_dwordx4 v[66:67], v[38:41], off
	v_pk_fma_f32 v[4:5], v[2:3], s[12:13], v[102:103] op_sel_hi:[1,0,1] neg_lo:[0,0,1] neg_hi:[0,0,1]
	v_pk_add_f32 v[2:3], v[2:3], v[36:37] neg_lo:[0,1] neg_hi:[0,1]
	v_cvt_pk_bf16_f32 v21, v4, v5
	v_pk_add_f32 v[2:3], v[2:3], v[72:73]
	global_store_dwordx4 v[54:55], v[42:45], off
	v_pk_fma_f32 v[4:5], v[2:3], s[12:13], v[72:73] op_sel_hi:[1,0,1] neg_lo:[0,0,1] neg_hi:[0,0,1]
	v_pk_add_f32 v[2:3], v[2:3], v[88:89] neg_lo:[0,1] neg_hi:[0,1]
	v_cvt_pk_bf16_f32 v17, v4, v5
	v_pk_add_f32 v[2:3], v[2:3], v[80:81]
	global_store_dwordx4 v[64:65], v[46:49], off
	v_pk_fma_f32 v[4:5], v[2:3], s[12:13], v[80:81] op_sel_hi:[1,0,1] neg_lo:[0,0,1] neg_hi:[0,0,1]
	v_pk_add_f32 v[2:3], v[2:3], v[98:99] neg_lo:[0,1] neg_hi:[0,1]
	v_cvt_pk_bf16_f32 v13, v4, v5
	v_pk_add_f32 v[2:3], v[2:3], v[8:9]
	global_store_dwordx4 v[52:53], v[18:21], off
	v_pk_fma_f32 v[2:3], v[2:3], s[12:13], v[8:9] op_sel_hi:[1,0,1] neg_lo:[0,0,1] neg_hi:[0,0,1]
	global_store_dwordx4 v[60:61], v[14:17], off
	global_store_dwordx4 v[62:63], v[10:13], off

; DEV unsigned cvt_pk_bf16(float lo, float hi) { const f32x2_t v = {lo, hi}; const bf16x2_t b = __builtin_convertvector(v, bf16x2_t); return __builtin_bit_cast(unsigned, b); }
; __global__ void __launch_bounds__(512) hymba_fwd(Params p) {
;     ...
;             const float ic = 1.f / (float)win;
;             uint4 o; o.x = cvt_pk_bf16(acc[0] * ic - self[0], acc[1] * ic - self[1]); o.y = cvt_pk_bf16(acc[2] * ic - self[2], acc[3] * ic - self[3]);
;             o.z = cvt_pk_bf16(acc[4] * ic - self[4], acc[5] * ic - self[5]); o.w = cvt_pk_bf16(acc[6] * ic - self[6], acc[7] * ic - self[7]);
;             *(uint4*)(dpl + (size_t)row * LDP + c8) = o;
.LBB0_748:
	s_or_b64 exec, exec, s[12:13]
	v_cvt_f32_ubyte0_e32 v10, v40


; DEV unsigned cvt_pk_bf16(float lo, float hi) { const f32x2_t v = {lo, hi}; const bf16x2_t b = __builtin_convertvector(v, bf16x2_t); return __builtin_bit_cast(unsigned, b); }
; DEV float bflo(unsigned u) { return __uint_as_float(u << 16); }
; DEV float bfhi(unsigned u) { return __uint_as_float(u & 0xffff0000u); }
; __global__ void __launch_bounds__(512) hymba_fwd(Params p) {
;     ...
;         for (int i = TP * 128 + bid * 512 + tid; i < TT * 128; i += G * 512) {
;             const int row = i >> 7, c8 = (i & 127) * 8, g = c8 >> 8, win = 2 << g;
;             float acc[8] = {0.f, 0.f, 0.f, 0.f, 0.f, 0.f, 0.f, 0.f}, self[8];
;             const int tloc = (row - TP) & 3;
;             for (int k = 0; k < win; ++k) {
;                 const int tt = tloc - k;
;                 if (tt >= 0) {
;                     const uint4 u = *(const uint4*)(proj + (size_t)(row - k) * NPJ + C_U + c8);
;                     const float f[8] = {bflo(u.x), bfhi(u.x), bflo(u.y), bfhi(u.y), bflo(u.z), bfhi(u.z), bflo(u.w), bfhi(u.w)};
; #pragma unroll
;                     for (int e = 0; e < 8; ++e) { acc[e] += f[e]; if (k == 0) self[e] = f[e]; }
;                 } else {
;                     const float* sp = p.in[7] + ((size_t)((row - TP) >> 2) * 15 + (15 + tt)) * 1024 + c8;
;                     const f32x4 s0 = *(const f32x4*)sp, s1 = *(const f32x4*)(sp + 4);
;                     acc[0] += s0[0]; acc[1] += s0[1]; acc[2] += s0[2]; acc[3] += s0[3]; acc[4] += s1[0]; acc[5] += s1[1]; acc[6] += s1[2]; acc[7] += s1[3];
;                 }
;             }
;             const float ic = 1.f / (float)win;
;             uint4 o; o.x = cvt_pk_bf16(acc[0] * ic - self[0], acc[1] * ic - self[1]); o.y = cvt_pk_bf16(acc[2] * ic - self[2], acc[3] * ic - self[3]);
;             o.z = cvt_pk_bf16(acc[4] * ic - self[4], acc[5] * ic - self[5]); o.w = cvt_pk_bf16(acc[6] * ic - self[6], acc[7] * ic - self[7]);
;             *(uint4*)(dpl + (size_t)row * LDP + c8) = o;
	v_add_u32_e32 v23, s18, v23


; DEV unsigned cvt_pk_bf16(float lo, float hi) { const f32x2_t v = {lo, hi}; const bf16x2_t b = __builtin_convertvector(v, bf16x2_t); return __builtin_bit_cast(unsigned, b); }
; __global__ void __launch_bounds__(512) hymba_fwd(Params p) {
;     ...
;             const float ic = 1.f / (float)win;
;             uint4 o; o.x = cvt_pk_bf16(acc[0] * ic - self[0], acc[1] * ic - self[1]); o.y = cvt_pk_bf16(acc[2] * ic - self[2], acc[3] * ic - self[3]);
;             o.z = cvt_pk_bf16(acc[4] * ic - self[4], acc[5] * ic - self[5]); o.w = cvt_pk_bf16(acc[6] * ic - self[6], acc[7] * ic - self[7]);
;             *(uint4*)(dpl + (size_t)row * LDP + c8) = o;
	v_rcp_f32_e32 v11, v10
	s_nop 0
	v_mul_f32_e32 v10, 1.0, v11
	v_pk_fma_f32 v[2:3], v[10:11], v[2:3], v[34:35] op_sel_hi:[0,1,1] neg_lo:[0,0,1] neg_hi:[0,0,1]
	v_pk_fma_f32 v[4:5], v[10:11], v[4:5], v[32:33] op_sel_hi:[0,1,1] neg_lo:[0,0,1] neg_hi:[0,0,1]
	v_cvt_pk_bf16_f32 v2, v2, v3
	v_cvt_pk_bf16_f32 v3, v4, v5
	v_pk_fma_f32 v[4:5], v[10:11], v[6:7], v[30:31] op_sel_hi:[0,1,1] neg_lo:[0,0,1] neg_hi:[0,0,1]
	v_pk_fma_f32 v[6:7], v[10:11], v[8:9], v[28:29] op_sel_hi:[0,1,1] neg_lo:[0,0,1] neg_hi:[0,0,1]
	v_cvt_pk_bf16_f32 v4, v4, v5
	v_cvt_pk_bf16_f32 v5, v6, v7
	v_mad_i64_i32 v[6:7], s[12:13], v22, s23, v[140:141]
	v_lshlrev_b32_e32 v20, 1, v24
	v_cmp_lt_i32_e32 vcc, s24, v23
	v_lshl_add_u64 v[6:7], v[6:7], 0, v[20:21]
	s_or_b64 s[8:9], vcc, s[8:9]
	v_add_u32_e32 v25, s19, v25
	global_store_dwordx4 v[6:7], v[2:5], off
	s_andn2_b64 exec, exec, s[8:9]
	s_cbranch_execz .LBB0_755

; DEV float bf2f(unsigned b) { return __uint_as_float(b << 16); }
; DEV float silu_f(float x) { return x / (1.f + __expf(-x)); }
; DEV void gdn_sample_item(const Params& p, int item, unsigned char* lds) {
;     ...
;     for (int m = 0; m < 3; ++m) {
;         const int col = m * 1024 + h * 128 + c;
;         float x[7], wj[4];
; #pragma unroll
;         for (int j = 0; j < 3; ++j) x[j] = p.in[6][((size_t)sb * 3 + j) * 3072 + col];
; #pragma unroll
;         for (int t = 0; t < 4; ++t) x[3 + t] = bf2f(proj[(size_t)(r0 + t) * NPJ + col]);
; #pragma unroll
;         for (int j = 0; j < 4; ++j) wj[j] = p.in[10][j * 3072 + col];
; #pragma unroll
;         for (int t = 0; t < 4; ++t) {
;             const float y = silu_f(wj[0] * x[t] + wj[1] * x[t + 1] + wj[2] * x[t + 2] + wj[3] * x[t + 3]);
.LBB0_823:
	s_add_i32 s4, s71, s86
	s_min_i32 s52, s4, 0x3ff
	v_mov_b32_e32 v97, v1
	s_and_b32 s37, s52, 7
	s_lshl_b32 s87, s37, 7
	v_and_b32_e32 v96, 0x7f, v97
	v_or_b32_e32 v28, s87, v96
	s_ashr_i32 s5, s52, 3
	v_lshlrev_b32_e32 v2, 2, v28
	s_mul_i32 s4, s5, 3
	v_lshl_add_u64 v[6:7], s[26:27], 0, v[2:3]
	v_mad_i64_i32 v[6:7], s[6:7], s4, v78, v[6:7]
	v_add_co_u32_e32 v8, vcc, s66, v6
	v_lshl_add_u64 v[22:23], s[16:17], 0, v[2:3]
	s_nop 0
	v_addc_co_u32_e32 v9, vcc, 0, v7, vcc
	v_add_co_u32_e32 v10, vcc, s67, v6
	s_lshl_b32 s8, s5, 2
	s_nop 0
	v_addc_co_u32_e32 v11, vcc, 0, v7, vcc
	global_load_dword v29, v[6:7], off
	global_load_dword v13, v[8:9], off
	s_nop 0
	global_load_dword v10, v[10:11], off
	v_lshlrev_b32_e32 v6, 1, v28
	v_mov_b32_e32 v7, v3
	v_add_co_u32_e32 v24, vcc, s68, v22
	s_add_i32 s42, s8, 0x2000
	v_lshl_add_u64 v[20:21], s[10:11], 0, v[6:7]
	v_addc_co_u32_e32 v25, vcc, 0, v23, vcc
	v_mad_i64_i32 v[6:7], s[6:7], s42, v78, v[20:21]
	v_add_co_u32_e32 v14, vcc, s69, v22
	global_load_ushort v9, v[6:7], off
	global_load_dword v5, v2, s[16:17]
	s_nop 0
	global_load_dword v6, v[24:25], off offset:-4096
	v_addc_co_u32_e32 v15, vcc, 0, v23, vcc
	v_add_co_u32_e32 v26, vcc, s73, v22
	global_load_dword v7, v[14:15], off offset:-4096
	s_nop 0
	v_addc_co_u32_e32 v27, vcc, 0, v23, vcc
	global_load_dword v8, v[26:27], off offset:-4096
	v_or_b32_e32 v12, 0x400, v28
	v_add_co_u32_e32 v16, vcc, s77, v22
	v_lshlrev_b32_e32 v2, 2, v12
	s_nop 0
	v_addc_co_u32_e32 v17, vcc, 0, v23, vcc
	global_load_dword v11, v[14:15], off
	global_load_dword v74, v[16:17], off
	v_lshl_add_u64 v[14:15], s[26:27], 0, v[2:3]
	v_mad_i64_i32 v[14:15], s[6:7], s4, v78, v[14:15]
	s_mul_i32 s5, s5, 0xc000
	v_add_co_u32_e32 v16, vcc, s66, v14
	s_add_i32 s9, s5, 0x6000000
	s_add_i32 s40, s8, 0x2001
	s_add_i32 s38, s8, 0x2002
	s_add_i32 s15, s5, 0x6006000
	s_add_i32 s36, s8, 0x2003
	s_add_i32 s5, s5, 0x6009000
	v_addc_co_u32_e32 v17, vcc, 0, v15, vcc
	s_mul_hi_i32 s14, s42, 0x3000
	v_add_co_u32_e32 v18, vcc, s67, v14
	s_add_u32 s50, s10, s9
	s_nop 0
	v_addc_co_u32_e32 v19, vcc, 0, v15, vcc
	global_load_dword v38, v[14:15], off
	s_nop 0
	global_load_dword v16, v[16:17], off
	s_nop 0
	global_load_dword v14, v[18:19], off
	s_addc_u32 s51, s11, s14
	v_lshlrev_b32_e32 v17, 1, v12
	global_load_ushort v39, v17, s[50:51]
	global_load_dword v18, v2, s[16:17]
	global_load_dword v19, v[24:25], off
	global_load_dword v12, v[26:27], off
	v_add_co_u32_e32 v24, vcc, s74, v22
	s_mul_i32 s9, s40, 0x3000
	s_nop 0
	v_addc_co_u32_e32 v25, vcc, 0, v23, vcc
	v_add_co_u32_e32 v22, vcc, s76, v22
	s_mul_hi_i32 s8, s40, 0x3000
	s_nop 0
	v_addc_co_u32_e32 v23, vcc, 0, v23, vcc
	global_load_dword v76, v[24:25], off
	global_load_dword v75, v[22:23], off
	v_mad_i64_i32 v[22:23], s[6:7], s40, v78, v[20:21]
	v_mad_i64_i32 v[24:25], s[6:7], s38, v78, v[20:21]
	v_mad_i64_i32 v[20:21], s[6:7], s36, v78, v[20:21]
	global_load_ushort v26, v[22:23], off
	global_load_ushort v15, v[24:25], off
	s_nop 0
	global_load_ushort v21, v[20:21], off
	s_add_u32 s48, s10, s9
	v_or_b32_e32 v23, 0x800, v28
	s_addc_u32 s49, s11, s8
	v_lshlrev_b32_e32 v2, 2, v23
	s_mul_hi_i32 s14, s38, 0x3000
	s_add_u32 s46, s10, s15
	s_addc_u32 s47, s11, s14
	v_lshl_add_u64 v[30:31], s[26:27], 0, v[2:3]
	s_add_u32 s44, s10, s5
	v_mad_i64_i32 v[30:31], s[4:5], s4, v78, v[30:31]
	v_add_co_u32_e32 v32, vcc, s66, v30
	s_mul_hi_i32 s39, s36, 0x3000
	s_nop 0
	v_addc_co_u32_e32 v33, vcc, 0, v31, vcc
	v_add_co_u32_e32 v34, vcc, s67, v30
	global_load_dword v77, v2, s[16:17]
	s_addc_u32 s45, s11, s39
	global_load_ushort v28, v17, s[48:49]
	global_load_ushort v25, v17, s[46:47]
	global_load_ushort v22, v17, s[44:45]
	s_waitcnt vmcnt(22)
	v_lshlrev_b32_e32 v20, 16, v9
	s_waitcnt vmcnt(20)
	v_mul_f32_e32 v24, v13, v6
	v_fmac_f32_e32 v24, v29, v5
	v_addc_co_u32_e32 v35, vcc, 0, v31, vcc
	v_ashrrev_i32_e32 v104, 6, v97
	s_waitcnt vmcnt(19)
	v_fmac_f32_e32 v24, v10, v7
	v_and_b32_e32 v40, 63, v97
	s_waitcnt vmcnt(18)
	v_fmac_f32_e32 v24, v8, v20
	v_mul_f32_e32 v9, 0xbfb8aa3b, v24
	v_exp_f32_e32 v9, v9
	s_nop 0
	v_add_f32_e32 v27, 1.0, v9
	global_load_dword v9, v[30:31], off
	global_load_dword v109, v[32:33], off
	global_load_dword v107, v[34:35], off
	v_lshlrev_b32_e32 v30, 1, v23
	v_mov_b32_e32 v31, v3
	v_lshl_add_u64 v[30:31], s[10:11], 0, v[30:31]
	v_mad_i64_i32 v[32:33], s[4:5], s42, v78, v[30:31]
	v_mad_i64_i32 v[34:35], s[4:5], s40, v78, v[30:31]
	v_mad_i64_i32 v[36:37], s[4:5], s38, v78, v[30:31]
	v_mad_i64_i32 v[30:31], s[4:5], s36, v78, v[30:31]
	global_load_ushort v111, v[32:33], off
	global_load_ushort v110, v[34:35], off
	global_load_ushort v108, v[36:37], off
	global_load_ushort v106, v[30:31], off


; DEV float silu_f(float x) { return x / (1.f + __expf(-x)); }
; DEV void gdn_sample_item(const Params& p, int item, unsigned char* lds) {
;     ...
; #pragma unroll
;         for (int t = 0; t < 4; ++t) {
;             const float y = silu_f(wj[0] * x[t] + wj[1] * x[t + 1] + wj[2] * x[t + 2] + wj[3] * x[t + 3]);
;             if (m == 0) qv[t] = y; else if (m == 1) kv[t] = y; else vv[t] = y;
	s_waitcnt vmcnt(19)
	v_lshlrev_b32_e32 v23, 16, v39

; DEV float silu_f(float x) { return x / (1.f + __expf(-x)); }
; DEV void gdn_sample_item(const Params& p, int item, unsigned char* lds) {
;     ...
; #pragma unroll
;         for (int t = 0; t < 4; ++t) {
;             const float y = silu_f(wj[0] * x[t] + wj[1] * x[t + 1] + wj[2] * x[t + 2] + wj[3] * x[t + 3]);
;             if (m == 0) qv[t] = y; else if (m == 1) kv[t] = y; else vv[t] = y;
	s_waitcnt vmcnt(17)
	v_mul_f32_e32 v30, v16, v19
	v_fmac_f32_e32 v30, v38, v18
	v_fmac_f32_e32 v30, v14, v11
	s_waitcnt vmcnt(16)
	v_fmac_f32_e32 v30, v12, v23
	v_mul_f32_e32 v31, 0xbfb8aa3b, v30


; DEV float silu_f(float x) { return x / (1.f + __expf(-x)); }
; DEV void gdn_sample_item(const Params& p, int item, unsigned char* lds) {
;     ...
; #pragma unroll
;         for (int t = 0; t < 4; ++t) {
;             const float y = silu_f(wj[0] * x[t] + wj[1] * x[t + 1] + wj[2] * x[t + 2] + wj[3] * x[t + 3]);
;             if (m == 0) qv[t] = y; else if (m == 1) kv[t] = y; else vv[t] = y;
	v_exp_f32_e32 v31, v31


; DEV float silu_f(float x) { return x / (1.f + __expf(-x)); }
; DEV void gdn_sample_item(const Params& p, int item, unsigned char* lds) {
;     ...
; #pragma unroll
;         for (int t = 0; t < 4; ++t) {
;             const float y = silu_f(wj[0] * x[t] + wj[1] * x[t + 1] + wj[2] * x[t + 2] + wj[3] * x[t + 3]);
;             if (m == 0) qv[t] = y; else if (m == 1) kv[t] = y; else vv[t] = y;
	s_nop 0
	v_add_f32_e32 v29, 1.0, v31


; DEV float silu_f(float x) { return x / (1.f + __expf(-x)); }
; DEV void gdn_sample_item(const Params& p, int item, unsigned char* lds) {
;     ...
; #pragma unroll
;         for (int t = 0; t < 4; ++t) {
;             const float y = silu_f(wj[0] * x[t] + wj[1] * x[t + 1] + wj[2] * x[t + 2] + wj[3] * x[t + 3]);
;             if (m == 0) qv[t] = y; else if (m == 1) kv[t] = y; else vv[t] = y;
	v_rcp_f32_e32 v2, v27
	s_nop 0
	v_mul_f32_e32 v2, v24, v2
	v_cmp_eq_u32_e64 s[4:5], 0, v40


; DEV float silu_f(float x) { return x / (1.f + __expf(-x)); }
; DEV void gdn_sample_item(const Params& p, int item, unsigned char* lds) {
;     ...
; #pragma unroll
;         for (int t = 0; t < 4; ++t) {
;             const float y = silu_f(wj[0] * x[t] + wj[1] * x[t + 1] + wj[2] * x[t + 2] + wj[3] * x[t + 3]);
;             if (m == 0) qv[t] = y; else if (m == 1) kv[t] = y; else vv[t] = y;
;         }
;     }
; #pragma unroll
;     for (int t = 0; t < 4; ++t) {
;         const float a = wave_sum(qv[t] * qv[t]), bq = wave_sum(kv[t] * kv[t]);
;         if (lane == 0) { red[wid * 8 + t] = a; red[wid * 8 + 4 + t] = bq; }
;     }
	v_cmp_lt_i32_e32 vcc, v81, v80
	v_rcp_f32_e32 v17, v29
	s_nop 0
	v_mul_f32_e32 v17, v30, v17
	v_mul_f32_e32 v27, v17, v17
	v_cndmask_b32_e32 v24, v79, v81, vcc
	v_lshlrev_b32_e32 v98, 2, v24
	v_mul_f32_e32 v24, v2, v2
	ds_bpermute_b32 v24, v98, v24
	ds_bpermute_b32 v27, v98, v27
	v_cmp_lt_i32_e32 vcc, v82, v80
	s_waitcnt lgkmcnt(1)
	v_fmac_f32_e32 v24, v2, v2
	v_cndmask_b32_e32 v29, v79, v82, vcc
	v_lshlrev_b32_e32 v99, 2, v29
	s_waitcnt lgkmcnt(0)
	v_fmac_f32_e32 v27, v17, v17
	ds_bpermute_b32 v29, v99, v24
	ds_bpermute_b32 v30, v99, v27
	v_cmp_lt_i32_e32 vcc, v83, v80
	s_waitcnt lgkmcnt(1)
	v_add_f32_e32 v24, v24, v29
	v_cndmask_b32_e32 v31, v79, v83, vcc
	v_lshlrev_b32_e32 v100, 2, v31
	s_waitcnt lgkmcnt(0)
	v_add_f32_e32 v27, v27, v30
	ds_bpermute_b32 v29, v100, v24
	ds_bpermute_b32 v30, v100, v27
	v_cmp_lt_i32_e32 vcc, v84, v80
	s_waitcnt lgkmcnt(1)
	v_add_f32_e32 v24, v24, v29
	v_cndmask_b32_e32 v31, v79, v84, vcc
	v_lshlrev_b32_e32 v101, 2, v31
	s_waitcnt lgkmcnt(0)
	v_add_f32_e32 v27, v27, v30
	ds_bpermute_b32 v29, v101, v24
	ds_bpermute_b32 v30, v101, v27
	v_cmp_lt_i32_e32 vcc, v85, v80
	s_waitcnt lgkmcnt(1)
	v_add_f32_e32 v24, v24, v29
	v_cndmask_b32_e32 v31, v79, v85, vcc
	v_lshlrev_b32_e32 v102, 2, v31
	s_waitcnt lgkmcnt(0)
	v_add_f32_e32 v30, v27, v30
	ds_bpermute_b32 v29, v102, v24
	ds_bpermute_b32 v31, v102, v30
	v_cmp_lt_i32_e32 vcc, v86, v80
	s_waitcnt lgkmcnt(0)
	v_add_f32_e32 v30, v30, v31
	v_cndmask_b32_e32 v27, v79, v86, vcc
	v_lshlrev_b32_e32 v103, 2, v27
	v_add_f32_e32 v27, v24, v29
	ds_bpermute_b32 v29, v103, v27
	ds_bpermute_b32 v31, v103, v30
	v_lshlrev_b32_e32 v24, 3, v104
	v_lshl_add_u32 v24, v24, 2, s70
	s_and_saveexec_b64 s[6:7], s[4:5]
	s_cbranch_execz .LBB0_825
	s_waitcnt lgkmcnt(1)
	v_add_f32_e32 v27, v27, v29
	s_waitcnt lgkmcnt(0)
	v_add_f32_e32 v29, v30, v31
	v_add_u32_e32 v30, 0x1000, v24
	ds_write2_b32 v30, v27, v29 offset1:4
.LBB0_825:
	s_or_b64 exec, exec, s[6:7]
	s_waitcnt lgkmcnt(1)
	v_mul_f32_e32 v29, v10, v6
	v_fmac_f32_e32 v29, v13, v5
	s_waitcnt vmcnt(13)
	v_lshlrev_b32_e32 v27, 16, v26
	v_fmac_f32_e32 v29, v7, v20
	v_fmac_f32_e32 v29, v8, v27
	v_mul_f32_e32 v13, 0xbfb8aa3b, v29
	v_exp_f32_e32 v13, v13
	s_waitcnt vmcnt(9)
	v_lshlrev_b32_e32 v26, 16, v28
	s_waitcnt lgkmcnt(0)
	v_mul_f32_e32 v31, v14, v19
	v_fmac_f32_e32 v31, v16, v18
	v_add_f32_e32 v13, 1.0, v13


; DEV float silu_f(float x) { return x / (1.f + __expf(-x)); }
; DEV void gdn_sample_item(const Params& p, int item, unsigned char* lds) {
;     ...
; #pragma unroll
;         for (int t = 0; t < 4; ++t) {
;             const float y = silu_f(wj[0] * x[t] + wj[1] * x[t + 1] + wj[2] * x[t + 2] + wj[3] * x[t + 3]);
;             if (m == 0) qv[t] = y; else if (m == 1) kv[t] = y; else vv[t] = y;
	v_fmac_f32_e32 v31, v11, v23
	v_fmac_f32_e32 v31, v12, v26
	v_mul_f32_e32 v16, 0xbfb8aa3b, v31

; DEV float silu_f(float x) { return x / (1.f + __expf(-x)); }
; DEV void gdn_sample_item(const Params& p, int item, unsigned char* lds) {
;     ...
; #pragma unroll
;         for (int t = 0; t < 4; ++t) {
;             const float y = silu_f(wj[0] * x[t] + wj[1] * x[t + 1] + wj[2] * x[t + 2] + wj[3] * x[t + 3]);
;             if (m == 0) qv[t] = y; else if (m == 1) kv[t] = y; else vv[t] = y;
	v_exp_f32_e32 v16, v16


; DEV float silu_f(float x) { return x / (1.f + __expf(-x)); }
; DEV void gdn_sample_item(const Params& p, int item, unsigned char* lds) {
;     ...
; #pragma unroll
;         for (int t = 0; t < 4; ++t) {
;             const float y = silu_f(wj[0] * x[t] + wj[1] * x[t + 1] + wj[2] * x[t + 2] + wj[3] * x[t + 3]);
;             if (m == 0) qv[t] = y; else if (m == 1) kv[t] = y; else vv[t] = y;
	s_nop 0
	v_add_f32_e32 v16, 1.0, v16


; DEV float silu_f(float x) { return x / (1.f + __expf(-x)); }
; DEV void gdn_sample_item(const Params& p, int item, unsigned char* lds) {
;     ...
; #pragma unroll
;         for (int t = 0; t < 4; ++t) {
;             const float y = silu_f(wj[0] * x[t] + wj[1] * x[t + 1] + wj[2] * x[t + 2] + wj[3] * x[t + 3]);
;             if (m == 0) qv[t] = y; else if (m == 1) kv[t] = y; else vv[t] = y;
	v_rcp_f32_e32 v28, v13
	s_nop 0
	v_mul_f32_e32 v13, v29, v28


; DEV float silu_f(float x) { return x / (1.f + __expf(-x)); }
; DEV void gdn_sample_item(const Params& p, int item, unsigned char* lds) {
;     ...
; #pragma unroll
;         for (int t = 0; t < 4; ++t) {
;             const float y = silu_f(wj[0] * x[t] + wj[1] * x[t + 1] + wj[2] * x[t + 2] + wj[3] * x[t + 3]);
;             if (m == 0) qv[t] = y; else if (m == 1) kv[t] = y; else vv[t] = y;
;         }
;     }
; #pragma unroll
;     for (int t = 0; t < 4; ++t) {
;         const float a = wave_sum(qv[t] * qv[t]), bq = wave_sum(kv[t] * kv[t]);
;         if (lane == 0) { red[wid * 8 + t] = a; red[wid * 8 + 4 + t] = bq; }
;     }
	v_rcp_f32_e32 v28, v16
	s_nop 0
	v_mul_f32_e32 v16, v31, v28
	v_mul_f32_e32 v28, v13, v13
	v_mul_f32_e32 v29, v16, v16
	ds_bpermute_b32 v28, v98, v28
	ds_bpermute_b32 v29, v98, v29
	s_waitcnt lgkmcnt(1)
	v_fmac_f32_e32 v28, v13, v13
	s_waitcnt lgkmcnt(0)
	v_fmac_f32_e32 v29, v16, v16
	ds_bpermute_b32 v30, v99, v28
	ds_bpermute_b32 v31, v99, v29
	s_waitcnt lgkmcnt(1)
	v_add_f32_e32 v28, v28, v30
	s_waitcnt lgkmcnt(0)
	v_add_f32_e32 v29, v29, v31
	ds_bpermute_b32 v30, v100, v28
	ds_bpermute_b32 v31, v100, v29
	s_waitcnt lgkmcnt(1)
	v_add_f32_e32 v28, v28, v30
	s_waitcnt lgkmcnt(0)
	v_add_f32_e32 v29, v29, v31
	ds_bpermute_b32 v30, v101, v28
	ds_bpermute_b32 v31, v101, v29
	s_waitcnt lgkmcnt(1)
	v_add_f32_e32 v28, v28, v30
	s_waitcnt lgkmcnt(0)
	v_add_f32_e32 v31, v29, v31
	ds_bpermute_b32 v30, v102, v28
	ds_bpermute_b32 v32, v102, v31
	s_waitcnt lgkmcnt(1)
	v_add_f32_e32 v28, v28, v30
	s_waitcnt lgkmcnt(0)
	v_add_f32_e32 v30, v31, v32
	ds_bpermute_b32 v29, v103, v28
	ds_bpermute_b32 v31, v103, v30
	s_and_saveexec_b64 s[6:7], s[4:5]
	s_cbranch_execz .LBB0_827
	s_waitcnt lgkmcnt(1)
	v_add_f32_e32 v28, v28, v29
	s_waitcnt lgkmcnt(0)
	v_add_f32_e32 v29, v30, v31
	v_add_u32_e32 v30, 0x1000, v24
	ds_write2_b32 v30, v28, v29 offset0:1 offset1:5
.LBB0_827:
	s_or_b64 exec, exec, s[6:7]
	v_lshlrev_b32_e32 v28, 16, v15
	v_mul_f32_e32 v15, v6, v20
	v_fmac_f32_e32 v15, v10, v5
	v_fmac_f32_e32 v15, v7, v27
	v_fmac_f32_e32 v15, v8, v28
	v_mul_f32_e32 v10, 0xbfb8aa3b, v15
	s_waitcnt lgkmcnt(1)
	v_exp_f32_e32 v29, v10
	s_waitcnt vmcnt(8)
	v_lshlrev_b32_e32 v10, 16, v25
	s_waitcnt lgkmcnt(0)
	v_mul_f32_e32 v31, v19, v23
	v_fmac_f32_e32 v31, v14, v18
	v_add_f32_e32 v25, 1.0, v29


; DEV float silu_f(float x) { return x / (1.f + __expf(-x)); }
; DEV void gdn_sample_item(const Params& p, int item, unsigned char* lds) {
;     ...
; #pragma unroll
;         for (int t = 0; t < 4; ++t) {
;             const float y = silu_f(wj[0] * x[t] + wj[1] * x[t + 1] + wj[2] * x[t + 2] + wj[3] * x[t + 3]);
;             if (m == 0) qv[t] = y; else if (m == 1) kv[t] = y; else vv[t] = y;
	v_fmac_f32_e32 v31, v11, v26
	v_fmac_f32_e32 v31, v12, v10
	v_mul_f32_e32 v14, 0xbfb8aa3b, v31


; DEV float silu_f(float x) { return x / (1.f + __expf(-x)); }
; DEV void gdn_sample_item(const Params& p, int item, unsigned char* lds) {
;     ...
; #pragma unroll
;         for (int t = 0; t < 4; ++t) {
;             const float y = silu_f(wj[0] * x[t] + wj[1] * x[t + 1] + wj[2] * x[t + 2] + wj[3] * x[t + 3]);
;             if (m == 0) qv[t] = y; else if (m == 1) kv[t] = y; else vv[t] = y;
	v_exp_f32_e32 v14, v14


; DEV float silu_f(float x) { return x / (1.f + __expf(-x)); }
; DEV void gdn_sample_item(const Params& p, int item, unsigned char* lds) {
;     ...
; #pragma unroll
;         for (int t = 0; t < 4; ++t) {
;             const float y = silu_f(wj[0] * x[t] + wj[1] * x[t + 1] + wj[2] * x[t + 2] + wj[3] * x[t + 3]);
;             if (m == 0) qv[t] = y; else if (m == 1) kv[t] = y; else vv[t] = y;
	s_nop 0
	v_add_f32_e32 v32, 1.0, v14


; DEV float silu_f(float x) { return x / (1.f + __expf(-x)); }
; DEV void gdn_sample_item(const Params& p, int item, unsigned char* lds) {
;     ...
; #pragma unroll
;         for (int t = 0; t < 4; ++t) {
;             const float y = silu_f(wj[0] * x[t] + wj[1] * x[t + 1] + wj[2] * x[t + 2] + wj[3] * x[t + 3]);
;             if (m == 0) qv[t] = y; else if (m == 1) kv[t] = y; else vv[t] = y;
	v_rcp_f32_e32 v14, v25
	s_nop 0
	v_mul_f32_e32 v14, v15, v14


; DEV float silu_f(float x) { return x / (1.f + __expf(-x)); }
; DEV void gdn_sample_item(const Params& p, int item, unsigned char* lds) {
;     ...
; #pragma unroll
;         for (int t = 0; t < 4; ++t) {
;             const float y = silu_f(wj[0] * x[t] + wj[1] * x[t + 1] + wj[2] * x[t + 2] + wj[3] * x[t + 3]);
;             if (m == 0) qv[t] = y; else if (m == 1) kv[t] = y; else vv[t] = y;
;         }
;     }
; #pragma unroll
;     for (int t = 0; t < 4; ++t) {
;         const float a = wave_sum(qv[t] * qv[t]), bq = wave_sum(kv[t] * kv[t]);
;         if (lane == 0) { red[wid * 8 + t] = a; red[wid * 8 + 4 + t] = bq; }
;     }
	v_rcp_f32_e32 v15, v32
	s_nop 0
	v_mul_f32_e32 v15, v31, v15
	v_mul_f32_e32 v25, v14, v14
	v_mul_f32_e32 v29, v15, v15
	ds_bpermute_b32 v25, v98, v25
	ds_bpermute_b32 v29, v98, v29
	s_waitcnt lgkmcnt(1)
	v_fmac_f32_e32 v25, v14, v14
	s_waitcnt lgkmcnt(0)
	v_fmac_f32_e32 v29, v15, v15
	ds_bpermute_b32 v30, v99, v25
	ds_bpermute_b32 v31, v99, v29
	s_waitcnt lgkmcnt(1)
	v_add_f32_e32 v25, v25, v30
	s_waitcnt lgkmcnt(0)
	v_add_f32_e32 v29, v29, v31
	ds_bpermute_b32 v30, v100, v25
	ds_bpermute_b32 v31, v100, v29
	s_waitcnt lgkmcnt(1)
	v_add_f32_e32 v25, v25, v30
	s_waitcnt lgkmcnt(0)
	v_add_f32_e32 v29, v29, v31
	ds_bpermute_b32 v30, v101, v25
	ds_bpermute_b32 v31, v101, v29
	s_waitcnt lgkmcnt(1)
	v_add_f32_e32 v25, v25, v30
	s_waitcnt lgkmcnt(0)
	v_add_f32_e32 v31, v29, v31
	ds_bpermute_b32 v30, v102, v25
	ds_bpermute_b32 v32, v102, v31
	s_waitcnt lgkmcnt(1)
	v_add_f32_e32 v25, v25, v30
	s_waitcnt lgkmcnt(0)
	v_add_f32_e32 v30, v31, v32
	ds_bpermute_b32 v29, v103, v25
	ds_bpermute_b32 v31, v103, v30
	s_and_saveexec_b64 s[6:7], s[4:5]
	s_cbranch_execz .LBB0_829
	s_waitcnt lgkmcnt(1)
	v_add_f32_e32 v25, v25, v29
	s_waitcnt lgkmcnt(0)
	v_add_f32_e32 v29, v30, v31
	v_add_u32_e32 v30, 0x1000, v24
	ds_write2_b32 v30, v25, v29 offset0:2 offset1:6
.LBB0_829:
	s_or_b64 exec, exec, s[6:7]
	v_mul_f32_e32 v6, v6, v27
	v_fmac_f32_e32 v6, v5, v20
	v_lshlrev_b32_e32 v21, 16, v21
	v_fmac_f32_e32 v6, v7, v28
	v_fmac_f32_e32 v6, v8, v21
	v_mul_f32_e32 v5, 0xbfb8aa3b, v6
	v_exp_f32_e32 v5, v5
	v_mul_f32_e32 v19, v19, v26
	v_fmac_f32_e32 v19, v18, v23
	s_waitcnt vmcnt(7)
	v_lshlrev_b32_e32 v7, 16, v22
	v_add_f32_e32 v5, 1.0, v5


; DEV float silu_f(float x) { return x / (1.f + __expf(-x)); }
; DEV void gdn_sample_item(const Params& p, int item, unsigned char* lds) {
;     ...
; #pragma unroll
;         for (int t = 0; t < 4; ++t) {
;             const float y = silu_f(wj[0] * x[t] + wj[1] * x[t + 1] + wj[2] * x[t + 2] + wj[3] * x[t + 3]);
;             if (m == 0) qv[t] = y; else if (m == 1) kv[t] = y; else vv[t] = y;
	v_fmac_f32_e32 v19, v11, v10
	v_fmac_f32_e32 v19, v12, v7
	v_mul_f32_e32 v7, 0xbfb8aa3b, v19
	v_exp_f32_e32 v7, v7


; DEV float silu_f(float x) { return x / (1.f + __expf(-x)); }
; DEV void gdn_sample_item(const Params& p, int item, unsigned char* lds) {
;     ...
; #pragma unroll
;         for (int t = 0; t < 4; ++t) {
;             const float y = silu_f(wj[0] * x[t] + wj[1] * x[t + 1] + wj[2] * x[t + 2] + wj[3] * x[t + 3]);
;             if (m == 0) qv[t] = y; else if (m == 1) kv[t] = y; else vv[t] = y;
	s_nop 0
	v_add_f32_e32 v7, 1.0, v7


; DEV float silu_f(float x) { return x / (1.f + __expf(-x)); }
; DEV void gdn_sample_item(const Params& p, int item, unsigned char* lds) {
;     ...
; #pragma unroll
;         for (int t = 0; t < 4; ++t) {
;             const float y = silu_f(wj[0] * x[t] + wj[1] * x[t + 1] + wj[2] * x[t + 2] + wj[3] * x[t + 3]);
;             if (m == 0) qv[t] = y; else if (m == 1) kv[t] = y; else vv[t] = y;
	v_rcp_f32_e32 v8, v5
	s_nop 0
	v_mul_f32_e32 v11, v6, v8


; DEV float silu_f(float x) { return x / (1.f + __expf(-x)); }
; DEV void gdn_sample_item(const Params& p, int item, unsigned char* lds) {
;     ...
; #pragma unroll
;         for (int t = 0; t < 4; ++t) {
;             const float y = silu_f(wj[0] * x[t] + wj[1] * x[t + 1] + wj[2] * x[t + 2] + wj[3] * x[t + 3]);
;             if (m == 0) qv[t] = y; else if (m == 1) kv[t] = y; else vv[t] = y;
;         }
;     }
; #pragma unroll
;     for (int t = 0; t < 4; ++t) {
;         const float a = wave_sum(qv[t] * qv[t]), bq = wave_sum(kv[t] * kv[t]);
;         if (lane == 0) { red[wid * 8 + t] = a; red[wid * 8 + 4 + t] = bq; }
;     }
	v_rcp_f32_e32 v5, v7
	s_nop 0
	v_mul_f32_e32 v12, v19, v5
	v_mul_f32_e32 v5, v11, v11
	v_mul_f32_e32 v6, v12, v12
	ds_bpermute_b32 v5, v98, v5
	ds_bpermute_b32 v6, v98, v6
	s_waitcnt lgkmcnt(1)
	v_fmac_f32_e32 v5, v11, v11
	s_waitcnt lgkmcnt(0)
	v_fmac_f32_e32 v6, v12, v12
	ds_bpermute_b32 v7, v99, v5
	ds_bpermute_b32 v8, v99, v6
	s_waitcnt lgkmcnt(1)
	v_add_f32_e32 v5, v5, v7
	s_waitcnt lgkmcnt(0)
	v_add_f32_e32 v6, v6, v8
	ds_bpermute_b32 v7, v100, v5
	ds_bpermute_b32 v8, v100, v6
	s_waitcnt lgkmcnt(1)
	v_add_f32_e32 v5, v5, v7
	s_waitcnt lgkmcnt(0)
	v_add_f32_e32 v6, v6, v8
	ds_bpermute_b32 v7, v101, v5
	ds_bpermute_b32 v8, v101, v6
	s_waitcnt lgkmcnt(1)
	v_add_f32_e32 v5, v5, v7
	s_waitcnt lgkmcnt(0)
	v_add_f32_e32 v8, v6, v8
	ds_bpermute_b32 v7, v102, v5
	ds_bpermute_b32 v10, v102, v8
	s_waitcnt lgkmcnt(1)
	v_add_f32_e32 v5, v5, v7
	s_waitcnt lgkmcnt(0)
	v_add_f32_e32 v7, v8, v10
	ds_bpermute_b32 v6, v103, v5
	ds_bpermute_b32 v8, v103, v7
	s_and_saveexec_b64 s[6:7], s[4:5]
	s_cbranch_execz .LBB0_831
	s_waitcnt lgkmcnt(1)
	v_add_f32_e32 v5, v5, v6
	s_waitcnt lgkmcnt(0)
	v_add_f32_e32 v6, v7, v8
	v_add_u32_e32 v7, 0x1000, v24
	ds_write2_b32 v7, v5, v6 offset0:3 offset1:7

; DEV void gdn_sample_item(const Params& p, int item, unsigned char* lds) {
;     ...
;         float a = 0.f, bb = 0.f;
; #pragma unroll
;         for (int kq = 0; kq < 4; ++kq) { a += ab[(size_t)kq * TT * 16 + (size_t)(r0 + t) * 16 + h]; bb += ab[(size_t)kq * TT * 16 + (size_t)(r0 + t) * 16 + 8 + h]; }
;         const float xx = a + p.in[12][h];
;         const float sp = xx > 20.f ? xx : log1pf(__expf(xx));
;         gt[t] = __expf(-__expf(p.in[11][h]) * sp);
;         bt[t] = 1.f / (1.f + __expf(-bb));
.LBB0_848:
	v_add_f32_e32 v2, 0, v2
	v_add_f32_e32 v2, v2, v6
	v_add_f32_e32 v2, v2, v7
	v_add_f32_e32 v2, v2, v8
	v_mul_f32_e32 v2, 0xbfb8aa3b, v2
	v_exp_f32_e32 v2, v2
	v_ashrrev_i32_e32 v154, 7, v97
	v_lshlrev_b32_e32 v6, 6, v154
	v_mul_f32_e32 v5, v10, v13
	v_add_f32_e32 v132, 1.0, v2


; DEV void gdn_sample_item(const Params& p, int item, unsigned char* lds) {
;     ...
;         const float xx = a + p.in[12][h];
;         const float sp = xx > 20.f ? xx : log1pf(__expf(xx));
;         gt[t] = __expf(-__expf(p.in[11][h]) * sp);
;         bt[t] = 1.f / (1.f + __expf(-bb));
;     }
;     f32x2_t S[32];
;     const float* sp0 = p.in[5] + ((size_t)(sb * 8 + h) * 128 + half * 64) * 128 + c;
; #pragma unroll
;     for (int d = 0; d < 64; ++d) S[d >> 1][d & 1] = __builtin_nontemporal_load(sp0 + (size_t)d * 128);
	s_ashr_i32 s53, s52, 31
	v_ashrrev_i32_e32 v7, 31, v6
	v_mul_f32_e32 v2, 0x3fb8aa3b, v5
	s_lshl_b64 s[8:9], s[52:53], 14
	v_lshlrev_b64 v[6:7], 7, v[6:7]
	v_exp_f32_e32 v8, v2

; DEV void gdn_sample_item(const Params& p, int item, unsigned char* lds) {
;     ...
;         const float xx = a + p.in[12][h];
;         const float sp = xx > 20.f ? xx : log1pf(__expf(xx));
;         gt[t] = __expf(-__expf(p.in[11][h]) * sp);
;         bt[t] = 1.f / (1.f + __expf(-bb));
;     }
;     f32x2_t S[32];
;     const float* sp0 = p.in[5] + ((size_t)(sb * 8 + h) * 128 + half * 64) * 128 + c;
; #pragma unroll
;     for (int d = 0; d < 64; ++d) S[d >> 1][d & 1] = __builtin_nontemporal_load(sp0 + (size_t)d * 128);
	v_lshl_add_u64 v[6:7], v[6:7], 0, s[8:9]

; DEV float silu_f(float x) { return x / (1.f + __expf(-x)); }
; DEV void gdn_sample_item(const Params& p, int item, unsigned char* lds) {
;     ...
;             const float y = silu_f(wj[0] * x[t] + wj[1] * x[t + 1] + wj[2] * x[t + 2] + wj[3] * x[t + 3]);
;             if (m == 0) qv[t] = y; else if (m == 1) kv[t] = y; else vv[t] = y;
;         }
;     }
; #pragma unroll
;     for (int t = 0; t < 4; ++t) {
;         const float a = wave_sum(qv[t] * qv[t]), bq = wave_sum(kv[t] * kv[t]);
;         if (lane == 0) { red[wid * 8 + t] = a; red[wid * 8 + 4 + t] = bq; }
;     }
;     __syncthreads();
;     float gt[4], bt[4];
; #pragma unroll
;     for (int t = 0; t < 4; ++t) {
;         const float sq = red[(2 * half) * 8 + t] + red[(2 * half + 1) * 8 + t], sk = red[(2 * half) * 8 + 4 + t] + red[(2 * half + 1) * 8 + 4 + t];
;         if (half == 0) {
;             qsh[t * 128 + c] = qv[t] * rsqrtf(sq + EPS) * 0.08838834764831845f;
;             ksh[t * 128 + c] = kv[t] * rsqrtf(sk + EPS);
;         }
;         float a = 0.f, bb = 0.f;
; #pragma unroll
;         for (int kq = 0; kq < 4; ++kq) { a += ab[(size_t)kq * TT * 16 + (size_t)(r0 + t) * 16 + h]; bb += ab[(size_t)kq * TT * 16 + (size_t)(r0 + t) * 16 + 8 + h]; }
;         const float xx = a + p.in[12][h];
;         const float sp = xx > 20.f ? xx : log1pf(__expf(xx));
;         gt[t] = __expf(-__expf(p.in[11][h]) * sp);
;         bt[t] = 1.f / (1.f + __expf(-bb));
;     }
;     f32x2_t S[32];
;     const float* sp0 = p.in[5] + ((size_t)(sb * 8 + h) * 128 + half * 64) * 128 + c;
; #pragma unroll
;     for (int d = 0; d < 64; ++d) S[d >> 1][d & 1] = __builtin_nontemporal_load(sp0 + (size_t)d * 128);
	v_lshl_add_u64 v[10:11], v[6:7], 2, s[24:25]
	v_lshlrev_b32_e32 v2, 2, v96
	v_lshl_add_u64 v[66:67], v[10:11], 0, v[2:3]
	v_add_co_u32_e32 v28, vcc, s85, v66
	global_load_dword v10, v[66:67], off nt
	global_load_dword v11, v[66:67], off offset:512 nt
	global_load_dword v12, v[66:67], off offset:1024 nt
	global_load_dword v13, v[66:67], off offset:1536 nt
	global_load_dword v14, v[66:67], off offset:2048 nt
	global_load_dword v15, v[66:67], off offset:2560 nt
	global_load_dword v16, v[66:67], off offset:3072 nt
	global_load_dword v17, v[66:67], off offset:3584 nt
	v_addc_co_u32_e32 v29, vcc, 0, v67, vcc
	v_add_co_u32_e32 v36, vcc, s65, v66
	v_mul_f32_e32 v155, v109, v76
	s_nop 0
	v_addc_co_u32_e32 v37, vcc, 0, v67, vcc
	global_load_dword v18, v[36:37], off offset:-4096 nt
	global_load_dword v26, v[36:37], off nt
	global_load_dword v27, v[36:37], off offset:512 nt
	v_add_co_u32_e32 v52, vcc, s66, v66
	v_fmac_f32_e32 v155, v9, v77
	s_nop 0
	v_addc_co_u32_e32 v53, vcc, 0, v67, vcc
	v_add_co_u32_e32 v38, vcc, s68, v66
	v_fmac_f32_e32 v155, v107, v75
	s_nop 0
	v_addc_co_u32_e32 v39, vcc, 0, v67, vcc
	global_load_dword v19, v[28:29], off offset:512 nt
	global_load_dword v20, v[28:29], off offset:1024 nt
	global_load_dword v21, v[28:29], off offset:1536 nt
	global_load_dword v22, v[28:29], off offset:2048 nt
	global_load_dword v23, v[28:29], off offset:2560 nt
	global_load_dword v24, v[28:29], off offset:3072 nt
	global_load_dword v25, v[28:29], off offset:3584 nt
	global_load_dword v35, v[52:53], off offset:512 nt
	s_nop 0
	global_load_dword v28, v[36:37], off offset:1024 nt
	global_load_dword v29, v[36:37], off offset:1536 nt
	global_load_dword v30, v[36:37], off offset:2048 nt
	global_load_dword v31, v[36:37], off offset:2560 nt
	global_load_dword v32, v[36:37], off offset:3072 nt
	global_load_dword v33, v[36:37], off offset:3584 nt
	global_load_dword v34, v[38:39], off offset:-4096 nt
	global_load_dword v42, v[38:39], off nt
	v_add_co_u32_e32 v58, vcc, s74, v66
	s_nop 1
	v_addc_co_u32_e32 v59, vcc, 0, v67, vcc
	v_add_co_u32_e32 v68, vcc, s67, v66
	s_nop 1
	v_addc_co_u32_e32 v69, vcc, 0, v67, vcc
	global_load_dword v43, v[38:39], off offset:512 nt
	global_load_dword v44, v[38:39], off offset:1024 nt
	global_load_dword v45, v[38:39], off offset:1536 nt
	global_load_dword v46, v[38:39], off offset:2048 nt
	global_load_dword v47, v[38:39], off offset:2560 nt
	global_load_dword v48, v[38:39], off offset:3072 nt
	global_load_dword v49, v[38:39], off offset:3584 nt
	global_load_dword v50, v[68:69], off offset:-4096 nt
	global_load_dword v36, v[52:53], off offset:1024 nt
	global_load_dword v37, v[52:53], off offset:1536 nt
	s_nop 0
	global_load_dword v38, v[52:53], off offset:2048 nt
	global_load_dword v39, v[52:53], off offset:2560 nt
	global_load_dword v40, v[52:53], off offset:3072 nt
	global_load_dword v41, v[52:53], off offset:3584 nt
	global_load_dword v51, v[58:59], off offset:512 nt
	s_nop 0
	global_load_dword v52, v[58:59], off offset:1024 nt
	global_load_dword v53, v[58:59], off offset:1536 nt
	global_load_dword v54, v[58:59], off offset:2048 nt
	global_load_dword v55, v[58:59], off offset:2560 nt
	global_load_dword v56, v[58:59], off offset:3072 nt
	global_load_dword v57, v[58:59], off offset:3584 nt
	s_nop 0
	global_load_dword v58, v[68:69], off nt
	global_load_dword v59, v[68:69], off offset:512 nt
	global_load_dword v60, v[68:69], off offset:1024 nt
	global_load_dword v61, v[68:69], off offset:1536 nt
	global_load_dword v62, v[68:69], off offset:2048 nt
	global_load_dword v63, v[68:69], off offset:2560 nt
	global_load_dword v64, v[68:69], off offset:3072 nt
	global_load_dword v65, v[68:69], off offset:3584 nt
	v_add_co_u32_e32 v130, vcc, s69, v66
	s_nop 1
	v_addc_co_u32_e32 v131, vcc, 0, v67, vcc
	global_load_dword v66, v[130:131], off nt
	global_load_dword v67, v[130:131], off offset:512 nt
	global_load_dword v68, v[130:131], off offset:1024 nt
	global_load_dword v69, v[130:131], off offset:1536 nt
	global_load_dword v70, v[130:131], off offset:2048 nt
	global_load_dword v71, v[130:131], off offset:2560 nt
	global_load_dword v72, v[130:131], off offset:3072 nt
	global_load_dword v73, v[130:131], off offset:3584 nt
	v_lshlrev_b32_e32 v130, 16, v111
	v_fmac_f32_e32 v155, v74, v130
	v_mul_f32_e32 v9, 0xbfb8aa3b, v155
	v_exp_f32_e32 v9, v9


; DEV float silu_f(float x) { return x / (1.f + __expf(-x)); }
; DEV void gdn_sample_item(const Params& p, int item, unsigned char* lds) {
;     ...
;             const float y = silu_f(wj[0] * x[t] + wj[1] * x[t + 1] + wj[2] * x[t + 2] + wj[3] * x[t + 3]);
;             if (m == 0) qv[t] = y; else if (m == 1) kv[t] = y; else vv[t] = y;
;         }
;     }
; #pragma unroll
;     for (int t = 0; t < 4; ++t) {
;         const float a = wave_sum(qv[t] * qv[t]), bq = wave_sum(kv[t] * kv[t]);
;         if (lane == 0) { red[wid * 8 + t] = a; red[wid * 8 + 4 + t] = bq; }
;     }
;     __syncthreads();
;     float gt[4], bt[4];
; #pragma unroll
;     for (int t = 0; t < 4; ++t) {
;         const float sq = red[(2 * half) * 8 + t] + red[(2 * half + 1) * 8 + t], sk = red[(2 * half) * 8 + 4 + t] + red[(2 * half + 1) * 8 + 4 + t];
;         if (half == 0) {
;             qsh[t * 128 + c] = qv[t] * rsqrtf(sq + EPS) * 0.08838834764831845f;
;             ksh[t * 128 + c] = kv[t] * rsqrtf(sk + EPS);
;         }
;         float a = 0.f, bb = 0.f;
; #pragma unroll
;         for (int kq = 0; kq < 4; ++kq) { a += ab[(size_t)kq * TT * 16 + (size_t)(r0 + t) * 16 + h]; bb += ab[(size_t)kq * TT * 16 + (size_t)(r0 + t) * 16 + 8 + h]; }
;         const float xx = a + p.in[12][h];
;         const float sp = xx > 20.f ? xx : log1pf(__expf(xx));
;         gt[t] = __expf(-__expf(p.in[11][h]) * sp);
;         bt[t] = 1.f / (1.f + __expf(-bb));
	s_nop 0
	v_add_f32_e32 v9, 1.0, v9


; DEV void gdn_sample_item(const Params& p, int item, unsigned char* lds) {
;     ...
;         bt[t] = 1.f / (1.f + __expf(-bb));
;     }
;     f32x2_t S[32];
;     const float* sp0 = p.in[5] + ((size_t)(sb * 8 + h) * 128 + half * 64) * 128 + c;
; #pragma unroll
;     for (int d = 0; d < 64; ++d) S[d >> 1][d & 1] = __builtin_nontemporal_load(sp0 + (size_t)d * 128);
;     __syncthreads();
;     float ot[4];
; #pragma unroll
;     for (int t = 0; t < 4; ++t) {
;         const float* kk = ksh + t * 128 + half * 64; const float* qq = qsh + t * 128 + half * 64;
;         f32x2_t ks2 = {0.f, 0.f};
; #pragma unroll
;         for (int d4 = 0; d4 < 16; ++d4) { const f32x4 k4 = *(const f32x4*)(kk + d4 * 4); ks2 += (f32x2_t){k4[0], k4[1]} * S[d4 * 2]; ks2 += (f32x2_t){k4[2], k4[3]} * S[d4 * 2 + 1]; }
	v_lshl_add_u32 v111, v154, 8, s70
	v_rcp_f32_e32 v5, v132
	s_nop 0
	v_mul_f32_e32 v5, 1.0, v5
	s_waitcnt lgkmcnt(0)
	s_barrier
	ds_read_b128 v[132:135], v111
	ds_read_b128 v[142:145], v111 offset:16
	ds_read_b128 v[146:149], v111 offset:32
	ds_read_b128 v[150:153], v111 offset:48

; DEV void gdn_sample_item(const Params& p, int item, unsigned char* lds) {
;     ...
;         const float* kk = ksh + t * 128 + half * 64; const float* qq = qsh + t * 128 + half * 64;
;         f32x2_t ks2 = {0.f, 0.f};
; #pragma unroll
;         for (int d4 = 0; d4 < 16; ++d4) { const f32x4 k4 = *(const f32x4*)(kk + d4 * 4); ks2 += (f32x2_t){k4[0], k4[1]} * S[d4 * 2]; ks2 += (f32x2_t){k4[2], k4[3]} * S[d4 * 2 + 1]; }
;         part[(t * 2 + half) * 128 + c] = ks2[0] + ks2[1];
	v_cmp_eq_u32_e64 s[8:9], 1, v154
	s_waitcnt vmcnt(62) lgkmcnt(3)
	v_pk_fma_f32 v[132:133], v[10:11], v[132:133], 0 op_sel_hi:[1,1,0]
	s_waitcnt vmcnt(60)
	v_pk_fma_f32 v[132:133], v[12:13], v[134:135], v[132:133]
	s_waitcnt vmcnt(58) lgkmcnt(2)
	v_pk_fma_f32 v[132:133], v[14:15], v[142:143], v[132:133]
	s_waitcnt vmcnt(56)
	v_pk_fma_f32 v[132:133], v[16:17], v[144:145], v[132:133]
	ds_read_b128 v[142:145], v111 offset:80
	s_waitcnt vmcnt(52) lgkmcnt(2)
	v_pk_fma_f32 v[136:137], v[18:19], v[146:147], v[132:133]
	ds_read_b128 v[132:135], v111 offset:64
	s_waitcnt vmcnt(50)
	v_pk_fma_f32 v[136:137], v[20:21], v[148:149], v[136:137]
	ds_read_b128 v[146:149], v111 offset:96
	s_waitcnt vmcnt(48) lgkmcnt(3)
	v_pk_fma_f32 v[136:137], v[22:23], v[150:151], v[136:137]
	s_waitcnt vmcnt(46)
	v_pk_fma_f32 v[136:137], v[24:25], v[152:153], v[136:137]
	s_waitcnt lgkmcnt(1)
	v_pk_fma_f32 v[132:133], v[26:27], v[132:133], v[136:137]
	s_waitcnt vmcnt(43)
	v_pk_fma_f32 v[132:133], v[28:29], v[134:135], v[132:133]
	s_waitcnt vmcnt(41)
	v_pk_fma_f32 v[136:137], v[30:31], v[142:143], v[132:133]
	ds_read_b128 v[132:135], v111 offset:112
	s_waitcnt vmcnt(39)
	v_pk_fma_f32 v[136:137], v[32:33], v[144:145], v[136:137]
	ds_read_b128 v[142:145], v111 offset:128
	s_waitcnt vmcnt(38) lgkmcnt(2)
	v_pk_fma_f32 v[136:137], v[34:35], v[146:147], v[136:137]
	s_waitcnt vmcnt(27)
	v_pk_fma_f32 v[136:137], v[36:37], v[148:149], v[136:137]
	ds_read_b128 v[146:149], v111 offset:144
	s_waitcnt vmcnt(25) lgkmcnt(2)
	v_pk_fma_f32 v[132:133], v[38:39], v[132:133], v[136:137]
	s_waitcnt vmcnt(23)
	v_pk_fma_f32 v[132:133], v[40:41], v[134:135], v[132:133]
	s_waitcnt lgkmcnt(1)
	v_pk_fma_f32 v[136:137], v[42:43], v[142:143], v[132:133]
	ds_read_b128 v[132:135], v111 offset:160
	v_pk_fma_f32 v[136:137], v[44:45], v[144:145], v[136:137]
	ds_read_b128 v[142:145], v111 offset:176
	s_waitcnt lgkmcnt(2)
	v_pk_fma_f32 v[136:137], v[46:47], v[146:147], v[136:137]
	s_nop 0
	v_pk_fma_f32 v[136:137], v[48:49], v[148:149], v[136:137]
	ds_read_b128 v[146:149], v111 offset:192
	s_waitcnt vmcnt(22) lgkmcnt(2)
	v_pk_fma_f32 v[132:133], v[50:51], v[132:133], v[136:137]
	s_waitcnt vmcnt(20)
	v_pk_fma_f32 v[132:133], v[52:53], v[134:135], v[132:133]
	s_waitcnt vmcnt(18) lgkmcnt(1)
	v_pk_fma_f32 v[132:133], v[54:55], v[142:143], v[132:133]
	s_waitcnt vmcnt(16)
	v_pk_fma_f32 v[136:137], v[56:57], v[144:145], v[132:133]
	ds_read_b128 v[132:135], v111 offset:208
	ds_read_b128 v[142:145], v111 offset:224
	s_waitcnt vmcnt(14) lgkmcnt(2)
	v_pk_fma_f32 v[136:137], v[58:59], v[146:147], v[136:137]
	s_waitcnt vmcnt(12)
	v_pk_fma_f32 v[136:137], v[60:61], v[148:149], v[136:137]
	ds_read_b128 v[146:149], v111 offset:240
	s_waitcnt vmcnt(10) lgkmcnt(2)
	v_pk_fma_f32 v[132:133], v[62:63], v[132:133], v[136:137]
	s_waitcnt vmcnt(8)
	v_pk_fma_f32 v[132:133], v[64:65], v[134:135], v[132:133]

; DEV float silu_f(float x) { return x / (1.f + __expf(-x)); }
; DEV void gdn_sample_item(const Params& p, int item, unsigned char* lds) {
;     ...
;             const float y = silu_f(wj[0] * x[t] + wj[1] * x[t + 1] + wj[2] * x[t + 2] + wj[3] * x[t + 3]);
;     ...
;         const float* kk = ksh + t * 128 + half * 64; const float* qq = qsh + t * 128 + half * 64;
;         f32x2_t ks2 = {0.f, 0.f};
; #pragma unroll
;         for (int d4 = 0; d4 < 16; ++d4) { const f32x4 k4 = *(const f32x4*)(kk + d4 * 4); ks2 += (f32x2_t){k4[0], k4[1]} * S[d4 * 2]; ks2 += (f32x2_t){k4[2], k4[3]} * S[d4 * 2 + 1]; }
;         part[(t * 2 + half) * 128 + c] = ks2[0] + ks2[1];
;         __syncthreads();
;         const float kS = part[(t * 2) * 128 + c] + part[(t * 2 + 1) * 128 + c];
;         const float eg = gt[t], dl = bt[t] * (vv[t] - eg * kS);
;         const f32x2_t eg2 = {eg, eg}, dl2 = {dl, dl};
;         f32x2_t o2 = {0.f, 0.f};
; #pragma unroll
;         for (int d4 = 0; d4 < 16; ++d4) {
;             const f32x4 k4 = *(const f32x4*)(kk + d4 * 4), q4 = *(const f32x4*)(qq + d4 * 4);
;             const f32x2_t s0 = S[d4 * 2] * eg2 + (f32x2_t){k4[0], k4[1]} * dl2, s1 = S[d4 * 2 + 1] * eg2 + (f32x2_t){k4[2], k4[3]} * dl2;
;             S[d4 * 2] = s0; S[d4 * 2 + 1] = s1;
;             o2 += (f32x2_t){q4[0], q4[1]} * s0; o2 += (f32x2_t){q4[2], q4[3]} * s1;
;         }
	s_waitcnt vmcnt(6) lgkmcnt(1)
	v_pk_fma_f32 v[132:133], v[66:67], v[142:143], v[132:133]
	v_rcp_f32_e32 v134, v9
	s_nop 0
	v_mul_f32_e32 v9, v155, v134
	s_waitcnt vmcnt(4)
	v_pk_fma_f32 v[132:133], v[68:69], v[144:145], v[132:133]
	s_waitcnt vmcnt(2) lgkmcnt(0)
	v_pk_fma_f32 v[132:133], v[70:71], v[146:147], v[132:133]
	s_waitcnt vmcnt(0)
	v_pk_fma_f32 v[132:133], v[72:73], v[148:149], v[132:133]
	s_nop 0
	v_add_f32_e32 v131, v132, v133
	ds_write_b32 v105, v131 offset:4352
	v_add_u32_e32 v131, s70, v2
	s_waitcnt lgkmcnt(0)
	s_barrier
	ds_read2st64_b32 v[132:133], v131 offset0:17 offset1:19
	s_waitcnt lgkmcnt(0)
	v_add_f32_e32 v132, v132, v133
	v_fma_f32 v9, -v8, v132, v9
	v_mul_f32_e32 v136, v5, v9
	ds_read_b128 v[132:135], v111
	ds_read_b128 v[142:145], v111 offset:16
	ds_read_b128 v[146:149], v111 offset:32
	ds_read_b128 v[150:153], v111 offset:48
	ds_read_b128 v[154:157], v111 offset:2048
	s_waitcnt lgkmcnt(4)
	v_pk_mul_f32 v[132:133], v[132:133], v[136:137] op_sel_hi:[1,0]
	s_waitcnt lgkmcnt(3)
	v_pk_mul_f32 v[142:143], v[142:143], v[136:137] op_sel_hi:[1,0]
	v_pk_fma_f32 v[10:11], v[8:9], v[10:11], v[132:133] op_sel_hi:[0,1,1]
	v_pk_mul_f32 v[132:133], v[134:135], v[136:137] op_sel_hi:[1,0]
	s_waitcnt lgkmcnt(0)
	v_pk_fma_f32 v[154:155], v[154:155], v[10:11], 0 op_sel_hi:[1,1,0]
	v_pk_fma_f32 v[12:13], v[8:9], v[12:13], v[132:133] op_sel_hi:[0,1,1]
	ds_read_b128 v[132:135], v111 offset:2064
	v_pk_fma_f32 v[154:155], v[156:157], v[12:13], v[154:155]
	v_pk_fma_f32 v[14:15], v[8:9], v[14:15], v[142:143] op_sel_hi:[0,1,1]
	v_pk_mul_f32 v[142:143], v[144:145], v[136:137] op_sel_hi:[1,0]
	s_waitcnt lgkmcnt(0)
	v_pk_fma_f32 v[132:133], v[132:133], v[14:15], v[154:155]
	v_pk_fma_f32 v[16:17], v[8:9], v[16:17], v[142:143] op_sel_hi:[0,1,1]
	v_pk_fma_f32 v[154:155], v[134:135], v[16:17], v[132:133]
	ds_read_b128 v[132:135], v111 offset:2080
	v_pk_mul_f32 v[142:143], v[136:137], v[146:147] op_sel_hi:[0,1]
	v_pk_fma_f32 v[18:19], v[8:9], v[18:19], v[142:143] op_sel_hi:[0,1,1]
	v_pk_mul_f32 v[142:143], v[136:137], v[148:149] op_sel_hi:[0,1]
	v_pk_fma_f32 v[20:21], v[8:9], v[20:21], v[142:143] op_sel_hi:[0,1,1]
	ds_read_b128 v[142:145], v111 offset:2096
	s_waitcnt lgkmcnt(1)
	v_pk_fma_f32 v[132:133], v[132:133], v[18:19], v[154:155]
	s_nop 0
	v_pk_fma_f32 v[146:147], v[134:135], v[20:21], v[132:133]
	v_pk_mul_f32 v[132:133], v[136:137], v[150:151] op_sel_hi:[0,1]
	v_pk_fma_f32 v[22:23], v[8:9], v[22:23], v[132:133] op_sel_hi:[0,1,1]
	v_pk_mul_f32 v[132:133], v[136:137], v[152:153] op_sel_hi:[0,1]
	v_pk_fma_f32 v[24:25], v[8:9], v[24:25], v[132:133] op_sel_hi:[0,1,1]
	ds_read_b128 v[132:135], v111 offset:64
	s_waitcnt lgkmcnt(1)
	v_pk_fma_f32 v[142:143], v[142:143], v[22:23], v[146:147]
	s_waitcnt lgkmcnt(0)
	v_pk_mul_f32 v[132:133], v[136:137], v[132:133] op_sel_hi:[0,1]
	v_pk_fma_f32 v[150:151], v[144:145], v[24:25], v[142:143]
	ds_read_b128 v[142:145], v111 offset:2112
	ds_read_b128 v[146:149], v111 offset:80
	v_pk_fma_f32 v[26:27], v[8:9], v[26:27], v[132:133] op_sel_hi:[0,1,1]
	v_pk_mul_f32 v[132:133], v[136:137], v[134:135] op_sel_hi:[0,1]
	v_pk_fma_f32 v[28:29], v[8:9], v[28:29], v[132:133] op_sel_hi:[0,1,1]
	ds_read_b128 v[132:135], v111 offset:2128
	s_waitcnt lgkmcnt(2)
	v_pk_fma_f32 v[142:143], v[142:143], v[26:27], v[150:151]
	s_nop 0
	v_pk_fma_f32 v[150:151], v[144:145], v[28:29], v[142:143]
	s_waitcnt lgkmcnt(1)
	v_pk_mul_f32 v[142:143], v[136:137], v[146:147] op_sel_hi:[0,1]
	v_pk_fma_f32 v[30:31], v[8:9], v[30:31], v[142:143] op_sel_hi:[0,1,1]
	v_pk_mul_f32 v[142:143], v[136:137], v[148:149] op_sel_hi:[0,1]
	v_pk_fma_f32 v[32:33], v[8:9], v[32:33], v[142:143] op_sel_hi:[0,1,1]
	ds_read_b128 v[142:145], v111 offset:96
	s_waitcnt lgkmcnt(1)
	v_pk_fma_f32 v[132:133], v[132:133], v[30:31], v[150:151]
	s_waitcnt lgkmcnt(0)
	v_pk_mul_f32 v[142:143], v[136:137], v[142:143] op_sel_hi:[0,1]
	v_pk_fma_f32 v[150:151], v[134:135], v[32:33], v[132:133]
	ds_read_b128 v[132:135], v111 offset:2144
	ds_read_b128 v[146:149], v111 offset:112
	v_pk_fma_f32 v[34:35], v[8:9], v[34:35], v[142:143] op_sel_hi:[0,1,1]
	v_pk_mul_f32 v[142:143], v[136:137], v[144:145] op_sel_hi:[0,1]
	v_pk_fma_f32 v[36:37], v[8:9], v[36:37], v[142:143] op_sel_hi:[0,1,1]
	ds_read_b128 v[142:145], v111 offset:2160
	s_waitcnt lgkmcnt(2)
	v_pk_fma_f32 v[132:133], v[132:133], v[34:35], v[150:151]
	s_nop 0
	v_pk_fma_f32 v[150:151], v[134:135], v[36:37], v[132:133]
	s_waitcnt lgkmcnt(1)
	v_pk_mul_f32 v[132:133], v[136:137], v[146:147] op_sel_hi:[0,1]
	v_pk_fma_f32 v[38:39], v[8:9], v[38:39], v[132:133] op_sel_hi:[0,1,1]
	v_pk_mul_f32 v[132:133], v[136:137], v[148:149] op_sel_hi:[0,1]
	v_pk_fma_f32 v[40:41], v[8:9], v[40:41], v[132:133] op_sel_hi:[0,1,1]
	ds_read_b128 v[132:135], v111 offset:128
	s_waitcnt lgkmcnt(1)
; DEV void gdn_sample_item(const Params& p, int item, unsigned char* lds) {
;     ...
;         float a = 0.f, bb = 0.f;
; #pragma unroll
;         for (int kq = 0; kq < 4; ++kq) { a += ab[(size_t)kq * TT * 16 + (size_t)(r0 + t) * 16 + h]; bb += ab[(size_t)kq * TT * 16 + (size_t)(r0 + t) * 16 + 8 + h]; }
;         const float xx = a + p.in[12][h];
;         const float sp = xx > 20.f ? xx : log1pf(__expf(xx));
;         gt[t] = __expf(-__expf(p.in[11][h]) * sp);
;         bt[t] = 1.f / (1.f + __expf(-bb));
;     ...
;         for (int d4 = 0; d4 < 16; ++d4) {
;             const f32x4 k4 = *(const f32x4*)(kk + d4 * 4), q4 = *(const f32x4*)(qq + d4 * 4);
;             const f32x2_t s0 = S[d4 * 2] * eg2 + (f32x2_t){k4[0], k4[1]} * dl2, s1 = S[d4 * 2 + 1] * eg2 + (f32x2_t){k4[2], k4[3]} * dl2;
;             S[d4 * 2] = s0; S[d4 * 2 + 1] = s1;
;             o2 += (f32x2_t){q4[0], q4[1]} * s0; o2 += (f32x2_t){q4[2], q4[3]} * s1;
;         }
;         const float o = o2[0] + o2[1];
;         ot[t] = o;
;         if (half == 1) opart[t * 128 + c] = o;
	v_pk_fma_f32 v[142:143], v[142:143], v[38:39], v[150:151]
	s_waitcnt lgkmcnt(0)
	v_pk_mul_f32 v[132:133], v[136:137], v[132:133] op_sel_hi:[0,1]
	v_pk_fma_f32 v[150:151], v[144:145], v[40:41], v[142:143]
	ds_read_b128 v[142:145], v111 offset:2176
	ds_read_b128 v[146:149], v111 offset:144
	v_pk_fma_f32 v[42:43], v[8:9], v[42:43], v[132:133] op_sel_hi:[0,1,1]
	v_pk_mul_f32 v[132:133], v[136:137], v[134:135] op_sel_hi:[0,1]
	v_pk_fma_f32 v[44:45], v[8:9], v[44:45], v[132:133] op_sel_hi:[0,1,1]
	ds_read_b128 v[132:135], v111 offset:2192
	s_waitcnt lgkmcnt(2)
	v_pk_fma_f32 v[142:143], v[142:143], v[42:43], v[150:151]
	s_nop 0
	v_pk_fma_f32 v[150:151], v[144:145], v[44:45], v[142:143]
	s_waitcnt lgkmcnt(1)
	v_pk_mul_f32 v[142:143], v[136:137], v[146:147] op_sel_hi:[0,1]
	v_pk_fma_f32 v[46:47], v[8:9], v[46:47], v[142:143] op_sel_hi:[0,1,1]
	v_pk_mul_f32 v[142:143], v[136:137], v[148:149] op_sel_hi:[0,1]
	v_pk_fma_f32 v[48:49], v[8:9], v[48:49], v[142:143] op_sel_hi:[0,1,1]
	ds_read_b128 v[142:145], v111 offset:160
	s_waitcnt lgkmcnt(1)
	v_pk_fma_f32 v[132:133], v[132:133], v[46:47], v[150:151]
	s_waitcnt lgkmcnt(0)
	v_pk_mul_f32 v[142:143], v[136:137], v[142:143] op_sel_hi:[0,1]
	v_pk_fma_f32 v[150:151], v[134:135], v[48:49], v[132:133]
	ds_read_b128 v[132:135], v111 offset:2208
	ds_read_b128 v[146:149], v111 offset:176
	v_pk_fma_f32 v[50:51], v[8:9], v[50:51], v[142:143] op_sel_hi:[0,1,1]
	v_pk_mul_f32 v[142:143], v[136:137], v[144:145] op_sel_hi:[0,1]
	v_pk_fma_f32 v[52:53], v[8:9], v[52:53], v[142:143] op_sel_hi:[0,1,1]
	ds_read_b128 v[142:145], v111 offset:2224
	s_waitcnt lgkmcnt(2)
	v_pk_fma_f32 v[132:133], v[132:133], v[50:51], v[150:151]
	s_nop 0
	v_pk_fma_f32 v[150:151], v[134:135], v[52:53], v[132:133]
	s_waitcnt lgkmcnt(1)
	v_pk_mul_f32 v[132:133], v[136:137], v[146:147] op_sel_hi:[0,1]
	v_pk_fma_f32 v[54:55], v[8:9], v[54:55], v[132:133] op_sel_hi:[0,1,1]
	v_pk_mul_f32 v[132:133], v[136:137], v[148:149] op_sel_hi:[0,1]
	v_pk_fma_f32 v[56:57], v[8:9], v[56:57], v[132:133] op_sel_hi:[0,1,1]
	ds_read_b128 v[132:135], v111 offset:192
	s_waitcnt lgkmcnt(1)
	v_pk_fma_f32 v[142:143], v[142:143], v[54:55], v[150:151]
	s_waitcnt lgkmcnt(0)
	v_pk_mul_f32 v[132:133], v[136:137], v[132:133] op_sel_hi:[0,1]
	v_pk_fma_f32 v[150:151], v[144:145], v[56:57], v[142:143]
	ds_read_b128 v[142:145], v111 offset:2240
	ds_read_b128 v[146:149], v111 offset:208
	v_pk_fma_f32 v[58:59], v[8:9], v[58:59], v[132:133] op_sel_hi:[0,1,1]
	v_pk_mul_f32 v[132:133], v[136:137], v[134:135] op_sel_hi:[0,1]
	v_pk_fma_f32 v[60:61], v[8:9], v[60:61], v[132:133] op_sel_hi:[0,1,1]
	s_waitcnt lgkmcnt(1)
	v_pk_fma_f32 v[142:143], v[142:143], v[58:59], v[150:151]
	ds_read_b128 v[132:135], v111 offset:2256
	v_pk_fma_f32 v[150:151], v[144:145], v[60:61], v[142:143]
	s_waitcnt lgkmcnt(1)
	v_pk_mul_f32 v[142:143], v[136:137], v[146:147] op_sel_hi:[0,1]
	v_pk_fma_f32 v[62:63], v[8:9], v[62:63], v[142:143] op_sel_hi:[0,1,1]
	v_pk_mul_f32 v[142:143], v[136:137], v[148:149] op_sel_hi:[0,1]
	v_pk_fma_f32 v[64:65], v[8:9], v[64:65], v[142:143] op_sel_hi:[0,1,1]
	ds_read_b128 v[142:145], v111 offset:224
	s_waitcnt lgkmcnt(1)
	v_pk_fma_f32 v[132:133], v[132:133], v[62:63], v[150:151]
	s_waitcnt lgkmcnt(0)
	v_pk_mul_f32 v[142:143], v[136:137], v[142:143] op_sel_hi:[0,1]
	v_pk_fma_f32 v[150:151], v[134:135], v[64:65], v[132:133]
	ds_read_b128 v[132:135], v111 offset:2272
	ds_read_b128 v[146:149], v111 offset:240
	v_pk_fma_f32 v[66:67], v[8:9], v[66:67], v[142:143] op_sel_hi:[0,1,1]
	v_pk_mul_f32 v[142:143], v[136:137], v[144:145] op_sel_hi:[0,1]
	v_pk_fma_f32 v[68:69], v[8:9], v[68:69], v[142:143] op_sel_hi:[0,1,1]
	ds_read_b128 v[142:145], v111 offset:2288
	s_waitcnt lgkmcnt(2)
	v_pk_fma_f32 v[132:133], v[132:133], v[66:67], v[150:151]
	s_nop 0
	v_pk_fma_f32 v[132:133], v[134:135], v[68:69], v[132:133]
	s_waitcnt lgkmcnt(1)
	v_pk_mul_f32 v[134:135], v[136:137], v[146:147] op_sel_hi:[0,1]
	v_pk_fma_f32 v[70:71], v[8:9], v[70:71], v[134:135] op_sel_hi:[0,1,1]
	v_pk_mul_f32 v[134:135], v[136:137], v[148:149] op_sel_hi:[0,1]
	v_pk_fma_f32 v[8:9], v[8:9], v[72:73], v[134:135] op_sel_hi:[0,1,1]
	s_waitcnt lgkmcnt(0)
	v_pk_fma_f32 v[72:73], v[142:143], v[70:71], v[132:133]
	s_nop 0
	v_pk_fma_f32 v[72:73], v[144:145], v[8:9], v[72:73]
	s_nop 0
	v_add_f32_e32 v5, v72, v73
	s_and_saveexec_b64 s[52:53], s[8:9]
	ds_write_b32 v131, v5 offset:8448
	s_or_b64 exec, exec, s[52:53]
	v_add_f32_e32 v72, 0, v120
	v_add_f32_e32 v72, v72, v121
	v_add_f32_e32 v72, v72, v122
	v_add_f32_e32 v72, v72, v123
	v_mul_f32_e32 v72, 0xbfb8aa3b, v72
	v_exp_f32_e32 v72, v72
	v_mul_f32_e32 v136, v107, v76
	v_fmac_f32_e32 v136, v109, v77
	v_lshlrev_b32_e32 v110, 16, v110
	v_add_f32_e32 v120, 1.0, v72
	v_fmac_f32_e32 v136, v75, v130

; DEV float silu_f(float x) { return x / (1.f + __expf(-x)); }
; DEV void gdn_sample_item(const Params& p, int item, unsigned char* lds) {
;     ...
;             const float y = silu_f(wj[0] * x[t] + wj[1] * x[t + 1] + wj[2] * x[t + 2] + wj[3] * x[t + 3]);
	v_fmac_f32_e32 v136, v74, v110

; DEV float silu_f(float x) { return x / (1.f + __expf(-x)); }
; DEV void gdn_sample_item(const Params& p, int item, unsigned char* lds) {
;     ...
;             const float y = silu_f(wj[0] * x[t] + wj[1] * x[t + 1] + wj[2] * x[t + 2] + wj[3] * x[t + 3]);
;     ...
;         const float xx = a + p.in[12][h];
;         const float sp = xx > 20.f ? xx : log1pf(__expf(xx));
;         gt[t] = __expf(-__expf(p.in[11][h]) * sp);
	v_mul_f32_e32 v109, 0xbfb8aa3b, v136
	v_exp_f32_e32 v109, v109
	v_mul_f32_e32 v73, v128, v129
	v_mul_f32_e32 v73, 0x3fb8aa3b, v73

; DEV void gdn_sample_item(const Params& p, int item, unsigned char* lds) {
;     ...
;         gt[t] = __expf(-__expf(p.in[11][h]) * sp);
	v_exp_f32_e32 v72, v73


; DEV float silu_f(float x) { return x / (1.f + __expf(-x)); }
; DEV void gdn_sample_item(const Params& p, int item, unsigned char* lds) {
;     ...
;             const float y = silu_f(wj[0] * x[t] + wj[1] * x[t + 1] + wj[2] * x[t + 2] + wj[3] * x[t + 3]);
	v_add_f32_e32 v109, 1.0, v109


; DEV void gdn_sample_item(const Params& p, int item, unsigned char* lds) {
;     ...
;         bt[t] = 1.f / (1.f + __expf(-bb));
	v_rcp_f32_e32 v73, v120
	s_nop 0
	v_mul_f32_e32 v73, 1.0, v73


; DEV void gdn_sample_item(const Params& p, int item, unsigned char* lds) {
;     ...
;         const float* kk = ksh + t * 128 + half * 64; const float* qq = qsh + t * 128 + half * 64;
;         f32x2_t ks2 = {0.f, 0.f};
; #pragma unroll
;         for (int d4 = 0; d4 < 16; ++d4) { const f32x4 k4 = *(const f32x4*)(kk + d4 * 4); ks2 += (f32x2_t){k4[0], k4[1]} * S[d4 * 2]; ks2 += (f32x2_t){k4[2], k4[3]} * S[d4 * 2 + 1]; }
	ds_read_b128 v[120:123], v111 offset:512
	ds_read_b128 v[132:135], v111 offset:528
	ds_read_b128 v[142:145], v111 offset:544
	ds_read_b128 v[146:149], v111 offset:560


; DEV void gdn_sample_item(const Params& p, int item, unsigned char* lds) {
;     ...
;         for (int d4 = 0; d4 < 16; ++d4) { const f32x4 k4 = *(const f32x4*)(kk + d4 * 4); ks2 += (f32x2_t){k4[0], k4[1]} * S[d4 * 2]; ks2 += (f32x2_t){k4[2], k4[3]} * S[d4 * 2 + 1]; }
	s_waitcnt lgkmcnt(3)
	v_pk_fma_f32 v[120:121], v[10:11], v[120:121], 0 op_sel_hi:[1,1,0]

; DEV void gdn_sample_item(const Params& p, int item, unsigned char* lds) {
;     ...
;         for (int d4 = 0; d4 < 16; ++d4) { const f32x4 k4 = *(const f32x4*)(kk + d4 * 4); ks2 += (f32x2_t){k4[0], k4[1]} * S[d4 * 2]; ks2 += (f32x2_t){k4[2], k4[3]} * S[d4 * 2 + 1]; }
	v_pk_fma_f32 v[120:121], v[12:13], v[122:123], v[120:121]

; DEV void gdn_sample_item(const Params& p, int item, unsigned char* lds) {
;     ...
;         const float* kk = ksh + t * 128 + half * 64; const float* qq = qsh + t * 128 + half * 64;
;         f32x2_t ks2 = {0.f, 0.f};
; #pragma unroll
;         for (int d4 = 0; d4 < 16; ++d4) { const f32x4 k4 = *(const f32x4*)(kk + d4 * 4); ks2 += (f32x2_t){k4[0], k4[1]} * S[d4 * 2]; ks2 += (f32x2_t){k4[2], k4[3]} * S[d4 * 2 + 1]; }
;         part[(t * 2 + half) * 128 + c] = ks2[0] + ks2[1];
	s_waitcnt lgkmcnt(2)
	v_pk_fma_f32 v[120:121], v[14:15], v[132:133], v[120:121]
	s_nop 0
	v_pk_fma_f32 v[120:121], v[16:17], v[134:135], v[120:121]
	ds_read_b128 v[132:135], v111 offset:592
	s_waitcnt lgkmcnt(2)
	v_pk_fma_f32 v[128:129], v[18:19], v[142:143], v[120:121]
	ds_read_b128 v[120:123], v111 offset:576
	v_pk_fma_f32 v[128:129], v[20:21], v[144:145], v[128:129]
	ds_read_b128 v[142:145], v111 offset:608
	s_waitcnt lgkmcnt(3)
	v_pk_fma_f32 v[128:129], v[22:23], v[146:147], v[128:129]
	s_nop 0
	v_pk_fma_f32 v[128:129], v[24:25], v[148:149], v[128:129]
	s_waitcnt lgkmcnt(1)
	v_pk_fma_f32 v[120:121], v[26:27], v[120:121], v[128:129]
	s_nop 0
	v_pk_fma_f32 v[120:121], v[28:29], v[122:123], v[120:121]
	s_nop 0
	v_pk_fma_f32 v[128:129], v[30:31], v[132:133], v[120:121]
	ds_read_b128 v[120:123], v111 offset:624
	v_pk_fma_f32 v[128:129], v[32:33], v[134:135], v[128:129]
	ds_read_b128 v[132:135], v111 offset:640
	s_waitcnt lgkmcnt(2)
	v_pk_fma_f32 v[128:129], v[34:35], v[142:143], v[128:129]
	s_nop 0
	v_pk_fma_f32 v[128:129], v[36:37], v[144:145], v[128:129]
	ds_read_b128 v[142:145], v111 offset:656
	s_waitcnt lgkmcnt(2)
	v_pk_fma_f32 v[120:121], v[38:39], v[120:121], v[128:129]
	s_nop 0
	v_pk_fma_f32 v[120:121], v[40:41], v[122:123], v[120:121]
	s_waitcnt lgkmcnt(1)
	v_pk_fma_f32 v[128:129], v[42:43], v[132:133], v[120:121]
	ds_read_b128 v[120:123], v111 offset:672
	v_pk_fma_f32 v[128:129], v[44:45], v[134:135], v[128:129]
	ds_read_b128 v[132:135], v111 offset:688
	s_waitcnt lgkmcnt(2)
	v_pk_fma_f32 v[128:129], v[46:47], v[142:143], v[128:129]
	s_nop 0
	v_pk_fma_f32 v[128:129], v[48:49], v[144:145], v[128:129]
	ds_read_b128 v[142:145], v111 offset:704
	s_waitcnt lgkmcnt(2)
	v_pk_fma_f32 v[120:121], v[50:51], v[120:121], v[128:129]
	s_nop 0
	v_pk_fma_f32 v[120:121], v[52:53], v[122:123], v[120:121]
	s_waitcnt lgkmcnt(1)
	v_pk_fma_f32 v[120:121], v[54:55], v[132:133], v[120:121]
	s_nop 0
	v_pk_fma_f32 v[128:129], v[56:57], v[134:135], v[120:121]
	ds_read_b128 v[120:123], v111 offset:720
	ds_read_b128 v[132:135], v111 offset:736
	s_waitcnt lgkmcnt(2)
	v_pk_fma_f32 v[128:129], v[58:59], v[142:143], v[128:129]
	s_nop 0
	v_pk_fma_f32 v[128:129], v[60:61], v[144:145], v[128:129]
	ds_read_b128 v[142:145], v111 offset:752
	s_waitcnt lgkmcnt(2)
	v_pk_fma_f32 v[120:121], v[62:63], v[120:121], v[128:129]
	s_nop 0
	v_pk_fma_f32 v[120:121], v[64:65], v[122:123], v[120:121]

; DEV void gdn_sample_item(const Params& p, int item, unsigned char* lds) {
;     ...
;         for (int d4 = 0; d4 < 16; ++d4) { const f32x4 k4 = *(const f32x4*)(kk + d4 * 4); ks2 += (f32x2_t){k4[0], k4[1]} * S[d4 * 2]; ks2 += (f32x2_t){k4[2], k4[3]} * S[d4 * 2 + 1]; }
	s_waitcnt lgkmcnt(1)
	v_pk_fma_f32 v[120:121], v[66:67], v[132:133], v[120:121]

; DEV float silu_f(float x) { return x / (1.f + __expf(-x)); }
; DEV void gdn_sample_item(const Params& p, int item, unsigned char* lds) {
;     ...
;             const float y = silu_f(wj[0] * x[t] + wj[1] * x[t + 1] + wj[2] * x[t + 2] + wj[3] * x[t + 3]);
;     ...
;         part[(t * 2 + half) * 128 + c] = ks2[0] + ks2[1];
;         __syncthreads();
;         const float kS = part[(t * 2) * 128 + c] + part[(t * 2 + 1) * 128 + c];
;         const float eg = gt[t], dl = bt[t] * (vv[t] - eg * kS);
;         const f32x2_t eg2 = {eg, eg}, dl2 = {dl, dl};
;         f32x2_t o2 = {0.f, 0.f};
; #pragma unroll
;         for (int d4 = 0; d4 < 16; ++d4) {
;             const f32x4 k4 = *(const f32x4*)(kk + d4 * 4), q4 = *(const f32x4*)(qq + d4 * 4);
;             const f32x2_t s0 = S[d4 * 2] * eg2 + (f32x2_t){k4[0], k4[1]} * dl2, s1 = S[d4 * 2 + 1] * eg2 + (f32x2_t){k4[2], k4[3]} * dl2;
;             S[d4 * 2] = s0; S[d4 * 2 + 1] = s1;
;             o2 += (f32x2_t){q4[0], q4[1]} * s0; o2 += (f32x2_t){q4[2], q4[3]} * s1;
;         }
	v_pk_fma_f32 v[120:121], v[68:69], v[134:135], v[120:121]
	v_rcp_f32_e32 v122, v109
	s_nop 0
	v_mul_f32_e32 v109, v136, v122
	s_waitcnt lgkmcnt(0)
	v_pk_fma_f32 v[120:121], v[70:71], v[142:143], v[120:121]
	s_nop 0
	v_pk_fma_f32 v[120:121], v[8:9], v[144:145], v[120:121]
	s_nop 0
	v_add_f32_e32 v120, v120, v121
	ds_write_b32 v105, v120 offset:5376
	s_waitcnt lgkmcnt(0)
	s_barrier
	ds_read2st64_b32 v[120:121], v131 offset0:21 offset1:23
	s_waitcnt lgkmcnt(0)
	v_add_f32_e32 v120, v120, v121
	v_fma_f32 v109, -v72, v120, v109
	v_mul_f32_e32 v128, v73, v109
	ds_read_b128 v[120:123], v111 offset:512
	ds_read_b128 v[132:135], v111 offset:528
	ds_read_b128 v[142:145], v111 offset:544
	ds_read_b128 v[146:149], v111 offset:560
	ds_read_b128 v[150:153], v111 offset:2560
	s_waitcnt lgkmcnt(4)
	v_pk_mul_f32 v[120:121], v[120:121], v[128:129] op_sel_hi:[1,0]
	s_waitcnt lgkmcnt(3)
	v_pk_mul_f32 v[132:133], v[132:133], v[128:129] op_sel_hi:[1,0]
	v_pk_fma_f32 v[10:11], v[72:73], v[10:11], v[120:121] op_sel_hi:[0,1,1]
	v_pk_mul_f32 v[120:121], v[122:123], v[128:129] op_sel_hi:[1,0]
	s_waitcnt lgkmcnt(0)
	v_pk_fma_f32 v[136:137], v[150:151], v[10:11], 0 op_sel_hi:[1,1,0]
	v_pk_fma_f32 v[12:13], v[72:73], v[12:13], v[120:121] op_sel_hi:[0,1,1]
	ds_read_b128 v[120:123], v111 offset:2576
	v_pk_fma_f32 v[136:137], v[152:153], v[12:13], v[136:137]
	v_pk_fma_f32 v[14:15], v[72:73], v[14:15], v[132:133] op_sel_hi:[0,1,1]
	v_pk_mul_f32 v[132:133], v[134:135], v[128:129] op_sel_hi:[1,0]
	s_waitcnt lgkmcnt(0)
	v_pk_fma_f32 v[120:121], v[120:121], v[14:15], v[136:137]
	v_pk_fma_f32 v[16:17], v[72:73], v[16:17], v[132:133] op_sel_hi:[0,1,1]
	v_pk_fma_f32 v[136:137], v[122:123], v[16:17], v[120:121]
	ds_read_b128 v[120:123], v111 offset:2592
	v_pk_mul_f32 v[132:133], v[128:129], v[142:143] op_sel_hi:[0,1]
	v_pk_fma_f32 v[18:19], v[72:73], v[18:19], v[132:133] op_sel_hi:[0,1,1]
	v_pk_mul_f32 v[132:133], v[128:129], v[144:145] op_sel_hi:[0,1]
	v_pk_fma_f32 v[20:21], v[72:73], v[20:21], v[132:133] op_sel_hi:[0,1,1]
	ds_read_b128 v[132:135], v111 offset:2608
	s_waitcnt lgkmcnt(1)
	v_pk_fma_f32 v[120:121], v[120:121], v[18:19], v[136:137]
	s_nop 0
	v_pk_fma_f32 v[136:137], v[122:123], v[20:21], v[120:121]
	v_pk_mul_f32 v[120:121], v[128:129], v[146:147] op_sel_hi:[0,1]
	v_pk_fma_f32 v[22:23], v[72:73], v[22:23], v[120:121] op_sel_hi:[0,1,1]
	v_pk_mul_f32 v[120:121], v[128:129], v[148:149] op_sel_hi:[0,1]
	v_pk_fma_f32 v[24:25], v[72:73], v[24:25], v[120:121] op_sel_hi:[0,1,1]
	ds_read_b128 v[120:123], v111 offset:576
	s_waitcnt lgkmcnt(1)
	v_pk_fma_f32 v[132:133], v[132:133], v[22:23], v[136:137]
	s_waitcnt lgkmcnt(0)
	v_pk_mul_f32 v[120:121], v[128:129], v[120:121] op_sel_hi:[0,1]
	v_pk_fma_f32 v[136:137], v[134:135], v[24:25], v[132:133]
	ds_read_b128 v[132:135], v111 offset:2624
	ds_read_b128 v[142:145], v111 offset:592
	v_pk_fma_f32 v[26:27], v[72:73], v[26:27], v[120:121] op_sel_hi:[0,1,1]
	v_pk_mul_f32 v[120:121], v[128:129], v[122:123] op_sel_hi:[0,1]
	v_pk_fma_f32 v[28:29], v[72:73], v[28:29], v[120:121] op_sel_hi:[0,1,1]
	ds_read_b128 v[120:123], v111 offset:2640
	s_waitcnt lgkmcnt(2)
	v_pk_fma_f32 v[132:133], v[132:133], v[26:27], v[136:137]
	s_nop 0
	v_pk_fma_f32 v[136:137], v[134:135], v[28:29], v[132:133]
	s_waitcnt lgkmcnt(1)
	v_pk_mul_f32 v[132:133], v[128:129], v[142:143] op_sel_hi:[0,1]
	v_pk_fma_f32 v[30:31], v[72:73], v[30:31], v[132:133] op_sel_hi:[0,1,1]
	v_pk_mul_f32 v[132:133], v[128:129], v[144:145] op_sel_hi:[0,1]
	v_pk_fma_f32 v[32:33], v[72:73], v[32:33], v[132:133] op_sel_hi:[0,1,1]
	ds_read_b128 v[132:135], v111 offset:608
	s_waitcnt lgkmcnt(1)
	v_pk_fma_f32 v[120:121], v[120:121], v[30:31], v[136:137]
	s_waitcnt lgkmcnt(0)
	v_pk_mul_f32 v[132:133], v[128:129], v[132:133] op_sel_hi:[0,1]
	v_pk_fma_f32 v[136:137], v[122:123], v[32:33], v[120:121]
	ds_read_b128 v[120:123], v111 offset:2656
	ds_read_b128 v[142:145], v111 offset:624
	v_pk_fma_f32 v[34:35], v[72:73], v[34:35], v[132:133] op_sel_hi:[0,1,1]
	v_pk_mul_f32 v[132:133], v[128:129], v[134:135] op_sel_hi:[0,1]
	v_pk_fma_f32 v[36:37], v[72:73], v[36:37], v[132:133] op_sel_hi:[0,1,1]
	ds_read_b128 v[132:135], v111 offset:2672
	s_waitcnt lgkmcnt(2)
	v_pk_fma_f32 v[120:121], v[120:121], v[34:35], v[136:137]
	s_nop 0
	v_pk_fma_f32 v[136:137], v[122:123], v[36:37], v[120:121]
	s_waitcnt lgkmcnt(1)
	v_pk_mul_f32 v[120:121], v[128:129], v[142:143] op_sel_hi:[0,1]
	v_pk_fma_f32 v[38:39], v[72:73], v[38:39], v[120:121] op_sel_hi:[0,1,1]
	v_pk_mul_f32 v[120:121], v[128:129], v[144:145] op_sel_hi:[0,1]
	v_pk_fma_f32 v[40:41], v[72:73], v[40:41], v[120:121] op_sel_hi:[0,1,1]
	ds_read_b128 v[120:123], v111 offset:640
	s_waitcnt lgkmcnt(1)
	v_pk_fma_f32 v[132:133], v[132:133], v[38:39], v[136:137]
	s_waitcnt lgkmcnt(0)
; DEV void gdn_sample_item(const Params& p, int item, unsigned char* lds) {
;     ...
;         float a = 0.f, bb = 0.f;
; #pragma unroll
;         for (int kq = 0; kq < 4; ++kq) { a += ab[(size_t)kq * TT * 16 + (size_t)(r0 + t) * 16 + h]; bb += ab[(size_t)kq * TT * 16 + (size_t)(r0 + t) * 16 + 8 + h]; }
;         const float xx = a + p.in[12][h];
;         const float sp = xx > 20.f ? xx : log1pf(__expf(xx));
;         gt[t] = __expf(-__expf(p.in[11][h]) * sp);
;         bt[t] = 1.f / (1.f + __expf(-bb));
;     ...
;         for (int d4 = 0; d4 < 16; ++d4) {
;             const f32x4 k4 = *(const f32x4*)(kk + d4 * 4), q4 = *(const f32x4*)(qq + d4 * 4);
;             const f32x2_t s0 = S[d4 * 2] * eg2 + (f32x2_t){k4[0], k4[1]} * dl2, s1 = S[d4 * 2 + 1] * eg2 + (f32x2_t){k4[2], k4[3]} * dl2;
;             S[d4 * 2] = s0; S[d4 * 2 + 1] = s1;
;             o2 += (f32x2_t){q4[0], q4[1]} * s0; o2 += (f32x2_t){q4[2], q4[3]} * s1;
;         }
;         const float o = o2[0] + o2[1];
;         ot[t] = o;
;         if (half == 1) opart[t * 128 + c] = o;
	v_pk_mul_f32 v[120:121], v[128:129], v[120:121] op_sel_hi:[0,1]
	v_pk_fma_f32 v[136:137], v[134:135], v[40:41], v[132:133]
	ds_read_b128 v[132:135], v111 offset:2688
	ds_read_b128 v[142:145], v111 offset:656
	v_pk_fma_f32 v[42:43], v[72:73], v[42:43], v[120:121] op_sel_hi:[0,1,1]
	v_pk_mul_f32 v[120:121], v[128:129], v[122:123] op_sel_hi:[0,1]
	v_pk_fma_f32 v[44:45], v[72:73], v[44:45], v[120:121] op_sel_hi:[0,1,1]
	ds_read_b128 v[120:123], v111 offset:2704
	s_waitcnt lgkmcnt(2)
	v_pk_fma_f32 v[132:133], v[132:133], v[42:43], v[136:137]
	s_nop 0
	v_pk_fma_f32 v[136:137], v[134:135], v[44:45], v[132:133]
	s_waitcnt lgkmcnt(1)
	v_pk_mul_f32 v[132:133], v[128:129], v[142:143] op_sel_hi:[0,1]
	v_pk_fma_f32 v[46:47], v[72:73], v[46:47], v[132:133] op_sel_hi:[0,1,1]
	v_pk_mul_f32 v[132:133], v[128:129], v[144:145] op_sel_hi:[0,1]
	v_pk_fma_f32 v[48:49], v[72:73], v[48:49], v[132:133] op_sel_hi:[0,1,1]
	ds_read_b128 v[132:135], v111 offset:672
	s_waitcnt lgkmcnt(1)
	v_pk_fma_f32 v[120:121], v[120:121], v[46:47], v[136:137]
	s_waitcnt lgkmcnt(0)
	v_pk_mul_f32 v[132:133], v[128:129], v[132:133] op_sel_hi:[0,1]
	v_pk_fma_f32 v[136:137], v[122:123], v[48:49], v[120:121]
	ds_read_b128 v[120:123], v111 offset:2720
	ds_read_b128 v[142:145], v111 offset:688
	v_pk_fma_f32 v[50:51], v[72:73], v[50:51], v[132:133] op_sel_hi:[0,1,1]
	v_pk_mul_f32 v[132:133], v[128:129], v[134:135] op_sel_hi:[0,1]
	v_pk_fma_f32 v[52:53], v[72:73], v[52:53], v[132:133] op_sel_hi:[0,1,1]
	ds_read_b128 v[132:135], v111 offset:2736
	s_waitcnt lgkmcnt(2)
	v_pk_fma_f32 v[120:121], v[120:121], v[50:51], v[136:137]
	s_nop 0
	v_pk_fma_f32 v[136:137], v[122:123], v[52:53], v[120:121]
	s_waitcnt lgkmcnt(1)
	v_pk_mul_f32 v[120:121], v[128:129], v[142:143] op_sel_hi:[0,1]
	v_pk_fma_f32 v[54:55], v[72:73], v[54:55], v[120:121] op_sel_hi:[0,1,1]
	v_pk_mul_f32 v[120:121], v[128:129], v[144:145] op_sel_hi:[0,1]
	v_pk_fma_f32 v[56:57], v[72:73], v[56:57], v[120:121] op_sel_hi:[0,1,1]
	ds_read_b128 v[120:123], v111 offset:704
	s_waitcnt lgkmcnt(1)
	v_pk_fma_f32 v[132:133], v[132:133], v[54:55], v[136:137]
	s_waitcnt lgkmcnt(0)
	v_pk_mul_f32 v[120:121], v[128:129], v[120:121] op_sel_hi:[0,1]
	v_pk_fma_f32 v[136:137], v[134:135], v[56:57], v[132:133]
	ds_read_b128 v[132:135], v111 offset:2752
	ds_read_b128 v[142:145], v111 offset:720
	v_pk_fma_f32 v[58:59], v[72:73], v[58:59], v[120:121] op_sel_hi:[0,1,1]
	v_pk_mul_f32 v[120:121], v[128:129], v[122:123] op_sel_hi:[0,1]
	v_pk_fma_f32 v[60:61], v[72:73], v[60:61], v[120:121] op_sel_hi:[0,1,1]
	s_waitcnt lgkmcnt(1)
	v_pk_fma_f32 v[132:133], v[132:133], v[58:59], v[136:137]
	ds_read_b128 v[120:123], v111 offset:2768
	v_pk_fma_f32 v[136:137], v[134:135], v[60:61], v[132:133]
	s_waitcnt lgkmcnt(1)
	v_pk_mul_f32 v[132:133], v[128:129], v[142:143] op_sel_hi:[0,1]
	v_pk_fma_f32 v[62:63], v[72:73], v[62:63], v[132:133] op_sel_hi:[0,1,1]
	v_pk_mul_f32 v[132:133], v[128:129], v[144:145] op_sel_hi:[0,1]
	v_pk_fma_f32 v[64:65], v[72:73], v[64:65], v[132:133] op_sel_hi:[0,1,1]
	ds_read_b128 v[132:135], v111 offset:736
	s_waitcnt lgkmcnt(1)
	v_pk_fma_f32 v[120:121], v[120:121], v[62:63], v[136:137]
	s_waitcnt lgkmcnt(0)
	v_pk_mul_f32 v[132:133], v[128:129], v[132:133] op_sel_hi:[0,1]
	v_pk_fma_f32 v[136:137], v[122:123], v[64:65], v[120:121]
	ds_read_b128 v[120:123], v111 offset:2784
	ds_read_b128 v[142:145], v111 offset:752
	v_pk_fma_f32 v[66:67], v[72:73], v[66:67], v[132:133] op_sel_hi:[0,1,1]
	v_pk_mul_f32 v[132:133], v[128:129], v[134:135] op_sel_hi:[0,1]
	v_pk_fma_f32 v[68:69], v[72:73], v[68:69], v[132:133] op_sel_hi:[0,1,1]
	ds_read_b128 v[132:135], v111 offset:2800
	s_waitcnt lgkmcnt(2)
	v_pk_fma_f32 v[120:121], v[120:121], v[66:67], v[136:137]
	s_nop 0
	v_pk_fma_f32 v[120:121], v[122:123], v[68:69], v[120:121]
	s_waitcnt lgkmcnt(1)
	v_pk_mul_f32 v[122:123], v[128:129], v[142:143] op_sel_hi:[0,1]
	v_pk_fma_f32 v[70:71], v[72:73], v[70:71], v[122:123] op_sel_hi:[0,1,1]
	v_pk_mul_f32 v[122:123], v[128:129], v[144:145] op_sel_hi:[0,1]
	v_pk_fma_f32 v[8:9], v[72:73], v[8:9], v[122:123] op_sel_hi:[0,1,1]
	s_waitcnt lgkmcnt(0)
	v_pk_fma_f32 v[72:73], v[132:133], v[70:71], v[120:121]
	s_nop 0
	v_pk_fma_f32 v[72:73], v[134:135], v[8:9], v[72:73]
	s_nop 0
	v_add_f32_e32 v73, v72, v73
	s_and_saveexec_b64 s[52:53], s[8:9]
	ds_write_b32 v105, v73 offset:8448
	s_or_b64 exec, exec, s[52:53]
	v_add_f32_e32 v72, 0, v116
	v_add_f32_e32 v72, v72, v117
	v_add_f32_e32 v72, v72, v118
	v_add_f32_e32 v72, v72, v119
	v_mul_f32_e32 v72, 0xbfb8aa3b, v72
	v_exp_f32_e32 v72, v72
	v_mul_f32_e32 v136, v76, v130
	v_fmac_f32_e32 v136, v107, v77
	v_lshlrev_b32_e32 v108, 16, v108
	v_add_f32_e32 v116, 1.0, v72
	v_fmac_f32_e32 v136, v75, v110

; DEV float silu_f(float x) { return x / (1.f + __expf(-x)); }
; DEV void gdn_sample_item(const Params& p, int item, unsigned char* lds) {
;     ...
;             const float y = silu_f(wj[0] * x[t] + wj[1] * x[t + 1] + wj[2] * x[t + 2] + wj[3] * x[t + 3]);
	v_fmac_f32_e32 v136, v74, v108

; DEV float silu_f(float x) { return x / (1.f + __expf(-x)); }
; DEV void gdn_sample_item(const Params& p, int item, unsigned char* lds) {
;     ...
;             const float y = silu_f(wj[0] * x[t] + wj[1] * x[t + 1] + wj[2] * x[t + 2] + wj[3] * x[t + 3]);
;     ...
;         const float xx = a + p.in[12][h];
;         const float sp = xx > 20.f ? xx : log1pf(__expf(xx));
;         gt[t] = __expf(-__expf(p.in[11][h]) * sp);
	v_mul_f32_e32 v107, 0xbfb8aa3b, v136
	v_exp_f32_e32 v107, v107
	v_mul_f32_e32 v109, v126, v127
	v_mul_f32_e32 v109, 0x3fb8aa3b, v109

; DEV void gdn_sample_item(const Params& p, int item, unsigned char* lds) {
;     ...
;         gt[t] = __expf(-__expf(p.in[11][h]) * sp);
	v_exp_f32_e32 v72, v109


; DEV float silu_f(float x) { return x / (1.f + __expf(-x)); }
; DEV void gdn_sample_item(const Params& p, int item, unsigned char* lds) {
;     ...
;             const float y = silu_f(wj[0] * x[t] + wj[1] * x[t + 1] + wj[2] * x[t + 2] + wj[3] * x[t + 3]);
	v_add_f32_e32 v107, 1.0, v107


; DEV void gdn_sample_item(const Params& p, int item, unsigned char* lds) {
;     ...
;         bt[t] = 1.f / (1.f + __expf(-bb));
	v_rcp_f32_e32 v109, v116
	s_nop 0
	v_mul_f32_e32 v109, 1.0, v109


; DEV void gdn_sample_item(const Params& p, int item, unsigned char* lds) {
;     ...
;         const float* kk = ksh + t * 128 + half * 64; const float* qq = qsh + t * 128 + half * 64;
;         f32x2_t ks2 = {0.f, 0.f};
; #pragma unroll
;         for (int d4 = 0; d4 < 16; ++d4) { const f32x4 k4 = *(const f32x4*)(kk + d4 * 4); ks2 += (f32x2_t){k4[0], k4[1]} * S[d4 * 2]; ks2 += (f32x2_t){k4[2], k4[3]} * S[d4 * 2 + 1]; }
	ds_read_b128 v[116:119], v111 offset:1024


; DEV void gdn_sample_item(const Params& p, int item, unsigned char* lds) {
;     ...
;         const float* kk = ksh + t * 128 + half * 64; const float* qq = qsh + t * 128 + half * 64;
;         f32x2_t ks2 = {0.f, 0.f};
; #pragma unroll
;         for (int d4 = 0; d4 < 16; ++d4) { const f32x4 k4 = *(const f32x4*)(kk + d4 * 4); ks2 += (f32x2_t){k4[0], k4[1]} * S[d4 * 2]; ks2 += (f32x2_t){k4[2], k4[3]} * S[d4 * 2 + 1]; }
;         part[(t * 2 + half) * 128 + c] = ks2[0] + ks2[1];
	ds_read_b128 v[120:123], v111 offset:1040
	ds_read_b128 v[126:129], v111 offset:1056
	ds_read_b128 v[132:135], v111 offset:1072
	s_waitcnt lgkmcnt(3)
	v_pk_fma_f32 v[116:117], v[10:11], v[116:117], 0 op_sel_hi:[1,1,0]
	s_nop 0
	v_pk_fma_f32 v[116:117], v[12:13], v[118:119], v[116:117]
	s_waitcnt lgkmcnt(2)
	v_pk_fma_f32 v[116:117], v[14:15], v[120:121], v[116:117]
	s_nop 0
	v_pk_fma_f32 v[116:117], v[16:17], v[122:123], v[116:117]
	s_waitcnt lgkmcnt(1)
	v_pk_fma_f32 v[120:121], v[18:19], v[126:127], v[116:117]
	ds_read_b128 v[116:119], v111 offset:1088
	v_pk_fma_f32 v[120:121], v[20:21], v[128:129], v[120:121]
	s_waitcnt lgkmcnt(1)
	v_pk_fma_f32 v[126:127], v[22:23], v[132:133], v[120:121]
	ds_read_b128 v[120:123], v111 offset:1104
	v_pk_fma_f32 v[126:127], v[24:25], v[134:135], v[126:127]
	s_waitcnt lgkmcnt(1)
	v_pk_fma_f32 v[116:117], v[26:27], v[116:117], v[126:127]
	ds_read_b128 v[126:129], v111 offset:1120
	v_pk_fma_f32 v[116:117], v[28:29], v[118:119], v[116:117]
	s_waitcnt lgkmcnt(1)
	v_pk_fma_f32 v[120:121], v[30:31], v[120:121], v[116:117]
	ds_read_b128 v[116:119], v111 offset:1136
	v_pk_fma_f32 v[120:121], v[32:33], v[122:123], v[120:121]
	s_waitcnt lgkmcnt(1)
	v_pk_fma_f32 v[126:127], v[34:35], v[126:127], v[120:121]
	ds_read_b128 v[120:123], v111 offset:1152
	v_pk_fma_f32 v[126:127], v[36:37], v[128:129], v[126:127]
	s_waitcnt lgkmcnt(1)
	v_pk_fma_f32 v[116:117], v[38:39], v[116:117], v[126:127]
	ds_read_b128 v[126:129], v111 offset:1168
	v_pk_fma_f32 v[116:117], v[40:41], v[118:119], v[116:117]
	s_waitcnt lgkmcnt(1)
	v_pk_fma_f32 v[120:121], v[42:43], v[120:121], v[116:117]
	ds_read_b128 v[116:119], v111 offset:1184
	v_pk_fma_f32 v[120:121], v[44:45], v[122:123], v[120:121]
	s_waitcnt lgkmcnt(1)
	v_pk_fma_f32 v[126:127], v[46:47], v[126:127], v[120:121]
	ds_read_b128 v[120:123], v111 offset:1200
	v_pk_fma_f32 v[126:127], v[48:49], v[128:129], v[126:127]
	s_waitcnt lgkmcnt(1)
	v_pk_fma_f32 v[116:117], v[50:51], v[116:117], v[126:127]
	ds_read_b128 v[126:129], v111 offset:1216
	v_pk_fma_f32 v[116:117], v[52:53], v[118:119], v[116:117]
	s_waitcnt lgkmcnt(1)
	v_pk_fma_f32 v[116:117], v[54:55], v[120:121], v[116:117]
	s_nop 0
	v_pk_fma_f32 v[120:121], v[56:57], v[122:123], v[116:117]
	ds_read_b128 v[116:119], v111 offset:1232
	s_waitcnt lgkmcnt(1)
	v_pk_fma_f32 v[126:127], v[58:59], v[126:127], v[120:121]
	ds_read_b128 v[120:123], v111 offset:1248
	v_pk_fma_f32 v[132:133], v[60:61], v[128:129], v[126:127]
	ds_read_b128 v[126:129], v111 offset:1264
	s_waitcnt lgkmcnt(2)
	v_pk_fma_f32 v[116:117], v[62:63], v[116:117], v[132:133]
	s_nop 0
	v_pk_fma_f32 v[116:117], v[64:65], v[118:119], v[116:117]

; DEV void gdn_sample_item(const Params& p, int item, unsigned char* lds) {
;     ...
;         for (int d4 = 0; d4 < 16; ++d4) { const f32x4 k4 = *(const f32x4*)(kk + d4 * 4); ks2 += (f32x2_t){k4[0], k4[1]} * S[d4 * 2]; ks2 += (f32x2_t){k4[2], k4[3]} * S[d4 * 2 + 1]; }
	s_waitcnt lgkmcnt(1)
	v_pk_fma_f32 v[116:117], v[66:67], v[120:121], v[116:117]

; DEV float silu_f(float x) { return x / (1.f + __expf(-x)); }
; DEV void gdn_sample_item(const Params& p, int item, unsigned char* lds) {
;     ...
;             const float y = silu_f(wj[0] * x[t] + wj[1] * x[t + 1] + wj[2] * x[t + 2] + wj[3] * x[t + 3]);
;     ...
;         part[(t * 2 + half) * 128 + c] = ks2[0] + ks2[1];
;         __syncthreads();
;         const float kS = part[(t * 2) * 128 + c] + part[(t * 2 + 1) * 128 + c];
;         const float eg = gt[t], dl = bt[t] * (vv[t] - eg * kS);
;         const f32x2_t eg2 = {eg, eg}, dl2 = {dl, dl};
;         f32x2_t o2 = {0.f, 0.f};
; #pragma unroll
;         for (int d4 = 0; d4 < 16; ++d4) {
;             const f32x4 k4 = *(const f32x4*)(kk + d4 * 4), q4 = *(const f32x4*)(qq + d4 * 4);
;             const f32x2_t s0 = S[d4 * 2] * eg2 + (f32x2_t){k4[0], k4[1]} * dl2, s1 = S[d4 * 2 + 1] * eg2 + (f32x2_t){k4[2], k4[3]} * dl2;
;             S[d4 * 2] = s0; S[d4 * 2 + 1] = s1;
;             o2 += (f32x2_t){q4[0], q4[1]} * s0; o2 += (f32x2_t){q4[2], q4[3]} * s1;
;         }
	v_pk_fma_f32 v[116:117], v[68:69], v[122:123], v[116:117]
	v_rcp_f32_e32 v118, v107
	s_nop 0
	v_mul_f32_e32 v107, v136, v118
	s_waitcnt lgkmcnt(0)
	v_pk_fma_f32 v[116:117], v[70:71], v[126:127], v[116:117]
	s_nop 0
	v_pk_fma_f32 v[116:117], v[8:9], v[128:129], v[116:117]
	s_nop 0
	v_add_f32_e32 v116, v116, v117
	ds_write_b32 v105, v116 offset:6400
	s_waitcnt lgkmcnt(0)
	s_barrier
	ds_read2st64_b32 v[116:117], v131 offset0:25 offset1:27
	s_waitcnt lgkmcnt(0)
	v_add_f32_e32 v116, v116, v117
	v_fma_f32 v107, -v72, v116, v107
	v_mul_f32_e32 v136, v109, v107
	ds_read_b128 v[116:119], v111 offset:1024
	ds_read_b128 v[120:123], v111 offset:1040
	ds_read_b128 v[126:129], v111 offset:1056
	ds_read_b128 v[132:135], v111 offset:1072
	ds_read_b128 v[142:145], v111 offset:3072
	s_waitcnt lgkmcnt(4)
	v_pk_mul_f32 v[116:117], v[116:117], v[136:137] op_sel_hi:[1,0]
	s_waitcnt lgkmcnt(3)
	v_pk_mul_f32 v[120:121], v[120:121], v[136:137] op_sel_hi:[1,0]
	v_pk_fma_f32 v[10:11], v[72:73], v[10:11], v[116:117] op_sel_hi:[0,1,1]
	v_pk_mul_f32 v[116:117], v[118:119], v[136:137] op_sel_hi:[1,0]
	s_waitcnt lgkmcnt(0)
	v_pk_fma_f32 v[142:143], v[142:143], v[10:11], 0 op_sel_hi:[1,1,0]
	v_pk_fma_f32 v[12:13], v[72:73], v[12:13], v[116:117] op_sel_hi:[0,1,1]
	ds_read_b128 v[116:119], v111 offset:3088
	v_pk_fma_f32 v[142:143], v[144:145], v[12:13], v[142:143]
	v_pk_fma_f32 v[14:15], v[72:73], v[14:15], v[120:121] op_sel_hi:[0,1,1]
	v_pk_mul_f32 v[120:121], v[122:123], v[136:137] op_sel_hi:[1,0]
	s_waitcnt lgkmcnt(0)
	v_pk_fma_f32 v[116:117], v[116:117], v[14:15], v[142:143]
	v_pk_fma_f32 v[16:17], v[72:73], v[16:17], v[120:121] op_sel_hi:[0,1,1]
	v_pk_fma_f32 v[142:143], v[118:119], v[16:17], v[116:117]
	ds_read_b128 v[116:119], v111 offset:3104
	v_pk_mul_f32 v[120:121], v[136:137], v[126:127] op_sel_hi:[0,1]
	v_pk_fma_f32 v[18:19], v[72:73], v[18:19], v[120:121] op_sel_hi:[0,1,1]
	v_pk_mul_f32 v[120:121], v[136:137], v[128:129] op_sel_hi:[0,1]
	v_pk_fma_f32 v[20:21], v[72:73], v[20:21], v[120:121] op_sel_hi:[0,1,1]
	ds_read_b128 v[120:123], v111 offset:3120
	s_waitcnt lgkmcnt(1)
	v_pk_fma_f32 v[116:117], v[116:117], v[18:19], v[142:143]
	s_nop 0
	v_pk_fma_f32 v[126:127], v[118:119], v[20:21], v[116:117]
	v_pk_mul_f32 v[116:117], v[136:137], v[132:133] op_sel_hi:[0,1]
	v_pk_fma_f32 v[22:23], v[72:73], v[22:23], v[116:117] op_sel_hi:[0,1,1]
	v_pk_mul_f32 v[116:117], v[136:137], v[134:135] op_sel_hi:[0,1]
	v_pk_fma_f32 v[24:25], v[72:73], v[24:25], v[116:117] op_sel_hi:[0,1,1]
	ds_read_b128 v[116:119], v111 offset:1088
	s_waitcnt lgkmcnt(1)
	v_pk_fma_f32 v[120:121], v[120:121], v[22:23], v[126:127]
	s_waitcnt lgkmcnt(0)
	v_pk_mul_f32 v[116:117], v[136:137], v[116:117] op_sel_hi:[0,1]
	v_pk_fma_f32 v[132:133], v[122:123], v[24:25], v[120:121]
	ds_read_b128 v[120:123], v111 offset:3136
	ds_read_b128 v[126:129], v111 offset:1104
	v_pk_fma_f32 v[26:27], v[72:73], v[26:27], v[116:117] op_sel_hi:[0,1,1]
	v_pk_mul_f32 v[116:117], v[136:137], v[118:119] op_sel_hi:[0,1]
	v_pk_fma_f32 v[28:29], v[72:73], v[28:29], v[116:117] op_sel_hi:[0,1,1]
	ds_read_b128 v[116:119], v111 offset:3152
	s_waitcnt lgkmcnt(2)
	v_pk_fma_f32 v[120:121], v[120:121], v[26:27], v[132:133]
	s_nop 0
	v_pk_fma_f32 v[132:133], v[122:123], v[28:29], v[120:121]
	s_waitcnt lgkmcnt(1)
	v_pk_mul_f32 v[120:121], v[136:137], v[126:127] op_sel_hi:[0,1]
	v_pk_fma_f32 v[30:31], v[72:73], v[30:31], v[120:121] op_sel_hi:[0,1,1]
	v_pk_mul_f32 v[120:121], v[136:137], v[128:129] op_sel_hi:[0,1]
	v_pk_fma_f32 v[32:33], v[72:73], v[32:33], v[120:121] op_sel_hi:[0,1,1]
	ds_read_b128 v[120:123], v111 offset:1120
	s_waitcnt lgkmcnt(1)
	v_pk_fma_f32 v[116:117], v[116:117], v[30:31], v[132:133]
	s_waitcnt lgkmcnt(0)
	v_pk_mul_f32 v[120:121], v[136:137], v[120:121] op_sel_hi:[0,1]
	v_pk_fma_f32 v[132:133], v[118:119], v[32:33], v[116:117]
	ds_read_b128 v[116:119], v111 offset:3168
	ds_read_b128 v[126:129], v111 offset:1136
	v_pk_fma_f32 v[34:35], v[72:73], v[34:35], v[120:121] op_sel_hi:[0,1,1]
	v_pk_mul_f32 v[120:121], v[136:137], v[122:123] op_sel_hi:[0,1]
	v_pk_fma_f32 v[36:37], v[72:73], v[36:37], v[120:121] op_sel_hi:[0,1,1]
	ds_read_b128 v[120:123], v111 offset:3184
	s_waitcnt lgkmcnt(2)
	v_pk_fma_f32 v[116:117], v[116:117], v[34:35], v[132:133]
	s_nop 0
	v_pk_fma_f32 v[132:133], v[118:119], v[36:37], v[116:117]
	s_waitcnt lgkmcnt(1)
	v_pk_mul_f32 v[116:117], v[136:137], v[126:127] op_sel_hi:[0,1]
	v_pk_fma_f32 v[38:39], v[72:73], v[38:39], v[116:117] op_sel_hi:[0,1,1]
	v_pk_mul_f32 v[116:117], v[136:137], v[128:129] op_sel_hi:[0,1]
	v_pk_fma_f32 v[40:41], v[72:73], v[40:41], v[116:117] op_sel_hi:[0,1,1]
	ds_read_b128 v[116:119], v111 offset:1152
	s_waitcnt lgkmcnt(1)
	v_pk_fma_f32 v[120:121], v[120:121], v[38:39], v[132:133]
	s_waitcnt lgkmcnt(0)
; DEV void gdn_sample_item(const Params& p, int item, unsigned char* lds) {
;     ...
;         float a = 0.f, bb = 0.f;
; #pragma unroll
;         for (int kq = 0; kq < 4; ++kq) { a += ab[(size_t)kq * TT * 16 + (size_t)(r0 + t) * 16 + h]; bb += ab[(size_t)kq * TT * 16 + (size_t)(r0 + t) * 16 + 8 + h]; }
;         const float xx = a + p.in[12][h];
;         const float sp = xx > 20.f ? xx : log1pf(__expf(xx));
;         gt[t] = __expf(-__expf(p.in[11][h]) * sp);
;         bt[t] = 1.f / (1.f + __expf(-bb));
;     ...
;         for (int d4 = 0; d4 < 16; ++d4) {
;             const f32x4 k4 = *(const f32x4*)(kk + d4 * 4), q4 = *(const f32x4*)(qq + d4 * 4);
;             const f32x2_t s0 = S[d4 * 2] * eg2 + (f32x2_t){k4[0], k4[1]} * dl2, s1 = S[d4 * 2 + 1] * eg2 + (f32x2_t){k4[2], k4[3]} * dl2;
;             S[d4 * 2] = s0; S[d4 * 2 + 1] = s1;
;             o2 += (f32x2_t){q4[0], q4[1]} * s0; o2 += (f32x2_t){q4[2], q4[3]} * s1;
;         }
;         const float o = o2[0] + o2[1];
;         ot[t] = o;
;         if (half == 1) opart[t * 128 + c] = o;
	v_pk_mul_f32 v[116:117], v[136:137], v[116:117] op_sel_hi:[0,1]
	v_pk_fma_f32 v[132:133], v[122:123], v[40:41], v[120:121]
	ds_read_b128 v[120:123], v111 offset:3200
	ds_read_b128 v[126:129], v111 offset:1168
	v_pk_fma_f32 v[42:43], v[72:73], v[42:43], v[116:117] op_sel_hi:[0,1,1]
	v_pk_mul_f32 v[116:117], v[136:137], v[118:119] op_sel_hi:[0,1]
	v_pk_fma_f32 v[44:45], v[72:73], v[44:45], v[116:117] op_sel_hi:[0,1,1]
	ds_read_b128 v[116:119], v111 offset:3216
	s_waitcnt lgkmcnt(2)
	v_pk_fma_f32 v[120:121], v[120:121], v[42:43], v[132:133]
	s_nop 0
	v_pk_fma_f32 v[132:133], v[122:123], v[44:45], v[120:121]
	s_waitcnt lgkmcnt(1)
	v_pk_mul_f32 v[120:121], v[136:137], v[126:127] op_sel_hi:[0,1]
	v_pk_fma_f32 v[46:47], v[72:73], v[46:47], v[120:121] op_sel_hi:[0,1,1]
	v_pk_mul_f32 v[120:121], v[136:137], v[128:129] op_sel_hi:[0,1]
	v_pk_fma_f32 v[48:49], v[72:73], v[48:49], v[120:121] op_sel_hi:[0,1,1]
	ds_read_b128 v[120:123], v111 offset:1184
	s_waitcnt lgkmcnt(1)
	v_pk_fma_f32 v[116:117], v[116:117], v[46:47], v[132:133]
	s_waitcnt lgkmcnt(0)
	v_pk_mul_f32 v[120:121], v[136:137], v[120:121] op_sel_hi:[0,1]
	v_pk_fma_f32 v[132:133], v[118:119], v[48:49], v[116:117]
	ds_read_b128 v[116:119], v111 offset:3232
	ds_read_b128 v[126:129], v111 offset:1200
	v_pk_fma_f32 v[50:51], v[72:73], v[50:51], v[120:121] op_sel_hi:[0,1,1]
	v_pk_mul_f32 v[120:121], v[136:137], v[122:123] op_sel_hi:[0,1]
	v_pk_fma_f32 v[52:53], v[72:73], v[52:53], v[120:121] op_sel_hi:[0,1,1]
	ds_read_b128 v[120:123], v111 offset:3248
	s_waitcnt lgkmcnt(2)
	v_pk_fma_f32 v[116:117], v[116:117], v[50:51], v[132:133]
	s_nop 0
	v_pk_fma_f32 v[132:133], v[118:119], v[52:53], v[116:117]
	s_waitcnt lgkmcnt(1)
	v_pk_mul_f32 v[116:117], v[136:137], v[126:127] op_sel_hi:[0,1]
	v_pk_fma_f32 v[54:55], v[72:73], v[54:55], v[116:117] op_sel_hi:[0,1,1]
	v_pk_mul_f32 v[116:117], v[136:137], v[128:129] op_sel_hi:[0,1]
	v_pk_fma_f32 v[56:57], v[72:73], v[56:57], v[116:117] op_sel_hi:[0,1,1]
	ds_read_b128 v[116:119], v111 offset:1216
	s_waitcnt lgkmcnt(1)
	v_pk_fma_f32 v[120:121], v[120:121], v[54:55], v[132:133]
	s_waitcnt lgkmcnt(0)
	v_pk_mul_f32 v[116:117], v[136:137], v[116:117] op_sel_hi:[0,1]
	v_pk_fma_f32 v[132:133], v[122:123], v[56:57], v[120:121]
	ds_read_b128 v[120:123], v111 offset:3264
	ds_read_b128 v[126:129], v111 offset:1232
	v_pk_fma_f32 v[58:59], v[72:73], v[58:59], v[116:117] op_sel_hi:[0,1,1]
	v_pk_mul_f32 v[116:117], v[136:137], v[118:119] op_sel_hi:[0,1]
	v_pk_fma_f32 v[60:61], v[72:73], v[60:61], v[116:117] op_sel_hi:[0,1,1]
	s_waitcnt lgkmcnt(1)
	v_pk_fma_f32 v[120:121], v[120:121], v[58:59], v[132:133]
	ds_read_b128 v[116:119], v111 offset:3280
	v_pk_fma_f32 v[132:133], v[122:123], v[60:61], v[120:121]
	s_waitcnt lgkmcnt(1)
	v_pk_mul_f32 v[120:121], v[136:137], v[126:127] op_sel_hi:[0,1]
	v_pk_fma_f32 v[62:63], v[72:73], v[62:63], v[120:121] op_sel_hi:[0,1,1]
	v_pk_mul_f32 v[120:121], v[136:137], v[128:129] op_sel_hi:[0,1]
	v_pk_fma_f32 v[64:65], v[72:73], v[64:65], v[120:121] op_sel_hi:[0,1,1]
	ds_read_b128 v[120:123], v111 offset:1248
	s_waitcnt lgkmcnt(1)
	v_pk_fma_f32 v[116:117], v[116:117], v[62:63], v[132:133]
	s_waitcnt lgkmcnt(0)
	v_pk_mul_f32 v[120:121], v[136:137], v[120:121] op_sel_hi:[0,1]
	v_pk_fma_f32 v[132:133], v[118:119], v[64:65], v[116:117]
	ds_read_b128 v[116:119], v111 offset:3296
	ds_read_b128 v[126:129], v111 offset:1264
	v_pk_fma_f32 v[66:67], v[72:73], v[66:67], v[120:121] op_sel_hi:[0,1,1]
	v_pk_mul_f32 v[120:121], v[136:137], v[122:123] op_sel_hi:[0,1]
	v_pk_fma_f32 v[68:69], v[72:73], v[68:69], v[120:121] op_sel_hi:[0,1,1]
	ds_read_b128 v[120:123], v111 offset:3312
	s_waitcnt lgkmcnt(2)
	v_pk_fma_f32 v[116:117], v[116:117], v[66:67], v[132:133]
	s_nop 0
	v_pk_fma_f32 v[116:117], v[118:119], v[68:69], v[116:117]
	s_waitcnt lgkmcnt(1)
	v_pk_mul_f32 v[118:119], v[136:137], v[126:127] op_sel_hi:[0,1]
	v_pk_fma_f32 v[70:71], v[72:73], v[70:71], v[118:119] op_sel_hi:[0,1,1]
	v_pk_mul_f32 v[118:119], v[136:137], v[128:129] op_sel_hi:[0,1]
	v_pk_fma_f32 v[8:9], v[72:73], v[8:9], v[118:119] op_sel_hi:[0,1,1]
	s_waitcnt lgkmcnt(0)
	v_pk_fma_f32 v[116:117], v[120:121], v[70:71], v[116:117]
	s_nop 0
	v_pk_fma_f32 v[116:117], v[122:123], v[8:9], v[116:117]
	s_nop 0
	v_add_f32_e32 v107, v116, v117
	s_and_saveexec_b64 s[52:53], s[8:9]
	ds_write_b32 v131, v107 offset:9472
	s_or_b64 exec, exec, s[52:53]
	v_add_f32_e32 v72, 0, v112
	v_add_f32_e32 v72, v72, v113
	v_add_f32_e32 v72, v72, v114
	v_add_f32_e32 v72, v72, v115
	v_mul_f32_e32 v72, 0xbfb8aa3b, v72
	v_exp_f32_e32 v72, v72
	v_mul_f32_e32 v110, v76, v110
	v_fmac_f32_e32 v110, v77, v130
	v_lshlrev_b32_e32 v106, 16, v106
	v_add_f32_e32 v112, 1.0, v72
	v_fmac_f32_e32 v110, v75, v108

; DEV float silu_f(float x) { return x / (1.f + __expf(-x)); }
; DEV void gdn_sample_item(const Params& p, int item, unsigned char* lds) {
;     ...
;             const float y = silu_f(wj[0] * x[t] + wj[1] * x[t + 1] + wj[2] * x[t + 2] + wj[3] * x[t + 3]);
	v_fmac_f32_e32 v110, v74, v106

; DEV float silu_f(float x) { return x / (1.f + __expf(-x)); }
; DEV void gdn_sample_item(const Params& p, int item, unsigned char* lds) {
;     ...
;             const float y = silu_f(wj[0] * x[t] + wj[1] * x[t + 1] + wj[2] * x[t + 2] + wj[3] * x[t + 3]);
;     ...
;         const float xx = a + p.in[12][h];
;         const float sp = xx > 20.f ? xx : log1pf(__expf(xx));
;         gt[t] = __expf(-__expf(p.in[11][h]) * sp);
	v_mul_f32_e32 v74, 0xbfb8aa3b, v110
	v_exp_f32_e32 v74, v74
	v_mul_f32_e32 v109, v124, v125
	v_mul_f32_e32 v109, 0x3fb8aa3b, v109

; DEV void gdn_sample_item(const Params& p, int item, unsigned char* lds) {
;     ...
;         gt[t] = __expf(-__expf(p.in[11][h]) * sp);
	v_exp_f32_e32 v72, v109


; DEV float silu_f(float x) { return x / (1.f + __expf(-x)); }
; DEV void gdn_sample_item(const Params& p, int item, unsigned char* lds) {
;     ...
;             const float y = silu_f(wj[0] * x[t] + wj[1] * x[t + 1] + wj[2] * x[t + 2] + wj[3] * x[t + 3]);
	v_add_f32_e32 v106, 1.0, v74


; DEV void gdn_sample_item(const Params& p, int item, unsigned char* lds) {
;     ...
;         bt[t] = 1.f / (1.f + __expf(-bb));
	v_rcp_f32_e32 v74, v112
	s_nop 0
	v_mul_f32_e32 v126, 1.0, v74


; DEV void gdn_sample_item(const Params& p, int item, unsigned char* lds) {
;     ...
;         const float* kk = ksh + t * 128 + half * 64; const float* qq = qsh + t * 128 + half * 64;
;         f32x2_t ks2 = {0.f, 0.f};
; #pragma unroll
;         for (int d4 = 0; d4 < 16; ++d4) { const f32x4 k4 = *(const f32x4*)(kk + d4 * 4); ks2 += (f32x2_t){k4[0], k4[1]} * S[d4 * 2]; ks2 += (f32x2_t){k4[2], k4[3]} * S[d4 * 2 + 1]; }
	ds_read_b128 v[74:77], v111 offset:1536
	ds_read_b128 v[112:115], v111 offset:1552
	ds_read_b128 v[116:119], v111 offset:1568
	ds_read_b128 v[120:123], v111 offset:1584


; DEV void gdn_sample_item(const Params& p, int item, unsigned char* lds) {
;     ...
;         for (int d4 = 0; d4 < 16; ++d4) { const f32x4 k4 = *(const f32x4*)(kk + d4 * 4); ks2 += (f32x2_t){k4[0], k4[1]} * S[d4 * 2]; ks2 += (f32x2_t){k4[2], k4[3]} * S[d4 * 2 + 1]; }
	s_waitcnt lgkmcnt(3)
	v_pk_fma_f32 v[74:75], v[10:11], v[74:75], 0 op_sel_hi:[1,1,0]

; DEV void gdn_sample_item(const Params& p, int item, unsigned char* lds) {
;     ...
;         for (int d4 = 0; d4 < 16; ++d4) { const f32x4 k4 = *(const f32x4*)(kk + d4 * 4); ks2 += (f32x2_t){k4[0], k4[1]} * S[d4 * 2]; ks2 += (f32x2_t){k4[2], k4[3]} * S[d4 * 2 + 1]; }
	v_pk_fma_f32 v[74:75], v[12:13], v[76:77], v[74:75]

; DEV void gdn_sample_item(const Params& p, int item, unsigned char* lds) {
;     ...
;         const float* kk = ksh + t * 128 + half * 64; const float* qq = qsh + t * 128 + half * 64;
;         f32x2_t ks2 = {0.f, 0.f};
; #pragma unroll
;         for (int d4 = 0; d4 < 16; ++d4) { const f32x4 k4 = *(const f32x4*)(kk + d4 * 4); ks2 += (f32x2_t){k4[0], k4[1]} * S[d4 * 2]; ks2 += (f32x2_t){k4[2], k4[3]} * S[d4 * 2 + 1]; }
;         part[(t * 2 + half) * 128 + c] = ks2[0] + ks2[1];
	s_waitcnt lgkmcnt(2)
	v_pk_fma_f32 v[74:75], v[14:15], v[112:113], v[74:75]
	s_nop 0
	v_pk_fma_f32 v[74:75], v[16:17], v[114:115], v[74:75]
	ds_read_b128 v[112:115], v111 offset:1616
	s_waitcnt lgkmcnt(2)
	v_pk_fma_f32 v[108:109], v[18:19], v[116:117], v[74:75]
	ds_read_b128 v[74:77], v111 offset:1600
	v_pk_fma_f32 v[108:109], v[20:21], v[118:119], v[108:109]
	ds_read_b128 v[116:119], v111 offset:1632
	s_waitcnt lgkmcnt(3)
	v_pk_fma_f32 v[108:109], v[22:23], v[120:121], v[108:109]
	s_nop 0
	v_pk_fma_f32 v[108:109], v[24:25], v[122:123], v[108:109]
	s_waitcnt lgkmcnt(1)
	v_pk_fma_f32 v[74:75], v[26:27], v[74:75], v[108:109]
	s_nop 0
	v_pk_fma_f32 v[74:75], v[28:29], v[76:77], v[74:75]
	s_nop 0
	v_pk_fma_f32 v[108:109], v[30:31], v[112:113], v[74:75]
	ds_read_b128 v[74:77], v111 offset:1648
	v_pk_fma_f32 v[108:109], v[32:33], v[114:115], v[108:109]
	ds_read_b128 v[112:115], v111 offset:1664
	s_waitcnt lgkmcnt(2)
	v_pk_fma_f32 v[108:109], v[34:35], v[116:117], v[108:109]
	s_nop 0
	v_pk_fma_f32 v[108:109], v[36:37], v[118:119], v[108:109]
	ds_read_b128 v[116:119], v111 offset:1680
	s_waitcnt lgkmcnt(2)
	v_pk_fma_f32 v[74:75], v[38:39], v[74:75], v[108:109]
	s_nop 0
	v_pk_fma_f32 v[74:75], v[40:41], v[76:77], v[74:75]
	s_waitcnt lgkmcnt(1)
	v_pk_fma_f32 v[108:109], v[42:43], v[112:113], v[74:75]
	ds_read_b128 v[74:77], v111 offset:1696
	v_pk_fma_f32 v[108:109], v[44:45], v[114:115], v[108:109]
	ds_read_b128 v[112:115], v111 offset:1712
	s_waitcnt lgkmcnt(2)
	v_pk_fma_f32 v[108:109], v[46:47], v[116:117], v[108:109]
	s_nop 0
	v_pk_fma_f32 v[108:109], v[48:49], v[118:119], v[108:109]
	ds_read_b128 v[116:119], v111 offset:1728
	s_waitcnt lgkmcnt(2)
	v_pk_fma_f32 v[74:75], v[50:51], v[74:75], v[108:109]
	s_nop 0
	v_pk_fma_f32 v[74:75], v[52:53], v[76:77], v[74:75]
	s_waitcnt lgkmcnt(1)
	v_pk_fma_f32 v[74:75], v[54:55], v[112:113], v[74:75]
	s_nop 0
	v_pk_fma_f32 v[108:109], v[56:57], v[114:115], v[74:75]
	ds_read_b128 v[74:77], v111 offset:1744
	ds_read_b128 v[112:115], v111 offset:1760
	s_waitcnt lgkmcnt(2)
	v_pk_fma_f32 v[108:109], v[58:59], v[116:117], v[108:109]
	s_nop 0
	v_pk_fma_f32 v[108:109], v[60:61], v[118:119], v[108:109]
	ds_read_b128 v[116:119], v111 offset:1776
	s_waitcnt lgkmcnt(2)
	v_pk_fma_f32 v[74:75], v[62:63], v[74:75], v[108:109]
	s_nop 0
	v_pk_fma_f32 v[74:75], v[64:65], v[76:77], v[74:75]

; DEV void gdn_sample_item(const Params& p, int item, unsigned char* lds) {
;     ...
;         for (int d4 = 0; d4 < 16; ++d4) { const f32x4 k4 = *(const f32x4*)(kk + d4 * 4); ks2 += (f32x2_t){k4[0], k4[1]} * S[d4 * 2]; ks2 += (f32x2_t){k4[2], k4[3]} * S[d4 * 2 + 1]; }
	s_waitcnt lgkmcnt(1)
	v_pk_fma_f32 v[74:75], v[66:67], v[112:113], v[74:75]

; DEV float silu_f(float x) { return x / (1.f + __expf(-x)); }
; DEV void gdn_sample_item(const Params& p, int item, unsigned char* lds) {
;     ...
;             const float y = silu_f(wj[0] * x[t] + wj[1] * x[t + 1] + wj[2] * x[t + 2] + wj[3] * x[t + 3]);
;     ...
;         part[(t * 2 + half) * 128 + c] = ks2[0] + ks2[1];
;         __syncthreads();
;         const float kS = part[(t * 2) * 128 + c] + part[(t * 2 + 1) * 128 + c];
;         const float eg = gt[t], dl = bt[t] * (vv[t] - eg * kS);
;         const f32x2_t eg2 = {eg, eg}, dl2 = {dl, dl};
;         f32x2_t o2 = {0.f, 0.f};
; #pragma unroll
;         for (int d4 = 0; d4 < 16; ++d4) {
;             const f32x4 k4 = *(const f32x4*)(kk + d4 * 4), q4 = *(const f32x4*)(qq + d4 * 4);
;             const f32x2_t s0 = S[d4 * 2] * eg2 + (f32x2_t){k4[0], k4[1]} * dl2, s1 = S[d4 * 2 + 1] * eg2 + (f32x2_t){k4[2], k4[3]} * dl2;
;             S[d4 * 2] = s0; S[d4 * 2 + 1] = s1;
;             o2 += (f32x2_t){q4[0], q4[1]} * s0; o2 += (f32x2_t){q4[2], q4[3]} * s1;
;         }
	v_pk_fma_f32 v[74:75], v[68:69], v[114:115], v[74:75]
	v_rcp_f32_e32 v76, v106
	s_nop 0
	v_mul_f32_e32 v76, v110, v76
	s_waitcnt lgkmcnt(0)
	v_pk_fma_f32 v[74:75], v[70:71], v[116:117], v[74:75]
	s_nop 0
	v_pk_fma_f32 v[74:75], v[8:9], v[118:119], v[74:75]
	s_nop 0
	v_add_f32_e32 v74, v74, v75
	ds_write_b32 v105, v74 offset:7424
	s_waitcnt lgkmcnt(0)
	s_barrier
	ds_read2st64_b32 v[74:75], v131 offset0:29 offset1:31
	s_waitcnt lgkmcnt(0)
	v_add_f32_e32 v74, v74, v75
	v_fma_f32 v74, -v72, v74, v76
	v_mul_f32_e32 v106, v126, v74
	ds_read_b128 v[74:77], v111 offset:1536
	ds_read_b128 v[112:115], v111 offset:1552
	ds_read_b128 v[116:119], v111 offset:1568
	ds_read_b128 v[120:123], v111 offset:1584
	ds_read_b128 v[124:127], v111 offset:3584
	s_waitcnt lgkmcnt(4)
	v_pk_mul_f32 v[74:75], v[74:75], v[106:107] op_sel_hi:[1,0]
	ds_read_b128 v[128:131], v111 offset:3600
	v_pk_fma_f32 v[10:11], v[72:73], v[10:11], v[74:75] op_sel_hi:[0,1,1]
	v_pk_mul_f32 v[74:75], v[76:77], v[106:107] op_sel_hi:[1,0]
	s_nop 0
	v_pk_fma_f32 v[12:13], v[72:73], v[12:13], v[74:75] op_sel_hi:[0,1,1]
	s_waitcnt lgkmcnt(1)
	v_pk_fma_f32 v[74:75], v[124:125], v[10:11], 0 op_sel_hi:[1,1,0]
	s_nop 0
	v_pk_fma_f32 v[108:109], v[126:127], v[12:13], v[74:75]
	v_pk_mul_f32 v[74:75], v[112:113], v[106:107] op_sel_hi:[1,0]
	s_nop 0
	v_pk_fma_f32 v[74:75], v[72:73], v[14:15], v[74:75] op_sel_hi:[0,1,1]
	v_pk_mul_f32 v[14:15], v[114:115], v[106:107] op_sel_hi:[1,0]
	ds_read_b128 v[112:115], v111 offset:3616
	v_pk_fma_f32 v[76:77], v[72:73], v[16:17], v[14:15] op_sel_hi:[0,1,1]
	s_waitcnt lgkmcnt(1)
	v_pk_fma_f32 v[14:15], v[128:129], v[74:75], v[108:109]
	v_pk_mul_f32 v[16:17], v[106:107], v[118:119] op_sel_hi:[0,1]
	v_pk_fma_f32 v[108:109], v[130:131], v[76:77], v[14:15]
	v_pk_mul_f32 v[14:15], v[106:107], v[116:117] op_sel_hi:[0,1]
	v_pk_fma_f32 v[14:15], v[72:73], v[18:19], v[14:15] op_sel_hi:[0,1,1]
	ds_read_b128 v[116:119], v111 offset:3632
	v_pk_fma_f32 v[16:17], v[72:73], v[20:21], v[16:17] op_sel_hi:[0,1,1]
	s_waitcnt lgkmcnt(1)
	v_pk_fma_f32 v[18:19], v[112:113], v[14:15], v[108:109]
	v_pk_mul_f32 v[20:21], v[106:107], v[122:123] op_sel_hi:[0,1]
	v_pk_fma_f32 v[108:109], v[114:115], v[16:17], v[18:19]
	v_pk_mul_f32 v[18:19], v[106:107], v[120:121] op_sel_hi:[0,1]
	v_pk_fma_f32 v[18:19], v[72:73], v[22:23], v[18:19] op_sel_hi:[0,1,1]
	v_pk_fma_f32 v[20:21], v[72:73], v[24:25], v[20:21] op_sel_hi:[0,1,1]
	ds_read_b128 v[22:25], v111 offset:1600
	s_waitcnt lgkmcnt(1)
	v_pk_fma_f32 v[108:109], v[116:117], v[18:19], v[108:109]
	s_waitcnt lgkmcnt(0)
	v_pk_mul_f32 v[22:23], v[106:107], v[22:23] op_sel_hi:[0,1]
	v_pk_fma_f32 v[108:109], v[118:119], v[20:21], v[108:109]
	ds_read_b128 v[112:115], v111 offset:3648
	ds_read_b128 v[116:119], v111 offset:1616
	v_pk_fma_f32 v[22:23], v[72:73], v[26:27], v[22:23] op_sel_hi:[0,1,1]
	v_pk_mul_f32 v[24:25], v[106:107], v[24:25] op_sel_hi:[0,1]
	v_pk_fma_f32 v[24:25], v[72:73], v[28:29], v[24:25] op_sel_hi:[0,1,1]
	s_waitcnt lgkmcnt(1)
	v_pk_fma_f32 v[26:27], v[112:113], v[22:23], v[108:109]
	s_waitcnt lgkmcnt(0)
	v_pk_mul_f32 v[28:29], v[106:107], v[118:119] op_sel_hi:[0,1]
	v_pk_fma_f32 v[108:109], v[114:115], v[24:25], v[26:27]
	v_pk_mul_f32 v[26:27], v[106:107], v[116:117] op_sel_hi:[0,1]
	ds_read_b128 v[120:123], v111 offset:3664
	v_pk_fma_f32 v[26:27], v[72:73], v[30:31], v[26:27] op_sel_hi:[0,1,1]
	v_pk_fma_f32 v[28:29], v[72:73], v[32:33], v[28:29] op_sel_hi:[0,1,1]
	ds_read_b128 v[30:33], v111 offset:1632
	ds_read_b128 v[112:115], v111 offset:3680
	ds_read_b128 v[116:119], v111 offset:1648
	s_waitcnt lgkmcnt(3)
	v_pk_fma_f32 v[108:109], v[120:121], v[26:27], v[108:109]
	s_waitcnt lgkmcnt(2)
	v_pk_mul_f32 v[30:31], v[106:107], v[30:31] op_sel_hi:[0,1]
	v_pk_fma_f32 v[108:109], v[122:123], v[28:29], v[108:109]
	v_pk_fma_f32 v[30:31], v[72:73], v[34:35], v[30:31] op_sel_hi:[0,1,1]
	v_pk_mul_f32 v[32:33], v[106:107], v[32:33] op_sel_hi:[0,1]
	v_pk_fma_f32 v[32:33], v[72:73], v[36:37], v[32:33] op_sel_hi:[0,1,1]
	s_waitcnt lgkmcnt(1)
	v_pk_fma_f32 v[34:35], v[112:113], v[30:31], v[108:109]
	s_waitcnt lgkmcnt(0)
	v_pk_mul_f32 v[36:37], v[106:107], v[118:119] op_sel_hi:[0,1]
	v_pk_fma_f32 v[108:109], v[114:115], v[32:33], v[34:35]
	v_pk_mul_f32 v[34:35], v[106:107], v[116:117] op_sel_hi:[0,1]
	ds_read_b128 v[120:123], v111 offset:3696
	v_pk_fma_f32 v[34:35], v[72:73], v[38:39], v[34:35] op_sel_hi:[0,1,1]
	v_pk_fma_f32 v[36:37], v[72:73], v[40:41], v[36:37] op_sel_hi:[0,1,1]
	ds_read_b128 v[38:41], v111 offset:1664
	ds_read_b128 v[112:115], v111 offset:3712
	ds_read_b128 v[116:119], v111 offset:1680
	s_waitcnt lgkmcnt(3)
	v_pk_fma_f32 v[108:109], v[120:121], v[34:35], v[108:109]
	s_waitcnt lgkmcnt(2)
	v_pk_mul_f32 v[38:39], v[106:107], v[38:39] op_sel_hi:[0,1]
	v_pk_fma_f32 v[108:109], v[122:123], v[36:37], v[108:109]
	v_pk_fma_f32 v[38:39], v[72:73], v[42:43], v[38:39] op_sel_hi:[0,1,1]
	v_pk_mul_f32 v[40:41], v[106:107], v[40:41] op_sel_hi:[0,1]
	v_pk_fma_f32 v[40:41], v[72:73], v[44:45], v[40:41] op_sel_hi:[0,1,1]
	s_waitcnt lgkmcnt(1)
	v_pk_fma_f32 v[42:43], v[112:113], v[38:39], v[108:109]
	s_waitcnt lgkmcnt(0)
	v_pk_mul_f32 v[44:45], v[106:107], v[118:119] op_sel_hi:[0,1]
	v_pk_fma_f32 v[108:109], v[114:115], v[40:41], v[42:43]
	v_pk_mul_f32 v[42:43], v[106:107], v[116:117] op_sel_hi:[0,1]
	ds_read_b128 v[120:123], v111 offset:3728
	v_pk_fma_f32 v[42:43], v[72:73], v[46:47], v[42:43] op_sel_hi:[0,1,1]
	v_pk_fma_f32 v[44:45], v[72:73], v[48:49], v[44:45] op_sel_hi:[0,1,1]
	ds_read_b128 v[46:49], v111 offset:1696
	ds_read_b128 v[112:115], v111 offset:3744
	ds_read_b128 v[116:119], v111 offset:1712
	s_waitcnt lgkmcnt(3)
; DEV void gdn_sample_item(const Params& p, int item, unsigned char* lds) {
;     ...
;         for (int d4 = 0; d4 < 16; ++d4) {
;             const f32x4 k4 = *(const f32x4*)(kk + d4 * 4), q4 = *(const f32x4*)(qq + d4 * 4);
;             const f32x2_t s0 = S[d4 * 2] * eg2 + (f32x2_t){k4[0], k4[1]} * dl2, s1 = S[d4 * 2 + 1] * eg2 + (f32x2_t){k4[2], k4[3]} * dl2;
;             S[d4 * 2] = s0; S[d4 * 2 + 1] = s1;
;             o2 += (f32x2_t){q4[0], q4[1]} * s0; o2 += (f32x2_t){q4[2], q4[3]} * s1;
;         }
	v_pk_fma_f32 v[108:109], v[120:121], v[42:43], v[108:109]
	s_waitcnt lgkmcnt(2)
	v_pk_mul_f32 v[46:47], v[106:107], v[46:47] op_sel_hi:[0,1]
	v_pk_fma_f32 v[108:109], v[122:123], v[44:45], v[108:109]
	v_pk_fma_f32 v[46:47], v[72:73], v[50:51], v[46:47] op_sel_hi:[0,1,1]
	v_pk_mul_f32 v[48:49], v[106:107], v[48:49] op_sel_hi:[0,1]
	v_pk_fma_f32 v[48:49], v[72:73], v[52:53], v[48:49] op_sel_hi:[0,1,1]
	s_waitcnt lgkmcnt(1)
	v_pk_fma_f32 v[50:51], v[112:113], v[46:47], v[108:109]
	s_waitcnt lgkmcnt(0)
	v_pk_mul_f32 v[52:53], v[106:107], v[118:119] op_sel_hi:[0,1]
	v_pk_fma_f32 v[108:109], v[114:115], v[48:49], v[50:51]
	v_pk_mul_f32 v[50:51], v[106:107], v[116:117] op_sel_hi:[0,1]
	ds_read_b128 v[120:123], v111 offset:3760
	v_pk_fma_f32 v[50:51], v[72:73], v[54:55], v[50:51] op_sel_hi:[0,1,1]
	v_pk_fma_f32 v[52:53], v[72:73], v[56:57], v[52:53] op_sel_hi:[0,1,1]
	ds_read_b128 v[54:57], v111 offset:1728
	ds_read_b128 v[112:115], v111 offset:3776
	ds_read_b128 v[116:119], v111 offset:1744
	s_waitcnt lgkmcnt(3)
	v_pk_fma_f32 v[108:109], v[120:121], v[50:51], v[108:109]
	s_waitcnt lgkmcnt(2)
	v_pk_mul_f32 v[54:55], v[106:107], v[54:55] op_sel_hi:[0,1]
	v_pk_fma_f32 v[108:109], v[122:123], v[52:53], v[108:109]
	v_pk_fma_f32 v[54:55], v[72:73], v[58:59], v[54:55] op_sel_hi:[0,1,1]
	v_pk_mul_f32 v[56:57], v[106:107], v[56:57] op_sel_hi:[0,1]
	v_pk_fma_f32 v[56:57], v[72:73], v[60:61], v[56:57] op_sel_hi:[0,1,1]
	s_waitcnt lgkmcnt(1)
	v_pk_fma_f32 v[58:59], v[112:113], v[54:55], v[108:109]
	ds_read_b128 v[120:123], v111 offset:3792
	v_pk_fma_f32 v[108:109], v[114:115], v[56:57], v[58:59]
	s_waitcnt lgkmcnt(1)
	v_pk_mul_f32 v[58:59], v[106:107], v[116:117] op_sel_hi:[0,1]
	v_pk_mul_f32 v[60:61], v[106:107], v[118:119] op_sel_hi:[0,1]
	v_pk_fma_f32 v[58:59], v[72:73], v[62:63], v[58:59] op_sel_hi:[0,1,1]
	v_pk_fma_f32 v[60:61], v[72:73], v[64:65], v[60:61] op_sel_hi:[0,1,1]
	ds_read_b128 v[62:65], v111 offset:1760
	ds_read_b128 v[112:115], v111 offset:3808
	ds_read_b128 v[116:119], v111 offset:1776
	s_waitcnt lgkmcnt(3)
	v_pk_fma_f32 v[108:109], v[120:121], v[58:59], v[108:109]
	s_waitcnt lgkmcnt(2)
	v_pk_mul_f32 v[62:63], v[106:107], v[62:63] op_sel_hi:[0,1]
	v_pk_fma_f32 v[120:121], v[122:123], v[60:61], v[108:109]
	ds_read_b128 v[108:111], v111 offset:3824
	v_pk_fma_f32 v[62:63], v[72:73], v[66:67], v[62:63] op_sel_hi:[0,1,1]
	v_pk_mul_f32 v[64:65], v[106:107], v[64:65] op_sel_hi:[0,1]
	v_pk_fma_f32 v[64:65], v[72:73], v[68:69], v[64:65] op_sel_hi:[0,1,1]
	s_waitcnt lgkmcnt(2)
	v_pk_fma_f32 v[66:67], v[112:113], v[62:63], v[120:121]
	s_nop 0
	v_pk_fma_f32 v[68:69], v[114:115], v[64:65], v[66:67]
	s_waitcnt lgkmcnt(1)
	v_pk_mul_f32 v[66:67], v[106:107], v[116:117] op_sel_hi:[0,1]
	v_pk_fma_f32 v[66:67], v[72:73], v[70:71], v[66:67] op_sel_hi:[0,1,1]
	v_pk_mul_f32 v[70:71], v[106:107], v[118:119] op_sel_hi:[0,1]
	v_pk_fma_f32 v[8:9], v[72:73], v[8:9], v[70:71] op_sel_hi:[0,1,1]
	s_waitcnt lgkmcnt(0)
; DEV void gdn_sample_item(const Params& p, int item, unsigned char* lds) {
;     ...
;         const float o = o2[0] + o2[1];
;         ot[t] = o;
;         if (half == 1) opart[t * 128 + c] = o;
;     }
;     float* dso = p.out + O_DS + ((size_t)(sb * 8 + h) * 128 + half * 64) * 128 + c;
; #pragma unroll
;     for (int d = 0; d < 64; ++d) __builtin_nontemporal_store(S[d >> 1][d & 1], dso + (size_t)d * 128);
;     __syncthreads();
;     if (half == 0) {
; #pragma unroll
;         for (int t = 0; t < 4; ++t) { ot[t] += opart[t * 128 + c]; const float a = wave_sum(ot[t] * ot[t]); if (lane == 0) red2[wid * 4 + t] = a; }
;     }
	v_pk_fma_f32 v[68:69], v[108:109], v[66:67], v[68:69]
	s_nop 0
	v_pk_fma_f32 v[68:69], v[110:111], v[8:9], v[68:69]
	s_nop 0
	v_add_f32_e32 v68, v68, v69
	s_and_saveexec_b64 s[52:53], s[8:9]
	v_lshl_or_b32 v69, v97, 2, v94
	v_add_u32_e32 v69, s70, v69
	ds_write_b32 v69, v68 offset:8448
	s_or_b64 exec, exec, s[52:53]
	v_lshl_add_u64 v[6:7], v[6:7], 2, s[12:13]
	v_lshl_add_u64 v[6:7], v[6:7], 0, v[2:3]
	global_store_dword v[6:7], v10, off nt
	global_store_dword v[6:7], v11, off offset:512 nt
	global_store_dword v[6:7], v12, off offset:1024 nt
	global_store_dword v[6:7], v13, off offset:1536 nt
	global_store_dword v[6:7], v74, off offset:2048 nt
	global_store_dword v[6:7], v75, off offset:2560 nt
	global_store_dword v[6:7], v76, off offset:3072 nt
	global_store_dword v[6:7], v77, off offset:3584 nt
	v_add_co_u32_e32 v10, vcc, s85, v6
	s_nop 1
	v_addc_co_u32_e32 v11, vcc, 0, v7, vcc
	v_add_co_u32_e32 v12, vcc, s65, v6
	s_nop 1
	v_addc_co_u32_e32 v13, vcc, 0, v7, vcc
	global_store_dword v[12:13], v14, off offset:-4096 nt
	global_store_dword v[10:11], v15, off offset:512 nt
	global_store_dword v[10:11], v16, off offset:1024 nt
	global_store_dword v[10:11], v17, off offset:1536 nt
	global_store_dword v[10:11], v18, off offset:2048 nt
	global_store_dword v[10:11], v19, off offset:2560 nt
	global_store_dword v[10:11], v20, off offset:3072 nt
	global_store_dword v[10:11], v21, off offset:3584 nt
	global_store_dword v[12:13], v22, off nt
	global_store_dword v[12:13], v23, off offset:512 nt
	global_store_dword v[12:13], v24, off offset:1024 nt
	global_store_dword v[12:13], v25, off offset:1536 nt
	global_store_dword v[12:13], v26, off offset:2048 nt
	global_store_dword v[12:13], v27, off offset:2560 nt
	global_store_dword v[12:13], v28, off offset:3072 nt
	global_store_dword v[12:13], v29, off offset:3584 nt
	v_add_co_u32_e32 v10, vcc, s66, v6
	s_nop 1
	v_addc_co_u32_e32 v11, vcc, 0, v7, vcc
	v_add_co_u32_e32 v12, vcc, s68, v6
	s_nop 1
	v_addc_co_u32_e32 v13, vcc, 0, v7, vcc
	global_store_dword v[12:13], v30, off offset:-4096 nt
	global_store_dword v[10:11], v31, off offset:512 nt
	global_store_dword v[10:11], v32, off offset:1024 nt
	global_store_dword v[10:11], v33, off offset:1536 nt
	global_store_dword v[10:11], v34, off offset:2048 nt
	global_store_dword v[10:11], v35, off offset:2560 nt
	global_store_dword v[10:11], v36, off offset:3072 nt
	global_store_dword v[10:11], v37, off offset:3584 nt
	global_store_dword v[12:13], v38, off nt
	global_store_dword v[12:13], v39, off offset:512 nt
	global_store_dword v[12:13], v40, off offset:1024 nt
	global_store_dword v[12:13], v41, off offset:1536 nt
	global_store_dword v[12:13], v42, off offset:2048 nt
	global_store_dword v[12:13], v43, off offset:2560 nt
	global_store_dword v[12:13], v44, off offset:3072 nt
	global_store_dword v[12:13], v45, off offset:3584 nt
	v_add_co_u32_e32 v10, vcc, s74, v6
	s_nop 1
	v_addc_co_u32_e32 v11, vcc, 0, v7, vcc
	v_add_co_u32_e32 v12, vcc, s67, v6
	s_nop 1
	v_addc_co_u32_e32 v13, vcc, 0, v7, vcc
	v_add_co_u32_e32 v6, vcc, s69, v6
	global_store_dword v[12:13], v46, off offset:-4096 nt
	global_store_dword v[10:11], v47, off offset:512 nt
	global_store_dword v[10:11], v48, off offset:1024 nt
	global_store_dword v[10:11], v49, off offset:1536 nt
	global_store_dword v[10:11], v50, off offset:2048 nt
	global_store_dword v[10:11], v51, off offset:2560 nt
	global_store_dword v[10:11], v52, off offset:3072 nt
	global_store_dword v[10:11], v53, off offset:3584 nt
	global_store_dword v[12:13], v54, off nt
	global_store_dword v[12:13], v55, off offset:512 nt
	global_store_dword v[12:13], v56, off offset:1024 nt
	global_store_dword v[12:13], v57, off offset:1536 nt
	global_store_dword v[12:13], v58, off offset:2048 nt
	global_store_dword v[12:13], v59, off offset:2560 nt
	global_store_dword v[12:13], v60, off offset:3072 nt
	global_store_dword v[12:13], v61, off offset:3584 nt
	v_addc_co_u32_e32 v7, vcc, 0, v7, vcc
	global_store_dword v[6:7], v62, off nt
	global_store_dword v[6:7], v63, off offset:512 nt
	global_store_dword v[6:7], v64, off offset:1024 nt
	global_store_dword v[6:7], v65, off offset:1536 nt
	global_store_dword v[6:7], v66, off offset:2048 nt
	global_store_dword v[6:7], v67, off offset:2560 nt
	global_store_dword v[6:7], v8, off offset:3072 nt
	global_store_dword v[6:7], v9, off offset:3584 nt
	s_waitcnt lgkmcnt(0)
	s_barrier
	s_and_saveexec_b64 s[8:9], s[6:7]
	s_cbranch_execz .LBB0_866
	ds_read_b32 v6, v105 offset:8448
	s_waitcnt lgkmcnt(0)
	v_add_f32_e32 v5, v5, v6
	v_mul_f32_e32 v6, v5, v5
	ds_bpermute_b32 v6, v98, v6
	s_waitcnt lgkmcnt(0)
	v_fmac_f32_e32 v6, v5, v5
	ds_bpermute_b32 v7, v99, v6
	s_waitcnt lgkmcnt(0)
	v_add_f32_e32 v6, v6, v7
	ds_bpermute_b32 v7, v100, v6
	s_waitcnt lgkmcnt(0)
	v_add_f32_e32 v6, v6, v7
	ds_bpermute_b32 v7, v101, v6
	s_waitcnt lgkmcnt(0)
	v_add_f32_e32 v6, v6, v7
	ds_bpermute_b32 v7, v102, v6
	s_waitcnt lgkmcnt(0)
	v_add_f32_e32 v7, v6, v7
	ds_bpermute_b32 v8, v103, v7
	v_lshlrev_b32_e32 v6, 2, v104
	v_lshl_add_u32 v6, v6, 2, s70
	s_and_saveexec_b64 s[52:53], s[4:5]
	s_cbranch_execz .LBB0_859
	s_waitcnt lgkmcnt(0)
	v_add_f32_e32 v7, v7, v8
	ds_write_b32 v6, v7 offset:4224

; DEV bf16_t f2bf(float f) { return (bf16_t)(cvt_pk_bf16(f, 0.f) & 0xffffu); }
; DEV float bf2f(unsigned b) { return __uint_as_float(b << 16); }
; DEV float silu_f(float x) { return x / (1.f + __expf(-x)); }
; DEV void gdn_sample_item(const Params& p, int item, unsigned char* lds) {
;     ...
;     __syncthreads();
;     if (half == 0) {
;         bf16_t* mix = (bf16_t*)(p.ws + WS_MIX);
;         const float gn = p.in[13][c];
; #pragma unroll
;         for (int t = 0; t < 4; ++t) {
;             const float ms = (red2[t] + red2[4 + t]) * (1.f / 128.f);
;             const float z = bf2f(proj[(size_t)(r0 + t) * NPJ + C_ZA + h * 128 + c]);
;             mix[(size_t)(r0 + t) * LDB + h * 128 + c] = f2bf(ot[t] * rsqrtf(ms + EPS) * gn * silu_f(z));
.LBB0_866:
	s_or_b64 exec, exec, s[8:9]
	s_waitcnt lgkmcnt(0)
	s_barrier
	s_and_saveexec_b64 s[8:9], s[6:7]
	s_cbranch_execz .LBB0_822
	s_lshl_b32 s14, s87, 1
	s_add_u32 s4, s62, s14
	s_addc_u32 s5, s63, 0
	s_add_u32 s6, s50, s14
	global_load_dword v24, v2, s[22:23]
	v_lshlrev_b32_e32 v2, 1, v96
	s_addc_u32 s7, s51, 0
	v_lshl_add_u64 v[6:7], s[6:7], 0, v[2:3]
	v_add_co_u32_e32 v6, vcc, s85, v6
	v_mov_b32_e32 v10, s70
	s_nop 0
	v_addc_co_u32_e32 v7, vcc, 0, v7, vcc
	global_load_ushort v25, v[6:7], off offset:2048
	ds_read_b128 v[6:9], v10 offset:4224
	ds_read_b128 v[10:13], v10 offset:4240
	v_lshl_add_u64 v[16:17], s[4:5], 0, v[2:3]
	v_mad_i64_i32 v[18:19], s[4:5], s42, v95, v[16:17]
	s_add_u32 s4, s48, s14
	s_addc_u32 s5, s49, 0
	s_waitcnt lgkmcnt(0)
	v_pk_add_f32 v[6:7], v[6:7], v[10:11]
	v_lshl_add_u64 v[10:11], s[4:5], 0, v[2:3]
	v_mov_b64_e32 v[14:15], s[30:31]
	s_add_u32 s4, s46, s14
	v_add_co_u32_e32 v10, vcc, s85, v10
	v_pk_fma_f32 v[6:7], v[6:7], s[34:35], v[14:15] op_sel_hi:[1,0,0]
	s_nop 0
	v_addc_co_u32_e32 v11, vcc, 0, v11, vcc
	s_addc_u32 s5, s47, 0
	v_mul_f32_e32 v20, 0x4b800000, v6
	v_cmp_gt_f32_e32 vcc, s79, v6
	s_add_u32 s6, s44, s14
	s_addc_u32 s7, s45, 0
	v_cndmask_b32_e32 v6, v6, v20, vcc
	v_lshl_add_u64 v[20:21], s[4:5], 0, v[2:3]
	v_rsq_f32_e32 v6, v6
	v_lshl_add_u64 v[22:23], s[6:7], 0, v[2:3]
	v_add_co_u32_e64 v20, s[4:5], s85, v20
	v_mul_f32_e32 v26, 0x45800000, v6
	s_nop 0
	v_addc_co_u32_e64 v21, s[4:5], 0, v21, s[4:5]
	v_cndmask_b32_e32 v6, v6, v26, vcc
	v_add_co_u32_e64 v22, s[4:5], s85, v22
	v_mul_f32_e32 v5, v5, v6
	s_nop 0
	v_addc_co_u32_e64 v23, s[4:5], 0, v23, s[4:5]
	v_pk_add_f32 v[8:9], v[8:9], v[12:13]
	s_waitcnt vmcnt(1)
	v_mul_f32_e32 v5, v24, v5
	v_pk_fma_f32 v[8:9], v[8:9], s[34:35], v[14:15] op_sel_hi:[1,0,0]
	s_waitcnt vmcnt(0)
	v_lshlrev_b32_e32 v2, 16, v25
	v_mul_f32_e32 v25, 0xbfb8aa3b, v2
	v_exp_f32_e32 v25, v25
	v_mul_f32_e32 v12, 0x4b800000, v8
	v_mul_f32_e32 v13, 0x4b800000, v9
	v_cmp_gt_f32_e64 s[6:7], s79, v9
	v_add_f32_e32 v6, 1.0, v25


; DEV bf16_t f2bf(float f) { return (bf16_t)(cvt_pk_bf16(f, 0.f) & 0xffffu); }
; DEV float bf2f(unsigned b) { return __uint_as_float(b << 16); }
; DEV float silu_f(float x) { return x / (1.f + __expf(-x)); }
; DEV void gdn_sample_item(const Params& p, int item, unsigned char* lds) {
;     ...
;         for (int t = 0; t < 4; ++t) {
;             const float ms = (red2[t] + red2[4 + t]) * (1.f / 128.f);
;             const float z = bf2f(proj[(size_t)(r0 + t) * NPJ + C_ZA + h * 128 + c]);
;             mix[(size_t)(r0 + t) * LDB + h * 128 + c] = f2bf(ot[t] * rsqrtf(ms + EPS) * gn * silu_f(z));
	v_rcp_f32_e32 v25, v6
	s_nop 0
	v_mul_f32_e32 v2, v2, v25
	v_mul_f32_e32 v2, v2, v5
	v_cvt_pk_bf16_f32 v2, v2, s0
	global_store_short v[18:19], v2, off
	global_load_ushort v2, v[10:11], off offset:2048
	s_nop 0
	global_load_ushort v5, v[20:21], off offset:2048
	global_load_ushort v18, v[22:23], off offset:2048
	v_mad_i64_i32 v[10:11], s[4:5], s40, v95, v[16:17]
	v_mul_f32_e32 v6, 0x4b800000, v7
	v_cmp_gt_f32_e32 vcc, s79, v7
	v_cmp_gt_f32_e64 s[4:5], s79, v8
	s_waitcnt vmcnt(2)
	v_lshlrev_b32_e32 v2, 16, v2
	v_cndmask_b32_e32 v6, v7, v6, vcc
	v_cndmask_b32_e64 v7, v8, v12, s[4:5]
	v_cndmask_b32_e64 v8, v9, v13, s[6:7]
	v_rsq_f32_e32 v12, v7
	v_rsq_f32_e32 v9, v6
	v_rsq_f32_e32 v8, v8
	s_waitcnt vmcnt(1)
	v_lshlrev_b32_e32 v5, 16, v5
	v_mul_f32_e32 v14, 0x45800000, v12
	v_mul_f32_e32 v13, 0x45800000, v9
	v_mul_f32_e32 v15, 0x45800000, v8
	v_cndmask_b32_e64 v12, v12, v14, s[4:5]
	v_mul_f32_e32 v14, 0xbfb8aa3b, v2
	v_cndmask_b32_e32 v9, v9, v13, vcc
	v_cndmask_b32_e64 v8, v8, v15, s[6:7]
	s_waitcnt vmcnt(0)
	v_lshlrev_b32_e32 v13, 16, v18
	v_mul_f32_e32 v15, 0xbfb8aa3b, v5
	v_exp_f32_e32 v14, v14
	v_mul_f32_e32 v18, 0xbfb8aa3b, v13
	v_exp_f32_e32 v15, v15
	v_exp_f32_e32 v18, v18
	v_add_f32_e32 v14, 1.0, v14
	v_mul_f32_e32 v9, v73, v9
	v_mul_f32_e32 v12, v107, v12
	v_mul_f32_e32 v8, v68, v8
	v_add_f32_e32 v15, 1.0, v15

; DEV bf16_t f2bf(float f) { return (bf16_t)(cvt_pk_bf16(f, 0.f) & 0xffffu); }
; DEV float bf2f(unsigned b) { return __uint_as_float(b << 16); }
; DEV float silu_f(float x) { return x / (1.f + __expf(-x)); }
; DEV void gdn_sample_item(const Params& p, int item, unsigned char* lds) {
;     ...
;         for (int t = 0; t < 4; ++t) {
;             const float ms = (red2[t] + red2[4 + t]) * (1.f / 128.f);
;             const float z = bf2f(proj[(size_t)(r0 + t) * NPJ + C_ZA + h * 128 + c]);
;             mix[(size_t)(r0 + t) * LDB + h * 128 + c] = f2bf(ot[t] * rsqrtf(ms + EPS) * gn * silu_f(z));
	v_mul_f32_e32 v9, v24, v9
	v_mul_f32_e32 v12, v24, v12
	v_mul_f32_e32 v8, v24, v8
	v_add_f32_e32 v18, 1.0, v18


; DEV bf16_t f2bf(float f) { return (bf16_t)(cvt_pk_bf16(f, 0.f) & 0xffffu); }
; DEV float silu_f(float x) { return x / (1.f + __expf(-x)); }
; DEV void gdn_sample_item(const Params& p, int item, unsigned char* lds) {
;     ...
;             mix[(size_t)(r0 + t) * LDB + h * 128 + c] = f2bf(ot[t] * rsqrtf(ms + EPS) * gn * silu_f(z));
	s_mov_b64 vcc, s[4:5]

; DEV bf16_t f2bf(float f) { return (bf16_t)(cvt_pk_bf16(f, 0.f) & 0xffffu); }
; DEV float silu_f(float x) { return x / (1.f + __expf(-x)); }
; DEV void gdn_sample_item(const Params& p, int item, unsigned char* lds) {
;     ...
;             mix[(size_t)(r0 + t) * LDB + h * 128 + c] = f2bf(ot[t] * rsqrtf(ms + EPS) * gn * silu_f(z));
	v_rcp_f32_e32 v19, v14
	s_nop 0
	v_mul_f32_e32 v2, v2, v19

; DEV bf16_t f2bf(float f) { return (bf16_t)(cvt_pk_bf16(f, 0.f) & 0xffffu); }
; DEV float silu_f(float x) { return x / (1.f + __expf(-x)); }
; DEV void gdn_sample_item(const Params& p, int item, unsigned char* lds) {
;     ...
;             mix[(size_t)(r0 + t) * LDB + h * 128 + c] = f2bf(ot[t] * rsqrtf(ms + EPS) * gn * silu_f(z));
	s_mov_b64 vcc, s[6:7]
	v_mul_f32_e32 v2, v2, v9
	v_rcp_f32_e32 v14, v15
	s_nop 0
	v_mul_f32_e32 v5, v5, v14

; DEV bf16_t f2bf(float f) { return (bf16_t)(cvt_pk_bf16(f, 0.f) & 0xffffu); }
; DEV float silu_f(float x) { return x / (1.f + __expf(-x)); }
; DEV void gdn_sample_item(const Params& p, int item, unsigned char* lds) {
;     ...
;             mix[(size_t)(r0 + t) * LDB + h * 128 + c] = f2bf(ot[t] * rsqrtf(ms + EPS) * gn * silu_f(z));
	v_cvt_pk_bf16_f32 v2, v2, s0
	v_mul_f32_e32 v5, v5, v12
	v_rcp_f32_e32 v9, v18
	s_nop 0
	v_mul_f32_e32 v9, v13, v9
	v_mad_i64_i32 v[6:7], s[38:39], s38, v95, v[16:17]
	global_store_short v[10:11], v2, off
	v_cvt_pk_bf16_f32 v2, v5, s0
	v_mul_f32_e32 v5, v9, v8
	global_store_short v[6:7], v2, off
	v_cvt_pk_bf16_f32 v2, v5, s0
	v_mad_i64_i32 v[6:7], s[4:5], s36, v95, v[16:17]
	global_store_short v[6:7], v2, off
	s_branch .LBB0_822

; #define LAS __attribute__((address_space(3)))
; template <int WT, class Epi>
; DEV void gemm_tile(const bf16_t* __restrict__ A, int lda, const bf16_t* __restrict__ Bt, int ldb, int K, unsigned char* lds, const Epi& epi) {
;     ...
;     const int lrow = tid >> 3, lcs = (tid & 7) ^ (lrow & 7);
;     const bf16_t* ap = A + (size_t)lrow * lda + lcs * 8;
;     const bf16_t* bp = Bt + (size_t)lrow * ldb + lcs * 8;
;     const unsigned l3a = (unsigned)(size_t)(LAS unsigned char*)lds;
;     const int nk = K >> 6;
;     ...
;     constexpr int NSTG = 65536 / STB;
; #pragma unroll
;     for (int s_ = 0; s_ < NSTG - 1; ++s_) if (s_ < nk) GLDS_STAGE(s_ * STB, s_);
;     const int aoff = (wr * WT + fr) * 128, boff = OPB + (wc * WT + fr) * 128, sw = fr & 7;
;     int cur = 0, nxt = (NSTG - 1) * STB;
;     for (int kt = 0; kt < nk; ++kt) {
;         if (NSTG == 4 && kt + 2 < nk) { if (FI == 2) asm volatile("s_waitcnt vmcnt(8)" ::: "memory"); else asm volatile("s_waitcnt vmcnt(0)" ::: "memory"); }
;         else asm volatile("s_waitcnt vmcnt(0)" ::: "memory");
;         __syncthreads();
;         if (kt + NSTG - 1 < nk) GLDS_STAGE(nxt, kt + NSTG - 1);
; #pragma unroll
;         for (int kh = 0; kh < 2; ++kh) {
;             bf16x8 af[FI], bfr[FI];
;             const int ch = ((kh * 4 + fq) ^ sw) << 4;
; #pragma unroll
;             for (int i = 0; i < FI; ++i) { af[i] = *(const bf16x8*)(lds + cur + aoff + i * 2048 + ch); bfr[i] = *(const bf16x8*)(lds + cur + boff + i * 2048 + ch); }
; #pragma unroll
;             for (int mi = 0; mi < FI; ++mi)
; #pragma unroll
;                 for (int ni = 0; ni < FI; ++ni) acc[mi][ni] = __builtin_amdgcn_mfma_f32_16x16x32_bf16(bfr[ni], af[mi], acc[mi][ni], 0, 0, 0);
; __global__ void __launch_bounds__(512) hymba_fwd(Params p) {
;     ...
;             for (int t0 = 2 * ob; t0 < NPL; t0 += 2 * no) { const int t = min(t0 + vb, NPL - 1); int nt, mt; tile_map(t, 68, 8, mt, nt); const int g = nt >> 1;
;                 EpiPoolS e{mt * 128, nt * 128, proj, p.in[15], mix + (size_t)mt * 128 * LDB + 1024 + nt * 128, LDB};
;                 gemm_tile<64>(dpl + (size_t)mt * 128 * LDP + g * 256, LDP, Wt_pool + (size_t)nt * 128 * LDM, LDM, 256, vlds, e);
.LBB0_870:
	s_add_i32 s14, s71, s72
	s_min_i32 s14, s14, 0x21f
	s_and_b32 s15, s14, 7
	s_mulk_i32 s15, 0x44
	s_ashr_i32 s14, s14, 3
	s_add_i32 s14, s15, s14
	s_ashr_i32 s15, s14, 31
	s_lshr_b32 s15, s15, 26
	s_add_i32 s15, s14, s15
	s_ashr_i32 s68, s15, 6
	s_lshl_b32 s81, s68, 3
	s_sub_i32 s68, 0x44, s81
	s_andn2_b32 s15, s15, 63
	s_min_u32 s82, s68, 8
	s_sub_i32 s14, s14, s15
	s_sext_i32_i8 s15, s14
	v_cvt_f32_ubyte0_e32 v3, s82
	v_cvt_f32_i32_e32 v2, s15
	v_rcp_iflag_f32_e32 v4, v3
	s_ashr_i32 s68, s15, 30
	s_or_b32 s83, s68, 1
	v_mov_b32_e32 v137, v1
	v_mul_f32_e32 v4, v2, v4
	v_trunc_f32_e32 v4, v4
	v_fma_f32 v2, -v4, v3, v2
	v_cvt_i32_f32_e32 v4, v4
	v_cmp_ge_f32_e64 s[68:69], |v2|, v3
	s_and_b64 s[68:69], s[68:69], exec
	s_cselect_b32 s15, s83, 0
	v_readfirstlane_b32 s68, v4
	s_add_i32 s15, s68, s15
	s_sext_i32_i8 s84, s15
	s_mul_i32 s15, s15, s82
	s_sub_i32 s14, s14, s15
	s_sext_i32_i8 s14, s14
	s_add_i32 s14, s81, s14
	s_lshl_b32 s68, s84, 7
	v_mad_i64_i32 v[2:3], s[82:83], s14, v134, v[174:175]
	s_ashr_i32 s69, s68, 31
	v_lshl_add_u64 v[132:133], s[68:69], 1, v[2:3]
	v_mad_i64_i32 v[2:3], s[82:83], s14, v135, v[140:141]
	s_and_b32 s82, s68, 0xffffff00
	s_ashr_i32 s83, s82, 31
	v_ashrrev_i32_e32 v6, 3, v137
	v_xor_b32_e32 v7, v6, v137
	v_lshl_add_u64 v[2:3], s[82:83], 1, v[2:3]
	v_mad_i64_i32 v[4:5], s[82:83], s84, v136, v[138:139]
	v_lshlrev_b32_e32 v7, 4, v7
	v_lshlrev_b32_e32 v9, 4, v137
	v_mad_i64_i32 v[2:3], s[82:83], v6, s77, v[2:3]
	v_and_b32_e32 v130, 0x70, v7
	v_mad_i64_i32 v[4:5], s[82:83], v6, s78, v[4:5]
	v_add_u32_e32 v6, s70, v9
	s_lshl_b32 s81, s14, 7
	v_lshl_add_u64 v[2:3], v[2:3], 0, v[130:131]
	v_add_u32_e32 v7, 0x4000, v6
	v_readfirstlane_b32 s14, v6
	s_mov_b32 s15, m0
	s_mov_b32 m0, s14
	s_nop 0
	global_load_lds_dwordx4 v[2:3], off
	s_mov_b32 m0, s15
	v_lshl_add_u64 v[4:5], v[4:5], 0, v[130:131]
	v_readfirstlane_b32 s15, v7
	s_mov_b32 s82, m0
	s_mov_b32 m0, s15
	s_nop 0
	global_load_lds_dwordx4 v[4:5], off
	s_mov_b32 m0, s82
	v_lshl_add_u64 v[6:7], v[2:3], 0, s[6:7]
	s_add_i32 s82, s14, 0x1000
	s_mov_b32 s83, m0
	s_mov_b32 m0, s82
	s_nop 0
	global_load_lds_dwordx4 v[6:7], off
	s_mov_b32 m0, s83
	v_lshl_add_u64 v[6:7], v[4:5], 0, s[8:9]
	s_add_i32 s83, s15, 0x1000
	s_mov_b32 s84, m0
	s_mov_b32 m0, s83
	s_nop 0
	global_load_lds_dwordx4 v[6:7], off
	s_mov_b32 m0, s84
	v_lshl_add_u64 v[6:7], v[2:3], 0, s[10:11]
	s_add_i32 s83, s14, 0x2000
	s_mov_b32 s84, m0
	s_mov_b32 m0, s83
	s_nop 0
	global_load_lds_dwordx4 v[6:7], off
	s_mov_b32 m0, s84
	v_lshl_add_u64 v[6:7], v[4:5], 0, s[12:13]
	s_add_i32 s84, s15, 0x2000
	s_mov_b32 s85, m0
	s_mov_b32 m0, s84
	s_nop 0
	global_load_lds_dwordx4 v[6:7], off
	s_mov_b32 m0, s85
	v_lshl_add_u64 v[6:7], v[2:3], 0, s[16:17]
	s_add_i32 s84, s14, 0x3000
	s_mov_b32 s85, m0
	s_mov_b32 m0, s84
	s_nop 0
	global_load_lds_dwordx4 v[6:7], off
	s_mov_b32 m0, s85
	v_lshl_add_u64 v[6:7], v[4:5], 0, s[18:19]
	v_and_b32_e32 v8, 15, v137
	s_addk_i32 s15, 0x3000
	s_mov_b32 s85, m0
	s_mov_b32 m0, s15
	s_nop 0
	global_load_lds_dwordx4 v[6:7], off
	s_mov_b32 m0, s85
	v_ashrrev_i32_e32 v6, 1, v137
	v_and_or_b32 v130, v6, s76, v8
	v_lshlrev_b32_e32 v6, 7, v137
	v_add_u32_e32 v102, 0x4000, v9
	v_add_u32_e32 v12, s73, v9
	v_and_b32_e32 v11, 0x2780, v6
	s_waitcnt vmcnt(0)
	s_waitcnt lgkmcnt(0)
	s_barrier
	v_lshl_add_u64 v[6:7], v[2:3], 0, s[20:21]
	v_add_u32_e32 v13, s73, v102
	v_readfirstlane_b32 s15, v12
	s_mov_b32 s85, m0
	s_mov_b32 m0, s15
	s_nop 0
	global_load_lds_dwordx4 v[6:7], off
	s_mov_b32 m0, s85
	v_lshl_add_u64 v[8:9], v[4:5], 0, s[20:21]
	v_readfirstlane_b32 s85, v13
	s_mov_b32 s86, m0
	s_mov_b32 m0, s85
	s_nop 0
	global_load_lds_dwordx4 v[8:9], off
	s_mov_b32 m0, s86
	v_lshl_add_u64 v[6:7], v[2:3], 0, s[22:23]
	s_add_i32 s86, s15, 0x1000
	s_mov_b32 s87, m0
	s_mov_b32 m0, s86
	s_nop 0
	global_load_lds_dwordx4 v[6:7], off
	s_mov_b32 m0, s87
	v_lshl_add_u64 v[6:7], v[4:5], 0, s[24:25]
	s_add_i32 s87, s85, 0x1000
	s_mov_b32 s88, m0
	s_mov_b32 m0, s87
	s_nop 0
	global_load_lds_dwordx4 v[6:7], off
	s_mov_b32 m0, s88
	v_lshl_add_u64 v[6:7], v[2:3], 0, s[26:27]
	s_add_i32 s88, s15, 0x2000
	s_mov_b32 s89, m0
	s_mov_b32 m0, s88
	s_nop 0
	global_load_lds_dwordx4 v[6:7], off
	s_mov_b32 m0, s89
	v_lshl_add_u64 v[6:7], v[4:5], 0, s[30:31]
	s_add_i32 s89, s85, 0x2000
	s_mov_b32 s90, m0
	s_mov_b32 m0, s89
	s_nop 0
	global_load_lds_dwordx4 v[6:7], off
	s_mov_b32 m0, s90
	v_lshl_add_u64 v[6:7], v[2:3], 0, s[34:35]
	v_lshrrev_b32_e32 v10, 4, v137
	v_and_b32_e32 v74, 7, v137
	s_add_i32 s90, s15, 0x3000
	s_mov_b32 s91, m0
	s_mov_b32 m0, s90
	s_nop 0
	global_load_lds_dwordx4 v[6:7], off
	s_mov_b32 m0, s91
	v_lshl_add_u64 v[6:7], v[4:5], 0, s[36:37]
	s_add_i32 s91, s85, 0x3000
	s_mov_b32 s92, m0
	s_mov_b32 m0, s91
	s_nop 0
	global_load_lds_dwordx4 v[6:7], off
	s_mov_b32 m0, s92
	v_bitop3_b32 v6, v10, v74, 3 bitop3:0x6c
	v_lshl_add_u32 v75, v130, 7, s70
	v_lshlrev_b32_e32 v6, 4, v6
	v_add_u32_e32 v76, s70, v11
	v_add_u32_e32 v126, v75, v6
	v_add_u32_e32 v118, v76, v6
	ds_read_b128 v[6:9], v126
	ds_read_b128 v[10:13], v118 offset:16384
	ds_read_b128 v[14:17], v126 offset:2048
	ds_read_b128 v[18:21], v118 offset:18432
	ds_read_b128 v[22:25], v126 offset:4096
	ds_read_b128 v[26:29], v118 offset:20480
	ds_read_b128 v[30:33], v126 offset:6144
	ds_read_b128 v[34:37], v118 offset:22528
	v_bfe_u32 v142, v137, 4, 2
	s_waitcnt lgkmcnt(6)
	v_mfma_f32_16x16x32_bf16 v[38:41], v[10:13], v[6:9], 0
	v_and_b32_e32 v143, 64, v137
	s_add_i32 s72, s72, s74
	s_waitcnt lgkmcnt(4)
	v_mfma_f32_16x16x32_bf16 v[42:45], v[18:21], v[6:9], 0
	s_waitcnt lgkmcnt(2)
	v_mfma_f32_16x16x32_bf16 v[46:49], v[26:29], v[6:9], 0
	s_waitcnt lgkmcnt(0)
	v_mfma_f32_16x16x32_bf16 v[6:9], v[34:37], v[6:9], 0
	v_mfma_f32_16x16x32_bf16 v[50:53], v[10:13], v[14:17], 0
	v_mfma_f32_16x16x32_bf16 v[54:57], v[18:21], v[14:17], 0
	v_mfma_f32_16x16x32_bf16 v[58:61], v[26:29], v[14:17], 0
	v_mfma_f32_16x16x32_bf16 v[14:17], v[34:37], v[14:17], 0
	v_mfma_f32_16x16x32_bf16 v[62:65], v[10:13], v[22:25], 0
	v_mfma_f32_16x16x32_bf16 v[66:69], v[18:21], v[22:25], 0
	v_mfma_f32_16x16x32_bf16 v[70:73], v[26:29], v[22:25], 0
	v_mfma_f32_16x16x32_bf16 v[22:25], v[34:37], v[22:25], 0
	v_mfma_f32_16x16x32_bf16 v[10:13], v[10:13], v[30:33], 0
	v_mfma_f32_16x16x32_bf16 v[18:21], v[18:21], v[30:33], 0
	v_mfma_f32_16x16x32_bf16 v[26:29], v[26:29], v[30:33], 0
	v_mfma_f32_16x16x32_bf16 v[30:33], v[34:37], v[30:33], 0
	v_bitop3_b32 v34, v142, v74, 4 bitop3:0x36
	v_lshlrev_b32_e32 v34, 4, v34
	v_add_u32_e32 v114, v75, v34
	v_add_u32_e32 v115, v76, v34
	ds_read_b128 v[34:37], v114
	ds_read_b128 v[74:77], v115 offset:16384
	ds_read_b128 v[78:81], v114 offset:2048
	ds_read_b128 v[82:85], v115 offset:18432
	ds_read_b128 v[86:89], v114 offset:4096
	ds_read_b128 v[90:93], v115 offset:20480
	ds_read_b128 v[94:97], v114 offset:6144
	ds_read_b128 v[98:101], v115 offset:22528
	s_waitcnt lgkmcnt(6)
	v_mfma_f32_16x16x32_bf16 v[38:41], v[74:77], v[34:37], v[38:41]
	s_waitcnt vmcnt(0)
	s_waitcnt lgkmcnt(0)
	s_barrier
; #define GLDS_STAGE(st, kt_) do { \
;         _Pragma("unroll") for (int i_ = 0; i_ < FI; ++i_) { \
;             glds16(ap + (size_t)(32 * i_) * lda + (kt_) * 64, l3a + (st) + tid * 16 + i_ * 4096); \
;             glds16(bp + (size_t)(32 * i_) * ldb + (kt_) * 64, l3a + (st) + OPB + tid * 16 + i_ * 4096); } } while (0)
; #define GLDS_STAGE(st, kt_) do { \
;         _Pragma("unroll") for (int i_ = 0; i_ < 4; ++i_) { \
;             glds16(ap + (size_t)(64 * i_) * lda + (kt_) * 64, l3a + (st) + tid * 16 + i_ * 8192); \
;             glds16(bp + (size_t)(64 * i_) * ldb + (kt_) * 64, l3a + (st) + 32768 + tid * 16 + i_ * 8192); } } while (0)
; template <int WT, class Epi>
; DEV void gemm_tile(const bf16_t* __restrict__ A, int lda, const bf16_t* __restrict__ Bt, int ldb, int K, unsigned char* lds, const Epi& epi) {
;     ...
;     for (int kt = 0; kt < nk; ++kt) {
;         if (NSTG == 4 && kt + 2 < nk) { if (FI == 2) asm volatile("s_waitcnt vmcnt(8)" ::: "memory"); else asm volatile("s_waitcnt vmcnt(0)" ::: "memory"); }
;         else asm volatile("s_waitcnt vmcnt(0)" ::: "memory");
;         __syncthreads();
;         if (kt + NSTG - 1 < nk) GLDS_STAGE(nxt, kt + NSTG - 1);
; #pragma unroll
;         for (int kh = 0; kh < 2; ++kh) {
;             bf16x8 af[FI], bfr[FI];
;             const int ch = ((kh * 4 + fq) ^ sw) << 4;
; #pragma unroll
;             for (int i = 0; i < FI; ++i) { af[i] = *(const bf16x8*)(lds + cur + aoff + i * 2048 + ch); bfr[i] = *(const bf16x8*)(lds + cur + boff + i * 2048 + ch); }
; #pragma unroll
;             for (int mi = 0; mi < FI; ++mi)
; #pragma unroll
;                 for (int ni = 0; ni < FI; ++ni) acc[mi][ni] = __builtin_amdgcn_mfma_f32_16x16x32_bf16(bfr[ni], af[mi], acc[mi][ni], 0, 0, 0);
	v_mfma_f32_16x16x32_bf16 v[42:45], v[82:85], v[34:37], v[42:45]
	v_mfma_f32_16x16x32_bf16 v[46:49], v[90:93], v[34:37], v[46:49]
	v_mfma_f32_16x16x32_bf16 v[6:9], v[98:101], v[34:37], v[6:9]
	v_mfma_f32_16x16x32_bf16 v[34:37], v[74:77], v[78:81], v[50:53]
	v_mfma_f32_16x16x32_bf16 v[50:53], v[82:85], v[78:81], v[54:57]
	v_mfma_f32_16x16x32_bf16 v[54:57], v[90:93], v[78:81], v[58:61]
	v_mfma_f32_16x16x32_bf16 v[58:61], v[74:77], v[86:89], v[62:65]
	v_mfma_f32_16x16x32_bf16 v[62:65], v[82:85], v[86:89], v[66:69]
	v_mfma_f32_16x16x32_bf16 v[66:69], v[90:93], v[86:89], v[70:73]
	v_mfma_f32_16x16x32_bf16 v[10:13], v[74:77], v[94:97], v[10:13]
	s_nop 1
	v_lshl_add_u64 v[70:71], v[2:3], 0, s[38:39]
	v_add_u32_e32 v74, s70, v102
	s_mov_b32 s92, m0
	s_mov_b32 m0, s14
	s_nop 0
	global_load_lds_dwordx4 v[70:71], off
	s_mov_b32 m0, s92
	v_lshl_add_u64 v[72:73], v[4:5], 0, s[38:39]
	v_readfirstlane_b32 s14, v74
	s_mov_b32 s92, m0
	s_mov_b32 m0, s14
	s_nop 0
	global_load_lds_dwordx4 v[72:73], off
	s_mov_b32 m0, s92
	v_lshl_add_u64 v[70:71], v[2:3], 0, s[40:41]
	s_mov_b32 s92, m0
	s_mov_b32 m0, s82
	s_nop 0
	global_load_lds_dwordx4 v[70:71], off
	s_mov_b32 m0, s92
	v_lshl_add_u64 v[70:71], v[4:5], 0, s[42:43]
	s_add_i32 s82, s14, 0x1000
	s_mov_b32 s92, m0
	s_mov_b32 m0, s82
	s_nop 0
	global_load_lds_dwordx4 v[70:71], off
	s_mov_b32 m0, s92
	v_lshl_add_u64 v[70:71], v[2:3], 0, s[44:45]
	s_mov_b32 s82, m0
	s_mov_b32 m0, s83
	s_nop 0
	global_load_lds_dwordx4 v[70:71], off
	s_mov_b32 m0, s82
	v_lshl_add_u64 v[70:71], v[4:5], 0, s[46:47]
	s_add_i32 s82, s14, 0x2000
	s_mov_b32 s83, m0
	s_mov_b32 m0, s82
	s_nop 0
	global_load_lds_dwordx4 v[70:71], off
	s_mov_b32 m0, s83
	v_lshl_add_u64 v[70:71], v[2:3], 0, s[48:49]
	s_mov_b32 s82, m0
	s_mov_b32 m0, s84
	s_nop 0
	global_load_lds_dwordx4 v[70:71], off
	s_mov_b32 m0, s82
	v_lshl_add_u64 v[70:71], v[4:5], 0, s[50:51]
	s_addk_i32 s14, 0x3000
	s_mov_b32 s82, m0
	s_mov_b32 m0, s14
	s_nop 0
	global_load_lds_dwordx4 v[70:71], off
	s_mov_b32 m0, s82
	v_mfma_f32_16x16x32_bf16 v[14:17], v[98:101], v[78:81], v[14:17]
	s_cmpk_lt_i32 s72, 0x220
	v_mfma_f32_16x16x32_bf16 v[22:25], v[98:101], v[86:89], v[22:25]
	v_mfma_f32_16x16x32_bf16 v[18:21], v[82:85], v[94:97], v[18:21]
	v_mfma_f32_16x16x32_bf16 v[26:29], v[90:93], v[94:97], v[26:29]
	v_mfma_f32_16x16x32_bf16 v[30:33], v[98:101], v[94:97], v[30:33]
	ds_read_b128 v[70:73], v126 offset:32768
	ds_read_b128 v[74:77], v118 offset:49152
	ds_read_b128 v[78:81], v126 offset:34816
	ds_read_b128 v[82:85], v118 offset:51200
	ds_read_b128 v[86:89], v126 offset:36864
	ds_read_b128 v[90:93], v118 offset:53248
	ds_read_b128 v[94:97], v126 offset:38912
	ds_read_b128 v[98:101], v118 offset:55296
	s_waitcnt lgkmcnt(6)
	v_mfma_f32_16x16x32_bf16 v[38:41], v[74:77], v[70:73], v[38:41]
	s_waitcnt lgkmcnt(4)
	v_mfma_f32_16x16x32_bf16 v[42:45], v[82:85], v[70:73], v[42:45]
	s_waitcnt lgkmcnt(2)
	v_mfma_f32_16x16x32_bf16 v[46:49], v[90:93], v[70:73], v[46:49]
	s_waitcnt lgkmcnt(0)
	v_mfma_f32_16x16x32_bf16 v[6:9], v[98:101], v[70:73], v[6:9]
	v_mfma_f32_16x16x32_bf16 v[34:37], v[74:77], v[78:81], v[34:37]
	v_mfma_f32_16x16x32_bf16 v[50:53], v[82:85], v[78:81], v[50:53]
	v_mfma_f32_16x16x32_bf16 v[54:57], v[90:93], v[78:81], v[54:57]
	v_mfma_f32_16x16x32_bf16 v[14:17], v[98:101], v[78:81], v[14:17]
	v_mfma_f32_16x16x32_bf16 v[58:61], v[74:77], v[86:89], v[58:61]
	v_mfma_f32_16x16x32_bf16 v[62:65], v[82:85], v[86:89], v[62:65]
	v_mfma_f32_16x16x32_bf16 v[66:69], v[90:93], v[86:89], v[66:69]
	v_mfma_f32_16x16x32_bf16 v[22:25], v[98:101], v[86:89], v[22:25]
	v_mfma_f32_16x16x32_bf16 v[10:13], v[74:77], v[94:97], v[10:13]
	v_mfma_f32_16x16x32_bf16 v[18:21], v[82:85], v[94:97], v[18:21]
	v_mfma_f32_16x16x32_bf16 v[26:29], v[90:93], v[94:97], v[26:29]
	v_mfma_f32_16x16x32_bf16 v[30:33], v[98:101], v[94:97], v[30:33]
	ds_read_b128 v[70:73], v114 offset:32768
	ds_read_b128 v[74:77], v115 offset:49152
	ds_read_b128 v[78:81], v114 offset:34816
	ds_read_b128 v[82:85], v115 offset:51200
	ds_read_b128 v[86:89], v114 offset:36864
	ds_read_b128 v[90:93], v115 offset:53248
	ds_read_b128 v[94:97], v114 offset:38912
	ds_read_b128 v[98:101], v115 offset:55296
	s_waitcnt vmcnt(0)
	s_waitcnt lgkmcnt(0)
	v_mfma_f32_16x16x32_bf16 v[38:41], v[74:77], v[70:73], v[38:41]
	s_barrier
; #define GLDS_STAGE(st, kt_) do { \
;         _Pragma("unroll") for (int i_ = 0; i_ < FI; ++i_) { \
;             glds16(ap + (size_t)(32 * i_) * lda + (kt_) * 64, l3a + (st) + tid * 16 + i_ * 4096); \
;             glds16(bp + (size_t)(32 * i_) * ldb + (kt_) * 64, l3a + (st) + OPB + tid * 16 + i_ * 4096); } } while (0)
; #define GLDS_STAGE(st, kt_) do { \
;         _Pragma("unroll") for (int i_ = 0; i_ < 4; ++i_) { \
;             glds16(ap + (size_t)(64 * i_) * lda + (kt_) * 64, l3a + (st) + tid * 16 + i_ * 8192); \
;             glds16(bp + (size_t)(64 * i_) * ldb + (kt_) * 64, l3a + (st) + 32768 + tid * 16 + i_ * 8192); } } while (0)
; template <int WT, class Epi>
; DEV void gemm_tile(const bf16_t* __restrict__ A, int lda, const bf16_t* __restrict__ Bt, int ldb, int K, unsigned char* lds, const Epi& epi) {
;     ...
;     for (int kt = 0; kt < nk; ++kt) {
;         if (NSTG == 4 && kt + 2 < nk) { if (FI == 2) asm volatile("s_waitcnt vmcnt(8)" ::: "memory"); else asm volatile("s_waitcnt vmcnt(0)" ::: "memory"); }
;         else asm volatile("s_waitcnt vmcnt(0)" ::: "memory");
;         __syncthreads();
;         if (kt + NSTG - 1 < nk) GLDS_STAGE(nxt, kt + NSTG - 1);
; #pragma unroll
;         for (int kh = 0; kh < 2; ++kh) {
;             bf16x8 af[FI], bfr[FI];
;             const int ch = ((kh * 4 + fq) ^ sw) << 4;
; #pragma unroll
;             for (int i = 0; i < FI; ++i) { af[i] = *(const bf16x8*)(lds + cur + aoff + i * 2048 + ch); bfr[i] = *(const bf16x8*)(lds + cur + boff + i * 2048 + ch); }
; #pragma unroll
;             for (int mi = 0; mi < FI; ++mi)
; #pragma unroll
;                 for (int ni = 0; ni < FI; ++ni) acc[mi][ni] = __builtin_amdgcn_mfma_f32_16x16x32_bf16(bfr[ni], af[mi], acc[mi][ni], 0, 0, 0);
	v_mfma_f32_16x16x32_bf16 v[42:45], v[82:85], v[70:73], v[42:45]
	v_mfma_f32_16x16x32_bf16 v[46:49], v[90:93], v[70:73], v[46:49]
	v_mfma_f32_16x16x32_bf16 v[6:9], v[98:101], v[70:73], v[6:9]
	v_lshl_add_u64 v[70:71], v[2:3], 0, s[52:53]
	s_mov_b32 s14, m0
	s_mov_b32 m0, s15
	s_nop 0
	global_load_lds_dwordx4 v[70:71], off
	s_mov_b32 m0, s14
	v_lshl_add_u64 v[72:73], v[4:5], 0, s[52:53]
	s_mov_b32 s14, m0
	s_mov_b32 m0, s85
	s_nop 0
	global_load_lds_dwordx4 v[72:73], off
	s_mov_b32 m0, s14
	v_lshl_add_u64 v[70:71], v[2:3], 0, s[54:55]
	s_mov_b32 s14, m0
	s_mov_b32 m0, s86
	s_nop 0
	global_load_lds_dwordx4 v[70:71], off
	s_mov_b32 m0, s14
	v_lshl_add_u64 v[70:71], v[4:5], 0, s[56:57]
	s_mov_b32 s14, m0
	s_mov_b32 m0, s87
	s_nop 0
	global_load_lds_dwordx4 v[70:71], off
	s_mov_b32 m0, s14
	v_lshl_add_u64 v[70:71], v[2:3], 0, s[58:59]
	s_mov_b32 s14, m0
	s_mov_b32 m0, s88
	s_nop 0
	global_load_lds_dwordx4 v[70:71], off
	s_mov_b32 m0, s14
	v_lshl_add_u64 v[70:71], v[4:5], 0, s[60:61]
	s_mov_b32 s14, m0
	s_mov_b32 m0, s89
	s_nop 0
	global_load_lds_dwordx4 v[70:71], off
	s_mov_b32 m0, s14
	v_lshl_add_u64 v[2:3], v[2:3], 0, s[62:63]
	s_mov_b32 s14, m0
	s_mov_b32 m0, s90
	s_nop 0
	global_load_lds_dwordx4 v[2:3], off
	s_mov_b32 m0, s14
	v_lshl_add_u64 v[2:3], v[4:5], 0, s[64:65]
	s_mov_b32 s14, m0
	s_mov_b32 m0, s91
	s_nop 0
	global_load_lds_dwordx4 v[2:3], off
	s_mov_b32 m0, s14
	v_mfma_f32_16x16x32_bf16 v[34:37], v[74:77], v[78:81], v[34:37]
	v_mfma_f32_16x16x32_bf16 v[50:53], v[82:85], v[78:81], v[50:53]
	v_mfma_f32_16x16x32_bf16 v[54:57], v[90:93], v[78:81], v[54:57]
	v_mfma_f32_16x16x32_bf16 v[14:17], v[98:101], v[78:81], v[14:17]
	v_mfma_f32_16x16x32_bf16 v[58:61], v[74:77], v[86:89], v[58:61]
	v_mfma_f32_16x16x32_bf16 v[62:65], v[82:85], v[86:89], v[62:65]
	v_mfma_f32_16x16x32_bf16 v[66:69], v[90:93], v[86:89], v[66:69]
	v_mfma_f32_16x16x32_bf16 v[22:25], v[98:101], v[86:89], v[22:25]
	v_mfma_f32_16x16x32_bf16 v[10:13], v[74:77], v[94:97], v[10:13]
	v_mfma_f32_16x16x32_bf16 v[18:21], v[82:85], v[94:97], v[18:21]
	v_mfma_f32_16x16x32_bf16 v[26:29], v[90:93], v[94:97], v[26:29]
	v_mfma_f32_16x16x32_bf16 v[30:33], v[98:101], v[94:97], v[30:33]
	ds_read_b128 v[2:5], v126
	ds_read_b128 v[70:73], v118 offset:16384
	ds_read_b128 v[74:77], v126 offset:2048
	ds_read_b128 v[78:81], v118 offset:18432
	ds_read_b128 v[82:85], v126 offset:4096
	ds_read_b128 v[86:89], v118 offset:20480
	ds_read_b128 v[90:93], v126 offset:6144
	ds_read_b128 v[94:97], v118 offset:22528
	s_waitcnt lgkmcnt(6)
	v_mfma_f32_16x16x32_bf16 v[38:41], v[70:73], v[2:5], v[38:41]
	s_waitcnt lgkmcnt(4)
	v_mfma_f32_16x16x32_bf16 v[42:45], v[78:81], v[2:5], v[42:45]
	s_waitcnt lgkmcnt(2)
	v_mfma_f32_16x16x32_bf16 v[46:49], v[86:89], v[2:5], v[46:49]
	s_waitcnt lgkmcnt(0)
	v_mfma_f32_16x16x32_bf16 v[2:5], v[94:97], v[2:5], v[6:9]
	v_mfma_f32_16x16x32_bf16 v[6:9], v[70:73], v[74:77], v[34:37]
	v_mfma_f32_16x16x32_bf16 v[50:53], v[78:81], v[74:77], v[50:53]
	v_mfma_f32_16x16x32_bf16 v[54:57], v[86:89], v[74:77], v[54:57]
	v_mfma_f32_16x16x32_bf16 v[14:17], v[94:97], v[74:77], v[14:17]
	v_mfma_f32_16x16x32_bf16 v[58:61], v[70:73], v[82:85], v[58:61]
	v_mfma_f32_16x16x32_bf16 v[62:65], v[78:81], v[82:85], v[62:65]
	v_mfma_f32_16x16x32_bf16 v[66:69], v[86:89], v[82:85], v[66:69]
	v_mfma_f32_16x16x32_bf16 v[74:77], v[94:97], v[82:85], v[22:25]
	v_mfma_f32_16x16x32_bf16 v[10:13], v[70:73], v[90:93], v[10:13]
	v_mfma_f32_16x16x32_bf16 v[78:81], v[78:81], v[90:93], v[18:21]
	v_mfma_f32_16x16x32_bf16 v[82:85], v[86:89], v[90:93], v[26:29]
	v_mfma_f32_16x16x32_bf16 v[86:89], v[94:97], v[90:93], v[30:33]
	s_nop 2
	ds_read_b128 v[30:33], v114
	ds_read_b128 v[90:93], v115 offset:16384
	ds_read_b128 v[70:73], v114 offset:2048
	ds_read_b128 v[94:97], v115 offset:18432
	ds_read_b128 v[98:101], v114 offset:4096
	ds_read_b128 v[102:105], v115 offset:20480
	ds_read_b128 v[106:109], v114 offset:6144
	ds_read_b128 v[110:113], v115 offset:22528
	s_waitcnt vmcnt(0)
	s_waitcnt lgkmcnt(0)
	v_mfma_f32_16x16x32_bf16 v[18:21], v[90:93], v[30:33], v[38:41]
	s_barrier
; DEV unsigned cvt_pk_bf16(float lo, float hi) { const f32x2_t v = {lo, hi}; const bf16x2_t b = __builtin_convertvector(v, bf16x2_t); return __builtin_bit_cast(unsigned, b); }
; template <int WT, class Epi>
; DEV void gemm_tile(const bf16_t* __restrict__ A, int lda, const bf16_t* __restrict__ Bt, int ldb, int K, unsigned char* lds, const Epi& epi) {
;     ...
;         for (int kh = 0; kh < 2; ++kh) {
;             bf16x8 af[FI], bfr[FI];
;             const int ch = ((kh * 4 + fq) ^ sw) << 4;
; #pragma unroll
;             for (int i = 0; i < FI; ++i) { af[i] = *(const bf16x8*)(lds + cur + aoff + i * 2048 + ch); bfr[i] = *(const bf16x8*)(lds + cur + boff + i * 2048 + ch); }
; #pragma unroll
;             for (int mi = 0; mi < FI; ++mi)
; #pragma unroll
;                 for (int ni = 0; ni < FI; ++ni) acc[mi][ni] = __builtin_amdgcn_mfma_f32_16x16x32_bf16(bfr[ni], af[mi], acc[mi][ni], 0, 0, 0);
;     ...
;     if constexpr (Epi::STAGE) {
;         constexpr int RB = 4 * WT, CPR = RB / 16;
; #pragma unroll
;         for (int mi = 0; mi < FI; ++mi)
; #pragma unroll
;             for (int ni = 0; ni < FI; ++ni) {
;                 const int row = wr * WT + mi * 16 + fr, col = wc * WT + ni * 16 + fq * 4;
;                 const f32x4 v = epi.xform(row, col, acc[mi][ni]);
;                 uint2 w; w.x = cvt_pk_bf16(v[0], v[1]); w.y = cvt_pk_bf16(v[2], v[3]);
;                 *(uint2*)(lds + row * RB + ((((col >> 3) ^ (row & (CPR - 1))) << 4) | (((col >> 2) & 1) << 3))) = w;
	v_mfma_f32_16x16x32_bf16 v[22:25], v[94:97], v[30:33], v[42:45]
	v_mfma_f32_16x16x32_bf16 v[26:29], v[102:105], v[30:33], v[46:49]
	v_mfma_f32_16x16x32_bf16 v[30:33], v[110:113], v[30:33], v[2:5]
	v_mfma_f32_16x16x32_bf16 v[34:37], v[90:93], v[70:73], v[6:9]
	v_mfma_f32_16x16x32_bf16 v[38:41], v[94:97], v[70:73], v[50:53]
	v_mfma_f32_16x16x32_bf16 v[50:53], v[102:105], v[70:73], v[54:57]
	v_mfma_f32_16x16x32_bf16 v[54:57], v[110:113], v[70:73], v[14:17]
	v_mfma_f32_16x16x32_bf16 v[58:61], v[90:93], v[98:101], v[58:61]
	v_mfma_f32_16x16x32_bf16 v[62:65], v[94:97], v[98:101], v[62:65]
	v_mfma_f32_16x16x32_bf16 v[66:69], v[102:105], v[98:101], v[66:69]
	v_mfma_f32_16x16x32_bf16 v[70:73], v[110:113], v[98:101], v[74:77]
	v_mfma_f32_16x16x32_bf16 v[74:77], v[90:93], v[106:109], v[10:13]
	v_mfma_f32_16x16x32_bf16 v[78:81], v[94:97], v[106:109], v[78:81]
	v_mfma_f32_16x16x32_bf16 v[82:85], v[102:105], v[106:109], v[82:85]
	v_mfma_f32_16x16x32_bf16 v[86:89], v[110:113], v[106:109], v[86:89]
	ds_read_b128 v[2:5], v115 offset:55296
	ds_read_b128 v[42:45], v114 offset:38912
	ds_read_b128 v[6:9], v115 offset:53248
	ds_read_b128 v[14:17], v114 offset:36864
	ds_read_b128 v[10:13], v115 offset:51200
	ds_read_b128 v[90:93], v114 offset:34816
	ds_read_b128 v[46:49], v115 offset:49152
	ds_read_b128 v[94:97], v114 offset:32768
	ds_read_b128 v[98:101], v118 offset:55296
	ds_read_b128 v[102:105], v126 offset:38912
	ds_read_b128 v[106:109], v118 offset:53248
	ds_read_b128 v[114:117], v126 offset:36864
	ds_read_b128 v[110:113], v118 offset:51200
	ds_read_b128 v[122:125], v126 offset:34816
	ds_read_b128 v[118:121], v118 offset:49152
	ds_read_b128 v[126:129], v126 offset:32768
	s_waitcnt lgkmcnt(0)
	s_barrier
	v_mfma_f32_16x16x32_bf16 v[18:21], v[118:121], v[126:129], v[18:21]
	v_mfma_f32_16x16x32_bf16 v[22:25], v[110:113], v[126:129], v[22:25]
	v_mfma_f32_16x16x32_bf16 v[26:29], v[106:109], v[126:129], v[26:29]
	v_mfma_f32_16x16x32_bf16 v[30:33], v[98:101], v[126:129], v[30:33]
	v_mfma_f32_16x16x32_bf16 v[34:37], v[118:121], v[122:125], v[34:37]
	v_mfma_f32_16x16x32_bf16 v[38:41], v[110:113], v[122:125], v[38:41]
	v_mfma_f32_16x16x32_bf16 v[126:129], v[106:109], v[122:125], v[50:53]
	v_mfma_f32_16x16x32_bf16 v[122:125], v[98:101], v[122:125], v[54:57]
	v_mfma_f32_16x16x32_bf16 v[144:147], v[118:121], v[114:117], v[58:61]
	v_mfma_f32_16x16x32_bf16 v[148:151], v[110:113], v[114:117], v[62:65]
	v_mfma_f32_16x16x32_bf16 v[66:69], v[106:109], v[114:117], v[66:69]
	v_mfma_f32_16x16x32_bf16 v[70:73], v[98:101], v[114:117], v[70:73]
	v_mfma_f32_16x16x32_bf16 v[74:77], v[118:121], v[102:105], v[74:77]
	v_mfma_f32_16x16x32_bf16 v[78:81], v[110:113], v[102:105], v[78:81]
	v_mfma_f32_16x16x32_bf16 v[82:85], v[106:109], v[102:105], v[82:85]
	v_mfma_f32_16x16x32_bf16 v[86:89], v[98:101], v[102:105], v[86:89]
	v_mfma_f32_16x16x32_bf16 v[98:101], v[46:49], v[94:97], v[18:21]
	v_mfma_f32_16x16x32_bf16 v[102:105], v[10:13], v[94:97], v[22:25]
	v_mfma_f32_16x16x32_bf16 v[62:65], v[6:9], v[94:97], v[26:29]
	v_mfma_f32_16x16x32_bf16 v[58:61], v[2:5], v[94:97], v[30:33]
	v_mfma_f32_16x16x32_bf16 v[54:57], v[46:49], v[90:93], v[34:37]
	v_mfma_f32_16x16x32_bf16 v[50:53], v[10:13], v[90:93], v[38:41]
	v_mfma_f32_16x16x32_bf16 v[38:41], v[6:9], v[90:93], v[126:129]
	v_mfma_f32_16x16x32_bf16 v[34:37], v[2:5], v[90:93], v[122:125]
	v_lshl_add_u32 v90, v130, 8, s70
	v_mfma_f32_16x16x32_bf16 v[30:33], v[46:49], v[14:17], v[144:147]
	v_mfma_f32_16x16x32_bf16 v[26:29], v[10:13], v[14:17], v[148:151]
	v_mfma_f32_16x16x32_bf16 v[22:25], v[6:9], v[14:17], v[66:69]
	v_mfma_f32_16x16x32_bf16 v[18:21], v[2:5], v[14:17], v[70:73]
	v_mfma_f32_16x16x32_bf16 v[14:17], v[46:49], v[42:45], v[74:77]
	v_mfma_f32_16x16x32_bf16 v[10:13], v[10:13], v[42:45], v[78:81]
	v_mfma_f32_16x16x32_bf16 v[6:9], v[6:9], v[42:45], v[82:85]
	v_mfma_f32_16x16x32_bf16 v[2:5], v[2:5], v[42:45], v[86:89]
	v_lshrrev_b32_e32 v42, 1, v137
	s_nop 1
	v_lshl_or_b32 v88, v142, 2, v143
	v_and_b32_e32 v89, 8, v42
	v_add_u32_e32 v42, s81, v130
	v_or_b32_e32 v46, s68, v88
	v_mad_i64_i32 v[42:43], s[82:83], v42, s79, v[172:173]
	v_ashrrev_i32_e32 v47, 31, v46
	v_lshl_add_u64 v[82:83], v[42:43], 0, s[66:67]
	v_lshlrev_b64 v[68:69], 1, v[46:47]
	v_lshl_add_u64 v[42:43], v[82:83], 0, v[68:69]
	global_load_dwordx2 v[48:49], v[42:43], off
	v_lshl_add_u64 v[70:71], v[46:47], 2, s[4:5]
	global_load_dwordx4 v[42:45], v[70:71], off
	s_waitcnt vmcnt(1)
	v_lshlrev_b32_e32 v47, 16, v48
	v_and_b32_e32 v48, 0xffff0000, v48
	v_mul_f32_e32 v66, 0xbfb8aa3b, v47
	v_mul_f32_e32 v67, 0xbfb8aa3b, v48
	v_exp_f32_e32 v66, v66
	v_exp_f32_e32 v67, v67
	s_waitcnt vmcnt(0)
	v_pk_mul_f32 v[74:75], v[98:99], v[42:43]
	v_pk_mul_f32 v[72:73], v[100:101], v[44:45]
	v_pk_mul_f32 v[42:43], v[54:55], v[42:43]
	v_pk_add_f32 v[66:67], v[66:67], 1.0 op_sel_hi:[1,0]
	v_pk_mul_f32 v[44:45], v[56:57], v[44:45]


; DEV float bflo(unsigned u) { return __uint_as_float(u << 16); }
; DEV float bfhi(unsigned u) { return __uint_as_float(u & 0xffff0000u); }
; DEV float silu_f(float x) { return x / (1.f + __expf(-x)); }
;     DEV f32x4 xform(int r, int c, f32x4 v) const {
;     ...
;         o[2] = v[2] * s[2] * silu_f(bflo(z.y)); o[3] = v[3] * s[3] * silu_f(bfhi(z.y));
	s_nop 0


; DEV float bflo(unsigned u) { return __uint_as_float(u << 16); }
; DEV float bfhi(unsigned u) { return __uint_as_float(u & 0xffff0000u); }
; DEV float silu_f(float x) { return x / (1.f + __expf(-x)); }
;     DEV f32x4 xform(int r, int c, f32x4 v) const {
;     ...
;         o[2] = v[2] * s[2] * silu_f(bflo(z.y)); o[3] = v[3] * s[3] * silu_f(bfhi(z.y));
	v_rcp_f32_e32 v76, v67
	s_nop 0
	v_mul_f32_e32 v67, v48, v76


; DEV float bflo(unsigned u) { return __uint_as_float(u << 16); }
; DEV float bfhi(unsigned u) { return __uint_as_float(u & 0xffff0000u); }
; DEV float silu_f(float x) { return x / (1.f + __expf(-x)); }
;     DEV f32x4 xform(int r, int c, f32x4 v) const {
;     ...
;         o[2] = v[2] * s[2] * silu_f(bflo(z.y)); o[3] = v[3] * s[3] * silu_f(bfhi(z.y));
	s_nop 0


; DEV unsigned cvt_pk_bf16(float lo, float hi) { const f32x2_t v = {lo, hi}; const bf16x2_t b = __builtin_convertvector(v, bf16x2_t); return __builtin_bit_cast(unsigned, b); }
; DEV float bflo(unsigned u) { return __uint_as_float(u << 16); }
; DEV float bfhi(unsigned u) { return __uint_as_float(u & 0xffff0000u); }
; DEV float silu_f(float x) { return x / (1.f + __expf(-x)); }
; template <int WT, class Epi>
; DEV void gemm_tile(const bf16_t* __restrict__ A, int lda, const bf16_t* __restrict__ Bt, int ldb, int K, unsigned char* lds, const Epi& epi) {
;     ...
;                 uint2 w; w.x = cvt_pk_bf16(v[0], v[1]); w.y = cvt_pk_bf16(v[2], v[3]);
;                 *(uint2*)(lds + row * RB + ((((col >> 3) ^ (row & (CPR - 1))) << 4) | (((col >> 2) & 1) << 3))) = w;
;     DEV f32x4 xform(int r, int c, f32x4 v) const {
;     ...
;         o[2] = v[2] * s[2] * silu_f(bflo(z.y)); o[3] = v[3] * s[3] * silu_f(bfhi(z.y));
	v_rcp_f32_e32 v48, v66
	s_nop 0
	v_mul_f32_e32 v66, v47, v48
	v_pk_mul_f32 v[66:67], v[74:75], v[66:67]
	v_lshlrev_b32_e32 v47, 16, v49
	v_and_b32_e32 v74, 0xffff0000, v49
	v_mul_f32_e32 v48, 0xbfb8aa3b, v47
	v_mul_f32_e32 v49, 0xbfb8aa3b, v74
	v_exp_f32_e32 v48, v48
	v_exp_f32_e32 v49, v49
	v_cvt_pk_bf16_f32 v66, v66, v67
	v_pk_add_f32 v[48:49], v[48:49], 1.0 op_sel_hi:[1,0]
	s_nop 0


; DEV float bflo(unsigned u) { return __uint_as_float(u << 16); }
; DEV float bfhi(unsigned u) { return __uint_as_float(u & 0xffff0000u); }
; DEV float silu_f(float x) { return x / (1.f + __expf(-x)); }
;     DEV f32x4 xform(int r, int c, f32x4 v) const {
;     ...
;         o[2] = v[2] * s[2] * silu_f(bflo(z.y)); o[3] = v[3] * s[3] * silu_f(bfhi(z.y));
	s_nop 0


; DEV float bflo(unsigned u) { return __uint_as_float(u << 16); }
; DEV float bfhi(unsigned u) { return __uint_as_float(u & 0xffff0000u); }
; DEV float silu_f(float x) { return x / (1.f + __expf(-x)); }
;     DEV f32x4 xform(int r, int c, f32x4 v) const {
;     ...
;         o[2] = v[2] * s[2] * silu_f(bflo(z.y)); o[3] = v[3] * s[3] * silu_f(bfhi(z.y));
	v_rcp_f32_e32 v75, v49
	s_nop 0
	v_mul_f32_e32 v49, v74, v75


; DEV float bflo(unsigned u) { return __uint_as_float(u << 16); }
; DEV float bfhi(unsigned u) { return __uint_as_float(u & 0xffff0000u); }
; DEV float silu_f(float x) { return x / (1.f + __expf(-x)); }
;     DEV f32x4 xform(int r, int c, f32x4 v) const {
;     ...
;         o[2] = v[2] * s[2] * silu_f(bflo(z.y)); o[3] = v[3] * s[3] * silu_f(bfhi(z.y));
	s_nop 0


; DEV unsigned cvt_pk_bf16(float lo, float hi) { const f32x2_t v = {lo, hi}; const bf16x2_t b = __builtin_convertvector(v, bf16x2_t); return __builtin_bit_cast(unsigned, b); }
; DEV float bflo(unsigned u) { return __uint_as_float(u << 16); }
; DEV float bfhi(unsigned u) { return __uint_as_float(u & 0xffff0000u); }
; DEV float silu_f(float x) { return x / (1.f + __expf(-x)); }
; template <int WT, class Epi>
; DEV void gemm_tile(const bf16_t* __restrict__ A, int lda, const bf16_t* __restrict__ Bt, int ldb, int K, unsigned char* lds, const Epi& epi) {
;     ...
;                 uint2 w; w.x = cvt_pk_bf16(v[0], v[1]); w.y = cvt_pk_bf16(v[2], v[3]);
;                 *(uint2*)(lds + row * RB + ((((col >> 3) ^ (row & (CPR - 1))) << 4) | (((col >> 2) & 1) << 3))) = w;
;     DEV f32x4 xform(int r, int c, f32x4 v) const {
;     ...
;         o[2] = v[2] * s[2] * silu_f(bflo(z.y)); o[3] = v[3] * s[3] * silu_f(bfhi(z.y));
	v_rcp_f32_e32 v74, v48
	s_nop 0
	v_mul_f32_e32 v48, v47, v74
	v_pk_mul_f32 v[48:49], v[72:73], v[48:49]
	v_or_b32_e32 v77, 16, v88
	v_cvt_pk_bf16_f32 v67, v48, v49
	v_or_b32_e32 v48, s68, v77
	v_ashrrev_i32_e32 v49, 31, v48
	v_lshlrev_b64 v[72:73], 1, v[48:49]
	v_lshl_add_u64 v[48:49], v[82:83], 0, v[72:73]
	global_load_dwordx2 v[74:75], v[48:49], off
	v_lshrrev_b32_e32 v47, 3, v88
	v_bitop3_b32 v47, v47, v137, 15 bitop3:0x78
	v_lshl_or_b32 v76, v47, 4, v89
	v_add_u32_e32 v47, v90, v76
	ds_write_b64 v47, v[66:67]
	v_mov_b32_e32 v47, s69
	v_lshl_add_u64 v[66:67], v[46:47], 2, s[4:5]
	global_load_dwordx4 v[46:49], v[66:67], off offset:64
	s_waitcnt vmcnt(1)
	v_lshlrev_b32_e32 v86, 16, v74
	v_and_b32_e32 v74, 0xffff0000, v74
	v_mul_f32_e32 v78, 0xbfb8aa3b, v86
	v_mul_f32_e32 v79, 0xbfb8aa3b, v74
	v_exp_f32_e32 v78, v78
	v_exp_f32_e32 v79, v79
	s_waitcnt vmcnt(0)
	v_pk_mul_f32 v[84:85], v[102:103], v[46:47]
	v_pk_add_f32 v[78:79], v[78:79], 1.0 op_sel_hi:[1,0]
	v_pk_mul_f32 v[80:81], v[104:105], v[48:49]


; DEV float bflo(unsigned u) { return __uint_as_float(u << 16); }
; DEV float bfhi(unsigned u) { return __uint_as_float(u & 0xffff0000u); }
; DEV float silu_f(float x) { return x / (1.f + __expf(-x)); }
;     DEV f32x4 xform(int r, int c, f32x4 v) const {
;     ...
;         o[2] = v[2] * s[2] * silu_f(bflo(z.y)); o[3] = v[3] * s[3] * silu_f(bfhi(z.y));
	v_pk_mul_f32 v[46:47], v[50:51], v[46:47]
	v_pk_mul_f32 v[48:49], v[52:53], v[48:49]


; DEV float bflo(unsigned u) { return __uint_as_float(u << 16); }
; DEV float bfhi(unsigned u) { return __uint_as_float(u & 0xffff0000u); }
; DEV float silu_f(float x) { return x / (1.f + __expf(-x)); }
;     DEV f32x4 xform(int r, int c, f32x4 v) const {
;     ...
;         o[2] = v[2] * s[2] * silu_f(bflo(z.y)); o[3] = v[3] * s[3] * silu_f(bfhi(z.y));
	v_rcp_f32_e32 v87, v79
	s_nop 0
	v_mul_f32_e32 v79, v74, v87


; DEV float bflo(unsigned u) { return __uint_as_float(u << 16); }
; DEV float bfhi(unsigned u) { return __uint_as_float(u & 0xffff0000u); }
; DEV float silu_f(float x) { return x / (1.f + __expf(-x)); }
;     DEV f32x4 xform(int r, int c, f32x4 v) const {
;     ...
;         o[2] = v[2] * s[2] * silu_f(bflo(z.y)); o[3] = v[3] * s[3] * silu_f(bfhi(z.y));
	s_nop 0


; DEV unsigned cvt_pk_bf16(float lo, float hi) { const f32x2_t v = {lo, hi}; const bf16x2_t b = __builtin_convertvector(v, bf16x2_t); return __builtin_bit_cast(unsigned, b); }
; DEV float bflo(unsigned u) { return __uint_as_float(u << 16); }
; DEV float bfhi(unsigned u) { return __uint_as_float(u & 0xffff0000u); }
; DEV float silu_f(float x) { return x / (1.f + __expf(-x)); }
; template <int WT, class Epi>
; DEV void gemm_tile(const bf16_t* __restrict__ A, int lda, const bf16_t* __restrict__ Bt, int ldb, int K, unsigned char* lds, const Epi& epi) {
;     ...
;                 uint2 w; w.x = cvt_pk_bf16(v[0], v[1]); w.y = cvt_pk_bf16(v[2], v[3]);
;     DEV f32x4 xform(int r, int c, f32x4 v) const {
;     ...
;         o[2] = v[2] * s[2] * silu_f(bflo(z.y)); o[3] = v[3] * s[3] * silu_f(bfhi(z.y));
	v_rcp_f32_e32 v74, v78
	s_nop 0
	v_mul_f32_e32 v78, v86, v74
	v_pk_mul_f32 v[78:79], v[84:85], v[78:79]
	v_lshlrev_b32_e32 v84, 16, v75
	v_and_b32_e32 v85, 0xffff0000, v75
	v_mul_f32_e32 v74, 0xbfb8aa3b, v84
	v_mul_f32_e32 v75, 0xbfb8aa3b, v85
	v_exp_f32_e32 v74, v74
	v_exp_f32_e32 v75, v75
	v_cvt_pk_bf16_f32 v78, v78, v79
	v_pk_add_f32 v[74:75], v[74:75], 1.0 op_sel_hi:[1,0]
	s_nop 0


; DEV float bflo(unsigned u) { return __uint_as_float(u << 16); }
; DEV float bfhi(unsigned u) { return __uint_as_float(u & 0xffff0000u); }
; DEV float silu_f(float x) { return x / (1.f + __expf(-x)); }
;     DEV f32x4 xform(int r, int c, f32x4 v) const {
;     ...
;         o[0] = v[0] * s[0] * silu_f(bflo(z.x)); o[1] = v[1] * s[1] * silu_f(bfhi(z.x));
;         o[2] = v[2] * s[2] * silu_f(bflo(z.y)); o[3] = v[3] * s[3] * silu_f(bfhi(z.y));
	s_nop 0


; DEV float bflo(unsigned u) { return __uint_as_float(u << 16); }
; DEV float bfhi(unsigned u) { return __uint_as_float(u & 0xffff0000u); }
; DEV float silu_f(float x) { return x / (1.f + __expf(-x)); }
;     DEV f32x4 xform(int r, int c, f32x4 v) const {
;     ...
;         o[0] = v[0] * s[0] * silu_f(bflo(z.x)); o[1] = v[1] * s[1] * silu_f(bfhi(z.x));
;         o[2] = v[2] * s[2] * silu_f(bflo(z.y)); o[3] = v[3] * s[3] * silu_f(bfhi(z.y));
	v_rcp_f32_e32 v86, v75
	s_nop 0
	v_mul_f32_e32 v75, v85, v86


; DEV float bflo(unsigned u) { return __uint_as_float(u << 16); }
; DEV float bfhi(unsigned u) { return __uint_as_float(u & 0xffff0000u); }
; DEV float silu_f(float x) { return x / (1.f + __expf(-x)); }
;     DEV f32x4 xform(int r, int c, f32x4 v) const {
;     ...
;         o[0] = v[0] * s[0] * silu_f(bflo(z.x)); o[1] = v[1] * s[1] * silu_f(bfhi(z.x));
;         o[2] = v[2] * s[2] * silu_f(bflo(z.y)); o[3] = v[3] * s[3] * silu_f(bfhi(z.y));
	s_nop 0


; DEV unsigned cvt_pk_bf16(float lo, float hi) { const f32x2_t v = {lo, hi}; const bf16x2_t b = __builtin_convertvector(v, bf16x2_t); return __builtin_bit_cast(unsigned, b); }
; DEV float bflo(unsigned u) { return __uint_as_float(u << 16); }
; DEV float bfhi(unsigned u) { return __uint_as_float(u & 0xffff0000u); }
; DEV float silu_f(float x) { return x / (1.f + __expf(-x)); }
; template <int WT, class Epi>
; DEV void gemm_tile(const bf16_t* __restrict__ A, int lda, const bf16_t* __restrict__ Bt, int ldb, int K, unsigned char* lds, const Epi& epi) {
;     ...
;                 const int row = wr * WT + mi * 16 + fr, col = wc * WT + ni * 16 + fq * 4;
;                 const f32x4 v = epi.xform(row, col, acc[mi][ni]);
;                 uint2 w; w.x = cvt_pk_bf16(v[0], v[1]); w.y = cvt_pk_bf16(v[2], v[3]);
;                 *(uint2*)(lds + row * RB + ((((col >> 3) ^ (row & (CPR - 1))) << 4) | (((col >> 2) & 1) << 3))) = w;
;     DEV f32x4 xform(int r, int c, f32x4 v) const {
;         const int row = m0 + r, col = n0 + c;
;         const uint2 z = *(const uint2*)(proj + (size_t)row * NPJ + C_ZB + col);
;         const f32x4 s = *(const f32x4*)(scale + col);
;         f32x4 o;
;         o[0] = v[0] * s[0] * silu_f(bflo(z.x)); o[1] = v[1] * s[1] * silu_f(bfhi(z.x));
;         o[2] = v[2] * s[2] * silu_f(bflo(z.y)); o[3] = v[3] * s[3] * silu_f(bfhi(z.y));
	v_rcp_f32_e32 v85, v74
	s_nop 0
	v_mul_f32_e32 v74, v84, v85
	v_pk_mul_f32 v[74:75], v[80:81], v[74:75]
	v_or_b32_e32 v91, 32, v88
	v_cvt_pk_bf16_f32 v79, v74, v75
	v_lshrrev_b32_e32 v74, 3, v77
	v_bitop3_b32 v74, v74, v137, 15 bitop3:0x78
	v_lshl_or_b32 v77, v74, 4, v89
	v_add_u32_e32 v74, v90, v77
	ds_write_b64 v74, v[78:79]
	v_or_b32_e32 v74, s68, v91
	v_ashrrev_i32_e32 v75, 31, v74
	v_lshlrev_b64 v[74:75], 1, v[74:75]
	v_lshl_add_u64 v[78:79], v[82:83], 0, v[74:75]
	global_load_dwordx2 v[84:85], v[78:79], off
	s_nop 0
	global_load_dwordx4 v[78:81], v[66:67], off offset:128
	s_waitcnt vmcnt(1)
	v_lshlrev_b32_e32 v92, 16, v84
	v_and_b32_e32 v84, 0xffff0000, v84
	v_mul_f32_e32 v86, 0xbfb8aa3b, v92
	s_waitcnt vmcnt(0)
	v_pk_mul_f32 v[62:63], v[62:63], v[78:79]
	v_mul_f32_e32 v78, 0xbfb8aa3b, v84
	v_exp_f32_e32 v86, v86
	v_exp_f32_e32 v87, v78
	v_pk_mul_f32 v[64:65], v[64:65], v[80:81]
	v_pk_add_f32 v[78:79], v[86:87], 1.0 op_sel_hi:[1,0]
	s_nop 0


; DEV float bflo(unsigned u) { return __uint_as_float(u << 16); }
; DEV float bfhi(unsigned u) { return __uint_as_float(u & 0xffff0000u); }
; DEV float silu_f(float x) { return x / (1.f + __expf(-x)); }
;     DEV f32x4 xform(int r, int c, f32x4 v) const {
;     ...
;         o[0] = v[0] * s[0] * silu_f(bflo(z.x)); o[1] = v[1] * s[1] * silu_f(bfhi(z.x));
;         o[2] = v[2] * s[2] * silu_f(bflo(z.y)); o[3] = v[3] * s[3] * silu_f(bfhi(z.y));
	s_nop 0


; DEV float bflo(unsigned u) { return __uint_as_float(u << 16); }
; DEV float bfhi(unsigned u) { return __uint_as_float(u & 0xffff0000u); }
; DEV float silu_f(float x) { return x / (1.f + __expf(-x)); }
;     DEV f32x4 xform(int r, int c, f32x4 v) const {
;     ...
;         o[0] = v[0] * s[0] * silu_f(bflo(z.x)); o[1] = v[1] * s[1] * silu_f(bfhi(z.x));
;         o[2] = v[2] * s[2] * silu_f(bflo(z.y)); o[3] = v[3] * s[3] * silu_f(bfhi(z.y));
	v_rcp_f32_e32 v80, v79
	s_nop 0
	v_mul_f32_e32 v79, v84, v80


; DEV float bflo(unsigned u) { return __uint_as_float(u << 16); }
; DEV float bfhi(unsigned u) { return __uint_as_float(u & 0xffff0000u); }
; DEV float silu_f(float x) { return x / (1.f + __expf(-x)); }
;     DEV f32x4 xform(int r, int c, f32x4 v) const {
;     ...
;         o[0] = v[0] * s[0] * silu_f(bflo(z.x)); o[1] = v[1] * s[1] * silu_f(bfhi(z.x));
;         o[2] = v[2] * s[2] * silu_f(bflo(z.y)); o[3] = v[3] * s[3] * silu_f(bfhi(z.y));
	s_nop 0


; DEV float bflo(unsigned u) { return __uint_as_float(u << 16); }
; DEV float bfhi(unsigned u) { return __uint_as_float(u & 0xffff0000u); }
; DEV float silu_f(float x) { return x / (1.f + __expf(-x)); }
;     DEV f32x4 xform(int r, int c, f32x4 v) const {
;         const int row = m0 + r, col = n0 + c;
;         const uint2 z = *(const uint2*)(proj + (size_t)row * NPJ + C_ZB + col);
;         const f32x4 s = *(const f32x4*)(scale + col);
;         f32x4 o;
;         o[0] = v[0] * s[0] * silu_f(bflo(z.x)); o[1] = v[1] * s[1] * silu_f(bfhi(z.x));
;         o[2] = v[2] * s[2] * silu_f(bflo(z.y)); o[3] = v[3] * s[3] * silu_f(bfhi(z.y));
	v_rcp_f32_e32 v80, v78
	s_nop 0
	v_mul_f32_e32 v78, v92, v80
	v_lshlrev_b32_e32 v80, 16, v85
	v_and_b32_e32 v81, 0xffff0000, v85
	v_pk_mul_f32 v[62:63], v[62:63], v[78:79]
	v_mul_f32_e32 v78, 0xbfb8aa3b, v80
	v_mul_f32_e32 v79, 0xbfb8aa3b, v81
	v_exp_f32_e32 v78, v78
	v_exp_f32_e32 v79, v79
	v_cvt_pk_bf16_f32 v62, v62, v63
	v_pk_add_f32 v[78:79], v[78:79], 1.0 op_sel_hi:[1,0]
	s_nop 0


; DEV float bflo(unsigned u) { return __uint_as_float(u << 16); }
; DEV float bfhi(unsigned u) { return __uint_as_float(u & 0xffff0000u); }
; DEV float silu_f(float x) { return x / (1.f + __expf(-x)); }
;     DEV f32x4 xform(int r, int c, f32x4 v) const {
;     ...
;         o[0] = v[0] * s[0] * silu_f(bflo(z.x)); o[1] = v[1] * s[1] * silu_f(bfhi(z.x));
;         o[2] = v[2] * s[2] * silu_f(bflo(z.y)); o[3] = v[3] * s[3] * silu_f(bfhi(z.y));
	s_nop 0


; DEV float bflo(unsigned u) { return __uint_as_float(u << 16); }
; DEV float bfhi(unsigned u) { return __uint_as_float(u & 0xffff0000u); }
; DEV float silu_f(float x) { return x / (1.f + __expf(-x)); }
;     DEV f32x4 xform(int r, int c, f32x4 v) const {
;     ...
;         o[0] = v[0] * s[0] * silu_f(bflo(z.x)); o[1] = v[1] * s[1] * silu_f(bfhi(z.x));
;         o[2] = v[2] * s[2] * silu_f(bflo(z.y)); o[3] = v[3] * s[3] * silu_f(bfhi(z.y));
	v_rcp_f32_e32 v84, v79
	s_nop 0
	v_mul_f32_e32 v79, v81, v84


; DEV float bflo(unsigned u) { return __uint_as_float(u << 16); }
; DEV float bfhi(unsigned u) { return __uint_as_float(u & 0xffff0000u); }
; DEV float silu_f(float x) { return x / (1.f + __expf(-x)); }
;     DEV f32x4 xform(int r, int c, f32x4 v) const {
;     ...
;         o[0] = v[0] * s[0] * silu_f(bflo(z.x)); o[1] = v[1] * s[1] * silu_f(bfhi(z.x));
;         o[2] = v[2] * s[2] * silu_f(bflo(z.y)); o[3] = v[3] * s[3] * silu_f(bfhi(z.y));
	s_nop 0


; DEV unsigned cvt_pk_bf16(float lo, float hi) { const f32x2_t v = {lo, hi}; const bf16x2_t b = __builtin_convertvector(v, bf16x2_t); return __builtin_bit_cast(unsigned, b); }
; DEV float bflo(unsigned u) { return __uint_as_float(u << 16); }
; DEV float bfhi(unsigned u) { return __uint_as_float(u & 0xffff0000u); }
; DEV float silu_f(float x) { return x / (1.f + __expf(-x)); }
; template <int WT, class Epi>
; DEV void gemm_tile(const bf16_t* __restrict__ A, int lda, const bf16_t* __restrict__ Bt, int ldb, int K, unsigned char* lds, const Epi& epi) {
;     ...
;                 const int row = wr * WT + mi * 16 + fr, col = wc * WT + ni * 16 + fq * 4;
;                 const f32x4 v = epi.xform(row, col, acc[mi][ni]);
;                 uint2 w; w.x = cvt_pk_bf16(v[0], v[1]); w.y = cvt_pk_bf16(v[2], v[3]);
;                 *(uint2*)(lds + row * RB + ((((col >> 3) ^ (row & (CPR - 1))) << 4) | (((col >> 2) & 1) << 3))) = w;
;     DEV f32x4 xform(int r, int c, f32x4 v) const {
;         const int row = m0 + r, col = n0 + c;
;         const uint2 z = *(const uint2*)(proj + (size_t)row * NPJ + C_ZB + col);
;         const f32x4 s = *(const f32x4*)(scale + col);
;         f32x4 o;
;         o[0] = v[0] * s[0] * silu_f(bflo(z.x)); o[1] = v[1] * s[1] * silu_f(bfhi(z.x));
;         o[2] = v[2] * s[2] * silu_f(bflo(z.y)); o[3] = v[3] * s[3] * silu_f(bfhi(z.y));
	v_rcp_f32_e32 v81, v78
	s_nop 0
	v_mul_f32_e32 v78, v80, v81
	v_pk_mul_f32 v[64:65], v[64:65], v[78:79]
	s_nop 0
	v_cvt_pk_bf16_f32 v63, v64, v65
	v_lshrrev_b32_e32 v64, 3, v91
	v_bitop3_b32 v64, v64, v137, 15 bitop3:0x78
	v_lshl_or_b32 v64, v64, 4, v89
	v_add_u32_e32 v65, v90, v64
	ds_write_b64 v65, v[62:63]
	v_or_b32_e32 v65, 48, v88
	v_or_b32_e32 v62, s68, v65
	v_ashrrev_i32_e32 v63, 31, v62
	v_lshlrev_b64 v[62:63], 1, v[62:63]
	v_lshl_add_u64 v[78:79], v[82:83], 0, v[62:63]
	global_load_dwordx2 v[82:83], v[78:79], off
	s_nop 0
	global_load_dwordx4 v[78:81], v[66:67], off offset:192
	s_waitcnt vmcnt(1)
	v_lshlrev_b32_e32 v86, 16, v82
	v_and_b32_e32 v82, 0xffff0000, v82
	v_mul_f32_e32 v84, 0xbfb8aa3b, v86
	s_waitcnt vmcnt(0)
	v_pk_mul_f32 v[58:59], v[58:59], v[78:79]
	v_mul_f32_e32 v78, 0xbfb8aa3b, v82
	v_exp_f32_e32 v84, v84
	v_exp_f32_e32 v85, v78
	v_pk_mul_f32 v[60:61], v[60:61], v[80:81]
	v_pk_add_f32 v[78:79], v[84:85], 1.0 op_sel_hi:[1,0]
	s_nop 0


; DEV float bflo(unsigned u) { return __uint_as_float(u << 16); }
; DEV float bfhi(unsigned u) { return __uint_as_float(u & 0xffff0000u); }
; DEV float silu_f(float x) { return x / (1.f + __expf(-x)); }
;     DEV f32x4 xform(int r, int c, f32x4 v) const {
;     ...
;         o[0] = v[0] * s[0] * silu_f(bflo(z.x)); o[1] = v[1] * s[1] * silu_f(bfhi(z.x));
;         o[2] = v[2] * s[2] * silu_f(bflo(z.y)); o[3] = v[3] * s[3] * silu_f(bfhi(z.y));
	s_nop 0


; DEV float bflo(unsigned u) { return __uint_as_float(u << 16); }
; DEV float bfhi(unsigned u) { return __uint_as_float(u & 0xffff0000u); }
; DEV float silu_f(float x) { return x / (1.f + __expf(-x)); }
;     DEV f32x4 xform(int r, int c, f32x4 v) const {
;     ...
;         o[0] = v[0] * s[0] * silu_f(bflo(z.x)); o[1] = v[1] * s[1] * silu_f(bfhi(z.x));
;         o[2] = v[2] * s[2] * silu_f(bflo(z.y)); o[3] = v[3] * s[3] * silu_f(bfhi(z.y));
	v_rcp_f32_e32 v80, v79
	s_nop 0
	v_mul_f32_e32 v79, v82, v80


; DEV float bflo(unsigned u) { return __uint_as_float(u << 16); }
; DEV float bfhi(unsigned u) { return __uint_as_float(u & 0xffff0000u); }
; DEV float silu_f(float x) { return x / (1.f + __expf(-x)); }
;     DEV f32x4 xform(int r, int c, f32x4 v) const {
;     ...
;         o[0] = v[0] * s[0] * silu_f(bflo(z.x)); o[1] = v[1] * s[1] * silu_f(bfhi(z.x));
;         o[2] = v[2] * s[2] * silu_f(bflo(z.y)); o[3] = v[3] * s[3] * silu_f(bfhi(z.y));
	s_nop 0


; DEV float bflo(unsigned u) { return __uint_as_float(u << 16); }
; DEV float bfhi(unsigned u) { return __uint_as_float(u & 0xffff0000u); }
; DEV float silu_f(float x) { return x / (1.f + __expf(-x)); }
;     DEV f32x4 xform(int r, int c, f32x4 v) const {
;         const int row = m0 + r, col = n0 + c;
;         const uint2 z = *(const uint2*)(proj + (size_t)row * NPJ + C_ZB + col);
;         const f32x4 s = *(const f32x4*)(scale + col);
;         f32x4 o;
;         o[0] = v[0] * s[0] * silu_f(bflo(z.x)); o[1] = v[1] * s[1] * silu_f(bfhi(z.x));
;         o[2] = v[2] * s[2] * silu_f(bflo(z.y)); o[3] = v[3] * s[3] * silu_f(bfhi(z.y));
	v_rcp_f32_e32 v80, v78
	s_nop 0
	v_mul_f32_e32 v78, v86, v80
	v_lshlrev_b32_e32 v80, 16, v83
	v_and_b32_e32 v81, 0xffff0000, v83
	v_pk_mul_f32 v[58:59], v[58:59], v[78:79]
	v_mul_f32_e32 v78, 0xbfb8aa3b, v80
	v_mul_f32_e32 v79, 0xbfb8aa3b, v81
	v_exp_f32_e32 v78, v78
	v_exp_f32_e32 v79, v79
	s_nop 0
	v_pk_add_f32 v[78:79], v[78:79], 1.0 op_sel_hi:[1,0]
	s_nop 0


; DEV float bflo(unsigned u) { return __uint_as_float(u << 16); }
; DEV float bfhi(unsigned u) { return __uint_as_float(u & 0xffff0000u); }
; DEV float silu_f(float x) { return x / (1.f + __expf(-x)); }
;     DEV f32x4 xform(int r, int c, f32x4 v) const {
;     ...
;         o[0] = v[0] * s[0] * silu_f(bflo(z.x)); o[1] = v[1] * s[1] * silu_f(bfhi(z.x));
;         o[2] = v[2] * s[2] * silu_f(bflo(z.y)); o[3] = v[3] * s[3] * silu_f(bfhi(z.y));
	s_nop 0


; DEV float bflo(unsigned u) { return __uint_as_float(u << 16); }
; DEV float bfhi(unsigned u) { return __uint_as_float(u & 0xffff0000u); }
; DEV float silu_f(float x) { return x / (1.f + __expf(-x)); }
;     DEV f32x4 xform(int r, int c, f32x4 v) const {
;     ...
;         o[0] = v[0] * s[0] * silu_f(bflo(z.x)); o[1] = v[1] * s[1] * silu_f(bfhi(z.x));
;         o[2] = v[2] * s[2] * silu_f(bflo(z.y)); o[3] = v[3] * s[3] * silu_f(bfhi(z.y));
	v_rcp_f32_e32 v82, v79
	s_nop 0
	v_mul_f32_e32 v79, v81, v82


; DEV float bflo(unsigned u) { return __uint_as_float(u << 16); }
; DEV float bfhi(unsigned u) { return __uint_as_float(u & 0xffff0000u); }
; DEV float silu_f(float x) { return x / (1.f + __expf(-x)); }
;     DEV f32x4 xform(int r, int c, f32x4 v) const {
;     ...
;         o[0] = v[0] * s[0] * silu_f(bflo(z.x)); o[1] = v[1] * s[1] * silu_f(bfhi(z.x));
;         o[2] = v[2] * s[2] * silu_f(bflo(z.y)); o[3] = v[3] * s[3] * silu_f(bfhi(z.y));
	s_nop 0


; DEV unsigned cvt_pk_bf16(float lo, float hi) { const f32x2_t v = {lo, hi}; const bf16x2_t b = __builtin_convertvector(v, bf16x2_t); return __builtin_bit_cast(unsigned, b); }
; DEV float bflo(unsigned u) { return __uint_as_float(u << 16); }
; DEV float bfhi(unsigned u) { return __uint_as_float(u & 0xffff0000u); }
; DEV float silu_f(float x) { return x / (1.f + __expf(-x)); }
; template <int WT, class Epi>
; DEV void gemm_tile(const bf16_t* __restrict__ A, int lda, const bf16_t* __restrict__ Bt, int ldb, int K, unsigned char* lds, const Epi& epi) {
;     ...
;                 const int row = wr * WT + mi * 16 + fr, col = wc * WT + ni * 16 + fq * 4;
;                 const f32x4 v = epi.xform(row, col, acc[mi][ni]);
;                 uint2 w; w.x = cvt_pk_bf16(v[0], v[1]); w.y = cvt_pk_bf16(v[2], v[3]);
;                 *(uint2*)(lds + row * RB + ((((col >> 3) ^ (row & (CPR - 1))) << 4) | (((col >> 2) & 1) << 3))) = w;
;     DEV f32x4 xform(int r, int c, f32x4 v) const {
;         const int row = m0 + r, col = n0 + c;
;         const uint2 z = *(const uint2*)(proj + (size_t)row * NPJ + C_ZB + col);
;         const f32x4 s = *(const f32x4*)(scale + col);
;         f32x4 o;
;         o[0] = v[0] * s[0] * silu_f(bflo(z.x)); o[1] = v[1] * s[1] * silu_f(bfhi(z.x));
;         o[2] = v[2] * s[2] * silu_f(bflo(z.y)); o[3] = v[3] * s[3] * silu_f(bfhi(z.y));
	v_rcp_f32_e32 v81, v78
	s_nop 0
	v_mul_f32_e32 v78, v80, v81
	v_pk_mul_f32 v[60:61], v[60:61], v[78:79]
	v_cvt_pk_bf16_f32 v78, v58, v59
	v_lshrrev_b32_e32 v58, 3, v65
	v_bitop3_b32 v58, v58, v137, 15 bitop3:0x78
	v_lshl_or_b32 v58, v58, 4, v89
	v_cvt_pk_bf16_f32 v79, v60, v61
	v_add_u32_e32 v59, v90, v58
	ds_write_b64 v59, v[78:79]
	v_or_b32_e32 v59, 16, v130
	v_lshl_add_u32 v65, v59, 8, s70
	v_add_u32_e32 v59, s81, v59
	v_mad_i64_i32 v[60:61], s[68:69], v59, s79, v[172:173]
	v_lshl_add_u64 v[60:61], v[60:61], 0, s[66:67]
	v_lshl_add_u64 v[78:79], v[60:61], 0, v[68:69]
	global_load_dwordx2 v[78:79], v[78:79], off
	s_waitcnt vmcnt(0)
	v_lshlrev_b32_e32 v59, 16, v78
	v_and_b32_e32 v78, 0xffff0000, v78
	v_mul_f32_e32 v80, 0xbfb8aa3b, v59
	v_mul_f32_e32 v54, 0xbfb8aa3b, v78
	v_exp_f32_e32 v80, v80
	v_exp_f32_e32 v81, v54
	s_nop 0
	v_pk_add_f32 v[54:55], v[80:81], 1.0 op_sel_hi:[1,0]
	s_nop 0


; DEV float bflo(unsigned u) { return __uint_as_float(u << 16); }
; DEV float bfhi(unsigned u) { return __uint_as_float(u & 0xffff0000u); }
; DEV float silu_f(float x) { return x / (1.f + __expf(-x)); }
;     DEV f32x4 xform(int r, int c, f32x4 v) const {
;     ...
;         o[0] = v[0] * s[0] * silu_f(bflo(z.x)); o[1] = v[1] * s[1] * silu_f(bfhi(z.x));
;         o[2] = v[2] * s[2] * silu_f(bflo(z.y)); o[3] = v[3] * s[3] * silu_f(bfhi(z.y));
	s_nop 0


; DEV float bflo(unsigned u) { return __uint_as_float(u << 16); }
; DEV float bfhi(unsigned u) { return __uint_as_float(u & 0xffff0000u); }
; DEV float silu_f(float x) { return x / (1.f + __expf(-x)); }
;     DEV f32x4 xform(int r, int c, f32x4 v) const {
;     ...
;         o[0] = v[0] * s[0] * silu_f(bflo(z.x)); o[1] = v[1] * s[1] * silu_f(bfhi(z.x));
;         o[2] = v[2] * s[2] * silu_f(bflo(z.y)); o[3] = v[3] * s[3] * silu_f(bfhi(z.y));
	v_rcp_f32_e32 v56, v55
	s_nop 0
	v_mul_f32_e32 v55, v78, v56


; DEV float bflo(unsigned u) { return __uint_as_float(u << 16); }
; DEV float bfhi(unsigned u) { return __uint_as_float(u & 0xffff0000u); }
; DEV float silu_f(float x) { return x / (1.f + __expf(-x)); }
;     DEV f32x4 xform(int r, int c, f32x4 v) const {
;     ...
;         o[0] = v[0] * s[0] * silu_f(bflo(z.x)); o[1] = v[1] * s[1] * silu_f(bfhi(z.x));
;         o[2] = v[2] * s[2] * silu_f(bflo(z.y)); o[3] = v[3] * s[3] * silu_f(bfhi(z.y));
	s_nop 0


; DEV float bflo(unsigned u) { return __uint_as_float(u << 16); }
; DEV float bfhi(unsigned u) { return __uint_as_float(u & 0xffff0000u); }
; DEV float silu_f(float x) { return x / (1.f + __expf(-x)); }
;     DEV f32x4 xform(int r, int c, f32x4 v) const {
;         const int row = m0 + r, col = n0 + c;
;         const uint2 z = *(const uint2*)(proj + (size_t)row * NPJ + C_ZB + col);
;         const f32x4 s = *(const f32x4*)(scale + col);
;         f32x4 o;
;         o[0] = v[0] * s[0] * silu_f(bflo(z.x)); o[1] = v[1] * s[1] * silu_f(bfhi(z.x));
;         o[2] = v[2] * s[2] * silu_f(bflo(z.y)); o[3] = v[3] * s[3] * silu_f(bfhi(z.y));
	v_rcp_f32_e32 v56, v54
	s_nop 0
	v_mul_f32_e32 v54, v59, v56
	v_lshlrev_b32_e32 v56, 16, v79
	v_and_b32_e32 v57, 0xffff0000, v79
	v_pk_mul_f32 v[42:43], v[42:43], v[54:55]
	v_mul_f32_e32 v54, 0xbfb8aa3b, v56
	v_mul_f32_e32 v55, 0xbfb8aa3b, v57
	v_exp_f32_e32 v54, v54
	v_exp_f32_e32 v55, v55
	v_cvt_pk_bf16_f32 v42, v42, v43
	v_pk_add_f32 v[54:55], v[54:55], 1.0 op_sel_hi:[1,0]
	s_nop 0


; DEV float bflo(unsigned u) { return __uint_as_float(u << 16); }
; DEV float bfhi(unsigned u) { return __uint_as_float(u & 0xffff0000u); }
; DEV float silu_f(float x) { return x / (1.f + __expf(-x)); }
;     DEV f32x4 xform(int r, int c, f32x4 v) const {
;     ...
;         o[0] = v[0] * s[0] * silu_f(bflo(z.x)); o[1] = v[1] * s[1] * silu_f(bfhi(z.x));
;         o[2] = v[2] * s[2] * silu_f(bflo(z.y)); o[3] = v[3] * s[3] * silu_f(bfhi(z.y));
	s_nop 0


; DEV float bflo(unsigned u) { return __uint_as_float(u << 16); }
; DEV float bfhi(unsigned u) { return __uint_as_float(u & 0xffff0000u); }
; DEV float silu_f(float x) { return x / (1.f + __expf(-x)); }
;     DEV f32x4 xform(int r, int c, f32x4 v) const {
;     ...
;         o[0] = v[0] * s[0] * silu_f(bflo(z.x)); o[1] = v[1] * s[1] * silu_f(bfhi(z.x));
;         o[2] = v[2] * s[2] * silu_f(bflo(z.y)); o[3] = v[3] * s[3] * silu_f(bfhi(z.y));
	v_rcp_f32_e32 v59, v55
	s_nop 0
	v_mul_f32_e32 v55, v57, v59


; DEV float bflo(unsigned u) { return __uint_as_float(u << 16); }
; DEV float bfhi(unsigned u) { return __uint_as_float(u & 0xffff0000u); }
; DEV float silu_f(float x) { return x / (1.f + __expf(-x)); }
;     DEV f32x4 xform(int r, int c, f32x4 v) const {
;     ...
;         o[0] = v[0] * s[0] * silu_f(bflo(z.x)); o[1] = v[1] * s[1] * silu_f(bfhi(z.x));
;         o[2] = v[2] * s[2] * silu_f(bflo(z.y)); o[3] = v[3] * s[3] * silu_f(bfhi(z.y));
	s_nop 0


; DEV unsigned cvt_pk_bf16(float lo, float hi) { const f32x2_t v = {lo, hi}; const bf16x2_t b = __builtin_convertvector(v, bf16x2_t); return __builtin_bit_cast(unsigned, b); }
; DEV float bflo(unsigned u) { return __uint_as_float(u << 16); }
; DEV float bfhi(unsigned u) { return __uint_as_float(u & 0xffff0000u); }
; DEV float silu_f(float x) { return x / (1.f + __expf(-x)); }
; template <int WT, class Epi>
; DEV void gemm_tile(const bf16_t* __restrict__ A, int lda, const bf16_t* __restrict__ Bt, int ldb, int K, unsigned char* lds, const Epi& epi) {
;     ...
;                 const int row = wr * WT + mi * 16 + fr, col = wc * WT + ni * 16 + fq * 4;
;                 const f32x4 v = epi.xform(row, col, acc[mi][ni]);
;                 uint2 w; w.x = cvt_pk_bf16(v[0], v[1]); w.y = cvt_pk_bf16(v[2], v[3]);
;                 *(uint2*)(lds + row * RB + ((((col >> 3) ^ (row & (CPR - 1))) << 4) | (((col >> 2) & 1) << 3))) = w;
;     DEV f32x4 xform(int r, int c, f32x4 v) const {
;         const int row = m0 + r, col = n0 + c;
;         const uint2 z = *(const uint2*)(proj + (size_t)row * NPJ + C_ZB + col);
;         const f32x4 s = *(const f32x4*)(scale + col);
;         f32x4 o;
;         o[0] = v[0] * s[0] * silu_f(bflo(z.x)); o[1] = v[1] * s[1] * silu_f(bfhi(z.x));
;         o[2] = v[2] * s[2] * silu_f(bflo(z.y)); o[3] = v[3] * s[3] * silu_f(bfhi(z.y));
	v_rcp_f32_e32 v57, v54
	s_nop 0
	v_mul_f32_e32 v54, v56, v57
	v_pk_mul_f32 v[44:45], v[44:45], v[54:55]
	s_nop 0
	v_cvt_pk_bf16_f32 v43, v44, v45
	v_add_u32_e32 v44, v65, v76
	ds_write_b64 v44, v[42:43]
	v_lshl_add_u64 v[42:43], v[60:61], 0, v[72:73]
	global_load_dwordx2 v[42:43], v[42:43], off
	s_waitcnt vmcnt(0)
	v_lshlrev_b32_e32 v54, 16, v42
	v_and_b32_e32 v42, 0xffff0000, v42
	v_mul_f32_e32 v44, 0xbfb8aa3b, v54
	v_mul_f32_e32 v45, 0xbfb8aa3b, v42
	v_exp_f32_e32 v44, v44
	v_exp_f32_e32 v45, v45
	s_nop 0
	v_pk_add_f32 v[44:45], v[44:45], 1.0 op_sel_hi:[1,0]
	s_nop 0


; DEV float bflo(unsigned u) { return __uint_as_float(u << 16); }
; DEV float bfhi(unsigned u) { return __uint_as_float(u & 0xffff0000u); }
; DEV float silu_f(float x) { return x / (1.f + __expf(-x)); }
;     DEV f32x4 xform(int r, int c, f32x4 v) const {
;     ...
;         o[0] = v[0] * s[0] * silu_f(bflo(z.x)); o[1] = v[1] * s[1] * silu_f(bfhi(z.x));
;         o[2] = v[2] * s[2] * silu_f(bflo(z.y)); o[3] = v[3] * s[3] * silu_f(bfhi(z.y));
	s_nop 0


; DEV float bflo(unsigned u) { return __uint_as_float(u << 16); }
; DEV float bfhi(unsigned u) { return __uint_as_float(u & 0xffff0000u); }
; DEV float silu_f(float x) { return x / (1.f + __expf(-x)); }
;     DEV f32x4 xform(int r, int c, f32x4 v) const {
;     ...
;         o[0] = v[0] * s[0] * silu_f(bflo(z.x)); o[1] = v[1] * s[1] * silu_f(bfhi(z.x));
;         o[2] = v[2] * s[2] * silu_f(bflo(z.y)); o[3] = v[3] * s[3] * silu_f(bfhi(z.y));
	v_rcp_f32_e32 v50, v45
	s_nop 0
	v_mul_f32_e32 v45, v42, v50


; DEV float bflo(unsigned u) { return __uint_as_float(u << 16); }
; DEV float bfhi(unsigned u) { return __uint_as_float(u & 0xffff0000u); }
; DEV float silu_f(float x) { return x / (1.f + __expf(-x)); }
;     DEV f32x4 xform(int r, int c, f32x4 v) const {
;     ...
;         o[0] = v[0] * s[0] * silu_f(bflo(z.x)); o[1] = v[1] * s[1] * silu_f(bfhi(z.x));
;         o[2] = v[2] * s[2] * silu_f(bflo(z.y)); o[3] = v[3] * s[3] * silu_f(bfhi(z.y));
	s_nop 0


; DEV float bflo(unsigned u) { return __uint_as_float(u << 16); }
; DEV float bfhi(unsigned u) { return __uint_as_float(u & 0xffff0000u); }
; DEV float silu_f(float x) { return x / (1.f + __expf(-x)); }
;     DEV f32x4 xform(int r, int c, f32x4 v) const {
;         const int row = m0 + r, col = n0 + c;
;         const uint2 z = *(const uint2*)(proj + (size_t)row * NPJ + C_ZB + col);
;         const f32x4 s = *(const f32x4*)(scale + col);
;         f32x4 o;
;         o[0] = v[0] * s[0] * silu_f(bflo(z.x)); o[1] = v[1] * s[1] * silu_f(bfhi(z.x));
;         o[2] = v[2] * s[2] * silu_f(bflo(z.y)); o[3] = v[3] * s[3] * silu_f(bfhi(z.y));
	v_rcp_f32_e32 v42, v44
	s_nop 0
	v_mul_f32_e32 v44, v54, v42
	v_pk_mul_f32 v[44:45], v[46:47], v[44:45]
	v_lshlrev_b32_e32 v46, 16, v43
	v_and_b32_e32 v47, 0xffff0000, v43
	v_mul_f32_e32 v42, 0xbfb8aa3b, v46
	v_mul_f32_e32 v43, 0xbfb8aa3b, v47
	v_exp_f32_e32 v42, v42
	v_exp_f32_e32 v43, v43
	v_cvt_pk_bf16_f32 v44, v44, v45
	v_pk_add_f32 v[42:43], v[42:43], 1.0 op_sel_hi:[1,0]
	s_nop 0


; DEV float bflo(unsigned u) { return __uint_as_float(u << 16); }
; DEV float bfhi(unsigned u) { return __uint_as_float(u & 0xffff0000u); }
; DEV float silu_f(float x) { return x / (1.f + __expf(-x)); }
;     DEV f32x4 xform(int r, int c, f32x4 v) const {
;     ...
;         o[0] = v[0] * s[0] * silu_f(bflo(z.x)); o[1] = v[1] * s[1] * silu_f(bfhi(z.x));
;         o[2] = v[2] * s[2] * silu_f(bflo(z.y)); o[3] = v[3] * s[3] * silu_f(bfhi(z.y));
	s_nop 0


; DEV float bflo(unsigned u) { return __uint_as_float(u << 16); }
; DEV float bfhi(unsigned u) { return __uint_as_float(u & 0xffff0000u); }
; DEV float silu_f(float x) { return x / (1.f + __expf(-x)); }
;     DEV f32x4 xform(int r, int c, f32x4 v) const {
;     ...
;         o[0] = v[0] * s[0] * silu_f(bflo(z.x)); o[1] = v[1] * s[1] * silu_f(bfhi(z.x));
;         o[2] = v[2] * s[2] * silu_f(bflo(z.y)); o[3] = v[3] * s[3] * silu_f(bfhi(z.y));
	v_rcp_f32_e32 v50, v43
	s_nop 0
	v_mul_f32_e32 v43, v47, v50


; DEV float bflo(unsigned u) { return __uint_as_float(u << 16); }
; DEV float bfhi(unsigned u) { return __uint_as_float(u & 0xffff0000u); }
; DEV float silu_f(float x) { return x / (1.f + __expf(-x)); }
;     DEV f32x4 xform(int r, int c, f32x4 v) const {
;     ...
;         o[0] = v[0] * s[0] * silu_f(bflo(z.x)); o[1] = v[1] * s[1] * silu_f(bfhi(z.x));
;         o[2] = v[2] * s[2] * silu_f(bflo(z.y)); o[3] = v[3] * s[3] * silu_f(bfhi(z.y));
	s_nop 0


; DEV unsigned cvt_pk_bf16(float lo, float hi) { const f32x2_t v = {lo, hi}; const bf16x2_t b = __builtin_convertvector(v, bf16x2_t); return __builtin_bit_cast(unsigned, b); }
; DEV float bflo(unsigned u) { return __uint_as_float(u << 16); }
; DEV float bfhi(unsigned u) { return __uint_as_float(u & 0xffff0000u); }
; DEV float silu_f(float x) { return x / (1.f + __expf(-x)); }
; template <int WT, class Epi>
; DEV void gemm_tile(const bf16_t* __restrict__ A, int lda, const bf16_t* __restrict__ Bt, int ldb, int K, unsigned char* lds, const Epi& epi) {
;     ...
;                 const int row = wr * WT + mi * 16 + fr, col = wc * WT + ni * 16 + fq * 4;
;                 const f32x4 v = epi.xform(row, col, acc[mi][ni]);
;                 uint2 w; w.x = cvt_pk_bf16(v[0], v[1]); w.y = cvt_pk_bf16(v[2], v[3]);
;                 *(uint2*)(lds + row * RB + ((((col >> 3) ^ (row & (CPR - 1))) << 4) | (((col >> 2) & 1) << 3))) = w;
;     DEV f32x4 xform(int r, int c, f32x4 v) const {
;         const int row = m0 + r, col = n0 + c;
;         const uint2 z = *(const uint2*)(proj + (size_t)row * NPJ + C_ZB + col);
;         const f32x4 s = *(const f32x4*)(scale + col);
;         f32x4 o;
;         o[0] = v[0] * s[0] * silu_f(bflo(z.x)); o[1] = v[1] * s[1] * silu_f(bfhi(z.x));
;         o[2] = v[2] * s[2] * silu_f(bflo(z.y)); o[3] = v[3] * s[3] * silu_f(bfhi(z.y));
	v_rcp_f32_e32 v47, v42
	s_nop 0
	v_mul_f32_e32 v42, v46, v47
	v_pk_mul_f32 v[42:43], v[48:49], v[42:43]
	s_nop 0
	v_cvt_pk_bf16_f32 v45, v42, v43
	v_add_u32_e32 v42, v65, v77
	ds_write_b64 v42, v[44:45]
	v_lshl_add_u64 v[42:43], v[60:61], 0, v[74:75]
	global_load_dwordx2 v[46:47], v[42:43], off
	s_nop 0
	global_load_dwordx4 v[42:45], v[66:67], off offset:128
	s_waitcnt vmcnt(1)
	v_lshlrev_b32_e32 v50, 16, v46
	v_and_b32_e32 v46, 0xffff0000, v46
	v_mul_f32_e32 v48, 0xbfb8aa3b, v50
	s_waitcnt vmcnt(0)
	v_pk_mul_f32 v[38:39], v[38:39], v[42:43]
	v_mul_f32_e32 v42, 0xbfb8aa3b, v46
	v_exp_f32_e32 v48, v48
	v_exp_f32_e32 v49, v42
	v_pk_mul_f32 v[40:41], v[40:41], v[44:45]
	v_pk_add_f32 v[42:43], v[48:49], 1.0 op_sel_hi:[1,0]
	s_nop 0


; DEV float bflo(unsigned u) { return __uint_as_float(u << 16); }
; DEV float bfhi(unsigned u) { return __uint_as_float(u & 0xffff0000u); }
; DEV float silu_f(float x) { return x / (1.f + __expf(-x)); }
;     DEV f32x4 xform(int r, int c, f32x4 v) const {
;     ...
;         o[0] = v[0] * s[0] * silu_f(bflo(z.x)); o[1] = v[1] * s[1] * silu_f(bfhi(z.x));
;         o[2] = v[2] * s[2] * silu_f(bflo(z.y)); o[3] = v[3] * s[3] * silu_f(bfhi(z.y));
	s_nop 0


; DEV float bflo(unsigned u) { return __uint_as_float(u << 16); }
; DEV float bfhi(unsigned u) { return __uint_as_float(u & 0xffff0000u); }
; DEV float silu_f(float x) { return x / (1.f + __expf(-x)); }
;     DEV f32x4 xform(int r, int c, f32x4 v) const {
;     ...
;         o[0] = v[0] * s[0] * silu_f(bflo(z.x)); o[1] = v[1] * s[1] * silu_f(bfhi(z.x));
;         o[2] = v[2] * s[2] * silu_f(bflo(z.y)); o[3] = v[3] * s[3] * silu_f(bfhi(z.y));
	v_rcp_f32_e32 v44, v43
	s_nop 0
	v_mul_f32_e32 v43, v46, v44


; DEV float bflo(unsigned u) { return __uint_as_float(u << 16); }
; DEV float bfhi(unsigned u) { return __uint_as_float(u & 0xffff0000u); }
; DEV float silu_f(float x) { return x / (1.f + __expf(-x)); }
;     DEV f32x4 xform(int r, int c, f32x4 v) const {
;     ...
;         o[0] = v[0] * s[0] * silu_f(bflo(z.x)); o[1] = v[1] * s[1] * silu_f(bfhi(z.x));
;         o[2] = v[2] * s[2] * silu_f(bflo(z.y)); o[3] = v[3] * s[3] * silu_f(bfhi(z.y));
	s_nop 0


; DEV float bflo(unsigned u) { return __uint_as_float(u << 16); }
; DEV float bfhi(unsigned u) { return __uint_as_float(u & 0xffff0000u); }
; DEV float silu_f(float x) { return x / (1.f + __expf(-x)); }
;     DEV f32x4 xform(int r, int c, f32x4 v) const {
;         const int row = m0 + r, col = n0 + c;
;         const uint2 z = *(const uint2*)(proj + (size_t)row * NPJ + C_ZB + col);
;         const f32x4 s = *(const f32x4*)(scale + col);
;         f32x4 o;
;         o[0] = v[0] * s[0] * silu_f(bflo(z.x)); o[1] = v[1] * s[1] * silu_f(bfhi(z.x));
;         o[2] = v[2] * s[2] * silu_f(bflo(z.y)); o[3] = v[3] * s[3] * silu_f(bfhi(z.y));
	v_rcp_f32_e32 v44, v42
	s_nop 0
	v_mul_f32_e32 v42, v50, v44
	v_lshlrev_b32_e32 v44, 16, v47
	v_and_b32_e32 v45, 0xffff0000, v47
	v_pk_mul_f32 v[38:39], v[38:39], v[42:43]
	v_mul_f32_e32 v42, 0xbfb8aa3b, v44
	v_mul_f32_e32 v43, 0xbfb8aa3b, v45
	v_exp_f32_e32 v42, v42
	v_exp_f32_e32 v43, v43
	v_cvt_pk_bf16_f32 v38, v38, v39
	v_pk_add_f32 v[42:43], v[42:43], 1.0 op_sel_hi:[1,0]
	s_nop 0


; DEV float bflo(unsigned u) { return __uint_as_float(u << 16); }
; DEV float bfhi(unsigned u) { return __uint_as_float(u & 0xffff0000u); }
; DEV float silu_f(float x) { return x / (1.f + __expf(-x)); }
;     DEV f32x4 xform(int r, int c, f32x4 v) const {
;     ...
;         o[0] = v[0] * s[0] * silu_f(bflo(z.x)); o[1] = v[1] * s[1] * silu_f(bfhi(z.x));
;         o[2] = v[2] * s[2] * silu_f(bflo(z.y)); o[3] = v[3] * s[3] * silu_f(bfhi(z.y));
	s_nop 0


; DEV float bflo(unsigned u) { return __uint_as_float(u << 16); }
; DEV float bfhi(unsigned u) { return __uint_as_float(u & 0xffff0000u); }
; DEV float silu_f(float x) { return x / (1.f + __expf(-x)); }
;     DEV f32x4 xform(int r, int c, f32x4 v) const {
;     ...
;         o[0] = v[0] * s[0] * silu_f(bflo(z.x)); o[1] = v[1] * s[1] * silu_f(bfhi(z.x));
;         o[2] = v[2] * s[2] * silu_f(bflo(z.y)); o[3] = v[3] * s[3] * silu_f(bfhi(z.y));
	v_rcp_f32_e32 v46, v43
	s_nop 0
	v_mul_f32_e32 v43, v45, v46


; DEV float bflo(unsigned u) { return __uint_as_float(u << 16); }
; DEV float bfhi(unsigned u) { return __uint_as_float(u & 0xffff0000u); }
; DEV float silu_f(float x) { return x / (1.f + __expf(-x)); }
;     DEV f32x4 xform(int r, int c, f32x4 v) const {
;     ...
;         o[0] = v[0] * s[0] * silu_f(bflo(z.x)); o[1] = v[1] * s[1] * silu_f(bfhi(z.x));
;         o[2] = v[2] * s[2] * silu_f(bflo(z.y)); o[3] = v[3] * s[3] * silu_f(bfhi(z.y));
	s_nop 0


; DEV unsigned cvt_pk_bf16(float lo, float hi) { const f32x2_t v = {lo, hi}; const bf16x2_t b = __builtin_convertvector(v, bf16x2_t); return __builtin_bit_cast(unsigned, b); }
; DEV float bflo(unsigned u) { return __uint_as_float(u << 16); }
; DEV float bfhi(unsigned u) { return __uint_as_float(u & 0xffff0000u); }
; DEV float silu_f(float x) { return x / (1.f + __expf(-x)); }
; template <int WT, class Epi>
; DEV void gemm_tile(const bf16_t* __restrict__ A, int lda, const bf16_t* __restrict__ Bt, int ldb, int K, unsigned char* lds, const Epi& epi) {
;     ...
;                 const int row = wr * WT + mi * 16 + fr, col = wc * WT + ni * 16 + fq * 4;
;                 const f32x4 v = epi.xform(row, col, acc[mi][ni]);
;                 uint2 w; w.x = cvt_pk_bf16(v[0], v[1]); w.y = cvt_pk_bf16(v[2], v[3]);
;                 *(uint2*)(lds + row * RB + ((((col >> 3) ^ (row & (CPR - 1))) << 4) | (((col >> 2) & 1) << 3))) = w;
;     DEV f32x4 xform(int r, int c, f32x4 v) const {
;         const int row = m0 + r, col = n0 + c;
;         const uint2 z = *(const uint2*)(proj + (size_t)row * NPJ + C_ZB + col);
;         const f32x4 s = *(const f32x4*)(scale + col);
;         f32x4 o;
;         o[0] = v[0] * s[0] * silu_f(bflo(z.x)); o[1] = v[1] * s[1] * silu_f(bfhi(z.x));
;         o[2] = v[2] * s[2] * silu_f(bflo(z.y)); o[3] = v[3] * s[3] * silu_f(bfhi(z.y));
	v_rcp_f32_e32 v45, v42
	s_nop 0
	v_mul_f32_e32 v42, v44, v45
	v_pk_mul_f32 v[40:41], v[40:41], v[42:43]
	s_nop 0
	v_cvt_pk_bf16_f32 v39, v40, v41
	v_add_u32_e32 v40, v65, v64
	ds_write_b64 v40, v[38:39]
	v_lshl_add_u64 v[38:39], v[60:61], 0, v[62:63]
	global_load_dwordx2 v[42:43], v[38:39], off
	s_nop 0
	global_load_dwordx4 v[38:41], v[66:67], off offset:192
	s_waitcnt vmcnt(1)
	v_lshlrev_b32_e32 v46, 16, v42
	v_and_b32_e32 v42, 0xffff0000, v42
	v_mul_f32_e32 v44, 0xbfb8aa3b, v46
	s_waitcnt vmcnt(0)
	v_pk_mul_f32 v[34:35], v[34:35], v[38:39]
	v_mul_f32_e32 v38, 0xbfb8aa3b, v42
	v_exp_f32_e32 v44, v44
	v_exp_f32_e32 v45, v38
	v_pk_mul_f32 v[36:37], v[36:37], v[40:41]
	v_pk_add_f32 v[38:39], v[44:45], 1.0 op_sel_hi:[1,0]
	s_nop 0


; DEV float bflo(unsigned u) { return __uint_as_float(u << 16); }
; DEV float bfhi(unsigned u) { return __uint_as_float(u & 0xffff0000u); }
; DEV float silu_f(float x) { return x / (1.f + __expf(-x)); }
;     DEV f32x4 xform(int r, int c, f32x4 v) const {
;     ...
;         o[0] = v[0] * s[0] * silu_f(bflo(z.x)); o[1] = v[1] * s[1] * silu_f(bfhi(z.x));
;         o[2] = v[2] * s[2] * silu_f(bflo(z.y)); o[3] = v[3] * s[3] * silu_f(bfhi(z.y));
	s_nop 0


; DEV float bflo(unsigned u) { return __uint_as_float(u << 16); }
; DEV float bfhi(unsigned u) { return __uint_as_float(u & 0xffff0000u); }
; DEV float silu_f(float x) { return x / (1.f + __expf(-x)); }
;     DEV f32x4 xform(int r, int c, f32x4 v) const {
;     ...
;         o[0] = v[0] * s[0] * silu_f(bflo(z.x)); o[1] = v[1] * s[1] * silu_f(bfhi(z.x));
;         o[2] = v[2] * s[2] * silu_f(bflo(z.y)); o[3] = v[3] * s[3] * silu_f(bfhi(z.y));
	v_rcp_f32_e32 v40, v39
	s_nop 0
	v_mul_f32_e32 v39, v42, v40


; DEV float bflo(unsigned u) { return __uint_as_float(u << 16); }
; DEV float bfhi(unsigned u) { return __uint_as_float(u & 0xffff0000u); }
; DEV float silu_f(float x) { return x / (1.f + __expf(-x)); }
;     DEV f32x4 xform(int r, int c, f32x4 v) const {
;     ...
;         o[0] = v[0] * s[0] * silu_f(bflo(z.x)); o[1] = v[1] * s[1] * silu_f(bfhi(z.x));
;         o[2] = v[2] * s[2] * silu_f(bflo(z.y)); o[3] = v[3] * s[3] * silu_f(bfhi(z.y));
	s_nop 0


; DEV float bflo(unsigned u) { return __uint_as_float(u << 16); }
; DEV float bfhi(unsigned u) { return __uint_as_float(u & 0xffff0000u); }
; DEV float silu_f(float x) { return x / (1.f + __expf(-x)); }
;     DEV f32x4 xform(int r, int c, f32x4 v) const {
;         const int row = m0 + r, col = n0 + c;
;         const uint2 z = *(const uint2*)(proj + (size_t)row * NPJ + C_ZB + col);
;         const f32x4 s = *(const f32x4*)(scale + col);
;         f32x4 o;
;         o[0] = v[0] * s[0] * silu_f(bflo(z.x)); o[1] = v[1] * s[1] * silu_f(bfhi(z.x));
;         o[2] = v[2] * s[2] * silu_f(bflo(z.y)); o[3] = v[3] * s[3] * silu_f(bfhi(z.y));
	v_rcp_f32_e32 v40, v38
	s_nop 0
	v_mul_f32_e32 v38, v46, v40
	v_lshlrev_b32_e32 v40, 16, v43
	v_and_b32_e32 v41, 0xffff0000, v43
	v_pk_mul_f32 v[34:35], v[34:35], v[38:39]
	v_mul_f32_e32 v38, 0xbfb8aa3b, v40
	v_mul_f32_e32 v39, 0xbfb8aa3b, v41
	v_exp_f32_e32 v38, v38
	v_exp_f32_e32 v39, v39
	v_cvt_pk_bf16_f32 v34, v34, v35
	v_pk_add_f32 v[38:39], v[38:39], 1.0 op_sel_hi:[1,0]
	s_nop 0


; DEV float bflo(unsigned u) { return __uint_as_float(u << 16); }
; DEV float bfhi(unsigned u) { return __uint_as_float(u & 0xffff0000u); }
; DEV float silu_f(float x) { return x / (1.f + __expf(-x)); }
;     DEV f32x4 xform(int r, int c, f32x4 v) const {
;     ...
;         o[0] = v[0] * s[0] * silu_f(bflo(z.x)); o[1] = v[1] * s[1] * silu_f(bfhi(z.x));
;         o[2] = v[2] * s[2] * silu_f(bflo(z.y)); o[3] = v[3] * s[3] * silu_f(bfhi(z.y));
	s_nop 0


; DEV float bflo(unsigned u) { return __uint_as_float(u << 16); }
; DEV float bfhi(unsigned u) { return __uint_as_float(u & 0xffff0000u); }
; DEV float silu_f(float x) { return x / (1.f + __expf(-x)); }
;     DEV f32x4 xform(int r, int c, f32x4 v) const {
;     ...
;         o[0] = v[0] * s[0] * silu_f(bflo(z.x)); o[1] = v[1] * s[1] * silu_f(bfhi(z.x));
;         o[2] = v[2] * s[2] * silu_f(bflo(z.y)); o[3] = v[3] * s[3] * silu_f(bfhi(z.y));
	v_rcp_f32_e32 v42, v39
	s_nop 0
	v_mul_f32_e32 v39, v41, v42


; DEV float bflo(unsigned u) { return __uint_as_float(u << 16); }
; DEV float bfhi(unsigned u) { return __uint_as_float(u & 0xffff0000u); }
; DEV float silu_f(float x) { return x / (1.f + __expf(-x)); }
;     DEV f32x4 xform(int r, int c, f32x4 v) const {
;     ...
;         o[0] = v[0] * s[0] * silu_f(bflo(z.x)); o[1] = v[1] * s[1] * silu_f(bfhi(z.x));
;         o[2] = v[2] * s[2] * silu_f(bflo(z.y)); o[3] = v[3] * s[3] * silu_f(bfhi(z.y));
	s_nop 0


; DEV unsigned cvt_pk_bf16(float lo, float hi) { const f32x2_t v = {lo, hi}; const bf16x2_t b = __builtin_convertvector(v, bf16x2_t); return __builtin_bit_cast(unsigned, b); }
; DEV float bflo(unsigned u) { return __uint_as_float(u << 16); }
; DEV float bfhi(unsigned u) { return __uint_as_float(u & 0xffff0000u); }
; DEV float silu_f(float x) { return x / (1.f + __expf(-x)); }
; template <int WT, class Epi>
; DEV void gemm_tile(const bf16_t* __restrict__ A, int lda, const bf16_t* __restrict__ Bt, int ldb, int K, unsigned char* lds, const Epi& epi) {
;     ...
;                 const int row = wr * WT + mi * 16 + fr, col = wc * WT + ni * 16 + fq * 4;
;                 const f32x4 v = epi.xform(row, col, acc[mi][ni]);
;                 uint2 w; w.x = cvt_pk_bf16(v[0], v[1]); w.y = cvt_pk_bf16(v[2], v[3]);
;                 *(uint2*)(lds + row * RB + ((((col >> 3) ^ (row & (CPR - 1))) << 4) | (((col >> 2) & 1) << 3))) = w;
;     DEV f32x4 xform(int r, int c, f32x4 v) const {
;         const int row = m0 + r, col = n0 + c;
;         const uint2 z = *(const uint2*)(proj + (size_t)row * NPJ + C_ZB + col);
;         const f32x4 s = *(const f32x4*)(scale + col);
;         f32x4 o;
;         o[0] = v[0] * s[0] * silu_f(bflo(z.x)); o[1] = v[1] * s[1] * silu_f(bfhi(z.x));
;         o[2] = v[2] * s[2] * silu_f(bflo(z.y)); o[3] = v[3] * s[3] * silu_f(bfhi(z.y));
	v_rcp_f32_e32 v41, v38
	s_nop 0
	v_mul_f32_e32 v38, v40, v41
	v_pk_mul_f32 v[36:37], v[36:37], v[38:39]
	s_nop 0
	v_cvt_pk_bf16_f32 v35, v36, v37
	v_add_u32_e32 v36, v65, v58
	ds_write_b64 v36, v[34:35]
	v_or_b32_e32 v34, 32, v130
	v_lshl_add_u32 v44, v34, 8, s70
	v_add_u32_e32 v34, s81, v34
	v_mad_i64_i32 v[34:35], s[68:69], v34, s79, v[172:173]
	v_lshl_add_u64 v[38:39], v[34:35], 0, s[66:67]
	v_lshl_add_u64 v[34:35], v[38:39], 0, v[68:69]
	global_load_dwordx2 v[40:41], v[34:35], off
	s_nop 0
	global_load_dwordx4 v[34:37], v[70:71], off
	s_waitcnt vmcnt(1)
	v_lshlrev_b32_e32 v45, 16, v40
	v_and_b32_e32 v40, 0xffff0000, v40
	v_mul_f32_e32 v42, 0xbfb8aa3b, v45
	s_waitcnt vmcnt(0)
	v_pk_mul_f32 v[30:31], v[30:31], v[34:35]
	v_mul_f32_e32 v34, 0xbfb8aa3b, v40
	v_exp_f32_e32 v42, v42
	v_exp_f32_e32 v43, v34
	v_pk_mul_f32 v[32:33], v[32:33], v[36:37]
	v_pk_add_f32 v[34:35], v[42:43], 1.0 op_sel_hi:[1,0]
	s_nop 0


; DEV float bflo(unsigned u) { return __uint_as_float(u << 16); }
; DEV float bfhi(unsigned u) { return __uint_as_float(u & 0xffff0000u); }
; DEV float silu_f(float x) { return x / (1.f + __expf(-x)); }
;     DEV f32x4 xform(int r, int c, f32x4 v) const {
;     ...
;         o[0] = v[0] * s[0] * silu_f(bflo(z.x)); o[1] = v[1] * s[1] * silu_f(bfhi(z.x));
;         o[2] = v[2] * s[2] * silu_f(bflo(z.y)); o[3] = v[3] * s[3] * silu_f(bfhi(z.y));
	s_nop 0


; DEV float bflo(unsigned u) { return __uint_as_float(u << 16); }
; DEV float bfhi(unsigned u) { return __uint_as_float(u & 0xffff0000u); }
; DEV float silu_f(float x) { return x / (1.f + __expf(-x)); }
;     DEV f32x4 xform(int r, int c, f32x4 v) const {
;     ...
;         o[0] = v[0] * s[0] * silu_f(bflo(z.x)); o[1] = v[1] * s[1] * silu_f(bfhi(z.x));
;         o[2] = v[2] * s[2] * silu_f(bflo(z.y)); o[3] = v[3] * s[3] * silu_f(bfhi(z.y));
	v_rcp_f32_e32 v36, v35
	s_nop 0
	v_mul_f32_e32 v35, v40, v36


; DEV float bflo(unsigned u) { return __uint_as_float(u << 16); }
; DEV float bfhi(unsigned u) { return __uint_as_float(u & 0xffff0000u); }
; DEV float silu_f(float x) { return x / (1.f + __expf(-x)); }
;     DEV f32x4 xform(int r, int c, f32x4 v) const {
;     ...
;         o[0] = v[0] * s[0] * silu_f(bflo(z.x)); o[1] = v[1] * s[1] * silu_f(bfhi(z.x));
;         o[2] = v[2] * s[2] * silu_f(bflo(z.y)); o[3] = v[3] * s[3] * silu_f(bfhi(z.y));
	s_nop 0


; DEV float bflo(unsigned u) { return __uint_as_float(u << 16); }
; DEV float bfhi(unsigned u) { return __uint_as_float(u & 0xffff0000u); }
; DEV float silu_f(float x) { return x / (1.f + __expf(-x)); }
;     DEV f32x4 xform(int r, int c, f32x4 v) const {
;         const int row = m0 + r, col = n0 + c;
;         const uint2 z = *(const uint2*)(proj + (size_t)row * NPJ + C_ZB + col);
;         const f32x4 s = *(const f32x4*)(scale + col);
;         f32x4 o;
;         o[0] = v[0] * s[0] * silu_f(bflo(z.x)); o[1] = v[1] * s[1] * silu_f(bfhi(z.x));
;         o[2] = v[2] * s[2] * silu_f(bflo(z.y)); o[3] = v[3] * s[3] * silu_f(bfhi(z.y));
	v_rcp_f32_e32 v36, v34
	s_nop 0
	v_mul_f32_e32 v34, v45, v36
	v_lshlrev_b32_e32 v36, 16, v41
	v_and_b32_e32 v37, 0xffff0000, v41
	v_pk_mul_f32 v[30:31], v[30:31], v[34:35]
	v_mul_f32_e32 v34, 0xbfb8aa3b, v36
	v_mul_f32_e32 v35, 0xbfb8aa3b, v37
	v_exp_f32_e32 v34, v34
	v_exp_f32_e32 v35, v35
	v_cvt_pk_bf16_f32 v30, v30, v31
	v_pk_add_f32 v[34:35], v[34:35], 1.0 op_sel_hi:[1,0]
	s_nop 0


; DEV float bflo(unsigned u) { return __uint_as_float(u << 16); }
; DEV float bfhi(unsigned u) { return __uint_as_float(u & 0xffff0000u); }
; DEV float silu_f(float x) { return x / (1.f + __expf(-x)); }
;     DEV f32x4 xform(int r, int c, f32x4 v) const {
;     ...
;         o[0] = v[0] * s[0] * silu_f(bflo(z.x)); o[1] = v[1] * s[1] * silu_f(bfhi(z.x));
;         o[2] = v[2] * s[2] * silu_f(bflo(z.y)); o[3] = v[3] * s[3] * silu_f(bfhi(z.y));
	s_nop 0


; DEV float bflo(unsigned u) { return __uint_as_float(u << 16); }
; DEV float bfhi(unsigned u) { return __uint_as_float(u & 0xffff0000u); }
; DEV float silu_f(float x) { return x / (1.f + __expf(-x)); }
;     DEV f32x4 xform(int r, int c, f32x4 v) const {
;     ...
;         o[0] = v[0] * s[0] * silu_f(bflo(z.x)); o[1] = v[1] * s[1] * silu_f(bfhi(z.x));
;         o[2] = v[2] * s[2] * silu_f(bflo(z.y)); o[3] = v[3] * s[3] * silu_f(bfhi(z.y));
	v_rcp_f32_e32 v40, v35
	s_nop 0
	v_mul_f32_e32 v35, v37, v40


; DEV float bflo(unsigned u) { return __uint_as_float(u << 16); }
; DEV float bfhi(unsigned u) { return __uint_as_float(u & 0xffff0000u); }
; DEV float silu_f(float x) { return x / (1.f + __expf(-x)); }
;     DEV f32x4 xform(int r, int c, f32x4 v) const {
;     ...
;         o[0] = v[0] * s[0] * silu_f(bflo(z.x)); o[1] = v[1] * s[1] * silu_f(bfhi(z.x));
;         o[2] = v[2] * s[2] * silu_f(bflo(z.y)); o[3] = v[3] * s[3] * silu_f(bfhi(z.y));
	s_nop 0


; DEV unsigned cvt_pk_bf16(float lo, float hi) { const f32x2_t v = {lo, hi}; const bf16x2_t b = __builtin_convertvector(v, bf16x2_t); return __builtin_bit_cast(unsigned, b); }
; DEV float bflo(unsigned u) { return __uint_as_float(u << 16); }
; DEV float bfhi(unsigned u) { return __uint_as_float(u & 0xffff0000u); }
; DEV float silu_f(float x) { return x / (1.f + __expf(-x)); }
; template <int WT, class Epi>
; DEV void gemm_tile(const bf16_t* __restrict__ A, int lda, const bf16_t* __restrict__ Bt, int ldb, int K, unsigned char* lds, const Epi& epi) {
;     ...
;                 const int row = wr * WT + mi * 16 + fr, col = wc * WT + ni * 16 + fq * 4;
;                 const f32x4 v = epi.xform(row, col, acc[mi][ni]);
;                 uint2 w; w.x = cvt_pk_bf16(v[0], v[1]); w.y = cvt_pk_bf16(v[2], v[3]);
;                 *(uint2*)(lds + row * RB + ((((col >> 3) ^ (row & (CPR - 1))) << 4) | (((col >> 2) & 1) << 3))) = w;
;     DEV f32x4 xform(int r, int c, f32x4 v) const {
;         const int row = m0 + r, col = n0 + c;
;         const uint2 z = *(const uint2*)(proj + (size_t)row * NPJ + C_ZB + col);
;         const f32x4 s = *(const f32x4*)(scale + col);
;         f32x4 o;
;         o[0] = v[0] * s[0] * silu_f(bflo(z.x)); o[1] = v[1] * s[1] * silu_f(bfhi(z.x));
;         o[2] = v[2] * s[2] * silu_f(bflo(z.y)); o[3] = v[3] * s[3] * silu_f(bfhi(z.y));
	v_rcp_f32_e32 v37, v34
	s_nop 0
	v_mul_f32_e32 v34, v36, v37
	v_pk_mul_f32 v[32:33], v[32:33], v[34:35]
	s_nop 0
	v_cvt_pk_bf16_f32 v31, v32, v33
	v_add_u32_e32 v32, v44, v76
	ds_write_b64 v32, v[30:31]
	v_lshl_add_u64 v[30:31], v[38:39], 0, v[72:73]
	global_load_dwordx2 v[34:35], v[30:31], off
	s_nop 0
	global_load_dwordx4 v[30:33], v[66:67], off offset:64
	s_waitcnt vmcnt(1)
	v_lshlrev_b32_e32 v40, 16, v34
	v_and_b32_e32 v34, 0xffff0000, v34
	v_mul_f32_e32 v36, 0xbfb8aa3b, v40
	s_waitcnt vmcnt(0)
	v_pk_mul_f32 v[26:27], v[26:27], v[30:31]
	v_mul_f32_e32 v30, 0xbfb8aa3b, v34
	v_exp_f32_e32 v36, v36
	v_exp_f32_e32 v37, v30
	v_pk_mul_f32 v[28:29], v[28:29], v[32:33]
	v_pk_add_f32 v[30:31], v[36:37], 1.0 op_sel_hi:[1,0]
	s_nop 0


; DEV float bflo(unsigned u) { return __uint_as_float(u << 16); }
; DEV float bfhi(unsigned u) { return __uint_as_float(u & 0xffff0000u); }
; DEV float silu_f(float x) { return x / (1.f + __expf(-x)); }
;     DEV f32x4 xform(int r, int c, f32x4 v) const {
;     ...
;         o[0] = v[0] * s[0] * silu_f(bflo(z.x)); o[1] = v[1] * s[1] * silu_f(bfhi(z.x));
;         o[2] = v[2] * s[2] * silu_f(bflo(z.y)); o[3] = v[3] * s[3] * silu_f(bfhi(z.y));
	s_nop 0


; DEV float bflo(unsigned u) { return __uint_as_float(u << 16); }
; DEV float bfhi(unsigned u) { return __uint_as_float(u & 0xffff0000u); }
; DEV float silu_f(float x) { return x / (1.f + __expf(-x)); }
;     DEV f32x4 xform(int r, int c, f32x4 v) const {
;     ...
;         o[0] = v[0] * s[0] * silu_f(bflo(z.x)); o[1] = v[1] * s[1] * silu_f(bfhi(z.x));
;         o[2] = v[2] * s[2] * silu_f(bflo(z.y)); o[3] = v[3] * s[3] * silu_f(bfhi(z.y));
	v_rcp_f32_e32 v32, v31
	s_nop 0
	v_mul_f32_e32 v31, v34, v32


; DEV float bflo(unsigned u) { return __uint_as_float(u << 16); }
; DEV float bfhi(unsigned u) { return __uint_as_float(u & 0xffff0000u); }
; DEV float silu_f(float x) { return x / (1.f + __expf(-x)); }
;     DEV f32x4 xform(int r, int c, f32x4 v) const {
;     ...
;         o[0] = v[0] * s[0] * silu_f(bflo(z.x)); o[1] = v[1] * s[1] * silu_f(bfhi(z.x));
;         o[2] = v[2] * s[2] * silu_f(bflo(z.y)); o[3] = v[3] * s[3] * silu_f(bfhi(z.y));
	s_nop 0


; DEV float bflo(unsigned u) { return __uint_as_float(u << 16); }
; DEV float bfhi(unsigned u) { return __uint_as_float(u & 0xffff0000u); }
; DEV float silu_f(float x) { return x / (1.f + __expf(-x)); }
;     DEV f32x4 xform(int r, int c, f32x4 v) const {
;     ...
;         o[0] = v[0] * s[0] * silu_f(bflo(z.x)); o[1] = v[1] * s[1] * silu_f(bfhi(z.x));
;         o[2] = v[2] * s[2] * silu_f(bflo(z.y)); o[3] = v[3] * s[3] * silu_f(bfhi(z.y));
	v_rcp_f32_e32 v32, v30
	s_nop 0
	v_mul_f32_e32 v30, v40, v32
	v_lshlrev_b32_e32 v32, 16, v35
	v_and_b32_e32 v33, 0xffff0000, v35
	v_pk_mul_f32 v[26:27], v[26:27], v[30:31]
	v_mul_f32_e32 v30, 0xbfb8aa3b, v32
	v_mul_f32_e32 v31, 0xbfb8aa3b, v33
	v_exp_f32_e32 v30, v30
	v_exp_f32_e32 v31, v31
	v_cvt_pk_bf16_f32 v26, v26, v27
	v_pk_add_f32 v[30:31], v[30:31], 1.0 op_sel_hi:[1,0]
	s_nop 0


; DEV float bflo(unsigned u) { return __uint_as_float(u << 16); }
; DEV float bfhi(unsigned u) { return __uint_as_float(u & 0xffff0000u); }
; DEV float silu_f(float x) { return x / (1.f + __expf(-x)); }
;     DEV f32x4 xform(int r, int c, f32x4 v) const {
;     ...
;         o[0] = v[0] * s[0] * silu_f(bflo(z.x)); o[1] = v[1] * s[1] * silu_f(bfhi(z.x));
;         o[2] = v[2] * s[2] * silu_f(bflo(z.y)); o[3] = v[3] * s[3] * silu_f(bfhi(z.y));
	s_nop 0


; DEV float bflo(unsigned u) { return __uint_as_float(u << 16); }
; DEV float bfhi(unsigned u) { return __uint_as_float(u & 0xffff0000u); }
; DEV float silu_f(float x) { return x / (1.f + __expf(-x)); }
;     DEV f32x4 xform(int r, int c, f32x4 v) const {
;     ...
;         o[0] = v[0] * s[0] * silu_f(bflo(z.x)); o[1] = v[1] * s[1] * silu_f(bfhi(z.x));
;         o[2] = v[2] * s[2] * silu_f(bflo(z.y)); o[3] = v[3] * s[3] * silu_f(bfhi(z.y));
	v_rcp_f32_e32 v34, v31
	s_nop 0
	v_mul_f32_e32 v31, v33, v34


; DEV float bflo(unsigned u) { return __uint_as_float(u << 16); }
; DEV float bfhi(unsigned u) { return __uint_as_float(u & 0xffff0000u); }
; DEV float silu_f(float x) { return x / (1.f + __expf(-x)); }
;     DEV f32x4 xform(int r, int c, f32x4 v) const {
;     ...
;         o[0] = v[0] * s[0] * silu_f(bflo(z.x)); o[1] = v[1] * s[1] * silu_f(bfhi(z.x));
;         o[2] = v[2] * s[2] * silu_f(bflo(z.y)); o[3] = v[3] * s[3] * silu_f(bfhi(z.y));
	s_nop 0


; DEV unsigned cvt_pk_bf16(float lo, float hi) { const f32x2_t v = {lo, hi}; const bf16x2_t b = __builtin_convertvector(v, bf16x2_t); return __builtin_bit_cast(unsigned, b); }
; DEV float bflo(unsigned u) { return __uint_as_float(u << 16); }
; DEV float bfhi(unsigned u) { return __uint_as_float(u & 0xffff0000u); }
; DEV float silu_f(float x) { return x / (1.f + __expf(-x)); }
; template <int WT, class Epi>
; DEV void gemm_tile(const bf16_t* __restrict__ A, int lda, const bf16_t* __restrict__ Bt, int ldb, int K, unsigned char* lds, const Epi& epi) {
;     ...
;                 uint2 w; w.x = cvt_pk_bf16(v[0], v[1]); w.y = cvt_pk_bf16(v[2], v[3]);
;                 *(uint2*)(lds + row * RB + ((((col >> 3) ^ (row & (CPR - 1))) << 4) | (((col >> 2) & 1) << 3))) = w;
;     DEV f32x4 xform(int r, int c, f32x4 v) const {
;     ...
;         const uint2 z = *(const uint2*)(proj + (size_t)row * NPJ + C_ZB + col);
;         const f32x4 s = *(const f32x4*)(scale + col);
;         f32x4 o;
;         o[0] = v[0] * s[0] * silu_f(bflo(z.x)); o[1] = v[1] * s[1] * silu_f(bfhi(z.x));
;         o[2] = v[2] * s[2] * silu_f(bflo(z.y)); o[3] = v[3] * s[3] * silu_f(bfhi(z.y));
	v_rcp_f32_e32 v33, v30
	s_nop 0
	v_mul_f32_e32 v30, v32, v33
	v_pk_mul_f32 v[28:29], v[28:29], v[30:31]
	s_nop 0
	v_cvt_pk_bf16_f32 v27, v28, v29
	v_add_u32_e32 v28, v44, v77
	ds_write_b64 v28, v[26:27]
	v_lshl_add_u64 v[26:27], v[38:39], 0, v[74:75]
	global_load_dwordx2 v[30:31], v[26:27], off
	s_nop 0
	global_load_dwordx4 v[26:29], v[66:67], off offset:128
	s_waitcnt vmcnt(1)
	v_lshlrev_b32_e32 v34, 16, v30
	v_and_b32_e32 v30, 0xffff0000, v30
	v_mul_f32_e32 v32, 0xbfb8aa3b, v34
	s_waitcnt vmcnt(0)
	v_pk_mul_f32 v[22:23], v[22:23], v[26:27]
	v_mul_f32_e32 v26, 0xbfb8aa3b, v30
	v_exp_f32_e32 v32, v32
	v_exp_f32_e32 v33, v26
	v_pk_mul_f32 v[24:25], v[24:25], v[28:29]
	v_pk_add_f32 v[26:27], v[32:33], 1.0 op_sel_hi:[1,0]
	s_nop 0


; DEV float bflo(unsigned u) { return __uint_as_float(u << 16); }
; DEV float bfhi(unsigned u) { return __uint_as_float(u & 0xffff0000u); }
; DEV float silu_f(float x) { return x / (1.f + __expf(-x)); }
;     DEV f32x4 xform(int r, int c, f32x4 v) const {
;     ...
;         o[0] = v[0] * s[0] * silu_f(bflo(z.x)); o[1] = v[1] * s[1] * silu_f(bfhi(z.x));
;         o[2] = v[2] * s[2] * silu_f(bflo(z.y)); o[3] = v[3] * s[3] * silu_f(bfhi(z.y));
	s_nop 0


; DEV float bflo(unsigned u) { return __uint_as_float(u << 16); }
; DEV float bfhi(unsigned u) { return __uint_as_float(u & 0xffff0000u); }
; DEV float silu_f(float x) { return x / (1.f + __expf(-x)); }
;     DEV f32x4 xform(int r, int c, f32x4 v) const {
;     ...
;         o[0] = v[0] * s[0] * silu_f(bflo(z.x)); o[1] = v[1] * s[1] * silu_f(bfhi(z.x));
;         o[2] = v[2] * s[2] * silu_f(bflo(z.y)); o[3] = v[3] * s[3] * silu_f(bfhi(z.y));
	v_rcp_f32_e32 v28, v27
	s_nop 0
	v_mul_f32_e32 v27, v30, v28


; DEV float bflo(unsigned u) { return __uint_as_float(u << 16); }
; DEV float bfhi(unsigned u) { return __uint_as_float(u & 0xffff0000u); }
; DEV float silu_f(float x) { return x / (1.f + __expf(-x)); }
;     DEV f32x4 xform(int r, int c, f32x4 v) const {
;     ...
;         o[0] = v[0] * s[0] * silu_f(bflo(z.x)); o[1] = v[1] * s[1] * silu_f(bfhi(z.x));
;         o[2] = v[2] * s[2] * silu_f(bflo(z.y)); o[3] = v[3] * s[3] * silu_f(bfhi(z.y));
	s_nop 0


; DEV float bflo(unsigned u) { return __uint_as_float(u << 16); }
; DEV float bfhi(unsigned u) { return __uint_as_float(u & 0xffff0000u); }
; DEV float silu_f(float x) { return x / (1.f + __expf(-x)); }
;     DEV f32x4 xform(int r, int c, f32x4 v) const {
;     ...
;         o[0] = v[0] * s[0] * silu_f(bflo(z.x)); o[1] = v[1] * s[1] * silu_f(bfhi(z.x));
;         o[2] = v[2] * s[2] * silu_f(bflo(z.y)); o[3] = v[3] * s[3] * silu_f(bfhi(z.y));
	v_rcp_f32_e32 v28, v26
	s_nop 0
	v_mul_f32_e32 v26, v34, v28
	v_lshlrev_b32_e32 v28, 16, v31
	v_and_b32_e32 v29, 0xffff0000, v31
	v_pk_mul_f32 v[22:23], v[22:23], v[26:27]
	v_mul_f32_e32 v26, 0xbfb8aa3b, v28
	v_mul_f32_e32 v27, 0xbfb8aa3b, v29
	v_exp_f32_e32 v26, v26
	v_exp_f32_e32 v27, v27
	v_cvt_pk_bf16_f32 v22, v22, v23
	v_pk_add_f32 v[26:27], v[26:27], 1.0 op_sel_hi:[1,0]
	s_nop 0


; DEV float bflo(unsigned u) { return __uint_as_float(u << 16); }
; DEV float bfhi(unsigned u) { return __uint_as_float(u & 0xffff0000u); }
; DEV float silu_f(float x) { return x / (1.f + __expf(-x)); }
;     DEV f32x4 xform(int r, int c, f32x4 v) const {
;     ...
;         o[0] = v[0] * s[0] * silu_f(bflo(z.x)); o[1] = v[1] * s[1] * silu_f(bfhi(z.x));
;         o[2] = v[2] * s[2] * silu_f(bflo(z.y)); o[3] = v[3] * s[3] * silu_f(bfhi(z.y));
	s_nop 0


; DEV float bflo(unsigned u) { return __uint_as_float(u << 16); }
; DEV float bfhi(unsigned u) { return __uint_as_float(u & 0xffff0000u); }
; DEV float silu_f(float x) { return x / (1.f + __expf(-x)); }
;     DEV f32x4 xform(int r, int c, f32x4 v) const {
;     ...
;         o[0] = v[0] * s[0] * silu_f(bflo(z.x)); o[1] = v[1] * s[1] * silu_f(bfhi(z.x));
;         o[2] = v[2] * s[2] * silu_f(bflo(z.y)); o[3] = v[3] * s[3] * silu_f(bfhi(z.y));
	v_rcp_f32_e32 v30, v27
	s_nop 0
	v_mul_f32_e32 v27, v29, v30


; DEV float bflo(unsigned u) { return __uint_as_float(u << 16); }
; DEV float bfhi(unsigned u) { return __uint_as_float(u & 0xffff0000u); }
; DEV float silu_f(float x) { return x / (1.f + __expf(-x)); }
;     DEV f32x4 xform(int r, int c, f32x4 v) const {
;     ...
;         o[0] = v[0] * s[0] * silu_f(bflo(z.x)); o[1] = v[1] * s[1] * silu_f(bfhi(z.x));
;         o[2] = v[2] * s[2] * silu_f(bflo(z.y)); o[3] = v[3] * s[3] * silu_f(bfhi(z.y));
	s_nop 0


; DEV unsigned cvt_pk_bf16(float lo, float hi) { const f32x2_t v = {lo, hi}; const bf16x2_t b = __builtin_convertvector(v, bf16x2_t); return __builtin_bit_cast(unsigned, b); }
; DEV float bflo(unsigned u) { return __uint_as_float(u << 16); }
; DEV float bfhi(unsigned u) { return __uint_as_float(u & 0xffff0000u); }
; DEV float silu_f(float x) { return x / (1.f + __expf(-x)); }
; template <int WT, class Epi>
; DEV void gemm_tile(const bf16_t* __restrict__ A, int lda, const bf16_t* __restrict__ Bt, int ldb, int K, unsigned char* lds, const Epi& epi) {
;     ...
;                 uint2 w; w.x = cvt_pk_bf16(v[0], v[1]); w.y = cvt_pk_bf16(v[2], v[3]);
;                 *(uint2*)(lds + row * RB + ((((col >> 3) ^ (row & (CPR - 1))) << 4) | (((col >> 2) & 1) << 3))) = w;
;     DEV f32x4 xform(int r, int c, f32x4 v) const {
;     ...
;         const uint2 z = *(const uint2*)(proj + (size_t)row * NPJ + C_ZB + col);
;         const f32x4 s = *(const f32x4*)(scale + col);
;         f32x4 o;
;         o[0] = v[0] * s[0] * silu_f(bflo(z.x)); o[1] = v[1] * s[1] * silu_f(bfhi(z.x));
;         o[2] = v[2] * s[2] * silu_f(bflo(z.y)); o[3] = v[3] * s[3] * silu_f(bfhi(z.y));
	v_rcp_f32_e32 v29, v26
	s_nop 0
	v_mul_f32_e32 v26, v28, v29
	v_pk_mul_f32 v[24:25], v[24:25], v[26:27]
	s_nop 0
	v_cvt_pk_bf16_f32 v23, v24, v25
	v_add_u32_e32 v24, v44, v64
	ds_write_b64 v24, v[22:23]
	v_lshl_add_u64 v[22:23], v[38:39], 0, v[62:63]
	global_load_dwordx2 v[26:27], v[22:23], off
	s_nop 0
	global_load_dwordx4 v[22:25], v[66:67], off offset:192
	s_waitcnt vmcnt(1)
	v_lshlrev_b32_e32 v30, 16, v26
	v_and_b32_e32 v26, 0xffff0000, v26
	v_mul_f32_e32 v28, 0xbfb8aa3b, v30
	s_waitcnt vmcnt(0)
	v_pk_mul_f32 v[18:19], v[18:19], v[22:23]
	v_mul_f32_e32 v22, 0xbfb8aa3b, v26
	v_exp_f32_e32 v28, v28
	v_exp_f32_e32 v29, v22
	v_pk_mul_f32 v[20:21], v[20:21], v[24:25]
	v_pk_add_f32 v[22:23], v[28:29], 1.0 op_sel_hi:[1,0]
	s_nop 0


; DEV float bflo(unsigned u) { return __uint_as_float(u << 16); }
; DEV float bfhi(unsigned u) { return __uint_as_float(u & 0xffff0000u); }
; DEV float silu_f(float x) { return x / (1.f + __expf(-x)); }
;     DEV f32x4 xform(int r, int c, f32x4 v) const {
;     ...
;         o[0] = v[0] * s[0] * silu_f(bflo(z.x)); o[1] = v[1] * s[1] * silu_f(bfhi(z.x));
;         o[2] = v[2] * s[2] * silu_f(bflo(z.y)); o[3] = v[3] * s[3] * silu_f(bfhi(z.y));
	s_nop 0


; DEV float bflo(unsigned u) { return __uint_as_float(u << 16); }
; DEV float bfhi(unsigned u) { return __uint_as_float(u & 0xffff0000u); }
; DEV float silu_f(float x) { return x / (1.f + __expf(-x)); }
;     DEV f32x4 xform(int r, int c, f32x4 v) const {
;     ...
;         o[0] = v[0] * s[0] * silu_f(bflo(z.x)); o[1] = v[1] * s[1] * silu_f(bfhi(z.x));
;         o[2] = v[2] * s[2] * silu_f(bflo(z.y)); o[3] = v[3] * s[3] * silu_f(bfhi(z.y));
	v_rcp_f32_e32 v24, v23
	s_nop 0
	v_mul_f32_e32 v23, v26, v24


; DEV float bflo(unsigned u) { return __uint_as_float(u << 16); }
; DEV float bfhi(unsigned u) { return __uint_as_float(u & 0xffff0000u); }
; DEV float silu_f(float x) { return x / (1.f + __expf(-x)); }
;     DEV f32x4 xform(int r, int c, f32x4 v) const {
;     ...
;         o[0] = v[0] * s[0] * silu_f(bflo(z.x)); o[1] = v[1] * s[1] * silu_f(bfhi(z.x));
;         o[2] = v[2] * s[2] * silu_f(bflo(z.y)); o[3] = v[3] * s[3] * silu_f(bfhi(z.y));
	s_nop 0


; DEV float bflo(unsigned u) { return __uint_as_float(u << 16); }
; DEV float bfhi(unsigned u) { return __uint_as_float(u & 0xffff0000u); }
; DEV float silu_f(float x) { return x / (1.f + __expf(-x)); }
;     DEV f32x4 xform(int r, int c, f32x4 v) const {
;     ...
;         o[0] = v[0] * s[0] * silu_f(bflo(z.x)); o[1] = v[1] * s[1] * silu_f(bfhi(z.x));
;         o[2] = v[2] * s[2] * silu_f(bflo(z.y)); o[3] = v[3] * s[3] * silu_f(bfhi(z.y));
	v_rcp_f32_e32 v24, v22
	s_nop 0
	v_mul_f32_e32 v22, v30, v24
	v_lshlrev_b32_e32 v24, 16, v27
	v_and_b32_e32 v25, 0xffff0000, v27
	v_pk_mul_f32 v[18:19], v[18:19], v[22:23]
	v_mul_f32_e32 v22, 0xbfb8aa3b, v24
	v_mul_f32_e32 v23, 0xbfb8aa3b, v25
	v_exp_f32_e32 v22, v22
	v_exp_f32_e32 v23, v23
	v_cvt_pk_bf16_f32 v18, v18, v19
	v_pk_add_f32 v[22:23], v[22:23], 1.0 op_sel_hi:[1,0]
	s_nop 0


; DEV float bflo(unsigned u) { return __uint_as_float(u << 16); }
; DEV float bfhi(unsigned u) { return __uint_as_float(u & 0xffff0000u); }
; DEV float silu_f(float x) { return x / (1.f + __expf(-x)); }
;     DEV f32x4 xform(int r, int c, f32x4 v) const {
;     ...
;         o[0] = v[0] * s[0] * silu_f(bflo(z.x)); o[1] = v[1] * s[1] * silu_f(bfhi(z.x));
;         o[2] = v[2] * s[2] * silu_f(bflo(z.y)); o[3] = v[3] * s[3] * silu_f(bfhi(z.y));
	s_nop 0


; DEV float bflo(unsigned u) { return __uint_as_float(u << 16); }
; DEV float bfhi(unsigned u) { return __uint_as_float(u & 0xffff0000u); }
; DEV float silu_f(float x) { return x / (1.f + __expf(-x)); }
;     DEV f32x4 xform(int r, int c, f32x4 v) const {
;     ...
;         o[0] = v[0] * s[0] * silu_f(bflo(z.x)); o[1] = v[1] * s[1] * silu_f(bfhi(z.x));
;         o[2] = v[2] * s[2] * silu_f(bflo(z.y)); o[3] = v[3] * s[3] * silu_f(bfhi(z.y));
	v_rcp_f32_e32 v26, v23
	s_nop 0
	v_mul_f32_e32 v23, v25, v26


; DEV float bflo(unsigned u) { return __uint_as_float(u << 16); }
; DEV float bfhi(unsigned u) { return __uint_as_float(u & 0xffff0000u); }
; DEV float silu_f(float x) { return x / (1.f + __expf(-x)); }
;     DEV f32x4 xform(int r, int c, f32x4 v) const {
;     ...
;         o[0] = v[0] * s[0] * silu_f(bflo(z.x)); o[1] = v[1] * s[1] * silu_f(bfhi(z.x));
;         o[2] = v[2] * s[2] * silu_f(bflo(z.y)); o[3] = v[3] * s[3] * silu_f(bfhi(z.y));
	s_nop 0


; DEV unsigned cvt_pk_bf16(float lo, float hi) { const f32x2_t v = {lo, hi}; const bf16x2_t b = __builtin_convertvector(v, bf16x2_t); return __builtin_bit_cast(unsigned, b); }
; DEV float bflo(unsigned u) { return __uint_as_float(u << 16); }
; DEV float bfhi(unsigned u) { return __uint_as_float(u & 0xffff0000u); }
; DEV float silu_f(float x) { return x / (1.f + __expf(-x)); }
; template <int WT, class Epi>
; DEV void gemm_tile(const bf16_t* __restrict__ A, int lda, const bf16_t* __restrict__ Bt, int ldb, int K, unsigned char* lds, const Epi& epi) {
;     ...
;                 uint2 w; w.x = cvt_pk_bf16(v[0], v[1]); w.y = cvt_pk_bf16(v[2], v[3]);
;                 *(uint2*)(lds + row * RB + ((((col >> 3) ^ (row & (CPR - 1))) << 4) | (((col >> 2) & 1) << 3))) = w;
;     DEV f32x4 xform(int r, int c, f32x4 v) const {
;     ...
;         const uint2 z = *(const uint2*)(proj + (size_t)row * NPJ + C_ZB + col);
;         const f32x4 s = *(const f32x4*)(scale + col);
;         f32x4 o;
;         o[0] = v[0] * s[0] * silu_f(bflo(z.x)); o[1] = v[1] * s[1] * silu_f(bfhi(z.x));
;         o[2] = v[2] * s[2] * silu_f(bflo(z.y)); o[3] = v[3] * s[3] * silu_f(bfhi(z.y));
	v_rcp_f32_e32 v25, v22
	s_nop 0
	v_mul_f32_e32 v22, v24, v25
	v_pk_mul_f32 v[20:21], v[20:21], v[22:23]
	s_nop 0
	v_cvt_pk_bf16_f32 v19, v20, v21
	v_add_u32_e32 v20, v44, v58
	ds_write_b64 v20, v[18:19]
	v_or_b32_e32 v18, 48, v130
	v_lshl_add_u32 v28, v18, 8, s70
	v_add_u32_e32 v18, s81, v18
	v_mad_i64_i32 v[18:19], s[68:69], v18, s79, v[172:173]
	v_lshl_add_u64 v[22:23], v[18:19], 0, s[66:67]
	v_lshl_add_u64 v[18:19], v[22:23], 0, v[68:69]
	global_load_dwordx2 v[24:25], v[18:19], off
	s_nop 0
	global_load_dwordx4 v[18:21], v[70:71], off
	s_waitcnt vmcnt(1)
	v_lshlrev_b32_e32 v29, 16, v24
	v_and_b32_e32 v24, 0xffff0000, v24
	v_mul_f32_e32 v26, 0xbfb8aa3b, v29
	s_waitcnt vmcnt(0)
	v_pk_mul_f32 v[14:15], v[14:15], v[18:19]
	v_mul_f32_e32 v18, 0xbfb8aa3b, v24
	v_exp_f32_e32 v26, v26
	v_exp_f32_e32 v27, v18
	v_pk_mul_f32 v[16:17], v[16:17], v[20:21]
	v_pk_add_f32 v[18:19], v[26:27], 1.0 op_sel_hi:[1,0]
	s_nop 0


; DEV float bflo(unsigned u) { return __uint_as_float(u << 16); }
; DEV float bfhi(unsigned u) { return __uint_as_float(u & 0xffff0000u); }
; DEV float silu_f(float x) { return x / (1.f + __expf(-x)); }
;     DEV f32x4 xform(int r, int c, f32x4 v) const {
;     ...
;         o[0] = v[0] * s[0] * silu_f(bflo(z.x)); o[1] = v[1] * s[1] * silu_f(bfhi(z.x));
;         o[2] = v[2] * s[2] * silu_f(bflo(z.y)); o[3] = v[3] * s[3] * silu_f(bfhi(z.y));
	s_nop 0


; DEV float bflo(unsigned u) { return __uint_as_float(u << 16); }
; DEV float bfhi(unsigned u) { return __uint_as_float(u & 0xffff0000u); }
; DEV float silu_f(float x) { return x / (1.f + __expf(-x)); }
;     DEV f32x4 xform(int r, int c, f32x4 v) const {
;     ...
;         o[0] = v[0] * s[0] * silu_f(bflo(z.x)); o[1] = v[1] * s[1] * silu_f(bfhi(z.x));
;         o[2] = v[2] * s[2] * silu_f(bflo(z.y)); o[3] = v[3] * s[3] * silu_f(bfhi(z.y));
	v_rcp_f32_e32 v20, v19
	s_nop 0
	v_mul_f32_e32 v19, v24, v20


; DEV float bflo(unsigned u) { return __uint_as_float(u << 16); }
; DEV float bfhi(unsigned u) { return __uint_as_float(u & 0xffff0000u); }
; DEV float silu_f(float x) { return x / (1.f + __expf(-x)); }
;     DEV f32x4 xform(int r, int c, f32x4 v) const {
;     ...
;         o[0] = v[0] * s[0] * silu_f(bflo(z.x)); o[1] = v[1] * s[1] * silu_f(bfhi(z.x));
;         o[2] = v[2] * s[2] * silu_f(bflo(z.y)); o[3] = v[3] * s[3] * silu_f(bfhi(z.y));
	s_nop 0


; DEV float bflo(unsigned u) { return __uint_as_float(u << 16); }
; DEV float bfhi(unsigned u) { return __uint_as_float(u & 0xffff0000u); }
; DEV float silu_f(float x) { return x / (1.f + __expf(-x)); }
;     DEV f32x4 xform(int r, int c, f32x4 v) const {
;     ...
;         o[0] = v[0] * s[0] * silu_f(bflo(z.x)); o[1] = v[1] * s[1] * silu_f(bfhi(z.x));
;         o[2] = v[2] * s[2] * silu_f(bflo(z.y)); o[3] = v[3] * s[3] * silu_f(bfhi(z.y));
	v_rcp_f32_e32 v20, v18
	s_nop 0
	v_mul_f32_e32 v18, v29, v20
	v_lshlrev_b32_e32 v20, 16, v25
	v_and_b32_e32 v21, 0xffff0000, v25
	v_pk_mul_f32 v[14:15], v[14:15], v[18:19]
	v_mul_f32_e32 v18, 0xbfb8aa3b, v20
	v_mul_f32_e32 v19, 0xbfb8aa3b, v21
	v_exp_f32_e32 v18, v18
	v_exp_f32_e32 v19, v19
	v_cvt_pk_bf16_f32 v14, v14, v15
	v_pk_add_f32 v[18:19], v[18:19], 1.0 op_sel_hi:[1,0]
	s_nop 0


; DEV float bflo(unsigned u) { return __uint_as_float(u << 16); }
; DEV float bfhi(unsigned u) { return __uint_as_float(u & 0xffff0000u); }
; DEV float silu_f(float x) { return x / (1.f + __expf(-x)); }
;     DEV f32x4 xform(int r, int c, f32x4 v) const {
;     ...
;         o[0] = v[0] * s[0] * silu_f(bflo(z.x)); o[1] = v[1] * s[1] * silu_f(bfhi(z.x));
;         o[2] = v[2] * s[2] * silu_f(bflo(z.y)); o[3] = v[3] * s[3] * silu_f(bfhi(z.y));
	s_nop 0


; DEV float bflo(unsigned u) { return __uint_as_float(u << 16); }
; DEV float bfhi(unsigned u) { return __uint_as_float(u & 0xffff0000u); }
; DEV float silu_f(float x) { return x / (1.f + __expf(-x)); }
;     DEV f32x4 xform(int r, int c, f32x4 v) const {
;     ...
;         o[0] = v[0] * s[0] * silu_f(bflo(z.x)); o[1] = v[1] * s[1] * silu_f(bfhi(z.x));
;         o[2] = v[2] * s[2] * silu_f(bflo(z.y)); o[3] = v[3] * s[3] * silu_f(bfhi(z.y));
	v_rcp_f32_e32 v24, v19
	s_nop 0
	v_mul_f32_e32 v19, v21, v24


; DEV float bflo(unsigned u) { return __uint_as_float(u << 16); }
; DEV float bfhi(unsigned u) { return __uint_as_float(u & 0xffff0000u); }
; DEV float silu_f(float x) { return x / (1.f + __expf(-x)); }
;     DEV f32x4 xform(int r, int c, f32x4 v) const {
;     ...
;         o[0] = v[0] * s[0] * silu_f(bflo(z.x)); o[1] = v[1] * s[1] * silu_f(bfhi(z.x));
;         o[2] = v[2] * s[2] * silu_f(bflo(z.y)); o[3] = v[3] * s[3] * silu_f(bfhi(z.y));
	s_nop 0


; DEV unsigned cvt_pk_bf16(float lo, float hi) { const f32x2_t v = {lo, hi}; const bf16x2_t b = __builtin_convertvector(v, bf16x2_t); return __builtin_bit_cast(unsigned, b); }
; DEV float bflo(unsigned u) { return __uint_as_float(u << 16); }
; DEV float bfhi(unsigned u) { return __uint_as_float(u & 0xffff0000u); }
; DEV float silu_f(float x) { return x / (1.f + __expf(-x)); }
; template <int WT, class Epi>
; DEV void gemm_tile(const bf16_t* __restrict__ A, int lda, const bf16_t* __restrict__ Bt, int ldb, int K, unsigned char* lds, const Epi& epi) {
;     ...
;                 uint2 w; w.x = cvt_pk_bf16(v[0], v[1]); w.y = cvt_pk_bf16(v[2], v[3]);
;                 *(uint2*)(lds + row * RB + ((((col >> 3) ^ (row & (CPR - 1))) << 4) | (((col >> 2) & 1) << 3))) = w;
;     DEV f32x4 xform(int r, int c, f32x4 v) const {
;     ...
;         const uint2 z = *(const uint2*)(proj + (size_t)row * NPJ + C_ZB + col);
;         const f32x4 s = *(const f32x4*)(scale + col);
;         f32x4 o;
;         o[0] = v[0] * s[0] * silu_f(bflo(z.x)); o[1] = v[1] * s[1] * silu_f(bfhi(z.x));
;         o[2] = v[2] * s[2] * silu_f(bflo(z.y)); o[3] = v[3] * s[3] * silu_f(bfhi(z.y));
	v_rcp_f32_e32 v21, v18
	s_nop 0
	v_mul_f32_e32 v18, v20, v21
	v_pk_mul_f32 v[16:17], v[16:17], v[18:19]
	s_nop 0
	v_cvt_pk_bf16_f32 v15, v16, v17
	v_add_u32_e32 v16, v28, v76
	ds_write_b64 v16, v[14:15]
	v_lshl_add_u64 v[14:15], v[22:23], 0, v[72:73]
	global_load_dwordx2 v[18:19], v[14:15], off
	s_nop 0
	global_load_dwordx4 v[14:17], v[66:67], off offset:64
	s_waitcnt vmcnt(1)
	v_lshlrev_b32_e32 v24, 16, v18
	v_and_b32_e32 v18, 0xffff0000, v18
	v_mul_f32_e32 v20, 0xbfb8aa3b, v24
	s_waitcnt vmcnt(0)
	v_pk_mul_f32 v[10:11], v[10:11], v[14:15]
	v_mul_f32_e32 v14, 0xbfb8aa3b, v18
	v_exp_f32_e32 v20, v20
	v_exp_f32_e32 v21, v14
	v_pk_mul_f32 v[12:13], v[12:13], v[16:17]
	v_pk_add_f32 v[14:15], v[20:21], 1.0 op_sel_hi:[1,0]
	s_nop 0


; DEV float bflo(unsigned u) { return __uint_as_float(u << 16); }
; DEV float bfhi(unsigned u) { return __uint_as_float(u & 0xffff0000u); }
; DEV float silu_f(float x) { return x / (1.f + __expf(-x)); }
;     DEV f32x4 xform(int r, int c, f32x4 v) const {
;     ...
;         o[0] = v[0] * s[0] * silu_f(bflo(z.x)); o[1] = v[1] * s[1] * silu_f(bfhi(z.x));
;         o[2] = v[2] * s[2] * silu_f(bflo(z.y)); o[3] = v[3] * s[3] * silu_f(bfhi(z.y));
	s_nop 0


; DEV float bflo(unsigned u) { return __uint_as_float(u << 16); }
; DEV float bfhi(unsigned u) { return __uint_as_float(u & 0xffff0000u); }
; DEV float silu_f(float x) { return x / (1.f + __expf(-x)); }
;     DEV f32x4 xform(int r, int c, f32x4 v) const {
;     ...
;         o[0] = v[0] * s[0] * silu_f(bflo(z.x)); o[1] = v[1] * s[1] * silu_f(bfhi(z.x));
;         o[2] = v[2] * s[2] * silu_f(bflo(z.y)); o[3] = v[3] * s[3] * silu_f(bfhi(z.y));
	v_rcp_f32_e32 v16, v15
	s_nop 0
	v_mul_f32_e32 v15, v18, v16


; DEV float bflo(unsigned u) { return __uint_as_float(u << 16); }
; DEV float bfhi(unsigned u) { return __uint_as_float(u & 0xffff0000u); }
; DEV float silu_f(float x) { return x / (1.f + __expf(-x)); }
;     DEV f32x4 xform(int r, int c, f32x4 v) const {
;     ...
;         o[0] = v[0] * s[0] * silu_f(bflo(z.x)); o[1] = v[1] * s[1] * silu_f(bfhi(z.x));
;         o[2] = v[2] * s[2] * silu_f(bflo(z.y)); o[3] = v[3] * s[3] * silu_f(bfhi(z.y));
	s_nop 0


; DEV float bflo(unsigned u) { return __uint_as_float(u << 16); }
; DEV float bfhi(unsigned u) { return __uint_as_float(u & 0xffff0000u); }
; DEV float silu_f(float x) { return x / (1.f + __expf(-x)); }
;     DEV f32x4 xform(int r, int c, f32x4 v) const {
;     ...
;         o[0] = v[0] * s[0] * silu_f(bflo(z.x)); o[1] = v[1] * s[1] * silu_f(bfhi(z.x));
;         o[2] = v[2] * s[2] * silu_f(bflo(z.y)); o[3] = v[3] * s[3] * silu_f(bfhi(z.y));
	v_rcp_f32_e32 v16, v14
	s_nop 0
	v_mul_f32_e32 v14, v24, v16
	v_lshlrev_b32_e32 v16, 16, v19
	v_and_b32_e32 v17, 0xffff0000, v19
	v_pk_mul_f32 v[10:11], v[10:11], v[14:15]
	v_mul_f32_e32 v14, 0xbfb8aa3b, v16
	v_mul_f32_e32 v15, 0xbfb8aa3b, v17
	v_exp_f32_e32 v14, v14
	v_exp_f32_e32 v15, v15
	v_cvt_pk_bf16_f32 v10, v10, v11
	v_pk_add_f32 v[14:15], v[14:15], 1.0 op_sel_hi:[1,0]
	s_nop 0


; DEV float bflo(unsigned u) { return __uint_as_float(u << 16); }
; DEV float bfhi(unsigned u) { return __uint_as_float(u & 0xffff0000u); }
; DEV float silu_f(float x) { return x / (1.f + __expf(-x)); }
;     DEV f32x4 xform(int r, int c, f32x4 v) const {
;     ...
;         o[0] = v[0] * s[0] * silu_f(bflo(z.x)); o[1] = v[1] * s[1] * silu_f(bfhi(z.x));
;         o[2] = v[2] * s[2] * silu_f(bflo(z.y)); o[3] = v[3] * s[3] * silu_f(bfhi(z.y));
	s_nop 0


; DEV float bflo(unsigned u) { return __uint_as_float(u << 16); }
; DEV float bfhi(unsigned u) { return __uint_as_float(u & 0xffff0000u); }
; DEV float silu_f(float x) { return x / (1.f + __expf(-x)); }
;     DEV f32x4 xform(int r, int c, f32x4 v) const {
;     ...
;         o[0] = v[0] * s[0] * silu_f(bflo(z.x)); o[1] = v[1] * s[1] * silu_f(bfhi(z.x));
;         o[2] = v[2] * s[2] * silu_f(bflo(z.y)); o[3] = v[3] * s[3] * silu_f(bfhi(z.y));
	v_rcp_f32_e32 v18, v15
	s_nop 0
	v_mul_f32_e32 v15, v17, v18


; DEV float bflo(unsigned u) { return __uint_as_float(u << 16); }
; DEV float bfhi(unsigned u) { return __uint_as_float(u & 0xffff0000u); }
; DEV float silu_f(float x) { return x / (1.f + __expf(-x)); }
;     DEV f32x4 xform(int r, int c, f32x4 v) const {
;     ...
;         o[0] = v[0] * s[0] * silu_f(bflo(z.x)); o[1] = v[1] * s[1] * silu_f(bfhi(z.x));
;         o[2] = v[2] * s[2] * silu_f(bflo(z.y)); o[3] = v[3] * s[3] * silu_f(bfhi(z.y));
	s_nop 0


; DEV unsigned cvt_pk_bf16(float lo, float hi) { const f32x2_t v = {lo, hi}; const bf16x2_t b = __builtin_convertvector(v, bf16x2_t); return __builtin_bit_cast(unsigned, b); }
; DEV float bflo(unsigned u) { return __uint_as_float(u << 16); }
; DEV float bfhi(unsigned u) { return __uint_as_float(u & 0xffff0000u); }
; DEV float silu_f(float x) { return x / (1.f + __expf(-x)); }
; template <int WT, class Epi>
; DEV void gemm_tile(const bf16_t* __restrict__ A, int lda, const bf16_t* __restrict__ Bt, int ldb, int K, unsigned char* lds, const Epi& epi) {
;     ...
;                 uint2 w; w.x = cvt_pk_bf16(v[0], v[1]); w.y = cvt_pk_bf16(v[2], v[3]);
;                 *(uint2*)(lds + row * RB + ((((col >> 3) ^ (row & (CPR - 1))) << 4) | (((col >> 2) & 1) << 3))) = w;
;     DEV f32x4 xform(int r, int c, f32x4 v) const {
;     ...
;         const uint2 z = *(const uint2*)(proj + (size_t)row * NPJ + C_ZB + col);
;         const f32x4 s = *(const f32x4*)(scale + col);
;         f32x4 o;
;         o[0] = v[0] * s[0] * silu_f(bflo(z.x)); o[1] = v[1] * s[1] * silu_f(bfhi(z.x));
;         o[2] = v[2] * s[2] * silu_f(bflo(z.y)); o[3] = v[3] * s[3] * silu_f(bfhi(z.y));
	v_rcp_f32_e32 v17, v14
	s_nop 0
	v_mul_f32_e32 v14, v16, v17
	v_pk_mul_f32 v[12:13], v[12:13], v[14:15]
	s_nop 0
	v_cvt_pk_bf16_f32 v11, v12, v13
	v_add_u32_e32 v12, v28, v77
	ds_write_b64 v12, v[10:11]
	v_lshl_add_u64 v[10:11], v[22:23], 0, v[74:75]
	global_load_dwordx2 v[14:15], v[10:11], off
	s_nop 0
	global_load_dwordx4 v[10:13], v[66:67], off offset:128
	s_waitcnt vmcnt(1)
	v_lshlrev_b32_e32 v18, 16, v14
	v_and_b32_e32 v14, 0xffff0000, v14
	v_mul_f32_e32 v16, 0xbfb8aa3b, v18
	s_waitcnt vmcnt(0)
	v_pk_mul_f32 v[6:7], v[6:7], v[10:11]
	v_mul_f32_e32 v10, 0xbfb8aa3b, v14
	v_exp_f32_e32 v16, v16
	v_exp_f32_e32 v17, v10
	v_pk_mul_f32 v[8:9], v[8:9], v[12:13]
	v_pk_add_f32 v[10:11], v[16:17], 1.0 op_sel_hi:[1,0]
	s_nop 0


; DEV float bflo(unsigned u) { return __uint_as_float(u << 16); }
; DEV float bfhi(unsigned u) { return __uint_as_float(u & 0xffff0000u); }
; DEV float silu_f(float x) { return x / (1.f + __expf(-x)); }
;     DEV f32x4 xform(int r, int c, f32x4 v) const {
;     ...
;         o[0] = v[0] * s[0] * silu_f(bflo(z.x)); o[1] = v[1] * s[1] * silu_f(bfhi(z.x));
;         o[2] = v[2] * s[2] * silu_f(bflo(z.y)); o[3] = v[3] * s[3] * silu_f(bfhi(z.y));
	s_nop 0


; DEV float bflo(unsigned u) { return __uint_as_float(u << 16); }
; DEV float bfhi(unsigned u) { return __uint_as_float(u & 0xffff0000u); }
; DEV float silu_f(float x) { return x / (1.f + __expf(-x)); }
;     DEV f32x4 xform(int r, int c, f32x4 v) const {
;     ...
;         o[0] = v[0] * s[0] * silu_f(bflo(z.x)); o[1] = v[1] * s[1] * silu_f(bfhi(z.x));
;         o[2] = v[2] * s[2] * silu_f(bflo(z.y)); o[3] = v[3] * s[3] * silu_f(bfhi(z.y));
	v_rcp_f32_e32 v12, v11
	s_nop 0
	v_mul_f32_e32 v11, v14, v12


; DEV float bflo(unsigned u) { return __uint_as_float(u << 16); }
; DEV float bfhi(unsigned u) { return __uint_as_float(u & 0xffff0000u); }
; DEV float silu_f(float x) { return x / (1.f + __expf(-x)); }
;     DEV f32x4 xform(int r, int c, f32x4 v) const {
;     ...
;         o[0] = v[0] * s[0] * silu_f(bflo(z.x)); o[1] = v[1] * s[1] * silu_f(bfhi(z.x));
;         o[2] = v[2] * s[2] * silu_f(bflo(z.y)); o[3] = v[3] * s[3] * silu_f(bfhi(z.y));
	s_nop 0


; DEV float bflo(unsigned u) { return __uint_as_float(u << 16); }
; DEV float bfhi(unsigned u) { return __uint_as_float(u & 0xffff0000u); }
; DEV float silu_f(float x) { return x / (1.f + __expf(-x)); }
;     DEV f32x4 xform(int r, int c, f32x4 v) const {
;     ...
;         o[0] = v[0] * s[0] * silu_f(bflo(z.x)); o[1] = v[1] * s[1] * silu_f(bfhi(z.x));
;         o[2] = v[2] * s[2] * silu_f(bflo(z.y)); o[3] = v[3] * s[3] * silu_f(bfhi(z.y));
	v_rcp_f32_e32 v12, v10
	s_nop 0
	v_mul_f32_e32 v10, v18, v12
	v_lshlrev_b32_e32 v12, 16, v15
	v_and_b32_e32 v13, 0xffff0000, v15
	v_pk_mul_f32 v[6:7], v[6:7], v[10:11]
	v_mul_f32_e32 v10, 0xbfb8aa3b, v12
	v_mul_f32_e32 v11, 0xbfb8aa3b, v13
	v_exp_f32_e32 v10, v10
	v_exp_f32_e32 v11, v11
	v_cvt_pk_bf16_f32 v6, v6, v7
	v_pk_add_f32 v[10:11], v[10:11], 1.0 op_sel_hi:[1,0]
	s_nop 0


; DEV float bflo(unsigned u) { return __uint_as_float(u << 16); }
; DEV float bfhi(unsigned u) { return __uint_as_float(u & 0xffff0000u); }
; DEV float silu_f(float x) { return x / (1.f + __expf(-x)); }
;     DEV f32x4 xform(int r, int c, f32x4 v) const {
;     ...
;         o[0] = v[0] * s[0] * silu_f(bflo(z.x)); o[1] = v[1] * s[1] * silu_f(bfhi(z.x));
;         o[2] = v[2] * s[2] * silu_f(bflo(z.y)); o[3] = v[3] * s[3] * silu_f(bfhi(z.y));
	s_nop 0


; DEV float bflo(unsigned u) { return __uint_as_float(u << 16); }
; DEV float bfhi(unsigned u) { return __uint_as_float(u & 0xffff0000u); }
; DEV float silu_f(float x) { return x / (1.f + __expf(-x)); }
;     DEV f32x4 xform(int r, int c, f32x4 v) const {
;     ...
;         o[0] = v[0] * s[0] * silu_f(bflo(z.x)); o[1] = v[1] * s[1] * silu_f(bfhi(z.x));
;         o[2] = v[2] * s[2] * silu_f(bflo(z.y)); o[3] = v[3] * s[3] * silu_f(bfhi(z.y));
	v_rcp_f32_e32 v14, v11
	s_nop 0
	v_mul_f32_e32 v11, v13, v14


; DEV float bflo(unsigned u) { return __uint_as_float(u << 16); }
; DEV float bfhi(unsigned u) { return __uint_as_float(u & 0xffff0000u); }
; DEV float silu_f(float x) { return x / (1.f + __expf(-x)); }
;     DEV f32x4 xform(int r, int c, f32x4 v) const {
;     ...
;         o[0] = v[0] * s[0] * silu_f(bflo(z.x)); o[1] = v[1] * s[1] * silu_f(bfhi(z.x));
;         o[2] = v[2] * s[2] * silu_f(bflo(z.y)); o[3] = v[3] * s[3] * silu_f(bfhi(z.y));
	s_nop 0


; DEV unsigned cvt_pk_bf16(float lo, float hi) { const f32x2_t v = {lo, hi}; const bf16x2_t b = __builtin_convertvector(v, bf16x2_t); return __builtin_bit_cast(unsigned, b); }
; DEV float bflo(unsigned u) { return __uint_as_float(u << 16); }
; DEV float bfhi(unsigned u) { return __uint_as_float(u & 0xffff0000u); }
; DEV float silu_f(float x) { return x / (1.f + __expf(-x)); }
; template <int WT, class Epi>
; DEV void gemm_tile(const bf16_t* __restrict__ A, int lda, const bf16_t* __restrict__ Bt, int ldb, int K, unsigned char* lds, const Epi& epi) {
;     ...
;                 uint2 w; w.x = cvt_pk_bf16(v[0], v[1]); w.y = cvt_pk_bf16(v[2], v[3]);
;                 *(uint2*)(lds + row * RB + ((((col >> 3) ^ (row & (CPR - 1))) << 4) | (((col >> 2) & 1) << 3))) = w;
;     DEV f32x4 xform(int r, int c, f32x4 v) const {
;     ...
;         const uint2 z = *(const uint2*)(proj + (size_t)row * NPJ + C_ZB + col);
;         const f32x4 s = *(const f32x4*)(scale + col);
;         f32x4 o;
;         o[0] = v[0] * s[0] * silu_f(bflo(z.x)); o[1] = v[1] * s[1] * silu_f(bfhi(z.x));
;         o[2] = v[2] * s[2] * silu_f(bflo(z.y)); o[3] = v[3] * s[3] * silu_f(bfhi(z.y));
	v_rcp_f32_e32 v13, v10
	s_nop 0
	v_mul_f32_e32 v10, v12, v13
	v_pk_mul_f32 v[8:9], v[8:9], v[10:11]
	s_nop 0
	v_cvt_pk_bf16_f32 v7, v8, v9
	v_add_u32_e32 v8, v28, v64
	ds_write_b64 v8, v[6:7]
	v_lshl_add_u64 v[6:7], v[22:23], 0, v[62:63]
	global_load_dwordx2 v[10:11], v[6:7], off
	s_nop 0
	global_load_dwordx4 v[6:9], v[66:67], off offset:192
	s_waitcnt vmcnt(1)
	v_lshlrev_b32_e32 v14, 16, v10
	v_and_b32_e32 v10, 0xffff0000, v10
	v_mul_f32_e32 v12, 0xbfb8aa3b, v14
	s_waitcnt vmcnt(0)
	v_pk_mul_f32 v[2:3], v[2:3], v[6:7]
	v_mul_f32_e32 v6, 0xbfb8aa3b, v10
	v_exp_f32_e32 v12, v12
	v_exp_f32_e32 v13, v6
	v_pk_mul_f32 v[4:5], v[4:5], v[8:9]
	v_pk_add_f32 v[6:7], v[12:13], 1.0 op_sel_hi:[1,0]
	s_nop 0


; DEV float bflo(unsigned u) { return __uint_as_float(u << 16); }
; DEV float bfhi(unsigned u) { return __uint_as_float(u & 0xffff0000u); }
; DEV float silu_f(float x) { return x / (1.f + __expf(-x)); }
;     DEV f32x4 xform(int r, int c, f32x4 v) const {
;     ...
;         o[0] = v[0] * s[0] * silu_f(bflo(z.x)); o[1] = v[1] * s[1] * silu_f(bfhi(z.x));
;         o[2] = v[2] * s[2] * silu_f(bflo(z.y)); o[3] = v[3] * s[3] * silu_f(bfhi(z.y));
	s_nop 0


; DEV float bflo(unsigned u) { return __uint_as_float(u << 16); }
; DEV float bfhi(unsigned u) { return __uint_as_float(u & 0xffff0000u); }
; DEV float silu_f(float x) { return x / (1.f + __expf(-x)); }
;     DEV f32x4 xform(int r, int c, f32x4 v) const {
;     ...
;         o[0] = v[0] * s[0] * silu_f(bflo(z.x)); o[1] = v[1] * s[1] * silu_f(bfhi(z.x));
;         o[2] = v[2] * s[2] * silu_f(bflo(z.y)); o[3] = v[3] * s[3] * silu_f(bfhi(z.y));
	v_rcp_f32_e32 v8, v7
	s_nop 0
	v_mul_f32_e32 v7, v10, v8


; DEV float bflo(unsigned u) { return __uint_as_float(u << 16); }
; DEV float bfhi(unsigned u) { return __uint_as_float(u & 0xffff0000u); }
; DEV float silu_f(float x) { return x / (1.f + __expf(-x)); }
;     DEV f32x4 xform(int r, int c, f32x4 v) const {
;     ...
;         o[0] = v[0] * s[0] * silu_f(bflo(z.x)); o[1] = v[1] * s[1] * silu_f(bfhi(z.x));
;         o[2] = v[2] * s[2] * silu_f(bflo(z.y)); o[3] = v[3] * s[3] * silu_f(bfhi(z.y));
	s_nop 0


; DEV float bflo(unsigned u) { return __uint_as_float(u << 16); }
; DEV float bfhi(unsigned u) { return __uint_as_float(u & 0xffff0000u); }
; DEV float silu_f(float x) { return x / (1.f + __expf(-x)); }
;     DEV f32x4 xform(int r, int c, f32x4 v) const {
;     ...
;         o[0] = v[0] * s[0] * silu_f(bflo(z.x)); o[1] = v[1] * s[1] * silu_f(bfhi(z.x));
;         o[2] = v[2] * s[2] * silu_f(bflo(z.y)); o[3] = v[3] * s[3] * silu_f(bfhi(z.y));
	v_rcp_f32_e32 v8, v6
	s_nop 0
	v_mul_f32_e32 v6, v14, v8
	v_lshlrev_b32_e32 v8, 16, v11
	v_and_b32_e32 v9, 0xffff0000, v11
	v_pk_mul_f32 v[2:3], v[2:3], v[6:7]
	v_mul_f32_e32 v6, 0xbfb8aa3b, v8
	v_mul_f32_e32 v7, 0xbfb8aa3b, v9
	v_exp_f32_e32 v6, v6
	v_exp_f32_e32 v7, v7
	v_cvt_pk_bf16_f32 v2, v2, v3
	v_pk_add_f32 v[6:7], v[6:7], 1.0 op_sel_hi:[1,0]
	s_nop 0


; DEV float bflo(unsigned u) { return __uint_as_float(u << 16); }
; DEV float bfhi(unsigned u) { return __uint_as_float(u & 0xffff0000u); }
; DEV float silu_f(float x) { return x / (1.f + __expf(-x)); }
;     DEV f32x4 xform(int r, int c, f32x4 v) const {
;     ...
;         o[0] = v[0] * s[0] * silu_f(bflo(z.x)); o[1] = v[1] * s[1] * silu_f(bfhi(z.x));
;         o[2] = v[2] * s[2] * silu_f(bflo(z.y)); o[3] = v[3] * s[3] * silu_f(bfhi(z.y));
	s_nop 0


; DEV float bflo(unsigned u) { return __uint_as_float(u << 16); }
; DEV float bfhi(unsigned u) { return __uint_as_float(u & 0xffff0000u); }
; DEV float silu_f(float x) { return x / (1.f + __expf(-x)); }
;     DEV f32x4 xform(int r, int c, f32x4 v) const {
;     ...
;         o[0] = v[0] * s[0] * silu_f(bflo(z.x)); o[1] = v[1] * s[1] * silu_f(bfhi(z.x));
;         o[2] = v[2] * s[2] * silu_f(bflo(z.y)); o[3] = v[3] * s[3] * silu_f(bfhi(z.y));
	v_rcp_f32_e32 v10, v7
	s_nop 0
	v_mul_f32_e32 v7, v9, v10


; DEV float bflo(unsigned u) { return __uint_as_float(u << 16); }
; DEV float bfhi(unsigned u) { return __uint_as_float(u & 0xffff0000u); }
; DEV float silu_f(float x) { return x / (1.f + __expf(-x)); }
;     DEV f32x4 xform(int r, int c, f32x4 v) const {
;     ...
;         o[0] = v[0] * s[0] * silu_f(bflo(z.x)); o[1] = v[1] * s[1] * silu_f(bfhi(z.x));
;         o[2] = v[2] * s[2] * silu_f(bflo(z.y)); o[3] = v[3] * s[3] * silu_f(bfhi(z.y));
	s_nop 0


; DEV float bflo(unsigned u) { return __uint_as_float(u << 16); }
; DEV float bfhi(unsigned u) { return __uint_as_float(u & 0xffff0000u); }
; DEV float silu_f(float x) { return x / (1.f + __expf(-x)); }
; template <int WT, class Epi>
; DEV void gemm_tile(const bf16_t* __restrict__ A, int lda, const bf16_t* __restrict__ Bt, int ldb, int K, unsigned char* lds, const Epi& epi) {
;     ...
;         __syncthreads();
; #pragma unroll
;         for (int i = 0; i < (2 * WT * CPR) / 256; ++i) {
;             const int idx = tid + 256 * i, row = idx / CPR, cp = idx % CPR, c = cp ^ (row & (CPR - 1));
;             const uint4 d = *(const uint4*)(lds + row * RB + (cp << 4));
;             *(uint4*)(epi.obase + (size_t)row * epi.old + c * 8) = epi.finish(row, c * 8, d);
;         }
;     DEV f32x4 xform(int r, int c, f32x4 v) const {
;     ...
;         o[0] = v[0] * s[0] * silu_f(bflo(z.x)); o[1] = v[1] * s[1] * silu_f(bfhi(z.x));
;         o[2] = v[2] * s[2] * silu_f(bflo(z.y)); o[3] = v[3] * s[3] * silu_f(bfhi(z.y));
	v_rcp_f32_e32 v9, v6
	s_nop 0
	v_mul_f32_e32 v6, v8, v9
	v_pk_mul_f32 v[4:5], v[4:5], v[6:7]
	s_nop 0
	v_cvt_pk_bf16_f32 v3, v4, v5
	v_add_u32_e32 v4, v28, v58
	ds_write_b64 v4, v[2:3]
	v_ashrrev_i32_e32 v2, 31, v137
	v_lshrrev_b32_e32 v2, 28, v2
	v_add_u32_e32 v2, v137, v2
	v_ashrrev_i32_e32 v3, 4, v2
	v_and_b32_e32 v2, -16, v2
	v_sub_u32_e32 v2, v137, v2
	v_bitop3_b32 v4, v3, v2, 15 bitop3:0x6c
	v_lshlrev_b32_e32 v5, 8, v3
	v_lshlrev_b32_e32 v2, 4, v2
	v_add3_u32 v8, s70, v5, v2
	v_lshlrev_b32_e32 v2, 3, v4
	v_mad_i64_i32 v[4:5], s[68:69], v3, s80, v[132:133]
	v_ashrrev_i32_e32 v3, 31, v2
	s_waitcnt lgkmcnt(0)
	s_barrier
	v_lshl_add_u64 v[6:7], v[2:3], 1, v[4:5]
	ds_read_b128 v[2:5], v8
	s_waitcnt lgkmcnt(0)
	global_store_dwordx4 v[6:7], v[2:5], off offset:2048
	s_nop 1
	v_add_u32_e32 v2, 0x100, v137
	v_ashrrev_i32_e32 v3, 31, v2
	v_lshrrev_b32_e32 v3, 28, v3
	v_add_u32_e32 v3, v2, v3
	v_ashrrev_i32_e32 v4, 4, v3
	v_and_b32_e32 v3, -16, v3
	v_sub_u32_e32 v2, v2, v3
	v_bitop3_b32 v3, v4, v2, 15 bitop3:0x6c
	v_lshlrev_b32_e32 v5, 8, v4
	v_lshlrev_b32_e32 v2, 4, v2
	v_add3_u32 v8, s70, v5, v2
	v_lshlrev_b32_e32 v2, 3, v3
	v_mad_i64_i32 v[4:5], s[68:69], v4, s80, v[132:133]
	v_ashrrev_i32_e32 v3, 31, v2
	v_lshl_add_u64 v[6:7], v[2:3], 1, v[4:5]
	ds_read_b128 v[2:5], v8
	s_waitcnt lgkmcnt(0)
	global_store_dwordx4 v[6:7], v[2:5], off offset:2048
	s_nop 1
	v_add_u32_e32 v2, 0x200, v137
	v_ashrrev_i32_e32 v3, 31, v2
	v_lshrrev_b32_e32 v3, 28, v3
	v_add_u32_e32 v3, v2, v3
	v_ashrrev_i32_e32 v4, 4, v3
	v_and_b32_e32 v3, -16, v3
	v_sub_u32_e32 v2, v2, v3
	v_bitop3_b32 v3, v4, v2, 15 bitop3:0x6c
	v_lshlrev_b32_e32 v5, 8, v4
	v_lshlrev_b32_e32 v2, 4, v2
	v_add3_u32 v8, s70, v5, v2
	v_lshlrev_b32_e32 v2, 3, v3
	v_mad_i64_i32 v[4:5], s[68:69], v4, s80, v[132:133]
	v_ashrrev_i32_e32 v3, 31, v2
	v_lshl_add_u64 v[6:7], v[2:3], 1, v[4:5]
	ds_read_b128 v[2:5], v8
	s_waitcnt lgkmcnt(0)
	global_store_dwordx4 v[6:7], v[2:5], off offset:2048
	s_nop 1
	v_add_u32_e32 v2, 0x300, v137
	v_ashrrev_i32_e32 v3, 31, v2
	v_lshrrev_b32_e32 v3, 28, v3
	v_add_u32_e32 v3, v2, v3
	v_ashrrev_i32_e32 v4, 4, v3
	v_and_b32_e32 v3, -16, v3
	v_sub_u32_e32 v2, v2, v3
	v_bitop3_b32 v3, v4, v2, 15 bitop3:0x6c
	v_lshlrev_b32_e32 v5, 8, v4
	v_lshlrev_b32_e32 v2, 4, v2
	v_add3_u32 v8, s70, v5, v2
	v_lshlrev_b32_e32 v2, 3, v3
	v_mad_i64_i32 v[4:5], s[68:69], v4, s80, v[132:133]
	v_ashrrev_i32_e32 v3, 31, v2
	v_lshl_add_u64 v[6:7], v[2:3], 1, v[4:5]
	ds_read_b128 v[2:5], v8
	s_waitcnt lgkmcnt(0)
	global_store_dwordx4 v[6:7], v[2:5], off offset:2048
	s_nop 1
	v_add_u32_e32 v2, 0x400, v137
	v_ashrrev_i32_e32 v3, 31, v2
	v_lshrrev_b32_e32 v3, 28, v3
	v_add_u32_e32 v3, v2, v3
	v_ashrrev_i32_e32 v4, 4, v3
	v_and_b32_e32 v3, -16, v3
	v_sub_u32_e32 v2, v2, v3
	v_bitop3_b32 v3, v4, v2, 15 bitop3:0x6c
	v_lshlrev_b32_e32 v5, 8, v4
	v_lshlrev_b32_e32 v2, 4, v2
	v_add3_u32 v8, s70, v5, v2
	v_lshlrev_b32_e32 v2, 3, v3
	v_mad_i64_i32 v[4:5], s[68:69], v4, s80, v[132:133]
	v_ashrrev_i32_e32 v3, 31, v2
	v_lshl_add_u64 v[6:7], v[2:3], 1, v[4:5]
	ds_read_b128 v[2:5], v8
	s_waitcnt lgkmcnt(0)
	global_store_dwordx4 v[6:7], v[2:5], off offset:2048
	s_nop 1
	v_add_u32_e32 v2, 0x500, v137
	v_ashrrev_i32_e32 v3, 31, v2
	v_lshrrev_b32_e32 v3, 28, v3
	v_add_u32_e32 v3, v2, v3
	v_ashrrev_i32_e32 v4, 4, v3
	v_and_b32_e32 v3, -16, v3
	v_sub_u32_e32 v2, v2, v3
	v_bitop3_b32 v3, v4, v2, 15 bitop3:0x6c
	v_lshlrev_b32_e32 v5, 8, v4
	v_lshlrev_b32_e32 v2, 4, v2
	v_add3_u32 v8, s70, v5, v2
	v_lshlrev_b32_e32 v2, 3, v3
	v_mad_i64_i32 v[4:5], s[68:69], v4, s80, v[132:133]
	v_ashrrev_i32_e32 v3, 31, v2
	v_lshl_add_u64 v[6:7], v[2:3], 1, v[4:5]
	ds_read_b128 v[2:5], v8
	s_waitcnt lgkmcnt(0)
	global_store_dwordx4 v[6:7], v[2:5], off offset:2048
	s_nop 1
	v_add_u32_e32 v2, 0x600, v137
	v_ashrrev_i32_e32 v3, 31, v2
	v_lshrrev_b32_e32 v3, 28, v3
	v_add_u32_e32 v3, v2, v3
	v_ashrrev_i32_e32 v4, 4, v3
	v_and_b32_e32 v3, -16, v3
	v_sub_u32_e32 v2, v2, v3
	v_bitop3_b32 v3, v4, v2, 15 bitop3:0x6c
	v_lshlrev_b32_e32 v5, 8, v4
	v_lshlrev_b32_e32 v2, 4, v2
	v_add3_u32 v8, s70, v5, v2
	v_lshlrev_b32_e32 v2, 3, v3
	v_mad_i64_i32 v[4:5], s[68:69], v4, s80, v[132:133]
	v_ashrrev_i32_e32 v3, 31, v2
	v_lshl_add_u64 v[6:7], v[2:3], 1, v[4:5]
	ds_read_b128 v[2:5], v8
	s_waitcnt lgkmcnt(0)
	global_store_dwordx4 v[6:7], v[2:5], off offset:2048
	s_nop 1
	v_add_u32_e32 v2, 0x700, v137
	v_ashrrev_i32_e32 v3, 31, v2
	v_lshrrev_b32_e32 v3, 28, v3
	v_add_u32_e32 v3, v2, v3
	v_ashrrev_i32_e32 v4, 4, v3
	v_and_b32_e32 v3, -16, v3
	v_sub_u32_e32 v2, v2, v3
	v_bitop3_b32 v3, v4, v2, 15 bitop3:0x6c
	v_lshlrev_b32_e32 v5, 8, v4
	v_lshlrev_b32_e32 v2, 4, v2
	v_add3_u32 v8, s70, v5, v2
	v_lshlrev_b32_e32 v2, 3, v3
	v_mad_i64_i32 v[4:5], s[68:69], v4, s80, v[132:133]
	v_ashrrev_i32_e32 v3, 31, v2
	v_lshl_add_u64 v[6:7], v[2:3], 1, v[4:5]
	ds_read_b128 v[2:5], v8
	s_waitcnt lgkmcnt(0)
	global_store_dwordx4 v[6:7], v[2:5], off offset:2048
	s_barrier
	s_cbranch_scc1 .LBB0_870

; DEV unsigned cvt_pk_bf16(float lo, float hi) { const f32x2_t v = {lo, hi}; const bf16x2_t b = __builtin_convertvector(v, bf16x2_t); return __builtin_bit_cast(unsigned, b); }
; DEV float bflo(unsigned u) { return __uint_as_float(u << 16); }
; DEV float bfhi(unsigned u) { return __uint_as_float(u & 0xffff0000u); }
; DEV float silu_f(float x) { return x / (1.f + __expf(-x)); }
; __global__ void __launch_bounds__(512) hymba_fwd(Params p) {
;     ...
;         for (int i = bid * 512 + tid; i < TP * 8 * 16; i += G * 512) {
;             const int l16 = i & 15, rh = i >> 4, h = rh & 7, row = rh >> 3;
;             const float* op = obuf + (size_t)row * 1024 + h * 128 + l16 * 8;
;             const f32x4 a = __builtin_nontemporal_load((const f32x4*)op), b4 = __builtin_nontemporal_load((const f32x4*)(op + 4));
;             float ss = a[0] * a[0] + a[1] * a[1] + a[2] * a[2] + a[3] * a[3] + b4[0] * b4[0] + b4[1] * b4[1] + b4[2] * b4[2] + b4[3] * b4[3];
;             ss += __shfl_xor(ss, 1); ss += __shfl_xor(ss, 2); ss += __shfl_xor(ss, 4); ss += __shfl_xor(ss, 8);
;             const float rs = rsqrtf(ss * (1.f / 128.f) + EPS);
;             const f32x4 g0 = *(const f32x4*)(p.in[13] + l16 * 8), g1 = *(const f32x4*)(p.in[13] + l16 * 8 + 4);
;             const uint4 z = *(const uint4*)(proj + (size_t)row * NPJ + C_ZA + h * 128 + l16 * 8);
;             uint4 o;
;             o.x = cvt_pk_bf16(a[0] * rs * g0[0] * silu_f(bflo(z.x)), a[1] * rs * g0[1] * silu_f(bfhi(z.x)));
;             o.y = cvt_pk_bf16(a[2] * rs * g0[2] * silu_f(bflo(z.y)), a[3] * rs * g0[3] * silu_f(bfhi(z.y)));
;             o.z = cvt_pk_bf16(b4[0] * rs * g1[0] * silu_f(bflo(z.z)), b4[1] * rs * g1[1] * silu_f(bfhi(z.z)));
;             o.w = cvt_pk_bf16(b4[2] * rs * g1[2] * silu_f(bflo(z.w)), b4[3] * rs * g1[3] * silu_f(bfhi(z.w)));
;             *(uint4*)(mix + (size_t)row * LDB + h * 128 + l16 * 8) = o;
.LBB0_945:
	v_ashrrev_i32_e32 v6, 7, v1
	v_ashrrev_i32_e32 v7, 31, v6
	v_and_b32_e32 v22, 0x380, v12
	v_mad_i64_i32 v[32:33], s[4:5], v6, s31, v[172:173]
	v_mad_i64_i32 v[34:35], s[4:5], v6, s35, v[174:175]
	v_lshlrev_b64 v[6:7], 12, v[6:7]
	v_and_b32_e32 v14, 0x78, v12
	v_lshlrev_b32_e32 v4, 2, v22
	v_lshl_add_u64 v[6:7], v[2:3], 0, v[6:7]
	v_lshl_add_u64 v[6:7], v[6:7], 0, v[4:5]
	v_lshlrev_b32_e32 v4, 2, v14
	v_lshl_add_u64 v[6:7], v[6:7], 0, v[4:5]
	v_lshlrev_b32_e32 v30, 1, v14
	s_waitcnt lgkmcnt(0)
	global_load_dwordx4 v[14:17], v4, s[22:23] offset:16
	global_load_dwordx4 v[18:21], v4, s[22:23]
	v_lshlrev_b32_e32 v4, 1, v22
	global_load_dwordx4 v[22:25], v[6:7], off offset:16 nt
	global_load_dwordx4 v[26:29], v[6:7], off nt
	v_mov_b32_e32 v31, v5
	v_add_u32_e32 v1, s26, v1
	v_lshl_add_u64 v[6:7], v[32:33], 0, v[4:5]
	v_cmp_lt_i32_e32 vcc, s36, v1
	v_lshl_add_u64 v[6:7], v[6:7], 0, v[30:31]
	s_or_b64 s[24:25], vcc, s[24:25]
	v_add_co_u32_e32 v6, vcc, s34, v6
	v_lshl_add_u64 v[32:33], v[34:35], 0, v[4:5]
	s_nop 0
	v_addc_co_u32_e32 v7, vcc, 0, v7, vcc
	v_lshl_add_u64 v[34:35], v[32:33], 0, v[30:31]
	global_load_dwordx4 v[30:33], v[6:7], off offset:2048
	v_add_u32_e32 v12, s27, v12
	s_waitcnt vmcnt(2)
	v_pk_mul_f32 v[38:39], v[22:23], v[22:23]
	s_waitcnt vmcnt(1)
	v_mul_f32_e32 v4, v27, v27
	v_pk_mul_f32 v[6:7], v[28:29], v[28:29]
	v_fmac_f32_e32 v4, v26, v26
	v_add_f32_e32 v4, v6, v4
	v_add_f32_e32 v4, v7, v4
	v_add_f32_e32 v4, v38, v4
	v_pk_mul_f32 v[36:37], v[24:25], v[24:25]
	v_add_f32_e32 v4, v39, v4
	v_add_f32_e32 v4, v36, v4
	v_add_f32_e32 v4, v37, v4
	s_waitcnt vmcnt(0)
	v_and_b32_e32 v47, 0xffff0000, v33
	v_lshlrev_b32_e32 v40, 16, v30
	v_and_b32_e32 v41, 0xffff0000, v30
	v_mul_f32_e32 v48, 0xbfb8aa3b, v47
	v_lshlrev_b32_e32 v46, 16, v33
	v_mul_f32_e32 v6, 0xbfb8aa3b, v40
	v_mul_f32_e32 v7, 0xbfb8aa3b, v41
	v_exp_f32_e32 v39, v48
	ds_bpermute_b32 v48, v8, v4
	v_lshlrev_b32_e32 v42, 16, v31
	v_and_b32_e32 v43, 0xffff0000, v31
	v_mul_f32_e32 v38, 0xbfb8aa3b, v46
	v_exp_f32_e32 v6, v6
	v_exp_f32_e32 v7, v7
	v_mul_f32_e32 v30, 0xbfb8aa3b, v42
	v_mul_f32_e32 v31, 0xbfb8aa3b, v43
	v_exp_f32_e32 v38, v38
	v_lshlrev_b32_e32 v44, 16, v32
	v_and_b32_e32 v45, 0xffff0000, v32
	v_exp_f32_e32 v30, v30
	v_exp_f32_e32 v31, v31
	v_mul_f32_e32 v32, 0xbfb8aa3b, v44
	v_mul_f32_e32 v33, 0xbfb8aa3b, v45
	v_exp_f32_e32 v32, v32
	v_exp_f32_e32 v33, v33
	v_pk_add_f32 v[6:7], v[6:7], 1.0 op_sel_hi:[1,0]
	s_waitcnt lgkmcnt(0)
	v_add_f32_e32 v4, v4, v48
	v_pk_add_f32 v[36:37], v[38:39], 1.0 op_sel_hi:[1,0]

; DEV unsigned cvt_pk_bf16(float lo, float hi) { const f32x2_t v = {lo, hi}; const bf16x2_t b = __builtin_convertvector(v, bf16x2_t); return __builtin_bit_cast(unsigned, b); }
; DEV float bflo(unsigned u) { return __uint_as_float(u << 16); }
; DEV float bfhi(unsigned u) { return __uint_as_float(u & 0xffff0000u); }
; DEV float silu_f(float x) { return x / (1.f + __expf(-x)); }
; __global__ void __launch_bounds__(512) hymba_fwd(Params p) {
;     ...
;             ss += __shfl_xor(ss, 1); ss += __shfl_xor(ss, 2); ss += __shfl_xor(ss, 4); ss += __shfl_xor(ss, 8);
;             const float rs = rsqrtf(ss * (1.f / 128.f) + EPS);
;             const f32x4 g0 = *(const f32x4*)(p.in[13] + l16 * 8), g1 = *(const f32x4*)(p.in[13] + l16 * 8 + 4);
;             const uint4 z = *(const uint4*)(proj + (size_t)row * NPJ + C_ZA + h * 128 + l16 * 8);
;             uint4 o;
;             o.x = cvt_pk_bf16(a[0] * rs * g0[0] * silu_f(bflo(z.x)), a[1] * rs * g0[1] * silu_f(bfhi(z.x)));
;             o.y = cvt_pk_bf16(a[2] * rs * g0[2] * silu_f(bflo(z.y)), a[3] * rs * g0[3] * silu_f(bfhi(z.y)));
;             o.z = cvt_pk_bf16(b4[0] * rs * g1[0] * silu_f(bflo(z.z)), b4[1] * rs * g1[1] * silu_f(bfhi(z.z)));
;             o.w = cvt_pk_bf16(b4[2] * rs * g1[2] * silu_f(bflo(z.w)), b4[3] * rs * g1[3] * silu_f(bfhi(z.w)));
	ds_bpermute_b32 v48, v9, v4
	v_pk_add_f32 v[30:31], v[30:31], 1.0 op_sel_hi:[1,0]


; DEV unsigned cvt_pk_bf16(float lo, float hi) { const f32x2_t v = {lo, hi}; const bf16x2_t b = __builtin_convertvector(v, bf16x2_t); return __builtin_bit_cast(unsigned, b); }
; DEV float bflo(unsigned u) { return __uint_as_float(u << 16); }
; DEV float bfhi(unsigned u) { return __uint_as_float(u & 0xffff0000u); }
; DEV float silu_f(float x) { return x / (1.f + __expf(-x)); }
; __global__ void __launch_bounds__(512) hymba_fwd(Params p) {
;     ...
;             ss += __shfl_xor(ss, 1); ss += __shfl_xor(ss, 2); ss += __shfl_xor(ss, 4); ss += __shfl_xor(ss, 8);
;             const float rs = rsqrtf(ss * (1.f / 128.f) + EPS);
;             const f32x4 g0 = *(const f32x4*)(p.in[13] + l16 * 8), g1 = *(const f32x4*)(p.in[13] + l16 * 8 + 4);
;             const uint4 z = *(const uint4*)(proj + (size_t)row * NPJ + C_ZA + h * 128 + l16 * 8);
;             uint4 o;
;             o.x = cvt_pk_bf16(a[0] * rs * g0[0] * silu_f(bflo(z.x)), a[1] * rs * g0[1] * silu_f(bfhi(z.x)));
;             o.y = cvt_pk_bf16(a[2] * rs * g0[2] * silu_f(bflo(z.y)), a[3] * rs * g0[3] * silu_f(bfhi(z.y)));
;             o.z = cvt_pk_bf16(b4[0] * rs * g1[0] * silu_f(bflo(z.z)), b4[1] * rs * g1[1] * silu_f(bfhi(z.z)));
;             o.w = cvt_pk_bf16(b4[2] * rs * g1[2] * silu_f(bflo(z.w)), b4[3] * rs * g1[3] * silu_f(bfhi(z.w)));
	v_pk_add_f32 v[32:33], v[32:33], 1.0 op_sel_hi:[1,0]


; DEV unsigned cvt_pk_bf16(float lo, float hi) { const f32x2_t v = {lo, hi}; const bf16x2_t b = __builtin_convertvector(v, bf16x2_t); return __builtin_bit_cast(unsigned, b); }
; DEV float bflo(unsigned u) { return __uint_as_float(u << 16); }
; DEV float bfhi(unsigned u) { return __uint_as_float(u & 0xffff0000u); }
; DEV float silu_f(float x) { return x / (1.f + __expf(-x)); }
; __global__ void __launch_bounds__(512) hymba_fwd(Params p) {
;     ...
;             ss += __shfl_xor(ss, 1); ss += __shfl_xor(ss, 2); ss += __shfl_xor(ss, 4); ss += __shfl_xor(ss, 8);
;             const float rs = rsqrtf(ss * (1.f / 128.f) + EPS);
;             const f32x4 g0 = *(const f32x4*)(p.in[13] + l16 * 8), g1 = *(const f32x4*)(p.in[13] + l16 * 8 + 4);
;             const uint4 z = *(const uint4*)(proj + (size_t)row * NPJ + C_ZA + h * 128 + l16 * 8);
;             uint4 o;
;             o.x = cvt_pk_bf16(a[0] * rs * g0[0] * silu_f(bflo(z.x)), a[1] * rs * g0[1] * silu_f(bfhi(z.x)));
;             o.y = cvt_pk_bf16(a[2] * rs * g0[2] * silu_f(bflo(z.y)), a[3] * rs * g0[3] * silu_f(bfhi(z.y)));
;             o.z = cvt_pk_bf16(b4[0] * rs * g1[0] * silu_f(bflo(z.z)), b4[1] * rs * g1[1] * silu_f(bfhi(z.z)));
;             o.w = cvt_pk_bf16(b4[2] * rs * g1[2] * silu_f(bflo(z.w)), b4[3] * rs * g1[3] * silu_f(bfhi(z.w)));
	s_waitcnt lgkmcnt(0)
	v_add_f32_e32 v4, v4, v48


; __global__ void __launch_bounds__(512) hymba_fwd(Params p) {
;     ...
;             ss += __shfl_xor(ss, 1); ss += __shfl_xor(ss, 2); ss += __shfl_xor(ss, 4); ss += __shfl_xor(ss, 8);
	ds_bpermute_b32 v48, v10, v4


; __global__ void __launch_bounds__(512) hymba_fwd(Params p) {
;     ...
;             ss += __shfl_xor(ss, 1); ss += __shfl_xor(ss, 2); ss += __shfl_xor(ss, 4); ss += __shfl_xor(ss, 8);
	s_mov_b64 vcc, s[4:5]
	s_waitcnt lgkmcnt(0)
	v_add_f32_e32 v4, v4, v48


; DEV float silu_f(float x) { return x / (1.f + __expf(-x)); }
	v_rcp_f32_e32 v38, v7
	s_nop 0
	v_mul_f32_e32 v7, v41, v38

; DEV float silu_f(float x) { return x / (1.f + __expf(-x)); }
; __global__ void __launch_bounds__(512) hymba_fwd(Params p) {
;     ...
;             ss += __shfl_xor(ss, 1); ss += __shfl_xor(ss, 2); ss += __shfl_xor(ss, 4); ss += __shfl_xor(ss, 8);
	s_mov_b64 vcc, s[6:7]
	ds_bpermute_b32 v39, v11, v4


; DEV float silu_f(float x) { return x / (1.f + __expf(-x)); }
	v_rcp_f32_e32 v38, v6
	s_nop 0
	v_mul_f32_e32 v6, v40, v38

; DEV float silu_f(float x) { return x / (1.f + __expf(-x)); }
	s_mov_b64 vcc, s[8:9]


; DEV float silu_f(float x) { return x / (1.f + __expf(-x)); }
	v_rcp_f32_e32 v38, v31
	s_nop 0
	v_mul_f32_e32 v31, v43, v38

; DEV float silu_f(float x) { return x / (1.f + __expf(-x)); }
	s_mov_b64 vcc, s[10:11]


; DEV float silu_f(float x) { return x / (1.f + __expf(-x)); }
	v_rcp_f32_e32 v38, v30
	s_nop 0
	v_mul_f32_e32 v30, v42, v38

; DEV float silu_f(float x) { return x / (1.f + __expf(-x)); }
	s_mov_b64 vcc, s[12:13]


; DEV float silu_f(float x) { return x / (1.f + __expf(-x)); }
	v_rcp_f32_e32 v38, v33
	s_nop 0
	v_mul_f32_e32 v33, v45, v38

; DEV float silu_f(float x) { return x / (1.f + __expf(-x)); }
	s_mov_b64 vcc, s[16:17]

; DEV float silu_f(float x) { return x / (1.f + __expf(-x)); }
	v_rcp_f32_e32 v38, v32
	s_nop 0
	v_mul_f32_e32 v32, v44, v38

; DEV float silu_f(float x) { return x / (1.f + __expf(-x)); }
; __global__ void __launch_bounds__(512) hymba_fwd(Params p) {
;     ...
;             ss += __shfl_xor(ss, 1); ss += __shfl_xor(ss, 2); ss += __shfl_xor(ss, 4); ss += __shfl_xor(ss, 8);
	s_mov_b64 vcc, s[18:19]
	s_waitcnt lgkmcnt(0)
	v_add_f32_e32 v4, v4, v39
	v_rcp_f32_e32 v38, v37
	s_nop 0
	v_mul_f32_e32 v37, v47, v38

; DEV unsigned cvt_pk_bf16(float lo, float hi) { const f32x2_t v = {lo, hi}; const bf16x2_t b = __builtin_convertvector(v, bf16x2_t); return __builtin_bit_cast(unsigned, b); }
; DEV float bflo(unsigned u) { return __uint_as_float(u << 16); }
; DEV float bfhi(unsigned u) { return __uint_as_float(u & 0xffff0000u); }
; DEV float silu_f(float x) { return x / (1.f + __expf(-x)); }
; __global__ void __launch_bounds__(512) hymba_fwd(Params p) {
;     ...
;             const float rs = rsqrtf(ss * (1.f / 128.f) + EPS);
;             const f32x4 g0 = *(const f32x4*)(p.in[13] + l16 * 8), g1 = *(const f32x4*)(p.in[13] + l16 * 8 + 4);
;             const uint4 z = *(const uint4*)(proj + (size_t)row * NPJ + C_ZA + h * 128 + l16 * 8);
;             uint4 o;
;             o.x = cvt_pk_bf16(a[0] * rs * g0[0] * silu_f(bflo(z.x)), a[1] * rs * g0[1] * silu_f(bfhi(z.x)));
;             o.y = cvt_pk_bf16(a[2] * rs * g0[2] * silu_f(bflo(z.y)), a[3] * rs * g0[3] * silu_f(bfhi(z.y)));
;             o.z = cvt_pk_bf16(b4[0] * rs * g1[0] * silu_f(bflo(z.z)), b4[1] * rs * g1[1] * silu_f(bfhi(z.z)));
;             o.w = cvt_pk_bf16(b4[2] * rs * g1[2] * silu_f(bflo(z.w)), b4[3] * rs * g1[3] * silu_f(bfhi(z.w)));
;             *(uint4*)(mix + (size_t)row * LDB + h * 128 + l16 * 8) = o;
	v_fmamk_f32 v4, v4, 0x3c000000, v13
	v_rcp_f32_e32 v38, v36
	s_nop 0
	v_mul_f32_e32 v36, v46, v38
	v_mul_f32_e32 v38, 0x4b800000, v4
	v_cmp_gt_f32_e32 vcc, s30, v4
	s_nop 1
	v_cndmask_b32_e32 v4, v4, v38, vcc
	v_rsq_f32_e32 v4, v4
	s_nop 0
	v_mul_f32_e32 v38, 0x45800000, v4
	v_cndmask_b32_e32 v4, v4, v38, vcc
	v_pk_mul_f32 v[26:27], v[26:27], v[4:5] op_sel_hi:[1,0]
	v_pk_mul_f32 v[28:29], v[28:29], v[4:5] op_sel_hi:[1,0]
	v_pk_mul_f32 v[22:23], v[22:23], v[4:5] op_sel_hi:[1,0]
	v_pk_mul_f32 v[24:25], v[24:25], v[4:5] op_sel_hi:[1,0]
	v_pk_mul_f32 v[18:19], v[18:19], v[26:27]
	v_pk_mul_f32 v[20:21], v[20:21], v[28:29]
	v_pk_mul_f32 v[14:15], v[14:15], v[22:23]
	v_pk_mul_f32 v[16:17], v[16:17], v[24:25]
	v_pk_mul_f32 v[6:7], v[6:7], v[18:19]
	v_pk_mul_f32 v[18:19], v[30:31], v[20:21]
	v_pk_mul_f32 v[20:21], v[32:33], v[14:15]
	v_pk_mul_f32 v[22:23], v[36:37], v[16:17]
	v_cvt_pk_bf16_f32 v14, v6, v7
	v_cvt_pk_bf16_f32 v15, v18, v19
	v_cvt_pk_bf16_f32 v16, v20, v21
	v_cvt_pk_bf16_f32 v17, v22, v23
	global_store_dwordx4 v[34:35], v[14:17], off
	s_andn2_b64 exec, exec, s[24:25]
	s_cbranch_execnz .LBB0_945
